# drop m0 save/restore around every LDS-DMA issue
# speedup vs baseline: 1.0054x; 1.0054x over previous
; DI int get_tid() { int t = threadIdx.x; asm volatile("" : "+v"(t)); return t; }
; DI float zero_f() { float z = 0.f; asm volatile("" : "+v"(z)); return z; }
; template <int MT, class Epi>
; DI void gemm_tile(const u16* __restrict__ X, long ldx, const u16* __restrict__ W, long ldw, int K, char* smem,
;                   int m0, int n0, const Epi& epi, bool pre = false, const u16* Xn = nullptr, const u16* Wn = nullptr) {
;   const int tid = get_tid(), lane = tid & 63, wave = tid >> 6;
;   const int wm = wave & 1, wn = wave >> 1;
;   const int lr = lane & 15, g = lane >> 4;
;   const int rsw = (lr >> 1) & 7;
;   f32x4 acc[4][MT];
;   { const float z = zero_f();
; #pragma unroll
;   for (int a = 0; a < 4; ++a)
; #pragma unroll
;     for (int b = 0; b < MT; ++b) acc[a][b] = (f32x4){z, z, z, z}; }
;   const int wu = __builtin_amdgcn_readfirstlane(wave);
;   const unsigned sbase = (unsigned)__builtin_amdgcn_readfirstlane((int)(unsigned)(size_t)smem);
;   const int r8 = lane >> 3, c0 = (lane & 7) ^ (r8 >> 1);
;   const long oxe = (long)(wu * MT * 8 + r8) * ldx + (c0 << 3), oxo = (long)(wu * MT * 8 + r8) * ldx + ((c0 ^ 4) << 3);
;   const long owe = (long)(wu * 32 + r8) * ldw + (c0 << 3), owo = (long)(wu * 32 + r8) * ldw + ((c0 ^ 4) << 3);
;   const u16 *xe = X + oxe, *xo = X + oxo, *we = W + owe, *wo = W + owo;
;   const long ldx8 = 8 * ldx, ldw8 = 8 * ldw;
;   const unsigned xdst = sbase + wu * MT * 1024, wdst = sbase + 16384 + wu * 4096;
;     ...
;   if (!pre) {
;     __syncthreads();
;     GT_DMA(0u)
;   } else {
;     xe += 64; xo += 64; we += 64; wo += 64;
;   }
;   const int nk = K >> 6;
;   int kt = 0;
;   do {
;     asm volatile("s_waitcnt vmcnt(0)" ::: "memory");
;     __syncthreads();
;     if (kt + 1 < nk) GT_DMA((unsigned)((kt + 1) & 1) * 32768u)
;     else if (Xn != nullptr) { xe = Xn + oxe; xo = Xn + oxo; we = Wn + owe; wo = Wn + owo; GT_DMA(0u) }
; DI void phase_odd(const Params& p, int o, int sub, char* smem) {
;     ...
;         const int u = t - 512, tm = u >> 3, tn = u & 7, m0 = M_PROMPT + tm * 64;
;         gemm_tile<2>(ao + (size_t)m0 * 1024, 1024, W + WO_O + (size_t)tn * 128 * 1024, 1024, 1024, smem, m0, tn * 128, epi);
.LBB0_26:
	s_and_b32 s7, s4, 7
	s_lshl_b32 s34, s7, 18
	s_cmpk_gt_i32 s6, 0x1ff
	s_mov_b64 s[38:39], -1
	s_cbranch_scc0 .LBB0_30
	s_bfe_u32 s8, s5, 0x190006
	s_mov_b32 s9, s35
	s_lshl_b64 s[12:13], s[8:9], 17
	s_lshl_b32 s8, s6, 3
	s_and_b32 s8, s8, 0x7fffffc0
	s_add_i32 s38, s8, 0x3000
	s_mov_b32 s39, s35
	s_and_b32 s7, s6, 7
	s_lshl_b64 s[8:9], s[38:39], 11
	v_readlane_b32 s10, v252, 24
	v_mov_b32_e32 v1, v185
	v_readlane_b32 s11, v252, 25
	s_add_u32 s8, s10, s8
	s_addc_u32 s9, s11, s9
	v_ashrrev_i32_e32 v2, 6, v1
	v_bfe_u32 v4, v1, 3, 3
	v_readfirstlane_b32 s11, v2
	v_and_b32_e32 v40, 1, v2
	v_bfe_u32 v42, v1, 4, 2
	v_lshl_or_b32 v2, s11, 4, v4
	v_bitop3_b32 v8, v42, v1, 7 bitop3:0x78
	v_ashrrev_i32_e32 v3, 31, v2
	s_lshl_b32 s10, s7, 18
	v_readlane_b32 s16, v252, 26
	v_lshl_or_b32 v4, s11, 5, v4
	v_lshlrev_b64 v[2:3], 11, v[2:3]
	v_lshlrev_b32_e32 v182, 4, v8
	v_readlane_b32 s17, v252, 27
	s_add_u32 s14, s16, s10
	v_mov_b32_e32 v0, v183
	v_ashrrev_i32_e32 v5, 31, v4
	v_lshl_add_u64 v[6:7], s[8:9], 0, v[2:3]
	v_xor_b32_e32 v10, 64, v182
	v_mov_b32_e32 v11, v183
	s_addc_u32 s15, s17, 0
	v_lshl_add_u64 v[8:9], v[6:7], 0, v[182:183]
	v_lshl_add_u64 v[6:7], v[6:7], 0, v[10:11]
	v_lshlrev_b64 v[4:5], 11, v[4:5]
	s_lshl_b32 s8, s11, 11
	s_barrier
	s_mov_b32 m0, s8
	s_nop 0
	global_load_lds_dwordx4 v[8:9], off
	s_mov_b64 s[18:19], 0x4000
	v_lshl_add_u64 v[12:13], s[14:15], 0, v[4:5]
	s_lshl_b32 s11, s11, 12
	v_lshl_add_u64 v[6:7], v[6:7], 0, s[18:19]
	s_or_b32 s9, s8, 0x400
	s_mov_b32 m0, s9
	s_nop 0
	global_load_lds_dwordx4 v[6:7], off
	v_lshl_add_u64 v[14:15], v[12:13], 0, v[182:183]
	v_lshl_add_u64 v[6:7], v[12:13], 0, v[10:11]
	s_add_i32 s9, s11, 0x4000
	s_mov_b32 m0, s9
	s_nop 0
	global_load_lds_dwordx4 v[14:15], off
	v_lshl_add_u64 v[8:9], v[6:7], 0, s[18:19]
	s_add_i32 s14, s11, 0x4400
	s_mov_b32 m0, s14
	s_nop 0
	global_load_lds_dwordx4 v[8:9], off
	s_mov_b64 s[14:15], 0x8000
	v_lshl_add_u64 v[8:9], v[14:15], 0, s[14:15]
	s_add_i32 s14, s11, 0x4800
	s_mov_b32 m0, s14
	s_nop 0
	global_load_lds_dwordx4 v[8:9], off
	s_mov_b64 s[14:15], 0xc000
	s_waitcnt vmcnt(7)
	v_lshrrev_b32_e32 v16, 1, v1
	v_lshl_add_u64 v[6:7], v[6:7], 0, s[14:15]
	s_addk_i32 s11, 0x4c00
	s_mov_b32 m0, s11
	s_nop 0
	global_load_lds_dwordx4 v[6:7], off
	v_bitop3_b32 v6, v42, v16, 7 bitop3:0x78
	v_lshl_add_u64 v[4:5], s[34:35], 0, v[4:5]
	v_lshlrev_b32_e32 v48, 4, v6
	v_lshl_add_u64 v[6:7], v[4:5], 0, v[10:11]
	s_waitcnt vmcnt(4)
	v_lshl_add_u64 v[32:33], s[16:17], 0, v[6:7]
	v_readlane_b32 s16, v255, 5
	v_lshl_add_u64 v[4:5], v[4:5], 0, v[182:183]
	v_readlane_b32 s20, v255, 9
	v_readlane_b32 s21, v255, 10
	v_lshl_add_u64 v[2:3], s[12:13], 0, v[2:3]
	v_readlane_b32 s12, v254, 54
	v_lshl_add_u64 v[34:35], s[20:21], 0, v[4:5]
	v_bitop3_b32 v4, v2, v182, 64 bitop3:0xf6
	v_mov_b32_e32 v5, v3
	v_readlane_b32 s13, v254, 55
	v_and_b32_e32 v41, 15, v1
	v_ashrrev_i32_e32 v43, 7, v1
	v_bfe_u32 v1, v1, 1, 3
	v_lshl_add_u64 v[36:37], s[12:13], 0, v[4:5]
	v_readlane_b32 s12, v254, 57
	v_bitop3_b32 v1, v42, v1, 4 bitop3:0x36
	v_readlane_b32 s17, v255, 6
	v_or_b32_e32 v2, v2, v182
	v_readlane_b32 s13, v254, 58
	s_mov_b32 s10, 0
	v_lshlrev_b32_e32 v47, 12, v40
	v_lshlrev_b32_e32 v44, 7, v41
	v_lshlrev_b32_e32 v45, 13, v43
	v_lshlrev_b32_e32 v46, 4, v1
	v_lshl_add_u64 v[38:39], s[12:13], 0, v[2:3]
	s_mov_b64 s[40:41], 0
	v_mov_b32_e32 v1, v0
	v_mov_b32_e32 v2, v0
	v_mov_b32_e32 v3, v0
	v_mov_b32_e32 v4, v0
	v_mov_b32_e32 v5, v0
	v_mov_b32_e32 v6, v0
	v_mov_b32_e32 v7, v0
	v_mov_b32_e32 v8, v0
	v_mov_b32_e32 v9, v0
	v_mov_b32_e32 v10, v0
	v_mov_b32_e32 v11, v0
	v_mov_b32_e32 v12, v0
	v_mov_b32_e32 v13, v0
	v_mov_b32_e32 v14, v0
	v_mov_b32_e32 v15, v0
	v_mov_b32_e32 v16, v0
	v_mov_b32_e32 v17, v0
	v_mov_b32_e32 v18, v0
	v_mov_b32_e32 v19, v0
	v_mov_b32_e32 v20, v0
	v_mov_b32_e32 v21, v0
	v_mov_b32_e32 v22, v0
	v_mov_b32_e32 v23, v0
	v_mov_b32_e32 v24, v0
	v_mov_b32_e32 v25, v0
	v_mov_b32_e32 v26, v0
	v_mov_b32_e32 v27, v0
	v_mov_b32_e32 v28, v0
	v_mov_b32_e32 v29, v0
	v_mov_b32_e32 v30, v0
	v_mov_b32_e32 v31, v0
	s_mov_b64 s[16:17], 0x5a0080
	v_readlane_b32 s18, v255, 7
	v_readlane_b32 s19, v255, 8
	v_readlane_b32 s22, v255, 11
	v_readlane_b32 s23, v255, 12
.LBB0_28:
	s_add_i32 s11, s10, 0x8000
	s_and_b32 s12, s11, 0x8000
	v_lshl_add_u64 v[54:55], v[36:37], 0, s[40:41]
	v_lshl_add_u64 v[56:57], v[38:39], 0, s[40:41]
	s_waitcnt vmcnt(0)
	s_barrier
; DI void st_bf4(u16* p, float a, float b, float c, float d) { *(uint2*)p = make_uint2(pk2(a, b), pk2(c, d)); }
; template <int MT, class Epi>
; DI void gemm_tile(const u16* __restrict__ X, long ldx, const u16* __restrict__ W, long ldw, int K, char* smem,
;                   int m0, int n0, const Epi& epi, bool pre = false, const u16* Xn = nullptr, const u16* Wn = nullptr) {
;     ...
;   do {
;     asm volatile("s_waitcnt vmcnt(0)" ::: "memory");
;     __syncthreads();
;     if (kt + 1 < nk) GT_DMA((unsigned)((kt + 1) & 1) * 32768u)
;     else if (Xn != nullptr) { xe = Xn + oxe; xo = Xn + oxo; we = Wn + owe; wo = Wn + owo; GT_DMA(0u) }
;     const char* cur = smem + (kt & 1) * 32768;
; #pragma unroll
;     for (int ks = 0; ks < 2; ++ks) {
;       bf16x8 xf[MT], wf[4];
;       const int ch = ((ks * 4 + g) ^ rsw) << 4;
; #pragma unroll
;       for (int i = 0; i < MT; ++i) xf[i] = *(const bf16x8*)(cur + (wm * 16 * MT + i * 16 + lr) * 128 + ch);
; #pragma unroll
;       for (int i = 0; i < 4; ++i) wf[i] = *(const bf16x8*)(cur + 16384 + (wn * 64 + i * 16 + lr) * 128 + ch);
; #pragma unroll
;       for (int nt = 0; nt < 4; ++nt)
; #pragma unroll
;         for (int mt = 0; mt < MT; ++mt)
;           acc[nt][mt] = __builtin_amdgcn_mfma_f32_16x16x32_bf16(wf[nt], xf[mt], acc[nt][mt], 0, 0, 0);
;     }
;   } while (++kt < nk);
;     ...
;   epi.run(acc, m0 + wm * 16 * MT + lr, n0 + wn * 64 + 4 * g);
;   template <int NT, int MT> DI void run(f32x4 (&acc)[NT][MT], int mb, int nb) const {
; #pragma unroll
;     for (int nt = 0; nt < NT; ++nt)
; #pragma unroll
;       for (int mt = 0; mt < MT; ++mt) {
;         f32x4 v = acc[nt][mt];
;         st_bf4(C + (size_t)(mb + mt * 16) * ldc + nb + nt * 16, v[0], v[1], v[2], v[3]);
;       }
	s_add_i32 s13, s12, s8
	s_mov_b32 m0, s13
	s_nop 0
	global_load_lds_dwordx4 v[56:57], off
	v_lshl_add_u64 v[52:53], v[34:35], 0, s[40:41]
	v_lshl_add_u64 v[54:55], v[54:55], 0, s[94:95]
	s_addk_i32 s13, 0x400
	s_mov_b32 m0, s13
	s_nop 0
	global_load_lds_dwordx4 v[54:55], off
	v_lshl_add_u64 v[50:51], v[32:33], 0, s[40:41]
	v_lshl_add_u64 v[58:59], v[52:53], 0, s[16:17]
	s_add_i32 s12, s12, s9
	s_mov_b32 m0, s12
	s_nop 0
	global_load_lds_dwordx4 v[58:59], off
	v_lshl_add_u64 v[54:55], v[50:51], 0, s[94:95]
	s_add_i32 s13, s12, 0x400
	s_mov_b32 m0, s13
	s_nop 0
	global_load_lds_dwordx4 v[54:55], off
	s_and_b32 s10, s10, 0x8000
	v_lshl_add_u64 v[52:53], v[52:53], 0, s[66:67]
	s_add_i32 s13, s12, 0x800
	s_mov_b32 m0, s13
	s_nop 0
	global_load_lds_dwordx4 v[52:53], off
	v_or_b32_e32 v49, s10, v48
	v_lshl_add_u64 v[50:51], v[50:51], 0, s[54:55]
	s_addk_i32 s12, 0xc00
	s_mov_b32 m0, s12
	s_nop 0
	global_load_lds_dwordx4 v[50:51], off
	v_add3_u32 v54, v49, v47, v44
	v_add3_u32 v49, v49, v45, v44
	ds_read_b128 v[50:53], v54
	ds_read_b128 v[54:57], v54 offset:2048
	ds_read_b128 v[58:61], v49 offset:16384
	ds_read_b128 v[62:65], v49 offset:18432
	ds_read_b128 v[66:69], v49 offset:20480
	ds_read_b128 v[70:73], v49 offset:22528
	v_or_b32_e32 v49, s10, v46
	s_waitcnt lgkmcnt(3)
	v_mfma_f32_16x16x32_bf16 v[24:27], v[58:61], v[54:57], v[24:27]
	s_add_u32 s40, s40, 0x80
	s_addc_u32 s41, s41, 0
	s_cmpk_lg_i32 s40, 0x780
	s_waitcnt lgkmcnt(2)
	v_mfma_f32_16x16x32_bf16 v[16:19], v[62:65], v[54:57], v[16:19]
	s_mov_b32 s10, s11
	s_waitcnt lgkmcnt(1)
	v_mfma_f32_16x16x32_bf16 v[8:11], v[66:69], v[54:57], v[8:11]
	s_waitcnt lgkmcnt(0)
	v_mfma_f32_16x16x32_bf16 v[0:3], v[70:73], v[54:57], v[0:3]
	v_add3_u32 v54, v49, v47, v44
	v_add3_u32 v49, v49, v45, v44
	v_mfma_f32_16x16x32_bf16 v[28:31], v[58:61], v[50:53], v[28:31]
	v_mfma_f32_16x16x32_bf16 v[20:23], v[62:65], v[50:53], v[20:23]
	v_mfma_f32_16x16x32_bf16 v[12:15], v[66:69], v[50:53], v[12:15]
	v_mfma_f32_16x16x32_bf16 v[4:7], v[70:73], v[50:53], v[4:7]
	ds_read_b128 v[50:53], v54
	ds_read_b128 v[54:57], v54 offset:2048
	ds_read_b128 v[58:61], v49 offset:16384
	ds_read_b128 v[62:65], v49 offset:18432
	ds_read_b128 v[66:69], v49 offset:20480
	ds_read_b128 v[70:73], v49 offset:22528
	s_waitcnt lgkmcnt(3)
	v_mfma_f32_16x16x32_bf16 v[28:31], v[58:61], v[50:53], v[28:31]
	v_mfma_f32_16x16x32_bf16 v[24:27], v[58:61], v[54:57], v[24:27]
	s_waitcnt lgkmcnt(2)
	v_mfma_f32_16x16x32_bf16 v[20:23], v[62:65], v[50:53], v[20:23]
	v_mfma_f32_16x16x32_bf16 v[16:19], v[62:65], v[54:57], v[16:19]
	s_waitcnt lgkmcnt(1)
	v_mfma_f32_16x16x32_bf16 v[12:15], v[66:69], v[50:53], v[12:15]
	v_mfma_f32_16x16x32_bf16 v[8:11], v[66:69], v[54:57], v[8:11]
	s_waitcnt lgkmcnt(0)
	v_mfma_f32_16x16x32_bf16 v[4:7], v[70:73], v[50:53], v[4:7]
	v_mfma_f32_16x16x32_bf16 v[0:3], v[70:73], v[54:57], v[0:3]
	s_cbranch_scc1 .LBB0_28
	v_add3_u32 v36, v48, v47, v44
	v_add3_u32 v60, v48, v45, v44
	s_waitcnt vmcnt(0)
	s_barrier
	ds_read_b128 v[32:35], v36 offset:32768
	ds_read_b128 v[36:39], v36 offset:34816
	ds_read_b128 v[48:51], v60 offset:49152
	ds_read_b128 v[52:55], v60 offset:51200
	ds_read_b128 v[56:59], v60 offset:53248
	ds_read_b128 v[60:63], v60 offset:55296
	s_waitcnt lgkmcnt(3)
	v_mfma_f32_16x16x32_bf16 v[24:27], v[48:51], v[36:39], v[24:27]
	s_lshl_b32 s7, s7, 7
	s_waitcnt lgkmcnt(2)
	v_mfma_f32_16x16x32_bf16 v[16:19], v[52:55], v[36:39], v[16:19]
	s_waitcnt lgkmcnt(1)
	v_mfma_f32_16x16x32_bf16 v[12:15], v[56:59], v[32:35], v[12:15]
	v_mfma_f32_16x16x32_bf16 v[8:11], v[56:59], v[36:39], v[8:11]
	v_add3_u32 v56, v46, v45, v44
	s_waitcnt lgkmcnt(0)
	v_mfma_f32_16x16x32_bf16 v[0:3], v[60:63], v[36:39], v[0:3]
	v_add3_u32 v36, v46, v47, v44
	v_mfma_f32_16x16x32_bf16 v[28:31], v[48:51], v[32:35], v[28:31]
	v_mfma_f32_16x16x32_bf16 v[20:23], v[52:55], v[32:35], v[20:23]
	v_mfma_f32_16x16x32_bf16 v[4:7], v[60:63], v[32:35], v[4:7]
	ds_read_b128 v[32:35], v36 offset:32768
	ds_read_b128 v[36:39], v36 offset:34816
	ds_read_b128 v[44:47], v56 offset:49152
	ds_read_b128 v[48:51], v56 offset:51200
	ds_read_b128 v[52:55], v56 offset:53248
	ds_read_b128 v[56:59], v56 offset:55296
	s_waitcnt lgkmcnt(3)
	v_mfma_f32_16x16x32_bf16 v[28:31], v[44:47], v[32:35], v[28:31]
	s_waitcnt lgkmcnt(2)
	v_mfma_f32_16x16x32_bf16 v[20:23], v[48:51], v[32:35], v[20:23]
	s_nop 5
	v_cvt_pk_bf16_f32 v28, v28, v29
	v_cvt_pk_bf16_f32 v29, v30, v31
	s_waitcnt lgkmcnt(1)
	v_mfma_f32_16x16x32_bf16 v[12:15], v[52:55], v[32:35], v[12:15]
	s_waitcnt lgkmcnt(0)
	v_mfma_f32_16x16x32_bf16 v[4:7], v[56:59], v[32:35], v[4:7]
	v_lshlrev_b32_e32 v32, 5, v40
	v_or3_b32 v182, v32, s38, v41
	v_lshl_add_u32 v32, v43, 6, s7
	v_lshl_or_b32 v32, v42, 2, v32
	v_ashrrev_i32_e32 v33, 31, v32
	v_lshlrev_b64 v[34:35], 11, v[182:183]
	v_mfma_f32_16x16x32_bf16 v[24:27], v[44:47], v[36:39], v[24:27]
	v_lshl_add_u64 v[34:35], s[92:93], 0, v[34:35]
	v_lshlrev_b64 v[32:33], 1, v[32:33]
	v_lshl_add_u64 v[34:35], v[34:35], 0, v[32:33]
	v_mfma_f32_16x16x32_bf16 v[16:19], v[48:51], v[36:39], v[16:19]
	v_or_b32_e32 v182, 16, v182
	global_store_dwordx2 v[34:35], v[28:29], off
	v_lshlrev_b64 v[28:29], 11, v[182:183]
	v_mfma_f32_16x16x32_bf16 v[8:11], v[52:55], v[36:39], v[8:11]
	v_lshl_add_u64 v[28:29], s[92:93], 0, v[28:29]
	v_lshl_add_u64 v[28:29], v[28:29], 0, v[32:33]
	v_cvt_pk_bf16_f32 v24, v24, v25
	v_mfma_f32_16x16x32_bf16 v[0:3], v[56:59], v[36:39], v[0:3]
	v_cvt_pk_bf16_f32 v25, v26, v27
	v_cvt_pk_bf16_f32 v20, v20, v21
	v_cvt_pk_bf16_f32 v21, v22, v23
	v_cvt_pk_bf16_f32 v16, v16, v17
	v_cvt_pk_bf16_f32 v17, v18, v19
	v_cvt_pk_bf16_f32 v12, v12, v13
	v_cvt_pk_bf16_f32 v13, v14, v15
	v_cvt_pk_bf16_f32 v8, v8, v9
	v_cvt_pk_bf16_f32 v9, v10, v11
	v_cvt_pk_bf16_f32 v4, v4, v5
	v_cvt_pk_bf16_f32 v5, v6, v7
	v_cvt_pk_bf16_f32 v0, v0, v1
	v_cvt_pk_bf16_f32 v1, v2, v3
	s_mov_b64 s[38:39], 0
	global_store_dwordx2 v[28:29], v[24:25], off
	global_store_dwordx2 v[34:35], v[20:21], off offset:32
	global_store_dwordx2 v[28:29], v[16:17], off offset:32
	global_store_dwordx2 v[34:35], v[12:13], off offset:64
	global_store_dwordx2 v[28:29], v[8:9], off offset:64
	global_store_dwordx2 v[34:35], v[4:5], off offset:96
	global_store_dwordx2 v[28:29], v[0:1], off offset:96
; DI int get_tid() { int t = threadIdx.x; asm volatile("" : "+v"(t)); return t; }
; DI float zero_f() { float z = 0.f; asm volatile("" : "+v"(z)); return z; }
; template <int BM, class Epi>
; DI void gemm_dma(const u16* __restrict__ X, long ldx, const u16* __restrict__ W, long ldw, int K, char* smem,
;                  int m0, int n0, const Epi& epi) {
;     ...
;   const int tid = get_tid(), lane = tid & 63, wave = tid >> 6;
;   const int lr = lane & 15, g = lane >> 4;
;   const int rd = lr * 64 + ((g ^ ((4 - (lr >> 2)) & 3)) << 4);
;   const int xrow0 = BIG ? wave * 64 : (wave & 1) * (BM / 2);
;   const int wrow0 = BIG ? 0 : (wave >> 1) * 64;
;   f32x4 acc[NT][MT];
;   { const float z = zero_f();
; #pragma unroll
;   for (int a = 0; a < NT; ++a)
; #pragma unroll
;     for (int b = 0; b < MT; ++b) acc[a][b] = (f32x4){z, z, z, z}; }
;   const int wu = __builtin_amdgcn_readfirstlane(wave);
;   const unsigned sbase = (unsigned)__builtin_amdgcn_readfirstlane((int)(unsigned)(size_t)smem);
;   const int r16 = lane >> 2, chunk = (lane & 3) ^ ((4 - (r16 >> 2)) & 3);
;   const u16* xs = X + (long)(wu * XD * 16 + r16) * ldx + (chunk << 3);
;   const u16* ws = W + (long)(wu * 32 + r16) * ldw + (chunk << 3);
;   const long ldx16 = 16 * ldx, ldw16 = 16 * ldw;
;   const unsigned xdst = sbase + wu * XD * 1024, wdst = sbase + BM * 64 + wu * 2048;
;     ...
;   const int nk = K >> 5;
;   __syncthreads();
; #pragma unroll
;   for (int s = 0; s < D - 1; ++s) GD_ISSUE(s)
;   int cur = 0, nxt = D - 1, kt = 0;
; DI void phase_odd(const Params& p, int o, int sub, char* smem) {
;     ...
;         const int tm = t >> 3, tn = t & 7;
;         gemm_dma<256>(ao + (size_t)tm * 256 * 1024, 1024, W + WO_O + (size_t)tn * 128 * 1024, 1024, 1024, smem, tm * 256, tn * 128, epi);
.LBB0_30:
	s_and_b64 vcc, exec, s[38:39]
	s_cbranch_vccz .LBB0_25
	s_ashr_i32 s38, s6, 3
	s_ashr_i32 s39, s38, 31
	v_mov_b32_e32 v1, v185
	s_and_b32 s7, s6, 7
	s_lshl_b64 s[40:41], s[38:39], 19
	v_readlane_b32 s8, v252, 24
	v_readlane_b32 s9, v252, 25
	v_lshrrev_b32_e32 v2, 2, v1
	s_add_u32 s8, s8, s40
	s_waitcnt vmcnt(9)
	v_and_b32_e32 v133, 15, v1
	v_bfe_u32 v132, v1, 4, 2
	v_sub_u32_e32 v2, 0, v2
	s_addc_u32 s9, s9, s41
	s_lshl_b32 s10, s7, 18
	v_readlane_b32 s12, v252, 26
	v_lshlrev_b32_e32 v0, 6, v133
	v_bitop3_b32 v2, v132, v2, 3 bitop3:0x78
	v_readlane_b32 s13, v252, 27
	s_add_u32 s12, s12, s10
	v_lshl_or_b32 v134, v2, 4, v0
	v_readfirstlane_b32 s14, v1
	v_lshrrev_b32_e32 v2, 4, v1
	s_addc_u32 s13, s13, 0
	s_ashr_i32 s15, s14, 6
	v_bfe_u32 v6, v1, 2, 4
	v_sub_u32_e32 v14, 0, v2
	s_andn2_b32 s14, s14, 63
	v_xor_b32_e32 v7, v1, v14
	v_or_b32_e32 v2, s14, v6
	v_ashrrev_i32_e32 v3, 31, v2
	v_lshlrev_b32_e32 v7, 4, v7
	v_lshl_or_b32 v6, s15, 5, v6
	v_lshlrev_b64 v[2:3], 11, v[2:3]
	v_and_b32_e32 v182, 48, v7
	v_ashrrev_i32_e32 v7, 31, v6
	v_mov_b32_e32 v0, v183
	v_lshl_add_u64 v[4:5], s[8:9], 0, v[2:3]
	v_lshlrev_b64 v[6:7], 11, v[6:7]
	v_lshl_add_u64 v[4:5], v[4:5], 0, v[182:183]
	v_lshl_add_u64 v[8:9], s[12:13], 0, v[6:7]
	s_lshl_b32 s8, s15, 12
	s_barrier
	s_mov_b32 m0, s8
	s_nop 0
	global_load_lds_dwordx4 v[4:5], off
	s_mov_b64 s[16:17], 0x8000
	v_lshl_add_u64 v[10:11], v[4:5], 0, s[16:17]
	s_or_b32 s13, s8, 0x400
	s_mov_b32 m0, s13
	s_nop 0
	global_load_lds_dwordx4 v[10:11], off
	s_mov_b64 s[18:19], 0x10000
	v_lshl_add_u64 v[10:11], v[4:5], 0, s[18:19]
	s_or_b32 s13, s8, 0x800
	s_mov_b32 m0, s13
	s_nop 0
	global_load_lds_dwordx4 v[10:11], off
	s_mov_b64 s[20:21], 0x18000
	s_lshl_b32 s12, s15, 11
	v_lshl_add_u64 v[10:11], v[4:5], 0, s[20:21]
	s_or_b32 s13, s8, 0xc00
	s_mov_b32 m0, s13
	s_nop 0
	global_load_lds_dwordx4 v[10:11], off
	v_lshl_add_u64 v[8:9], v[8:9], 0, v[182:183]
	s_add_i32 s9, s12, 0x4000
	s_mov_b32 m0, s9
	s_nop 0
	global_load_lds_dwordx4 v[8:9], off
	v_lshl_add_u64 v[10:11], v[8:9], 0, s[16:17]
	s_add_i32 s13, s12, 0x4400
	s_mov_b32 m0, s13
	s_nop 0
	global_load_lds_dwordx4 v[10:11], off
	v_lshl_add_u64 v[10:11], v[4:5], 0, 64
	s_add_i32 s13, s8, 0x6000
	s_mov_b32 m0, s13
	s_nop 0
	global_load_lds_dwordx4 v[10:11], off
	s_mov_b64 s[22:23], 0x8040
	v_lshl_add_u64 v[10:11], v[4:5], 0, s[22:23]
	s_add_i32 s13, s8, 0x6400
	s_mov_b32 m0, s13
	s_nop 0
	global_load_lds_dwordx4 v[10:11], off
	s_mov_b64 s[14:15], 0x10040
	v_lshl_add_u64 v[10:11], v[4:5], 0, s[14:15]
	s_add_i32 s13, s8, 0x6800
	s_mov_b32 m0, s13
	s_nop 0
	global_load_lds_dwordx4 v[10:11], off
	s_mov_b64 s[14:15], 0x18040
	v_lshl_add_u64 v[4:5], v[4:5], 0, s[14:15]
	s_add_i32 s13, s8, 0x6c00
	s_mov_b32 m0, s13
	s_nop 0
	global_load_lds_dwordx4 v[4:5], off
	v_lshl_add_u64 v[12:13], v[8:9], 0, 64
	s_add_i32 s13, s12, 0xa000
	s_mov_b32 m0, s13
	s_nop 0
	global_load_lds_dwordx4 v[12:13], off
	v_lshl_add_u64 v[4:5], v[8:9], 0, s[22:23]
	s_add_i32 s12, s12, 0xa400
	s_mov_b32 m0, s12
	s_nop 0
	global_load_lds_dwordx4 v[4:5], off
	v_and_b32_e32 v135, 0xffffffc0, v1
	v_bitop3_b32 v1, v1, 3, v14 bitop3:0x48
	v_lshl_add_u64 v[4:5], s[34:35], 0, v[6:7]
	v_lshlrev_b32_e32 v182, 4, v1
	v_readlane_b32 s12, v254, 59
	v_lshl_add_u64 v[4:5], v[4:5], 0, v[182:183]
	v_readlane_b32 s13, v254, 60
	v_lshl_add_u64 v[2:3], s[40:41], 0, v[2:3]
	v_or_b32_e32 v2, v2, v182
	s_waitcnt vmcnt(8)
	v_lshl_add_u64 v[128:129], s[12:13], 0, v[4:5]
	v_readlane_b32 s12, v254, 61
	v_readlane_b32 s13, v254, 62
	s_mov_b32 s10, 2
	s_mov_b32 s11, 0
	v_lshlrev_b32_e32 v136, 6, v135
	v_lshl_add_u64 v[130:131], s[12:13], 0, v[2:3]
	s_mov_b64 s[40:41], 0
	v_mov_b32_e32 v1, v0
	v_mov_b32_e32 v2, v0
	v_mov_b32_e32 v3, v0
	v_mov_b32_e32 v4, v0
	v_mov_b32_e32 v5, v0
	v_mov_b32_e32 v6, v0
	v_mov_b32_e32 v7, v0
	v_mov_b32_e32 v8, v0
	v_mov_b32_e32 v9, v0
	v_mov_b32_e32 v10, v0
	v_mov_b32_e32 v11, v0
	v_mov_b32_e32 v12, v0
	v_mov_b32_e32 v13, v0
	v_mov_b32_e32 v14, v0
	v_mov_b32_e32 v15, v0
	s_waitcnt vmcnt(7)
	v_mov_b32_e32 v16, v0
	v_mov_b32_e32 v17, v0
	v_mov_b32_e32 v18, v0
	v_mov_b32_e32 v19, v0
	s_waitcnt vmcnt(5)
	v_mov_b32_e32 v20, v0
	v_mov_b32_e32 v21, v0
	v_mov_b32_e32 v22, v0
	v_mov_b32_e32 v23, v0
	v_mov_b32_e32 v24, v0
	v_mov_b32_e32 v25, v0
	v_mov_b32_e32 v26, v0
	v_mov_b32_e32 v27, v0
	s_waitcnt vmcnt(4)
	v_mov_b32_e32 v28, v0
	v_mov_b32_e32 v29, v0
	v_mov_b32_e32 v30, v0
	v_mov_b32_e32 v31, v0
	v_mov_b32_e32 v32, v0
	v_mov_b32_e32 v33, v0
	v_mov_b32_e32 v34, v0
	v_mov_b32_e32 v35, v0
	v_mov_b32_e32 v36, v0
	v_mov_b32_e32 v37, v0
	v_mov_b32_e32 v38, v0
	v_mov_b32_e32 v39, v0
	v_mov_b32_e32 v40, v0
	v_mov_b32_e32 v41, v0
	v_mov_b32_e32 v42, v0
	v_mov_b32_e32 v43, v0
	v_mov_b32_e32 v44, v0
	v_mov_b32_e32 v45, v0
	v_mov_b32_e32 v46, v0
	v_mov_b32_e32 v47, v0
	v_mov_b32_e32 v48, v0
	v_mov_b32_e32 v49, v0
	v_mov_b32_e32 v50, v0
	v_mov_b32_e32 v51, v0
	v_mov_b32_e32 v52, v0
	v_mov_b32_e32 v53, v0
	v_mov_b32_e32 v54, v0
	v_mov_b32_e32 v55, v0
	v_mov_b32_e32 v56, v0
	v_mov_b32_e32 v57, v0
	v_mov_b32_e32 v58, v0
	v_mov_b32_e32 v59, v0
	v_mov_b32_e32 v60, v0
	v_mov_b32_e32 v61, v0
	v_mov_b32_e32 v62, v0
	v_mov_b32_e32 v63, v0
	v_mov_b32_e32 v64, v0
	v_mov_b32_e32 v65, v0
	v_mov_b32_e32 v66, v0
	v_mov_b32_e32 v67, v0
	v_mov_b32_e32 v68, v0
	v_mov_b32_e32 v69, v0
	v_mov_b32_e32 v70, v0
	v_mov_b32_e32 v71, v0
	v_mov_b32_e32 v72, v0
	v_mov_b32_e32 v73, v0
	v_mov_b32_e32 v74, v0
	v_mov_b32_e32 v75, v0
	v_mov_b32_e32 v76, v0
	v_mov_b32_e32 v77, v0
	v_mov_b32_e32 v78, v0
	v_mov_b32_e32 v79, v0
	v_mov_b32_e32 v80, v0
	v_mov_b32_e32 v81, v0
	v_mov_b32_e32 v82, v0
	v_mov_b32_e32 v83, v0
	v_mov_b32_e32 v84, v0
	v_mov_b32_e32 v85, v0
	v_mov_b32_e32 v86, v0
	v_mov_b32_e32 v87, v0
	v_mov_b32_e32 v88, v0
	v_mov_b32_e32 v89, v0
	v_mov_b32_e32 v90, v0
	v_mov_b32_e32 v91, v0
	v_mov_b32_e32 v92, v0
	v_mov_b32_e32 v93, v0
	v_mov_b32_e32 v94, v0
	v_mov_b32_e32 v95, v0
	s_waitcnt vmcnt(0)
	v_mov_b32_e32 v96, v0
	v_mov_b32_e32 v97, v0
	v_mov_b32_e32 v98, v0
	v_mov_b32_e32 v99, v0
	v_mov_b32_e32 v100, v0
	v_mov_b32_e32 v101, v0
	v_mov_b32_e32 v102, v0
	v_mov_b32_e32 v103, v0
	v_mov_b32_e32 v104, v0
	v_mov_b32_e32 v105, v0
	v_mov_b32_e32 v106, v0
	v_mov_b32_e32 v107, v0
	v_mov_b32_e32 v108, v0
	v_mov_b32_e32 v109, v0
	v_mov_b32_e32 v110, v0
	v_mov_b32_e32 v111, v0
	v_mov_b32_e32 v112, v0
	v_mov_b32_e32 v113, v0
	v_mov_b32_e32 v114, v0
	v_mov_b32_e32 v115, v0
	v_mov_b32_e32 v116, v0
	v_mov_b32_e32 v117, v0
	v_mov_b32_e32 v118, v0
	v_mov_b32_e32 v119, v0
	v_mov_b32_e32 v120, v0
	v_mov_b32_e32 v121, v0
	v_mov_b32_e32 v122, v0
	v_mov_b32_e32 v123, v0
	v_mov_b32_e32 v124, v0
	v_mov_b32_e32 v125, v0
	v_mov_b32_e32 v126, v0
	v_mov_b32_e32 v127, v0
; template <int N> DI void wait_vm() { asm volatile("s_waitcnt vmcnt(%0)" ::"n"(N) : "memory"); }
; template <int BM, class Epi>
; DI void gemm_dma(const u16* __restrict__ X, long ldx, const u16* __restrict__ W, long ldw, int K, char* smem,
;                  int m0, int n0, const Epi& epi) {
;     ...
;   do {
;     if (kt + D - 2 < nk) wait_vm<PW * (D - 2)>(); else wait_vm<0>();
;     __syncthreads();
;     if (kt + D - 1 < nk) GD_ISSUE(nxt)
;     nxt = (nxt + 1 == D) ? 0 : nxt + 1;
;     const char* base = smem + cur * STG;
;     cur = (cur + 1 == D) ? 0 : cur + 1;
;     bf16x8 xf[MT];
; #pragma unroll
;     for (int i = 0; i < MT; ++i) xf[i] = *(const bf16x8*)(base + (xrow0 + i * 16) * 64 + rd);
; #pragma unroll
;     for (int nh = 0; nh < NT / 4; ++nh) {
;       bf16x8 wf[4];
; #pragma unroll
;       for (int i = 0; i < 4; ++i) wf[i] = *(const bf16x8*)(base + BM * 64 + (wrow0 + (nh * 4 + i) * 16) * 64 + rd);
; #pragma unroll
;       for (int i = 0; i < 4; ++i)
; #pragma unroll
;         for (int mt = 0; mt < MT; ++mt)
;           acc[nh * 4 + i][mt] = __builtin_amdgcn_mfma_f32_16x16x32_bf16(wf[i], xf[mt], acc[nh * 4 + i][mt], 0, 0, 0);
;     }
;   } while (++kt < nk);
.LBB0_32:
	s_mul_i32 s12, s10, 0x6000
	v_lshl_add_u64 v[196:197], v[130:131], 0, s[40:41]
	s_waitcnt vmcnt(6)
	s_barrier
	s_mul_i32 s98, s11, 0x6000
	v_or_b32_e32 v137, s98, v134
	v_add_u32_e32 v150, v137, v136
	ds_read_b128 v[138:141], v150
	ds_read_b128 v[142:145], v150 offset:1024
	ds_read_b128 v[146:149], v150 offset:2048
	ds_read_b128 v[150:153], v150 offset:3072
	ds_read_b128 v[154:157], v137 offset:16384
	ds_read_b128 v[158:161], v137 offset:17408
	ds_read_b128 v[162:165], v137 offset:18432
	ds_read_b128 v[166:169], v137 offset:19456
	ds_read_b128 v[226:229], v137 offset:20480
	ds_read_b128 v[230:233], v137 offset:21504
	ds_read_b128 v[234:237], v137 offset:22528
	ds_read_b128 v[238:241], v137 offset:23552
	s_add_i32 s13, s12, s8
	s_mov_b32 m0, s13
	s_nop 0
	global_load_lds_dwordx4 v[196:197], off
	v_lshl_add_u64 v[224:225], v[196:197], 0, s[16:17]
	s_add_i32 s14, s13, 0x400
	s_mov_b32 m0, s14
	s_nop 0
	global_load_lds_dwordx4 v[224:225], off
	v_lshl_add_u64 v[224:225], v[196:197], 0, s[18:19]
	s_add_i32 s14, s13, 0x800
	s_mov_b32 m0, s14
	s_nop 0
	global_load_lds_dwordx4 v[224:225], off
	v_lshl_add_u64 v[196:197], v[196:197], 0, s[20:21]
	s_addk_i32 s13, 0xc00
	s_mov_b32 m0, s13
	s_nop 0
	global_load_lds_dwordx4 v[196:197], off
	s_add_i32 s12, s12, s9
	v_lshl_add_u64 v[194:195], v[128:129], 0, s[40:41]
	s_mov_b32 m0, s12
	s_nop 0
	global_load_lds_dwordx4 v[194:195], off
	s_addk_i32 s12, 0x400
	v_lshl_add_u64 v[194:195], v[194:195], 0, s[16:17]
	s_mov_b32 m0, s12
	s_nop 0
	global_load_lds_dwordx4 v[194:195], off
	s_waitcnt lgkmcnt(7)
	v_mfma_f32_16x16x32_bf16 v[124:127], v[154:157], v[138:141], v[124:127]
	s_add_i32 s10, s10, 1
	s_add_i32 s11, s11, 1
	s_cmp_lg_u32 s10, 3
	v_mfma_f32_16x16x32_bf16 v[120:123], v[154:157], v[142:145], v[120:123]
	s_cselect_b32 s10, s10, 0
	s_cmp_lg_u32 s11, 3
	s_cselect_b32 s11, s11, 0
	v_mfma_f32_16x16x32_bf16 v[116:119], v[154:157], v[146:149], v[116:119]
	s_add_u32 s40, s40, 64
	s_addc_u32 s41, s41, 0
	s_cmpk_lg_i32 s40, 0x780
	v_mfma_f32_16x16x32_bf16 v[112:115], v[154:157], v[150:153], v[112:115]
	s_waitcnt lgkmcnt(6)
	v_mfma_f32_16x16x32_bf16 v[108:111], v[158:161], v[138:141], v[108:111]
	v_mfma_f32_16x16x32_bf16 v[104:107], v[158:161], v[142:145], v[104:107]
	v_mfma_f32_16x16x32_bf16 v[100:103], v[158:161], v[146:149], v[100:103]
	v_mfma_f32_16x16x32_bf16 v[96:99], v[158:161], v[150:153], v[96:99]
	s_waitcnt lgkmcnt(5)
	v_mfma_f32_16x16x32_bf16 v[92:95], v[162:165], v[138:141], v[92:95]
	v_mfma_f32_16x16x32_bf16 v[88:91], v[162:165], v[142:145], v[88:91]
	v_mfma_f32_16x16x32_bf16 v[84:87], v[162:165], v[146:149], v[84:87]
	v_mfma_f32_16x16x32_bf16 v[80:83], v[162:165], v[150:153], v[80:83]
	s_waitcnt lgkmcnt(4)
	v_mfma_f32_16x16x32_bf16 v[76:79], v[166:169], v[138:141], v[76:79]
	v_mfma_f32_16x16x32_bf16 v[72:75], v[166:169], v[142:145], v[72:75]
	v_mfma_f32_16x16x32_bf16 v[68:71], v[166:169], v[146:149], v[68:71]
	v_mfma_f32_16x16x32_bf16 v[64:67], v[166:169], v[150:153], v[64:67]
	s_waitcnt lgkmcnt(3)
	v_mfma_f32_16x16x32_bf16 v[60:63], v[226:229], v[138:141], v[60:63]
	v_mfma_f32_16x16x32_bf16 v[56:59], v[226:229], v[142:145], v[56:59]
	v_mfma_f32_16x16x32_bf16 v[52:55], v[226:229], v[146:149], v[52:55]
	v_mfma_f32_16x16x32_bf16 v[48:51], v[226:229], v[150:153], v[48:51]
	s_waitcnt lgkmcnt(2)
	v_mfma_f32_16x16x32_bf16 v[44:47], v[230:233], v[138:141], v[44:47]
	v_mfma_f32_16x16x32_bf16 v[40:43], v[230:233], v[142:145], v[40:43]
	v_mfma_f32_16x16x32_bf16 v[36:39], v[230:233], v[146:149], v[36:39]
	v_mfma_f32_16x16x32_bf16 v[32:35], v[230:233], v[150:153], v[32:35]
	s_waitcnt lgkmcnt(1)
	v_mfma_f32_16x16x32_bf16 v[28:31], v[234:237], v[138:141], v[28:31]
	v_mfma_f32_16x16x32_bf16 v[24:27], v[234:237], v[142:145], v[24:27]
	v_mfma_f32_16x16x32_bf16 v[20:23], v[234:237], v[146:149], v[20:23]
	v_mfma_f32_16x16x32_bf16 v[16:19], v[234:237], v[150:153], v[16:19]
	s_waitcnt lgkmcnt(0)
	v_mfma_f32_16x16x32_bf16 v[12:15], v[238:241], v[138:141], v[12:15]
	v_mfma_f32_16x16x32_bf16 v[8:11], v[238:241], v[142:145], v[8:11]
	v_mfma_f32_16x16x32_bf16 v[4:7], v[238:241], v[146:149], v[4:7]
	v_mfma_f32_16x16x32_bf16 v[0:3], v[238:241], v[150:153], v[0:3]
	s_cbranch_scc1 .LBB0_32
	v_add_u32_e32 v180, v134, v136
	s_waitcnt vmcnt(6)
	s_barrier
	ds_read_b128 v[128:131], v180
	ds_read_b128 v[136:139], v180 offset:1024
	ds_read_b128 v[140:143], v180 offset:2048
	ds_read_b128 v[144:147], v180 offset:3072
	ds_read_b128 v[148:151], v134 offset:16384
	ds_read_b128 v[152:155], v134 offset:17408
	ds_read_b128 v[156:159], v134 offset:18432
	ds_read_b128 v[160:163], v134 offset:19456
	s_waitcnt lgkmcnt(3)
	v_mfma_f32_16x16x32_bf16 v[124:127], v[148:151], v[128:131], v[124:127]
	s_lshl_b32 s7, s7, 8
	v_lshl_or_b32 v182, v132, 3, s7
	v_mfma_f32_16x16x32_bf16 v[120:123], v[148:151], v[136:139], v[120:123]
	v_mfma_f32_16x16x32_bf16 v[116:119], v[148:151], v[140:143], v[116:119]
	v_mfma_f32_16x16x32_bf16 v[112:115], v[148:151], v[144:147], v[112:115]
	s_waitcnt lgkmcnt(2)
	v_mfma_f32_16x16x32_bf16 v[108:111], v[152:155], v[128:131], v[108:111]
	v_mfma_f32_16x16x32_bf16 v[104:107], v[152:155], v[136:139], v[104:107]
	v_mfma_f32_16x16x32_bf16 v[100:103], v[152:155], v[140:143], v[100:103]
	v_mfma_f32_16x16x32_bf16 v[96:99], v[152:155], v[144:147], v[96:99]
	s_waitcnt lgkmcnt(1)
	v_mfma_f32_16x16x32_bf16 v[92:95], v[156:159], v[128:131], v[92:95]
	v_mfma_f32_16x16x32_bf16 v[88:91], v[156:159], v[136:139], v[88:91]
	v_mfma_f32_16x16x32_bf16 v[84:87], v[156:159], v[140:143], v[84:87]
	v_mfma_f32_16x16x32_bf16 v[148:151], v[156:159], v[144:147], v[80:83]
	s_waitcnt lgkmcnt(0)
	v_mfma_f32_16x16x32_bf16 v[76:79], v[160:163], v[128:131], v[76:79]
	v_mfma_f32_16x16x32_bf16 v[152:155], v[160:163], v[136:139], v[72:75]
	v_mfma_f32_16x16x32_bf16 v[68:71], v[160:163], v[140:143], v[68:71]
	v_mfma_f32_16x16x32_bf16 v[156:159], v[160:163], v[144:147], v[64:67]
	s_nop 2
	ds_read_b128 v[64:67], v134 offset:20480
	ds_read_b128 v[72:75], v134 offset:21504
	ds_read_b128 v[80:83], v134 offset:22528
	ds_read_b128 v[160:163], v134 offset:23552
	s_waitcnt vmcnt(0)
	s_waitcnt lgkmcnt(0)
	v_mfma_f32_16x16x32_bf16 v[60:63], v[64:67], v[128:131], v[60:63]
	s_barrier
; DI void st_bf4(u16* p, float a, float b, float c, float d) { *(uint2*)p = make_uint2(pk2(a, b), pk2(c, d)); }
; template <int BM, class Epi>
; DI void gemm_dma(const u16* __restrict__ X, long ldx, const u16* __restrict__ W, long ldw, int K, char* smem,
;                  int m0, int n0, const Epi& epi) {
;     ...
;     for (int i = 0; i < MT; ++i) xf[i] = *(const bf16x8*)(base + (xrow0 + i * 16) * 64 + rd);
; #pragma unroll
;     for (int nh = 0; nh < NT / 4; ++nh) {
;       bf16x8 wf[4];
; #pragma unroll
;       for (int i = 0; i < 4; ++i) wf[i] = *(const bf16x8*)(base + BM * 64 + (wrow0 + (nh * 4 + i) * 16) * 64 + rd);
; #pragma unroll
;       for (int i = 0; i < 4; ++i)
; #pragma unroll
;         for (int mt = 0; mt < MT; ++mt)
;           acc[nh * 4 + i][mt] = __builtin_amdgcn_mfma_f32_16x16x32_bf16(wf[i], xf[mt], acc[nh * 4 + i][mt], 0, 0, 0);
;     }
;   } while (++kt < nk);
;   template <int NT, int MT> DI void run(f32x4 (&acc)[NT][MT], int mb, int nb) const {
; #pragma unroll
;     for (int nt = 0; nt < NT; ++nt)
; #pragma unroll
;       for (int mt = 0; mt < MT; ++mt) {
;         f32x4 v = acc[nt][mt];
;         st_bf4(C + (size_t)(mb + mt * 16) * ldc + nb + nt * 16, v[0], v[1], v[2], v[3]);
;       }
	v_mfma_f32_16x16x32_bf16 v[164:167], v[64:67], v[136:139], v[56:59]
	v_mfma_f32_16x16x32_bf16 v[52:55], v[64:67], v[140:143], v[52:55]
	v_mfma_f32_16x16x32_bf16 v[168:171], v[64:67], v[144:147], v[48:51]
	v_mfma_f32_16x16x32_bf16 v[44:47], v[72:75], v[128:131], v[44:47]
	v_mfma_f32_16x16x32_bf16 v[172:175], v[72:75], v[136:139], v[40:43]
	v_mfma_f32_16x16x32_bf16 v[36:39], v[72:75], v[140:143], v[36:39]
	v_mfma_f32_16x16x32_bf16 v[176:179], v[72:75], v[144:147], v[32:35]
	v_mfma_f32_16x16x32_bf16 v[28:31], v[80:83], v[128:131], v[28:31]
	v_mfma_f32_16x16x32_bf16 v[24:27], v[80:83], v[136:139], v[24:27]
	v_mfma_f32_16x16x32_bf16 v[20:23], v[80:83], v[140:143], v[20:23]
	v_mfma_f32_16x16x32_bf16 v[16:19], v[80:83], v[144:147], v[16:19]
	v_mfma_f32_16x16x32_bf16 v[12:15], v[160:163], v[128:131], v[12:15]
	v_mfma_f32_16x16x32_bf16 v[8:11], v[160:163], v[136:139], v[8:11]
	v_mfma_f32_16x16x32_bf16 v[4:7], v[160:163], v[140:143], v[4:7]
	v_mfma_f32_16x16x32_bf16 v[0:3], v[160:163], v[144:147], v[0:3]
	ds_read_b128 v[128:131], v180 offset:24576
	ds_read_b128 v[136:139], v180 offset:25600
	ds_read_b128 v[140:143], v180 offset:26624
	ds_read_b128 v[144:147], v180 offset:27648
	ds_read_b128 v[32:35], v134 offset:40960
	ds_read_b128 v[40:43], v134 offset:41984
	ds_read_b128 v[48:51], v134 offset:43008
	ds_read_b128 v[160:163], v134 offset:44032
	s_waitcnt lgkmcnt(2)
	v_mfma_f32_16x16x32_bf16 v[108:111], v[40:43], v[128:131], v[108:111]
	v_mfma_f32_16x16x32_bf16 v[104:107], v[40:43], v[136:139], v[104:107]
	v_mfma_f32_16x16x32_bf16 v[100:103], v[40:43], v[140:143], v[100:103]
	s_nop 5
	v_cvt_pk_bf16_f32 v108, v108, v109
	v_cvt_pk_bf16_f32 v109, v110, v111
	v_cvt_pk_bf16_f32 v104, v104, v105
	v_mfma_f32_16x16x32_bf16 v[96:99], v[40:43], v[144:147], v[96:99]
	v_cvt_pk_bf16_f32 v105, v106, v107
	v_cvt_pk_bf16_f32 v100, v100, v101
	v_cvt_pk_bf16_f32 v101, v102, v103
	s_waitcnt lgkmcnt(1)
	v_mfma_f32_16x16x32_bf16 v[92:95], v[48:51], v[128:131], v[92:95]
	v_mfma_f32_16x16x32_bf16 v[80:83], v[48:51], v[136:139], v[88:91]
	s_nop 1
	v_cvt_pk_bf16_f32 v96, v96, v97
	v_cvt_pk_bf16_f32 v97, v98, v99
	s_nop 2
	v_cvt_pk_bf16_f32 v92, v92, v93
	v_mfma_f32_16x16x32_bf16 v[72:75], v[48:51], v[140:143], v[84:87]
	v_cvt_pk_bf16_f32 v93, v94, v95
	v_cvt_pk_bf16_f32 v80, v80, v81
	v_cvt_pk_bf16_f32 v81, v82, v83
	v_mfma_f32_16x16x32_bf16 v[64:67], v[48:51], v[144:147], v[148:151]
	s_waitcnt lgkmcnt(0)
	v_mfma_f32_16x16x32_bf16 v[48:51], v[160:163], v[136:139], v[152:155]
	s_nop 1
	v_cvt_pk_bf16_f32 v72, v72, v73
	v_cvt_pk_bf16_f32 v73, v74, v75
	s_nop 1
	v_cvt_pk_bf16_f32 v64, v64, v65
	v_mfma_f32_16x16x32_bf16 v[40:43], v[160:163], v[140:143], v[68:71]
	s_nop 2
	ds_read_b128 v[68:71], v134 offset:45056
	ds_read_b128 v[88:91], v134 offset:46080
	ds_read_b128 v[148:151], v134 offset:47104
	ds_read_b128 v[152:155], v134 offset:48128
	v_cvt_pk_bf16_f32 v65, v66, v67
	v_cvt_pk_bf16_f32 v48, v48, v49
	v_mfma_f32_16x16x32_bf16 v[124:127], v[32:35], v[128:131], v[124:127]
	v_cvt_pk_bf16_f32 v49, v50, v51
	v_cvt_pk_bf16_f32 v40, v40, v41
	v_cvt_pk_bf16_f32 v41, v42, v43
	v_mfma_f32_16x16x32_bf16 v[120:123], v[32:35], v[136:139], v[120:123]
	v_mfma_f32_16x16x32_bf16 v[116:119], v[32:35], v[140:143], v[116:119]
	v_mfma_f32_16x16x32_bf16 v[112:115], v[32:35], v[144:147], v[112:115]
	s_nop 5
	v_cvt_pk_bf16_f32 v120, v120, v121
	v_cvt_pk_bf16_f32 v121, v122, v123
	v_cvt_pk_bf16_f32 v116, v116, v117
	v_mfma_f32_16x16x32_bf16 v[56:59], v[160:163], v[128:131], v[76:79]
	v_cvt_pk_bf16_f32 v117, v118, v119
	v_cvt_pk_bf16_f32 v112, v112, v113
	v_cvt_pk_bf16_f32 v113, v114, v115
	v_mfma_f32_16x16x32_bf16 v[32:35], v[160:163], v[144:147], v[156:159]
	s_waitcnt lgkmcnt(3)
	v_mfma_f32_16x16x32_bf16 v[156:159], v[68:71], v[128:131], v[60:63]
	s_nop 1
	v_cvt_pk_bf16_f32 v56, v56, v57
	s_nop 2
	v_cvt_pk_bf16_f32 v32, v32, v33
	v_cvt_pk_bf16_f32 v33, v34, v35
	v_mfma_f32_16x16x32_bf16 v[76:79], v[68:71], v[140:143], v[52:55]
	v_cvt_pk_bf16_f32 v57, v58, v59
	s_waitcnt lgkmcnt(2)
	v_mfma_f32_16x16x32_bf16 v[60:63], v[88:91], v[128:131], v[44:47]
	v_mfma_f32_16x16x32_bf16 v[52:55], v[88:91], v[136:139], v[172:175]
	v_mfma_f32_16x16x32_bf16 v[44:47], v[88:91], v[140:143], v[36:39]
	v_mfma_f32_16x16x32_bf16 v[36:39], v[88:91], v[144:147], v[176:179]
	v_lshl_add_u32 v88, s38, 8, v135
	v_cvt_pk_bf16_f32 v90, v124, v125
	v_cvt_pk_bf16_f32 v91, v126, v127
	s_waitcnt lgkmcnt(1)
; DI void st_bf4(u16* p, float a, float b, float c, float d) { *(uint2*)p = make_uint2(pk2(a, b), pk2(c, d)); }
;   template <int NT, int MT> DI void run(f32x4 (&acc)[NT][MT], int mb, int nb) const {
; #pragma unroll
;     for (int nt = 0; nt < NT; ++nt)
; #pragma unroll
;       for (int mt = 0; mt < MT; ++mt) {
;         f32x4 v = acc[nt][mt];
;         st_bf4(C + (size_t)(mb + mt * 16) * ldc + nb + nt * 16, v[0], v[1], v[2], v[3]);
;       }
	v_mfma_f32_16x16x32_bf16 v[28:31], v[148:151], v[128:131], v[28:31]
	s_waitcnt lgkmcnt(0)
	v_mfma_f32_16x16x32_bf16 v[12:15], v[152:155], v[128:131], v[12:15]
	v_or_b32_e32 v128, v88, v133
	v_ashrrev_i32_e32 v129, 31, v128
	v_lshlrev_b64 v[88:89], 11, v[128:129]
	v_lshl_add_u64 v[88:89], s[92:93], 0, v[88:89]
	v_lshl_add_u64 v[88:89], v[88:89], 0, v[182:183]
	global_store_dwordx2 v[88:89], v[90:91], off
	v_or_b32_e32 v90, 16, v128
	v_ashrrev_i32_e32 v91, 31, v90
	v_lshlrev_b64 v[90:91], 11, v[90:91]
	v_lshl_add_u64 v[90:91], s[92:93], 0, v[90:91]
	v_lshl_add_u64 v[90:91], v[90:91], 0, v[182:183]
	global_store_dwordx2 v[90:91], v[120:121], off
	v_or_b32_e32 v120, 32, v128
	v_ashrrev_i32_e32 v121, 31, v120
	v_lshlrev_b64 v[120:121], 11, v[120:121]
	v_lshl_add_u64 v[120:121], s[92:93], 0, v[120:121]
	v_lshl_add_u64 v[120:121], v[120:121], 0, v[182:183]
	global_store_dwordx2 v[120:121], v[116:117], off
	v_or_b32_e32 v116, 48, v128
	v_ashrrev_i32_e32 v117, 31, v116
	v_mfma_f32_16x16x32_bf16 v[84:87], v[68:71], v[136:139], v[164:167]
	v_lshlrev_b64 v[116:117], 11, v[116:117]
	v_lshl_add_u64 v[116:117], s[92:93], 0, v[116:117]
	v_lshl_add_u64 v[116:117], v[116:117], 0, v[182:183]
	v_mfma_f32_16x16x32_bf16 v[68:71], v[68:71], v[144:147], v[168:171]
	global_store_dwordx2 v[116:117], v[32:33], off offset:96
	v_cvt_pk_bf16_f32 v32, v156, v157
	v_cvt_pk_bf16_f32 v33, v158, v159
	global_store_dwordx2 v[88:89], v[32:33], off offset:128
	v_cvt_pk_bf16_f32 v32, v84, v85
	v_cvt_pk_bf16_f32 v33, v86, v87
	global_store_dwordx2 v[90:91], v[32:33], off offset:128
	v_cvt_pk_bf16_f32 v32, v76, v77
	v_cvt_pk_bf16_f32 v33, v78, v79
	v_mfma_f32_16x16x32_bf16 v[24:27], v[148:151], v[136:139], v[24:27]
	global_store_dwordx2 v[120:121], v[32:33], off offset:128
	v_cvt_pk_bf16_f32 v32, v68, v69
	v_cvt_pk_bf16_f32 v33, v70, v71
	v_mfma_f32_16x16x32_bf16 v[20:23], v[148:151], v[140:143], v[20:23]
	global_store_dwordx2 v[116:117], v[32:33], off offset:128
	v_cvt_pk_bf16_f32 v32, v60, v61
	v_cvt_pk_bf16_f32 v33, v62, v63
	v_mfma_f32_16x16x32_bf16 v[16:19], v[148:151], v[144:147], v[16:19]
	global_store_dwordx2 v[88:89], v[32:33], off offset:160
	v_cvt_pk_bf16_f32 v32, v52, v53
	v_cvt_pk_bf16_f32 v33, v54, v55
	v_mfma_f32_16x16x32_bf16 v[8:11], v[152:155], v[136:139], v[8:11]
	global_store_dwordx2 v[90:91], v[32:33], off offset:160
	v_cvt_pk_bf16_f32 v32, v44, v45
	v_cvt_pk_bf16_f32 v33, v46, v47
	v_mfma_f32_16x16x32_bf16 v[4:7], v[152:155], v[140:143], v[4:7]
	global_store_dwordx2 v[120:121], v[32:33], off offset:160
	v_cvt_pk_bf16_f32 v32, v36, v37
	v_cvt_pk_bf16_f32 v33, v38, v39
	v_mfma_f32_16x16x32_bf16 v[0:3], v[152:155], v[144:147], v[0:3]
	v_cvt_pk_bf16_f32 v28, v28, v29
	v_cvt_pk_bf16_f32 v29, v30, v31
	v_cvt_pk_bf16_f32 v24, v24, v25
	v_cvt_pk_bf16_f32 v25, v26, v27
	v_cvt_pk_bf16_f32 v20, v20, v21
	v_cvt_pk_bf16_f32 v21, v22, v23
	v_cvt_pk_bf16_f32 v16, v16, v17
	v_cvt_pk_bf16_f32 v17, v18, v19
	v_cvt_pk_bf16_f32 v12, v12, v13
	v_cvt_pk_bf16_f32 v13, v14, v15
	v_cvt_pk_bf16_f32 v8, v8, v9
	v_cvt_pk_bf16_f32 v9, v10, v11
	v_cvt_pk_bf16_f32 v4, v4, v5
	v_cvt_pk_bf16_f32 v5, v6, v7
	v_cvt_pk_bf16_f32 v0, v0, v1
	v_cvt_pk_bf16_f32 v1, v2, v3
	global_store_dwordx2 v[116:117], v[112:113], off
	global_store_dwordx2 v[88:89], v[108:109], off offset:32
	global_store_dwordx2 v[90:91], v[104:105], off offset:32
	global_store_dwordx2 v[120:121], v[100:101], off offset:32
	global_store_dwordx2 v[116:117], v[96:97], off offset:32
	global_store_dwordx2 v[88:89], v[92:93], off offset:64
	global_store_dwordx2 v[90:91], v[80:81], off offset:64
	global_store_dwordx2 v[120:121], v[72:73], off offset:64
	global_store_dwordx2 v[116:117], v[64:65], off offset:64
	global_store_dwordx2 v[88:89], v[56:57], off offset:96
	global_store_dwordx2 v[90:91], v[48:49], off offset:96
	global_store_dwordx2 v[120:121], v[40:41], off offset:96
	global_store_dwordx2 v[116:117], v[32:33], off offset:160
	global_store_dwordx2 v[88:89], v[28:29], off offset:192
	global_store_dwordx2 v[90:91], v[24:25], off offset:192
	global_store_dwordx2 v[120:121], v[20:21], off offset:192
	global_store_dwordx2 v[116:117], v[16:17], off offset:192
	global_store_dwordx2 v[88:89], v[12:13], off offset:224
	global_store_dwordx2 v[90:91], v[8:9], off offset:224
	global_store_dwordx2 v[120:121], v[4:5], off offset:224
	global_store_dwordx2 v[116:117], v[0:1], off offset:224
	s_branch .LBB0_25

; DI float zero_f() { float z = 0.f; asm volatile("" : "+v"(z)); return z; }
; DI void attn_item(const u16* __restrict__ qbuf, const u16* __restrict__ knope, const u16* __restrict__ krope, ...
;     ...
;   f32x16 oacc[4];
;   { const float z = zero_f();
; #pragma unroll
;   for (int i = 0; i < 4; ++i)
; #pragma unroll
;     for (int j = 0; j < 16; ++j) oacc[i][j] = z; }
;   float m_run = -INFINITY, l_run = 0.f;
;   const int wu = __builtin_amdgcn_readfirstlane(wave);
;   const unsigned sbase = (unsigned)__builtin_amdgcn_readfirstlane((int)(unsigned)(size_t)smem);
;   const int r8 = lane >> 3, c0 = (lane & 7) ^ (r8 >> 1);
;   const unsigned ce = (unsigned)(c0 << 3), co = (unsigned)((c0 ^ 4) << 3);
;   unsigned ko = (unsigned)((kvrow0 + (wu & 1) * 32 + r8) * 1024 + head * 128 + (wu >> 1) * 64);
;   unsigned ro = (unsigned)((kvrow0 + wu * 16 + r8) * 64);
;   unsigned vo = (unsigned)((head * 128 + wu * 32 + r8) * vt_ld);
;   const unsigned vld8 = (unsigned)vt_ld * 8u;
;   const unsigned kdst = sbase + (wu >> 1) * 8192 + (wu & 1) * 4096;
;   const unsigned rdst = sbase + 16384 + wu * 2048;
;   const unsigned vdst = sbase + 24576 + wu * 4096;
;     ...
;   __syncthreads();
;   ATT_DMA(0u)
.LBB0_45:
	s_or_b64 exec, exec, s[40:41]
	s_mul_i32 s10, s7, 0x240000
	v_readlane_b32 s2, v252, 28
	s_mul_hi_u32 s9, s7, 0x240000
	s_add_u32 s40, s2, s10
	s_addc_u32 s41, s91, s9
	s_mulk_i32 s7, 0x460
	s_and_b32 s9, s87, 7
	v_and_b32_e32 v18, 63, v16
	s_add_i32 s8, s8, s7
	s_lshr_b32 s7, s4, 3
	s_lshl_b32 s12, s9, 7
	v_readfirstlane_b32 s9, v17
	v_lshrrev_b32_e32 v1, 1, v16
	s_mul_i32 s10, s7, 0x120000
	s_mul_i32 s13, s7, 0x12000
	v_lshrrev_b32_e32 v19, 3, v18
	v_lshrrev_b32_e32 v17, 4, v18
	s_and_b32 s7, s9, 1
	s_ashr_i32 s14, s9, 1
	v_bfe_u32 v2, v16, 1, 3
	v_lshlrev_b32_e32 v0, 7, v0
	v_bitop3_b32 v1, v147, v1, 7 bitop3:0x78
	v_bitop3_b32 v16, v17, v16, 7 bitop3:0x78
	s_lshl_b32 s6, s6, 7
	s_lshl_b32 s15, s14, 6
	v_or_b32_e32 v18, s8, v19
	s_lshl_b32 s16, s7, 15
	v_lshl_or_b32 v150, v1, 4, v0
	v_bitop3_b32 v1, v147, v2, 2 bitop3:0x36
	v_lshlrev_b32_e32 v152, 3, v16
	v_lshl_or_b32 v16, v18, 10, s6
	s_add_i32 s8, s16, s15
	s_lshl_b32 s17, s9, 5
	v_lshl_or_b32 v149, v1, 4, v0
	v_bitop3_b32 v1, v147, v2, 4 bitop3:0x36
	v_add_u32_e32 v20, s8, v16
	s_add_i32 s8, s17, s6
	v_lshl_or_b32 v148, v1, 4, v0
	v_bitop3_b32 v1, v147, v2, 6 bitop3:0x36
	v_or_b32_e32 v16, s8, v19
	s_movk_i32 s2, 0x480
	v_or_b32_e32 v182, v20, v152
	v_lshl_or_b32 v145, v1, 4, v0
	v_mov_b32_e32 v0, v183
	v_mul_lo_u32 v21, v16, s2
	s_lshl_b32 s8, s14, 13
	s_lshl_b32 s7, s7, 12
	v_lshl_add_u64 v[16:17], v[182:183], 1, s[92:93]
	v_bitop3_b32 v20, v20, v152, 32 bitop3:0xf6
	s_or_b32 s7, s8, s7
	s_barrier
	s_mov_b32 m0, s7
	s_nop 0
	global_load_lds_dwordx4 v[16:17], off
	v_add_u32_e32 v16, 0x2000, v20
	v_mov_b32_e32 v17, v183
	v_lshl_add_u64 v[16:17], v[16:17], 1, s[92:93]
	s_or_b32 s8, s7, 0x400
	s_mov_b32 m0, s8
	s_nop 0
	global_load_lds_dwordx4 v[16:17], off
	v_add_u32_e32 v182, 0x4000, v182
	v_lshl_add_u64 v[16:17], v[182:183], 1, s[92:93]
	s_or_b32 s8, s7, 0x800
	s_mov_b32 m0, s8
	s_nop 0
	global_load_lds_dwordx4 v[16:17], off
	v_add_u32_e32 v182, 0x6000, v20
	v_lshl_add_u64 v[16:17], v[182:183], 1, s[92:93]
	s_or_b32 s8, s7, 0xc00
	s_mov_b32 m0, s8
	s_nop 0
	global_load_lds_dwordx4 v[16:17], off
	s_lshl_b32 s19, s9, 10
	v_lshl_add_u32 v18, v18, 6, s19
	v_or_b32_e32 v182, v18, v152
	s_lshl_b32 s14, s9, 11
	v_lshl_add_u64 v[16:17], v[182:183], 1, s[30:31]
	v_bitop3_b32 v182, v152, v18, 32 bitop3:0xde
	s_lshl_b32 s18, s9, 12
	s_add_i32 s8, s14, 0x4000
	s_mov_b32 m0, s8
	s_nop 0
	global_load_lds_dwordx4 v[16:17], off
	v_lshl_add_u64 v[16:17], v[182:183], 1, s[30:31]
	s_mov_b64 s[22:23], 0x400
	v_lshl_add_u64 v[16:17], v[16:17], 0, s[22:23]
	v_or_b32_e32 v182, v21, v152
	s_addk_i32 s14, 0x4400
	s_mov_b32 m0, s14
	s_nop 0
	global_load_lds_dwordx4 v[16:17], off
	v_lshl_add_u64 v[16:17], v[182:183], 1, s[40:41]
	v_bitop3_b32 v18, v21, v152, 32 bitop3:0xf6
	s_add_i32 s9, s18, 0x6000
	s_mov_b32 m0, s9
	s_nop 0
	global_load_lds_dwordx4 v[16:17], off
	v_add_u32_e32 v16, 0x2400, v18
	v_mov_b32_e32 v17, v183
	v_lshl_add_u64 v[16:17], v[16:17], 1, s[40:41]
	s_add_i32 s14, s18, 0x6400
	s_mov_b32 m0, s14
	s_nop 0
	global_load_lds_dwordx4 v[16:17], off
	v_add_u32_e32 v182, 0x4800, v182
	v_lshl_add_u64 v[16:17], v[182:183], 1, s[40:41]
	s_add_i32 s14, s18, 0x6800
	s_mov_b32 m0, s14
	s_nop 0
	global_load_lds_dwordx4 v[16:17], off
	v_add_u32_e32 v182, 0x6c00, v18
	v_lshl_add_u64 v[16:17], v[182:183], 1, s[40:41]
	s_addk_i32 s18, 0x6c00
	s_mov_b32 m0, s18
	s_nop 0
	global_load_lds_dwordx4 v[16:17], off
	s_or_b32 s10, s10, s16
	s_add_i32 s14, s15, s12
	s_add_i32 s17, s17, s12
	v_mov_b32_e32 v14, v0
	v_mov_b32_e32 v15, v0
	s_add_i32 s14, s14, s10
	s_add_i32 s13, s13, s19
	v_or_b32_e32 v16, s17, v19
	v_mov_b32_e32 v1, v0
	v_mov_b32_e32 v2, v0
	v_mov_b32_e32 v3, v0
	v_mov_b32_e32 v4, v0
	v_mov_b32_e32 v5, v0
	v_mov_b32_e32 v6, v0
	v_mov_b32_e32 v7, v0
	v_mov_b32_e32 v8, v0
	v_mov_b32_e32 v9, v0
	v_mov_b32_e32 v10, v0
	v_mov_b32_e32 v11, v0
	v_mov_b32_e32 v12, v0
	v_mov_b32_e32 v13, v0
	v_lshl_add_u32 v154, v19, 10, s14
	v_lshl_or_b32 v155, v19, 6, s13
	v_mul_lo_u32 v156, v16, s2
	v_mov_b64_e32 v[30:31], v[14:15]
	v_mov_b64_e32 v[46:47], v[14:15]
	v_mov_b64_e32 v[62:63], v[14:15]
	v_xor_b32_e32 v153, 32, v152
	v_mov_b32_e32 v146, 0xff800000
	v_mov_b64_e32 v[28:29], v[12:13]
	v_mov_b64_e32 v[26:27], v[10:11]
	v_mov_b64_e32 v[24:25], v[8:9]
	v_mov_b64_e32 v[22:23], v[6:7]
	v_mov_b64_e32 v[20:21], v[4:5]
	v_mov_b64_e32 v[18:19], v[2:3]
	v_mov_b64_e32 v[16:17], v[0:1]
	v_mov_b64_e32 v[44:45], v[12:13]
	v_mov_b64_e32 v[42:43], v[10:11]
	v_mov_b64_e32 v[40:41], v[8:9]
	v_mov_b64_e32 v[38:39], v[6:7]
	v_mov_b64_e32 v[36:37], v[4:5]
	v_mov_b64_e32 v[34:35], v[2:3]
	v_mov_b64_e32 v[32:33], v[0:1]
	v_mov_b64_e32 v[60:61], v[12:13]
	v_mov_b64_e32 v[58:59], v[10:11]
	v_mov_b64_e32 v[56:57], v[8:9]
	v_mov_b64_e32 v[54:55], v[6:7]
	v_mov_b64_e32 v[52:53], v[4:5]
	v_mov_b64_e32 v[50:51], v[2:3]
	v_mov_b64_e32 v[48:49], v[0:1]
; DI void attn_item(const u16* __restrict__ qbuf, const u16* __restrict__ knope, const u16* __restrict__ krope, ...
;     ...
;   for (int kt = 0; kt < ntiles; ++kt) {
;     asm volatile("s_waitcnt vmcnt(0)" ::: "memory");
;     __syncthreads();
;     if (kt + 1 < ntiles) ATT_DMA((unsigned)((kt + 1) & 1) * 40960u)
;     if (active && kt < my_tiles) {
;       const char* cur = smem + (kt & 1) * 40960;
;       f32x16 st[2];
; #pragma unroll
;       for (int mt = 0; mt < 2; ++mt) {
; #pragma unroll
;         for (int j = 0; j < 16; ++j) st[mt][j] = 0.f;
; #pragma unroll
;         for (int ks = 0; ks < 12; ++ks) {
;           const bf16x8 kf = *(const bf16x8*)(cur + koff[ks & 3] + (ks >> 2) * 8192 + mt * 4096);
;           st[mt] = __builtin_amdgcn_mfma_f32_32x32x16_bf16(kf, qf[ks], st[mt], 0, 0, 0);
;         }
;       }
;       if (kt * 64 + 64 > nkeys) {
; #pragma unroll
;         for (int mt = 0; mt < 2; ++mt)
; #pragma unroll
;           for (int j = 0; j < 16; ++j) {
;             const int key = kt * 64 + mt * 32 + (j & 3) + 8 * (j >> 2) + 4 * h2;
;             if (key >= nkeys) st[mt][j] = -INFINITY;
;           }
;       }
;       float mx = fmaxf(st[0][0], st[1][0]);
; #pragma unroll
;       for (int j = 1; j < 16; ++j) mx = fmaxf(mx, fmaxf(st[0][j], st[1][j]));
;       mx = fmaxf(mx, __shfl_xor(mx, 32, 64));
;       const float m_new = fmaxf(m_run, mx);
;       const float alpha = __builtin_amdgcn_exp2f(m_run - m_new);
;       m_run = m_new;
;       float ps = 0.f;
; #pragma unroll
;       for (int mt = 0; mt < 2; ++mt)
; #pragma unroll
;         for (int j = 0; j < 16; ++j) { const float pv = __builtin_amdgcn_exp2f(st[mt][j] - m_new); st[mt][j] = pv; ps += pv; }
.LBB0_46:
	s_add_i32 s10, s11, 1
	s_bitcmp1_b32 s10, 0
	v_add_u32_e32 v66, v152, v154
	s_cselect_b32 s12, 0xa000, 0
	v_add_u32_e32 v182, 0x1010000, v66
	v_add_u32_e32 v67, v153, v154
	s_waitcnt vmcnt(0)
	s_barrier
	s_add_i32 s13, s12, s7
	v_lshl_add_u64 v[64:65], v[182:183], 1, s[92:93]
	s_mov_b32 m0, s13
	s_nop 0
	global_load_lds_dwordx4 v[64:65], off
	v_add_u32_e32 v182, 0x1012000, v67
	v_lshl_add_u64 v[64:65], v[182:183], 1, s[92:93]
	s_add_i32 s14, s13, 0x400
	s_mov_b32 m0, s14
	s_nop 0
	global_load_lds_dwordx4 v[64:65], off
	v_add_u32_e32 v182, 0x1014000, v66
	v_lshl_add_u64 v[64:65], v[182:183], 1, s[92:93]
	s_add_i32 s14, s13, 0x800
	s_mov_b32 m0, s14
	s_nop 0
	global_load_lds_dwordx4 v[64:65], off
	v_add_u32_e32 v182, 0x1016000, v67
	s_mov_b32 s2, 0x101000
	v_lshl_add_u64 v[64:65], v[182:183], 1, s[92:93]
	s_addk_i32 s13, 0xc00
	s_mov_b32 m0, s13
	s_nop 0
	global_load_lds_dwordx4 v[64:65], off
	v_add3_u32 v182, v152, v155, s2
	s_mov_b32 s2, 0x101200
	s_add_i32 s13, s12, s8
	v_lshl_add_u64 v[64:65], v[182:183], 1, s[30:31]
	s_mov_b32 m0, s13
	s_nop 0
	global_load_lds_dwordx4 v[64:65], off
	v_add3_u32 v182, v153, v155, s2
	v_add_u32_e32 v66, v152, v156
	v_lshl_add_u64 v[64:65], v[182:183], 1, s[30:31]
	s_addk_i32 s13, 0x400
	s_mov_b32 m0, s13
	s_nop 0
	global_load_lds_dwordx4 v[64:65], off
	v_add_u32_e32 v182, 64, v66
	v_add_u32_e32 v67, v153, v156
	s_add_i32 s12, s12, s9
	v_lshl_add_u64 v[64:65], v[182:183], 1, s[40:41]
	s_mov_b32 m0, s12
	s_nop 0
	global_load_lds_dwordx4 v[64:65], off
	v_add_u32_e32 v182, 0x2440, v67
	v_lshl_add_u64 v[64:65], v[182:183], 1, s[40:41]
	s_add_i32 s13, s12, 0x400
	s_mov_b32 m0, s13
	s_nop 0
	global_load_lds_dwordx4 v[64:65], off
	v_add_u32_e32 v182, 0x4840, v66
	v_lshl_add_u64 v[64:65], v[182:183], 1, s[40:41]
	s_add_i32 s13, s12, 0x800
	s_mov_b32 m0, s13
	s_nop 0
	global_load_lds_dwordx4 v[64:65], off
	v_add_u32_e32 v182, 0x6c40, v67
	v_lshl_add_u64 v[64:65], v[182:183], 1, s[40:41]
	s_addk_i32 s12, 0xc00
	s_mov_b32 m0, s12
	s_nop 0
	global_load_lds_dwordx4 v[64:65], off
	s_and_saveexec_b64 s[42:43], s[38:39]
	s_cbranch_execz .LBB0_50
	s_bitcmp1_b32 s11, 0
	s_cselect_b32 s11, 0xa000, 0
	v_or_b32_e32 v157, s11, v150
	v_or_b32_e32 v162, s11, v149
	v_or_b32_e32 v163, s11, v148
	v_or_b32_e32 v164, s11, v145
	ds_read_b128 v[224:227], v157
	ds_read_b128 v[228:231], v162
	ds_read_b128 v[232:235], v163
	ds_read_b128 v[236:239], v164
	ds_read_b128 v[240:243], v157 offset:8192
	ds_read_b128 v[244:247], v162 offset:8192
	ds_read_b128 v[248:251], v163 offset:8192
	ds_read_b128 v[186:189], v164 offset:8192
	s_waitcnt lgkmcnt(7)
	v_mfma_f32_32x32x16_bf16 v[64:79], v[224:227], v[140:143], 0
	ds_read_b128 v[224:227], v157 offset:16384
	s_waitcnt lgkmcnt(7)
	v_mfma_f32_32x32x16_bf16 v[64:79], v[228:231], v[136:139], v[64:79]
	ds_read_b128 v[228:231], v162 offset:16384
	s_waitcnt lgkmcnt(7)
	v_mfma_f32_32x32x16_bf16 v[64:79], v[232:235], v[132:135], v[64:79]
	ds_read_b128 v[232:235], v163 offset:16384
	s_waitcnt lgkmcnt(7)
	v_mfma_f32_32x32x16_bf16 v[64:79], v[236:239], v[128:131], v[64:79]
	ds_read_b128 v[236:239], v164 offset:16384
	s_waitcnt lgkmcnt(7)
	v_mfma_f32_32x32x16_bf16 v[64:79], v[240:243], v[124:127], v[64:79]
	ds_read_b128 v[240:243], v157 offset:4096
	s_waitcnt lgkmcnt(7)
	v_mfma_f32_32x32x16_bf16 v[64:79], v[244:247], v[120:123], v[64:79]
	ds_read_b128 v[244:247], v162 offset:4096
	s_waitcnt lgkmcnt(7)
	v_mfma_f32_32x32x16_bf16 v[64:79], v[248:251], v[116:119], v[64:79]
	ds_read_b128 v[248:251], v163 offset:4096
	s_waitcnt lgkmcnt(7)
	v_mfma_f32_32x32x16_bf16 v[64:79], v[186:189], v[112:115], v[64:79]
	ds_read_b128 v[186:189], v164 offset:4096
	s_waitcnt lgkmcnt(7)
	v_mfma_f32_32x32x16_bf16 v[64:79], v[224:227], v[108:111], v[64:79]
	ds_read_b128 v[224:227], v157 offset:12288
	s_waitcnt lgkmcnt(7)
	v_mfma_f32_32x32x16_bf16 v[64:79], v[228:231], v[104:107], v[64:79]
	ds_read_b128 v[228:231], v162 offset:12288
	s_waitcnt lgkmcnt(7)
	v_mfma_f32_32x32x16_bf16 v[64:79], v[232:235], v[100:103], v[64:79]
	ds_read_b128 v[232:235], v163 offset:12288
	s_waitcnt lgkmcnt(7)
	v_mfma_f32_32x32x16_bf16 v[64:79], v[236:239], v[96:99], v[64:79]
	ds_read_b128 v[236:239], v164 offset:12288
	s_waitcnt lgkmcnt(7)
	v_mfma_f32_32x32x16_bf16 v[80:95], v[240:243], v[140:143], 0
	ds_read_b128 v[240:243], v157 offset:20480
	s_waitcnt lgkmcnt(7)
	v_mfma_f32_32x32x16_bf16 v[80:95], v[244:247], v[136:139], v[80:95]
	ds_read_b128 v[244:247], v162 offset:20480
	s_waitcnt lgkmcnt(7)
	v_mfma_f32_32x32x16_bf16 v[80:95], v[248:251], v[132:135], v[80:95]
	ds_read_b128 v[248:251], v163 offset:20480
	s_waitcnt lgkmcnt(7)
	v_mfma_f32_32x32x16_bf16 v[80:95], v[186:189], v[128:131], v[80:95]
	ds_read_b128 v[186:189], v164 offset:20480
	s_waitcnt lgkmcnt(7)
	v_mfma_f32_32x32x16_bf16 v[80:95], v[224:227], v[124:127], v[80:95]
	ds_read_b128 v[224:227], v157 offset:24576
	s_waitcnt lgkmcnt(7)
	v_mfma_f32_32x32x16_bf16 v[80:95], v[228:231], v[120:123], v[80:95]
	ds_read_b128 v[228:231], v157 offset:28672
	s_waitcnt lgkmcnt(7)
	v_mfma_f32_32x32x16_bf16 v[80:95], v[232:235], v[116:119], v[80:95]
	ds_read_b128 v[232:235], v157 offset:32768
	s_waitcnt lgkmcnt(7)
	v_mfma_f32_32x32x16_bf16 v[80:95], v[236:239], v[112:115], v[80:95]
	ds_read_b128 v[236:239], v157 offset:36864
	s_waitcnt lgkmcnt(7)
	v_mfma_f32_32x32x16_bf16 v[80:95], v[240:243], v[108:111], v[80:95]
	ds_read_b128 v[240:243], v162 offset:24576
	s_waitcnt lgkmcnt(7)
	v_mfma_f32_32x32x16_bf16 v[80:95], v[244:247], v[104:107], v[80:95]
	ds_read_b128 v[244:247], v162 offset:28672
	s_waitcnt lgkmcnt(7)
	v_mfma_f32_32x32x16_bf16 v[80:95], v[248:251], v[100:103], v[80:95]
	ds_read_b128 v[248:251], v162 offset:32768
	s_waitcnt lgkmcnt(7)
	v_mfma_f32_32x32x16_bf16 v[80:95], v[186:189], v[96:99], v[80:95]
	ds_read_b128 v[186:189], v162 offset:36864
	s_nop 1
	v_max3_f32 v158, v64, v65, v66
	v_max3_f32 v159, v67, v68, v69
	v_max3_f32 v158, v158, v70, v71
	v_max3_f32 v159, v159, v72, v73
	v_max3_f32 v158, v158, v74, v75
	v_max3_f32 v159, v159, v76, v77
	v_max3_f32 v158, v158, v78, v79
	v_max_f32_e32 v158, v158, v159
	s_nop 1
	v_max3_f32 v159, v80, v81, v82
	v_max3_f32 v160, v83, v84, v85
	v_max3_f32 v159, v159, v86, v87
	v_max3_f32 v160, v160, v88, v89
	v_max3_f32 v159, v159, v90, v91
	v_max3_f32 v160, v160, v92, v93
	v_max3_f32 v159, v159, v94, v95
	v_max3_f32 v158, v158, v159, v160
	v_mov_b32_e32 v159, v158
	s_nop 1
	v_permlane32_swap_b32_e32 v158, v159
	v_max3_f32 v157, v146, v158, v159
	v_sub_f32_e32 v158, v146, v157
	v_cmp_gt_f32_e32 vcc, 0xc1000000, v158
	s_cbranch_vccnz .Lattn_resc_49
	v_mov_b32_e32 v157, v146
	v_mov_b32_e32 v146, 1.0
	s_branch .LBB0_49

; DI void attn_item(const u16* __restrict__ qbuf, const u16* __restrict__ knope, const u16* __restrict__ krope, ...
;     ...
;   const int wu = __builtin_amdgcn_readfirstlane(wave);
;   const unsigned sbase = (unsigned)__builtin_amdgcn_readfirstlane((int)(unsigned)(size_t)smem);
;   const int r8 = lane >> 3, c0 = (lane & 7) ^ (r8 >> 1);
;   const unsigned ce = (unsigned)(c0 << 3), co = (unsigned)((c0 ^ 4) << 3);
;   unsigned ko = (unsigned)((kvrow0 + (wu & 1) * 32 + r8) * 1024 + head * 128 + (wu >> 1) * 64);
;   unsigned ro = (unsigned)((kvrow0 + wu * 16 + r8) * 64);
;   unsigned vo = (unsigned)((head * 128 + wu * 32 + r8) * vt_ld);
;   const unsigned vld8 = (unsigned)vt_ld * 8u;
;   const unsigned kdst = sbase + (wu >> 1) * 8192 + (wu & 1) * 4096;
;   const unsigned rdst = sbase + 16384 + wu * 2048;
;   const unsigned vdst = sbase + 24576 + wu * 4096;
;     ...
;   __syncthreads();
;   ATT_DMA(0u)
;   for (int kt = 0; kt < ntiles; ++kt) {
;     asm volatile("s_waitcnt vmcnt(0)" ::: "memory");
;     __syncthreads();
;     if (kt + 1 < ntiles) ATT_DMA((unsigned)((kt + 1) & 1) * 40960u)
;     if (active && kt < my_tiles) {
.LBB0_62:
	s_or_b64 exec, exec, s[40:41]
	v_and_b32_e32 v3, 63, v0
	v_readfirstlane_b32 s11, v2
	v_lshrrev_b32_e32 v4, 3, v3
	v_lshrrev_b32_e32 v3, 4, v3
	s_and_b32 s10, s11, 1
	s_ashr_i32 s12, s11, 1
	v_bitop3_b32 v3, v3, v0, 7 bitop3:0x78
	s_lshl_b32 s14, s12, 6
	v_or_b32_e32 v5, s8, v4
	s_lshl_b32 s15, s10, 15
	v_lshlrev_b32_e32 v145, 3, v3
	v_lshl_or_b32 v3, v5, 10, s9
	s_add_i32 s15, s15, s14
	v_add_u32_e32 v3, s15, v3
	v_lshlrev_b32_e32 v8, 6, v5
	v_xor_b32_e32 v5, 32, v145
	v_or_b32_e32 v182, v3, v145
	v_add_u32_e32 v9, v3, v5
	v_mov_b32_e32 v48, v183
	s_lshl_b32 s12, s12, 13
	s_lshl_b32 s10, s10, 12
	v_lshl_add_u64 v[6:7], v[182:183], 1, s[92:93]
	v_add_u32_e32 v182, 0x2000, v9
	s_movk_i32 s2, 0x4000
	s_or_b32 s10, s12, s10
	s_barrier
	s_mov_b32 m0, s10
	s_nop 0
	global_load_lds_dwordx4 v[6:7], off
	v_lshl_add_u64 v[6:7], v[182:183], 1, s[92:93]
	v_add3_u32 v182, v3, v145, s2
	s_or_b32 s15, s10, 0x400
	s_mov_b32 m0, s15
	s_nop 0
	global_load_lds_dwordx4 v[6:7], off
	v_lshl_add_u64 v[6:7], v[182:183], 1, s[92:93]
	v_add_u32_e32 v182, 0x6000, v9
	s_or_b32 s15, s10, 0x800
	s_mov_b32 m0, s15
	s_nop 0
	global_load_lds_dwordx4 v[6:7], off
	v_lshl_add_u64 v[6:7], v[182:183], 1, s[92:93]
	s_lshl_b32 s14, s11, 5
	s_or_b32 s15, s10, 0xc00
	s_mov_b32 m0, s15
	s_nop 0
	global_load_lds_dwordx4 v[6:7], off
	v_lshl_add_u32 v6, s11, 10, v8
	s_add_i32 s14, s14, s9
	v_or_b32_e32 v182, v6, v145
	v_or_b32_e32 v4, s14, v4
	s_lshl_b32 s12, s11, 11
	v_lshl_add_u64 v[8:9], v[182:183], 1, s[30:31]
	v_bitop3_b32 v182, v145, v6, 32 bitop3:0xde
	v_lshlrev_b32_e32 v4, 13, v4
	s_lshl_b32 s14, s11, 12
	s_add_i32 s11, s12, 0x4000
	s_mov_b32 m0, s11
	s_nop 0
	global_load_lds_dwordx4 v[8:9], off
	v_lshl_add_u64 v[8:9], v[182:183], 1, s[30:31]
	s_mov_b64 s[16:17], 0x400
	v_lshl_add_u64 v[8:9], v[8:9], 0, s[16:17]
	v_or_b32_e32 v182, v4, v145
	s_addk_i32 s12, 0x4400
	s_mov_b32 m0, s12
	s_nop 0
	global_load_lds_dwordx4 v[8:9], off
	v_lshl_add_u64 v[8:9], v[182:183], 1, s[88:89]
	v_bitop3_b32 v7, v4, v145, 32 bitop3:0xf6
	s_add_i32 s12, s14, 0x6000
	s_mov_b32 m0, s12
	s_nop 0
	global_load_lds_dwordx4 v[8:9], off
	v_or_b32_e32 v8, 0x10000, v7
	v_mov_b32_e32 v9, v183
	v_lshl_add_u64 v[8:9], v[8:9], 1, s[88:89]
	s_add_i32 s15, s14, 0x6400
	s_mov_b32 m0, s15
	s_nop 0
	global_load_lds_dwordx4 v[8:9], off
	v_or_b32_e32 v182, 0x20000, v182
	v_lshl_add_u64 v[8:9], v[182:183], 1, s[88:89]
	s_add_i32 s15, s14, 0x6800
	s_mov_b32 m0, s15
	s_nop 0
	global_load_lds_dwordx4 v[8:9], off
	v_or_b32_e32 v182, 0x30000, v7
	v_lshl_add_u64 v[8:9], v[182:183], 1, s[88:89]
	s_addk_i32 s14, 0x6c00
	s_mov_b32 m0, s14
	s_nop 0
	global_load_lds_dwordx4 v[8:9], off
	v_mov_b32_e32 v49, v48
	v_mov_b32_e32 v50, v48
	v_mov_b32_e32 v51, v48
	v_mov_b32_e32 v52, v48
	v_mov_b32_e32 v53, v48
	v_mov_b32_e32 v54, v48
	v_mov_b32_e32 v55, v48
	v_mov_b32_e32 v56, v48
	v_mov_b32_e32 v57, v48
	v_mov_b32_e32 v58, v48
	v_mov_b32_e32 v59, v48
	v_mov_b32_e32 v60, v48
	v_mov_b32_e32 v61, v48
	v_mov_b32_e32 v62, v48
	v_mov_b32_e32 v63, v48
	s_cmp_lt_i32 s13, 0
	s_cbranch_scc1 .LBB0_74
	v_cmp_gt_i32_e32 vcc, 2, v2
	v_lshrrev_b32_e32 v2, 1, v0
	s_lshl_b32 s14, s13, 1
	v_bfe_u32 v0, v0, 1, 3
	v_lshlrev_b32_e32 v1, 7, v1
	v_bitop3_b32 v2, v147, v2, 7 bitop3:0x78
	s_add_i32 s13, s14, 2
	s_or_b32 s15, s14, 1
	v_lshl_or_b32 v149, v2, 4, v1
	v_bitop3_b32 v2, v147, v0, 2 bitop3:0x36
	v_mov_b32_e32 v7, s13
	v_mov_b32_e32 v8, s15
	v_lshl_or_b32 v150, v2, 4, v1
	v_bitop3_b32 v2, v147, v0, 4 bitop3:0x36
	v_bitop3_b32 v0, v147, v0, 6 bitop3:0x36
	v_cndmask_b32_e32 v148, v7, v8, vcc
	v_lshl_or_b32 v151, v2, 4, v1
	v_lshl_or_b32 v152, v0, 4, v1
	v_or_b32_e32 v153, 64, v4
	v_add_u32_e32 v154, 0x1000, v6
	v_add_u32_e32 v155, 0x10000, v3
	v_or_b32_e32 v157, 0x2000, v5
	v_or_b32_e32 v159, 0x6000, v5
	v_or_b32_e32 v160, 0x200, v5
	v_or_b32_e32 v161, 0x10000, v5
	v_or_b32_e32 v163, 0x30000, v5
	v_mov_b64_e32 v[0:1], v[48:49]
	v_mov_b64_e32 v[16:17], v[48:49]
	v_mov_b64_e32 v[32:33], v[48:49]
	s_lshl_b32 s14, s13, 6
	v_lshlrev_b32_e32 v156, 2, v147
	v_or_b32_e32 v158, 0x4000, v145
	v_or_b32_e32 v162, 0x20000, v145
	v_mov_b32_e32 v146, 0xff800000
	v_mov_b32_e32 v164, 0
	s_mov_b32 s15, 0
	v_mov_b64_e32 v[2:3], v[50:51]
	v_mov_b64_e32 v[4:5], v[52:53]
	v_mov_b64_e32 v[6:7], v[54:55]
	v_mov_b64_e32 v[8:9], v[56:57]
	v_mov_b64_e32 v[10:11], v[58:59]
	v_mov_b64_e32 v[12:13], v[60:61]
	v_mov_b64_e32 v[14:15], v[62:63]
	v_mov_b64_e32 v[18:19], v[50:51]
	v_mov_b64_e32 v[20:21], v[52:53]
	v_mov_b64_e32 v[22:23], v[54:55]
	v_mov_b64_e32 v[24:25], v[56:57]
	v_mov_b64_e32 v[26:27], v[58:59]
	v_mov_b64_e32 v[28:29], v[60:61]
	v_mov_b64_e32 v[30:31], v[62:63]
	v_mov_b64_e32 v[34:35], v[50:51]
	v_mov_b64_e32 v[36:37], v[52:53]
	v_mov_b64_e32 v[38:39], v[54:55]
	v_mov_b64_e32 v[40:41], v[56:57]
	v_mov_b64_e32 v[42:43], v[58:59]
	v_mov_b64_e32 v[44:45], v[60:61]
	v_mov_b64_e32 v[46:47], v[62:63]
	s_mov_b32 s17, 0
.LBB0_64:
	s_waitcnt vmcnt(0)
	s_add_i32 s16, s17, 1
	s_cmp_ge_i32 s16, s13
	s_barrier
	s_cbranch_scc1 .LBB0_67
	s_bitcmp1_b32 s16, 0
	s_cselect_b32 s18, 0xa000, 0
	v_add_u32_e32 v182, v155, v145
	s_add_i32 s19, s18, s10
	v_lshl_add_u64 v[64:65], v[182:183], 1, s[92:93]
	s_mov_b32 m0, s19
	s_nop 0
	global_load_lds_dwordx4 v[64:65], off
	v_add_u32_e32 v182, v157, v155
	v_lshl_add_u64 v[64:65], v[182:183], 1, s[92:93]
	s_add_i32 s34, s19, 0x400
	s_mov_b32 m0, s34
	s_nop 0
	global_load_lds_dwordx4 v[64:65], off
	v_add_u32_e32 v182, v158, v155
	v_lshl_add_u64 v[64:65], v[182:183], 1, s[92:93]
	s_add_i32 s34, s19, 0x800
	s_mov_b32 m0, s34
	s_nop 0
	global_load_lds_dwordx4 v[64:65], off
	v_add_u32_e32 v182, v159, v155
	v_lshl_add_u64 v[64:65], v[182:183], 1, s[92:93]
	s_addk_i32 s19, 0xc00
	s_mov_b32 m0, s19
	s_nop 0
	global_load_lds_dwordx4 v[64:65], off
	v_add_u32_e32 v182, v154, v145
	s_add_i32 s19, s18, s11
	v_lshl_add_u64 v[64:65], v[182:183], 1, s[30:31]
	s_mov_b32 m0, s19
	s_nop 0
	global_load_lds_dwordx4 v[64:65], off
	v_add_u32_e32 v182, v160, v154
	v_lshl_add_u64 v[64:65], v[182:183], 1, s[30:31]
	s_addk_i32 s19, 0x400
	s_mov_b32 m0, s19
	s_nop 0
	global_load_lds_dwordx4 v[64:65], off
	v_add_u32_e32 v182, v153, v145
	s_add_i32 s18, s18, s12
	v_lshl_add_u64 v[64:65], v[182:183], 1, s[88:89]
	s_mov_b32 m0, s18
	s_nop 0
	global_load_lds_dwordx4 v[64:65], off
	v_add_u32_e32 v182, v161, v153
	v_lshl_add_u64 v[64:65], v[182:183], 1, s[88:89]
	s_add_i32 s19, s18, 0x400
	s_mov_b32 m0, s19
	s_nop 0
	global_load_lds_dwordx4 v[64:65], off
	v_add_u32_e32 v182, v162, v153
	v_lshl_add_u64 v[64:65], v[182:183], 1, s[88:89]
	s_add_i32 s19, s18, 0x800
	s_mov_b32 m0, s19
	s_nop 0
	global_load_lds_dwordx4 v[64:65], off
	v_add_u32_e32 v182, v163, v153
	v_lshl_add_u64 v[64:65], v[182:183], 1, s[88:89]
	s_addk_i32 s18, 0xc00
	s_mov_b32 m0, s18
	s_nop 0
	global_load_lds_dwordx4 v[64:65], off
	v_add_u32_e32 v155, 0x10000, v155
	v_add_u32_e32 v154, 0x1000, v154
	v_add_u32_e32 v153, 64, v153
	v_cmp_lt_i32_e32 vcc, s17, v148
	s_and_b64 s[18:19], s[38:39], vcc
	s_and_saveexec_b64 s[84:85], s[18:19]
	s_cbranch_execnz .LBB0_68

; template <int N> DI void wait_vm() { asm volatile("s_waitcnt vmcnt(%0)" ::"n"(N) : "memory"); }
; template <int BM, class Epi>
; DI void gemm_dma(const u16* __restrict__ X, long ldx, const u16* __restrict__ W, long ldw, int K, char* smem,
;                  int m0, int n0, const Epi& epi) {
;     ...
;   const int wu = __builtin_amdgcn_readfirstlane(wave);
;   const unsigned sbase = (unsigned)__builtin_amdgcn_readfirstlane((int)(unsigned)(size_t)smem);
;   const int r16 = lane >> 2, chunk = (lane & 3) ^ ((4 - (r16 >> 2)) & 3);
;   const u16* xs = X + (long)(wu * XD * 16 + r16) * ldx + (chunk << 3);
;   const u16* ws = W + (long)(wu * 32 + r16) * ldw + (chunk << 3);
;   const long ldx16 = 16 * ldx, ldw16 = 16 * ldw;
;   const unsigned xdst = sbase + wu * XD * 1024, wdst = sbase + BM * 64 + wu * 2048;
;     ...
;   const int nk = K >> 5;
;   __syncthreads();
; #pragma unroll
;   for (int s = 0; s < D - 1; ++s) GD_ISSUE(s)
;   int cur = 0, nxt = D - 1, kt = 0;
;   do {
;     if (kt + D - 2 < nk) wait_vm<PW * (D - 2)>(); else wait_vm<0>();
;     __syncthreads();
;     if (kt + D - 1 < nk) GD_ISSUE(nxt)
;     nxt = (nxt + 1 == D) ? 0 : nxt + 1;
;     const char* base = smem + cur * STG;
;     cur = (cur + 1 == D) ? 0 : cur + 1;
;     bf16x8 xf[MT];
; #pragma unroll
;     for (int i = 0; i < MT; ++i) xf[i] = *(const bf16x8*)(base + (xrow0 + i * 16) * 64 + rd);
; #pragma unroll
;     for (int nh = 0; nh < NT / 4; ++nh) {
;       bf16x8 wf[4];
; #pragma unroll
;       for (int i = 0; i < 4; ++i) wf[i] = *(const bf16x8*)(base + BM * 64 + (wrow0 + (nh * 4 + i) * 16) * 64 + rd);
; DI void phase_odd(const Params& p, int o, int sub, char* smem) {
;     ...
;         int b, tm, tn; long kv0, ld; u16* C;
;         if (t < 512) { b = t >> 8; const int r = t & 255; tm = r >> 6; tn = r & 63; kv0 = (long)b * 8192; ld = 8192; C = vtb + (size_t)b * 1024 * 8192; }
;         else { const int u = t - 512; b = u / 36; const int r = u % 36; tm = r / 9; tn = r % 9; kv0 = (long)M_PROMPT + (long)b * KSTR_S; ld = KSTR_S;
;                C = vtb + (size_t)2 * 1024 * 8192 + (size_t)b * 1024 * KSTR_S; }
;         EpiVT ev{C, ld};
;         gemm_dma<256>(W + WO_KV + (size_t)(1024 + tm * 256) * 256, 256, ckvb + (size_t)(kv0 + tn * 128) * 256, 256, 256, smem, tm * 256, tn * 128, ev);
.LBB0_82:
	v_readlane_b32 s8, v255, 5
	s_lshl_b32 s7, s6, 17
	v_readlane_b32 s12, v255, 9
	v_readlane_b32 s9, v255, 6
	v_readlane_b32 s13, v255, 10
	s_add_u32 s8, s12, s7
	v_readlane_b32 s10, v255, 7
	s_addc_u32 s9, s13, 0
	s_lshl_b32 s5, s5, 7
	v_readlane_b32 s11, v255, 8
	s_add_u32 s10, s42, s5
	s_addc_u32 s11, s43, 0
	s_lshl_b64 s[10:11], s[10:11], 9
	v_mov_b32_e32 v1, v185
	s_add_u32 s42, s0, s10
	s_addc_u32 s43, s1, s11
	v_readfirstlane_b32 s7, v1
	v_lshrrev_b32_e32 v6, 4, v1
	s_ashr_i32 s10, s7, 6
	v_bfe_u32 v8, v1, 2, 4
	v_sub_u32_e32 v6, 0, v6
	s_andn2_b32 s7, s7, 63
	v_xor_b32_e32 v9, v1, v6
	v_or_b32_e32 v6, s7, v8
	v_lshrrev_b32_e32 v4, 2, v1
	v_ashrrev_i32_e32 v7, 31, v6
	v_and_b32_e32 v130, 15, v1
	v_bfe_u32 v2, v1, 4, 2
	v_sub_u32_e32 v4, 0, v4
	v_lshlrev_b64 v[6:7], 9, v[6:7]
	v_lshlrev_b32_e32 v9, 4, v9
	v_lshlrev_b32_e32 v3, 6, v130
	v_bitop3_b32 v2, v2, v4, 3 bitop3:0x78
	v_lshl_add_u64 v[6:7], s[8:9], 0, v[6:7]
	v_and_b32_e32 v182, 48, v9
	v_readlane_b32 s14, v255, 11
	v_lshl_or_b32 v10, v2, 4, v3
	v_mov_b32_e32 v2, v183
	v_lshl_add_u64 v[6:7], v[6:7], 0, v[182:183]
	s_mov_b64 s[8:9], 0x520000
	v_lshl_add_u64 v[12:13], v[6:7], 0, s[8:9]
	v_lshl_or_b32 v8, s10, 5, v8
	s_lshl_b32 s14, s10, 12
	s_barrier
	s_mov_b32 m0, s14
	s_nop 0
	global_load_lds_dwordx4 v[12:13], off
	s_mov_b64 s[8:9], 0x522000
	v_ashrrev_i32_e32 v9, 31, v8
	v_lshl_add_u64 v[12:13], v[6:7], 0, s[8:9]
	s_or_b32 s17, s14, 0x400
	s_mov_b32 m0, s17
	s_nop 0
	global_load_lds_dwordx4 v[12:13], off
	s_mov_b64 s[8:9], 0x524000
	v_lshlrev_b64 v[8:9], 9, v[8:9]
	v_lshl_add_u64 v[12:13], v[6:7], 0, s[8:9]
	s_or_b32 s18, s14, 0x800
	s_mov_b32 m0, s18
	s_nop 0
	global_load_lds_dwordx4 v[12:13], off
	s_mov_b64 s[8:9], 0x526000
	v_lshl_add_u64 v[8:9], s[42:43], 0, v[8:9]
	s_lshl_b32 s34, s10, 11
	v_lshl_add_u64 v[12:13], v[6:7], 0, s[8:9]
	s_or_b32 s16, s14, 0xc00
	s_mov_b32 m0, s16
	s_nop 0
	global_load_lds_dwordx4 v[12:13], off
	v_readlane_b32 s15, v255, 12
	v_lshl_add_u64 v[8:9], v[8:9], 0, v[182:183]
	s_add_i32 s13, s34, 0x4000
	s_mov_b32 m0, s13
	s_nop 0
	global_load_lds_dwordx4 v[8:9], off
	s_mov_b64 s[8:9], 0x2000
	v_lshl_add_u64 v[12:13], v[8:9], 0, s[8:9]
	s_add_i32 s15, s34, 0x4400
	s_mov_b32 m0, s15
	s_nop 0
	global_load_lds_dwordx4 v[12:13], off
	s_mov_b64 s[8:9], 0x520040
	v_lshl_add_u64 v[12:13], v[6:7], 0, s[8:9]
	s_add_i32 s10, s14, 0x6000
	s_mov_b32 m0, s10
	s_nop 0
	global_load_lds_dwordx4 v[12:13], off
	s_mov_b64 s[8:9], 0x522040
	v_lshl_add_u64 v[12:13], v[6:7], 0, s[8:9]
	s_add_i32 s9, s14, 0x6400
	s_mov_b32 m0, s9
	s_nop 0
	global_load_lds_dwordx4 v[12:13], off
	s_mov_b64 s[20:21], 0x524040
	v_lshl_add_u64 v[12:13], v[6:7], 0, s[20:21]
	s_add_i32 s12, s14, 0x6800
	s_mov_b32 m0, s12
	s_nop 0
	global_load_lds_dwordx4 v[12:13], off
	s_mov_b64 s[20:21], 0x526040
	v_lshl_add_u64 v[12:13], v[6:7], 0, s[20:21]
	s_add_i32 s11, s14, 0x6c00
	s_mov_b32 m0, s11
	s_nop 0
	global_load_lds_dwordx4 v[12:13], off
	v_lshl_add_u64 v[14:15], v[8:9], 0, 64
	s_add_i32 s7, s34, 0xa000
	s_mov_b32 m0, s7
	s_nop 0
	global_load_lds_dwordx4 v[14:15], off
	s_mov_b64 s[20:21], 0x2040
	v_lshl_add_u64 v[12:13], v[8:9], 0, s[20:21]
	s_add_i32 s8, s34, 0xa400
	s_mov_b32 m0, s8
	s_nop 0
	global_load_lds_dwordx4 v[12:13], off
	s_mov_b64 s[20:21], 0x520080
	v_lshl_add_u64 v[12:13], v[6:7], 0, s[20:21]
	s_waitcnt vmcnt(6)
	s_barrier
	s_add_i32 s42, s14, 0xc000
	s_mov_b32 m0, s42
	s_nop 0
	global_load_lds_dwordx4 v[12:13], off
	s_mov_b64 s[20:21], 0x522080
	v_lshl_add_u64 v[12:13], v[6:7], 0, s[20:21]
	s_add_i32 s41, s14, 0xc400
	s_mov_b32 m0, s41
	s_nop 0
	global_load_lds_dwordx4 v[12:13], off
	s_mov_b64 s[20:21], 0x524080
	v_lshl_add_u64 v[12:13], v[6:7], 0, s[20:21]
	s_add_i32 s44, s14, 0xc800
	s_mov_b32 m0, s44
	s_nop 0
	global_load_lds_dwordx4 v[12:13], off
	s_mov_b64 s[20:21], 0x526080
	v_lshl_add_u64 v[12:13], v[6:7], 0, s[20:21]
	s_add_i32 s43, s14, 0xcc00
	s_mov_b32 m0, s43
	s_nop 0
	global_load_lds_dwordx4 v[12:13], off
	v_lshl_add_u64 v[14:15], v[8:9], 0, s[28:29]
	v_and_b32_e32 v131, 0xffffffc0, v1
	s_add_i32 s19, s34, 0x10000
	s_mov_b32 m0, s19
	s_nop 0
	global_load_lds_dwordx4 v[14:15], off
	s_mov_b64 s[20:21], 0x2080
	v_lshl_add_u64 v[12:13], v[8:9], 0, s[20:21]
	s_add_i32 s34, s34, 0x10400
	s_mov_b32 m0, s34
	s_nop 0
	global_load_lds_dwordx4 v[12:13], off
	v_lshl_or_b32 v11, v131, 6, v10
	ds_read_b128 v[12:15], v11
	ds_read_b128 v[16:19], v11 offset:1024
	ds_read_b128 v[20:23], v11 offset:2048
	ds_read_b128 v[24:27], v11 offset:3072
	ds_read_b128 v[28:31], v10 offset:16384
	ds_read_b128 v[32:35], v10 offset:17408
	ds_read_b128 v[36:39], v10 offset:18432
	ds_read_b128 v[40:43], v10 offset:19456
	ds_read_b128 v[92:95], v10 offset:20480
	ds_read_b128 v[96:99], v10 offset:21504
	ds_read_b128 v[100:103], v10 offset:22528
	ds_read_b128 v[104:107], v10 offset:23552
	s_mov_b64 s[20:21], 0x5200c0
	v_lshl_add_u64 v[128:129], v[6:7], 0, s[20:21]
	s_mov_b64 s[20:21], 0xc0
	v_mov_b32_e32 v3, v2
	v_mov_b32_e32 v4, v2
	v_mov_b32_e32 v5, v2
	v_lshl_add_u64 v[148:149], v[8:9], 0, s[20:21]
	s_waitcnt vmcnt(6)
	s_waitcnt lgkmcnt(0)
	s_barrier
; template <int N> DI void wait_vm() { asm volatile("s_waitcnt vmcnt(%0)" ::"n"(N) : "memory"); }
; template <int BM, class Epi>
; DI void gemm_dma(const u16* __restrict__ X, long ldx, const u16* __restrict__ W, long ldw, int K, char* smem,
;                  int m0, int n0, const Epi& epi) {
;     ...
;   do {
;     if (kt + D - 2 < nk) wait_vm<PW * (D - 2)>(); else wait_vm<0>();
;     __syncthreads();
;     if (kt + D - 1 < nk) GD_ISSUE(nxt)
;     nxt = (nxt + 1 == D) ? 0 : nxt + 1;
;     const char* base = smem + cur * STG;
;     cur = (cur + 1 == D) ? 0 : cur + 1;
;     bf16x8 xf[MT];
; #pragma unroll
;     for (int i = 0; i < MT; ++i) xf[i] = *(const bf16x8*)(base + (xrow0 + i * 16) * 64 + rd);
; #pragma unroll
;     for (int nh = 0; nh < NT / 4; ++nh) {
;       bf16x8 wf[4];
; #pragma unroll
;       for (int i = 0; i < 4; ++i) wf[i] = *(const bf16x8*)(base + BM * 64 + (wrow0 + (nh * 4 + i) * 16) * 64 + rd);
; #pragma unroll
;       for (int i = 0; i < 4; ++i)
; #pragma unroll
;         for (int mt = 0; mt < MT; ++mt)
;           acc[nh * 4 + i][mt] = __builtin_amdgcn_mfma_f32_16x16x32_bf16(wf[i], xf[mt], acc[nh * 4 + i][mt], 0, 0, 0);
	s_mov_b32 m0, s14
	s_nop 0
	global_load_lds_dwordx4 v[128:129], off
	s_mov_b64 s[20:21], 0x5220c0
	v_mfma_f32_16x16x32_bf16 v[44:47], v[28:31], v[12:15], v[2:5]
	v_or_b32_e32 v178, 0x11000, v10
	v_or_b32_e32 v179, 0x11400, v10
	v_or_b32_e32 v180, 0x11800, v10
	v_mfma_f32_16x16x32_bf16 v[48:51], v[28:31], v[16:19], v[2:5]
	v_or_b32_e32 v181, 0x11c00, v10
	v_lshl_add_u32 v131, s6, 8, v131
	s_and_b32 s6, s5, 0x1f80
	v_mfma_f32_16x16x32_bf16 v[52:55], v[28:31], v[20:23], v[2:5]
	v_mfma_f32_16x16x32_bf16 v[28:31], v[28:31], v[24:27], v[2:5]
	v_mfma_f32_16x16x32_bf16 v[56:59], v[32:35], v[12:15], v[2:5]
	v_mfma_f32_16x16x32_bf16 v[60:63], v[32:35], v[16:19], v[2:5]
	v_mfma_f32_16x16x32_bf16 v[64:67], v[32:35], v[20:23], v[2:5]
	v_mfma_f32_16x16x32_bf16 v[32:35], v[32:35], v[24:27], v[2:5]
	v_mfma_f32_16x16x32_bf16 v[68:71], v[36:39], v[12:15], v[2:5]
	v_mfma_f32_16x16x32_bf16 v[72:75], v[36:39], v[16:19], v[2:5]
	v_mfma_f32_16x16x32_bf16 v[76:79], v[36:39], v[20:23], v[2:5]
	v_mfma_f32_16x16x32_bf16 v[36:39], v[36:39], v[24:27], v[2:5]
	v_mfma_f32_16x16x32_bf16 v[80:83], v[40:43], v[12:15], v[2:5]
	v_mfma_f32_16x16x32_bf16 v[84:87], v[40:43], v[16:19], v[2:5]
	v_mfma_f32_16x16x32_bf16 v[88:91], v[40:43], v[20:23], v[2:5]
	v_mfma_f32_16x16x32_bf16 v[40:43], v[40:43], v[24:27], v[2:5]
	v_mfma_f32_16x16x32_bf16 v[108:111], v[92:95], v[12:15], v[2:5]
	v_mfma_f32_16x16x32_bf16 v[112:115], v[92:95], v[16:19], v[2:5]
	v_mfma_f32_16x16x32_bf16 v[116:119], v[92:95], v[20:23], v[2:5]
	v_mfma_f32_16x16x32_bf16 v[92:95], v[92:95], v[24:27], v[2:5]
	v_mfma_f32_16x16x32_bf16 v[120:123], v[96:99], v[12:15], v[2:5]
	v_mfma_f32_16x16x32_bf16 v[124:127], v[96:99], v[16:19], v[2:5]
	v_mfma_f32_16x16x32_bf16 v[132:135], v[96:99], v[20:23], v[2:5]
	v_mfma_f32_16x16x32_bf16 v[96:99], v[96:99], v[24:27], v[2:5]
	v_mfma_f32_16x16x32_bf16 v[136:139], v[100:103], v[12:15], v[2:5]
	v_mfma_f32_16x16x32_bf16 v[140:143], v[100:103], v[16:19], v[2:5]
	v_mfma_f32_16x16x32_bf16 v[144:147], v[100:103], v[20:23], v[2:5]
	v_mfma_f32_16x16x32_bf16 v[100:103], v[100:103], v[24:27], v[2:5]
	v_mfma_f32_16x16x32_bf16 v[12:15], v[104:107], v[12:15], v[2:5]
	v_mfma_f32_16x16x32_bf16 v[16:19], v[104:107], v[16:19], v[2:5]
	v_mfma_f32_16x16x32_bf16 v[20:23], v[104:107], v[20:23], v[2:5]
	v_mfma_f32_16x16x32_bf16 v[2:5], v[104:107], v[24:27], v[2:5]
	v_lshl_add_u64 v[24:25], v[6:7], 0, s[20:21]
	s_mov_b32 m0, s17
	s_nop 0
	global_load_lds_dwordx4 v[24:25], off
	s_mov_b64 s[20:21], 0x5240c0
	v_lshl_add_u64 v[24:25], v[6:7], 0, s[20:21]
	s_mov_b32 m0, s18
	s_nop 0
	global_load_lds_dwordx4 v[24:25], off
	s_mov_b64 s[20:21], 0x5260c0
	v_lshl_add_u64 v[24:25], v[6:7], 0, s[20:21]
	s_mov_b32 m0, s16
	s_nop 0
	global_load_lds_dwordx4 v[24:25], off
	s_mov_b64 s[20:21], 0x20c0
	s_mov_b32 m0, s13
	s_nop 0
	global_load_lds_dwordx4 v[148:149], off
	v_lshl_add_u64 v[24:25], v[8:9], 0, s[20:21]
	s_mov_b32 m0, s15
	s_nop 0
	global_load_lds_dwordx4 v[24:25], off
	ds_read_b128 v[24:27], v11 offset:24576
	ds_read_b128 v[104:107], v11 offset:25600
	ds_read_b128 v[148:151], v11 offset:26624
	ds_read_b128 v[152:155], v11 offset:27648
	ds_read_b128 v[156:159], v10 offset:40960
	ds_read_b128 v[160:163], v10 offset:41984
	ds_read_b128 v[164:167], v10 offset:43008
	ds_read_b128 v[168:171], v10 offset:44032
	s_waitcnt lgkmcnt(3)
	v_mfma_f32_16x16x32_bf16 v[44:47], v[156:159], v[24:27], v[44:47]
	s_mov_b64 s[20:21], 0x520100
	v_lshl_add_u64 v[128:129], v[6:7], 0, s[20:21]
	s_mov_b64 s[20:21], 0x100
	v_mfma_f32_16x16x32_bf16 v[48:51], v[156:159], v[104:107], v[48:51]
	v_lshl_add_u64 v[172:173], v[8:9], 0, s[20:21]
	s_mov_b64 s[20:21], 0x522100
	v_mfma_f32_16x16x32_bf16 v[52:55], v[156:159], v[148:151], v[52:55]
	v_mfma_f32_16x16x32_bf16 v[28:31], v[156:159], v[152:155], v[28:31]
	s_waitcnt lgkmcnt(2)
	v_mfma_f32_16x16x32_bf16 v[56:59], v[160:163], v[24:27], v[56:59]
	v_mfma_f32_16x16x32_bf16 v[60:63], v[160:163], v[104:107], v[60:63]
	v_mfma_f32_16x16x32_bf16 v[64:67], v[160:163], v[148:151], v[64:67]
	v_mfma_f32_16x16x32_bf16 v[32:35], v[160:163], v[152:155], v[32:35]
	s_waitcnt lgkmcnt(1)
	v_mfma_f32_16x16x32_bf16 v[68:71], v[164:167], v[24:27], v[68:71]
	v_mfma_f32_16x16x32_bf16 v[72:75], v[164:167], v[104:107], v[72:75]
	v_mfma_f32_16x16x32_bf16 v[76:79], v[164:167], v[148:151], v[76:79]
	v_mfma_f32_16x16x32_bf16 v[36:39], v[164:167], v[152:155], v[36:39]
	s_waitcnt lgkmcnt(0)
	v_mfma_f32_16x16x32_bf16 v[80:83], v[168:171], v[24:27], v[80:83]
	v_mfma_f32_16x16x32_bf16 v[84:87], v[168:171], v[104:107], v[84:87]
	v_mfma_f32_16x16x32_bf16 v[88:91], v[168:171], v[148:151], v[88:91]
	v_mfma_f32_16x16x32_bf16 v[40:43], v[168:171], v[152:155], v[40:43]
	ds_read_b128 v[156:159], v10 offset:45056
	ds_read_b128 v[160:163], v10 offset:46080
	ds_read_b128 v[164:167], v10 offset:47104
	ds_read_b128 v[168:171], v10 offset:48128
	s_waitcnt vmcnt(6)
	s_waitcnt lgkmcnt(0)
	s_barrier
; template <int N> DI void wait_vm() { asm volatile("s_waitcnt vmcnt(%0)" ::"n"(N) : "memory"); }
; template <int BM, class Epi>
; DI void gemm_dma(const u16* __restrict__ X, long ldx, const u16* __restrict__ W, long ldw, int K, char* smem,
;                  int m0, int n0, const Epi& epi) {
;     ...
;   do {
;     if (kt + D - 2 < nk) wait_vm<PW * (D - 2)>(); else wait_vm<0>();
;     __syncthreads();
;     if (kt + D - 1 < nk) GD_ISSUE(nxt)
;     nxt = (nxt + 1 == D) ? 0 : nxt + 1;
;     const char* base = smem + cur * STG;
;     cur = (cur + 1 == D) ? 0 : cur + 1;
;     bf16x8 xf[MT];
; #pragma unroll
;     for (int i = 0; i < MT; ++i) xf[i] = *(const bf16x8*)(base + (xrow0 + i * 16) * 64 + rd);
; #pragma unroll
;     for (int nh = 0; nh < NT / 4; ++nh) {
;       bf16x8 wf[4];
; #pragma unroll
;       for (int i = 0; i < 4; ++i) wf[i] = *(const bf16x8*)(base + BM * 64 + (wrow0 + (nh * 4 + i) * 16) * 64 + rd);
; #pragma unroll
;       for (int i = 0; i < 4; ++i)
; #pragma unroll
;         for (int mt = 0; mt < MT; ++mt)
;           acc[nh * 4 + i][mt] = __builtin_amdgcn_mfma_f32_16x16x32_bf16(wf[i], xf[mt], acc[nh * 4 + i][mt], 0, 0, 0);
	s_mov_b32 m0, s10
	s_nop 0
	global_load_lds_dwordx4 v[128:129], off
	v_mfma_f32_16x16x32_bf16 v[108:111], v[156:159], v[24:27], v[108:111]
	v_mfma_f32_16x16x32_bf16 v[120:123], v[160:163], v[24:27], v[120:123]
	v_mfma_f32_16x16x32_bf16 v[136:139], v[164:167], v[24:27], v[136:139]
	v_mfma_f32_16x16x32_bf16 v[12:15], v[168:171], v[24:27], v[12:15]
	v_mfma_f32_16x16x32_bf16 v[24:27], v[168:171], v[152:155], v[2:5]
	s_nop 2
	v_lshl_add_u64 v[2:3], v[6:7], 0, s[20:21]
	s_mov_b32 m0, s9
	s_nop 0
	global_load_lds_dwordx4 v[2:3], off
	s_mov_b64 s[20:21], 0x524100
	v_lshl_add_u64 v[2:3], v[6:7], 0, s[20:21]
	s_mov_b32 m0, s12
	s_nop 0
	global_load_lds_dwordx4 v[2:3], off
	s_mov_b64 s[20:21], 0x526100
	v_lshl_add_u64 v[2:3], v[6:7], 0, s[20:21]
	s_mov_b32 m0, s11
	s_nop 0
	global_load_lds_dwordx4 v[2:3], off
	s_mov_b64 s[20:21], 0x2100
	s_mov_b32 m0, s7
	s_nop 0
	global_load_lds_dwordx4 v[172:173], off
	v_lshl_add_u64 v[2:3], v[8:9], 0, s[20:21]
	s_mov_b32 m0, s8
	s_nop 0
	global_load_lds_dwordx4 v[2:3], off
	v_or_b32_e32 v2, 0x10000, v10
	v_or_b32_e32 v3, 0x10400, v10
	v_or_b32_e32 v4, 0x10800, v10
	v_or_b32_e32 v5, 0x10c00, v10
	v_mfma_f32_16x16x32_bf16 v[112:115], v[156:159], v[104:107], v[112:115]
	s_mov_b64 s[20:21], 0x520140
	v_lshl_add_u64 v[128:129], v[6:7], 0, s[20:21]
	s_mov_b64 s[20:21], 0x140
	v_mfma_f32_16x16x32_bf16 v[116:119], v[156:159], v[148:151], v[116:119]
	v_lshl_add_u64 v[176:177], v[8:9], 0, s[20:21]
	s_mov_b64 s[20:21], 0x522140
	v_mfma_f32_16x16x32_bf16 v[92:95], v[156:159], v[152:155], v[92:95]
	v_mfma_f32_16x16x32_bf16 v[124:127], v[160:163], v[104:107], v[124:127]
	v_mfma_f32_16x16x32_bf16 v[132:135], v[160:163], v[148:151], v[132:135]
	v_mfma_f32_16x16x32_bf16 v[96:99], v[160:163], v[152:155], v[96:99]
	v_mfma_f32_16x16x32_bf16 v[140:143], v[164:167], v[104:107], v[140:143]
	v_mfma_f32_16x16x32_bf16 v[144:147], v[164:167], v[148:151], v[144:147]
	v_mfma_f32_16x16x32_bf16 v[100:103], v[164:167], v[152:155], v[100:103]
	v_mfma_f32_16x16x32_bf16 v[16:19], v[168:171], v[104:107], v[16:19]
	v_mfma_f32_16x16x32_bf16 v[20:23], v[168:171], v[148:151], v[20:23]
	ds_read_b128 v[104:107], v11 offset:49152
	ds_read_b128 v[148:151], v11 offset:50176
	ds_read_b128 v[152:155], v11 offset:51200
	ds_read_b128 v[156:159], v11 offset:52224
	ds_read_b128 v[160:163], v2
	ds_read_b128 v[164:167], v3
	ds_read_b128 v[168:171], v4
	ds_read_b128 v[172:175], v5
	s_waitcnt lgkmcnt(3)
	v_mfma_f32_16x16x32_bf16 v[44:47], v[160:163], v[104:107], v[44:47]
	v_mfma_f32_16x16x32_bf16 v[48:51], v[160:163], v[148:151], v[48:51]
	v_mfma_f32_16x16x32_bf16 v[52:55], v[160:163], v[152:155], v[52:55]
	v_mfma_f32_16x16x32_bf16 v[28:31], v[160:163], v[156:159], v[28:31]
	ds_read_b128 v[160:163], v178
	s_waitcnt lgkmcnt(3)
	v_mfma_f32_16x16x32_bf16 v[56:59], v[164:167], v[104:107], v[56:59]
	v_mfma_f32_16x16x32_bf16 v[60:63], v[164:167], v[148:151], v[60:63]
	v_mfma_f32_16x16x32_bf16 v[64:67], v[164:167], v[152:155], v[64:67]
	v_mfma_f32_16x16x32_bf16 v[32:35], v[164:167], v[156:159], v[32:35]
	ds_read_b128 v[164:167], v179
	s_waitcnt lgkmcnt(3)
	v_mfma_f32_16x16x32_bf16 v[68:71], v[168:171], v[104:107], v[68:71]
	v_mfma_f32_16x16x32_bf16 v[72:75], v[168:171], v[148:151], v[72:75]
	v_mfma_f32_16x16x32_bf16 v[76:79], v[168:171], v[152:155], v[76:79]
	v_mfma_f32_16x16x32_bf16 v[36:39], v[168:171], v[156:159], v[36:39]
	ds_read_b128 v[168:171], v180
	s_waitcnt lgkmcnt(3)
	v_mfma_f32_16x16x32_bf16 v[80:83], v[172:175], v[104:107], v[80:83]
	v_mfma_f32_16x16x32_bf16 v[84:87], v[172:175], v[148:151], v[84:87]
	v_mfma_f32_16x16x32_bf16 v[88:91], v[172:175], v[152:155], v[88:91]
	v_mfma_f32_16x16x32_bf16 v[40:43], v[172:175], v[156:159], v[40:43]
	ds_read_b128 v[172:175], v181
	s_waitcnt vmcnt(6)
	s_waitcnt lgkmcnt(0)
	s_barrier
	s_mov_b32 m0, s42
	s_nop 0
	global_load_lds_dwordx4 v[128:129], off
	v_mfma_f32_16x16x32_bf16 v[108:111], v[160:163], v[104:107], v[108:111]
	v_mfma_f32_16x16x32_bf16 v[120:123], v[164:167], v[104:107], v[120:123]
	v_mfma_f32_16x16x32_bf16 v[136:139], v[168:171], v[104:107], v[136:139]
	v_mfma_f32_16x16x32_bf16 v[12:15], v[172:175], v[104:107], v[12:15]
	v_lshl_add_u64 v[104:105], v[6:7], 0, s[20:21]
	s_mov_b32 m0, s41
	s_nop 0
	global_load_lds_dwordx4 v[104:105], off
	s_mov_b64 s[20:21], 0x524140
	v_lshl_add_u64 v[104:105], v[6:7], 0, s[20:21]
	s_mov_b32 m0, s44
	s_nop 0
	global_load_lds_dwordx4 v[104:105], off
	s_mov_b64 s[20:21], 0x526140
	v_lshl_add_u64 v[104:105], v[6:7], 0, s[20:21]
	s_mov_b32 m0, s43
	s_nop 0
	global_load_lds_dwordx4 v[104:105], off
	s_mov_b64 s[20:21], 0x2140
	s_mov_b32 m0, s19
	s_nop 0
	global_load_lds_dwordx4 v[176:177], off
	v_lshl_add_u64 v[104:105], v[8:9], 0, s[20:21]
	s_mov_b32 m0, s34
	s_nop 0
	global_load_lds_dwordx4 v[104:105], off
	v_mfma_f32_16x16x32_bf16 v[112:115], v[160:163], v[148:151], v[112:115]
	s_mov_b64 s[20:21], 0x520180
	v_lshl_add_u64 v[128:129], v[6:7], 0, s[20:21]
	s_mov_b64 s[20:21], 0x180
	v_mfma_f32_16x16x32_bf16 v[116:119], v[160:163], v[152:155], v[116:119]
	v_lshl_add_u64 v[176:177], v[8:9], 0, s[20:21]
	s_mov_b64 s[20:21], 0x522180
	v_mfma_f32_16x16x32_bf16 v[92:95], v[160:163], v[156:159], v[92:95]
	v_mfma_f32_16x16x32_bf16 v[124:127], v[164:167], v[148:151], v[124:127]
	v_mfma_f32_16x16x32_bf16 v[132:135], v[164:167], v[152:155], v[132:135]
	v_mfma_f32_16x16x32_bf16 v[96:99], v[164:167], v[156:159], v[96:99]
	v_mfma_f32_16x16x32_bf16 v[140:143], v[168:171], v[148:151], v[140:143]
	v_mfma_f32_16x16x32_bf16 v[144:147], v[168:171], v[152:155], v[144:147]
	v_mfma_f32_16x16x32_bf16 v[100:103], v[168:171], v[156:159], v[100:103]
	v_mfma_f32_16x16x32_bf16 v[16:19], v[172:175], v[148:151], v[16:19]
	v_mfma_f32_16x16x32_bf16 v[20:23], v[172:175], v[152:155], v[20:23]
	v_mfma_f32_16x16x32_bf16 v[24:27], v[172:175], v[156:159], v[24:27]
	ds_read_b128 v[104:107], v11
	ds_read_b128 v[148:151], v11 offset:1024
	ds_read_b128 v[152:155], v11 offset:2048
	ds_read_b128 v[156:159], v11 offset:3072
	ds_read_b128 v[160:163], v10 offset:16384
	ds_read_b128 v[164:167], v10 offset:17408
	ds_read_b128 v[168:171], v10 offset:18432
	ds_read_b128 v[172:175], v10 offset:19456
	s_waitcnt lgkmcnt(3)
; template <int N> DI void wait_vm() { asm volatile("s_waitcnt vmcnt(%0)" ::"n"(N) : "memory"); }
; template <int BM, class Epi>
; DI void gemm_dma(const u16* __restrict__ X, long ldx, const u16* __restrict__ W, long ldw, int K, char* smem,
;                  int m0, int n0, const Epi& epi) {
;     ...
;   do {
;     if (kt + D - 2 < nk) wait_vm<PW * (D - 2)>(); else wait_vm<0>();
;     __syncthreads();
;     if (kt + D - 1 < nk) GD_ISSUE(nxt)
;     nxt = (nxt + 1 == D) ? 0 : nxt + 1;
;     const char* base = smem + cur * STG;
;     cur = (cur + 1 == D) ? 0 : cur + 1;
;     bf16x8 xf[MT];
; #pragma unroll
;     for (int i = 0; i < MT; ++i) xf[i] = *(const bf16x8*)(base + (xrow0 + i * 16) * 64 + rd);
; #pragma unroll
;     for (int nh = 0; nh < NT / 4; ++nh) {
;       bf16x8 wf[4];
; #pragma unroll
;       for (int i = 0; i < 4; ++i) wf[i] = *(const bf16x8*)(base + BM * 64 + (wrow0 + (nh * 4 + i) * 16) * 64 + rd);
; #pragma unroll
;       for (int i = 0; i < 4; ++i)
; #pragma unroll
;         for (int mt = 0; mt < MT; ++mt)
;           acc[nh * 4 + i][mt] = __builtin_amdgcn_mfma_f32_16x16x32_bf16(wf[i], xf[mt], acc[nh * 4 + i][mt], 0, 0, 0);
	v_mfma_f32_16x16x32_bf16 v[44:47], v[160:163], v[104:107], v[44:47]
	v_mfma_f32_16x16x32_bf16 v[48:51], v[160:163], v[148:151], v[48:51]
	v_mfma_f32_16x16x32_bf16 v[52:55], v[160:163], v[152:155], v[52:55]
	v_mfma_f32_16x16x32_bf16 v[28:31], v[160:163], v[156:159], v[28:31]
	s_waitcnt lgkmcnt(2)
	v_mfma_f32_16x16x32_bf16 v[56:59], v[164:167], v[104:107], v[56:59]
	v_mfma_f32_16x16x32_bf16 v[60:63], v[164:167], v[148:151], v[60:63]
	v_mfma_f32_16x16x32_bf16 v[64:67], v[164:167], v[152:155], v[64:67]
	v_mfma_f32_16x16x32_bf16 v[32:35], v[164:167], v[156:159], v[32:35]
	s_waitcnt lgkmcnt(1)
	v_mfma_f32_16x16x32_bf16 v[68:71], v[168:171], v[104:107], v[68:71]
	v_mfma_f32_16x16x32_bf16 v[72:75], v[168:171], v[148:151], v[72:75]
	v_mfma_f32_16x16x32_bf16 v[76:79], v[168:171], v[152:155], v[76:79]
	v_mfma_f32_16x16x32_bf16 v[36:39], v[168:171], v[156:159], v[36:39]
	s_waitcnt lgkmcnt(0)
	v_mfma_f32_16x16x32_bf16 v[80:83], v[172:175], v[104:107], v[80:83]
	v_mfma_f32_16x16x32_bf16 v[84:87], v[172:175], v[148:151], v[84:87]
	v_mfma_f32_16x16x32_bf16 v[88:91], v[172:175], v[152:155], v[88:91]
	v_mfma_f32_16x16x32_bf16 v[40:43], v[172:175], v[156:159], v[40:43]
	ds_read_b128 v[160:163], v10 offset:20480
	ds_read_b128 v[164:167], v10 offset:21504
	ds_read_b128 v[168:171], v10 offset:22528
	ds_read_b128 v[172:175], v10 offset:23552
	s_waitcnt vmcnt(6)
	s_waitcnt lgkmcnt(0)
	s_barrier
	s_mov_b32 m0, s14
	s_nop 0
	global_load_lds_dwordx4 v[128:129], off
	v_mfma_f32_16x16x32_bf16 v[108:111], v[160:163], v[104:107], v[108:111]
	v_mfma_f32_16x16x32_bf16 v[120:123], v[164:167], v[104:107], v[120:123]
	v_mfma_f32_16x16x32_bf16 v[136:139], v[168:171], v[104:107], v[136:139]
	v_mfma_f32_16x16x32_bf16 v[12:15], v[172:175], v[104:107], v[12:15]
	v_lshl_add_u64 v[104:105], v[6:7], 0, s[20:21]
	s_mov_b32 m0, s17
	s_nop 0
	global_load_lds_dwordx4 v[104:105], off
	s_mov_b64 s[20:21], 0x524180
	v_lshl_add_u64 v[104:105], v[6:7], 0, s[20:21]
	s_mov_b32 m0, s18
	s_nop 0
	global_load_lds_dwordx4 v[104:105], off
	s_mov_b64 s[18:19], 0x526180
	v_lshl_add_u64 v[104:105], v[6:7], 0, s[18:19]
	s_mov_b32 m0, s16
	s_nop 0
	global_load_lds_dwordx4 v[104:105], off
	s_mov_b64 s[16:17], 0x2180
	s_mov_b32 m0, s13
	s_nop 0
	global_load_lds_dwordx4 v[176:177], off
	v_lshl_add_u64 v[104:105], v[8:9], 0, s[16:17]
	s_mov_b32 m0, s15
	s_nop 0
	global_load_lds_dwordx4 v[104:105], off
	v_mfma_f32_16x16x32_bf16 v[112:115], v[160:163], v[148:151], v[112:115]
	s_mov_b64 s[14:15], 0x5201c0
	v_lshl_add_u64 v[128:129], v[6:7], 0, s[14:15]
	s_mov_b64 s[14:15], 0x1c0
	v_mfma_f32_16x16x32_bf16 v[116:119], v[160:163], v[152:155], v[116:119]
	v_lshl_add_u64 v[176:177], v[8:9], 0, s[14:15]
	s_mov_b64 s[14:15], 0x5221c0
	v_mfma_f32_16x16x32_bf16 v[92:95], v[160:163], v[156:159], v[92:95]
	v_mfma_f32_16x16x32_bf16 v[124:127], v[164:167], v[148:151], v[124:127]
	v_mfma_f32_16x16x32_bf16 v[132:135], v[164:167], v[152:155], v[132:135]
	v_mfma_f32_16x16x32_bf16 v[96:99], v[164:167], v[156:159], v[96:99]
	v_mfma_f32_16x16x32_bf16 v[140:143], v[168:171], v[148:151], v[140:143]
	v_mfma_f32_16x16x32_bf16 v[144:147], v[168:171], v[152:155], v[144:147]
	v_mfma_f32_16x16x32_bf16 v[100:103], v[168:171], v[156:159], v[100:103]
	v_mfma_f32_16x16x32_bf16 v[16:19], v[172:175], v[148:151], v[16:19]
	v_mfma_f32_16x16x32_bf16 v[20:23], v[172:175], v[152:155], v[20:23]
	v_mfma_f32_16x16x32_bf16 v[24:27], v[172:175], v[156:159], v[24:27]
	ds_read_b128 v[104:107], v11 offset:24576
	ds_read_b128 v[148:151], v11 offset:25600
	ds_read_b128 v[152:155], v11 offset:26624
	ds_read_b128 v[156:159], v11 offset:27648
	ds_read_b128 v[160:163], v10 offset:40960
	ds_read_b128 v[164:167], v10 offset:41984
	ds_read_b128 v[168:171], v10 offset:43008
	ds_read_b128 v[172:175], v10 offset:44032
	s_waitcnt lgkmcnt(3)
	v_mfma_f32_16x16x32_bf16 v[44:47], v[160:163], v[104:107], v[44:47]
	v_mfma_f32_16x16x32_bf16 v[48:51], v[160:163], v[148:151], v[48:51]
	v_mfma_f32_16x16x32_bf16 v[52:55], v[160:163], v[152:155], v[52:55]
	v_mfma_f32_16x16x32_bf16 v[28:31], v[160:163], v[156:159], v[28:31]
	s_waitcnt lgkmcnt(2)
	v_mfma_f32_16x16x32_bf16 v[56:59], v[164:167], v[104:107], v[56:59]
	v_mfma_f32_16x16x32_bf16 v[60:63], v[164:167], v[148:151], v[60:63]
	v_mfma_f32_16x16x32_bf16 v[64:67], v[164:167], v[152:155], v[64:67]
	v_mfma_f32_16x16x32_bf16 v[32:35], v[164:167], v[156:159], v[32:35]
	s_waitcnt lgkmcnt(1)
	v_mfma_f32_16x16x32_bf16 v[68:71], v[168:171], v[104:107], v[68:71]
	v_mfma_f32_16x16x32_bf16 v[72:75], v[168:171], v[148:151], v[72:75]
	v_mfma_f32_16x16x32_bf16 v[76:79], v[168:171], v[152:155], v[76:79]
	v_mfma_f32_16x16x32_bf16 v[36:39], v[168:171], v[156:159], v[36:39]
	s_waitcnt lgkmcnt(0)
	v_mfma_f32_16x16x32_bf16 v[80:83], v[172:175], v[104:107], v[80:83]
	v_mfma_f32_16x16x32_bf16 v[84:87], v[172:175], v[148:151], v[84:87]
	v_mfma_f32_16x16x32_bf16 v[88:91], v[172:175], v[152:155], v[88:91]
	v_mfma_f32_16x16x32_bf16 v[40:43], v[172:175], v[156:159], v[40:43]
	ds_read_b128 v[160:163], v10 offset:45056
	ds_read_b128 v[164:167], v10 offset:46080
	ds_read_b128 v[168:171], v10 offset:47104
	ds_read_b128 v[172:175], v10 offset:48128
	s_waitcnt vmcnt(6)
	s_waitcnt lgkmcnt(0)
	s_barrier
; template <int N> DI void wait_vm() { asm volatile("s_waitcnt vmcnt(%0)" ::"n"(N) : "memory"); }
; template <int BM, class Epi>
; DI void gemm_dma(const u16* __restrict__ X, long ldx, const u16* __restrict__ W, long ldw, int K, char* smem,
;                  int m0, int n0, const Epi& epi) {
;     ...
;   do {
;     if (kt + D - 2 < nk) wait_vm<PW * (D - 2)>(); else wait_vm<0>();
;     __syncthreads();
;     if (kt + D - 1 < nk) GD_ISSUE(nxt)
;     nxt = (nxt + 1 == D) ? 0 : nxt + 1;
;     const char* base = smem + cur * STG;
;     cur = (cur + 1 == D) ? 0 : cur + 1;
;     bf16x8 xf[MT];
; #pragma unroll
;     for (int i = 0; i < MT; ++i) xf[i] = *(const bf16x8*)(base + (xrow0 + i * 16) * 64 + rd);
; #pragma unroll
;     for (int nh = 0; nh < NT / 4; ++nh) {
;       bf16x8 wf[4];
; #pragma unroll
;       for (int i = 0; i < 4; ++i) wf[i] = *(const bf16x8*)(base + BM * 64 + (wrow0 + (nh * 4 + i) * 16) * 64 + rd);
; #pragma unroll
;       for (int i = 0; i < 4; ++i)
; #pragma unroll
;         for (int mt = 0; mt < MT; ++mt)
;           acc[nh * 4 + i][mt] = __builtin_amdgcn_mfma_f32_16x16x32_bf16(wf[i], xf[mt], acc[nh * 4 + i][mt], 0, 0, 0);
	s_mov_b32 m0, s10
	s_nop 0
	global_load_lds_dwordx4 v[128:129], off
	v_mfma_f32_16x16x32_bf16 v[108:111], v[160:163], v[104:107], v[108:111]
	v_mfma_f32_16x16x32_bf16 v[120:123], v[164:167], v[104:107], v[120:123]
	v_mfma_f32_16x16x32_bf16 v[136:139], v[168:171], v[104:107], v[136:139]
	v_mfma_f32_16x16x32_bf16 v[12:15], v[172:175], v[104:107], v[12:15]
	v_lshl_add_u64 v[104:105], v[6:7], 0, s[14:15]
	s_mov_b32 m0, s9
	s_nop 0
	global_load_lds_dwordx4 v[104:105], off
	s_mov_b64 s[14:15], 0x5241c0
	v_lshl_add_u64 v[104:105], v[6:7], 0, s[14:15]
	s_mov_b32 m0, s12
	s_nop 0
	global_load_lds_dwordx4 v[104:105], off
	s_mov_b64 s[12:13], 0x5261c0
	v_lshl_add_u64 v[6:7], v[6:7], 0, s[12:13]
	s_mov_b32 m0, s11
	s_nop 0
	global_load_lds_dwordx4 v[6:7], off
	s_mov_b64 s[10:11], 0x21c0
	s_mov_b32 m0, s7
	s_nop 0
	global_load_lds_dwordx4 v[176:177], off
	v_lshl_add_u64 v[6:7], v[8:9], 0, s[10:11]
	s_mov_b32 m0, s8
	s_nop 0
	global_load_lds_dwordx4 v[6:7], off
	v_mfma_f32_16x16x32_bf16 v[112:115], v[160:163], v[148:151], v[112:115]
	v_mfma_f32_16x16x32_bf16 v[116:119], v[160:163], v[152:155], v[116:119]
	v_mfma_f32_16x16x32_bf16 v[92:95], v[160:163], v[156:159], v[92:95]
	v_mfma_f32_16x16x32_bf16 v[124:127], v[164:167], v[148:151], v[124:127]
	v_mfma_f32_16x16x32_bf16 v[132:135], v[164:167], v[152:155], v[132:135]
	v_mfma_f32_16x16x32_bf16 v[96:99], v[164:167], v[156:159], v[96:99]
	v_mfma_f32_16x16x32_bf16 v[140:143], v[168:171], v[148:151], v[140:143]
	v_mfma_f32_16x16x32_bf16 v[144:147], v[168:171], v[152:155], v[144:147]
	v_mfma_f32_16x16x32_bf16 v[100:103], v[168:171], v[156:159], v[100:103]
	v_mfma_f32_16x16x32_bf16 v[16:19], v[172:175], v[148:151], v[16:19]
	v_mfma_f32_16x16x32_bf16 v[20:23], v[172:175], v[152:155], v[20:23]
	v_mfma_f32_16x16x32_bf16 v[24:27], v[172:175], v[156:159], v[24:27]
	ds_read_b128 v[6:9], v11 offset:49152
	ds_read_b128 v[104:107], v11 offset:50176
	ds_read_b128 v[148:151], v11 offset:51200
	ds_read_b128 v[152:155], v11 offset:52224
	ds_read_b128 v[156:159], v2
	ds_read_b128 v[160:163], v3
	ds_read_b128 v[164:167], v4
	ds_read_b128 v[2:5], v5
	s_waitcnt lgkmcnt(3)
	v_mfma_f32_16x16x32_bf16 v[44:47], v[156:159], v[6:9], v[44:47]
	v_mfma_f32_16x16x32_bf16 v[48:51], v[156:159], v[104:107], v[48:51]
	v_mfma_f32_16x16x32_bf16 v[52:55], v[156:159], v[148:151], v[52:55]
	v_mfma_f32_16x16x32_bf16 v[28:31], v[156:159], v[152:155], v[28:31]
	s_waitcnt lgkmcnt(2)
	v_mfma_f32_16x16x32_bf16 v[56:59], v[160:163], v[6:9], v[56:59]
	v_mfma_f32_16x16x32_bf16 v[60:63], v[160:163], v[104:107], v[60:63]
	v_mfma_f32_16x16x32_bf16 v[64:67], v[160:163], v[148:151], v[64:67]
	v_mfma_f32_16x16x32_bf16 v[32:35], v[160:163], v[152:155], v[32:35]
	s_waitcnt lgkmcnt(1)
	v_mfma_f32_16x16x32_bf16 v[68:71], v[164:167], v[6:9], v[68:71]
	v_mfma_f32_16x16x32_bf16 v[72:75], v[164:167], v[104:107], v[72:75]
	v_mfma_f32_16x16x32_bf16 v[76:79], v[164:167], v[148:151], v[76:79]
	v_mfma_f32_16x16x32_bf16 v[36:39], v[164:167], v[152:155], v[36:39]
	s_waitcnt lgkmcnt(0)
	v_mfma_f32_16x16x32_bf16 v[80:83], v[2:5], v[6:9], v[80:83]
	v_mfma_f32_16x16x32_bf16 v[84:87], v[2:5], v[104:107], v[84:87]
	v_mfma_f32_16x16x32_bf16 v[88:91], v[2:5], v[148:151], v[88:91]
	v_mfma_f32_16x16x32_bf16 v[2:5], v[2:5], v[152:155], v[40:43]
	s_nop 2
	ds_read_b128 v[40:43], v178
	ds_read_b128 v[156:159], v179
	ds_read_b128 v[160:163], v180
	ds_read_b128 v[164:167], v181
	s_waitcnt vmcnt(6)
	s_waitcnt lgkmcnt(0)
	v_mfma_f32_16x16x32_bf16 v[108:111], v[40:43], v[6:9], v[108:111]
	s_barrier
	v_mfma_f32_16x16x32_bf16 v[112:115], v[40:43], v[104:107], v[112:115]
	v_mfma_f32_16x16x32_bf16 v[116:119], v[40:43], v[148:151], v[116:119]
	v_mfma_f32_16x16x32_bf16 v[40:43], v[40:43], v[152:155], v[92:95]
	v_mfma_f32_16x16x32_bf16 v[92:95], v[156:159], v[6:9], v[120:123]
	v_mfma_f32_16x16x32_bf16 v[120:123], v[156:159], v[104:107], v[124:127]
	v_mfma_f32_16x16x32_bf16 v[124:127], v[156:159], v[148:151], v[132:135]
	v_mfma_f32_16x16x32_bf16 v[96:99], v[156:159], v[152:155], v[96:99]
	v_mfma_f32_16x16x32_bf16 v[132:135], v[160:163], v[6:9], v[136:139]
	v_mfma_f32_16x16x32_bf16 v[136:139], v[160:163], v[104:107], v[140:143]
	v_mfma_f32_16x16x32_bf16 v[140:143], v[160:163], v[148:151], v[144:147]
	v_mfma_f32_16x16x32_bf16 v[100:103], v[160:163], v[152:155], v[100:103]
	v_mfma_f32_16x16x32_bf16 v[6:9], v[164:167], v[6:9], v[12:15]
	v_mfma_f32_16x16x32_bf16 v[12:15], v[164:167], v[104:107], v[16:19]
	v_mfma_f32_16x16x32_bf16 v[16:19], v[164:167], v[148:151], v[20:23]
	v_mfma_f32_16x16x32_bf16 v[20:23], v[164:167], v[152:155], v[24:27]
	s_nop 2
	ds_read_b128 v[24:27], v10 offset:23552
	ds_read_b128 v[104:107], v10 offset:22528
	ds_read_b128 v[144:147], v10 offset:21504
	ds_read_b128 v[148:151], v10 offset:20480
	ds_read_b128 v[152:155], v10 offset:19456
	ds_read_b128 v[156:159], v10 offset:18432
	ds_read_b128 v[160:163], v10 offset:17408
	ds_read_b128 v[164:167], v10 offset:16384
	ds_read_b128 v[168:171], v11 offset:3072
	ds_read_b128 v[172:175], v11 offset:2048
	ds_read_b128 v[176:179], v11 offset:1024
	ds_read_b128 v[186:189], v11
	s_waitcnt vmcnt(0)
	s_waitcnt lgkmcnt(0)
	v_mfma_f32_16x16x32_bf16 v[44:47], v[164:167], v[186:189], v[44:47]
	s_barrier
; DI void st_bf4(u16* p, float a, float b, float c, float d) { *(uint2*)p = make_uint2(pk2(a, b), pk2(c, d)); }
; template <int BM, class Epi>
; DI void gemm_dma(const u16* __restrict__ X, long ldx, const u16* __restrict__ W, long ldw, int K, char* smem,
;                  int m0, int n0, const Epi& epi) {
;     ...
;     for (int i = 0; i < MT; ++i) xf[i] = *(const bf16x8*)(base + (xrow0 + i * 16) * 64 + rd);
; #pragma unroll
;     for (int nh = 0; nh < NT / 4; ++nh) {
;       bf16x8 wf[4];
; #pragma unroll
;       for (int i = 0; i < 4; ++i) wf[i] = *(const bf16x8*)(base + BM * 64 + (wrow0 + (nh * 4 + i) * 16) * 64 + rd);
; #pragma unroll
;       for (int i = 0; i < 4; ++i)
; #pragma unroll
;         for (int mt = 0; mt < MT; ++mt)
;           acc[nh * 4 + i][mt] = __builtin_amdgcn_mfma_f32_16x16x32_bf16(wf[i], xf[mt], acc[nh * 4 + i][mt], 0, 0, 0);
;     }
;   } while (++kt < nk);
;     ...
;   epi.run(acc, m0 + xrow0 + lr, n0 + wrow0 + 4 * g);
;   template <int NT, int MT> DI void run(f32x4 (&acc)[NT][MT], int mb, int nb) const {
; #pragma unroll
;     for (int nt = 0; nt < NT; ++nt) {
;       const int n = nb + nt * 16;
;       const int np = (n & ~12) | ((n & 4) << 1) | ((n & 8) >> 1);
; #pragma unroll
;       for (int mt = 0; mt < MT; ++mt) {
;         f32x4 v = acc[nt][mt];
;         st_bf4(C + (size_t)(mb + mt * 16) * ldc + np, v[0], v[1], v[2], v[3]);
;       }
;     }
;   }
	v_mfma_f32_16x16x32_bf16 v[48:51], v[164:167], v[176:179], v[48:51]
	v_mfma_f32_16x16x32_bf16 v[52:55], v[164:167], v[172:175], v[52:55]
	v_mfma_f32_16x16x32_bf16 v[28:31], v[164:167], v[168:171], v[28:31]
	v_mfma_f32_16x16x32_bf16 v[56:59], v[160:163], v[186:189], v[56:59]
	v_mfma_f32_16x16x32_bf16 v[60:63], v[160:163], v[176:179], v[60:63]
	v_mfma_f32_16x16x32_bf16 v[64:67], v[160:163], v[172:175], v[64:67]
	v_mfma_f32_16x16x32_bf16 v[32:35], v[160:163], v[168:171], v[32:35]
	v_mfma_f32_16x16x32_bf16 v[68:71], v[156:159], v[186:189], v[68:71]
	v_mfma_f32_16x16x32_bf16 v[72:75], v[156:159], v[176:179], v[72:75]
	v_mfma_f32_16x16x32_bf16 v[76:79], v[156:159], v[172:175], v[76:79]
	v_mfma_f32_16x16x32_bf16 v[36:39], v[156:159], v[168:171], v[36:39]
	v_mfma_f32_16x16x32_bf16 v[156:159], v[152:155], v[186:189], v[80:83]
	v_mfma_f32_16x16x32_bf16 v[160:163], v[152:155], v[176:179], v[84:87]
	v_mfma_f32_16x16x32_bf16 v[164:167], v[152:155], v[172:175], v[88:91]
	v_mfma_f32_16x16x32_bf16 v[2:5], v[152:155], v[168:171], v[2:5]
	v_mfma_f32_16x16x32_bf16 v[152:155], v[148:151], v[186:189], v[108:111]
	v_mfma_f32_16x16x32_bf16 v[190:193], v[148:151], v[176:179], v[112:115]
	v_mfma_f32_16x16x32_bf16 v[194:197], v[148:151], v[172:175], v[116:119]
	v_mfma_f32_16x16x32_bf16 v[40:43], v[148:151], v[168:171], v[40:43]
	v_mfma_f32_16x16x32_bf16 v[148:151], v[144:147], v[186:189], v[92:95]
	v_mfma_f32_16x16x32_bf16 v[224:227], v[144:147], v[176:179], v[120:123]
	v_mfma_f32_16x16x32_bf16 v[228:231], v[144:147], v[172:175], v[124:127]
	v_mfma_f32_16x16x32_bf16 v[144:147], v[144:147], v[168:171], v[96:99]
	v_mfma_f32_16x16x32_bf16 v[132:135], v[104:107], v[186:189], v[132:135]
	v_mfma_f32_16x16x32_bf16 v[136:139], v[104:107], v[176:179], v[136:139]
	v_mfma_f32_16x16x32_bf16 v[140:143], v[104:107], v[172:175], v[140:143]
	v_mfma_f32_16x16x32_bf16 v[232:235], v[104:107], v[168:171], v[100:103]
	v_mfma_f32_16x16x32_bf16 v[6:9], v[24:27], v[186:189], v[6:9]
	v_mfma_f32_16x16x32_bf16 v[176:179], v[24:27], v[176:179], v[12:15]
	v_mfma_f32_16x16x32_bf16 v[172:175], v[24:27], v[172:175], v[16:19]
	v_mfma_f32_16x16x32_bf16 v[168:171], v[24:27], v[168:171], v[20:23]
	ds_read_b128 v[186:189], v10 offset:48128
	ds_read_b128 v[12:15], v10 offset:47104
	ds_read_b128 v[16:19], v10 offset:46080
	ds_read_b128 v[20:23], v10 offset:45056
	ds_read_b128 v[24:27], v10 offset:44032
	ds_read_b128 v[80:83], v10 offset:43008
	ds_read_b128 v[84:87], v10 offset:41984
	ds_read_b128 v[88:91], v10 offset:40960
	ds_read_b128 v[236:239], v11 offset:27648
	ds_read_b128 v[240:243], v11 offset:26624
	ds_read_b128 v[244:247], v11 offset:25600
	ds_read_b128 v[248:251], v11 offset:24576
	s_waitcnt lgkmcnt(3)
	v_mfma_f32_16x16x32_bf16 v[114:117], v[88:91], v[236:239], v[28:31]
	v_mfma_f32_16x16x32_bf16 v[98:101], v[84:87], v[236:239], v[32:35]
	s_waitcnt lgkmcnt(0)
	v_mfma_f32_16x16x32_bf16 v[30:33], v[12:15], v[248:251], v[132:135]
	s_nop 4
	v_cvt_pk_bf16_f32 v114, v114, v115
	v_cvt_pk_bf16_f32 v115, v116, v117
	v_cvt_pk_bf16_f32 v98, v98, v99
	v_or_b32_e32 v134, v131, v130
	v_lshrrev_b32_e32 v130, 1, v1
	v_mfma_f32_16x16x32_bf16 v[126:129], v[88:91], v[248:251], v[44:47]
	v_and_b32_e32 v130, 8, v130
	v_lshrrev_b32_e32 v1, 3, v1
	v_and_or_b32 v1, v1, 4, v130
	v_or_b32_e32 v132, s6, v1
	v_mad_i64_i32 v[130:131], s[6:7], s40, v134, 0
	v_lshl_add_u64 v[130:131], v[130:131], 1, s[38:39]
	v_lshlrev_b32_e32 v182, 1, v132
	v_mfma_f32_16x16x32_bf16 v[122:125], v[88:91], v[244:247], v[48:51]
	v_lshl_add_u64 v[132:133], v[130:131], 0, v[182:183]
	v_cvt_pk_bf16_f32 v126, v126, v127
	v_cvt_pk_bf16_f32 v127, v128, v129
	global_store_dwordx2 v[132:133], v[126:127], off
	v_or_b32_e32 v126, 16, v134
	v_mad_i64_i32 v[126:127], s[6:7], s40, v126, 0
	v_lshl_add_u64 v[126:127], v[126:127], 1, s[38:39]
	v_mfma_f32_16x16x32_bf16 v[118:121], v[88:91], v[240:243], v[52:55]
	v_lshl_add_u64 v[128:129], v[126:127], 0, v[182:183]
	v_cvt_pk_bf16_f32 v122, v122, v123
	v_cvt_pk_bf16_f32 v123, v124, v125
	global_store_dwordx2 v[128:129], v[122:123], off
	v_or_b32_e32 v122, 32, v134
	v_mad_i64_i32 v[122:123], s[6:7], s40, v122, 0
	v_lshl_add_u64 v[122:123], v[122:123], 1, s[38:39]
	v_lshl_add_u64 v[124:125], v[122:123], 0, v[182:183]
	v_cvt_pk_bf16_f32 v118, v118, v119
	v_cvt_pk_bf16_f32 v119, v120, v121
	v_mfma_f32_16x16x32_bf16 v[110:113], v[84:87], v[248:251], v[56:59]
	global_store_dwordx2 v[124:125], v[118:119], off
	v_or_b32_e32 v118, 48, v134
	v_mad_i64_i32 v[118:119], s[6:7], s40, v118, 0
	v_mfma_f32_16x16x32_bf16 v[106:109], v[84:87], v[244:247], v[60:63]
	v_lshl_add_u64 v[118:119], v[118:119], 1, s[38:39]
	v_or_b32_e32 v1, s5, v1
	v_lshl_add_u64 v[120:121], v[118:119], 0, v[182:183]
	v_mfma_f32_16x16x32_bf16 v[102:105], v[84:87], v[240:243], v[64:67]
	v_lshlrev_b32_e32 v182, 1, v1
	global_store_dwordx2 v[120:121], v[114:115], off
	v_lshl_add_u64 v[114:115], v[130:131], 0, v[182:183]
	v_mfma_f32_16x16x32_bf16 v[94:97], v[80:83], v[248:251], v[68:71]
	v_cvt_pk_bf16_f32 v110, v110, v111
	v_cvt_pk_bf16_f32 v111, v112, v113
	global_store_dwordx2 v[114:115], v[110:111], off offset:32
; DI void st_bf4(u16* p, float a, float b, float c, float d) { *(uint2*)p = make_uint2(pk2(a, b), pk2(c, d)); }
; template <int BM, class Epi>
; DI void gemm_dma(const u16* __restrict__ X, long ldx, const u16* __restrict__ W, long ldw, int K, char* smem,
;                  int m0, int n0, const Epi& epi) {
;     ...
;     for (int i = 0; i < MT; ++i) xf[i] = *(const bf16x8*)(base + (xrow0 + i * 16) * 64 + rd);
; #pragma unroll
;     for (int nh = 0; nh < NT / 4; ++nh) {
;       bf16x8 wf[4];
; #pragma unroll
;       for (int i = 0; i < 4; ++i) wf[i] = *(const bf16x8*)(base + BM * 64 + (wrow0 + (nh * 4 + i) * 16) * 64 + rd);
; #pragma unroll
;       for (int i = 0; i < 4; ++i)
; #pragma unroll
;         for (int mt = 0; mt < MT; ++mt)
;           acc[nh * 4 + i][mt] = __builtin_amdgcn_mfma_f32_16x16x32_bf16(wf[i], xf[mt], acc[nh * 4 + i][mt], 0, 0, 0);
;   template <int NT, int MT> DI void run(f32x4 (&acc)[NT][MT], int mb, int nb) const {
; #pragma unroll
;     for (int nt = 0; nt < NT; ++nt) {
;       const int n = nb + nt * 16;
;       const int np = (n & ~12) | ((n & 4) << 1) | ((n & 8) >> 1);
; #pragma unroll
;       for (int mt = 0; mt < MT; ++mt) {
;         f32x4 v = acc[nt][mt];
;         st_bf4(C + (size_t)(mb + mt * 16) * ldc + np, v[0], v[1], v[2], v[3]);
;       }
;     }
;   }
	v_mfma_f32_16x16x32_bf16 v[90:93], v[80:83], v[244:247], v[72:75]
	v_lshl_add_u64 v[110:111], v[126:127], 0, v[182:183]
	v_cvt_pk_bf16_f32 v106, v106, v107
	v_cvt_pk_bf16_f32 v107, v108, v109
	v_mfma_f32_16x16x32_bf16 v[86:89], v[80:83], v[240:243], v[76:79]
	global_store_dwordx2 v[110:111], v[106:107], off offset:32
	v_lshl_add_u64 v[106:107], v[122:123], 0, v[182:183]
	v_cvt_pk_bf16_f32 v102, v102, v103
	v_mfma_f32_16x16x32_bf16 v[82:85], v[80:83], v[236:239], v[36:39]
	v_cvt_pk_bf16_f32 v103, v104, v105
	global_store_dwordx2 v[106:107], v[102:103], off offset:32
	v_lshl_add_u64 v[102:103], v[118:119], 0, v[182:183]
	v_mfma_f32_16x16x32_bf16 v[78:81], v[24:27], v[248:251], v[156:159]
	v_cvt_pk_bf16_f32 v99, v100, v101
	v_cvt_pk_bf16_f32 v94, v94, v95
	v_cvt_pk_bf16_f32 v95, v96, v97
	v_mfma_f32_16x16x32_bf16 v[74:77], v[24:27], v[244:247], v[160:163]
	v_cvt_pk_bf16_f32 v90, v90, v91
	v_cvt_pk_bf16_f32 v91, v92, v93
	v_cvt_pk_bf16_f32 v86, v86, v87
	v_mfma_f32_16x16x32_bf16 v[70:73], v[24:27], v[240:243], v[164:167]
	v_cvt_pk_bf16_f32 v87, v88, v89
	v_cvt_pk_bf16_f32 v82, v82, v83
	v_cvt_pk_bf16_f32 v83, v84, v85
	v_mfma_f32_16x16x32_bf16 v[66:69], v[24:27], v[236:239], v[2:5]
	v_cvt_pk_bf16_f32 v78, v78, v79
	v_cvt_pk_bf16_f32 v79, v80, v81
	v_cvt_pk_bf16_f32 v74, v74, v75
	v_mfma_f32_16x16x32_bf16 v[62:65], v[20:23], v[248:251], v[152:155]
	v_cvt_pk_bf16_f32 v75, v76, v77
	v_cvt_pk_bf16_f32 v70, v70, v71
	v_cvt_pk_bf16_f32 v71, v72, v73
	v_mfma_f32_16x16x32_bf16 v[58:61], v[20:23], v[244:247], v[190:193]
	v_cvt_pk_bf16_f32 v66, v66, v67
	v_cvt_pk_bf16_f32 v67, v68, v69
	s_nop 1
	v_cvt_pk_bf16_f32 v62, v62, v63
	v_mfma_f32_16x16x32_bf16 v[54:57], v[20:23], v[240:243], v[194:197]
	v_cvt_pk_bf16_f32 v63, v64, v65
	s_nop 0
	v_cvt_pk_bf16_f32 v58, v58, v59
	v_cvt_pk_bf16_f32 v59, v60, v61
	v_mfma_f32_16x16x32_bf16 v[50:53], v[20:23], v[236:239], v[40:43]
	v_cvt_pk_bf16_f32 v30, v30, v31
	s_nop 1
	v_cvt_pk_bf16_f32 v54, v54, v55
	v_cvt_pk_bf16_f32 v55, v56, v57
	v_mfma_f32_16x16x32_bf16 v[46:49], v[16:19], v[248:251], v[148:151]
	v_cvt_pk_bf16_f32 v31, v32, v33
	s_nop 0
	v_cvt_pk_bf16_f32 v50, v50, v51
	v_cvt_pk_bf16_f32 v51, v52, v53
	v_mfma_f32_16x16x32_bf16 v[42:45], v[16:19], v[244:247], v[224:227]
	global_store_dwordx2 v[102:103], v[98:99], off offset:32
	s_nop 1
	v_cvt_pk_bf16_f32 v46, v46, v47
	v_cvt_pk_bf16_f32 v47, v48, v49
	v_mfma_f32_16x16x32_bf16 v[38:41], v[16:19], v[240:243], v[228:231]
	global_store_dwordx2 v[114:115], v[94:95], off offset:64
	s_nop 0
	v_cvt_pk_bf16_f32 v42, v42, v43
	v_cvt_pk_bf16_f32 v43, v44, v45
	v_mfma_f32_16x16x32_bf16 v[34:37], v[16:19], v[236:239], v[144:147]
	global_store_dwordx2 v[110:111], v[90:91], off offset:64
	s_nop 1
	v_cvt_pk_bf16_f32 v38, v38, v39
	v_cvt_pk_bf16_f32 v39, v40, v41
	v_mfma_f32_16x16x32_bf16 v[26:29], v[12:15], v[244:247], v[136:139]
	global_store_dwordx2 v[106:107], v[86:87], off offset:64
	s_nop 0
	v_cvt_pk_bf16_f32 v34, v34, v35
	v_cvt_pk_bf16_f32 v35, v36, v37
	v_mfma_f32_16x16x32_bf16 v[22:25], v[12:15], v[240:243], v[140:143]
	global_store_dwordx2 v[102:103], v[82:83], off offset:64
	s_nop 1
	v_cvt_pk_bf16_f32 v26, v26, v27
	v_cvt_pk_bf16_f32 v27, v28, v29
	v_mfma_f32_16x16x32_bf16 v[18:21], v[12:15], v[236:239], v[232:235]
	global_store_dwordx2 v[114:115], v[78:79], off offset:96
	s_nop 0
	v_cvt_pk_bf16_f32 v22, v22, v23
	v_cvt_pk_bf16_f32 v23, v24, v25
	v_mfma_f32_16x16x32_bf16 v[14:17], v[186:189], v[248:251], v[6:9]
	global_store_dwordx2 v[110:111], v[74:75], off offset:96
	s_nop 1
	v_cvt_pk_bf16_f32 v18, v18, v19
	v_cvt_pk_bf16_f32 v19, v20, v21
	v_mfma_f32_16x16x32_bf16 v[10:13], v[186:189], v[244:247], v[176:179]
	global_store_dwordx2 v[106:107], v[70:71], off offset:96
	s_nop 0
	v_cvt_pk_bf16_f32 v14, v14, v15
	v_cvt_pk_bf16_f32 v15, v16, v17
	v_mfma_f32_16x16x32_bf16 v[6:9], v[186:189], v[240:243], v[172:175]
	global_store_dwordx2 v[102:103], v[66:67], off offset:96
	s_nop 1
	v_cvt_pk_bf16_f32 v10, v10, v11
	v_cvt_pk_bf16_f32 v11, v12, v13
	v_mfma_f32_16x16x32_bf16 v[2:5], v[186:189], v[236:239], v[168:171]
	global_store_dwordx2 v[114:115], v[62:63], off offset:128
	s_nop 0
	v_cvt_pk_bf16_f32 v6, v6, v7
	v_cvt_pk_bf16_f32 v7, v8, v9
	global_store_dwordx2 v[110:111], v[58:59], off offset:128
	global_store_dwordx2 v[106:107], v[54:55], off offset:128
	s_nop 1
	v_cvt_pk_bf16_f32 v2, v2, v3
	v_cvt_pk_bf16_f32 v3, v4, v5
	global_store_dwordx2 v[102:103], v[50:51], off offset:128
	global_store_dwordx2 v[114:115], v[46:47], off offset:160
	global_store_dwordx2 v[110:111], v[42:43], off offset:160
	global_store_dwordx2 v[106:107], v[38:39], off offset:160
	global_store_dwordx2 v[102:103], v[34:35], off offset:160
	global_store_dwordx2 v[114:115], v[30:31], off offset:192
	global_store_dwordx2 v[110:111], v[26:27], off offset:192
	global_store_dwordx2 v[106:107], v[22:23], off offset:192
	global_store_dwordx2 v[102:103], v[18:19], off offset:192
	global_store_dwordx2 v[114:115], v[14:15], off offset:224
	global_store_dwordx2 v[110:111], v[10:11], off offset:224
	global_store_dwordx2 v[106:107], v[6:7], off offset:224
	global_store_dwordx2 v[102:103], v[2:3], off offset:224

; template <int N> DI void wait_vm() { asm volatile("s_waitcnt vmcnt(%0)" ::"n"(N) : "memory"); }
; template <int BM, class Epi>
; DI void gemm_dma(const u16* __restrict__ X, long ldx, const u16* __restrict__ W, long ldw, int K, char* smem,
;                  int m0, int n0, const Epi& epi) {
;     ...
;   const int wu = __builtin_amdgcn_readfirstlane(wave);
;   const unsigned sbase = (unsigned)__builtin_amdgcn_readfirstlane((int)(unsigned)(size_t)smem);
;   const int r16 = lane >> 2, chunk = (lane & 3) ^ ((4 - (r16 >> 2)) & 3);
;   const u16* xs = X + (long)(wu * XD * 16 + r16) * ldx + (chunk << 3);
;   const u16* ws = W + (long)(wu * 32 + r16) * ldw + (chunk << 3);
;   const long ldx16 = 16 * ldx, ldw16 = 16 * ldw;
;   const unsigned xdst = sbase + wu * XD * 1024, wdst = sbase + BM * 64 + wu * 2048;
;     ...
;   const int nk = K >> 5;
;   __syncthreads();
; #pragma unroll
;   for (int s = 0; s < D - 1; ++s) GD_ISSUE(s)
;   int cur = 0, nxt = D - 1, kt = 0;
;   do {
;     if (kt + D - 2 < nk) wait_vm<PW * (D - 2)>(); else wait_vm<0>();
;     __syncthreads();
;     if (kt + D - 1 < nk) GD_ISSUE(nxt)
;     nxt = (nxt + 1 == D) ? 0 : nxt + 1;
;     const char* base = smem + cur * STG;
;     cur = (cur + 1 == D) ? 0 : cur + 1;
;     bf16x8 xf[MT];
; #pragma unroll
;     for (int i = 0; i < MT; ++i) xf[i] = *(const bf16x8*)(base + (xrow0 + i * 16) * 64 + rd);
; #pragma unroll
;     for (int nh = 0; nh < NT / 4; ++nh) {
;       bf16x8 wf[4];
; #pragma unroll
;       for (int i = 0; i < 4; ++i) wf[i] = *(const bf16x8*)(base + BM * 64 + (wrow0 + (nh * 4 + i) * 16) * 64 + rd);
; DI void knope_tile(const Params& p, int u, char* smem) {
;   const u16* W = (const u16*)(p.ws + OFF_W);
;   const u16* ckvb = (const u16*)(p.ws + OFF_CKVB);
;   EpiBF16 ek{(u16*)(p.ws + OFF_KN), 1024};
;   const int tm = u >> 3, tn = u & 7;
;   gemm_dma<256>(ckvb + (size_t)tm * 256 * 256, 256, W + WO_KV + (size_t)tn * 128 * 256, 256, 256, smem, tm * 256, tn * 128, ek);
; }
.LBB0_84:
	s_cmpk_gt_i32 s4, 0x77f
	s_cbranch_scc1 .LBB0_92
	s_cmpk_gt_i32 s4, 0x43f
	s_mov_b64 s[38:39], -1
	s_cbranch_scc0 .LBB0_87
	s_add_i32 s5, s4, 0xfffffcc0
	s_bfe_u32 s98, s5, 0x30003
	s_and_b32 s99, s5, 7
	s_lshl_b32 s99, s99, 3
	s_andn2_b32 s5, s5, 63
	s_or_b32 s5, s5, s99
	s_or_b32 s5, s5, s98
	s_lshr_b32 s6, s5, 3
	s_and_b32 s5, s5, 7
	s_lshl_b32 s7, s6, 17
	s_add_u32 s8, s0, s7
	s_addc_u32 s9, s1, 0
	s_lshl_b32 s7, s5, 16
	v_mov_b32_e32 v11, v185
	s_add_u32 s10, s87, s7
	s_addc_u32 s11, s90, 0
	v_readfirstlane_b32 s7, v11
	v_lshrrev_b32_e32 v6, 4, v11
	s_ashr_i32 s12, s7, 6
	v_bfe_u32 v8, v11, 2, 4
	v_sub_u32_e32 v6, 0, v6
	s_andn2_b32 s7, s7, 63
	v_lshrrev_b32_e32 v3, 2, v11
	v_xor_b32_e32 v9, v11, v6
	v_or_b32_e32 v6, s7, v8
	v_and_b32_e32 v90, 15, v11
	v_bfe_u32 v1, v11, 4, 2
	v_sub_u32_e32 v3, 0, v3
	v_ashrrev_i32_e32 v7, 31, v6
	v_lshlrev_b32_e32 v2, 6, v90
	v_bitop3_b32 v3, v1, v3, 3 bitop3:0x78
	v_lshlrev_b64 v[6:7], 9, v[6:7]
	v_lshlrev_b32_e32 v9, 4, v9
	v_lshl_or_b32 v8, s12, 5, v8
	v_lshl_or_b32 v10, v3, 4, v2
	v_mov_b32_e32 v2, v183
	v_lshl_add_u64 v[6:7], s[8:9], 0, v[6:7]
	v_and_b32_e32 v182, 48, v9
	v_ashrrev_i32_e32 v9, 31, v8
	v_lshl_add_u64 v[6:7], v[6:7], 0, v[182:183]
	v_lshlrev_b64 v[8:9], 9, v[8:9]
	s_lshl_b32 s14, s12, 12
	s_barrier
	s_mov_b32 m0, s14
	s_nop 0
	global_load_lds_dwordx4 v[6:7], off
	s_mov_b64 s[8:9], 0x2000
	v_lshl_add_u64 v[8:9], s[10:11], 0, v[8:9]
	v_lshl_add_u64 v[12:13], v[6:7], 0, s[8:9]
	s_or_b32 s15, s14, 0x400
	s_mov_b32 m0, s15
	s_nop 0
	global_load_lds_dwordx4 v[12:13], off
	s_mov_b64 s[10:11], 0x4000
	v_lshl_add_u64 v[12:13], v[6:7], 0, s[10:11]
	s_or_b32 s16, s14, 0x800
	s_mov_b32 m0, s16
	s_nop 0
	global_load_lds_dwordx4 v[12:13], off
	s_mov_b64 s[10:11], 0x6000
	s_lshl_b32 s41, s12, 11
	v_lshl_add_u64 v[12:13], v[6:7], 0, s[10:11]
	s_or_b32 s17, s14, 0xc00
	s_mov_b32 m0, s17
	s_nop 0
	global_load_lds_dwordx4 v[12:13], off
	v_lshl_add_u64 v[8:9], v[8:9], 0, v[182:183]
	s_add_i32 s13, s41, 0x4000
	s_mov_b32 m0, s13
	s_nop 0
	global_load_lds_dwordx4 v[8:9], off
	v_lshl_add_u64 v[12:13], v[8:9], 0, s[8:9]
	s_add_i32 s18, s41, 0x4400
	s_mov_b32 m0, s18
	s_nop 0
	global_load_lds_dwordx4 v[12:13], off
	v_lshl_add_u64 v[12:13], v[6:7], 0, 64
	s_add_i32 s7, s14, 0x6000
	s_mov_b32 m0, s7
	s_nop 0
	global_load_lds_dwordx4 v[12:13], off
	s_mov_b64 s[20:21], 0x2040
	v_lshl_add_u64 v[12:13], v[6:7], 0, s[20:21]
	s_add_i32 s8, s14, 0x6400
	s_mov_b32 m0, s8
	s_nop 0
	global_load_lds_dwordx4 v[12:13], off
	s_mov_b64 s[10:11], 0x4040
	v_lshl_add_u64 v[12:13], v[6:7], 0, s[10:11]
	s_add_i32 s9, s14, 0x6800
	s_mov_b32 m0, s9
	s_nop 0
	global_load_lds_dwordx4 v[12:13], off
	s_mov_b64 s[10:11], 0x6040
	v_lshl_add_u64 v[12:13], v[6:7], 0, s[10:11]
	s_add_i32 s10, s14, 0x6c00
	s_mov_b32 m0, s10
	s_nop 0
	global_load_lds_dwordx4 v[12:13], off
	v_lshl_add_u64 v[14:15], v[8:9], 0, 64
	s_add_i32 s11, s41, 0xa000
	s_mov_b32 m0, s11
	s_nop 0
	global_load_lds_dwordx4 v[14:15], off
	v_lshl_add_u64 v[12:13], v[8:9], 0, s[20:21]
	s_add_i32 s12, s41, 0xa400
	s_mov_b32 m0, s12
	s_nop 0
	global_load_lds_dwordx4 v[12:13], off
	s_waitcnt vmcnt(6)
	s_barrier
	v_lshl_add_u64 v[14:15], v[6:7], 0, s[28:29]
	s_add_i32 s19, s14, 0xc000
	s_mov_b32 m0, s19
	s_nop 0
	global_load_lds_dwordx4 v[14:15], off
	s_mov_b64 s[20:21], 0x2080
	v_lshl_add_u64 v[14:15], v[6:7], 0, s[20:21]
	s_add_i32 s34, s14, 0xc400
	s_mov_b32 m0, s34
	s_nop 0
	global_load_lds_dwordx4 v[14:15], off
	v_lshl_add_u64 v[14:15], v[6:7], 0, s[94:95]
	s_add_i32 s38, s14, 0xc800
	s_mov_b32 m0, s38
	s_nop 0
	global_load_lds_dwordx4 v[14:15], off
	s_mov_b64 s[22:23], 0x6080
	v_lshl_add_u64 v[14:15], v[6:7], 0, s[22:23]
	s_add_i32 s39, s14, 0xcc00
	s_mov_b32 m0, s39
	s_nop 0
	global_load_lds_dwordx4 v[14:15], off
	v_and_b32_e32 v91, 0xffffffc0, v11
	v_lshl_add_u64 v[12:13], v[8:9], 0, s[28:29]
	s_add_i32 s40, s41, 0x10000
	s_mov_b32 m0, s40
	s_nop 0
	global_load_lds_dwordx4 v[12:13], off
	v_lshl_add_u64 v[12:13], v[8:9], 0, s[20:21]
	s_add_i32 s41, s41, 0x10400
	s_mov_b32 m0, s41
	s_nop 0
	global_load_lds_dwordx4 v[12:13], off
	v_lshl_or_b32 v11, v91, 6, v10
	ds_read_b128 v[12:15], v11
	ds_read_b128 v[16:19], v11 offset:1024
	ds_read_b128 v[20:23], v11 offset:2048
	ds_read_b128 v[24:27], v11 offset:3072
	ds_read_b128 v[28:31], v10 offset:16384
	ds_read_b128 v[32:35], v10 offset:17408
	ds_read_b128 v[36:39], v10 offset:18432
	ds_read_b128 v[40:43], v10 offset:19456
	ds_read_b128 v[96:99], v10 offset:20480
	ds_read_b128 v[100:103], v10 offset:21504
	ds_read_b128 v[104:107], v10 offset:22528
	ds_read_b128 v[108:111], v10 offset:23552
	s_mov_b64 s[20:21], 0xc0
	v_mov_b32_e32 v3, v2
	v_mov_b32_e32 v4, v2
	v_mov_b32_e32 v5, v2
	v_lshl_add_u64 v[88:89], v[6:7], 0, s[20:21]
	v_lshl_add_u64 v[148:149], v[8:9], 0, s[20:21]
	s_waitcnt vmcnt(6)
	s_waitcnt lgkmcnt(0)
	s_barrier
; template <int N> DI void wait_vm() { asm volatile("s_waitcnt vmcnt(%0)" ::"n"(N) : "memory"); }
; template <int BM, class Epi>
; DI void gemm_dma(const u16* __restrict__ X, long ldx, const u16* __restrict__ W, long ldw, int K, char* smem,
;                  int m0, int n0, const Epi& epi) {
;     ...
;   do {
;     if (kt + D - 2 < nk) wait_vm<PW * (D - 2)>(); else wait_vm<0>();
;     __syncthreads();
;     if (kt + D - 1 < nk) GD_ISSUE(nxt)
;     nxt = (nxt + 1 == D) ? 0 : nxt + 1;
;     const char* base = smem + cur * STG;
;     cur = (cur + 1 == D) ? 0 : cur + 1;
;     bf16x8 xf[MT];
; #pragma unroll
;     for (int i = 0; i < MT; ++i) xf[i] = *(const bf16x8*)(base + (xrow0 + i * 16) * 64 + rd);
; #pragma unroll
;     for (int nh = 0; nh < NT / 4; ++nh) {
;       bf16x8 wf[4];
; #pragma unroll
;       for (int i = 0; i < 4; ++i) wf[i] = *(const bf16x8*)(base + BM * 64 + (wrow0 + (nh * 4 + i) * 16) * 64 + rd);
; #pragma unroll
;       for (int i = 0; i < 4; ++i)
; #pragma unroll
;         for (int mt = 0; mt < MT; ++mt)
;           acc[nh * 4 + i][mt] = __builtin_amdgcn_mfma_f32_16x16x32_bf16(wf[i], xf[mt], acc[nh * 4 + i][mt], 0, 0, 0);
	s_mov_b32 m0, s14
	s_nop 0
	global_load_lds_dwordx4 v[88:89], off
	s_mov_b64 s[20:21], 0x20c0
	v_mfma_f32_16x16x32_bf16 v[44:47], v[28:31], v[12:15], v[2:5]
	s_mov_b64 s[22:23], 0x40c0
	v_or_b32_e32 v174, 0x10000, v10
	v_or_b32_e32 v175, 0x10400, v10
	v_mfma_f32_16x16x32_bf16 v[48:51], v[28:31], v[16:19], v[2:5]
	v_or_b32_e32 v176, 0x10800, v10
	v_or_b32_e32 v177, 0x10c00, v10
	v_or_b32_e32 v178, 0x11000, v10
	v_mfma_f32_16x16x32_bf16 v[52:55], v[28:31], v[20:23], v[2:5]
	v_or_b32_e32 v179, 0x11400, v10
	v_or_b32_e32 v180, 0x11800, v10
	v_or_b32_e32 v181, 0x11c00, v10
	v_mfma_f32_16x16x32_bf16 v[28:31], v[28:31], v[24:27], v[2:5]
	v_lshl_add_u32 v91, s6, 8, v91
	s_lshl_b32 s5, s5, 8
	v_lshl_or_b32 v182, v1, 3, s5
	v_mfma_f32_16x16x32_bf16 v[56:59], v[32:35], v[12:15], v[2:5]
	v_mfma_f32_16x16x32_bf16 v[60:63], v[32:35], v[16:19], v[2:5]
	v_mfma_f32_16x16x32_bf16 v[64:67], v[32:35], v[20:23], v[2:5]
	v_mfma_f32_16x16x32_bf16 v[32:35], v[32:35], v[24:27], v[2:5]
	v_mfma_f32_16x16x32_bf16 v[68:71], v[36:39], v[12:15], v[2:5]
	v_mfma_f32_16x16x32_bf16 v[72:75], v[36:39], v[16:19], v[2:5]
	v_mfma_f32_16x16x32_bf16 v[76:79], v[36:39], v[20:23], v[2:5]
	v_mfma_f32_16x16x32_bf16 v[36:39], v[36:39], v[24:27], v[2:5]
	v_mfma_f32_16x16x32_bf16 v[80:83], v[40:43], v[12:15], v[2:5]
	v_mfma_f32_16x16x32_bf16 v[84:87], v[40:43], v[16:19], v[2:5]
	v_mfma_f32_16x16x32_bf16 v[92:95], v[40:43], v[20:23], v[2:5]
	v_mfma_f32_16x16x32_bf16 v[40:43], v[40:43], v[24:27], v[2:5]
	v_mfma_f32_16x16x32_bf16 v[112:115], v[96:99], v[12:15], v[2:5]
	v_mfma_f32_16x16x32_bf16 v[116:119], v[96:99], v[16:19], v[2:5]
	v_mfma_f32_16x16x32_bf16 v[120:123], v[96:99], v[20:23], v[2:5]
	v_mfma_f32_16x16x32_bf16 v[96:99], v[96:99], v[24:27], v[2:5]
	v_mfma_f32_16x16x32_bf16 v[124:127], v[100:103], v[12:15], v[2:5]
	v_mfma_f32_16x16x32_bf16 v[128:131], v[100:103], v[16:19], v[2:5]
	v_mfma_f32_16x16x32_bf16 v[132:135], v[100:103], v[20:23], v[2:5]
	v_mfma_f32_16x16x32_bf16 v[100:103], v[100:103], v[24:27], v[2:5]
	v_mfma_f32_16x16x32_bf16 v[136:139], v[104:107], v[12:15], v[2:5]
	v_mfma_f32_16x16x32_bf16 v[140:143], v[104:107], v[16:19], v[2:5]
	v_mfma_f32_16x16x32_bf16 v[144:147], v[104:107], v[20:23], v[2:5]
	v_mfma_f32_16x16x32_bf16 v[104:107], v[104:107], v[24:27], v[2:5]
	v_mfma_f32_16x16x32_bf16 v[12:15], v[108:111], v[12:15], v[2:5]
	v_mfma_f32_16x16x32_bf16 v[16:19], v[108:111], v[16:19], v[2:5]
	v_mfma_f32_16x16x32_bf16 v[20:23], v[108:111], v[20:23], v[2:5]
	v_mfma_f32_16x16x32_bf16 v[2:5], v[108:111], v[24:27], v[2:5]
	v_lshl_add_u64 v[24:25], v[6:7], 0, s[20:21]
	s_mov_b32 m0, s15
	s_nop 0
	global_load_lds_dwordx4 v[24:25], off
	v_lshl_add_u64 v[24:25], v[6:7], 0, s[22:23]
	s_mov_b32 m0, s16
	s_nop 0
	global_load_lds_dwordx4 v[24:25], off
	s_mov_b64 s[22:23], 0x60c0
	v_lshl_add_u64 v[24:25], v[6:7], 0, s[22:23]
	s_mov_b32 m0, s17
	s_nop 0
	global_load_lds_dwordx4 v[24:25], off
	v_lshl_add_u64 v[24:25], v[8:9], 0, s[20:21]
	s_mov_b32 m0, s13
	s_nop 0
	global_load_lds_dwordx4 v[148:149], off
	s_mov_b64 s[20:21], 0x100
	s_mov_b32 m0, s18
	s_nop 0
	global_load_lds_dwordx4 v[24:25], off
	ds_read_b128 v[24:27], v11 offset:24576
	ds_read_b128 v[108:111], v11 offset:25600
	ds_read_b128 v[148:151], v11 offset:26624
	ds_read_b128 v[152:155], v11 offset:27648
	ds_read_b128 v[156:159], v10 offset:40960
	ds_read_b128 v[160:163], v10 offset:41984
	ds_read_b128 v[164:167], v10 offset:43008
	ds_read_b128 v[168:171], v10 offset:44032
	s_waitcnt lgkmcnt(3)
	v_mfma_f32_16x16x32_bf16 v[44:47], v[156:159], v[24:27], v[44:47]
	v_lshl_add_u64 v[88:89], v[6:7], 0, s[20:21]
	v_lshl_add_u64 v[172:173], v[8:9], 0, s[20:21]
	s_mov_b64 s[20:21], 0x2100
	v_mfma_f32_16x16x32_bf16 v[48:51], v[156:159], v[108:111], v[48:51]
	s_mov_b64 s[22:23], 0x4100
	v_mfma_f32_16x16x32_bf16 v[52:55], v[156:159], v[148:151], v[52:55]
	v_mfma_f32_16x16x32_bf16 v[28:31], v[156:159], v[152:155], v[28:31]
	s_waitcnt lgkmcnt(2)
	v_mfma_f32_16x16x32_bf16 v[56:59], v[160:163], v[24:27], v[56:59]
	v_mfma_f32_16x16x32_bf16 v[60:63], v[160:163], v[108:111], v[60:63]
	v_mfma_f32_16x16x32_bf16 v[64:67], v[160:163], v[148:151], v[64:67]
	v_mfma_f32_16x16x32_bf16 v[32:35], v[160:163], v[152:155], v[32:35]
	s_waitcnt lgkmcnt(1)
	v_mfma_f32_16x16x32_bf16 v[68:71], v[164:167], v[24:27], v[68:71]
	v_mfma_f32_16x16x32_bf16 v[72:75], v[164:167], v[108:111], v[72:75]
	v_mfma_f32_16x16x32_bf16 v[76:79], v[164:167], v[148:151], v[76:79]
	v_mfma_f32_16x16x32_bf16 v[36:39], v[164:167], v[152:155], v[36:39]
	s_waitcnt lgkmcnt(0)
	v_mfma_f32_16x16x32_bf16 v[80:83], v[168:171], v[24:27], v[80:83]
	v_mfma_f32_16x16x32_bf16 v[84:87], v[168:171], v[108:111], v[84:87]
	v_mfma_f32_16x16x32_bf16 v[92:95], v[168:171], v[148:151], v[92:95]
	v_mfma_f32_16x16x32_bf16 v[40:43], v[168:171], v[152:155], v[40:43]
	ds_read_b128 v[156:159], v10 offset:45056
	ds_read_b128 v[160:163], v10 offset:46080
	ds_read_b128 v[164:167], v10 offset:47104
	ds_read_b128 v[168:171], v10 offset:48128
	s_waitcnt vmcnt(6)
	s_waitcnt lgkmcnt(0)
	s_barrier
; template <int N> DI void wait_vm() { asm volatile("s_waitcnt vmcnt(%0)" ::"n"(N) : "memory"); }
; template <int BM, class Epi>
; DI void gemm_dma(const u16* __restrict__ X, long ldx, const u16* __restrict__ W, long ldw, int K, char* smem,
;                  int m0, int n0, const Epi& epi) {
;     ...
;   do {
;     if (kt + D - 2 < nk) wait_vm<PW * (D - 2)>(); else wait_vm<0>();
;     __syncthreads();
;     if (kt + D - 1 < nk) GD_ISSUE(nxt)
;     nxt = (nxt + 1 == D) ? 0 : nxt + 1;
;     const char* base = smem + cur * STG;
;     cur = (cur + 1 == D) ? 0 : cur + 1;
;     bf16x8 xf[MT];
; #pragma unroll
;     for (int i = 0; i < MT; ++i) xf[i] = *(const bf16x8*)(base + (xrow0 + i * 16) * 64 + rd);
; #pragma unroll
;     for (int nh = 0; nh < NT / 4; ++nh) {
;       bf16x8 wf[4];
; #pragma unroll
;       for (int i = 0; i < 4; ++i) wf[i] = *(const bf16x8*)(base + BM * 64 + (wrow0 + (nh * 4 + i) * 16) * 64 + rd);
; #pragma unroll
;       for (int i = 0; i < 4; ++i)
; #pragma unroll
;         for (int mt = 0; mt < MT; ++mt)
;           acc[nh * 4 + i][mt] = __builtin_amdgcn_mfma_f32_16x16x32_bf16(wf[i], xf[mt], acc[nh * 4 + i][mt], 0, 0, 0);
	s_mov_b32 m0, s7
	s_nop 0
	global_load_lds_dwordx4 v[88:89], off
	v_mfma_f32_16x16x32_bf16 v[112:115], v[156:159], v[24:27], v[112:115]
	v_mfma_f32_16x16x32_bf16 v[124:127], v[160:163], v[24:27], v[124:127]
	v_mfma_f32_16x16x32_bf16 v[136:139], v[164:167], v[24:27], v[136:139]
	v_mfma_f32_16x16x32_bf16 v[12:15], v[168:171], v[24:27], v[12:15]
	v_lshl_add_u64 v[24:25], v[6:7], 0, s[20:21]
	s_mov_b32 m0, s8
	s_nop 0
	global_load_lds_dwordx4 v[24:25], off
	v_lshl_add_u64 v[24:25], v[6:7], 0, s[22:23]
	s_mov_b32 m0, s9
	s_nop 0
	global_load_lds_dwordx4 v[24:25], off
	s_mov_b64 s[22:23], 0x6100
	v_lshl_add_u64 v[24:25], v[6:7], 0, s[22:23]
	s_mov_b32 m0, s10
	s_nop 0
	global_load_lds_dwordx4 v[24:25], off
	v_lshl_add_u64 v[24:25], v[8:9], 0, s[20:21]
	s_mov_b32 m0, s11
	s_nop 0
	global_load_lds_dwordx4 v[172:173], off
	v_mfma_f32_16x16x32_bf16 v[116:119], v[156:159], v[108:111], v[116:119]
	s_mov_b32 m0, s12
	s_nop 0
	global_load_lds_dwordx4 v[24:25], off
	s_mov_b64 s[20:21], 0x140
	v_lshl_add_u64 v[88:89], v[6:7], 0, s[20:21]
	v_mfma_f32_16x16x32_bf16 v[120:123], v[156:159], v[148:151], v[120:123]
	v_lshl_add_u64 v[172:173], v[8:9], 0, s[20:21]
	s_mov_b64 s[20:21], 0x2140
	s_mov_b64 s[22:23], 0x4140
	v_mfma_f32_16x16x32_bf16 v[96:99], v[156:159], v[152:155], v[96:99]
	v_mfma_f32_16x16x32_bf16 v[128:131], v[160:163], v[108:111], v[128:131]
	v_mfma_f32_16x16x32_bf16 v[132:135], v[160:163], v[148:151], v[132:135]
	v_mfma_f32_16x16x32_bf16 v[100:103], v[160:163], v[152:155], v[100:103]
	v_mfma_f32_16x16x32_bf16 v[140:143], v[164:167], v[108:111], v[140:143]
	v_mfma_f32_16x16x32_bf16 v[144:147], v[164:167], v[148:151], v[144:147]
	v_mfma_f32_16x16x32_bf16 v[104:107], v[164:167], v[152:155], v[104:107]
	v_mfma_f32_16x16x32_bf16 v[16:19], v[168:171], v[108:111], v[16:19]
	v_mfma_f32_16x16x32_bf16 v[20:23], v[168:171], v[148:151], v[20:23]
	v_mfma_f32_16x16x32_bf16 v[2:5], v[168:171], v[152:155], v[2:5]
	ds_read_b128 v[24:27], v11 offset:49152
	ds_read_b128 v[108:111], v11 offset:50176
	ds_read_b128 v[148:151], v11 offset:51200
	ds_read_b128 v[152:155], v11 offset:52224
	ds_read_b128 v[156:159], v174
	ds_read_b128 v[160:163], v175
	ds_read_b128 v[164:167], v176
	ds_read_b128 v[168:171], v177
	s_waitcnt lgkmcnt(3)
	v_mfma_f32_16x16x32_bf16 v[44:47], v[156:159], v[24:27], v[44:47]
	v_mfma_f32_16x16x32_bf16 v[48:51], v[156:159], v[108:111], v[48:51]
	v_mfma_f32_16x16x32_bf16 v[52:55], v[156:159], v[148:151], v[52:55]
	v_mfma_f32_16x16x32_bf16 v[28:31], v[156:159], v[152:155], v[28:31]
	ds_read_b128 v[156:159], v178
	s_waitcnt lgkmcnt(3)
	v_mfma_f32_16x16x32_bf16 v[56:59], v[160:163], v[24:27], v[56:59]
	v_mfma_f32_16x16x32_bf16 v[60:63], v[160:163], v[108:111], v[60:63]
	v_mfma_f32_16x16x32_bf16 v[64:67], v[160:163], v[148:151], v[64:67]
	v_mfma_f32_16x16x32_bf16 v[32:35], v[160:163], v[152:155], v[32:35]
	ds_read_b128 v[160:163], v179
	s_waitcnt lgkmcnt(3)
	v_mfma_f32_16x16x32_bf16 v[68:71], v[164:167], v[24:27], v[68:71]
	v_mfma_f32_16x16x32_bf16 v[72:75], v[164:167], v[108:111], v[72:75]
	v_mfma_f32_16x16x32_bf16 v[76:79], v[164:167], v[148:151], v[76:79]
	v_mfma_f32_16x16x32_bf16 v[36:39], v[164:167], v[152:155], v[36:39]
	ds_read_b128 v[164:167], v180
	s_waitcnt lgkmcnt(3)
	v_mfma_f32_16x16x32_bf16 v[80:83], v[168:171], v[24:27], v[80:83]
	v_mfma_f32_16x16x32_bf16 v[84:87], v[168:171], v[108:111], v[84:87]
	v_mfma_f32_16x16x32_bf16 v[92:95], v[168:171], v[148:151], v[92:95]
	v_mfma_f32_16x16x32_bf16 v[40:43], v[168:171], v[152:155], v[40:43]
	ds_read_b128 v[168:171], v181
	s_waitcnt vmcnt(6)
	s_waitcnt lgkmcnt(0)
	s_barrier
	s_mov_b32 m0, s19
	s_nop 0
	global_load_lds_dwordx4 v[88:89], off
	v_mfma_f32_16x16x32_bf16 v[112:115], v[156:159], v[24:27], v[112:115]
	v_mfma_f32_16x16x32_bf16 v[124:127], v[160:163], v[24:27], v[124:127]
	v_mfma_f32_16x16x32_bf16 v[136:139], v[164:167], v[24:27], v[136:139]
	v_mfma_f32_16x16x32_bf16 v[12:15], v[168:171], v[24:27], v[12:15]
	v_lshl_add_u64 v[24:25], v[6:7], 0, s[20:21]
	s_mov_b32 m0, s34
	s_nop 0
	global_load_lds_dwordx4 v[24:25], off
	v_lshl_add_u64 v[24:25], v[6:7], 0, s[22:23]
	s_mov_b32 m0, s38
	s_nop 0
	global_load_lds_dwordx4 v[24:25], off
	s_mov_b64 s[22:23], 0x6140
	v_lshl_add_u64 v[24:25], v[6:7], 0, s[22:23]
	s_mov_b32 m0, s39
	s_nop 0
	global_load_lds_dwordx4 v[24:25], off
	v_lshl_add_u64 v[24:25], v[8:9], 0, s[20:21]
	s_mov_b32 m0, s40
	s_nop 0
	global_load_lds_dwordx4 v[172:173], off
	v_mfma_f32_16x16x32_bf16 v[116:119], v[156:159], v[108:111], v[116:119]
	s_mov_b32 m0, s41
	s_nop 0
	global_load_lds_dwordx4 v[24:25], off
	s_mov_b64 s[20:21], 0x180
	v_lshl_add_u64 v[88:89], v[6:7], 0, s[20:21]
	v_mfma_f32_16x16x32_bf16 v[120:123], v[156:159], v[148:151], v[120:123]
	v_lshl_add_u64 v[172:173], v[8:9], 0, s[20:21]
	s_mov_b64 s[20:21], 0x2180
	s_mov_b64 s[38:39], 0
	v_mfma_f32_16x16x32_bf16 v[96:99], v[156:159], v[152:155], v[96:99]
	v_mfma_f32_16x16x32_bf16 v[128:131], v[160:163], v[108:111], v[128:131]
	v_mfma_f32_16x16x32_bf16 v[132:135], v[160:163], v[148:151], v[132:135]
	v_mfma_f32_16x16x32_bf16 v[100:103], v[160:163], v[152:155], v[100:103]
	v_mfma_f32_16x16x32_bf16 v[140:143], v[164:167], v[108:111], v[140:143]
	v_mfma_f32_16x16x32_bf16 v[144:147], v[164:167], v[148:151], v[144:147]
	v_mfma_f32_16x16x32_bf16 v[104:107], v[164:167], v[152:155], v[104:107]
	v_mfma_f32_16x16x32_bf16 v[16:19], v[168:171], v[108:111], v[16:19]
	v_mfma_f32_16x16x32_bf16 v[20:23], v[168:171], v[148:151], v[20:23]
	v_mfma_f32_16x16x32_bf16 v[2:5], v[168:171], v[152:155], v[2:5]
	ds_read_b128 v[24:27], v11
	ds_read_b128 v[108:111], v11 offset:1024
	ds_read_b128 v[148:151], v11 offset:2048
	ds_read_b128 v[152:155], v11 offset:3072
	ds_read_b128 v[156:159], v10 offset:16384
	ds_read_b128 v[160:163], v10 offset:17408
	ds_read_b128 v[164:167], v10 offset:18432
	ds_read_b128 v[168:171], v10 offset:19456
	s_waitcnt lgkmcnt(3)
; template <int N> DI void wait_vm() { asm volatile("s_waitcnt vmcnt(%0)" ::"n"(N) : "memory"); }
; template <int BM, class Epi>
; DI void gemm_dma(const u16* __restrict__ X, long ldx, const u16* __restrict__ W, long ldw, int K, char* smem,
;                  int m0, int n0, const Epi& epi) {
;     ...
;   do {
;     if (kt + D - 2 < nk) wait_vm<PW * (D - 2)>(); else wait_vm<0>();
;     __syncthreads();
;     if (kt + D - 1 < nk) GD_ISSUE(nxt)
;     nxt = (nxt + 1 == D) ? 0 : nxt + 1;
;     const char* base = smem + cur * STG;
;     cur = (cur + 1 == D) ? 0 : cur + 1;
;     bf16x8 xf[MT];
; #pragma unroll
;     for (int i = 0; i < MT; ++i) xf[i] = *(const bf16x8*)(base + (xrow0 + i * 16) * 64 + rd);
; #pragma unroll
;     for (int nh = 0; nh < NT / 4; ++nh) {
;       bf16x8 wf[4];
; #pragma unroll
;       for (int i = 0; i < 4; ++i) wf[i] = *(const bf16x8*)(base + BM * 64 + (wrow0 + (nh * 4 + i) * 16) * 64 + rd);
; #pragma unroll
;       for (int i = 0; i < 4; ++i)
; #pragma unroll
;         for (int mt = 0; mt < MT; ++mt)
;           acc[nh * 4 + i][mt] = __builtin_amdgcn_mfma_f32_16x16x32_bf16(wf[i], xf[mt], acc[nh * 4 + i][mt], 0, 0, 0);
	v_mfma_f32_16x16x32_bf16 v[44:47], v[156:159], v[24:27], v[44:47]
	v_mfma_f32_16x16x32_bf16 v[48:51], v[156:159], v[108:111], v[48:51]
	v_mfma_f32_16x16x32_bf16 v[52:55], v[156:159], v[148:151], v[52:55]
	v_mfma_f32_16x16x32_bf16 v[28:31], v[156:159], v[152:155], v[28:31]
	s_waitcnt lgkmcnt(2)
	v_mfma_f32_16x16x32_bf16 v[56:59], v[160:163], v[24:27], v[56:59]
	v_mfma_f32_16x16x32_bf16 v[60:63], v[160:163], v[108:111], v[60:63]
	v_mfma_f32_16x16x32_bf16 v[64:67], v[160:163], v[148:151], v[64:67]
	v_mfma_f32_16x16x32_bf16 v[32:35], v[160:163], v[152:155], v[32:35]
	s_waitcnt lgkmcnt(1)
	v_mfma_f32_16x16x32_bf16 v[68:71], v[164:167], v[24:27], v[68:71]
	v_mfma_f32_16x16x32_bf16 v[72:75], v[164:167], v[108:111], v[72:75]
	v_mfma_f32_16x16x32_bf16 v[76:79], v[164:167], v[148:151], v[76:79]
	v_mfma_f32_16x16x32_bf16 v[36:39], v[164:167], v[152:155], v[36:39]
	s_waitcnt lgkmcnt(0)
	v_mfma_f32_16x16x32_bf16 v[80:83], v[168:171], v[24:27], v[80:83]
	v_mfma_f32_16x16x32_bf16 v[84:87], v[168:171], v[108:111], v[84:87]
	v_mfma_f32_16x16x32_bf16 v[92:95], v[168:171], v[148:151], v[92:95]
	v_mfma_f32_16x16x32_bf16 v[40:43], v[168:171], v[152:155], v[40:43]
	ds_read_b128 v[156:159], v10 offset:20480
	ds_read_b128 v[160:163], v10 offset:21504
	ds_read_b128 v[164:167], v10 offset:22528
	ds_read_b128 v[168:171], v10 offset:23552
	s_waitcnt vmcnt(6)
	s_waitcnt lgkmcnt(0)
	s_barrier
	s_mov_b32 m0, s14
	s_nop 0
	global_load_lds_dwordx4 v[88:89], off
	v_mfma_f32_16x16x32_bf16 v[112:115], v[156:159], v[24:27], v[112:115]
	v_mfma_f32_16x16x32_bf16 v[124:127], v[160:163], v[24:27], v[124:127]
	v_mfma_f32_16x16x32_bf16 v[136:139], v[164:167], v[24:27], v[136:139]
	v_mfma_f32_16x16x32_bf16 v[12:15], v[168:171], v[24:27], v[12:15]
	v_lshl_add_u64 v[24:25], v[6:7], 0, s[20:21]
	s_mov_b32 m0, s15
	s_nop 0
	global_load_lds_dwordx4 v[24:25], off
	s_mov_b64 s[14:15], 0x4180
	v_lshl_add_u64 v[24:25], v[6:7], 0, s[14:15]
	s_mov_b32 m0, s16
	s_nop 0
	global_load_lds_dwordx4 v[24:25], off
	s_mov_b64 s[14:15], 0x6180
	v_lshl_add_u64 v[24:25], v[6:7], 0, s[14:15]
	s_mov_b32 m0, s17
	s_nop 0
	global_load_lds_dwordx4 v[24:25], off
	v_lshl_add_u64 v[24:25], v[8:9], 0, s[20:21]
	s_mov_b32 m0, s13
	s_nop 0
	global_load_lds_dwordx4 v[172:173], off
	s_mov_b32 m0, s18
	s_nop 0
	global_load_lds_dwordx4 v[24:25], off
	v_mfma_f32_16x16x32_bf16 v[116:119], v[156:159], v[108:111], v[116:119]
	s_mov_b64 s[14:15], 0x1c0
	v_lshl_add_u64 v[88:89], v[6:7], 0, s[14:15]
	v_lshl_add_u64 v[172:173], v[8:9], 0, s[14:15]
	v_mfma_f32_16x16x32_bf16 v[120:123], v[156:159], v[148:151], v[120:123]
	s_mov_b64 s[14:15], 0x21c0
	s_mov_b64 s[16:17], 0x41c0
	v_mfma_f32_16x16x32_bf16 v[96:99], v[156:159], v[152:155], v[96:99]
	v_mfma_f32_16x16x32_bf16 v[128:131], v[160:163], v[108:111], v[128:131]
	v_mfma_f32_16x16x32_bf16 v[132:135], v[160:163], v[148:151], v[132:135]
	v_mfma_f32_16x16x32_bf16 v[100:103], v[160:163], v[152:155], v[100:103]
	v_mfma_f32_16x16x32_bf16 v[140:143], v[164:167], v[108:111], v[140:143]
	v_mfma_f32_16x16x32_bf16 v[144:147], v[164:167], v[148:151], v[144:147]
	v_mfma_f32_16x16x32_bf16 v[104:107], v[164:167], v[152:155], v[104:107]
	v_mfma_f32_16x16x32_bf16 v[16:19], v[168:171], v[108:111], v[16:19]
	v_mfma_f32_16x16x32_bf16 v[20:23], v[168:171], v[148:151], v[20:23]
	v_mfma_f32_16x16x32_bf16 v[2:5], v[168:171], v[152:155], v[2:5]
	ds_read_b128 v[24:27], v11 offset:24576
	ds_read_b128 v[108:111], v11 offset:25600
	ds_read_b128 v[148:151], v11 offset:26624
	ds_read_b128 v[152:155], v11 offset:27648
	ds_read_b128 v[156:159], v10 offset:40960
	ds_read_b128 v[160:163], v10 offset:41984
	ds_read_b128 v[164:167], v10 offset:43008
	ds_read_b128 v[168:171], v10 offset:44032
	s_waitcnt lgkmcnt(3)
	v_mfma_f32_16x16x32_bf16 v[44:47], v[156:159], v[24:27], v[44:47]
	v_mfma_f32_16x16x32_bf16 v[48:51], v[156:159], v[108:111], v[48:51]
	v_mfma_f32_16x16x32_bf16 v[52:55], v[156:159], v[148:151], v[52:55]
	v_mfma_f32_16x16x32_bf16 v[28:31], v[156:159], v[152:155], v[28:31]
	s_waitcnt lgkmcnt(2)
	v_mfma_f32_16x16x32_bf16 v[56:59], v[160:163], v[24:27], v[56:59]
	v_mfma_f32_16x16x32_bf16 v[60:63], v[160:163], v[108:111], v[60:63]
	v_mfma_f32_16x16x32_bf16 v[64:67], v[160:163], v[148:151], v[64:67]
	v_mfma_f32_16x16x32_bf16 v[32:35], v[160:163], v[152:155], v[32:35]
	s_waitcnt lgkmcnt(1)
	v_mfma_f32_16x16x32_bf16 v[68:71], v[164:167], v[24:27], v[68:71]
	v_mfma_f32_16x16x32_bf16 v[72:75], v[164:167], v[108:111], v[72:75]
	v_mfma_f32_16x16x32_bf16 v[76:79], v[164:167], v[148:151], v[76:79]
	v_mfma_f32_16x16x32_bf16 v[36:39], v[164:167], v[152:155], v[36:39]
	s_waitcnt lgkmcnt(0)
	v_mfma_f32_16x16x32_bf16 v[80:83], v[168:171], v[24:27], v[80:83]
	v_mfma_f32_16x16x32_bf16 v[84:87], v[168:171], v[108:111], v[84:87]
	v_mfma_f32_16x16x32_bf16 v[92:95], v[168:171], v[148:151], v[92:95]
	v_mfma_f32_16x16x32_bf16 v[40:43], v[168:171], v[152:155], v[40:43]
	ds_read_b128 v[156:159], v10 offset:45056
	ds_read_b128 v[160:163], v10 offset:46080
	ds_read_b128 v[164:167], v10 offset:47104
	ds_read_b128 v[168:171], v10 offset:48128
	s_waitcnt vmcnt(6)
	s_waitcnt lgkmcnt(0)
	s_barrier
; template <int N> DI void wait_vm() { asm volatile("s_waitcnt vmcnt(%0)" ::"n"(N) : "memory"); }
; template <int BM, class Epi>
; DI void gemm_dma(const u16* __restrict__ X, long ldx, const u16* __restrict__ W, long ldw, int K, char* smem,
;                  int m0, int n0, const Epi& epi) {
;     ...
;   do {
;     if (kt + D - 2 < nk) wait_vm<PW * (D - 2)>(); else wait_vm<0>();
;     __syncthreads();
;     if (kt + D - 1 < nk) GD_ISSUE(nxt)
;     nxt = (nxt + 1 == D) ? 0 : nxt + 1;
;     const char* base = smem + cur * STG;
;     cur = (cur + 1 == D) ? 0 : cur + 1;
;     bf16x8 xf[MT];
; #pragma unroll
;     for (int i = 0; i < MT; ++i) xf[i] = *(const bf16x8*)(base + (xrow0 + i * 16) * 64 + rd);
; #pragma unroll
;     for (int nh = 0; nh < NT / 4; ++nh) {
;       bf16x8 wf[4];
; #pragma unroll
;       for (int i = 0; i < 4; ++i) wf[i] = *(const bf16x8*)(base + BM * 64 + (wrow0 + (nh * 4 + i) * 16) * 64 + rd);
; #pragma unroll
;       for (int i = 0; i < 4; ++i)
; #pragma unroll
;         for (int mt = 0; mt < MT; ++mt)
;           acc[nh * 4 + i][mt] = __builtin_amdgcn_mfma_f32_16x16x32_bf16(wf[i], xf[mt], acc[nh * 4 + i][mt], 0, 0, 0);
	s_mov_b32 m0, s7
	s_nop 0
	global_load_lds_dwordx4 v[88:89], off
	v_mfma_f32_16x16x32_bf16 v[112:115], v[156:159], v[24:27], v[112:115]
	v_mfma_f32_16x16x32_bf16 v[124:127], v[160:163], v[24:27], v[124:127]
	v_mfma_f32_16x16x32_bf16 v[136:139], v[164:167], v[24:27], v[136:139]
	v_mfma_f32_16x16x32_bf16 v[12:15], v[168:171], v[24:27], v[12:15]
	v_lshl_add_u64 v[24:25], v[6:7], 0, s[14:15]
	s_mov_b32 m0, s8
	s_nop 0
	global_load_lds_dwordx4 v[24:25], off
	v_lshl_add_u64 v[24:25], v[6:7], 0, s[16:17]
	s_mov_b32 m0, s9
	s_nop 0
	global_load_lds_dwordx4 v[24:25], off
	s_mov_b64 s[8:9], 0x61c0
	v_lshl_add_u64 v[6:7], v[6:7], 0, s[8:9]
	s_mov_b32 m0, s10
	s_nop 0
	global_load_lds_dwordx4 v[6:7], off
	v_lshl_add_u64 v[6:7], v[8:9], 0, s[14:15]
	s_mov_b32 m0, s11
	s_nop 0
	global_load_lds_dwordx4 v[172:173], off
	v_mfma_f32_16x16x32_bf16 v[116:119], v[156:159], v[108:111], v[116:119]
	s_mov_b32 m0, s12
	s_nop 0
	global_load_lds_dwordx4 v[6:7], off
	v_mfma_f32_16x16x32_bf16 v[120:123], v[156:159], v[148:151], v[120:123]
	v_mfma_f32_16x16x32_bf16 v[96:99], v[156:159], v[152:155], v[96:99]
	v_mfma_f32_16x16x32_bf16 v[128:131], v[160:163], v[108:111], v[128:131]
	v_mfma_f32_16x16x32_bf16 v[132:135], v[160:163], v[148:151], v[132:135]
	v_mfma_f32_16x16x32_bf16 v[100:103], v[160:163], v[152:155], v[100:103]
	v_mfma_f32_16x16x32_bf16 v[140:143], v[164:167], v[108:111], v[140:143]
	v_mfma_f32_16x16x32_bf16 v[144:147], v[164:167], v[148:151], v[144:147]
	v_mfma_f32_16x16x32_bf16 v[104:107], v[164:167], v[152:155], v[104:107]
	v_mfma_f32_16x16x32_bf16 v[16:19], v[168:171], v[108:111], v[16:19]
	v_mfma_f32_16x16x32_bf16 v[20:23], v[168:171], v[148:151], v[20:23]
	v_mfma_f32_16x16x32_bf16 v[2:5], v[168:171], v[152:155], v[2:5]
	ds_read_b128 v[6:9], v11 offset:49152
	ds_read_b128 v[24:27], v11 offset:50176
	ds_read_b128 v[108:111], v11 offset:51200
	ds_read_b128 v[148:151], v11 offset:52224
	ds_read_b128 v[152:155], v174
	ds_read_b128 v[156:159], v175
	ds_read_b128 v[160:163], v176
	ds_read_b128 v[164:167], v177
	s_waitcnt lgkmcnt(3)
	v_mfma_f32_16x16x32_bf16 v[44:47], v[152:155], v[6:9], v[44:47]
	v_mfma_f32_16x16x32_bf16 v[48:51], v[152:155], v[24:27], v[48:51]
	v_mfma_f32_16x16x32_bf16 v[52:55], v[152:155], v[108:111], v[52:55]
	v_mfma_f32_16x16x32_bf16 v[28:31], v[152:155], v[148:151], v[28:31]
	s_waitcnt lgkmcnt(2)
	v_mfma_f32_16x16x32_bf16 v[56:59], v[156:159], v[6:9], v[56:59]
	v_mfma_f32_16x16x32_bf16 v[60:63], v[156:159], v[24:27], v[60:63]
	v_mfma_f32_16x16x32_bf16 v[64:67], v[156:159], v[108:111], v[64:67]
	v_mfma_f32_16x16x32_bf16 v[32:35], v[156:159], v[148:151], v[32:35]
	s_waitcnt lgkmcnt(1)
	v_mfma_f32_16x16x32_bf16 v[68:71], v[160:163], v[6:9], v[68:71]
	v_mfma_f32_16x16x32_bf16 v[72:75], v[160:163], v[24:27], v[72:75]
	v_mfma_f32_16x16x32_bf16 v[76:79], v[160:163], v[108:111], v[76:79]
	v_mfma_f32_16x16x32_bf16 v[36:39], v[160:163], v[148:151], v[36:39]
	s_waitcnt lgkmcnt(0)
	v_mfma_f32_16x16x32_bf16 v[80:83], v[164:167], v[6:9], v[80:83]
	v_mfma_f32_16x16x32_bf16 v[84:87], v[164:167], v[24:27], v[84:87]
	v_mfma_f32_16x16x32_bf16 v[92:95], v[164:167], v[108:111], v[92:95]
	v_mfma_f32_16x16x32_bf16 v[40:43], v[164:167], v[148:151], v[40:43]
	ds_read_b128 v[152:155], v178
	ds_read_b128 v[156:159], v179
	ds_read_b128 v[160:163], v180
	ds_read_b128 v[164:167], v181
	s_waitcnt vmcnt(6)
	s_waitcnt lgkmcnt(0)
	v_mfma_f32_16x16x32_bf16 v[112:115], v[152:155], v[6:9], v[112:115]
	s_barrier
	v_mfma_f32_16x16x32_bf16 v[116:119], v[152:155], v[24:27], v[116:119]
	v_mfma_f32_16x16x32_bf16 v[120:123], v[152:155], v[108:111], v[120:123]
	v_mfma_f32_16x16x32_bf16 v[96:99], v[152:155], v[148:151], v[96:99]
	v_mfma_f32_16x16x32_bf16 v[124:127], v[156:159], v[6:9], v[124:127]
	v_mfma_f32_16x16x32_bf16 v[128:131], v[156:159], v[24:27], v[128:131]
	v_mfma_f32_16x16x32_bf16 v[132:135], v[156:159], v[108:111], v[132:135]
	v_mfma_f32_16x16x32_bf16 v[100:103], v[156:159], v[148:151], v[100:103]
	v_mfma_f32_16x16x32_bf16 v[136:139], v[160:163], v[6:9], v[136:139]
	v_mfma_f32_16x16x32_bf16 v[140:143], v[160:163], v[24:27], v[140:143]
	v_mfma_f32_16x16x32_bf16 v[144:147], v[160:163], v[108:111], v[144:147]
	v_mfma_f32_16x16x32_bf16 v[104:107], v[160:163], v[148:151], v[104:107]
	v_mfma_f32_16x16x32_bf16 v[6:9], v[164:167], v[6:9], v[12:15]
	v_mfma_f32_16x16x32_bf16 v[12:15], v[164:167], v[24:27], v[16:19]
	v_mfma_f32_16x16x32_bf16 v[16:19], v[164:167], v[108:111], v[20:23]
	v_mfma_f32_16x16x32_bf16 v[2:5], v[164:167], v[148:151], v[2:5]
	s_nop 1
	ds_read_b128 v[20:23], v10 offset:23552
	ds_read_b128 v[24:27], v10 offset:22528
	ds_read_b128 v[108:111], v10 offset:21504
	ds_read_b128 v[148:151], v10 offset:20480
	ds_read_b128 v[152:155], v10 offset:19456
	ds_read_b128 v[156:159], v10 offset:18432
	ds_read_b128 v[160:163], v10 offset:17408
	ds_read_b128 v[164:167], v10 offset:16384
	ds_read_b128 v[168:171], v11 offset:3072
	ds_read_b128 v[172:175], v11 offset:2048
	ds_read_b128 v[176:179], v11 offset:1024
	ds_read_b128 v[186:189], v11
	s_waitcnt vmcnt(0)
	s_waitcnt lgkmcnt(0)
	v_mfma_f32_16x16x32_bf16 v[44:47], v[164:167], v[186:189], v[44:47]
	s_barrier
; DI void st_bf4(u16* p, float a, float b, float c, float d) { *(uint2*)p = make_uint2(pk2(a, b), pk2(c, d)); }
; template <int BM, class Epi>
; DI void gemm_dma(const u16* __restrict__ X, long ldx, const u16* __restrict__ W, long ldw, int K, char* smem,
;                  int m0, int n0, const Epi& epi) {
;     ...
;     for (int i = 0; i < MT; ++i) xf[i] = *(const bf16x8*)(base + (xrow0 + i * 16) * 64 + rd);
; #pragma unroll
;     for (int nh = 0; nh < NT / 4; ++nh) {
;       bf16x8 wf[4];
; #pragma unroll
;       for (int i = 0; i < 4; ++i) wf[i] = *(const bf16x8*)(base + BM * 64 + (wrow0 + (nh * 4 + i) * 16) * 64 + rd);
; #pragma unroll
;       for (int i = 0; i < 4; ++i)
; #pragma unroll
;         for (int mt = 0; mt < MT; ++mt)
;           acc[nh * 4 + i][mt] = __builtin_amdgcn_mfma_f32_16x16x32_bf16(wf[i], xf[mt], acc[nh * 4 + i][mt], 0, 0, 0);
;   template <int NT, int MT> DI void run(f32x4 (&acc)[NT][MT], int mb, int nb) const {
; #pragma unroll
;     for (int nt = 0; nt < NT; ++nt)
; #pragma unroll
;       for (int mt = 0; mt < MT; ++mt) {
;         f32x4 v = acc[nt][mt];
;         st_bf4(C + (size_t)(mb + mt * 16) * ldc + nb + nt * 16, v[0], v[1], v[2], v[3]);
;       }
;   }
	v_mfma_f32_16x16x32_bf16 v[48:51], v[164:167], v[176:179], v[48:51]
	v_mfma_f32_16x16x32_bf16 v[52:55], v[164:167], v[172:175], v[52:55]
	v_mfma_f32_16x16x32_bf16 v[28:31], v[164:167], v[168:171], v[28:31]
	v_mfma_f32_16x16x32_bf16 v[56:59], v[160:163], v[186:189], v[56:59]
	v_mfma_f32_16x16x32_bf16 v[60:63], v[160:163], v[176:179], v[60:63]
	v_mfma_f32_16x16x32_bf16 v[64:67], v[160:163], v[172:175], v[64:67]
	v_mfma_f32_16x16x32_bf16 v[32:35], v[160:163], v[168:171], v[32:35]
	v_mfma_f32_16x16x32_bf16 v[68:71], v[156:159], v[186:189], v[68:71]
	v_mfma_f32_16x16x32_bf16 v[72:75], v[156:159], v[176:179], v[72:75]
	v_mfma_f32_16x16x32_bf16 v[76:79], v[156:159], v[172:175], v[76:79]
	v_mfma_f32_16x16x32_bf16 v[36:39], v[156:159], v[168:171], v[36:39]
	v_mfma_f32_16x16x32_bf16 v[156:159], v[152:155], v[186:189], v[80:83]
	v_mfma_f32_16x16x32_bf16 v[86:89], v[152:155], v[176:179], v[84:87]
	v_mfma_f32_16x16x32_bf16 v[92:95], v[152:155], v[172:175], v[92:95]
	v_mfma_f32_16x16x32_bf16 v[152:155], v[152:155], v[168:171], v[40:43]
	v_mfma_f32_16x16x32_bf16 v[112:115], v[148:151], v[186:189], v[112:115]
	v_mfma_f32_16x16x32_bf16 v[116:119], v[148:151], v[176:179], v[116:119]
	v_mfma_f32_16x16x32_bf16 v[120:123], v[148:151], v[172:175], v[120:123]
	v_mfma_f32_16x16x32_bf16 v[96:99], v[148:151], v[168:171], v[96:99]
	v_mfma_f32_16x16x32_bf16 v[124:127], v[108:111], v[186:189], v[124:127]
	v_mfma_f32_16x16x32_bf16 v[128:131], v[108:111], v[176:179], v[128:131]
	v_mfma_f32_16x16x32_bf16 v[132:135], v[108:111], v[172:175], v[132:135]
	v_mfma_f32_16x16x32_bf16 v[100:103], v[108:111], v[168:171], v[100:103]
	v_mfma_f32_16x16x32_bf16 v[108:111], v[24:27], v[186:189], v[136:139]
	v_mfma_f32_16x16x32_bf16 v[136:139], v[24:27], v[176:179], v[140:143]
	v_mfma_f32_16x16x32_bf16 v[140:143], v[24:27], v[172:175], v[144:147]
	v_mfma_f32_16x16x32_bf16 v[104:107], v[24:27], v[168:171], v[104:107]
	v_mfma_f32_16x16x32_bf16 v[6:9], v[20:23], v[186:189], v[6:9]
	v_mfma_f32_16x16x32_bf16 v[144:147], v[20:23], v[176:179], v[12:15]
	v_mfma_f32_16x16x32_bf16 v[148:151], v[20:23], v[172:175], v[16:19]
	v_mfma_f32_16x16x32_bf16 v[2:5], v[20:23], v[168:171], v[2:5]
	s_nop 0
	ds_read_b128 v[12:15], v11 offset:24576
	ds_read_b128 v[160:163], v11 offset:25600
	ds_read_b128 v[164:167], v11 offset:26624
	ds_read_b128 v[168:171], v11 offset:27648
	ds_read_b128 v[16:19], v10 offset:40960
	ds_read_b128 v[20:23], v10 offset:41984
	ds_read_b128 v[24:27], v10 offset:43008
	ds_read_b128 v[172:175], v10 offset:44032
	s_waitcnt lgkmcnt(3)
	v_mfma_f32_16x16x32_bf16 v[176:179], v[16:19], v[12:15], v[44:47]
	v_mfma_f32_16x16x32_bf16 v[186:189], v[16:19], v[160:163], v[48:51]
	v_mfma_f32_16x16x32_bf16 v[190:193], v[16:19], v[164:167], v[52:55]
	v_mfma_f32_16x16x32_bf16 v[194:197], v[16:19], v[168:171], v[28:31]
	s_waitcnt lgkmcnt(2)
	v_mfma_f32_16x16x32_bf16 v[224:227], v[20:23], v[12:15], v[56:59]
	v_mfma_f32_16x16x32_bf16 v[228:231], v[20:23], v[160:163], v[60:63]
	v_mfma_f32_16x16x32_bf16 v[232:235], v[20:23], v[164:167], v[64:67]
	v_mfma_f32_16x16x32_bf16 v[236:239], v[20:23], v[168:171], v[32:35]
	s_waitcnt lgkmcnt(1)
	v_mfma_f32_16x16x32_bf16 v[240:243], v[24:27], v[12:15], v[68:71]
	v_mfma_f32_16x16x32_bf16 v[66:69], v[24:27], v[168:171], v[36:39]
	s_waitcnt lgkmcnt(0)
	v_mfma_f32_16x16x32_bf16 v[42:45], v[172:175], v[164:167], v[92:95]
	v_mfma_f32_16x16x32_bf16 v[34:37], v[172:175], v[168:171], v[152:155]
	ds_read_b128 v[16:19], v10 offset:45056
	ds_read_b128 v[20:23], v10 offset:46080
	ds_read_b128 v[92:95], v10 offset:47104
	ds_read_b128 v[152:155], v10 offset:48128
	s_nop 0
	v_cvt_pk_bf16_f32 v66, v66, v67
	v_cvt_pk_bf16_f32 v67, v68, v69
	v_mfma_f32_16x16x32_bf16 v[82:85], v[24:27], v[160:163], v[72:75]
	v_cvt_pk_bf16_f32 v34, v34, v35
	v_cvt_pk_bf16_f32 v35, v36, v37
	v_cvt_pk_bf16_f32 v42, v42, v43
	v_mfma_f32_16x16x32_bf16 v[74:77], v[24:27], v[164:167], v[76:79]
	v_cvt_pk_bf16_f32 v43, v44, v45
	s_nop 2
	v_cvt_pk_bf16_f32 v82, v82, v83
	v_cvt_pk_bf16_f32 v83, v84, v85
	v_mfma_f32_16x16x32_bf16 v[50:53], v[172:175], v[160:163], v[86:89]
	s_waitcnt lgkmcnt(3)
	v_mfma_f32_16x16x32_bf16 v[112:115], v[16:19], v[12:15], v[112:115]
	v_cvt_pk_bf16_f32 v74, v74, v75
	v_cvt_pk_bf16_f32 v75, v76, v77
	s_nop 3
	v_cvt_pk_bf16_f32 v50, v50, v51
	v_mfma_f32_16x16x32_bf16 v[86:89], v[16:19], v[160:163], v[116:119]
	v_cvt_pk_bf16_f32 v51, v52, v53
	v_mfma_f32_16x16x32_bf16 v[78:81], v[16:19], v[164:167], v[120:123]
	v_mfma_f32_16x16x32_bf16 v[70:73], v[16:19], v[168:171], v[96:99]
	s_waitcnt lgkmcnt(2)
	v_mfma_f32_16x16x32_bf16 v[62:65], v[20:23], v[12:15], v[124:127]
	s_nop 0
	v_cvt_pk_bf16_f32 v96, v186, v187
	v_cvt_pk_bf16_f32 v97, v188, v189
	v_cvt_pk_bf16_f32 v98, v190, v191
	v_mfma_f32_16x16x32_bf16 v[54:57], v[20:23], v[160:163], v[128:131]
	v_cvt_pk_bf16_f32 v99, v192, v193
	v_mfma_f32_16x16x32_bf16 v[46:49], v[20:23], v[164:167], v[132:135]
	v_mfma_f32_16x16x32_bf16 v[38:41], v[20:23], v[168:171], v[100:103]
	s_waitcnt lgkmcnt(1)
; DI void st_bf4(u16* p, float a, float b, float c, float d) { *(uint2*)p = make_uint2(pk2(a, b), pk2(c, d)); }
; template <int BM, class Epi>
; DI void gemm_dma(const u16* __restrict__ X, long ldx, const u16* __restrict__ W, long ldw, int K, char* smem,
;                  int m0, int n0, const Epi& epi) {
;     ...
;       for (int i = 0; i < 4; ++i)
; #pragma unroll
;         for (int mt = 0; mt < MT; ++mt)
;           acc[nh * 4 + i][mt] = __builtin_amdgcn_mfma_f32_16x16x32_bf16(wf[i], xf[mt], acc[nh * 4 + i][mt], 0, 0, 0);
;   template <int NT, int MT> DI void run(f32x4 (&acc)[NT][MT], int mb, int nb) const {
; #pragma unroll
;     for (int nt = 0; nt < NT; ++nt)
; #pragma unroll
;       for (int mt = 0; mt < MT; ++mt) {
;         f32x4 v = acc[nt][mt];
;         st_bf4(C + (size_t)(mb + mt * 16) * ldc + nb + nt * 16, v[0], v[1], v[2], v[3]);
;       }
;   }
	v_mfma_f32_16x16x32_bf16 v[30:33], v[92:95], v[12:15], v[108:111]
	v_mfma_f32_16x16x32_bf16 v[26:29], v[92:95], v[160:163], v[136:139]
	v_mfma_f32_16x16x32_bf16 v[22:25], v[92:95], v[164:167], v[140:143]
	s_nop 5
	v_cvt_pk_bf16_f32 v30, v30, v31
	v_cvt_pk_bf16_f32 v31, v32, v33
	v_cvt_pk_bf16_f32 v26, v26, v27
	v_mfma_f32_16x16x32_bf16 v[18:21], v[92:95], v[168:171], v[104:107]
	v_or_b32_e32 v94, v91, v90
	v_ashrrev_i32_e32 v95, 31, v94
	v_lshlrev_b64 v[90:91], 11, v[94:95]
	v_lshl_add_u64 v[90:91], s[92:93], 0, v[90:91]
	v_lshl_add_u64 v[90:91], v[90:91], 0, v[182:183]
	v_cvt_pk_bf16_f32 v92, v176, v177
	v_cvt_pk_bf16_f32 v93, v178, v179
	global_store_dwordx2 v[90:91], v[92:93], off
	v_or_b32_e32 v92, 16, v94
	v_ashrrev_i32_e32 v93, 31, v92
	v_lshlrev_b64 v[92:93], 11, v[92:93]
	v_lshl_add_u64 v[92:93], s[92:93], 0, v[92:93]
	v_lshl_add_u64 v[92:93], v[92:93], 0, v[182:183]
	global_store_dwordx2 v[92:93], v[96:97], off
	v_or_b32_e32 v96, 32, v94
	v_or_b32_e32 v94, 48, v94
	v_ashrrev_i32_e32 v95, 31, v94
	v_lshlrev_b64 v[94:95], 11, v[94:95]
	v_ashrrev_i32_e32 v97, 31, v96
	v_lshl_add_u64 v[94:95], s[92:93], 0, v[94:95]
	v_lshlrev_b64 v[96:97], 11, v[96:97]
	v_lshl_add_u64 v[94:95], v[94:95], 0, v[182:183]
	v_lshl_add_u64 v[96:97], s[92:93], 0, v[96:97]
	global_store_dwordx2 v[94:95], v[34:35], off offset:96
	v_cvt_pk_bf16_f32 v34, v112, v113
	v_cvt_pk_bf16_f32 v35, v114, v115
	v_lshl_add_u64 v[96:97], v[96:97], 0, v[182:183]
	global_store_dwordx2 v[90:91], v[34:35], off offset:128
	v_cvt_pk_bf16_f32 v34, v86, v87
	v_cvt_pk_bf16_f32 v35, v88, v89
	global_store_dwordx2 v[96:97], v[98:99], off
	v_cvt_pk_bf16_f32 v98, v194, v195
	v_cvt_pk_bf16_f32 v99, v196, v197
	global_store_dwordx2 v[92:93], v[34:35], off offset:128
	v_cvt_pk_bf16_f32 v34, v78, v79
	v_cvt_pk_bf16_f32 v35, v80, v81
	v_mfma_f32_16x16x32_bf16 v[58:61], v[172:175], v[12:15], v[156:159]
	global_store_dwordx2 v[94:95], v[98:99], off
	v_cvt_pk_bf16_f32 v98, v224, v225
	v_cvt_pk_bf16_f32 v99, v226, v227
	s_waitcnt lgkmcnt(0)
	v_mfma_f32_16x16x32_bf16 v[14:17], v[152:155], v[12:15], v[6:9]
	global_store_dwordx2 v[96:97], v[34:35], off offset:128
	v_cvt_pk_bf16_f32 v34, v70, v71
	v_cvt_pk_bf16_f32 v35, v72, v73
	v_mfma_f32_16x16x32_bf16 v[10:13], v[152:155], v[160:163], v[144:147]
	global_store_dwordx2 v[90:91], v[98:99], off offset:32
	v_cvt_pk_bf16_f32 v98, v228, v229
	v_cvt_pk_bf16_f32 v99, v230, v231
	v_mfma_f32_16x16x32_bf16 v[6:9], v[152:155], v[164:167], v[148:151]
	global_store_dwordx2 v[94:95], v[34:35], off offset:128
	v_cvt_pk_bf16_f32 v34, v62, v63
	v_cvt_pk_bf16_f32 v35, v64, v65
	v_mfma_f32_16x16x32_bf16 v[2:5], v[152:155], v[168:171], v[2:5]
	global_store_dwordx2 v[92:93], v[98:99], off offset:32
	v_cvt_pk_bf16_f32 v98, v232, v233
	v_cvt_pk_bf16_f32 v99, v234, v235
	global_store_dwordx2 v[90:91], v[34:35], off offset:160
	v_cvt_pk_bf16_f32 v34, v54, v55
	v_cvt_pk_bf16_f32 v35, v56, v57
	global_store_dwordx2 v[96:97], v[98:99], off offset:32
	v_cvt_pk_bf16_f32 v98, v236, v237
	v_cvt_pk_bf16_f32 v99, v238, v239
	global_store_dwordx2 v[92:93], v[34:35], off offset:160
	v_cvt_pk_bf16_f32 v34, v46, v47
	v_cvt_pk_bf16_f32 v35, v48, v49
	global_store_dwordx2 v[94:95], v[98:99], off offset:32
	v_cvt_pk_bf16_f32 v98, v240, v241
	v_cvt_pk_bf16_f32 v99, v242, v243
	v_cvt_pk_bf16_f32 v58, v58, v59
	v_cvt_pk_bf16_f32 v59, v60, v61
	global_store_dwordx2 v[96:97], v[34:35], off offset:160
	v_cvt_pk_bf16_f32 v34, v38, v39
	v_cvt_pk_bf16_f32 v35, v40, v41
	v_cvt_pk_bf16_f32 v27, v28, v29
	v_cvt_pk_bf16_f32 v22, v22, v23
	v_cvt_pk_bf16_f32 v23, v24, v25
	v_cvt_pk_bf16_f32 v18, v18, v19
	v_cvt_pk_bf16_f32 v19, v20, v21
	v_cvt_pk_bf16_f32 v14, v14, v15
	v_cvt_pk_bf16_f32 v15, v16, v17
	v_cvt_pk_bf16_f32 v10, v10, v11
	v_cvt_pk_bf16_f32 v11, v12, v13
	v_cvt_pk_bf16_f32 v6, v6, v7
	v_cvt_pk_bf16_f32 v7, v8, v9
	v_cvt_pk_bf16_f32 v2, v2, v3
	v_cvt_pk_bf16_f32 v3, v4, v5
	global_store_dwordx2 v[90:91], v[98:99], off offset:64
	global_store_dwordx2 v[92:93], v[82:83], off offset:64
	global_store_dwordx2 v[96:97], v[74:75], off offset:64
	global_store_dwordx2 v[94:95], v[66:67], off offset:64
	global_store_dwordx2 v[90:91], v[58:59], off offset:96
	global_store_dwordx2 v[92:93], v[50:51], off offset:96
	global_store_dwordx2 v[96:97], v[42:43], off offset:96
	global_store_dwordx2 v[94:95], v[34:35], off offset:160
	global_store_dwordx2 v[90:91], v[30:31], off offset:192
	global_store_dwordx2 v[92:93], v[26:27], off offset:192
	global_store_dwordx2 v[96:97], v[22:23], off offset:192
	global_store_dwordx2 v[94:95], v[18:19], off offset:192
	global_store_dwordx2 v[90:91], v[14:15], off offset:224
	global_store_dwordx2 v[92:93], v[10:11], off offset:224
	global_store_dwordx2 v[96:97], v[6:7], off offset:224
	global_store_dwordx2 v[94:95], v[2:3], off offset:224

; template <int N> DI void wait_vm() { asm volatile("s_waitcnt vmcnt(%0)" ::"n"(N) : "memory"); }
; template <int BM, class Epi>
; DI void gemm_dma(const u16* __restrict__ X, long ldx, const u16* __restrict__ W, long ldw, int K, char* smem,
;                  int m0, int n0, const Epi& epi) {
;     ...
;   const int wu = __builtin_amdgcn_readfirstlane(wave);
;   const unsigned sbase = (unsigned)__builtin_amdgcn_readfirstlane((int)(unsigned)(size_t)smem);
;   const int r16 = lane >> 2, chunk = (lane & 3) ^ ((4 - (r16 >> 2)) & 3);
;   const u16* xs = X + (long)(wu * XD * 16 + r16) * ldx + (chunk << 3);
;   const u16* ws = W + (long)(wu * 32 + r16) * ldw + (chunk << 3);
;   const long ldx16 = 16 * ldx, ldw16 = 16 * ldw;
;   const unsigned xdst = sbase + wu * XD * 1024, wdst = sbase + BM * 64 + wu * 2048;
;     ...
;   const int nk = K >> 5;
;   __syncthreads();
; #pragma unroll
;   for (int s = 0; s < D - 1; ++s) GD_ISSUE(s)
;   int cur = 0, nxt = D - 1, kt = 0;
;   do {
;     if (kt + D - 2 < nk) wait_vm<PW * (D - 2)>(); else wait_vm<0>();
;     __syncthreads();
;     if (kt + D - 1 < nk) GD_ISSUE(nxt)
;     nxt = (nxt + 1 == D) ? 0 : nxt + 1;
;     const char* base = smem + cur * STG;
;     cur = (cur + 1 == D) ? 0 : cur + 1;
;     bf16x8 xf[MT];
; #pragma unroll
;     for (int i = 0; i < MT; ++i) xf[i] = *(const bf16x8*)(base + (xrow0 + i * 16) * 64 + rd);
; #pragma unroll
;     for (int nh = 0; nh < NT / 4; ++nh) {
;       bf16x8 wf[4];
; #pragma unroll
;       for (int i = 0; i < 4; ++i) wf[i] = *(const bf16x8*)(base + BM * 64 + (wrow0 + (nh * 4 + i) * 16) * 64 + rd);
; DI void knope_tile(const Params& p, int u, char* smem) {
;   const u16* W = (const u16*)(p.ws + OFF_W);
;   const u16* ckvb = (const u16*)(p.ws + OFF_CKVB);
;   EpiBF16 ek{(u16*)(p.ws + OFF_KN), 1024};
;   const int tm = u >> 3, tn = u & 7;
;   gemm_dma<256>(ckvb + (size_t)tm * 256 * 256, 256, W + WO_KV + (size_t)tn * 128 * 256, 256, 256, smem, tm * 256, tn * 128, ek);
; }
.LBB0_99:
	s_cmpk_gt_i32 s5, 0x62f
	s_mov_b64 s[38:39], -1
	s_cbranch_scc0 .LBB0_101
	s_add_i32 s4, s5, 0xfffff9d0
	s_bfe_u32 s98, s4, 0x30003
	s_and_b32 s99, s4, 7
	s_lshl_b32 s99, s99, 3
	s_andn2_b32 s4, s4, 63
	s_or_b32 s4, s4, s99
	s_or_b32 s4, s4, s98
	s_lshr_b32 s6, s4, 3
	s_and_b32 s4, s4, 7
	s_lshl_b32 s7, s6, 17
	s_add_u32 s8, s0, s7
	s_addc_u32 s9, s1, 0
	s_lshl_b32 s7, s4, 16
	v_mov_b32_e32 v11, v185
	s_add_u32 s10, s87, s7
	s_addc_u32 s11, s90, 0
	v_readfirstlane_b32 s7, v11
	v_lshrrev_b32_e32 v6, 4, v11
	s_ashr_i32 s12, s7, 6
	v_bfe_u32 v8, v11, 2, 4
	v_sub_u32_e32 v6, 0, v6
	s_andn2_b32 s7, s7, 63
	v_lshrrev_b32_e32 v3, 2, v11
	v_xor_b32_e32 v9, v11, v6
	v_or_b32_e32 v6, s7, v8
	v_and_b32_e32 v90, 15, v11
	v_bfe_u32 v1, v11, 4, 2
	v_sub_u32_e32 v3, 0, v3
	v_ashrrev_i32_e32 v7, 31, v6
	v_lshlrev_b32_e32 v2, 6, v90
	v_bitop3_b32 v3, v1, v3, 3 bitop3:0x78
	v_lshlrev_b64 v[6:7], 9, v[6:7]
	v_lshlrev_b32_e32 v9, 4, v9
	v_lshl_or_b32 v8, s12, 5, v8
	v_lshl_or_b32 v10, v3, 4, v2
	v_mov_b32_e32 v2, v183
	v_lshl_add_u64 v[6:7], s[8:9], 0, v[6:7]
	v_and_b32_e32 v182, 48, v9
	v_ashrrev_i32_e32 v9, 31, v8
	v_lshl_add_u64 v[6:7], v[6:7], 0, v[182:183]
	v_lshlrev_b64 v[8:9], 9, v[8:9]
	s_lshl_b32 s14, s12, 12
	s_barrier
	s_mov_b32 m0, s14
	s_nop 0
	global_load_lds_dwordx4 v[6:7], off
	s_mov_b64 s[8:9], 0x2000
	v_lshl_add_u64 v[8:9], s[10:11], 0, v[8:9]
	v_lshl_add_u64 v[12:13], v[6:7], 0, s[8:9]
	s_or_b32 s15, s14, 0x400
	s_mov_b32 m0, s15
	s_nop 0
	global_load_lds_dwordx4 v[12:13], off
	s_mov_b64 s[10:11], 0x4000
	v_lshl_add_u64 v[12:13], v[6:7], 0, s[10:11]
	s_or_b32 s16, s14, 0x800
	s_mov_b32 m0, s16
	s_nop 0
	global_load_lds_dwordx4 v[12:13], off
	s_mov_b64 s[10:11], 0x6000
	s_lshl_b32 s42, s12, 11
	v_lshl_add_u64 v[12:13], v[6:7], 0, s[10:11]
	s_or_b32 s17, s14, 0xc00
	s_mov_b32 m0, s17
	s_nop 0
	global_load_lds_dwordx4 v[12:13], off
	v_lshl_add_u64 v[8:9], v[8:9], 0, v[182:183]
	s_add_i32 s13, s42, 0x4000
	s_mov_b32 m0, s13
	s_nop 0
	global_load_lds_dwordx4 v[8:9], off
	v_lshl_add_u64 v[12:13], v[8:9], 0, s[8:9]
	s_add_i32 s18, s42, 0x4400
	s_mov_b32 m0, s18
	s_nop 0
	global_load_lds_dwordx4 v[12:13], off
	v_lshl_add_u64 v[12:13], v[6:7], 0, 64
	s_add_i32 s7, s14, 0x6000
	s_mov_b32 m0, s7
	s_nop 0
	global_load_lds_dwordx4 v[12:13], off
	s_mov_b64 s[20:21], 0x2040
	v_lshl_add_u64 v[12:13], v[6:7], 0, s[20:21]
	s_add_i32 s8, s14, 0x6400
	s_mov_b32 m0, s8
	s_nop 0
	global_load_lds_dwordx4 v[12:13], off
	s_mov_b64 s[10:11], 0x4040
	v_lshl_add_u64 v[12:13], v[6:7], 0, s[10:11]
	s_add_i32 s9, s14, 0x6800
	s_mov_b32 m0, s9
	s_nop 0
	global_load_lds_dwordx4 v[12:13], off
	s_mov_b64 s[10:11], 0x6040
	v_lshl_add_u64 v[12:13], v[6:7], 0, s[10:11]
	s_add_i32 s10, s14, 0x6c00
	s_mov_b32 m0, s10
	s_nop 0
	global_load_lds_dwordx4 v[12:13], off
	v_lshl_add_u64 v[14:15], v[8:9], 0, 64
	s_add_i32 s11, s42, 0xa000
	s_mov_b32 m0, s11
	s_nop 0
	global_load_lds_dwordx4 v[14:15], off
	v_lshl_add_u64 v[12:13], v[8:9], 0, s[20:21]
	s_add_i32 s12, s42, 0xa400
	s_mov_b32 m0, s12
	s_nop 0
	global_load_lds_dwordx4 v[12:13], off
	s_waitcnt vmcnt(6)
	s_barrier
	v_lshl_add_u64 v[14:15], v[6:7], 0, s[28:29]
	s_add_i32 s19, s14, 0xc000
	s_mov_b32 m0, s19
	s_nop 0
	global_load_lds_dwordx4 v[14:15], off
	s_mov_b64 s[20:21], 0x2080
	v_lshl_add_u64 v[14:15], v[6:7], 0, s[20:21]
	s_add_i32 s34, s14, 0xc400
	s_mov_b32 m0, s34
	s_nop 0
	global_load_lds_dwordx4 v[14:15], off
	v_lshl_add_u64 v[14:15], v[6:7], 0, s[94:95]
	s_add_i32 s38, s14, 0xc800
	s_mov_b32 m0, s38
	s_nop 0
	global_load_lds_dwordx4 v[14:15], off
	s_mov_b64 s[22:23], 0x6080
	v_lshl_add_u64 v[14:15], v[6:7], 0, s[22:23]
	s_add_i32 s43, s14, 0xcc00
	s_mov_b32 m0, s43
	s_nop 0
	global_load_lds_dwordx4 v[14:15], off
	v_and_b32_e32 v91, 0xffffffc0, v11
	v_lshl_add_u64 v[12:13], v[8:9], 0, s[28:29]
	s_add_i32 s39, s42, 0x10000
	s_mov_b32 m0, s39
	s_nop 0
	global_load_lds_dwordx4 v[12:13], off
	v_lshl_add_u64 v[12:13], v[8:9], 0, s[20:21]
	s_add_i32 s42, s42, 0x10400
	s_mov_b32 m0, s42
	s_nop 0
	global_load_lds_dwordx4 v[12:13], off
	v_lshl_or_b32 v11, v91, 6, v10
	ds_read_b128 v[12:15], v11
	s_waitcnt vmcnt(7)
	ds_read_b128 v[16:19], v11 offset:1024
	s_waitcnt vmcnt(5)
	ds_read_b128 v[20:23], v11 offset:2048
	ds_read_b128 v[24:27], v11 offset:3072
	s_waitcnt vmcnt(4)
	ds_read_b128 v[28:31], v10 offset:16384
	ds_read_b128 v[32:35], v10 offset:17408
	ds_read_b128 v[36:39], v10 offset:18432
	ds_read_b128 v[40:43], v10 offset:19456
	s_waitcnt vmcnt(0)
	ds_read_b128 v[96:99], v10 offset:20480
	ds_read_b128 v[100:103], v10 offset:21504
	ds_read_b128 v[104:107], v10 offset:22528
	ds_read_b128 v[108:111], v10 offset:23552
	s_mov_b64 s[20:21], 0xc0
	v_mov_b32_e32 v3, v2
	v_mov_b32_e32 v4, v2
	v_mov_b32_e32 v5, v2
	v_lshl_add_u64 v[88:89], v[6:7], 0, s[20:21]
	v_lshl_add_u64 v[148:149], v[8:9], 0, s[20:21]
	s_waitcnt vmcnt(6)
	s_waitcnt lgkmcnt(0)
	s_barrier
; template <int N> DI void wait_vm() { asm volatile("s_waitcnt vmcnt(%0)" ::"n"(N) : "memory"); }
; template <int BM, class Epi>
; DI void gemm_dma(const u16* __restrict__ X, long ldx, const u16* __restrict__ W, long ldw, int K, char* smem,
;                  int m0, int n0, const Epi& epi) {
;     ...
;   do {
;     if (kt + D - 2 < nk) wait_vm<PW * (D - 2)>(); else wait_vm<0>();
;     __syncthreads();
;     if (kt + D - 1 < nk) GD_ISSUE(nxt)
;     nxt = (nxt + 1 == D) ? 0 : nxt + 1;
;     const char* base = smem + cur * STG;
;     cur = (cur + 1 == D) ? 0 : cur + 1;
;     bf16x8 xf[MT];
; #pragma unroll
;     for (int i = 0; i < MT; ++i) xf[i] = *(const bf16x8*)(base + (xrow0 + i * 16) * 64 + rd);
; #pragma unroll
;     for (int nh = 0; nh < NT / 4; ++nh) {
;       bf16x8 wf[4];
; #pragma unroll
;       for (int i = 0; i < 4; ++i) wf[i] = *(const bf16x8*)(base + BM * 64 + (wrow0 + (nh * 4 + i) * 16) * 64 + rd);
; #pragma unroll
;       for (int i = 0; i < 4; ++i)
; #pragma unroll
;         for (int mt = 0; mt < MT; ++mt)
;           acc[nh * 4 + i][mt] = __builtin_amdgcn_mfma_f32_16x16x32_bf16(wf[i], xf[mt], acc[nh * 4 + i][mt], 0, 0, 0);
	s_mov_b32 m0, s14
	s_nop 0
	global_load_lds_dwordx4 v[88:89], off
	s_mov_b64 s[20:21], 0x20c0
	v_mfma_f32_16x16x32_bf16 v[44:47], v[28:31], v[12:15], v[2:5]
	s_mov_b64 s[22:23], 0x40c0
	v_or_b32_e32 v174, 0x10000, v10
	v_or_b32_e32 v175, 0x10400, v10
	v_mfma_f32_16x16x32_bf16 v[48:51], v[28:31], v[16:19], v[2:5]
	v_or_b32_e32 v176, 0x10800, v10
	v_or_b32_e32 v177, 0x10c00, v10
	v_or_b32_e32 v178, 0x11000, v10
	v_mfma_f32_16x16x32_bf16 v[52:55], v[28:31], v[20:23], v[2:5]
	v_or_b32_e32 v179, 0x11400, v10
	v_or_b32_e32 v180, 0x11800, v10
	v_or_b32_e32 v181, 0x11c00, v10
	v_mfma_f32_16x16x32_bf16 v[28:31], v[28:31], v[24:27], v[2:5]
	v_lshl_add_u32 v91, s6, 8, v91
	s_lshl_b32 s4, s4, 8
	v_lshl_or_b32 v182, v1, 3, s4
	v_mfma_f32_16x16x32_bf16 v[56:59], v[32:35], v[12:15], v[2:5]
	v_mfma_f32_16x16x32_bf16 v[60:63], v[32:35], v[16:19], v[2:5]
	v_mfma_f32_16x16x32_bf16 v[64:67], v[32:35], v[20:23], v[2:5]
	v_mfma_f32_16x16x32_bf16 v[32:35], v[32:35], v[24:27], v[2:5]
	v_mfma_f32_16x16x32_bf16 v[68:71], v[36:39], v[12:15], v[2:5]
	v_mfma_f32_16x16x32_bf16 v[72:75], v[36:39], v[16:19], v[2:5]
	v_mfma_f32_16x16x32_bf16 v[76:79], v[36:39], v[20:23], v[2:5]
	v_mfma_f32_16x16x32_bf16 v[36:39], v[36:39], v[24:27], v[2:5]
	v_mfma_f32_16x16x32_bf16 v[80:83], v[40:43], v[12:15], v[2:5]
	v_mfma_f32_16x16x32_bf16 v[84:87], v[40:43], v[16:19], v[2:5]
	v_mfma_f32_16x16x32_bf16 v[92:95], v[40:43], v[20:23], v[2:5]
	v_mfma_f32_16x16x32_bf16 v[40:43], v[40:43], v[24:27], v[2:5]
	v_mfma_f32_16x16x32_bf16 v[112:115], v[96:99], v[12:15], v[2:5]
	v_mfma_f32_16x16x32_bf16 v[116:119], v[96:99], v[16:19], v[2:5]
	v_mfma_f32_16x16x32_bf16 v[120:123], v[96:99], v[20:23], v[2:5]
	v_mfma_f32_16x16x32_bf16 v[96:99], v[96:99], v[24:27], v[2:5]
	v_mfma_f32_16x16x32_bf16 v[124:127], v[100:103], v[12:15], v[2:5]
	v_mfma_f32_16x16x32_bf16 v[128:131], v[100:103], v[16:19], v[2:5]
	v_mfma_f32_16x16x32_bf16 v[132:135], v[100:103], v[20:23], v[2:5]
	v_mfma_f32_16x16x32_bf16 v[100:103], v[100:103], v[24:27], v[2:5]
	v_mfma_f32_16x16x32_bf16 v[136:139], v[104:107], v[12:15], v[2:5]
	v_mfma_f32_16x16x32_bf16 v[140:143], v[104:107], v[16:19], v[2:5]
	v_mfma_f32_16x16x32_bf16 v[144:147], v[104:107], v[20:23], v[2:5]
	v_mfma_f32_16x16x32_bf16 v[104:107], v[104:107], v[24:27], v[2:5]
	v_mfma_f32_16x16x32_bf16 v[12:15], v[108:111], v[12:15], v[2:5]
	v_mfma_f32_16x16x32_bf16 v[16:19], v[108:111], v[16:19], v[2:5]
	v_mfma_f32_16x16x32_bf16 v[20:23], v[108:111], v[20:23], v[2:5]
	v_mfma_f32_16x16x32_bf16 v[2:5], v[108:111], v[24:27], v[2:5]
	v_lshl_add_u64 v[24:25], v[6:7], 0, s[20:21]
	s_mov_b32 m0, s15
	s_nop 0
	global_load_lds_dwordx4 v[24:25], off
	v_lshl_add_u64 v[24:25], v[6:7], 0, s[22:23]
	s_mov_b32 m0, s16
	s_nop 0
	global_load_lds_dwordx4 v[24:25], off
	s_mov_b64 s[22:23], 0x60c0
	v_lshl_add_u64 v[24:25], v[6:7], 0, s[22:23]
	s_mov_b32 m0, s17
	s_nop 0
	global_load_lds_dwordx4 v[24:25], off
	v_lshl_add_u64 v[24:25], v[8:9], 0, s[20:21]
	s_mov_b32 m0, s13
	s_nop 0
	global_load_lds_dwordx4 v[148:149], off
	s_mov_b64 s[20:21], 0x100
	s_mov_b32 m0, s18
	s_nop 0
	global_load_lds_dwordx4 v[24:25], off
	ds_read_b128 v[24:27], v11 offset:24576
	ds_read_b128 v[108:111], v11 offset:25600
	ds_read_b128 v[148:151], v11 offset:26624
	ds_read_b128 v[152:155], v11 offset:27648
	ds_read_b128 v[156:159], v10 offset:40960
	ds_read_b128 v[160:163], v10 offset:41984
	ds_read_b128 v[164:167], v10 offset:43008
	ds_read_b128 v[168:171], v10 offset:44032
	s_waitcnt lgkmcnt(3)
	v_mfma_f32_16x16x32_bf16 v[44:47], v[156:159], v[24:27], v[44:47]
	v_lshl_add_u64 v[88:89], v[6:7], 0, s[20:21]
	v_lshl_add_u64 v[172:173], v[8:9], 0, s[20:21]
	s_mov_b64 s[20:21], 0x2100
	v_mfma_f32_16x16x32_bf16 v[48:51], v[156:159], v[108:111], v[48:51]
	s_mov_b64 s[22:23], 0x4100
	v_mfma_f32_16x16x32_bf16 v[52:55], v[156:159], v[148:151], v[52:55]
	v_mfma_f32_16x16x32_bf16 v[28:31], v[156:159], v[152:155], v[28:31]
	s_waitcnt lgkmcnt(2)
	v_mfma_f32_16x16x32_bf16 v[56:59], v[160:163], v[24:27], v[56:59]
	v_mfma_f32_16x16x32_bf16 v[60:63], v[160:163], v[108:111], v[60:63]
	v_mfma_f32_16x16x32_bf16 v[64:67], v[160:163], v[148:151], v[64:67]
	v_mfma_f32_16x16x32_bf16 v[32:35], v[160:163], v[152:155], v[32:35]
	s_waitcnt lgkmcnt(1)
	v_mfma_f32_16x16x32_bf16 v[68:71], v[164:167], v[24:27], v[68:71]
	v_mfma_f32_16x16x32_bf16 v[72:75], v[164:167], v[108:111], v[72:75]
	v_mfma_f32_16x16x32_bf16 v[76:79], v[164:167], v[148:151], v[76:79]
	v_mfma_f32_16x16x32_bf16 v[36:39], v[164:167], v[152:155], v[36:39]
	s_waitcnt lgkmcnt(0)
	v_mfma_f32_16x16x32_bf16 v[80:83], v[168:171], v[24:27], v[80:83]
	v_mfma_f32_16x16x32_bf16 v[84:87], v[168:171], v[108:111], v[84:87]
	v_mfma_f32_16x16x32_bf16 v[92:95], v[168:171], v[148:151], v[92:95]
	v_mfma_f32_16x16x32_bf16 v[40:43], v[168:171], v[152:155], v[40:43]
	ds_read_b128 v[156:159], v10 offset:45056
	ds_read_b128 v[160:163], v10 offset:46080
	ds_read_b128 v[164:167], v10 offset:47104
	ds_read_b128 v[168:171], v10 offset:48128
	s_waitcnt vmcnt(6)
	s_waitcnt lgkmcnt(0)
	s_barrier
; template <int N> DI void wait_vm() { asm volatile("s_waitcnt vmcnt(%0)" ::"n"(N) : "memory"); }
; template <int BM, class Epi>
; DI void gemm_dma(const u16* __restrict__ X, long ldx, const u16* __restrict__ W, long ldw, int K, char* smem,
;                  int m0, int n0, const Epi& epi) {
;     ...
;   do {
;     if (kt + D - 2 < nk) wait_vm<PW * (D - 2)>(); else wait_vm<0>();
;     __syncthreads();
;     if (kt + D - 1 < nk) GD_ISSUE(nxt)
;     nxt = (nxt + 1 == D) ? 0 : nxt + 1;
;     const char* base = smem + cur * STG;
;     cur = (cur + 1 == D) ? 0 : cur + 1;
;     bf16x8 xf[MT];
; #pragma unroll
;     for (int i = 0; i < MT; ++i) xf[i] = *(const bf16x8*)(base + (xrow0 + i * 16) * 64 + rd);
; #pragma unroll
;     for (int nh = 0; nh < NT / 4; ++nh) {
;       bf16x8 wf[4];
; #pragma unroll
;       for (int i = 0; i < 4; ++i) wf[i] = *(const bf16x8*)(base + BM * 64 + (wrow0 + (nh * 4 + i) * 16) * 64 + rd);
; #pragma unroll
;       for (int i = 0; i < 4; ++i)
; #pragma unroll
;         for (int mt = 0; mt < MT; ++mt)
;           acc[nh * 4 + i][mt] = __builtin_amdgcn_mfma_f32_16x16x32_bf16(wf[i], xf[mt], acc[nh * 4 + i][mt], 0, 0, 0);
	s_mov_b32 m0, s7
	s_nop 0
	global_load_lds_dwordx4 v[88:89], off
	v_mfma_f32_16x16x32_bf16 v[112:115], v[156:159], v[24:27], v[112:115]
	v_mfma_f32_16x16x32_bf16 v[124:127], v[160:163], v[24:27], v[124:127]
	v_mfma_f32_16x16x32_bf16 v[136:139], v[164:167], v[24:27], v[136:139]
	v_mfma_f32_16x16x32_bf16 v[12:15], v[168:171], v[24:27], v[12:15]
	v_lshl_add_u64 v[24:25], v[6:7], 0, s[20:21]
	s_mov_b32 m0, s8
	s_nop 0
	global_load_lds_dwordx4 v[24:25], off
	v_lshl_add_u64 v[24:25], v[6:7], 0, s[22:23]
	s_mov_b32 m0, s9
	s_nop 0
	global_load_lds_dwordx4 v[24:25], off
	s_mov_b64 s[22:23], 0x6100
	v_lshl_add_u64 v[24:25], v[6:7], 0, s[22:23]
	s_mov_b32 m0, s10
	s_nop 0
	global_load_lds_dwordx4 v[24:25], off
	v_lshl_add_u64 v[24:25], v[8:9], 0, s[20:21]
	s_mov_b32 m0, s11
	s_nop 0
	global_load_lds_dwordx4 v[172:173], off
	v_mfma_f32_16x16x32_bf16 v[116:119], v[156:159], v[108:111], v[116:119]
	s_mov_b32 m0, s12
	s_nop 0
	global_load_lds_dwordx4 v[24:25], off
	s_mov_b64 s[20:21], 0x140
	v_lshl_add_u64 v[88:89], v[6:7], 0, s[20:21]
	v_mfma_f32_16x16x32_bf16 v[120:123], v[156:159], v[148:151], v[120:123]
	v_lshl_add_u64 v[172:173], v[8:9], 0, s[20:21]
	s_mov_b64 s[20:21], 0x2140
	s_mov_b64 s[22:23], 0x4140
	v_mfma_f32_16x16x32_bf16 v[96:99], v[156:159], v[152:155], v[96:99]
	v_mfma_f32_16x16x32_bf16 v[128:131], v[160:163], v[108:111], v[128:131]
	v_mfma_f32_16x16x32_bf16 v[132:135], v[160:163], v[148:151], v[132:135]
	v_mfma_f32_16x16x32_bf16 v[100:103], v[160:163], v[152:155], v[100:103]
	v_mfma_f32_16x16x32_bf16 v[140:143], v[164:167], v[108:111], v[140:143]
	v_mfma_f32_16x16x32_bf16 v[144:147], v[164:167], v[148:151], v[144:147]
	v_mfma_f32_16x16x32_bf16 v[104:107], v[164:167], v[152:155], v[104:107]
	v_mfma_f32_16x16x32_bf16 v[16:19], v[168:171], v[108:111], v[16:19]
	v_mfma_f32_16x16x32_bf16 v[20:23], v[168:171], v[148:151], v[20:23]
	v_mfma_f32_16x16x32_bf16 v[2:5], v[168:171], v[152:155], v[2:5]
	ds_read_b128 v[24:27], v11 offset:49152
	ds_read_b128 v[108:111], v11 offset:50176
	ds_read_b128 v[148:151], v11 offset:51200
	ds_read_b128 v[152:155], v11 offset:52224
	ds_read_b128 v[156:159], v174
	ds_read_b128 v[160:163], v175
	ds_read_b128 v[164:167], v176
	ds_read_b128 v[168:171], v177
	s_waitcnt lgkmcnt(3)
	v_mfma_f32_16x16x32_bf16 v[44:47], v[156:159], v[24:27], v[44:47]
	v_mfma_f32_16x16x32_bf16 v[48:51], v[156:159], v[108:111], v[48:51]
	v_mfma_f32_16x16x32_bf16 v[52:55], v[156:159], v[148:151], v[52:55]
	v_mfma_f32_16x16x32_bf16 v[28:31], v[156:159], v[152:155], v[28:31]
	ds_read_b128 v[156:159], v178
	s_waitcnt lgkmcnt(3)
	v_mfma_f32_16x16x32_bf16 v[56:59], v[160:163], v[24:27], v[56:59]
	v_mfma_f32_16x16x32_bf16 v[60:63], v[160:163], v[108:111], v[60:63]
	v_mfma_f32_16x16x32_bf16 v[64:67], v[160:163], v[148:151], v[64:67]
	v_mfma_f32_16x16x32_bf16 v[32:35], v[160:163], v[152:155], v[32:35]
	ds_read_b128 v[160:163], v179
	s_waitcnt lgkmcnt(3)
	v_mfma_f32_16x16x32_bf16 v[68:71], v[164:167], v[24:27], v[68:71]
	v_mfma_f32_16x16x32_bf16 v[72:75], v[164:167], v[108:111], v[72:75]
	v_mfma_f32_16x16x32_bf16 v[76:79], v[164:167], v[148:151], v[76:79]
	v_mfma_f32_16x16x32_bf16 v[36:39], v[164:167], v[152:155], v[36:39]
	ds_read_b128 v[164:167], v180
	s_waitcnt lgkmcnt(3)
	v_mfma_f32_16x16x32_bf16 v[80:83], v[168:171], v[24:27], v[80:83]
	v_mfma_f32_16x16x32_bf16 v[84:87], v[168:171], v[108:111], v[84:87]
	v_mfma_f32_16x16x32_bf16 v[92:95], v[168:171], v[148:151], v[92:95]
	v_mfma_f32_16x16x32_bf16 v[40:43], v[168:171], v[152:155], v[40:43]
	ds_read_b128 v[168:171], v181
	s_waitcnt vmcnt(6)
	s_waitcnt lgkmcnt(0)
	s_barrier
	s_mov_b32 m0, s19
	s_nop 0
	global_load_lds_dwordx4 v[88:89], off
	v_mfma_f32_16x16x32_bf16 v[112:115], v[156:159], v[24:27], v[112:115]
	v_mfma_f32_16x16x32_bf16 v[124:127], v[160:163], v[24:27], v[124:127]
	v_mfma_f32_16x16x32_bf16 v[136:139], v[164:167], v[24:27], v[136:139]
	v_mfma_f32_16x16x32_bf16 v[12:15], v[168:171], v[24:27], v[12:15]
	v_lshl_add_u64 v[24:25], v[6:7], 0, s[20:21]
	s_mov_b32 m0, s34
	s_nop 0
	global_load_lds_dwordx4 v[24:25], off
	v_lshl_add_u64 v[24:25], v[6:7], 0, s[22:23]
	s_mov_b32 m0, s38
	s_nop 0
	global_load_lds_dwordx4 v[24:25], off
	s_mov_b64 s[22:23], 0x6140
	v_lshl_add_u64 v[24:25], v[6:7], 0, s[22:23]
	s_mov_b32 m0, s43
	s_nop 0
	global_load_lds_dwordx4 v[24:25], off
	v_lshl_add_u64 v[24:25], v[8:9], 0, s[20:21]
	s_mov_b32 m0, s39
	s_nop 0
	global_load_lds_dwordx4 v[172:173], off
	v_mfma_f32_16x16x32_bf16 v[116:119], v[156:159], v[108:111], v[116:119]
	s_mov_b32 m0, s42
	s_nop 0
	global_load_lds_dwordx4 v[24:25], off
	s_mov_b64 s[20:21], 0x180
	v_lshl_add_u64 v[88:89], v[6:7], 0, s[20:21]
	v_mfma_f32_16x16x32_bf16 v[120:123], v[156:159], v[148:151], v[120:123]
	v_lshl_add_u64 v[172:173], v[8:9], 0, s[20:21]
	s_mov_b64 s[20:21], 0x2180
	s_mov_b64 s[38:39], 0
	v_mfma_f32_16x16x32_bf16 v[96:99], v[156:159], v[152:155], v[96:99]
	v_mfma_f32_16x16x32_bf16 v[128:131], v[160:163], v[108:111], v[128:131]
	v_mfma_f32_16x16x32_bf16 v[132:135], v[160:163], v[148:151], v[132:135]
	v_mfma_f32_16x16x32_bf16 v[100:103], v[160:163], v[152:155], v[100:103]
	v_mfma_f32_16x16x32_bf16 v[140:143], v[164:167], v[108:111], v[140:143]
	v_mfma_f32_16x16x32_bf16 v[144:147], v[164:167], v[148:151], v[144:147]
	v_mfma_f32_16x16x32_bf16 v[104:107], v[164:167], v[152:155], v[104:107]
	v_mfma_f32_16x16x32_bf16 v[16:19], v[168:171], v[108:111], v[16:19]
	v_mfma_f32_16x16x32_bf16 v[20:23], v[168:171], v[148:151], v[20:23]
	v_mfma_f32_16x16x32_bf16 v[2:5], v[168:171], v[152:155], v[2:5]
	ds_read_b128 v[24:27], v11
	ds_read_b128 v[108:111], v11 offset:1024
	ds_read_b128 v[148:151], v11 offset:2048
	ds_read_b128 v[152:155], v11 offset:3072
	ds_read_b128 v[156:159], v10 offset:16384
	ds_read_b128 v[160:163], v10 offset:17408
	ds_read_b128 v[164:167], v10 offset:18432
	ds_read_b128 v[168:171], v10 offset:19456
	s_waitcnt lgkmcnt(3)
; template <int N> DI void wait_vm() { asm volatile("s_waitcnt vmcnt(%0)" ::"n"(N) : "memory"); }
; template <int BM, class Epi>
; DI void gemm_dma(const u16* __restrict__ X, long ldx, const u16* __restrict__ W, long ldw, int K, char* smem,
;                  int m0, int n0, const Epi& epi) {
;     ...
;   do {
;     if (kt + D - 2 < nk) wait_vm<PW * (D - 2)>(); else wait_vm<0>();
;     __syncthreads();
;     if (kt + D - 1 < nk) GD_ISSUE(nxt)
;     nxt = (nxt + 1 == D) ? 0 : nxt + 1;
;     const char* base = smem + cur * STG;
;     cur = (cur + 1 == D) ? 0 : cur + 1;
;     bf16x8 xf[MT];
; #pragma unroll
;     for (int i = 0; i < MT; ++i) xf[i] = *(const bf16x8*)(base + (xrow0 + i * 16) * 64 + rd);
; #pragma unroll
;     for (int nh = 0; nh < NT / 4; ++nh) {
;       bf16x8 wf[4];
; #pragma unroll
;       for (int i = 0; i < 4; ++i) wf[i] = *(const bf16x8*)(base + BM * 64 + (wrow0 + (nh * 4 + i) * 16) * 64 + rd);
; #pragma unroll
;       for (int i = 0; i < 4; ++i)
; #pragma unroll
;         for (int mt = 0; mt < MT; ++mt)
;           acc[nh * 4 + i][mt] = __builtin_amdgcn_mfma_f32_16x16x32_bf16(wf[i], xf[mt], acc[nh * 4 + i][mt], 0, 0, 0);
	v_mfma_f32_16x16x32_bf16 v[44:47], v[156:159], v[24:27], v[44:47]
	v_mfma_f32_16x16x32_bf16 v[48:51], v[156:159], v[108:111], v[48:51]
	v_mfma_f32_16x16x32_bf16 v[52:55], v[156:159], v[148:151], v[52:55]
	v_mfma_f32_16x16x32_bf16 v[28:31], v[156:159], v[152:155], v[28:31]
	s_waitcnt lgkmcnt(2)
	v_mfma_f32_16x16x32_bf16 v[56:59], v[160:163], v[24:27], v[56:59]
	v_mfma_f32_16x16x32_bf16 v[60:63], v[160:163], v[108:111], v[60:63]
	v_mfma_f32_16x16x32_bf16 v[64:67], v[160:163], v[148:151], v[64:67]
	v_mfma_f32_16x16x32_bf16 v[32:35], v[160:163], v[152:155], v[32:35]
	s_waitcnt lgkmcnt(1)
	v_mfma_f32_16x16x32_bf16 v[68:71], v[164:167], v[24:27], v[68:71]
	v_mfma_f32_16x16x32_bf16 v[72:75], v[164:167], v[108:111], v[72:75]
	v_mfma_f32_16x16x32_bf16 v[76:79], v[164:167], v[148:151], v[76:79]
	v_mfma_f32_16x16x32_bf16 v[36:39], v[164:167], v[152:155], v[36:39]
	s_waitcnt lgkmcnt(0)
	v_mfma_f32_16x16x32_bf16 v[80:83], v[168:171], v[24:27], v[80:83]
	v_mfma_f32_16x16x32_bf16 v[84:87], v[168:171], v[108:111], v[84:87]
	v_mfma_f32_16x16x32_bf16 v[92:95], v[168:171], v[148:151], v[92:95]
	v_mfma_f32_16x16x32_bf16 v[40:43], v[168:171], v[152:155], v[40:43]
	ds_read_b128 v[156:159], v10 offset:20480
	ds_read_b128 v[160:163], v10 offset:21504
	ds_read_b128 v[164:167], v10 offset:22528
	ds_read_b128 v[168:171], v10 offset:23552
	s_waitcnt vmcnt(6)
	s_waitcnt lgkmcnt(0)
	s_barrier
	s_mov_b32 m0, s14
	s_nop 0
	global_load_lds_dwordx4 v[88:89], off
	v_mfma_f32_16x16x32_bf16 v[112:115], v[156:159], v[24:27], v[112:115]
	v_mfma_f32_16x16x32_bf16 v[124:127], v[160:163], v[24:27], v[124:127]
	v_mfma_f32_16x16x32_bf16 v[136:139], v[164:167], v[24:27], v[136:139]
	v_mfma_f32_16x16x32_bf16 v[12:15], v[168:171], v[24:27], v[12:15]
	v_lshl_add_u64 v[24:25], v[6:7], 0, s[20:21]
	s_mov_b32 m0, s15
	s_nop 0
	global_load_lds_dwordx4 v[24:25], off
	s_mov_b64 s[14:15], 0x4180
	v_lshl_add_u64 v[24:25], v[6:7], 0, s[14:15]
	s_mov_b32 m0, s16
	s_nop 0
	global_load_lds_dwordx4 v[24:25], off
	s_mov_b64 s[14:15], 0x6180
	v_lshl_add_u64 v[24:25], v[6:7], 0, s[14:15]
	s_mov_b32 m0, s17
	s_nop 0
	global_load_lds_dwordx4 v[24:25], off
	v_lshl_add_u64 v[24:25], v[8:9], 0, s[20:21]
	s_mov_b32 m0, s13
	s_nop 0
	global_load_lds_dwordx4 v[172:173], off
	s_mov_b32 m0, s18
	s_nop 0
	global_load_lds_dwordx4 v[24:25], off
	v_mfma_f32_16x16x32_bf16 v[116:119], v[156:159], v[108:111], v[116:119]
	s_mov_b64 s[14:15], 0x1c0
	v_lshl_add_u64 v[88:89], v[6:7], 0, s[14:15]
	v_lshl_add_u64 v[172:173], v[8:9], 0, s[14:15]
	v_mfma_f32_16x16x32_bf16 v[120:123], v[156:159], v[148:151], v[120:123]
	s_mov_b64 s[14:15], 0x21c0
	s_mov_b64 s[16:17], 0x41c0
	v_mfma_f32_16x16x32_bf16 v[96:99], v[156:159], v[152:155], v[96:99]
	v_mfma_f32_16x16x32_bf16 v[128:131], v[160:163], v[108:111], v[128:131]
	v_mfma_f32_16x16x32_bf16 v[132:135], v[160:163], v[148:151], v[132:135]
	v_mfma_f32_16x16x32_bf16 v[100:103], v[160:163], v[152:155], v[100:103]
	v_mfma_f32_16x16x32_bf16 v[140:143], v[164:167], v[108:111], v[140:143]
	v_mfma_f32_16x16x32_bf16 v[144:147], v[164:167], v[148:151], v[144:147]
	v_mfma_f32_16x16x32_bf16 v[104:107], v[164:167], v[152:155], v[104:107]
	v_mfma_f32_16x16x32_bf16 v[16:19], v[168:171], v[108:111], v[16:19]
	v_mfma_f32_16x16x32_bf16 v[20:23], v[168:171], v[148:151], v[20:23]
	v_mfma_f32_16x16x32_bf16 v[2:5], v[168:171], v[152:155], v[2:5]
	ds_read_b128 v[24:27], v11 offset:24576
	ds_read_b128 v[108:111], v11 offset:25600
	ds_read_b128 v[148:151], v11 offset:26624
	ds_read_b128 v[152:155], v11 offset:27648
	ds_read_b128 v[156:159], v10 offset:40960
	ds_read_b128 v[160:163], v10 offset:41984
	ds_read_b128 v[164:167], v10 offset:43008
	ds_read_b128 v[168:171], v10 offset:44032
	s_waitcnt lgkmcnt(3)
	v_mfma_f32_16x16x32_bf16 v[44:47], v[156:159], v[24:27], v[44:47]
	v_mfma_f32_16x16x32_bf16 v[48:51], v[156:159], v[108:111], v[48:51]
	v_mfma_f32_16x16x32_bf16 v[52:55], v[156:159], v[148:151], v[52:55]
	v_mfma_f32_16x16x32_bf16 v[28:31], v[156:159], v[152:155], v[28:31]
	s_waitcnt lgkmcnt(2)
	v_mfma_f32_16x16x32_bf16 v[56:59], v[160:163], v[24:27], v[56:59]
	v_mfma_f32_16x16x32_bf16 v[60:63], v[160:163], v[108:111], v[60:63]
	v_mfma_f32_16x16x32_bf16 v[64:67], v[160:163], v[148:151], v[64:67]
	v_mfma_f32_16x16x32_bf16 v[32:35], v[160:163], v[152:155], v[32:35]
	s_waitcnt lgkmcnt(1)
	v_mfma_f32_16x16x32_bf16 v[68:71], v[164:167], v[24:27], v[68:71]
	v_mfma_f32_16x16x32_bf16 v[72:75], v[164:167], v[108:111], v[72:75]
	v_mfma_f32_16x16x32_bf16 v[76:79], v[164:167], v[148:151], v[76:79]
	v_mfma_f32_16x16x32_bf16 v[36:39], v[164:167], v[152:155], v[36:39]
	s_waitcnt lgkmcnt(0)
	v_mfma_f32_16x16x32_bf16 v[80:83], v[168:171], v[24:27], v[80:83]
	v_mfma_f32_16x16x32_bf16 v[84:87], v[168:171], v[108:111], v[84:87]
	v_mfma_f32_16x16x32_bf16 v[92:95], v[168:171], v[148:151], v[92:95]
	v_mfma_f32_16x16x32_bf16 v[40:43], v[168:171], v[152:155], v[40:43]
	ds_read_b128 v[156:159], v10 offset:45056
	ds_read_b128 v[160:163], v10 offset:46080
	ds_read_b128 v[164:167], v10 offset:47104
	ds_read_b128 v[168:171], v10 offset:48128
	s_waitcnt vmcnt(6)
	s_waitcnt lgkmcnt(0)
	s_barrier
; template <int N> DI void wait_vm() { asm volatile("s_waitcnt vmcnt(%0)" ::"n"(N) : "memory"); }
; template <int BM, class Epi>
; DI void gemm_dma(const u16* __restrict__ X, long ldx, const u16* __restrict__ W, long ldw, int K, char* smem,
;                  int m0, int n0, const Epi& epi) {
;     ...
;   do {
;     if (kt + D - 2 < nk) wait_vm<PW * (D - 2)>(); else wait_vm<0>();
;     __syncthreads();
;     if (kt + D - 1 < nk) GD_ISSUE(nxt)
;     nxt = (nxt + 1 == D) ? 0 : nxt + 1;
;     const char* base = smem + cur * STG;
;     cur = (cur + 1 == D) ? 0 : cur + 1;
;     bf16x8 xf[MT];
; #pragma unroll
;     for (int i = 0; i < MT; ++i) xf[i] = *(const bf16x8*)(base + (xrow0 + i * 16) * 64 + rd);
; #pragma unroll
;     for (int nh = 0; nh < NT / 4; ++nh) {
;       bf16x8 wf[4];
; #pragma unroll
;       for (int i = 0; i < 4; ++i) wf[i] = *(const bf16x8*)(base + BM * 64 + (wrow0 + (nh * 4 + i) * 16) * 64 + rd);
; #pragma unroll
;       for (int i = 0; i < 4; ++i)
; #pragma unroll
;         for (int mt = 0; mt < MT; ++mt)
;           acc[nh * 4 + i][mt] = __builtin_amdgcn_mfma_f32_16x16x32_bf16(wf[i], xf[mt], acc[nh * 4 + i][mt], 0, 0, 0);
	s_mov_b32 m0, s7
	s_nop 0
	global_load_lds_dwordx4 v[88:89], off
	v_mfma_f32_16x16x32_bf16 v[112:115], v[156:159], v[24:27], v[112:115]
	v_mfma_f32_16x16x32_bf16 v[124:127], v[160:163], v[24:27], v[124:127]
	v_mfma_f32_16x16x32_bf16 v[136:139], v[164:167], v[24:27], v[136:139]
	v_mfma_f32_16x16x32_bf16 v[12:15], v[168:171], v[24:27], v[12:15]
	v_lshl_add_u64 v[24:25], v[6:7], 0, s[14:15]
	s_mov_b32 m0, s8
	s_nop 0
	global_load_lds_dwordx4 v[24:25], off
	v_lshl_add_u64 v[24:25], v[6:7], 0, s[16:17]
	s_mov_b32 m0, s9
	s_nop 0
	global_load_lds_dwordx4 v[24:25], off
	s_mov_b64 s[8:9], 0x61c0
	v_lshl_add_u64 v[6:7], v[6:7], 0, s[8:9]
	s_mov_b32 m0, s10
	s_nop 0
	global_load_lds_dwordx4 v[6:7], off
	v_lshl_add_u64 v[6:7], v[8:9], 0, s[14:15]
	s_mov_b32 m0, s11
	s_nop 0
	global_load_lds_dwordx4 v[172:173], off
	v_mfma_f32_16x16x32_bf16 v[116:119], v[156:159], v[108:111], v[116:119]
	s_mov_b32 m0, s12
	s_nop 0
	global_load_lds_dwordx4 v[6:7], off
	v_readlane_b32 s8, v255, 5
	v_readlane_b32 s14, v255, 11
	v_mfma_f32_16x16x32_bf16 v[120:123], v[156:159], v[148:151], v[120:123]
	v_readlane_b32 s9, v255, 6
	v_readlane_b32 s10, v255, 7
	v_readlane_b32 s11, v255, 8
	v_mfma_f32_16x16x32_bf16 v[96:99], v[156:159], v[152:155], v[96:99]
	v_readlane_b32 s12, v255, 9
	v_readlane_b32 s13, v255, 10
	v_readlane_b32 s15, v255, 12
	v_mfma_f32_16x16x32_bf16 v[128:131], v[160:163], v[108:111], v[128:131]
	s_add_i32 s4, s5, s14
	v_mfma_f32_16x16x32_bf16 v[132:135], v[160:163], v[148:151], v[132:135]
	v_mfma_f32_16x16x32_bf16 v[100:103], v[160:163], v[152:155], v[100:103]
	v_mfma_f32_16x16x32_bf16 v[140:143], v[164:167], v[108:111], v[140:143]
	v_mfma_f32_16x16x32_bf16 v[144:147], v[164:167], v[148:151], v[144:147]
	v_mfma_f32_16x16x32_bf16 v[104:107], v[164:167], v[152:155], v[104:107]
	v_mfma_f32_16x16x32_bf16 v[16:19], v[168:171], v[108:111], v[16:19]
	v_mfma_f32_16x16x32_bf16 v[20:23], v[168:171], v[148:151], v[20:23]
	v_mfma_f32_16x16x32_bf16 v[2:5], v[168:171], v[152:155], v[2:5]
	ds_read_b128 v[6:9], v11 offset:49152
	ds_read_b128 v[24:27], v11 offset:50176
	ds_read_b128 v[108:111], v11 offset:51200
	ds_read_b128 v[148:151], v11 offset:52224
	ds_read_b128 v[152:155], v174
	ds_read_b128 v[156:159], v175
	ds_read_b128 v[160:163], v176
	ds_read_b128 v[164:167], v177
	s_waitcnt lgkmcnt(3)
	v_mfma_f32_16x16x32_bf16 v[44:47], v[152:155], v[6:9], v[44:47]
	v_mfma_f32_16x16x32_bf16 v[48:51], v[152:155], v[24:27], v[48:51]
	v_mfma_f32_16x16x32_bf16 v[52:55], v[152:155], v[108:111], v[52:55]
	v_mfma_f32_16x16x32_bf16 v[28:31], v[152:155], v[148:151], v[28:31]
	s_waitcnt lgkmcnt(2)
	v_mfma_f32_16x16x32_bf16 v[56:59], v[156:159], v[6:9], v[56:59]
	v_mfma_f32_16x16x32_bf16 v[60:63], v[156:159], v[24:27], v[60:63]
	v_mfma_f32_16x16x32_bf16 v[64:67], v[156:159], v[108:111], v[64:67]
	v_mfma_f32_16x16x32_bf16 v[32:35], v[156:159], v[148:151], v[32:35]
	s_waitcnt lgkmcnt(1)
	v_mfma_f32_16x16x32_bf16 v[68:71], v[160:163], v[6:9], v[68:71]
	v_mfma_f32_16x16x32_bf16 v[72:75], v[160:163], v[24:27], v[72:75]
	v_mfma_f32_16x16x32_bf16 v[76:79], v[160:163], v[108:111], v[76:79]
	v_mfma_f32_16x16x32_bf16 v[36:39], v[160:163], v[148:151], v[36:39]
	s_waitcnt lgkmcnt(0)
	v_mfma_f32_16x16x32_bf16 v[80:83], v[164:167], v[6:9], v[80:83]
	v_mfma_f32_16x16x32_bf16 v[84:87], v[164:167], v[24:27], v[84:87]
	v_mfma_f32_16x16x32_bf16 v[92:95], v[164:167], v[108:111], v[92:95]
	v_mfma_f32_16x16x32_bf16 v[40:43], v[164:167], v[148:151], v[40:43]
	ds_read_b128 v[152:155], v178
	ds_read_b128 v[156:159], v179
	ds_read_b128 v[160:163], v180
	ds_read_b128 v[164:167], v181
	s_waitcnt vmcnt(6)
	s_waitcnt lgkmcnt(0)
	v_mfma_f32_16x16x32_bf16 v[112:115], v[152:155], v[6:9], v[112:115]
	s_barrier
	v_mfma_f32_16x16x32_bf16 v[116:119], v[152:155], v[24:27], v[116:119]
	v_mfma_f32_16x16x32_bf16 v[120:123], v[152:155], v[108:111], v[120:123]
	v_mfma_f32_16x16x32_bf16 v[96:99], v[152:155], v[148:151], v[96:99]
	v_mfma_f32_16x16x32_bf16 v[124:127], v[156:159], v[6:9], v[124:127]
	v_mfma_f32_16x16x32_bf16 v[128:131], v[156:159], v[24:27], v[128:131]
	v_mfma_f32_16x16x32_bf16 v[132:135], v[156:159], v[108:111], v[132:135]
	v_mfma_f32_16x16x32_bf16 v[100:103], v[156:159], v[148:151], v[100:103]
	v_mfma_f32_16x16x32_bf16 v[136:139], v[160:163], v[6:9], v[136:139]
	v_mfma_f32_16x16x32_bf16 v[140:143], v[160:163], v[24:27], v[140:143]
	v_mfma_f32_16x16x32_bf16 v[144:147], v[160:163], v[108:111], v[144:147]
	v_mfma_f32_16x16x32_bf16 v[104:107], v[160:163], v[148:151], v[104:107]
	v_mfma_f32_16x16x32_bf16 v[6:9], v[164:167], v[6:9], v[12:15]
	v_mfma_f32_16x16x32_bf16 v[12:15], v[164:167], v[24:27], v[16:19]
	v_mfma_f32_16x16x32_bf16 v[16:19], v[164:167], v[108:111], v[20:23]
	v_mfma_f32_16x16x32_bf16 v[2:5], v[164:167], v[148:151], v[2:5]
	s_nop 1
	ds_read_b128 v[20:23], v10 offset:23552
	ds_read_b128 v[24:27], v10 offset:22528
	ds_read_b128 v[108:111], v10 offset:21504
	ds_read_b128 v[148:151], v10 offset:20480
	ds_read_b128 v[152:155], v10 offset:19456
	ds_read_b128 v[156:159], v10 offset:18432
	ds_read_b128 v[160:163], v10 offset:17408
	ds_read_b128 v[164:167], v10 offset:16384
	ds_read_b128 v[168:171], v11 offset:3072
	ds_read_b128 v[172:175], v11 offset:2048
	ds_read_b128 v[176:179], v11 offset:1024
	ds_read_b128 v[186:189], v11
	s_waitcnt vmcnt(0)
	s_waitcnt lgkmcnt(0)
	v_mfma_f32_16x16x32_bf16 v[44:47], v[164:167], v[186:189], v[44:47]
	s_barrier
; DI void st_bf4(u16* p, float a, float b, float c, float d) { *(uint2*)p = make_uint2(pk2(a, b), pk2(c, d)); }
; template <int BM, class Epi>
; DI void gemm_dma(const u16* __restrict__ X, long ldx, const u16* __restrict__ W, long ldw, int K, char* smem,
;                  int m0, int n0, const Epi& epi) {
;     ...
;     for (int i = 0; i < MT; ++i) xf[i] = *(const bf16x8*)(base + (xrow0 + i * 16) * 64 + rd);
; #pragma unroll
;     for (int nh = 0; nh < NT / 4; ++nh) {
;       bf16x8 wf[4];
; #pragma unroll
;       for (int i = 0; i < 4; ++i) wf[i] = *(const bf16x8*)(base + BM * 64 + (wrow0 + (nh * 4 + i) * 16) * 64 + rd);
; #pragma unroll
;       for (int i = 0; i < 4; ++i)
; #pragma unroll
;         for (int mt = 0; mt < MT; ++mt)
;           acc[nh * 4 + i][mt] = __builtin_amdgcn_mfma_f32_16x16x32_bf16(wf[i], xf[mt], acc[nh * 4 + i][mt], 0, 0, 0);
;   template <int NT, int MT> DI void run(f32x4 (&acc)[NT][MT], int mb, int nb) const {
; #pragma unroll
;     for (int nt = 0; nt < NT; ++nt)
; #pragma unroll
;       for (int mt = 0; mt < MT; ++mt) {
;         f32x4 v = acc[nt][mt];
;         st_bf4(C + (size_t)(mb + mt * 16) * ldc + nb + nt * 16, v[0], v[1], v[2], v[3]);
;       }
;   }
	v_mfma_f32_16x16x32_bf16 v[48:51], v[164:167], v[176:179], v[48:51]
	v_mfma_f32_16x16x32_bf16 v[52:55], v[164:167], v[172:175], v[52:55]
	v_mfma_f32_16x16x32_bf16 v[28:31], v[164:167], v[168:171], v[28:31]
	v_mfma_f32_16x16x32_bf16 v[56:59], v[160:163], v[186:189], v[56:59]
	v_mfma_f32_16x16x32_bf16 v[60:63], v[160:163], v[176:179], v[60:63]
	v_mfma_f32_16x16x32_bf16 v[64:67], v[160:163], v[172:175], v[64:67]
	v_mfma_f32_16x16x32_bf16 v[32:35], v[160:163], v[168:171], v[32:35]
	v_mfma_f32_16x16x32_bf16 v[68:71], v[156:159], v[186:189], v[68:71]
	v_mfma_f32_16x16x32_bf16 v[72:75], v[156:159], v[176:179], v[72:75]
	v_mfma_f32_16x16x32_bf16 v[76:79], v[156:159], v[172:175], v[76:79]
	v_mfma_f32_16x16x32_bf16 v[36:39], v[156:159], v[168:171], v[36:39]
	v_mfma_f32_16x16x32_bf16 v[156:159], v[152:155], v[186:189], v[80:83]
	v_mfma_f32_16x16x32_bf16 v[86:89], v[152:155], v[176:179], v[84:87]
	v_mfma_f32_16x16x32_bf16 v[92:95], v[152:155], v[172:175], v[92:95]
	v_mfma_f32_16x16x32_bf16 v[152:155], v[152:155], v[168:171], v[40:43]
	v_mfma_f32_16x16x32_bf16 v[112:115], v[148:151], v[186:189], v[112:115]
	v_mfma_f32_16x16x32_bf16 v[116:119], v[148:151], v[176:179], v[116:119]
	v_mfma_f32_16x16x32_bf16 v[120:123], v[148:151], v[172:175], v[120:123]
	v_mfma_f32_16x16x32_bf16 v[96:99], v[148:151], v[168:171], v[96:99]
	v_mfma_f32_16x16x32_bf16 v[124:127], v[108:111], v[186:189], v[124:127]
	v_mfma_f32_16x16x32_bf16 v[128:131], v[108:111], v[176:179], v[128:131]
	v_mfma_f32_16x16x32_bf16 v[132:135], v[108:111], v[172:175], v[132:135]
	v_mfma_f32_16x16x32_bf16 v[100:103], v[108:111], v[168:171], v[100:103]
	v_mfma_f32_16x16x32_bf16 v[108:111], v[24:27], v[186:189], v[136:139]
	v_mfma_f32_16x16x32_bf16 v[136:139], v[24:27], v[176:179], v[140:143]
	v_mfma_f32_16x16x32_bf16 v[140:143], v[24:27], v[172:175], v[144:147]
	v_mfma_f32_16x16x32_bf16 v[104:107], v[24:27], v[168:171], v[104:107]
	v_mfma_f32_16x16x32_bf16 v[6:9], v[20:23], v[186:189], v[6:9]
	v_mfma_f32_16x16x32_bf16 v[144:147], v[20:23], v[176:179], v[12:15]
	v_mfma_f32_16x16x32_bf16 v[148:151], v[20:23], v[172:175], v[16:19]
	v_mfma_f32_16x16x32_bf16 v[2:5], v[20:23], v[168:171], v[2:5]
	s_nop 0
	ds_read_b128 v[12:15], v11 offset:24576
	ds_read_b128 v[160:163], v11 offset:25600
	ds_read_b128 v[164:167], v11 offset:26624
	ds_read_b128 v[168:171], v11 offset:27648
	ds_read_b128 v[16:19], v10 offset:40960
	ds_read_b128 v[20:23], v10 offset:41984
	ds_read_b128 v[24:27], v10 offset:43008
	ds_read_b128 v[172:175], v10 offset:44032
	s_waitcnt lgkmcnt(3)
	v_mfma_f32_16x16x32_bf16 v[176:179], v[16:19], v[12:15], v[44:47]
	v_mfma_f32_16x16x32_bf16 v[186:189], v[16:19], v[160:163], v[48:51]
	v_mfma_f32_16x16x32_bf16 v[190:193], v[16:19], v[164:167], v[52:55]
	v_mfma_f32_16x16x32_bf16 v[194:197], v[16:19], v[168:171], v[28:31]
	s_waitcnt lgkmcnt(2)
	v_mfma_f32_16x16x32_bf16 v[224:227], v[20:23], v[12:15], v[56:59]
	v_mfma_f32_16x16x32_bf16 v[228:231], v[20:23], v[160:163], v[60:63]
	v_mfma_f32_16x16x32_bf16 v[232:235], v[20:23], v[164:167], v[64:67]
	v_mfma_f32_16x16x32_bf16 v[236:239], v[20:23], v[168:171], v[32:35]
	s_waitcnt lgkmcnt(1)
	v_mfma_f32_16x16x32_bf16 v[240:243], v[24:27], v[12:15], v[68:71]
	v_mfma_f32_16x16x32_bf16 v[66:69], v[24:27], v[168:171], v[36:39]
	s_waitcnt lgkmcnt(0)
	v_mfma_f32_16x16x32_bf16 v[42:45], v[172:175], v[164:167], v[92:95]
	v_mfma_f32_16x16x32_bf16 v[34:37], v[172:175], v[168:171], v[152:155]
	ds_read_b128 v[16:19], v10 offset:45056
	ds_read_b128 v[20:23], v10 offset:46080
	ds_read_b128 v[92:95], v10 offset:47104
	ds_read_b128 v[152:155], v10 offset:48128
	s_nop 0
	v_cvt_pk_bf16_f32 v66, v66, v67
	v_cvt_pk_bf16_f32 v67, v68, v69
	v_mfma_f32_16x16x32_bf16 v[82:85], v[24:27], v[160:163], v[72:75]
	v_cvt_pk_bf16_f32 v34, v34, v35
	v_cvt_pk_bf16_f32 v35, v36, v37
	v_cvt_pk_bf16_f32 v42, v42, v43
	v_mfma_f32_16x16x32_bf16 v[74:77], v[24:27], v[164:167], v[76:79]
	v_cvt_pk_bf16_f32 v43, v44, v45
	s_nop 2
	v_cvt_pk_bf16_f32 v82, v82, v83
	v_cvt_pk_bf16_f32 v83, v84, v85
	v_mfma_f32_16x16x32_bf16 v[50:53], v[172:175], v[160:163], v[86:89]
	s_waitcnt lgkmcnt(3)
	v_mfma_f32_16x16x32_bf16 v[112:115], v[16:19], v[12:15], v[112:115]
	v_cvt_pk_bf16_f32 v74, v74, v75
	v_cvt_pk_bf16_f32 v75, v76, v77
	s_nop 3
	v_cvt_pk_bf16_f32 v50, v50, v51
	v_mfma_f32_16x16x32_bf16 v[86:89], v[16:19], v[160:163], v[116:119]
	v_cvt_pk_bf16_f32 v51, v52, v53
	v_mfma_f32_16x16x32_bf16 v[78:81], v[16:19], v[164:167], v[120:123]
	v_mfma_f32_16x16x32_bf16 v[70:73], v[16:19], v[168:171], v[96:99]
	s_waitcnt lgkmcnt(2)
	v_mfma_f32_16x16x32_bf16 v[62:65], v[20:23], v[12:15], v[124:127]
	s_nop 0
	v_cvt_pk_bf16_f32 v96, v186, v187
	v_cvt_pk_bf16_f32 v97, v188, v189
	v_cvt_pk_bf16_f32 v98, v190, v191
	v_mfma_f32_16x16x32_bf16 v[54:57], v[20:23], v[160:163], v[128:131]
	v_cvt_pk_bf16_f32 v99, v192, v193
	v_mfma_f32_16x16x32_bf16 v[46:49], v[20:23], v[164:167], v[132:135]
	v_mfma_f32_16x16x32_bf16 v[38:41], v[20:23], v[168:171], v[100:103]
	s_waitcnt lgkmcnt(1)
; DI void st_bf4(u16* p, float a, float b, float c, float d) { *(uint2*)p = make_uint2(pk2(a, b), pk2(c, d)); }
; template <int BM, class Epi>
; DI void gemm_dma(const u16* __restrict__ X, long ldx, const u16* __restrict__ W, long ldw, int K, char* smem,
;                  int m0, int n0, const Epi& epi) {
;     ...
;       for (int i = 0; i < 4; ++i)
; #pragma unroll
;         for (int mt = 0; mt < MT; ++mt)
;           acc[nh * 4 + i][mt] = __builtin_amdgcn_mfma_f32_16x16x32_bf16(wf[i], xf[mt], acc[nh * 4 + i][mt], 0, 0, 0);
;   template <int NT, int MT> DI void run(f32x4 (&acc)[NT][MT], int mb, int nb) const {
; #pragma unroll
;     for (int nt = 0; nt < NT; ++nt)
; #pragma unroll
;       for (int mt = 0; mt < MT; ++mt) {
;         f32x4 v = acc[nt][mt];
;         st_bf4(C + (size_t)(mb + mt * 16) * ldc + nb + nt * 16, v[0], v[1], v[2], v[3]);
;       }
;   }
	v_mfma_f32_16x16x32_bf16 v[30:33], v[92:95], v[12:15], v[108:111]
	v_mfma_f32_16x16x32_bf16 v[26:29], v[92:95], v[160:163], v[136:139]
	v_mfma_f32_16x16x32_bf16 v[22:25], v[92:95], v[164:167], v[140:143]
	s_nop 5
	v_cvt_pk_bf16_f32 v30, v30, v31
	v_cvt_pk_bf16_f32 v31, v32, v33
	v_cvt_pk_bf16_f32 v26, v26, v27
	v_mfma_f32_16x16x32_bf16 v[18:21], v[92:95], v[168:171], v[104:107]
	v_or_b32_e32 v94, v91, v90
	v_ashrrev_i32_e32 v95, 31, v94
	v_lshlrev_b64 v[90:91], 11, v[94:95]
	v_lshl_add_u64 v[90:91], s[92:93], 0, v[90:91]
	v_lshl_add_u64 v[90:91], v[90:91], 0, v[182:183]
	v_cvt_pk_bf16_f32 v92, v176, v177
	v_cvt_pk_bf16_f32 v93, v178, v179
	global_store_dwordx2 v[90:91], v[92:93], off
	v_or_b32_e32 v92, 16, v94
	v_ashrrev_i32_e32 v93, 31, v92
	v_lshlrev_b64 v[92:93], 11, v[92:93]
	v_lshl_add_u64 v[92:93], s[92:93], 0, v[92:93]
	v_lshl_add_u64 v[92:93], v[92:93], 0, v[182:183]
	global_store_dwordx2 v[92:93], v[96:97], off
	v_or_b32_e32 v96, 32, v94
	v_or_b32_e32 v94, 48, v94
	v_ashrrev_i32_e32 v95, 31, v94
	v_lshlrev_b64 v[94:95], 11, v[94:95]
	v_ashrrev_i32_e32 v97, 31, v96
	v_lshl_add_u64 v[94:95], s[92:93], 0, v[94:95]
	v_lshlrev_b64 v[96:97], 11, v[96:97]
	v_lshl_add_u64 v[94:95], v[94:95], 0, v[182:183]
	v_lshl_add_u64 v[96:97], s[92:93], 0, v[96:97]
	global_store_dwordx2 v[94:95], v[34:35], off offset:96
	v_cvt_pk_bf16_f32 v34, v112, v113
	v_cvt_pk_bf16_f32 v35, v114, v115
	v_lshl_add_u64 v[96:97], v[96:97], 0, v[182:183]
	global_store_dwordx2 v[90:91], v[34:35], off offset:128
	v_cvt_pk_bf16_f32 v34, v86, v87
	v_cvt_pk_bf16_f32 v35, v88, v89
	global_store_dwordx2 v[96:97], v[98:99], off
	v_cvt_pk_bf16_f32 v98, v194, v195
	v_cvt_pk_bf16_f32 v99, v196, v197
	global_store_dwordx2 v[92:93], v[34:35], off offset:128
	v_cvt_pk_bf16_f32 v34, v78, v79
	v_cvt_pk_bf16_f32 v35, v80, v81
	v_mfma_f32_16x16x32_bf16 v[58:61], v[172:175], v[12:15], v[156:159]
	global_store_dwordx2 v[94:95], v[98:99], off
	v_cvt_pk_bf16_f32 v98, v224, v225
	v_cvt_pk_bf16_f32 v99, v226, v227
	s_waitcnt lgkmcnt(0)
	v_mfma_f32_16x16x32_bf16 v[14:17], v[152:155], v[12:15], v[6:9]
	global_store_dwordx2 v[96:97], v[34:35], off offset:128
	v_cvt_pk_bf16_f32 v34, v70, v71
	v_cvt_pk_bf16_f32 v35, v72, v73
	v_mfma_f32_16x16x32_bf16 v[10:13], v[152:155], v[160:163], v[144:147]
	global_store_dwordx2 v[90:91], v[98:99], off offset:32
	v_cvt_pk_bf16_f32 v98, v228, v229
	v_cvt_pk_bf16_f32 v99, v230, v231
	v_mfma_f32_16x16x32_bf16 v[6:9], v[152:155], v[164:167], v[148:151]
	global_store_dwordx2 v[94:95], v[34:35], off offset:128
	v_cvt_pk_bf16_f32 v34, v62, v63
	v_cvt_pk_bf16_f32 v35, v64, v65
	v_mfma_f32_16x16x32_bf16 v[2:5], v[152:155], v[168:171], v[2:5]
	global_store_dwordx2 v[92:93], v[98:99], off offset:32
	v_cvt_pk_bf16_f32 v98, v232, v233
	v_cvt_pk_bf16_f32 v99, v234, v235
	global_store_dwordx2 v[90:91], v[34:35], off offset:160
	v_cvt_pk_bf16_f32 v34, v54, v55
	v_cvt_pk_bf16_f32 v35, v56, v57
	global_store_dwordx2 v[96:97], v[98:99], off offset:32
	v_cvt_pk_bf16_f32 v98, v236, v237
	v_cvt_pk_bf16_f32 v99, v238, v239
	global_store_dwordx2 v[92:93], v[34:35], off offset:160
	v_cvt_pk_bf16_f32 v34, v46, v47
	v_cvt_pk_bf16_f32 v35, v48, v49
	global_store_dwordx2 v[94:95], v[98:99], off offset:32
	v_cvt_pk_bf16_f32 v98, v240, v241
	v_cvt_pk_bf16_f32 v99, v242, v243
	v_cvt_pk_bf16_f32 v58, v58, v59
	v_cvt_pk_bf16_f32 v59, v60, v61
	global_store_dwordx2 v[96:97], v[34:35], off offset:160
	v_cvt_pk_bf16_f32 v34, v38, v39
	v_cvt_pk_bf16_f32 v35, v40, v41
	v_cvt_pk_bf16_f32 v27, v28, v29
	v_cvt_pk_bf16_f32 v22, v22, v23
	v_cvt_pk_bf16_f32 v23, v24, v25
	v_cvt_pk_bf16_f32 v18, v18, v19
	v_cvt_pk_bf16_f32 v19, v20, v21
	v_cvt_pk_bf16_f32 v14, v14, v15
	v_cvt_pk_bf16_f32 v15, v16, v17
	v_cvt_pk_bf16_f32 v10, v10, v11
	v_cvt_pk_bf16_f32 v11, v12, v13
	v_cvt_pk_bf16_f32 v6, v6, v7
	v_cvt_pk_bf16_f32 v7, v8, v9
	v_cvt_pk_bf16_f32 v2, v2, v3
	v_cvt_pk_bf16_f32 v3, v4, v5
	global_store_dwordx2 v[90:91], v[98:99], off offset:64
	global_store_dwordx2 v[92:93], v[82:83], off offset:64
	global_store_dwordx2 v[96:97], v[74:75], off offset:64
	global_store_dwordx2 v[94:95], v[66:67], off offset:64
	global_store_dwordx2 v[90:91], v[58:59], off offset:96
	global_store_dwordx2 v[92:93], v[50:51], off offset:96
	global_store_dwordx2 v[96:97], v[42:43], off offset:96
	global_store_dwordx2 v[94:95], v[34:35], off offset:160
	global_store_dwordx2 v[90:91], v[30:31], off offset:192
	global_store_dwordx2 v[92:93], v[26:27], off offset:192
	global_store_dwordx2 v[96:97], v[22:23], off offset:192
	global_store_dwordx2 v[94:95], v[18:19], off offset:192
	global_store_dwordx2 v[90:91], v[14:15], off offset:224
	global_store_dwordx2 v[92:93], v[10:11], off offset:224
	global_store_dwordx2 v[96:97], v[6:7], off offset:224
	global_store_dwordx2 v[94:95], v[2:3], off offset:224

; template <int MT, class Epi>
; DI void gemm_tile(const u16* __restrict__ X, long ldx, const u16* __restrict__ W, long ldw, int K, char* smem,
;                   int m0, int n0, const Epi& epi, bool pre = false, const u16* Xn = nullptr, const u16* Wn = nullptr) {
;     ...
;   const int wu = __builtin_amdgcn_readfirstlane(wave);
;   const unsigned sbase = (unsigned)__builtin_amdgcn_readfirstlane((int)(unsigned)(size_t)smem);
;   const int r8 = lane >> 3, c0 = (lane & 7) ^ (r8 >> 1);
;   const long oxe = (long)(wu * MT * 8 + r8) * ldx + (c0 << 3), oxo = (long)(wu * MT * 8 + r8) * ldx + ((c0 ^ 4) << 3);
;   const long owe = (long)(wu * 32 + r8) * ldw + (c0 << 3), owo = (long)(wu * 32 + r8) * ldw + ((c0 ^ 4) << 3);
;   const u16 *xe = X + oxe, *xo = X + oxo, *we = W + owe, *wo = W + owo;
;   const long ldx8 = 8 * ldx, ldw8 = 8 * ldw;
;   const unsigned xdst = sbase + wu * MT * 1024, wdst = sbase + 16384 + wu * 4096;
;     ...
;   if (!pre) {
;     __syncthreads();
;     GT_DMA(0u)
; DI void phase_odd(const Params& p, int o, int sub, char* smem) {
;     ...
;       if (t < 1584) {
;         const int tm = t / 12, tn = t % 12;
;         const int t2 = t + gridDim.x, tm2 = t2 / 12, tn2 = t2 % 12;
;         const bool nx = t2 < 1584;
;         gemm_tile<4>(qn + (size_t)tm * 128 * 384, 384, W + WO_Q + (size_t)tn * 128 * 384, 384, 384, smem, tm * 128, tn * 128, eq, pre,
;                      nx ? qn + (size_t)tm2 * 128 * 384 : nullptr, W + WO_Q + (size_t)tn2 * 128 * 384);
.LBB0_104:
	s_mul_hi_i32 s6, s5, 0x2aaaaaab
	s_lshr_b32 s9, s6, 31
	s_ashr_i32 s6, s6, 1
	s_add_i32 s6, s6, s9
	s_mul_i32 s9, s6, 12
	s_xor_b64 s[12:13], s[40:41], -1
	s_sub_i32 s5, s5, s9
	s_mul_i32 s10, s6, 0x18000
	s_mul_hi_i32 s9, s6, 0x18000
	s_add_u32 s10, s88, s10
	s_mul_i32 s14, s5, 0xc000
	s_waitcnt vmcnt(7)
	v_mov_b32_e32 v16, v185
	s_addc_u32 s11, s89, s9
	s_ashr_i32 s15, s14, 31
	s_lshl_b64 s[14:15], s[14:15], 1
	v_ashrrev_i32_e32 v1, 6, v16
	v_readlane_b32 s16, v252, 29
	v_bfe_u32 v70, v16, 4, 2
	v_readfirstlane_b32 s9, v1
	v_bfe_u32 v3, v16, 3, 3
	v_readlane_b32 s17, v252, 30
	s_add_u32 s14, s16, s14
	v_bitop3_b32 v6, v70, v16, 7 bitop3:0x78
	v_lshl_or_b32 v3, s9, 5, v3
	s_movk_i32 s16, 0x180
	s_addc_u32 s15, s17, s15
	v_mad_i64_i32 v[4:5], s[16:17], v3, s16, 0
	v_lshlrev_b32_e32 v3, 3, v6
	v_or_b32_e32 v6, v4, v3
	v_mov_b32_e32 v7, v5
	v_bitop3_b32 v4, v4, v3, 32 bitop3:0xf6
	v_lshlrev_b64 v[66:67], 1, v[6:7]
	v_lshlrev_b64 v[68:69], 1, v[4:5]
	v_lshl_add_u64 v[12:13], s[10:11], 0, v[66:67]
	v_lshl_add_u64 v[10:11], s[10:11], 0, v[68:69]
	s_lshl_b32 s10, s9, 12
	v_mov_b32_e32 v2, v183
	v_lshl_add_u64 v[8:9], s[14:15], 0, v[66:67]
	v_lshl_add_u64 v[6:7], s[14:15], 0, v[68:69]
	s_add_i32 s9, s10, 0x4000
	s_mov_b64 s[40:41], -1
	s_and_b64 vcc, exec, s[12:13]
	s_cbranch_vccz .LBB0_106
	s_barrier
	s_mov_b32 m0, s10
	s_nop 0
	global_load_lds_dwordx4 v[12:13], off
	s_mov_b64 s[18:19], 0x1800
	v_lshl_add_u64 v[4:5], v[10:11], 0, s[18:19]
	s_add_i32 s11, s10, 0x400
	s_mov_b32 m0, s11
	s_nop 0
	global_load_lds_dwordx4 v[4:5], off
	s_mov_b64 s[16:17], 0x3000
	v_lshl_add_u64 v[4:5], v[12:13], 0, s[16:17]
	s_add_i32 s12, s10, 0x800
	s_mov_b32 m0, s12
	s_nop 0
	global_load_lds_dwordx4 v[4:5], off
	s_mov_b64 s[20:21], 0x4800
	v_lshl_add_u64 v[4:5], v[10:11], 0, s[20:21]
	s_add_i32 s13, s10, 0xc00
	s_mov_b32 m0, s13
	s_nop 0
	global_load_lds_dwordx4 v[4:5], off
	v_lshl_add_u64 v[4:5], v[6:7], 0, s[18:19]
	s_mov_b32 m0, s9
	s_nop 0
	global_load_lds_dwordx4 v[8:9], off
	s_add_i32 s14, s10, 0x4400
	s_mov_b32 m0, s14
	s_nop 0
	global_load_lds_dwordx4 v[4:5], off
	v_lshl_add_u64 v[4:5], v[8:9], 0, s[16:17]
	s_add_i32 s15, s10, 0x4800
	s_mov_b32 m0, s15
	s_nop 0
	global_load_lds_dwordx4 v[4:5], off
	v_lshl_add_u64 v[4:5], v[6:7], 0, s[20:21]
	s_add_i32 s16, s10, 0x4c00
	s_mov_b32 m0, s16
	s_nop 0
	global_load_lds_dwordx4 v[4:5], off
	s_mov_b64 s[40:41], 0

; template <int MT, class Epi>
; DI void gemm_tile(const u16* __restrict__ X, long ldx, const u16* __restrict__ W, long ldw, int K, char* smem,
;                   int m0, int n0, const Epi& epi, bool pre = false, const u16* Xn = nullptr, const u16* Wn = nullptr) {
;     ...
;   do {
;     asm volatile("s_waitcnt vmcnt(0)" ::: "memory");
;     __syncthreads();
;     if (kt + 1 < nk) GT_DMA((unsigned)((kt + 1) & 1) * 32768u)
;     else if (Xn != nullptr) { xe = Xn + oxe; xo = Xn + oxo; we = Wn + owe; wo = Wn + owo; GT_DMA(0u) }
;     const char* cur = smem + (kt & 1) * 32768;
; #pragma unroll
;     for (int ks = 0; ks < 2; ++ks) {
;       bf16x8 xf[MT], wf[4];
;       const int ch = ((ks * 4 + g) ^ rsw) << 4;
; #pragma unroll
;       for (int i = 0; i < MT; ++i) xf[i] = *(const bf16x8*)(cur + (wm * 16 * MT + i * 16 + lr) * 128 + ch);
; #pragma unroll
;       for (int i = 0; i < 4; ++i) wf[i] = *(const bf16x8*)(cur + 16384 + (wn * 64 + i * 16 + lr) * 128 + ch);
; #pragma unroll
;       for (int nt = 0; nt < 4; ++nt)
; #pragma unroll
;         for (int mt = 0; mt < MT; ++mt)
;           acc[nt][mt] = __builtin_amdgcn_mfma_f32_16x16x32_bf16(wf[nt], xf[mt], acc[nt][mt], 0, 0, 0);
.LBB0_108:
	s_add_i32 s45, s10, 0x8000
	s_waitcnt vmcnt(0)
	s_barrier
	v_lshl_add_u64 v[14:15], v[12:13], 0, s[28:29]
	s_mov_b32 m0, s45
	s_nop 0
	global_load_lds_dwordx4 v[14:15], off
	s_mov_b64 s[20:21], 0x1880
	s_add_i32 s44, s10, 0x8400
	v_lshl_add_u64 v[14:15], v[10:11], 0, s[20:21]
	s_mov_b32 m0, s44
	s_nop 0
	global_load_lds_dwordx4 v[14:15], off
	s_mov_b64 s[22:23], 0x3080
	s_add_i32 s41, s10, 0x8800
	v_lshl_add_u64 v[14:15], v[12:13], 0, s[22:23]
	s_mov_b32 m0, s41
	s_nop 0
	global_load_lds_dwordx4 v[14:15], off
	s_mov_b64 s[48:49], 0x4880
	v_lshrrev_b32_e32 v3, 1, v16
	s_add_i32 s34, s10, 0x8c00
	v_lshl_add_u64 v[14:15], v[10:11], 0, s[48:49]
	s_mov_b32 m0, s34
	s_nop 0
	global_load_lds_dwordx4 v[14:15], off
	v_ashrrev_i32_e32 v72, 7, v16
	s_add_i32 s40, s10, 0xc000
	v_lshl_add_u64 v[4:5], v[8:9], 0, s[28:29]
	s_mov_b32 m0, s40
	s_nop 0
	global_load_lds_dwordx4 v[4:5], off
	v_bitop3_b32 v3, v70, v3, 7 bitop3:0x78
	v_and_b32_e32 v71, 15, v16
	s_add_i32 s19, s10, 0xc400
	v_lshl_add_u64 v[4:5], v[6:7], 0, s[20:21]
	s_mov_b32 m0, s19
	s_nop 0
	global_load_lds_dwordx4 v[4:5], off
	v_lshlrev_b32_e32 v3, 4, v3
	v_lshlrev_b32_e32 v17, 13, v72
	s_add_i32 s18, s10, 0xc800
	v_lshl_add_u64 v[4:5], v[8:9], 0, s[22:23]
	s_mov_b32 m0, s18
	s_nop 0
	global_load_lds_dwordx4 v[4:5], off
	v_lshlrev_b32_e32 v73, 7, v71
	v_or_b32_e32 v74, v3, v17
	s_add_i32 s17, s10, 0xcc00
	v_lshl_add_u64 v[4:5], v[6:7], 0, s[48:49]
	s_mov_b32 m0, s17
	s_nop 0
	global_load_lds_dwordx4 v[4:5], off
	v_or_b32_e32 v14, v74, v73
	v_and_b32_e32 v1, 1, v1
	s_waitcnt vmcnt(5)
	ds_read_b128 v[18:21], v14 offset:16384
	ds_read_b128 v[50:53], v14 offset:18432
	ds_read_b128 v[82:85], v14 offset:20480
	s_waitcnt vmcnt(0)
	ds_read_b128 v[98:101], v14 offset:22528
	v_lshlrev_b32_e32 v55, 13, v1
	v_bfe_u32 v16, v16, 1, 3
	v_or_b32_e32 v75, v3, v55
	v_bitop3_b32 v16, v70, v16, 4 bitop3:0x36
	v_or_b32_e32 v15, v75, v73
	v_lshlrev_b32_e32 v16, 4, v16
	ds_read_b128 v[22:25], v15
	ds_read_b128 v[30:33], v15 offset:2048
	ds_read_b128 v[38:41], v15 offset:4096
	ds_read_b128 v[46:49], v15 offset:6144
	v_or_b32_e32 v76, v16, v17
	v_or_b32_e32 v54, v76, v73
	ds_read_b128 v[102:105], v54 offset:16384
	v_mov_b32_e32 v3, v2
	v_mov_b32_e32 v4, v2
	v_mov_b32_e32 v5, v2
	v_or_b32_e32 v77, v16, v55
	s_mov_b64 s[20:21], 0x100
	s_waitcnt lgkmcnt(4)
	v_mfma_f32_16x16x32_bf16 v[26:29], v[18:21], v[22:25], v[2:5]
	s_mov_b64 s[22:23], 0x3100
	s_mov_b64 s[48:49], 0x4900
	s_cmp_eq_u64 s[42:43], 0
	s_waitcnt lgkmcnt(3)
	v_mfma_f32_16x16x32_bf16 v[34:37], v[18:21], v[30:33], v[2:5]
	s_waitcnt lgkmcnt(2)
	v_mfma_f32_16x16x32_bf16 v[42:45], v[18:21], v[38:41], v[2:5]
	s_waitcnt lgkmcnt(1)
	v_mfma_f32_16x16x32_bf16 v[18:21], v[18:21], v[46:49], v[2:5]
	v_mfma_f32_16x16x32_bf16 v[56:59], v[50:53], v[22:25], v[2:5]
	v_mfma_f32_16x16x32_bf16 v[60:63], v[50:53], v[30:33], v[2:5]
	v_mfma_f32_16x16x32_bf16 v[78:81], v[50:53], v[38:41], v[2:5]
	v_mfma_f32_16x16x32_bf16 v[50:53], v[50:53], v[46:49], v[2:5]
	v_mfma_f32_16x16x32_bf16 v[86:89], v[82:85], v[22:25], v[2:5]
	v_mfma_f32_16x16x32_bf16 v[90:93], v[82:85], v[30:33], v[2:5]
	v_mfma_f32_16x16x32_bf16 v[94:97], v[82:85], v[38:41], v[2:5]
	v_mfma_f32_16x16x32_bf16 v[82:85], v[82:85], v[46:49], v[2:5]
	v_mfma_f32_16x16x32_bf16 v[22:25], v[98:101], v[22:25], v[2:5]
	v_mfma_f32_16x16x32_bf16 v[30:33], v[98:101], v[30:33], v[2:5]
	v_mfma_f32_16x16x32_bf16 v[38:41], v[98:101], v[38:41], v[2:5]
	v_mfma_f32_16x16x32_bf16 v[46:49], v[98:101], v[46:49], v[2:5]
	s_nop 2
	v_or_b32_e32 v2, v77, v73
	ds_read_b128 v[98:101], v2
	ds_read_b128 v[106:109], v2 offset:2048
	ds_read_b128 v[110:113], v2 offset:4096
	ds_read_b128 v[114:117], v2 offset:6144
	s_waitcnt lgkmcnt(3)
	v_mfma_f32_16x16x32_bf16 v[26:29], v[102:105], v[98:101], v[26:29]
	v_lshl_add_u64 v[4:5], v[12:13], 0, s[20:21]
	s_waitcnt lgkmcnt(2)
	v_mfma_f32_16x16x32_bf16 v[34:37], v[102:105], v[106:109], v[34:37]
	s_waitcnt lgkmcnt(1)
	v_mfma_f32_16x16x32_bf16 v[42:45], v[102:105], v[110:113], v[42:45]
	s_waitcnt lgkmcnt(0)
	v_mfma_f32_16x16x32_bf16 v[16:19], v[102:105], v[114:117], v[18:21]
	ds_read_b128 v[102:105], v54 offset:18432
	s_waitcnt lgkmcnt(0)
	v_mfma_f32_16x16x32_bf16 v[56:59], v[102:105], v[98:101], v[56:59]
	v_mfma_f32_16x16x32_bf16 v[60:63], v[102:105], v[106:109], v[60:63]
	v_mfma_f32_16x16x32_bf16 v[78:81], v[102:105], v[110:113], v[78:81]
	v_mfma_f32_16x16x32_bf16 v[50:53], v[102:105], v[114:117], v[50:53]
	ds_read_b128 v[102:105], v54 offset:20480
	s_waitcnt lgkmcnt(0)
	v_mfma_f32_16x16x32_bf16 v[86:89], v[102:105], v[98:101], v[86:89]
	v_mfma_f32_16x16x32_bf16 v[90:93], v[102:105], v[106:109], v[90:93]
	v_mfma_f32_16x16x32_bf16 v[94:97], v[102:105], v[110:113], v[94:97]
	v_mfma_f32_16x16x32_bf16 v[82:85], v[102:105], v[114:117], v[82:85]
	ds_read_b128 v[102:105], v54 offset:22528
	s_waitcnt vmcnt(0)
	s_waitcnt lgkmcnt(0)
	v_mfma_f32_16x16x32_bf16 v[20:23], v[102:105], v[98:101], v[22:25]
	s_nop 2
	v_lshl_add_u64 v[24:25], v[8:9], 0, s[20:21]
	s_barrier
; template <int MT, class Epi>
; DI void gemm_tile(const u16* __restrict__ X, long ldx, const u16* __restrict__ W, long ldw, int K, char* smem,
;                   int m0, int n0, const Epi& epi, bool pre = false, const u16* Xn = nullptr, const u16* Wn = nullptr) {
;     ...
;   do {
;     asm volatile("s_waitcnt vmcnt(0)" ::: "memory");
;     __syncthreads();
;     if (kt + 1 < nk) GT_DMA((unsigned)((kt + 1) & 1) * 32768u)
;     else if (Xn != nullptr) { xe = Xn + oxe; xo = Xn + oxo; we = Wn + owe; wo = Wn + owo; GT_DMA(0u) }
;     const char* cur = smem + (kt & 1) * 32768;
; #pragma unroll
;     for (int ks = 0; ks < 2; ++ks) {
;       bf16x8 xf[MT], wf[4];
;       const int ch = ((ks * 4 + g) ^ rsw) << 4;
; #pragma unroll
;       for (int i = 0; i < MT; ++i) xf[i] = *(const bf16x8*)(cur + (wm * 16 * MT + i * 16 + lr) * 128 + ch);
; #pragma unroll
;       for (int i = 0; i < 4; ++i) wf[i] = *(const bf16x8*)(cur + 16384 + (wn * 64 + i * 16 + lr) * 128 + ch);
; #pragma unroll
;       for (int nt = 0; nt < 4; ++nt)
; #pragma unroll
;         for (int mt = 0; mt < MT; ++mt)
;           acc[nt][mt] = __builtin_amdgcn_mfma_f32_16x16x32_bf16(wf[nt], xf[mt], acc[nt][mt], 0, 0, 0);
	s_mov_b32 m0, s10
	s_nop 0
	global_load_lds_dwordx4 v[4:5], off
	s_mov_b64 s[20:21], 0x1900
	v_lshl_add_u64 v[4:5], v[10:11], 0, s[20:21]
	s_mov_b32 m0, s11
	s_nop 0
	global_load_lds_dwordx4 v[4:5], off
	v_lshl_add_u64 v[4:5], v[12:13], 0, s[22:23]
	s_mov_b32 m0, s12
	s_nop 0
	global_load_lds_dwordx4 v[4:5], off
	v_lshl_add_u64 v[4:5], v[10:11], 0, s[48:49]
	s_mov_b32 m0, s13
	s_nop 0
	global_load_lds_dwordx4 v[4:5], off
	v_lshl_add_u64 v[4:5], v[6:7], 0, s[20:21]
	s_mov_b32 m0, s9
	s_nop 0
	global_load_lds_dwordx4 v[24:25], off
	v_mfma_f32_16x16x32_bf16 v[30:33], v[102:105], v[106:109], v[30:33]
	s_mov_b32 m0, s14
	s_nop 0
	global_load_lds_dwordx4 v[4:5], off
	v_lshl_add_u64 v[4:5], v[8:9], 0, s[22:23]
	s_mov_b32 m0, s15
	s_nop 0
	global_load_lds_dwordx4 v[4:5], off
	v_lshl_add_u64 v[4:5], v[6:7], 0, s[48:49]
	s_mov_b32 m0, s16
	s_nop 0
	global_load_lds_dwordx4 v[4:5], off
	ds_read_b128 v[98:101], v14 offset:49152
	v_mfma_f32_16x16x32_bf16 v[38:41], v[102:105], v[110:113], v[38:41]
	ds_read_b128 v[106:109], v15 offset:34816
	ds_read_b128 v[110:113], v15 offset:36864
	s_mov_b64 s[20:21], 0x180
	v_mfma_f32_16x16x32_bf16 v[46:49], v[102:105], v[114:117], v[46:49]
	ds_read_b128 v[102:105], v15 offset:32768
	ds_read_b128 v[114:117], v15 offset:38912
	v_lshl_add_u64 v[4:5], v[12:13], 0, s[20:21]
	s_waitcnt lgkmcnt(1)
	v_mfma_f32_16x16x32_bf16 v[24:27], v[98:101], v[102:105], v[26:29]
	v_lshl_add_u64 v[64:65], v[8:9], 0, s[20:21]
	s_mov_b64 s[20:21], 0x1980
	s_mov_b64 s[22:23], 0x3180
	v_mfma_f32_16x16x32_bf16 v[34:37], v[98:101], v[106:109], v[34:37]
	s_mov_b64 s[48:49], 0x4980
	v_mfma_f32_16x16x32_bf16 v[42:45], v[98:101], v[110:113], v[42:45]
	s_waitcnt lgkmcnt(0)
	v_mfma_f32_16x16x32_bf16 v[16:19], v[98:101], v[114:117], v[16:19]
	ds_read_b128 v[98:101], v14 offset:51200
	s_waitcnt lgkmcnt(0)
	v_mfma_f32_16x16x32_bf16 v[56:59], v[98:101], v[102:105], v[56:59]
	v_mfma_f32_16x16x32_bf16 v[60:63], v[98:101], v[106:109], v[60:63]
	v_mfma_f32_16x16x32_bf16 v[78:81], v[98:101], v[110:113], v[78:81]
	v_mfma_f32_16x16x32_bf16 v[50:53], v[98:101], v[114:117], v[50:53]
	ds_read_b128 v[98:101], v14 offset:53248
	s_waitcnt lgkmcnt(0)
	v_mfma_f32_16x16x32_bf16 v[86:89], v[98:101], v[102:105], v[86:89]
	v_mfma_f32_16x16x32_bf16 v[90:93], v[98:101], v[106:109], v[90:93]
	v_mfma_f32_16x16x32_bf16 v[94:97], v[98:101], v[110:113], v[94:97]
	v_mfma_f32_16x16x32_bf16 v[82:85], v[98:101], v[114:117], v[82:85]
	ds_read_b128 v[98:101], v14 offset:55296
	s_waitcnt lgkmcnt(0)
	v_mfma_f32_16x16x32_bf16 v[20:23], v[98:101], v[102:105], v[20:23]
	ds_read_b128 v[102:105], v54 offset:49152
	v_mfma_f32_16x16x32_bf16 v[28:31], v[98:101], v[106:109], v[30:33]
	ds_read_b128 v[106:109], v2 offset:34816
	v_mfma_f32_16x16x32_bf16 v[38:41], v[98:101], v[110:113], v[38:41]
	ds_read_b128 v[110:113], v2 offset:36864
	v_mfma_f32_16x16x32_bf16 v[46:49], v[98:101], v[114:117], v[46:49]
	ds_read_b128 v[98:101], v2 offset:32768
	ds_read_b128 v[114:117], v2 offset:38912
	s_waitcnt lgkmcnt(1)
	v_mfma_f32_16x16x32_bf16 v[24:27], v[102:105], v[98:101], v[24:27]
	v_mfma_f32_16x16x32_bf16 v[32:35], v[102:105], v[106:109], v[34:37]
	v_mfma_f32_16x16x32_bf16 v[42:45], v[102:105], v[110:113], v[42:45]
	s_waitcnt lgkmcnt(0)
	v_mfma_f32_16x16x32_bf16 v[16:19], v[102:105], v[114:117], v[16:19]
	ds_read_b128 v[102:105], v54 offset:51200
	s_waitcnt lgkmcnt(0)
	v_mfma_f32_16x16x32_bf16 v[56:59], v[102:105], v[98:101], v[56:59]
	v_mfma_f32_16x16x32_bf16 v[60:63], v[102:105], v[106:109], v[60:63]
	v_mfma_f32_16x16x32_bf16 v[78:81], v[102:105], v[110:113], v[78:81]
	v_mfma_f32_16x16x32_bf16 v[50:53], v[102:105], v[114:117], v[50:53]
	ds_read_b128 v[102:105], v54 offset:53248
	s_waitcnt lgkmcnt(0)
	v_mfma_f32_16x16x32_bf16 v[86:89], v[102:105], v[98:101], v[86:89]
	v_mfma_f32_16x16x32_bf16 v[90:93], v[102:105], v[106:109], v[90:93]
	v_mfma_f32_16x16x32_bf16 v[94:97], v[102:105], v[110:113], v[94:97]
	v_mfma_f32_16x16x32_bf16 v[82:85], v[102:105], v[114:117], v[82:85]
	ds_read_b128 v[102:105], v54 offset:55296
	s_waitcnt vmcnt(0)
	s_waitcnt lgkmcnt(0)
	s_barrier
	s_mov_b32 m0, s45
	s_nop 0
	global_load_lds_dwordx4 v[4:5], off
	v_lshl_add_u64 v[4:5], v[10:11], 0, s[20:21]
	s_mov_b32 m0, s44
	s_nop 0
	global_load_lds_dwordx4 v[4:5], off
	v_lshl_add_u64 v[4:5], v[12:13], 0, s[22:23]
	s_mov_b32 m0, s41
	s_nop 0
	global_load_lds_dwordx4 v[4:5], off
	v_lshl_add_u64 v[4:5], v[10:11], 0, s[48:49]
	s_mov_b32 m0, s34
	s_nop 0
	global_load_lds_dwordx4 v[4:5], off
	v_lshl_add_u64 v[4:5], v[6:7], 0, s[20:21]
	s_mov_b32 m0, s40
	s_nop 0
	global_load_lds_dwordx4 v[64:65], off
	v_mfma_f32_16x16x32_bf16 v[20:23], v[102:105], v[98:101], v[20:23]
	s_mov_b32 m0, s19
	s_nop 0
	global_load_lds_dwordx4 v[4:5], off
	v_lshl_add_u64 v[4:5], v[8:9], 0, s[22:23]
	s_mov_b32 m0, s18
	s_nop 0
	global_load_lds_dwordx4 v[4:5], off
	v_lshl_add_u64 v[4:5], v[6:7], 0, s[48:49]
	s_mov_b32 m0, s17
	s_nop 0
	global_load_lds_dwordx4 v[4:5], off
	ds_read_b128 v[98:101], v14 offset:16384
	v_mfma_f32_16x16x32_bf16 v[28:31], v[102:105], v[106:109], v[28:31]
	ds_read_b128 v[106:109], v15 offset:2048
	s_mov_b64 s[20:21], 0x200
	v_lshl_add_u64 v[4:5], v[12:13], 0, s[20:21]
	v_mfma_f32_16x16x32_bf16 v[36:39], v[102:105], v[110:113], v[38:41]
	ds_read_b128 v[110:113], v15 offset:4096
	s_mov_b64 s[22:23], 0x3200
	s_mov_b64 s[48:49], 0x4a00
	v_mfma_f32_16x16x32_bf16 v[46:49], v[102:105], v[114:117], v[46:49]
	ds_read_b128 v[102:105], v15
	ds_read_b128 v[114:117], v15 offset:6144
	s_waitcnt lgkmcnt(1)
	v_mfma_f32_16x16x32_bf16 v[24:27], v[98:101], v[102:105], v[24:27]
	v_mfma_f32_16x16x32_bf16 v[32:35], v[98:101], v[106:109], v[32:35]
	v_mfma_f32_16x16x32_bf16 v[40:43], v[98:101], v[110:113], v[42:45]
	s_waitcnt lgkmcnt(0)
; template <int MT, class Epi>
; DI void gemm_tile(const u16* __restrict__ X, long ldx, const u16* __restrict__ W, long ldw, int K, char* smem,
;                   int m0, int n0, const Epi& epi, bool pre = false, const u16* Xn = nullptr, const u16* Wn = nullptr) {
;     ...
;   do {
;     asm volatile("s_waitcnt vmcnt(0)" ::: "memory");
;     __syncthreads();
;     if (kt + 1 < nk) GT_DMA((unsigned)((kt + 1) & 1) * 32768u)
;     else if (Xn != nullptr) { xe = Xn + oxe; xo = Xn + oxo; we = Wn + owe; wo = Wn + owo; GT_DMA(0u) }
;     const char* cur = smem + (kt & 1) * 32768;
; #pragma unroll
;     for (int ks = 0; ks < 2; ++ks) {
;       bf16x8 xf[MT], wf[4];
;       const int ch = ((ks * 4 + g) ^ rsw) << 4;
; #pragma unroll
;       for (int i = 0; i < MT; ++i) xf[i] = *(const bf16x8*)(cur + (wm * 16 * MT + i * 16 + lr) * 128 + ch);
; #pragma unroll
;       for (int i = 0; i < 4; ++i) wf[i] = *(const bf16x8*)(cur + 16384 + (wn * 64 + i * 16 + lr) * 128 + ch);
; #pragma unroll
;       for (int nt = 0; nt < 4; ++nt)
; #pragma unroll
;         for (int mt = 0; mt < MT; ++mt)
;           acc[nt][mt] = __builtin_amdgcn_mfma_f32_16x16x32_bf16(wf[nt], xf[mt], acc[nt][mt], 0, 0, 0);
	v_mfma_f32_16x16x32_bf16 v[16:19], v[98:101], v[114:117], v[16:19]
	ds_read_b128 v[98:101], v14 offset:18432
	s_waitcnt lgkmcnt(0)
	v_mfma_f32_16x16x32_bf16 v[56:59], v[98:101], v[102:105], v[56:59]
	v_mfma_f32_16x16x32_bf16 v[60:63], v[98:101], v[106:109], v[60:63]
	v_mfma_f32_16x16x32_bf16 v[78:81], v[98:101], v[110:113], v[78:81]
	v_mfma_f32_16x16x32_bf16 v[50:53], v[98:101], v[114:117], v[50:53]
	ds_read_b128 v[98:101], v14 offset:20480
	s_waitcnt lgkmcnt(0)
	v_mfma_f32_16x16x32_bf16 v[86:89], v[98:101], v[102:105], v[86:89]
	v_mfma_f32_16x16x32_bf16 v[90:93], v[98:101], v[106:109], v[90:93]
	v_mfma_f32_16x16x32_bf16 v[94:97], v[98:101], v[110:113], v[94:97]
	v_mfma_f32_16x16x32_bf16 v[82:85], v[98:101], v[114:117], v[82:85]
	ds_read_b128 v[98:101], v14 offset:22528
	s_waitcnt lgkmcnt(0)
	v_mfma_f32_16x16x32_bf16 v[20:23], v[98:101], v[102:105], v[20:23]
	ds_read_b128 v[102:105], v54 offset:16384
	v_mfma_f32_16x16x32_bf16 v[28:31], v[98:101], v[106:109], v[28:31]
	ds_read_b128 v[106:109], v2 offset:2048
	v_mfma_f32_16x16x32_bf16 v[36:39], v[98:101], v[110:113], v[36:39]
	ds_read_b128 v[110:113], v2 offset:4096
	v_mfma_f32_16x16x32_bf16 v[44:47], v[98:101], v[114:117], v[46:49]
	ds_read_b128 v[98:101], v2
	ds_read_b128 v[114:117], v2 offset:6144
	s_waitcnt lgkmcnt(1)
	v_mfma_f32_16x16x32_bf16 v[24:27], v[102:105], v[98:101], v[24:27]
	v_mfma_f32_16x16x32_bf16 v[32:35], v[102:105], v[106:109], v[32:35]
	v_mfma_f32_16x16x32_bf16 v[40:43], v[102:105], v[110:113], v[40:43]
	s_waitcnt lgkmcnt(0)
	v_mfma_f32_16x16x32_bf16 v[16:19], v[102:105], v[114:117], v[16:19]
	ds_read_b128 v[102:105], v54 offset:18432
	s_waitcnt lgkmcnt(0)
	v_mfma_f32_16x16x32_bf16 v[56:59], v[102:105], v[98:101], v[56:59]
	v_mfma_f32_16x16x32_bf16 v[60:63], v[102:105], v[106:109], v[60:63]
	v_mfma_f32_16x16x32_bf16 v[78:81], v[102:105], v[110:113], v[78:81]
	v_mfma_f32_16x16x32_bf16 v[48:51], v[102:105], v[114:117], v[50:53]
	ds_read_b128 v[102:105], v54 offset:20480
	s_waitcnt lgkmcnt(0)
	v_mfma_f32_16x16x32_bf16 v[86:89], v[102:105], v[98:101], v[86:89]
	v_lshl_add_u64 v[52:53], v[8:9], 0, s[20:21]
	s_mov_b64 s[20:21], 0x1a00
	v_mfma_f32_16x16x32_bf16 v[90:93], v[102:105], v[106:109], v[90:93]
	v_mfma_f32_16x16x32_bf16 v[94:97], v[102:105], v[110:113], v[94:97]
	v_mfma_f32_16x16x32_bf16 v[82:85], v[102:105], v[114:117], v[82:85]
	ds_read_b128 v[102:105], v54 offset:22528
	s_waitcnt vmcnt(0)
	s_waitcnt lgkmcnt(0)
	s_barrier
	s_mov_b32 m0, s10
	s_nop 0
	global_load_lds_dwordx4 v[4:5], off
	v_lshl_add_u64 v[4:5], v[10:11], 0, s[20:21]
	s_mov_b32 m0, s11
	s_nop 0
	global_load_lds_dwordx4 v[4:5], off
	v_lshl_add_u64 v[4:5], v[12:13], 0, s[22:23]
	s_mov_b32 m0, s12
	s_nop 0
	global_load_lds_dwordx4 v[4:5], off
	v_lshl_add_u64 v[4:5], v[10:11], 0, s[48:49]
	s_mov_b32 m0, s13
	s_nop 0
	global_load_lds_dwordx4 v[4:5], off
	v_lshl_add_u64 v[4:5], v[6:7], 0, s[20:21]
	s_mov_b32 m0, s9
	s_nop 0
	global_load_lds_dwordx4 v[52:53], off
	v_mfma_f32_16x16x32_bf16 v[20:23], v[102:105], v[98:101], v[20:23]
	s_mov_b32 m0, s14
	s_nop 0
	global_load_lds_dwordx4 v[4:5], off
	v_lshl_add_u64 v[4:5], v[8:9], 0, s[22:23]
	s_mov_b32 m0, s15
	s_nop 0
	global_load_lds_dwordx4 v[4:5], off
	v_lshl_add_u64 v[4:5], v[6:7], 0, s[48:49]
	s_mov_b32 m0, s16
	s_nop 0
	global_load_lds_dwordx4 v[4:5], off
	ds_read_b128 v[98:101], v14 offset:49152
	v_mfma_f32_16x16x32_bf16 v[28:31], v[102:105], v[106:109], v[28:31]
	ds_read_b128 v[106:109], v15 offset:34816
	s_mov_b64 s[20:21], 0x280
	v_lshl_add_u64 v[4:5], v[12:13], 0, s[20:21]
	v_mfma_f32_16x16x32_bf16 v[36:39], v[102:105], v[110:113], v[36:39]
	ds_read_b128 v[110:113], v15 offset:36864
	v_lshl_add_u64 v[52:53], v[8:9], 0, s[20:21]
	s_mov_b64 s[20:21], 0x1a80
	v_mfma_f32_16x16x32_bf16 v[44:47], v[102:105], v[114:117], v[44:47]
	ds_read_b128 v[102:105], v15 offset:32768
	ds_read_b128 v[114:117], v15 offset:38912
	s_mov_b64 s[22:23], 0x3280
	s_waitcnt lgkmcnt(1)
	v_mfma_f32_16x16x32_bf16 v[24:27], v[98:101], v[102:105], v[24:27]
	v_mfma_f32_16x16x32_bf16 v[32:35], v[98:101], v[106:109], v[32:35]
	v_mfma_f32_16x16x32_bf16 v[40:43], v[98:101], v[110:113], v[40:43]
	s_waitcnt lgkmcnt(0)
	v_mfma_f32_16x16x32_bf16 v[16:19], v[98:101], v[114:117], v[16:19]
	ds_read_b128 v[98:101], v14 offset:51200
	s_waitcnt lgkmcnt(0)
	v_mfma_f32_16x16x32_bf16 v[56:59], v[98:101], v[102:105], v[56:59]
	v_mfma_f32_16x16x32_bf16 v[60:63], v[98:101], v[106:109], v[60:63]
	v_mfma_f32_16x16x32_bf16 v[78:81], v[98:101], v[110:113], v[78:81]
	v_mfma_f32_16x16x32_bf16 v[48:51], v[98:101], v[114:117], v[48:51]
	ds_read_b128 v[98:101], v14 offset:53248
	s_waitcnt lgkmcnt(0)
	v_mfma_f32_16x16x32_bf16 v[86:89], v[98:101], v[102:105], v[86:89]
	v_mfma_f32_16x16x32_bf16 v[90:93], v[98:101], v[106:109], v[90:93]
	v_mfma_f32_16x16x32_bf16 v[94:97], v[98:101], v[110:113], v[94:97]
	v_mfma_f32_16x16x32_bf16 v[82:85], v[98:101], v[114:117], v[82:85]
	ds_read_b128 v[98:101], v14 offset:55296
	s_waitcnt lgkmcnt(0)
	v_mfma_f32_16x16x32_bf16 v[20:23], v[98:101], v[102:105], v[20:23]
	ds_read_b128 v[102:105], v54 offset:49152
	v_mfma_f32_16x16x32_bf16 v[28:31], v[98:101], v[106:109], v[28:31]
	ds_read_b128 v[106:109], v2 offset:34816
	v_mfma_f32_16x16x32_bf16 v[36:39], v[98:101], v[110:113], v[36:39]
	ds_read_b128 v[110:113], v2 offset:36864
	v_mfma_f32_16x16x32_bf16 v[44:47], v[98:101], v[114:117], v[44:47]
	ds_read_b128 v[98:101], v2 offset:32768
	ds_read_b128 v[114:117], v2 offset:38912
	s_waitcnt lgkmcnt(1)
	v_mfma_f32_16x16x32_bf16 v[24:27], v[102:105], v[98:101], v[24:27]
	v_mfma_f32_16x16x32_bf16 v[32:35], v[102:105], v[106:109], v[32:35]
	v_mfma_f32_16x16x32_bf16 v[40:43], v[102:105], v[110:113], v[40:43]
	s_waitcnt lgkmcnt(0)
	v_mfma_f32_16x16x32_bf16 v[16:19], v[102:105], v[114:117], v[16:19]
	ds_read_b128 v[102:105], v54 offset:51200
	s_waitcnt lgkmcnt(0)
	v_mfma_f32_16x16x32_bf16 v[56:59], v[102:105], v[98:101], v[56:59]
	v_mfma_f32_16x16x32_bf16 v[60:63], v[102:105], v[106:109], v[60:63]
	v_mfma_f32_16x16x32_bf16 v[78:81], v[102:105], v[110:113], v[78:81]
	v_mfma_f32_16x16x32_bf16 v[48:51], v[102:105], v[114:117], v[48:51]
	ds_read_b128 v[102:105], v54 offset:53248
	s_waitcnt lgkmcnt(0)
	v_mfma_f32_16x16x32_bf16 v[86:89], v[102:105], v[98:101], v[86:89]
	v_mfma_f32_16x16x32_bf16 v[90:93], v[102:105], v[106:109], v[90:93]
	v_mfma_f32_16x16x32_bf16 v[94:97], v[102:105], v[110:113], v[94:97]
	v_mfma_f32_16x16x32_bf16 v[82:85], v[102:105], v[114:117], v[82:85]
	ds_read_b128 v[102:105], v54 offset:55296
	s_waitcnt vmcnt(0)
	s_waitcnt lgkmcnt(0)
	s_barrier
; template <int MT, class Epi>
; DI void gemm_tile(const u16* __restrict__ X, long ldx, const u16* __restrict__ W, long ldw, int K, char* smem,
;                   int m0, int n0, const Epi& epi, bool pre = false, const u16* Xn = nullptr, const u16* Wn = nullptr) {
;     ...
;   do {
;     asm volatile("s_waitcnt vmcnt(0)" ::: "memory");
;     __syncthreads();
;     if (kt + 1 < nk) GT_DMA((unsigned)((kt + 1) & 1) * 32768u)
;     else if (Xn != nullptr) { xe = Xn + oxe; xo = Xn + oxo; we = Wn + owe; wo = Wn + owo; GT_DMA(0u) }
;     const char* cur = smem + (kt & 1) * 32768;
; #pragma unroll
;     for (int ks = 0; ks < 2; ++ks) {
;       bf16x8 xf[MT], wf[4];
;       const int ch = ((ks * 4 + g) ^ rsw) << 4;
; #pragma unroll
;       for (int i = 0; i < MT; ++i) xf[i] = *(const bf16x8*)(cur + (wm * 16 * MT + i * 16 + lr) * 128 + ch);
; #pragma unroll
;       for (int i = 0; i < 4; ++i) wf[i] = *(const bf16x8*)(cur + 16384 + (wn * 64 + i * 16 + lr) * 128 + ch);
; #pragma unroll
;       for (int nt = 0; nt < 4; ++nt)
; #pragma unroll
;         for (int mt = 0; mt < MT; ++mt)
;           acc[nt][mt] = __builtin_amdgcn_mfma_f32_16x16x32_bf16(wf[nt], xf[mt], acc[nt][mt], 0, 0, 0);
; DI void phase_odd(const Params& p, int o, int sub, char* smem) {
;     ...
;         const int tm = t / 12, tn = t % 12;
;         const int t2 = t + gridDim.x, tm2 = t2 / 12, tn2 = t2 % 12;
;         const bool nx = t2 < 1584;
;         gemm_tile<4>(qn + (size_t)tm * 128 * 384, 384, W + WO_Q + (size_t)tn * 128 * 384, 384, 384, smem, tm * 128, tn * 128, eq, pre,
;                      nx ? qn + (size_t)tm2 * 128 * 384 : nullptr, W + WO_Q + (size_t)tn2 * 128 * 384);
	s_mov_b32 m0, s45
	s_nop 0
	global_load_lds_dwordx4 v[4:5], off
	v_lshl_add_u64 v[4:5], v[10:11], 0, s[20:21]
	s_mov_b32 m0, s44
	s_nop 0
	global_load_lds_dwordx4 v[4:5], off
	v_lshl_add_u64 v[4:5], v[12:13], 0, s[22:23]
	s_mov_b32 m0, s41
	s_nop 0
	global_load_lds_dwordx4 v[4:5], off
	s_mov_b64 s[44:45], 0x4a80
	v_lshl_add_u64 v[4:5], v[10:11], 0, s[44:45]
	s_mov_b32 m0, s34
	s_nop 0
	global_load_lds_dwordx4 v[4:5], off
	s_mov_b32 m0, s40
	s_nop 0
	global_load_lds_dwordx4 v[52:53], off
	v_lshl_add_u64 v[4:5], v[6:7], 0, s[20:21]
	s_mov_b32 m0, s19
	s_nop 0
	global_load_lds_dwordx4 v[4:5], off
	v_lshl_add_u64 v[4:5], v[8:9], 0, s[22:23]
	s_mov_b32 m0, s18
	s_nop 0
	global_load_lds_dwordx4 v[4:5], off
	v_lshl_add_u64 v[4:5], v[6:7], 0, s[44:45]
	s_mov_b32 m0, s17
	s_nop 0
	global_load_lds_dwordx4 v[4:5], off
	ds_read_b128 v[4:7], v14 offset:16384
	ds_read_b128 v[126:129], v2 offset:4096
	v_mfma_f32_16x16x32_bf16 v[20:23], v[102:105], v[98:101], v[20:23]
	ds_read_b128 v[98:101], v15 offset:2048
	ds_read_b128 v[118:121], v2
	ds_read_b128 v[122:125], v2 offset:2048
	v_mfma_f32_16x16x32_bf16 v[28:31], v[102:105], v[106:109], v[28:31]
	ds_read_b128 v[106:109], v15 offset:6144
	v_mfma_f32_16x16x32_bf16 v[36:39], v[102:105], v[110:113], v[36:39]
	v_mfma_f32_16x16x32_bf16 v[8:11], v[102:105], v[114:117], v[44:47]
	ds_read_b128 v[102:105], v15 offset:4096
	s_nop 1
	ds_read_b128 v[44:47], v15
	s_waitcnt lgkmcnt(0)
	v_mfma_f32_16x16x32_bf16 v[24:27], v[4:7], v[44:47], v[24:27]
	v_mfma_f32_16x16x32_bf16 v[32:35], v[4:7], v[98:101], v[32:35]
	v_mfma_f32_16x16x32_bf16 v[40:43], v[4:7], v[102:105], v[40:43]
	v_mfma_f32_16x16x32_bf16 v[110:113], v[4:7], v[106:109], v[16:19]
	ds_read_b128 v[4:7], v14 offset:18432
	s_waitcnt lgkmcnt(0)
	v_mfma_f32_16x16x32_bf16 v[56:59], v[4:7], v[44:47], v[56:59]
	v_mfma_f32_16x16x32_bf16 v[60:63], v[4:7], v[98:101], v[60:63]
	v_mfma_f32_16x16x32_bf16 v[78:81], v[4:7], v[102:105], v[78:81]
	v_mfma_f32_16x16x32_bf16 v[48:51], v[4:7], v[106:109], v[48:51]
	ds_read_b128 v[4:7], v14 offset:20480
	s_waitcnt lgkmcnt(0)
	v_mfma_f32_16x16x32_bf16 v[86:89], v[4:7], v[44:47], v[86:89]
	v_mfma_f32_16x16x32_bf16 v[90:93], v[4:7], v[98:101], v[90:93]
	v_mfma_f32_16x16x32_bf16 v[94:97], v[4:7], v[102:105], v[94:97]
	v_mfma_f32_16x16x32_bf16 v[82:85], v[4:7], v[106:109], v[82:85]
	ds_read_b128 v[4:7], v14 offset:22528
	s_waitcnt lgkmcnt(0)
	v_mfma_f32_16x16x32_bf16 v[114:117], v[4:7], v[44:47], v[20:23]
	s_nop 2
	ds_read_b128 v[18:21], v54 offset:16384
	v_mfma_f32_16x16x32_bf16 v[98:101], v[4:7], v[98:101], v[28:31]
	v_mfma_f32_16x16x32_bf16 v[102:105], v[4:7], v[102:105], v[36:39]
	v_mfma_f32_16x16x32_bf16 v[106:109], v[4:7], v[106:109], v[8:11]
	ds_read_b128 v[2:5], v2 offset:6144
	s_waitcnt lgkmcnt(1)
	v_mfma_f32_16x16x32_bf16 v[10:13], v[18:21], v[122:125], v[32:35]
	s_nop 2
	ds_read_b128 v[34:37], v54 offset:18432
	v_mfma_f32_16x16x32_bf16 v[6:9], v[18:21], v[118:121], v[24:27]
	s_waitcnt lgkmcnt(0)
	v_mfma_f32_16x16x32_bf16 v[22:25], v[34:37], v[118:121], v[56:59]
	v_mfma_f32_16x16x32_bf16 v[26:29], v[34:37], v[122:125], v[60:63]
	v_mfma_f32_16x16x32_bf16 v[30:33], v[34:37], v[126:129], v[78:81]
	v_mfma_f32_16x16x32_bf16 v[34:37], v[34:37], v[2:5], v[48:51]
	s_nop 1
	ds_read_b128 v[78:81], v54 offset:22528
	ds_read_b128 v[50:53], v54 offset:20480
	v_mfma_f32_16x16x32_bf16 v[14:17], v[18:21], v[126:129], v[40:43]
	s_waitcnt vmcnt(0)
	s_waitcnt lgkmcnt(0)
	s_barrier
	v_mfma_f32_16x16x32_bf16 v[18:21], v[18:21], v[2:5], v[110:113]
	v_mfma_f32_16x16x32_bf16 v[38:41], v[50:53], v[118:121], v[86:89]
	v_mfma_f32_16x16x32_bf16 v[42:45], v[50:53], v[122:125], v[90:93]
	v_mfma_f32_16x16x32_bf16 v[46:49], v[50:53], v[126:129], v[94:97]
	v_mfma_f32_16x16x32_bf16 v[50:53], v[50:53], v[2:5], v[82:85]
	v_mfma_f32_16x16x32_bf16 v[54:57], v[78:81], v[118:121], v[114:117]
	v_mfma_f32_16x16x32_bf16 v[58:61], v[78:81], v[122:125], v[98:101]
	v_mfma_f32_16x16x32_bf16 v[62:65], v[78:81], v[126:129], v[102:105]
	v_mfma_f32_16x16x32_bf16 v[2:5], v[78:81], v[2:5], v[106:109]
	s_cbranch_scc1 .LBB0_110
	s_mul_i32 s8, s8, 12
	s_sub_i32 s7, s7, s8
	s_mul_i32 s18, s7, 0xc000
	s_ashr_i32 s19, s18, 31
	s_lshl_b64 s[18:19], s[18:19], 1
	v_readlane_b32 s20, v252, 29
	v_readlane_b32 s21, v252, 30
	s_add_u32 s18, s20, s18
	s_addc_u32 s19, s21, s19
	v_lshl_add_u64 v[78:79], s[18:19], 0, v[68:69]
	v_lshl_add_u64 v[80:81], s[18:19], 0, v[66:67]
	v_lshl_add_u64 v[68:69], s[42:43], 0, v[68:69]
	v_lshl_add_u64 v[66:67], s[42:43], 0, v[66:67]
	s_mov_b32 m0, s10
	s_nop 0
	global_load_lds_dwordx4 v[66:67], off
	s_mov_b64 s[18:19], 0x1800
	v_lshl_add_u64 v[82:83], v[68:69], 0, s[18:19]
	s_mov_b32 m0, s11
	s_nop 0
	global_load_lds_dwordx4 v[82:83], off
	s_mov_b64 s[10:11], 0x3000
	v_lshl_add_u64 v[66:67], v[66:67], 0, s[10:11]
	s_mov_b32 m0, s12
	s_nop 0
	global_load_lds_dwordx4 v[66:67], off
	s_mov_b64 s[20:21], 0x4800
	v_lshl_add_u64 v[66:67], v[68:69], 0, s[20:21]
	s_mov_b32 m0, s13
	s_nop 0
	global_load_lds_dwordx4 v[66:67], off
	v_lshl_add_u64 v[66:67], v[78:79], 0, s[18:19]
	s_mov_b32 m0, s9
	s_nop 0
	global_load_lds_dwordx4 v[80:81], off
	s_nop 0
	s_mov_b32 m0, s14
	s_nop 0
	global_load_lds_dwordx4 v[66:67], off
	v_lshl_add_u64 v[66:67], v[80:81], 0, s[10:11]
	s_mov_b32 m0, s15
	s_nop 0
	global_load_lds_dwordx4 v[66:67], off
	v_lshl_add_u64 v[66:67], v[78:79], 0, s[20:21]
	s_mov_b32 m0, s16
	s_nop 0
	global_load_lds_dwordx4 v[66:67], off

; DI int get_bid() { int b = blockIdx.x; asm volatile("" : "+s"(b)); return b; }
; template <int MT, class Epi>
; DI void gemm_tile(const u16* __restrict__ X, long ldx, const u16* __restrict__ W, long ldw, int K, char* smem,
;                   int m0, int n0, const Epi& epi, bool pre = false, const u16* Xn = nullptr, const u16* Wn = nullptr) {
;     ...
;   const int wu = __builtin_amdgcn_readfirstlane(wave);
;   const unsigned sbase = (unsigned)__builtin_amdgcn_readfirstlane((int)(unsigned)(size_t)smem);
;   const int r8 = lane >> 3, c0 = (lane & 7) ^ (r8 >> 1);
;   const long oxe = (long)(wu * MT * 8 + r8) * ldx + (c0 << 3), oxo = (long)(wu * MT * 8 + r8) * ldx + ((c0 ^ 4) << 3);
;   const long owe = (long)(wu * 32 + r8) * ldw + (c0 << 3), owo = (long)(wu * 32 + r8) * ldw + ((c0 ^ 4) << 3);
;   const u16 *xe = X + oxe, *xo = X + oxo, *we = W + owe, *wo = W + owo;
;   const long ldx8 = 8 * ldx, ldw8 = 8 * ldw;
;   const unsigned xdst = sbase + wu * MT * 1024, wdst = sbase + 16384 + wu * 4096;
;     ...
;   if (!pre) {
;     __syncthreads();
;     GT_DMA(0u)
; DI void phase_odd(const Params& p, int o, int sub, char* smem) {
;     ...
;     for (int t = get_bid(); t < 132 * 14; t += gridDim.x) {
;       const int tm = t / 14, tn = t % 14;
;       const int t2 = t + gridDim.x, tm2 = t2 / 14, tn2 = t2 % 14;
;       const bool nx = t2 < 132 * 14;
;       gemm_tile<4>(hbuf + (size_t)tm * 128 * 1024, 1024, W + WO_IN + (size_t)tn * 128 * 1024, 1024, 1024, smem, tm * 128, tn * 128, epi, pre,
;                    nx ? hbuf + (size_t)tm2 * 128 * 1024 : nullptr, W + WO_IN + (size_t)tn2 * 128 * 1024);
.LBB0_141:
	s_mul_hi_i32 s5, s4, 0x92492493
	s_add_i32 s5, s5, s4
	s_lshr_b32 s6, s5, 31
	s_ashr_i32 s5, s5, 3
	s_add_i32 s38, s5, s6
	v_mov_b32_e32 v5, v185
	s_mul_i32 s5, s38, 14
	s_sub_i32 s42, s4, s5
	v_ashrrev_i32_e32 v6, 6, v5
	v_bfe_u32 v4, v5, 3, 3
	v_readfirstlane_b32 s5, v6
	s_lshl_b32 s7, s5, 5
	v_bfe_u32 v1, v5, 4, 2
	v_or_b32_e32 v8, s7, v4
	v_bitop3_b32 v3, v1, v5, 7 bitop3:0x78
	v_ashrrev_i32_e32 v9, 31, v8
	v_lshlrev_b64 v[8:9], 10, v[8:9]
	v_lshlrev_b32_e32 v7, 3, v3
	s_ashr_i32 s39, s38, 31
	s_ashr_i32 s43, s42, 31
	v_or_b32_e32 v10, v8, v7
	v_mov_b32_e32 v11, v9
	v_bitop3_b32 v8, v8, v7, 32 bitop3:0xf6
	s_lshl_b32 s5, s5, 12
	s_lshl_b64 s[40:41], s[38:39], 18
	s_lshl_b64 s[44:45], s[42:43], 18
	v_mov_b32_e32 v2, v183
	s_add_i32 s6, s5, 0x4000
	s_and_b64 vcc, exec, s[46:47]
	v_lshlrev_b64 v[68:69], 1, v[10:11]
	v_lshlrev_b64 v[66:67], 1, v[8:9]
	s_cbranch_vccnz .LBB0_143
	s_add_u32 s8, s0, s40
	v_readlane_b32 s12, v255, 5
	s_addc_u32 s9, s1, s41
	v_readlane_b32 s16, v255, 9
	v_readlane_b32 s17, v255, 10
	s_add_u32 s10, s16, s44
	s_addc_u32 s11, s17, s45
	v_readlane_b32 s13, v255, 6
	v_lshl_add_u64 v[8:9], s[8:9], 0, v[68:69]
	v_lshl_add_u64 v[10:11], s[8:9], 0, v[66:67]
	v_lshl_add_u64 v[12:13], s[10:11], 0, v[68:69]
	v_lshl_add_u64 v[14:15], s[10:11], 0, v[66:67]
	s_barrier
	s_mov_b32 m0, s5
	s_nop 0
	global_load_lds_dwordx4 v[8:9], off
	s_mov_b64 s[10:11], 0x4000
	v_readlane_b32 s14, v255, 7
	v_readlane_b32 s15, v255, 8
	v_lshl_add_u64 v[16:17], v[10:11], 0, s[10:11]
	s_add_i32 s8, s5, 0x400
	s_mov_b32 m0, s8
	s_nop 0
	global_load_lds_dwordx4 v[16:17], off
	s_mov_b64 s[12:13], 0x8000
	v_lshl_add_u64 v[8:9], v[8:9], 0, s[12:13]
	s_add_i32 s8, s5, 0x800
	s_mov_b32 m0, s8
	s_nop 0
	global_load_lds_dwordx4 v[8:9], off
	s_mov_b64 s[14:15], 0xc000
	v_lshl_add_u64 v[8:9], v[10:11], 0, s[14:15]
	s_add_i32 s8, s5, 0xc00
	s_mov_b32 m0, s8
	s_nop 0
	global_load_lds_dwordx4 v[8:9], off
	s_mov_b32 m0, s6
	s_nop 0
	global_load_lds_dwordx4 v[12:13], off
	v_lshl_add_u64 v[8:9], v[14:15], 0, s[10:11]
	s_add_i32 s8, s5, 0x4400
	s_mov_b32 m0, s8
	s_nop 0
	global_load_lds_dwordx4 v[8:9], off
	v_lshl_add_u64 v[8:9], v[12:13], 0, s[12:13]
	s_add_i32 s8, s5, 0x4800
	s_mov_b32 m0, s8
	s_nop 0
	global_load_lds_dwordx4 v[8:9], off
	v_lshl_add_u64 v[8:9], v[14:15], 0, s[14:15]
	s_add_i32 s8, s5, 0x4c00
	s_mov_b32 m0, s8
	s_nop 0
	global_load_lds_dwordx4 v[8:9], off
	v_readlane_b32 s18, v255, 11
	v_readlane_b32 s19, v255, 12

; DI int get_bid() { int b = blockIdx.x; asm volatile("" : "+s"(b)); return b; }
; template <int MT, class Epi>
; DI void gemm_tile(const u16* __restrict__ X, long ldx, const u16* __restrict__ W, long ldw, int K, char* smem,
;                   int m0, int n0, const Epi& epi, bool pre = false, const u16* Xn = nullptr, const u16* Wn = nullptr) {
;     ...
;   do {
;     asm volatile("s_waitcnt vmcnt(0)" ::: "memory");
;     __syncthreads();
;     if (kt + 1 < nk) GT_DMA((unsigned)((kt + 1) & 1) * 32768u)
;     else if (Xn != nullptr) { xe = Xn + oxe; xo = Xn + oxo; we = Wn + owe; wo = Wn + owo; GT_DMA(0u) }
;     const char* cur = smem + (kt & 1) * 32768;
; #pragma unroll
;     for (int ks = 0; ks < 2; ++ks) {
;       bf16x8 xf[MT], wf[4];
;       const int ch = ((ks * 4 + g) ^ rsw) << 4;
; #pragma unroll
;       for (int i = 0; i < MT; ++i) xf[i] = *(const bf16x8*)(cur + (wm * 16 * MT + i * 16 + lr) * 128 + ch);
; #pragma unroll
;       for (int i = 0; i < 4; ++i) wf[i] = *(const bf16x8*)(cur + 16384 + (wn * 64 + i * 16 + lr) * 128 + ch);
; #pragma unroll
;       for (int nt = 0; nt < 4; ++nt)
; #pragma unroll
;         for (int mt = 0; mt < MT; ++mt)
;           acc[nt][mt] = __builtin_amdgcn_mfma_f32_16x16x32_bf16(wf[nt], xf[mt], acc[nt][mt], 0, 0, 0);
; DI void phase_odd(const Params& p, int o, int sub, char* smem) {
;     ...
;     for (int t = get_bid(); t < 132 * 14; t += gridDim.x) {
;       const int tm = t / 14, tn = t % 14;
;       const int t2 = t + gridDim.x, tm2 = t2 / 14, tn2 = t2 % 14;
;       const bool nx = t2 < 132 * 14;
;       gemm_tile<4>(hbuf + (size_t)tm * 128 * 1024, 1024, W + WO_IN + (size_t)tn * 128 * 1024, 1024, 1024, smem, tm * 128, tn * 128, epi, pre,
;                    nx ? hbuf + (size_t)tm2 * 128 * 1024 : nullptr, W + WO_IN + (size_t)tn2 * 128 * 1024);
.LBB0_144:
	s_add_i32 s7, s8, 0x8000
	v_lshl_add_u64 v[124:125], v[76:77], 0, s[40:41]
	s_and_b32 s9, s7, 0x8000
	v_lshl_add_u64 v[122:123], v[74:75], 0, s[40:41]
	v_lshl_add_u64 v[126:127], v[124:125], 0, s[74:75]
	s_waitcnt vmcnt(0)
	s_barrier
	s_and_b32 s8, s8, 0x8000
	v_or_b32_e32 v162, s8, v85
	v_add3_u32 v163, v162, v81, v82
	v_add3_u32 v164, v162, v84, v82
	v_or_b32_e32 v165, s8, v83
	v_add3_u32 v166, v165, v81, v82
	v_add3_u32 v167, v165, v84, v82
	ds_read_b128 v[86:89], v163
	ds_read_b128 v[90:93], v163 offset:2048
	ds_read_b128 v[94:97], v163 offset:4096
	ds_read_b128 v[98:101], v163 offset:6144
	ds_read_b128 v[102:105], v164 offset:16384
	ds_read_b128 v[106:109], v164 offset:18432
	ds_read_b128 v[110:113], v164 offset:20480
	ds_read_b128 v[114:117], v164 offset:22528
	ds_read_b128 v[130:133], v166
	ds_read_b128 v[134:137], v166 offset:2048
	ds_read_b128 v[138:141], v166 offset:4096
	ds_read_b128 v[142:145], v166 offset:6144
	ds_read_b128 v[146:149], v167 offset:16384
	ds_read_b128 v[150:153], v167 offset:18432
	ds_read_b128 v[154:157], v167 offset:20480
	ds_read_b128 v[158:161], v167 offset:22528
	s_add_i32 s10, s9, s5
	s_mov_b32 m0, s10
	s_nop 0
	global_load_lds_dwordx4 v[126:127], off
	v_lshl_add_u64 v[126:127], v[122:123], 0, s[94:95]
	s_add_i32 s11, s10, 0x400
	s_mov_b32 m0, s11
	s_nop 0
	global_load_lds_dwordx4 v[126:127], off
	v_lshl_add_u64 v[124:125], v[124:125], 0, s[76:77]
	s_add_i32 s11, s10, 0x800
	s_mov_b32 m0, s11
	s_nop 0
	global_load_lds_dwordx4 v[124:125], off
	v_lshl_add_u64 v[120:121], v[72:73], 0, s[40:41]
	v_lshl_add_u64 v[122:123], v[122:123], 0, s[54:55]
	s_addk_i32 s10, 0xc00
	s_mov_b32 m0, s10
	s_nop 0
	global_load_lds_dwordx4 v[122:123], off
	v_lshl_add_u64 v[118:119], v[70:71], 0, s[40:41]
	v_lshl_add_u64 v[128:129], v[120:121], 0, s[28:29]
	s_add_i32 s9, s9, s6
	s_mov_b32 m0, s9
	s_nop 0
	global_load_lds_dwordx4 v[128:129], off
	v_lshl_add_u64 v[122:123], v[118:119], 0, s[94:95]
	s_add_i32 s10, s9, 0x400
	s_mov_b32 m0, s10
	s_nop 0
	global_load_lds_dwordx4 v[122:123], off
	v_lshl_add_u64 v[120:121], v[120:121], 0, s[78:79]
	s_add_i32 s10, s9, 0x800
	s_mov_b32 m0, s10
	s_nop 0
	global_load_lds_dwordx4 v[120:121], off
	v_lshl_add_u64 v[118:119], v[118:119], 0, s[54:55]
	s_addk_i32 s9, 0xc00
	s_mov_b32 m0, s9
	s_nop 0
	global_load_lds_dwordx4 v[118:119], off
	s_mov_b32 s8, s7
	s_add_u32 s40, s40, 0x80
	s_addc_u32 s41, s41, 0
	s_cmpk_lg_i32 s40, 0x780
	s_waitcnt lgkmcnt(11)
	v_mfma_f32_16x16x32_bf16 v[62:65], v[102:105], v[86:89], v[62:65]
	v_mfma_f32_16x16x32_bf16 v[58:61], v[102:105], v[90:93], v[58:61]
	v_mfma_f32_16x16x32_bf16 v[54:57], v[102:105], v[94:97], v[54:57]
	v_mfma_f32_16x16x32_bf16 v[50:53], v[102:105], v[98:101], v[50:53]
	s_waitcnt lgkmcnt(10)
	v_mfma_f32_16x16x32_bf16 v[34:37], v[106:109], v[98:101], v[34:37]
	s_waitcnt lgkmcnt(9)
	v_mfma_f32_16x16x32_bf16 v[18:21], v[110:113], v[98:101], v[18:21]
	s_waitcnt lgkmcnt(8)
	v_mfma_f32_16x16x32_bf16 v[14:17], v[114:117], v[86:89], v[14:17]
	v_mfma_f32_16x16x32_bf16 v[10:13], v[114:117], v[90:93], v[10:13]
	v_mfma_f32_16x16x32_bf16 v[6:9], v[114:117], v[94:97], v[6:9]
	v_mfma_f32_16x16x32_bf16 v[2:5], v[114:117], v[98:101], v[2:5]
	v_mfma_f32_16x16x32_bf16 v[46:49], v[106:109], v[86:89], v[46:49]
	v_mfma_f32_16x16x32_bf16 v[42:45], v[106:109], v[90:93], v[42:45]
	v_mfma_f32_16x16x32_bf16 v[38:41], v[106:109], v[94:97], v[38:41]
	v_mfma_f32_16x16x32_bf16 v[30:33], v[110:113], v[86:89], v[30:33]
	v_mfma_f32_16x16x32_bf16 v[26:29], v[110:113], v[90:93], v[26:29]
	v_mfma_f32_16x16x32_bf16 v[22:25], v[110:113], v[94:97], v[22:25]
	s_waitcnt lgkmcnt(3)
	v_mfma_f32_16x16x32_bf16 v[62:65], v[146:149], v[130:133], v[62:65]
	v_mfma_f32_16x16x32_bf16 v[58:61], v[146:149], v[134:137], v[58:61]
	v_mfma_f32_16x16x32_bf16 v[54:57], v[146:149], v[138:141], v[54:57]
	v_mfma_f32_16x16x32_bf16 v[50:53], v[146:149], v[142:145], v[50:53]
	s_waitcnt lgkmcnt(2)
	v_mfma_f32_16x16x32_bf16 v[46:49], v[150:153], v[130:133], v[46:49]
	v_mfma_f32_16x16x32_bf16 v[42:45], v[150:153], v[134:137], v[42:45]
	v_mfma_f32_16x16x32_bf16 v[38:41], v[150:153], v[138:141], v[38:41]
	v_mfma_f32_16x16x32_bf16 v[34:37], v[150:153], v[142:145], v[34:37]
	s_waitcnt lgkmcnt(1)
	v_mfma_f32_16x16x32_bf16 v[30:33], v[154:157], v[130:133], v[30:33]
	v_mfma_f32_16x16x32_bf16 v[26:29], v[154:157], v[134:137], v[26:29]
	v_mfma_f32_16x16x32_bf16 v[22:25], v[154:157], v[138:141], v[22:25]
	v_mfma_f32_16x16x32_bf16 v[18:21], v[154:157], v[142:145], v[18:21]
	s_waitcnt lgkmcnt(0)
	v_mfma_f32_16x16x32_bf16 v[14:17], v[158:161], v[130:133], v[14:17]
	v_mfma_f32_16x16x32_bf16 v[10:13], v[158:161], v[134:137], v[10:13]
	v_mfma_f32_16x16x32_bf16 v[6:9], v[158:161], v[138:141], v[6:9]
	v_mfma_f32_16x16x32_bf16 v[2:5], v[158:161], v[142:145], v[2:5]
	s_cbranch_scc1 .LBB0_144
	v_readlane_b32 s8, v255, 5
	v_readlane_b32 s14, v255, 11
	s_add_i32 s4, s4, s14
	s_mul_hi_i32 s7, s4, 0x92492493
	s_add_i32 s7, s7, s4
	s_lshr_b32 s8, s7, 31
	s_ashr_i32 s7, s7, 3
	s_add_i32 s46, s7, s8
	s_cmpk_gt_i32 s4, 0x737
	v_readlane_b32 s9, v255, 6
	s_cselect_b64 s[40:41], -1, 0
	s_ashr_i32 s47, s46, 31
	s_lshl_b64 s[8:9], s[46:47], 18
	s_add_u32 s7, s0, s8
	s_addc_u32 s8, s1, s9
	s_cmpk_lt_i32 s4, 0x738
	s_waitcnt vmcnt(0)
	s_cselect_b32 s45, s8, 0
	s_cselect_b32 s44, s7, 0
	v_readlane_b32 s12, v255, 9
	v_readlane_b32 s13, v255, 10
	s_cmp_eq_u64 s[44:45], 0
	v_readlane_b32 s10, v255, 7
	v_readlane_b32 s11, v255, 8
	v_readlane_b32 s15, v255, 12
	s_barrier
	s_cbranch_scc1 .LBB0_147
	s_mul_i32 s7, s46, 14
	s_sub_i32 s8, s4, s7
	s_ashr_i32 s9, s8, 31
	s_lshl_b64 s[8:9], s[8:9], 18
	s_add_u32 s8, s12, s8
	s_addc_u32 s9, s13, s9
	v_lshl_add_u64 v[70:71], s[44:45], 0, v[68:69]
	v_lshl_add_u64 v[72:73], s[8:9], 0, v[66:67]
	v_lshl_add_u64 v[66:67], s[44:45], 0, v[66:67]
	s_mov_b32 m0, s5
	s_nop 0
	global_load_lds_dwordx4 v[70:71], off
	s_mov_b64 s[10:11], 0x4000
	v_lshl_add_u64 v[68:69], s[8:9], 0, v[68:69]
	v_lshl_add_u64 v[74:75], v[66:67], 0, s[10:11]
	s_add_i32 s7, s5, 0x400
	s_mov_b32 m0, s7
	s_nop 0
	global_load_lds_dwordx4 v[74:75], off
	s_mov_b64 s[12:13], 0x8000
	v_lshl_add_u64 v[70:71], v[70:71], 0, s[12:13]
	s_add_i32 s7, s5, 0x800
	s_mov_b32 m0, s7
	s_nop 0
	global_load_lds_dwordx4 v[70:71], off
	s_mov_b64 s[14:15], 0xc000
	v_lshl_add_u64 v[66:67], v[66:67], 0, s[14:15]
	s_add_i32 s7, s5, 0xc00
	s_mov_b32 m0, s7
	s_nop 0
	global_load_lds_dwordx4 v[66:67], off
	s_mov_b32 m0, s6
	s_nop 0
	global_load_lds_dwordx4 v[68:69], off
	v_lshl_add_u64 v[66:67], v[72:73], 0, s[10:11]
	s_add_i32 s6, s5, 0x4400
	s_mov_b32 m0, s6
	s_nop 0
	global_load_lds_dwordx4 v[66:67], off
	v_lshl_add_u64 v[66:67], v[68:69], 0, s[12:13]
	s_add_i32 s6, s5, 0x4800
	s_mov_b32 m0, s6
	s_nop 0
	global_load_lds_dwordx4 v[66:67], off
	v_lshl_add_u64 v[66:67], v[72:73], 0, s[14:15]
	s_addk_i32 s5, 0x4c00
	s_mov_b32 m0, s5
	s_nop 0
	global_load_lds_dwordx4 v[66:67], off

; DI float zero_f() { float z = 0.f; asm volatile("" : "+v"(z)); return z; }
; template <int MT, class Epi>
; DI void gemm_tile(const u16* __restrict__ X, long ldx, const u16* __restrict__ W, long ldw, int K, char* smem,
;                   int m0, int n0, const Epi& epi, bool pre = false, const u16* Xn = nullptr, const u16* Wn = nullptr) {
;     ...
;   f32x4 acc[4][MT];
;   { const float z = zero_f();
; #pragma unroll
;   for (int a = 0; a < 4; ++a)
; #pragma unroll
;     for (int b = 0; b < MT; ++b) acc[a][b] = (f32x4){z, z, z, z}; }
;   const int wu = __builtin_amdgcn_readfirstlane(wave);
;   const unsigned sbase = (unsigned)__builtin_amdgcn_readfirstlane((int)(unsigned)(size_t)smem);
;   const int r8 = lane >> 3, c0 = (lane & 7) ^ (r8 >> 1);
;   const long oxe = (long)(wu * MT * 8 + r8) * ldx + (c0 << 3), oxo = (long)(wu * MT * 8 + r8) * ldx + ((c0 ^ 4) << 3);
;   const long owe = (long)(wu * 32 + r8) * ldw + (c0 << 3), owo = (long)(wu * 32 + r8) * ldw + ((c0 ^ 4) << 3);
;   const u16 *xe = X + oxe, *xo = X + oxo, *we = W + owe, *wo = W + owo;
;   const long ldx8 = 8 * ldx, ldw8 = 8 * ldw;
;   const unsigned xdst = sbase + wu * MT * 1024, wdst = sbase + 16384 + wu * 4096;
;     ...
;   if (!pre) {
;     __syncthreads();
;     GT_DMA(0u)
; DI void phase_even(const Params& p, int e, int sub, char* smem) {
;     ...
;         const int u = t - 512, tm = u >> 3, tn = u & 7, m0 = M_PROMPT + tm * 64;
;         gemm_tile<2>(gbuf + (size_t)m0 * 2048, 2048, W + WE_OUT + (size_t)tn * 128 * 2048, 2048, 2048, smem, m0, tn * 128, epi);
.LBB0_286:
	s_and_b32 s7, s4, 7
	s_lshl_b32 s34, s7, 19
	s_cmpk_gt_i32 s6, 0x1ff
	s_mov_b64 s[38:39], -1
	s_cbranch_scc0 .LBB0_290
	s_bfe_u32 s8, s5, 0x190006
	s_mov_b32 s9, s35
	s_lshl_b64 s[12:13], s[8:9], 18
	s_lshl_b32 s8, s6, 3
	s_and_b32 s8, s8, 0x7fffffc0
	s_add_i32 s38, s8, 0x3000
	s_mov_b32 s39, s35
	s_and_b32 s7, s6, 7
	s_lshl_b64 s[8:9], s[38:39], 12
	v_readlane_b32 s10, v252, 35
	v_mov_b32_e32 v3, v185
	v_readlane_b32 s11, v252, 36
	s_add_u32 s8, s10, s8
	s_addc_u32 s9, s11, s9
	v_ashrrev_i32_e32 v4, 6, v3
	v_bfe_u32 v6, v3, 3, 3
	v_readfirstlane_b32 s11, v4
	v_and_b32_e32 v1, 1, v4
	v_bfe_u32 v43, v3, 4, 2
	v_lshl_or_b32 v4, s11, 4, v6
	v_bitop3_b32 v10, v43, v3, 7 bitop3:0x78
	v_ashrrev_i32_e32 v5, 31, v4
	s_lshl_b32 s10, s7, 19
	v_readlane_b32 s16, v252, 39
	v_lshl_or_b32 v6, s11, 5, v6
	v_lshlrev_b64 v[4:5], 12, v[4:5]
	v_lshlrev_b32_e32 v182, 4, v10
	v_readlane_b32 s17, v252, 40
	s_add_u32 s14, s16, s10
	v_mov_b32_e32 v2, v183
	v_ashrrev_i32_e32 v7, 31, v6
	v_lshl_add_u64 v[8:9], s[8:9], 0, v[4:5]
	v_xor_b32_e32 v12, 64, v182
	v_mov_b32_e32 v13, v183
	s_addc_u32 s15, s17, 0
	v_lshl_add_u64 v[10:11], v[8:9], 0, v[182:183]
	v_lshl_add_u64 v[8:9], v[8:9], 0, v[12:13]
	v_lshlrev_b64 v[6:7], 12, v[6:7]
	s_lshl_b32 s8, s11, 11
	s_barrier
	s_mov_b32 m0, s8
	s_nop 0
	global_load_lds_dwordx4 v[10:11], off
	s_mov_b64 s[18:19], 0x8000
	v_lshl_add_u64 v[14:15], s[14:15], 0, v[6:7]
	s_lshl_b32 s11, s11, 12
	v_lshl_add_u64 v[8:9], v[8:9], 0, s[18:19]
	s_or_b32 s9, s8, 0x400
	s_mov_b32 m0, s9
	s_nop 0
	global_load_lds_dwordx4 v[8:9], off
	v_lshl_add_u64 v[16:17], v[14:15], 0, v[182:183]
	v_lshl_add_u64 v[8:9], v[14:15], 0, v[12:13]
	s_add_i32 s9, s11, 0x4000
	s_mov_b32 m0, s9
	s_nop 0
	global_load_lds_dwordx4 v[16:17], off
	v_lshl_add_u64 v[10:11], v[8:9], 0, s[18:19]
	s_add_i32 s14, s11, 0x4400
	s_mov_b32 m0, s14
	s_nop 0
	global_load_lds_dwordx4 v[10:11], off
	s_mov_b64 s[14:15], 0x10000
	v_lshl_add_u64 v[10:11], v[16:17], 0, s[14:15]
	s_add_i32 s14, s11, 0x4800
	s_mov_b32 m0, s14
	s_nop 0
	global_load_lds_dwordx4 v[10:11], off
	s_mov_b64 s[14:15], 0x18000
	v_lshrrev_b32_e32 v18, 1, v3
	v_lshl_add_u64 v[8:9], v[8:9], 0, s[14:15]
	s_addk_i32 s11, 0x4c00
	s_mov_b32 m0, s11
	s_nop 0
	global_load_lds_dwordx4 v[8:9], off
	v_bitop3_b32 v8, v43, v18, 7 bitop3:0x78
	v_lshl_add_u64 v[6:7], s[34:35], 0, v[6:7]
	v_lshlrev_b32_e32 v49, 4, v8
	v_lshl_add_u64 v[8:9], v[6:7], 0, v[12:13]
	v_lshl_add_u64 v[34:35], s[16:17], 0, v[8:9]
	v_readlane_b32 s16, v255, 5
	v_lshl_add_u64 v[6:7], v[6:7], 0, v[182:183]
	v_readlane_b32 s20, v255, 9
	v_readlane_b32 s21, v255, 10
	v_lshl_add_u64 v[4:5], s[12:13], 0, v[4:5]
	v_readlane_b32 s12, v254, 63
	v_lshl_add_u64 v[36:37], s[20:21], 0, v[6:7]
	v_bitop3_b32 v6, v4, v182, 64 bitop3:0xf6
	v_mov_b32_e32 v7, v5
	v_readlane_b32 s13, v255, 0
	v_and_b32_e32 v42, 15, v3
	v_ashrrev_i32_e32 v44, 7, v3
	v_bfe_u32 v3, v3, 1, 3
	v_lshl_add_u64 v[38:39], s[12:13], 0, v[6:7]
	v_readlane_b32 s12, v255, 1
	v_bitop3_b32 v3, v43, v3, 4 bitop3:0x36
	v_readlane_b32 s17, v255, 6
	v_readlane_b32 s18, v255, 7
	v_readlane_b32 s19, v255, 8
	v_or_b32_e32 v4, v4, v182
	v_readlane_b32 s13, v255, 2
	s_mov_b32 s10, 0
	v_lshlrev_b32_e32 v48, 12, v1
	v_lshlrev_b32_e32 v45, 7, v42
	v_lshlrev_b32_e32 v46, 13, v44
	v_lshlrev_b32_e32 v47, 4, v3
	v_lshl_add_u64 v[40:41], s[12:13], 0, v[4:5]
	s_mov_b64 s[40:41], 0
	v_mov_b32_e32 v3, v2
	v_mov_b32_e32 v4, v2
	v_mov_b32_e32 v5, v2
	v_mov_b32_e32 v6, v2
	v_mov_b32_e32 v7, v2
	v_mov_b32_e32 v8, v2
	v_mov_b32_e32 v9, v2
	v_mov_b32_e32 v10, v2
	v_mov_b32_e32 v11, v2
	v_mov_b32_e32 v12, v2
	v_mov_b32_e32 v13, v2
	v_mov_b32_e32 v14, v2
	v_mov_b32_e32 v15, v2
	v_mov_b32_e32 v16, v2
	v_mov_b32_e32 v17, v2
	v_mov_b32_e32 v18, v2
	v_mov_b32_e32 v19, v2
	v_mov_b32_e32 v20, v2
	v_mov_b32_e32 v21, v2
	v_mov_b32_e32 v22, v2
	v_mov_b32_e32 v23, v2
	v_mov_b32_e32 v24, v2
	v_mov_b32_e32 v25, v2
	v_mov_b32_e32 v26, v2
	v_mov_b32_e32 v27, v2
	v_mov_b32_e32 v28, v2
	v_mov_b32_e32 v29, v2
	v_mov_b32_e32 v30, v2
	v_mov_b32_e32 v31, v2
	v_mov_b32_e32 v32, v2
	v_mov_b32_e32 v33, v2
	s_mov_b64 s[16:17], 0xa00080
	s_mov_b64 s[18:19], 0xa10080
	s_mov_b64 s[20:21], 0x18080
	v_readlane_b32 s22, v255, 11
	v_readlane_b32 s23, v255, 12
.LBB0_288:
	s_add_i32 s11, s10, 0x8000
	s_and_b32 s12, s11, 0x8000
	v_lshl_add_u64 v[54:55], v[38:39], 0, s[40:41]
	v_lshl_add_u64 v[56:57], v[40:41], 0, s[40:41]
	s_waitcnt vmcnt(0)
	s_barrier
; DI void st_bf4(u16* p, float a, float b, float c, float d) { *(uint2*)p = make_uint2(pk2(a, b), pk2(c, d)); }
; template <int MT, class Epi>
; DI void gemm_tile(const u16* __restrict__ X, long ldx, const u16* __restrict__ W, long ldw, int K, char* smem,
;                   int m0, int n0, const Epi& epi, bool pre = false, const u16* Xn = nullptr, const u16* Wn = nullptr) {
;     ...
;   do {
;     asm volatile("s_waitcnt vmcnt(0)" ::: "memory");
;     __syncthreads();
;     if (kt + 1 < nk) GT_DMA((unsigned)((kt + 1) & 1) * 32768u)
;     else if (Xn != nullptr) { xe = Xn + oxe; xo = Xn + oxo; we = Wn + owe; wo = Wn + owo; GT_DMA(0u) }
;     const char* cur = smem + (kt & 1) * 32768;
; #pragma unroll
;     for (int ks = 0; ks < 2; ++ks) {
;       bf16x8 xf[MT], wf[4];
;       const int ch = ((ks * 4 + g) ^ rsw) << 4;
; #pragma unroll
;       for (int i = 0; i < MT; ++i) xf[i] = *(const bf16x8*)(cur + (wm * 16 * MT + i * 16 + lr) * 128 + ch);
; #pragma unroll
;       for (int i = 0; i < 4; ++i) wf[i] = *(const bf16x8*)(cur + 16384 + (wn * 64 + i * 16 + lr) * 128 + ch);
; #pragma unroll
;       for (int nt = 0; nt < 4; ++nt)
; #pragma unroll
;         for (int mt = 0; mt < MT; ++mt)
;           acc[nt][mt] = __builtin_amdgcn_mfma_f32_16x16x32_bf16(wf[nt], xf[mt], acc[nt][mt], 0, 0, 0);
;     }
;   } while (++kt < nk);
;     ...
;   epi.run(acc, m0 + wm * 16 * MT + lr, n0 + wn * 64 + 4 * g);
;   template <int NT, int MT> DI void run(f32x4 (&acc)[NT][MT], int mb, int nb) const {
; #pragma unroll
;     for (int nt = 0; nt < NT; ++nt)
; #pragma unroll
;       for (int mt = 0; mt < MT; ++mt) {
;         f32x4 v = acc[nt][mt];
;         st_bf4(C + (size_t)(mb + mt * 16) * ldc + nb + nt * 16, v[0], v[1], v[2], v[3]);
;       }
	s_add_i32 s13, s12, s8
	s_mov_b32 m0, s13
	s_nop 0
	global_load_lds_dwordx4 v[56:57], off
	v_lshl_add_u64 v[52:53], v[36:37], 0, s[40:41]
	v_lshl_add_u64 v[54:55], v[54:55], 0, s[78:79]
	s_addk_i32 s13, 0x400
	s_mov_b32 m0, s13
	s_nop 0
	global_load_lds_dwordx4 v[54:55], off
	v_lshl_add_u64 v[50:51], v[34:35], 0, s[40:41]
	v_lshl_add_u64 v[58:59], v[52:53], 0, s[16:17]
	s_add_i32 s12, s12, s9
	s_mov_b32 m0, s12
	s_nop 0
	global_load_lds_dwordx4 v[58:59], off
	v_lshl_add_u64 v[54:55], v[50:51], 0, s[78:79]
	s_add_i32 s13, s12, 0x400
	s_mov_b32 m0, s13
	s_nop 0
	global_load_lds_dwordx4 v[54:55], off
	s_and_b32 s10, s10, 0x8000
	v_lshl_add_u64 v[52:53], v[52:53], 0, s[18:19]
	s_add_i32 s13, s12, 0x800
	s_mov_b32 m0, s13
	s_nop 0
	global_load_lds_dwordx4 v[52:53], off
	v_or_b32_e32 v58, s10, v49
	v_lshl_add_u64 v[50:51], v[50:51], 0, s[20:21]
	s_addk_i32 s12, 0xc00
	s_mov_b32 m0, s12
	s_nop 0
	global_load_lds_dwordx4 v[50:51], off
	v_add3_u32 v54, v58, v48, v45
	ds_read_b128 v[50:53], v54
	ds_read_b128 v[54:57], v54 offset:2048
	v_add3_u32 v70, v58, v46, v45
	ds_read_b128 v[58:61], v70 offset:16384
	ds_read_b128 v[62:65], v70 offset:18432
	ds_read_b128 v[66:69], v70 offset:20480
	ds_read_b128 v[70:73], v70 offset:22528
	s_waitcnt lgkmcnt(3)
	v_mfma_f32_16x16x32_bf16 v[30:33], v[58:61], v[50:53], v[30:33]
	s_add_u32 s40, s40, 0x80
	s_addc_u32 s41, s41, 0
	s_cmpk_lg_i32 s40, 0xf80
	v_mfma_f32_16x16x32_bf16 v[26:29], v[58:61], v[54:57], v[26:29]
	v_or_b32_e32 v58, s10, v47
	s_mov_b32 s10, s11
	s_waitcnt lgkmcnt(2)
	v_mfma_f32_16x16x32_bf16 v[18:21], v[62:65], v[54:57], v[18:21]
	s_waitcnt lgkmcnt(1)
	v_mfma_f32_16x16x32_bf16 v[10:13], v[66:69], v[54:57], v[10:13]
	s_waitcnt lgkmcnt(0)
	v_mfma_f32_16x16x32_bf16 v[6:9], v[70:73], v[50:53], v[6:9]
	v_mfma_f32_16x16x32_bf16 v[2:5], v[70:73], v[54:57], v[2:5]
	v_add3_u32 v54, v58, v48, v45
	v_add3_u32 v70, v58, v46, v45
	v_mfma_f32_16x16x32_bf16 v[22:25], v[62:65], v[50:53], v[22:25]
	v_mfma_f32_16x16x32_bf16 v[14:17], v[66:69], v[50:53], v[14:17]
	ds_read_b128 v[50:53], v54
	ds_read_b128 v[54:57], v54 offset:2048
	ds_read_b128 v[58:61], v70 offset:16384
	ds_read_b128 v[62:65], v70 offset:18432
	ds_read_b128 v[66:69], v70 offset:20480
	ds_read_b128 v[70:73], v70 offset:22528
	s_waitcnt lgkmcnt(3)
	v_mfma_f32_16x16x32_bf16 v[30:33], v[58:61], v[50:53], v[30:33]
	v_mfma_f32_16x16x32_bf16 v[26:29], v[58:61], v[54:57], v[26:29]
	s_waitcnt lgkmcnt(2)
	v_mfma_f32_16x16x32_bf16 v[22:25], v[62:65], v[50:53], v[22:25]
	v_mfma_f32_16x16x32_bf16 v[18:21], v[62:65], v[54:57], v[18:21]
	s_waitcnt lgkmcnt(1)
	v_mfma_f32_16x16x32_bf16 v[14:17], v[66:69], v[50:53], v[14:17]
	v_mfma_f32_16x16x32_bf16 v[10:13], v[66:69], v[54:57], v[10:13]
	s_waitcnt lgkmcnt(0)
	v_mfma_f32_16x16x32_bf16 v[6:9], v[70:73], v[50:53], v[6:9]
	v_mfma_f32_16x16x32_bf16 v[2:5], v[70:73], v[54:57], v[2:5]
	s_cbranch_scc1 .LBB0_288
	v_add3_u32 v38, v49, v48, v45
	v_add3_u32 v49, v49, v46, v45
	s_waitcnt vmcnt(0)
	s_barrier
	ds_read_b128 v[34:37], v38 offset:32768
	ds_read_b128 v[38:41], v38 offset:34816
	ds_read_b128 v[50:53], v49 offset:49152
	ds_read_b128 v[54:57], v49 offset:51200
	ds_read_b128 v[58:61], v49 offset:53248
	ds_read_b128 v[62:65], v49 offset:55296
	s_waitcnt lgkmcnt(3)
	v_mfma_f32_16x16x32_bf16 v[26:29], v[50:53], v[38:41], v[26:29]
	s_lshl_b32 s7, s7, 7
	v_lshlrev_b32_e32 v1, 5, v1
	v_or3_b32 v182, v1, s38, v42
	s_waitcnt lgkmcnt(2)
	v_mfma_f32_16x16x32_bf16 v[18:21], v[54:57], v[38:41], v[18:21]
	v_lshl_add_u32 v1, v44, 6, s7
	v_readlane_b32 s8, v252, 33
	v_readlane_b32 s9, v252, 34
	s_waitcnt lgkmcnt(1)
	v_mfma_f32_16x16x32_bf16 v[10:13], v[58:61], v[38:41], v[10:13]
	s_mov_b64 s[38:39], 0
	s_waitcnt lgkmcnt(0)
	v_mfma_f32_16x16x32_bf16 v[2:5], v[62:65], v[38:41], v[2:5]
	v_add3_u32 v38, v47, v48, v45
	v_add3_u32 v45, v47, v46, v45
	v_mfma_f32_16x16x32_bf16 v[30:33], v[50:53], v[34:37], v[30:33]
	v_mfma_f32_16x16x32_bf16 v[22:25], v[54:57], v[34:37], v[22:25]
	v_mfma_f32_16x16x32_bf16 v[14:17], v[58:61], v[34:37], v[14:17]
	v_mfma_f32_16x16x32_bf16 v[6:9], v[62:65], v[34:37], v[6:9]
	ds_read_b128 v[34:37], v38 offset:32768
	ds_read_b128 v[38:41], v38 offset:34816
	ds_read_b128 v[46:49], v45 offset:49152
	ds_read_b128 v[50:53], v45 offset:51200
	ds_read_b128 v[54:57], v45 offset:53248
	ds_read_b128 v[58:61], v45 offset:55296
	s_waitcnt lgkmcnt(3)
	v_mfma_f32_16x16x32_bf16 v[30:33], v[46:49], v[34:37], v[30:33]
	s_waitcnt lgkmcnt(2)
	v_mfma_f32_16x16x32_bf16 v[22:25], v[50:53], v[34:37], v[22:25]
	s_nop 5
	v_cvt_pk_bf16_f32 v30, v30, v31
	v_cvt_pk_bf16_f32 v31, v32, v33
	s_waitcnt lgkmcnt(1)
	v_mfma_f32_16x16x32_bf16 v[14:17], v[54:57], v[34:37], v[14:17]
	s_waitcnt lgkmcnt(0)
	v_mfma_f32_16x16x32_bf16 v[6:9], v[58:61], v[34:37], v[6:9]
	v_lshl_or_b32 v34, v43, 2, v1
	v_ashrrev_i32_e32 v35, 31, v34
	v_lshlrev_b64 v[36:37], 11, v[182:183]
	v_mfma_f32_16x16x32_bf16 v[26:29], v[46:49], v[38:41], v[26:29]
	v_lshl_add_u64 v[36:37], s[8:9], 0, v[36:37]
	v_lshlrev_b64 v[34:35], 1, v[34:35]
	v_lshl_add_u64 v[36:37], v[36:37], 0, v[34:35]
	v_mfma_f32_16x16x32_bf16 v[18:21], v[50:53], v[38:41], v[18:21]
	v_or_b32_e32 v182, 16, v182
	global_store_dwordx2 v[36:37], v[30:31], off
	v_lshlrev_b64 v[30:31], 11, v[182:183]
	v_mfma_f32_16x16x32_bf16 v[10:13], v[54:57], v[38:41], v[10:13]
	v_lshl_add_u64 v[30:31], s[8:9], 0, v[30:31]
	v_lshl_add_u64 v[30:31], v[30:31], 0, v[34:35]
	v_cvt_pk_bf16_f32 v26, v26, v27
	v_mfma_f32_16x16x32_bf16 v[2:5], v[58:61], v[38:41], v[2:5]
	v_cvt_pk_bf16_f32 v27, v28, v29
	v_cvt_pk_bf16_f32 v22, v22, v23
	v_cvt_pk_bf16_f32 v23, v24, v25
	v_cvt_pk_bf16_f32 v18, v18, v19
	v_cvt_pk_bf16_f32 v19, v20, v21
	v_cvt_pk_bf16_f32 v14, v14, v15
	v_cvt_pk_bf16_f32 v15, v16, v17
	v_cvt_pk_bf16_f32 v10, v10, v11
	v_cvt_pk_bf16_f32 v11, v12, v13
	v_cvt_pk_bf16_f32 v6, v6, v7
	v_cvt_pk_bf16_f32 v7, v8, v9
	v_cvt_pk_bf16_f32 v2, v2, v3
	v_cvt_pk_bf16_f32 v3, v4, v5
	global_store_dwordx2 v[30:31], v[26:27], off
	global_store_dwordx2 v[36:37], v[22:23], off offset:32
	global_store_dwordx2 v[30:31], v[18:19], off offset:32
	global_store_dwordx2 v[36:37], v[14:15], off offset:64
	global_store_dwordx2 v[30:31], v[10:11], off offset:64
	global_store_dwordx2 v[36:37], v[6:7], off offset:96
	global_store_dwordx2 v[30:31], v[2:3], off offset:96
; DI int get_tid() { int t = threadIdx.x; asm volatile("" : "+v"(t)); return t; }
; DI float zero_f() { float z = 0.f; asm volatile("" : "+v"(z)); return z; }
; template <int BM, class Epi>
; DI void gemm_dma(const u16* __restrict__ X, long ldx, const u16* __restrict__ W, long ldw, int K, char* smem,
;                  int m0, int n0, const Epi& epi) {
;     ...
;   const int tid = get_tid(), lane = tid & 63, wave = tid >> 6;
;   const int lr = lane & 15, g = lane >> 4;
;   const int rd = lr * 64 + ((g ^ ((4 - (lr >> 2)) & 3)) << 4);
;   const int xrow0 = BIG ? wave * 64 : (wave & 1) * (BM / 2);
;   const int wrow0 = BIG ? 0 : (wave >> 1) * 64;
;   f32x4 acc[NT][MT];
;   { const float z = zero_f();
; #pragma unroll
;   for (int a = 0; a < NT; ++a)
; #pragma unroll
;     for (int b = 0; b < MT; ++b) acc[a][b] = (f32x4){z, z, z, z}; }
;   const int wu = __builtin_amdgcn_readfirstlane(wave);
;   const unsigned sbase = (unsigned)__builtin_amdgcn_readfirstlane((int)(unsigned)(size_t)smem);
;   const int r16 = lane >> 2, chunk = (lane & 3) ^ ((4 - (r16 >> 2)) & 3);
;   const u16* xs = X + (long)(wu * XD * 16 + r16) * ldx + (chunk << 3);
;   const u16* ws = W + (long)(wu * 32 + r16) * ldw + (chunk << 3);
;   const long ldx16 = 16 * ldx, ldw16 = 16 * ldw;
;   const unsigned xdst = sbase + wu * XD * 1024, wdst = sbase + BM * 64 + wu * 2048;
;     ...
;   const int nk = K >> 5;
;   __syncthreads();
; #pragma unroll
;   for (int s = 0; s < D - 1; ++s) GD_ISSUE(s)
;   int cur = 0, nxt = D - 1, kt = 0;
.LBB0_290:
	s_and_b64 vcc, exec, s[38:39]
	s_cbranch_vccz .LBB0_285
	s_ashr_i32 s38, s6, 3
	s_ashr_i32 s39, s38, 31
	v_mov_b32_e32 v3, v185
	s_and_b32 s7, s6, 7
	s_lshl_b64 s[40:41], s[38:39], 20
	v_readlane_b32 s8, v252, 35
	v_readlane_b32 s9, v252, 36
	v_lshrrev_b32_e32 v4, 2, v3
	s_add_u32 s8, s8, s40
	v_and_b32_e32 v134, 15, v3
	v_bfe_u32 v1, v3, 4, 2
	v_sub_u32_e32 v4, 0, v4
	s_addc_u32 s9, s9, s41
	s_lshl_b32 s10, s7, 19
	v_readlane_b32 s12, v252, 39
	v_lshlrev_b32_e32 v2, 6, v134
	v_bitop3_b32 v4, v1, v4, 3 bitop3:0x78
	v_readlane_b32 s13, v252, 40
	s_add_u32 s12, s12, s10
	v_lshl_or_b32 v135, v4, 4, v2
	v_readfirstlane_b32 s14, v3
	v_lshrrev_b32_e32 v4, 4, v3
	s_addc_u32 s13, s13, 0
	s_ashr_i32 s15, s14, 6
	v_bfe_u32 v8, v3, 2, 4
	v_sub_u32_e32 v16, 0, v4
	s_andn2_b32 s14, s14, 63
	v_xor_b32_e32 v9, v3, v16
	v_or_b32_e32 v4, s14, v8
	v_ashrrev_i32_e32 v5, 31, v4
	v_lshlrev_b32_e32 v9, 4, v9
	v_lshl_or_b32 v8, s15, 5, v8
	v_lshlrev_b64 v[4:5], 12, v[4:5]
	v_and_b32_e32 v182, 48, v9
	v_ashrrev_i32_e32 v9, 31, v8
	v_mov_b32_e32 v2, v183
	v_lshl_add_u64 v[6:7], s[8:9], 0, v[4:5]
	v_lshlrev_b64 v[8:9], 12, v[8:9]
	v_lshl_add_u64 v[6:7], v[6:7], 0, v[182:183]
	v_lshl_add_u64 v[10:11], s[12:13], 0, v[8:9]
	s_lshl_b32 s8, s15, 12
	s_barrier
	s_mov_b32 m0, s8
	s_nop 0
	global_load_lds_dwordx4 v[6:7], off
	s_mov_b64 s[16:17], 0x10000
	v_lshl_add_u64 v[12:13], v[6:7], 0, s[16:17]
	s_or_b32 s13, s8, 0x400
	s_mov_b32 m0, s13
	s_nop 0
	global_load_lds_dwordx4 v[12:13], off
	s_mov_b64 s[20:21], 0x20000
	v_lshl_add_u64 v[12:13], v[6:7], 0, s[20:21]
	s_or_b32 s13, s8, 0x800
	s_mov_b32 m0, s13
	s_nop 0
	global_load_lds_dwordx4 v[12:13], off
	s_mov_b64 s[22:23], 0x30000
	s_lshl_b32 s12, s15, 11
	v_lshl_add_u64 v[12:13], v[6:7], 0, s[22:23]
	s_or_b32 s13, s8, 0xc00
	s_mov_b32 m0, s13
	s_nop 0
	global_load_lds_dwordx4 v[12:13], off
	v_lshl_add_u64 v[10:11], v[10:11], 0, v[182:183]
	s_add_i32 s9, s12, 0x4000
	s_mov_b32 m0, s9
	s_nop 0
	global_load_lds_dwordx4 v[10:11], off
	v_lshl_add_u64 v[12:13], v[10:11], 0, s[16:17]
	s_add_i32 s13, s12, 0x4400
	s_mov_b32 m0, s13
	s_nop 0
	global_load_lds_dwordx4 v[12:13], off
	v_lshl_add_u64 v[12:13], v[6:7], 0, 64
	s_add_i32 s13, s8, 0x6000
	s_mov_b32 m0, s13
	s_nop 0
	global_load_lds_dwordx4 v[12:13], off
	s_mov_b64 s[18:19], 0x10040
	v_lshl_add_u64 v[12:13], v[6:7], 0, s[18:19]
	s_add_i32 s13, s8, 0x6400
	s_mov_b32 m0, s13
	s_nop 0
	global_load_lds_dwordx4 v[12:13], off
	s_mov_b64 s[14:15], 0x20040
	v_lshl_add_u64 v[12:13], v[6:7], 0, s[14:15]
	s_add_i32 s13, s8, 0x6800
	s_mov_b32 m0, s13
	s_nop 0
	global_load_lds_dwordx4 v[12:13], off
	s_mov_b64 s[14:15], 0x30040
	v_lshl_add_u64 v[6:7], v[6:7], 0, s[14:15]
	s_add_i32 s13, s8, 0x6c00
	s_mov_b32 m0, s13
	s_nop 0
	global_load_lds_dwordx4 v[6:7], off
	v_lshl_add_u64 v[14:15], v[10:11], 0, 64
	s_add_i32 s13, s12, 0xa000
	s_mov_b32 m0, s13
	s_nop 0
	global_load_lds_dwordx4 v[14:15], off
	v_lshl_add_u64 v[6:7], v[10:11], 0, s[18:19]
	s_add_i32 s12, s12, 0xa400
	s_mov_b32 m0, s12
	s_nop 0
	global_load_lds_dwordx4 v[6:7], off
	v_and_b32_e32 v136, 0xffffffc0, v3
	v_bitop3_b32 v3, v3, 3, v16 bitop3:0x48
	v_lshl_add_u64 v[6:7], s[34:35], 0, v[8:9]
	v_lshlrev_b32_e32 v182, 4, v3
	v_readlane_b32 s12, v255, 3
	v_lshl_add_u64 v[6:7], v[6:7], 0, v[182:183]
	v_readlane_b32 s13, v255, 4
	v_lshl_add_u64 v[4:5], s[40:41], 0, v[4:5]
	v_or_b32_e32 v4, v4, v182
	v_lshl_add_u64 v[130:131], s[12:13], 0, v[6:7]
	v_readlane_b32 s12, v255, 13
	v_readlane_b32 s13, v255, 14
	s_mov_b32 s10, 2
	s_mov_b32 s11, 0
	v_lshlrev_b32_e32 v137, 6, v136
	v_lshl_add_u64 v[132:133], s[12:13], 0, v[4:5]
	s_mov_b64 s[40:41], 0
	v_mov_b32_e32 v3, v2
	v_mov_b32_e32 v4, v2
	v_mov_b32_e32 v5, v2
	v_mov_b32_e32 v6, v2
	v_mov_b32_e32 v7, v2
	v_mov_b32_e32 v8, v2
	v_mov_b32_e32 v9, v2
	v_mov_b32_e32 v10, v2
	v_mov_b32_e32 v11, v2
	v_mov_b32_e32 v12, v2
	v_mov_b32_e32 v13, v2
	v_mov_b32_e32 v14, v2
	v_mov_b32_e32 v15, v2
	v_mov_b32_e32 v16, v2
	v_mov_b32_e32 v17, v2
	v_mov_b32_e32 v18, v2
	v_mov_b32_e32 v19, v2
	v_mov_b32_e32 v20, v2
	v_mov_b32_e32 v21, v2
	v_mov_b32_e32 v22, v2
	v_mov_b32_e32 v23, v2
	v_mov_b32_e32 v24, v2
	v_mov_b32_e32 v25, v2
	v_mov_b32_e32 v26, v2
	v_mov_b32_e32 v27, v2
	v_mov_b32_e32 v28, v2
	v_mov_b32_e32 v29, v2
	v_mov_b32_e32 v30, v2
	v_mov_b32_e32 v31, v2
	v_mov_b32_e32 v32, v2
	v_mov_b32_e32 v33, v2
	v_mov_b32_e32 v34, v2
	v_mov_b32_e32 v35, v2
	v_mov_b32_e32 v36, v2
	v_mov_b32_e32 v37, v2
	v_mov_b32_e32 v38, v2
	v_mov_b32_e32 v39, v2
	v_mov_b32_e32 v40, v2
	v_mov_b32_e32 v41, v2
	v_mov_b32_e32 v42, v2
	v_mov_b32_e32 v43, v2
	v_mov_b32_e32 v44, v2
	v_mov_b32_e32 v45, v2
	v_mov_b32_e32 v46, v2
	v_mov_b32_e32 v47, v2
	v_mov_b32_e32 v48, v2
	v_mov_b32_e32 v49, v2
	v_mov_b32_e32 v50, v2
	v_mov_b32_e32 v51, v2
	v_mov_b32_e32 v52, v2
	v_mov_b32_e32 v53, v2
	v_mov_b32_e32 v54, v2
	v_mov_b32_e32 v55, v2
	v_mov_b32_e32 v56, v2
	v_mov_b32_e32 v57, v2
	v_mov_b32_e32 v58, v2
	v_mov_b32_e32 v59, v2
	v_mov_b32_e32 v60, v2
	v_mov_b32_e32 v61, v2
	v_mov_b32_e32 v62, v2
	v_mov_b32_e32 v63, v2
	v_mov_b32_e32 v64, v2
	v_mov_b32_e32 v65, v2
	v_mov_b32_e32 v66, v2
	v_mov_b32_e32 v67, v2
	v_mov_b32_e32 v68, v2
	v_mov_b32_e32 v69, v2
	v_mov_b32_e32 v70, v2
	v_mov_b32_e32 v71, v2
	v_mov_b32_e32 v72, v2
	v_mov_b32_e32 v73, v2
	v_mov_b32_e32 v74, v2
	v_mov_b32_e32 v75, v2
	v_mov_b32_e32 v76, v2
	v_mov_b32_e32 v77, v2
	v_mov_b32_e32 v78, v2
	v_mov_b32_e32 v79, v2
	v_mov_b32_e32 v80, v2
	v_mov_b32_e32 v81, v2
	v_mov_b32_e32 v82, v2
	v_mov_b32_e32 v83, v2
	v_mov_b32_e32 v84, v2
	v_mov_b32_e32 v85, v2
	v_mov_b32_e32 v86, v2
	v_mov_b32_e32 v87, v2
	v_mov_b32_e32 v88, v2
	v_mov_b32_e32 v89, v2
	v_mov_b32_e32 v90, v2
	v_mov_b32_e32 v91, v2
	v_mov_b32_e32 v92, v2
	v_mov_b32_e32 v93, v2
	v_mov_b32_e32 v94, v2
	v_mov_b32_e32 v95, v2
	v_mov_b32_e32 v96, v2
	v_mov_b32_e32 v97, v2
	v_mov_b32_e32 v98, v2
	v_mov_b32_e32 v99, v2
	v_mov_b32_e32 v100, v2
	v_mov_b32_e32 v101, v2
	v_mov_b32_e32 v102, v2
	v_mov_b32_e32 v103, v2
	v_mov_b32_e32 v104, v2
	v_mov_b32_e32 v105, v2
	v_mov_b32_e32 v106, v2
	v_mov_b32_e32 v107, v2
	v_mov_b32_e32 v108, v2
	v_mov_b32_e32 v109, v2
	v_mov_b32_e32 v110, v2
	v_mov_b32_e32 v111, v2
	v_mov_b32_e32 v112, v2
	v_mov_b32_e32 v113, v2
	v_mov_b32_e32 v114, v2
	v_mov_b32_e32 v115, v2
	v_mov_b32_e32 v116, v2
	v_mov_b32_e32 v117, v2
	v_mov_b32_e32 v118, v2
	v_mov_b32_e32 v119, v2
	v_mov_b32_e32 v120, v2
	v_mov_b32_e32 v121, v2
	v_mov_b32_e32 v122, v2
	v_mov_b32_e32 v123, v2
	v_mov_b32_e32 v124, v2
	v_mov_b32_e32 v125, v2
	v_mov_b32_e32 v126, v2
	v_mov_b32_e32 v127, v2
	v_mov_b32_e32 v128, v2
	v_mov_b32_e32 v129, v2
; template <int N> DI void wait_vm() { asm volatile("s_waitcnt vmcnt(%0)" ::"n"(N) : "memory"); }
; template <int BM, class Epi>
; DI void gemm_dma(const u16* __restrict__ X, long ldx, const u16* __restrict__ W, long ldw, int K, char* smem,
;                  int m0, int n0, const Epi& epi) {
;     ...
;   do {
;     if (kt + D - 2 < nk) wait_vm<PW * (D - 2)>(); else wait_vm<0>();
;     __syncthreads();
;     if (kt + D - 1 < nk) GD_ISSUE(nxt)
;     nxt = (nxt + 1 == D) ? 0 : nxt + 1;
;     const char* base = smem + cur * STG;
;     cur = (cur + 1 == D) ? 0 : cur + 1;
;     bf16x8 xf[MT];
; #pragma unroll
;     for (int i = 0; i < MT; ++i) xf[i] = *(const bf16x8*)(base + (xrow0 + i * 16) * 64 + rd);
; #pragma unroll
;     for (int nh = 0; nh < NT / 4; ++nh) {
;       bf16x8 wf[4];
; #pragma unroll
;       for (int i = 0; i < 4; ++i) wf[i] = *(const bf16x8*)(base + BM * 64 + (wrow0 + (nh * 4 + i) * 16) * 64 + rd);
; #pragma unroll
;       for (int i = 0; i < 4; ++i)
; #pragma unroll
;         for (int mt = 0; mt < MT; ++mt)
;           acc[nh * 4 + i][mt] = __builtin_amdgcn_mfma_f32_16x16x32_bf16(wf[i], xf[mt], acc[nh * 4 + i][mt], 0, 0, 0);
;     }
;   } while (++kt < nk);
.LBB0_292:
	s_mul_i32 s12, s10, 0x6000
	v_lshl_add_u64 v[196:197], v[132:133], 0, s[40:41]
	s_waitcnt vmcnt(6)
	s_barrier
	s_mul_i32 s98, s11, 0x6000
	v_or_b32_e32 v170, s98, v135
	v_add_u32_e32 v150, v170, v137
	ds_read_b128 v[138:141], v150
	ds_read_b128 v[142:145], v150 offset:1024
	ds_read_b128 v[146:149], v150 offset:2048
	ds_read_b128 v[150:153], v150 offset:3072
	ds_read_b128 v[154:157], v170 offset:16384
	ds_read_b128 v[158:161], v170 offset:17408
	ds_read_b128 v[162:165], v170 offset:18432
	ds_read_b128 v[166:169], v170 offset:19456
	ds_read_b128 v[226:229], v170 offset:20480
	ds_read_b128 v[230:233], v170 offset:21504
	ds_read_b128 v[234:237], v170 offset:22528
	ds_read_b128 v[238:241], v170 offset:23552
	s_add_i32 s13, s12, s8
	s_mov_b32 m0, s13
	s_nop 0
	global_load_lds_dwordx4 v[196:197], off
	v_lshl_add_u64 v[224:225], v[196:197], 0, s[16:17]
	s_add_i32 s14, s13, 0x400
	s_mov_b32 m0, s14
	s_nop 0
	global_load_lds_dwordx4 v[224:225], off
	v_lshl_add_u64 v[224:225], v[196:197], 0, s[20:21]
	s_add_i32 s14, s13, 0x800
	s_mov_b32 m0, s14
	s_nop 0
	global_load_lds_dwordx4 v[224:225], off
	v_lshl_add_u64 v[196:197], v[196:197], 0, s[22:23]
	s_addk_i32 s13, 0xc00
	s_mov_b32 m0, s13
	s_nop 0
	global_load_lds_dwordx4 v[196:197], off
	s_add_i32 s12, s12, s9
	v_lshl_add_u64 v[194:195], v[130:131], 0, s[40:41]
	s_mov_b32 m0, s12
	s_nop 0
	global_load_lds_dwordx4 v[194:195], off
	s_addk_i32 s12, 0x400
	v_lshl_add_u64 v[194:195], v[194:195], 0, s[16:17]
	s_mov_b32 m0, s12
	s_nop 0
	global_load_lds_dwordx4 v[194:195], off
	s_waitcnt lgkmcnt(7)
	v_mfma_f32_16x16x32_bf16 v[126:129], v[154:157], v[138:141], v[126:129]
	s_add_i32 s10, s10, 1
	s_add_i32 s11, s11, 1
	s_cmp_lg_u32 s10, 3
	v_mfma_f32_16x16x32_bf16 v[122:125], v[154:157], v[142:145], v[122:125]
	s_cselect_b32 s10, s10, 0
	s_cmp_lg_u32 s11, 3
	s_cselect_b32 s11, s11, 0
	v_mfma_f32_16x16x32_bf16 v[118:121], v[154:157], v[146:149], v[118:121]
	s_add_u32 s40, s40, 64
	s_addc_u32 s41, s41, 0
	s_cmpk_lg_i32 s40, 0xf80
	v_mfma_f32_16x16x32_bf16 v[114:117], v[154:157], v[150:153], v[114:117]
	s_waitcnt lgkmcnt(6)
	v_mfma_f32_16x16x32_bf16 v[110:113], v[158:161], v[138:141], v[110:113]
	v_mfma_f32_16x16x32_bf16 v[106:109], v[158:161], v[142:145], v[106:109]
	v_mfma_f32_16x16x32_bf16 v[102:105], v[158:161], v[146:149], v[102:105]
	v_mfma_f32_16x16x32_bf16 v[98:101], v[158:161], v[150:153], v[98:101]
	s_waitcnt lgkmcnt(5)
	v_mfma_f32_16x16x32_bf16 v[94:97], v[162:165], v[138:141], v[94:97]
	v_mfma_f32_16x16x32_bf16 v[90:93], v[162:165], v[142:145], v[90:93]
	v_mfma_f32_16x16x32_bf16 v[86:89], v[162:165], v[146:149], v[86:89]
	v_mfma_f32_16x16x32_bf16 v[82:85], v[162:165], v[150:153], v[82:85]
	s_waitcnt lgkmcnt(4)
	v_mfma_f32_16x16x32_bf16 v[78:81], v[166:169], v[138:141], v[78:81]
	v_mfma_f32_16x16x32_bf16 v[74:77], v[166:169], v[142:145], v[74:77]
	v_mfma_f32_16x16x32_bf16 v[70:73], v[166:169], v[146:149], v[70:73]
	v_mfma_f32_16x16x32_bf16 v[66:69], v[166:169], v[150:153], v[66:69]
	s_waitcnt lgkmcnt(3)
	v_mfma_f32_16x16x32_bf16 v[62:65], v[226:229], v[138:141], v[62:65]
	v_mfma_f32_16x16x32_bf16 v[58:61], v[226:229], v[142:145], v[58:61]
	v_mfma_f32_16x16x32_bf16 v[54:57], v[226:229], v[146:149], v[54:57]
	v_mfma_f32_16x16x32_bf16 v[50:53], v[226:229], v[150:153], v[50:53]
	s_waitcnt lgkmcnt(2)
	v_mfma_f32_16x16x32_bf16 v[46:49], v[230:233], v[138:141], v[46:49]
	v_mfma_f32_16x16x32_bf16 v[42:45], v[230:233], v[142:145], v[42:45]
	v_mfma_f32_16x16x32_bf16 v[38:41], v[230:233], v[146:149], v[38:41]
	v_mfma_f32_16x16x32_bf16 v[34:37], v[230:233], v[150:153], v[34:37]
	s_waitcnt lgkmcnt(1)
	v_mfma_f32_16x16x32_bf16 v[30:33], v[234:237], v[138:141], v[30:33]
	v_mfma_f32_16x16x32_bf16 v[26:29], v[234:237], v[142:145], v[26:29]
	v_mfma_f32_16x16x32_bf16 v[22:25], v[234:237], v[146:149], v[22:25]
	v_mfma_f32_16x16x32_bf16 v[18:21], v[234:237], v[150:153], v[18:21]
	s_waitcnt lgkmcnt(0)
	v_mfma_f32_16x16x32_bf16 v[14:17], v[238:241], v[138:141], v[14:17]
	v_mfma_f32_16x16x32_bf16 v[10:13], v[238:241], v[142:145], v[10:13]
	v_mfma_f32_16x16x32_bf16 v[6:9], v[238:241], v[146:149], v[6:9]
	v_mfma_f32_16x16x32_bf16 v[2:5], v[238:241], v[150:153], v[2:5]
	s_cbranch_scc1 .LBB0_292
	v_add_u32_e32 v137, v135, v137
	v_or_b32_e32 v150, 0x10000, v135
	v_or_b32_e32 v154, 0x10400, v135
	v_or_b32_e32 v158, 0x10800, v135
	v_or_b32_e32 v162, 0x10c00, v135
	s_waitcnt vmcnt(6)
	s_barrier
	ds_read_b128 v[130:133], v137 offset:49152
	ds_read_b128 v[138:141], v137 offset:50176
	ds_read_b128 v[142:145], v137 offset:51200
	ds_read_b128 v[146:149], v137 offset:52224
	ds_read_b128 v[150:153], v150
	ds_read_b128 v[154:157], v154
	ds_read_b128 v[158:161], v158
	ds_read_b128 v[162:165], v162
	s_waitcnt lgkmcnt(3)
	v_mfma_f32_16x16x32_bf16 v[126:129], v[150:153], v[130:133], v[126:129]
	v_readlane_b32 s8, v252, 33
	v_readlane_b32 s9, v252, 34
	s_lshl_b32 s7, s7, 8
	v_mfma_f32_16x16x32_bf16 v[122:125], v[150:153], v[138:141], v[122:125]
	v_lshl_or_b32 v182, v1, 3, s7
	v_mfma_f32_16x16x32_bf16 v[118:121], v[150:153], v[142:145], v[118:121]
	v_mfma_f32_16x16x32_bf16 v[114:117], v[150:153], v[146:149], v[114:117]
	s_waitcnt lgkmcnt(2)
	v_mfma_f32_16x16x32_bf16 v[110:113], v[154:157], v[130:133], v[110:113]
	v_mfma_f32_16x16x32_bf16 v[106:109], v[154:157], v[138:141], v[106:109]
	v_mfma_f32_16x16x32_bf16 v[102:105], v[154:157], v[142:145], v[102:105]
	v_mfma_f32_16x16x32_bf16 v[98:101], v[154:157], v[146:149], v[98:101]
	s_waitcnt lgkmcnt(1)
	v_mfma_f32_16x16x32_bf16 v[94:97], v[158:161], v[130:133], v[94:97]
	v_mfma_f32_16x16x32_bf16 v[150:153], v[158:161], v[138:141], v[90:93]
	v_mfma_f32_16x16x32_bf16 v[86:89], v[158:161], v[142:145], v[86:89]
	s_nop 1
	v_or_b32_e32 v90, 0x11c00, v135
	ds_read_b128 v[90:93], v90
	v_mfma_f32_16x16x32_bf16 v[154:157], v[158:161], v[146:149], v[82:85]
	s_waitcnt lgkmcnt(1)
	v_mfma_f32_16x16x32_bf16 v[78:81], v[162:165], v[130:133], v[78:81]
	s_nop 0
	v_or_b32_e32 v82, 0x11800, v135
	ds_read_b128 v[82:85], v82
	v_mfma_f32_16x16x32_bf16 v[158:161], v[162:165], v[138:141], v[74:77]
	v_mfma_f32_16x16x32_bf16 v[70:73], v[162:165], v[142:145], v[70:73]
	s_nop 1
	v_or_b32_e32 v74, 0x11400, v135
	ds_read_b128 v[74:77], v74
	v_mfma_f32_16x16x32_bf16 v[162:165], v[162:165], v[146:149], v[66:69]
	s_nop 2
	v_or_b32_e32 v66, 0x11000, v135
	ds_read_b128 v[66:69], v66
	s_waitcnt lgkmcnt(1)
	v_mfma_f32_16x16x32_bf16 v[46:49], v[74:77], v[130:133], v[46:49]
	s_waitcnt vmcnt(0)
	s_waitcnt lgkmcnt(0)
	s_barrier
; template <int BM, class Epi>
; DI void gemm_dma(const u16* __restrict__ X, long ldx, const u16* __restrict__ W, long ldw, int K, char* smem,
;                  int m0, int n0, const Epi& epi) {
;     ...
;     for (int i = 0; i < MT; ++i) xf[i] = *(const bf16x8*)(base + (xrow0 + i * 16) * 64 + rd);
; #pragma unroll
;     for (int nh = 0; nh < NT / 4; ++nh) {
;       bf16x8 wf[4];
; #pragma unroll
;       for (int i = 0; i < 4; ++i) wf[i] = *(const bf16x8*)(base + BM * 64 + (wrow0 + (nh * 4 + i) * 16) * 64 + rd);
; #pragma unroll
;       for (int i = 0; i < 4; ++i)
; #pragma unroll
;         for (int mt = 0; mt < MT; ++mt)
;           acc[nh * 4 + i][mt] = __builtin_amdgcn_mfma_f32_16x16x32_bf16(wf[i], xf[mt], acc[nh * 4 + i][mt], 0, 0, 0);
;     }
;   } while (++kt < nk);
;     ...
;   epi.run(acc, m0 + xrow0 + lr, n0 + wrow0 + 4 * g);
	v_mfma_f32_16x16x32_bf16 v[62:65], v[66:69], v[130:133], v[62:65]
	v_mfma_f32_16x16x32_bf16 v[166:169], v[66:69], v[138:141], v[58:61]
	v_mfma_f32_16x16x32_bf16 v[54:57], v[66:69], v[142:145], v[54:57]
	v_mfma_f32_16x16x32_bf16 v[170:173], v[66:69], v[146:149], v[50:53]
	v_mfma_f32_16x16x32_bf16 v[174:177], v[74:77], v[138:141], v[42:45]
	v_mfma_f32_16x16x32_bf16 v[38:41], v[74:77], v[142:145], v[38:41]
	v_mfma_f32_16x16x32_bf16 v[178:181], v[74:77], v[146:149], v[34:37]
	v_mfma_f32_16x16x32_bf16 v[30:33], v[82:85], v[130:133], v[30:33]
	v_mfma_f32_16x16x32_bf16 v[26:29], v[82:85], v[138:141], v[26:29]
	v_mfma_f32_16x16x32_bf16 v[22:25], v[82:85], v[142:145], v[22:25]
	v_mfma_f32_16x16x32_bf16 v[18:21], v[82:85], v[146:149], v[18:21]
	v_mfma_f32_16x16x32_bf16 v[14:17], v[90:93], v[130:133], v[14:17]
	v_mfma_f32_16x16x32_bf16 v[10:13], v[90:93], v[138:141], v[10:13]
	v_mfma_f32_16x16x32_bf16 v[6:9], v[90:93], v[142:145], v[6:9]
	v_mfma_f32_16x16x32_bf16 v[2:5], v[90:93], v[146:149], v[2:5]
	ds_read_b128 v[130:133], v137
	ds_read_b128 v[138:141], v137 offset:1024
	ds_read_b128 v[142:145], v137 offset:2048
	ds_read_b128 v[146:149], v137 offset:3072
	ds_read_b128 v[34:37], v135 offset:16384
	ds_read_b128 v[42:45], v135 offset:17408
	ds_read_b128 v[50:53], v135 offset:18432
	ds_read_b128 v[186:189], v135 offset:19456
	s_waitcnt lgkmcnt(2)
	v_mfma_f32_16x16x32_bf16 v[110:113], v[42:45], v[130:133], v[110:113]
	v_mfma_f32_16x16x32_bf16 v[106:109], v[42:45], v[138:141], v[106:109]
	v_mfma_f32_16x16x32_bf16 v[102:105], v[42:45], v[142:145], v[102:105]
	s_nop 5
	v_cvt_pk_bf16_f32 v110, v110, v111
	v_cvt_pk_bf16_f32 v111, v112, v113
	v_cvt_pk_bf16_f32 v106, v106, v107
	v_mfma_f32_16x16x32_bf16 v[190:193], v[42:45], v[146:149], v[98:101]
	v_cvt_pk_bf16_f32 v107, v108, v109
	v_cvt_pk_bf16_f32 v102, v102, v103
	v_cvt_pk_bf16_f32 v103, v104, v105
	s_waitcnt lgkmcnt(1)
	v_mfma_f32_16x16x32_bf16 v[82:85], v[50:53], v[138:141], v[150:153]
	v_mfma_f32_16x16x32_bf16 v[66:69], v[50:53], v[146:149], v[154:157]
	s_waitcnt lgkmcnt(0)
	v_mfma_f32_16x16x32_bf16 v[42:45], v[186:189], v[142:145], v[70:73]
	s_nop 2
	ds_read_b128 v[70:73], v135 offset:20480
	ds_read_b128 v[98:101], v135 offset:21504
	ds_read_b128 v[150:153], v135 offset:22528
	ds_read_b128 v[154:157], v135 offset:23552
	v_cvt_pk_bf16_f32 v82, v82, v83
	v_cvt_pk_bf16_f32 v83, v84, v85
	v_mfma_f32_16x16x32_bf16 v[90:93], v[50:53], v[130:133], v[94:97]
	v_cvt_pk_bf16_f32 v66, v66, v67
	v_cvt_pk_bf16_f32 v67, v68, v69
	v_cvt_pk_bf16_f32 v42, v42, v43
	v_mfma_f32_16x16x32_bf16 v[58:61], v[186:189], v[130:133], v[78:81]
	v_cvt_pk_bf16_f32 v43, v44, v45
	s_nop 2
	v_cvt_pk_bf16_f32 v90, v90, v91
	v_cvt_pk_bf16_f32 v91, v92, v93
	s_waitcnt lgkmcnt(3)
	v_mfma_f32_16x16x32_bf16 v[94:97], v[70:73], v[130:133], v[62:65]
	v_mfma_f32_16x16x32_bf16 v[78:81], v[70:73], v[142:145], v[54:57]
	v_cvt_pk_bf16_f32 v58, v58, v59
	v_cvt_pk_bf16_f32 v59, v60, v61
	s_waitcnt lgkmcnt(2)
	v_mfma_f32_16x16x32_bf16 v[62:65], v[98:101], v[130:133], v[46:49]
	v_mfma_f32_16x16x32_bf16 v[54:57], v[98:101], v[138:141], v[174:177]
	v_mfma_f32_16x16x32_bf16 v[46:49], v[98:101], v[142:145], v[38:41]
	v_mfma_f32_16x16x32_bf16 v[38:41], v[98:101], v[146:149], v[178:181]
	v_lshl_add_u32 v98, s38, 8, v136
	v_mfma_f32_16x16x32_bf16 v[126:129], v[34:37], v[130:133], v[126:129]
	s_waitcnt lgkmcnt(1)
	v_mfma_f32_16x16x32_bf16 v[30:33], v[150:153], v[130:133], v[30:33]
	s_waitcnt lgkmcnt(0)
; DI void st_bf4(u16* p, float a, float b, float c, float d) { *(uint2*)p = make_uint2(pk2(a, b), pk2(c, d)); }
;   template <int NT, int MT> DI void run(f32x4 (&acc)[NT][MT], int mb, int nb) const {
; #pragma unroll
;     for (int nt = 0; nt < NT; ++nt)
; #pragma unroll
;       for (int mt = 0; mt < MT; ++mt) {
;         f32x4 v = acc[nt][mt];
;         st_bf4(C + (size_t)(mb + mt * 16) * ldc + nb + nt * 16, v[0], v[1], v[2], v[3]);
;       }
	v_mfma_f32_16x16x32_bf16 v[14:17], v[154:157], v[130:133], v[14:17]
	v_or_b32_e32 v130, v98, v134
	v_ashrrev_i32_e32 v131, 31, v130
	v_lshlrev_b64 v[98:99], 11, v[130:131]
	v_lshl_add_u64 v[98:99], s[8:9], 0, v[98:99]
	v_lshl_add_u64 v[98:99], v[98:99], 0, v[182:183]
	v_cvt_pk_bf16_f32 v100, v126, v127
	v_cvt_pk_bf16_f32 v101, v128, v129
	v_mfma_f32_16x16x32_bf16 v[122:125], v[34:37], v[138:141], v[122:125]
	global_store_dwordx2 v[98:99], v[100:101], off
	v_or_b32_e32 v100, 16, v130
	v_ashrrev_i32_e32 v101, 31, v100
	v_lshlrev_b64 v[100:101], 11, v[100:101]
	v_lshl_add_u64 v[100:101], s[8:9], 0, v[100:101]
	v_lshl_add_u64 v[100:101], v[100:101], 0, v[182:183]
	s_nop 1
	v_cvt_pk_bf16_f32 v122, v122, v123
	v_cvt_pk_bf16_f32 v123, v124, v125
	v_mfma_f32_16x16x32_bf16 v[118:121], v[34:37], v[142:145], v[118:121]
	global_store_dwordx2 v[100:101], v[122:123], off
	v_or_b32_e32 v122, 32, v130
	v_ashrrev_i32_e32 v123, 31, v122
	v_lshlrev_b64 v[122:123], 11, v[122:123]
	v_lshl_add_u64 v[122:123], s[8:9], 0, v[122:123]
	v_lshl_add_u64 v[122:123], v[122:123], 0, v[182:183]
	s_nop 1
	v_cvt_pk_bf16_f32 v118, v118, v119
	v_cvt_pk_bf16_f32 v119, v120, v121
	v_mfma_f32_16x16x32_bf16 v[114:117], v[34:37], v[146:149], v[114:117]
	global_store_dwordx2 v[122:123], v[118:119], off
	v_or_b32_e32 v118, 48, v130
	v_ashrrev_i32_e32 v119, 31, v118
	v_mfma_f32_16x16x32_bf16 v[34:37], v[186:189], v[146:149], v[162:165]
	v_lshlrev_b64 v[118:119], 11, v[118:119]
	v_lshl_add_u64 v[118:119], s[8:9], 0, v[118:119]
	v_lshl_add_u64 v[118:119], v[118:119], 0, v[182:183]
	v_mfma_f32_16x16x32_bf16 v[74:77], v[50:53], v[142:145], v[86:89]
	v_cvt_pk_bf16_f32 v114, v114, v115
	s_nop 2
	v_cvt_pk_bf16_f32 v34, v34, v35
	v_cvt_pk_bf16_f32 v35, v36, v37
	v_mfma_f32_16x16x32_bf16 v[86:89], v[70:73], v[138:141], v[166:169]
	global_store_dwordx2 v[118:119], v[34:35], off offset:96
	v_cvt_pk_bf16_f32 v34, v94, v95
	v_cvt_pk_bf16_f32 v35, v96, v97
	v_mfma_f32_16x16x32_bf16 v[70:73], v[70:73], v[146:149], v[170:173]
	global_store_dwordx2 v[98:99], v[34:35], off offset:128
	s_nop 2
	v_cvt_pk_bf16_f32 v34, v86, v87
	v_cvt_pk_bf16_f32 v35, v88, v89
	global_store_dwordx2 v[100:101], v[34:35], off offset:128
	v_cvt_pk_bf16_f32 v34, v78, v79
	v_cvt_pk_bf16_f32 v35, v80, v81
	v_mfma_f32_16x16x32_bf16 v[50:53], v[186:189], v[138:141], v[158:161]
	global_store_dwordx2 v[122:123], v[34:35], off offset:128
	v_cvt_pk_bf16_f32 v34, v70, v71
	v_cvt_pk_bf16_f32 v35, v72, v73
	v_mfma_f32_16x16x32_bf16 v[26:29], v[150:153], v[138:141], v[26:29]
	global_store_dwordx2 v[118:119], v[34:35], off offset:128
	v_cvt_pk_bf16_f32 v34, v62, v63
	v_cvt_pk_bf16_f32 v35, v64, v65
	v_mfma_f32_16x16x32_bf16 v[22:25], v[150:153], v[142:145], v[22:25]
	global_store_dwordx2 v[98:99], v[34:35], off offset:160
	v_cvt_pk_bf16_f32 v34, v54, v55
	v_cvt_pk_bf16_f32 v35, v56, v57
	v_mfma_f32_16x16x32_bf16 v[18:21], v[150:153], v[146:149], v[18:21]
	global_store_dwordx2 v[100:101], v[34:35], off offset:160
	v_cvt_pk_bf16_f32 v34, v46, v47
	v_cvt_pk_bf16_f32 v35, v48, v49
	v_mfma_f32_16x16x32_bf16 v[10:13], v[154:157], v[138:141], v[10:13]
	v_cvt_pk_bf16_f32 v115, v116, v117
	global_store_dwordx2 v[122:123], v[102:103], off offset:32
	v_cvt_pk_bf16_f32 v102, v190, v191
	v_mfma_f32_16x16x32_bf16 v[6:9], v[154:157], v[142:145], v[6:9]
	v_cvt_pk_bf16_f32 v103, v192, v193
	v_cvt_pk_bf16_f32 v74, v74, v75
	v_cvt_pk_bf16_f32 v75, v76, v77
	v_mfma_f32_16x16x32_bf16 v[2:5], v[154:157], v[146:149], v[2:5]
	v_cvt_pk_bf16_f32 v50, v50, v51
	v_cvt_pk_bf16_f32 v51, v52, v53
	global_store_dwordx2 v[122:123], v[34:35], off offset:160
	v_cvt_pk_bf16_f32 v34, v38, v39
	v_cvt_pk_bf16_f32 v35, v40, v41
	v_cvt_pk_bf16_f32 v30, v30, v31
	v_cvt_pk_bf16_f32 v31, v32, v33
	v_cvt_pk_bf16_f32 v26, v26, v27
	v_cvt_pk_bf16_f32 v27, v28, v29
	v_cvt_pk_bf16_f32 v22, v22, v23
	v_cvt_pk_bf16_f32 v23, v24, v25
	v_cvt_pk_bf16_f32 v18, v18, v19
	v_cvt_pk_bf16_f32 v19, v20, v21
	v_cvt_pk_bf16_f32 v14, v14, v15
	v_cvt_pk_bf16_f32 v15, v16, v17
	v_cvt_pk_bf16_f32 v10, v10, v11
	v_cvt_pk_bf16_f32 v11, v12, v13
	v_cvt_pk_bf16_f32 v6, v6, v7
	v_cvt_pk_bf16_f32 v7, v8, v9
	v_cvt_pk_bf16_f32 v2, v2, v3
	v_cvt_pk_bf16_f32 v3, v4, v5
	global_store_dwordx2 v[118:119], v[114:115], off
	global_store_dwordx2 v[98:99], v[110:111], off offset:32
	global_store_dwordx2 v[100:101], v[106:107], off offset:32
	global_store_dwordx2 v[118:119], v[102:103], off offset:32
	global_store_dwordx2 v[98:99], v[90:91], off offset:64
	global_store_dwordx2 v[100:101], v[82:83], off offset:64
	global_store_dwordx2 v[122:123], v[74:75], off offset:64
	global_store_dwordx2 v[118:119], v[66:67], off offset:64
	global_store_dwordx2 v[98:99], v[58:59], off offset:96
	global_store_dwordx2 v[100:101], v[50:51], off offset:96
	global_store_dwordx2 v[122:123], v[42:43], off offset:96
	global_store_dwordx2 v[118:119], v[34:35], off offset:160
	global_store_dwordx2 v[98:99], v[30:31], off offset:192
	global_store_dwordx2 v[100:101], v[26:27], off offset:192
	global_store_dwordx2 v[122:123], v[22:23], off offset:192
	global_store_dwordx2 v[118:119], v[18:19], off offset:192
	global_store_dwordx2 v[98:99], v[14:15], off offset:224
	global_store_dwordx2 v[100:101], v[10:11], off offset:224
	global_store_dwordx2 v[122:123], v[6:7], off offset:224
	global_store_dwordx2 v[118:119], v[2:3], off offset:224
	s_branch .LBB0_285

; template <int MT, class Epi>
; DI void gemm_tile(const u16* __restrict__ X, long ldx, const u16* __restrict__ W, long ldw, int K, char* smem,
;                   int m0, int n0, const Epi& epi, bool pre = false, const u16* Xn = nullptr, const u16* Wn = nullptr) {
;     ...
;   const int wu = __builtin_amdgcn_readfirstlane(wave);
;   const unsigned sbase = (unsigned)__builtin_amdgcn_readfirstlane((int)(unsigned)(size_t)smem);
;   const int r8 = lane >> 3, c0 = (lane & 7) ^ (r8 >> 1);
;   const long oxe = (long)(wu * MT * 8 + r8) * ldx + (c0 << 3), oxo = (long)(wu * MT * 8 + r8) * ldx + ((c0 ^ 4) << 3);
;   const long owe = (long)(wu * 32 + r8) * ldw + (c0 << 3), owo = (long)(wu * 32 + r8) * ldw + ((c0 ^ 4) << 3);
;   const u16 *xe = X + oxe, *xo = X + oxo, *we = W + owe, *wo = W + owo;
;   const long ldx8 = 8 * ldx, ldw8 = 8 * ldw;
;   const unsigned xdst = sbase + wu * MT * 1024, wdst = sbase + 16384 + wu * 4096;
;     ...
;   if (!pre) {
;     __syncthreads();
;     GT_DMA(0u)
;   } else {
;     xe += 64; xo += 64; we += 64; wo += 64;
;   }
;   const int nk = K >> 6;
;   int kt = 0;
;   do {
;     asm volatile("s_waitcnt vmcnt(0)" ::: "memory");
;     __syncthreads();
;     if (kt + 1 < nk) GT_DMA((unsigned)((kt + 1) & 1) * 32768u)
;     else if (Xn != nullptr) { xe = Xn + oxe; xo = Xn + oxo; we = Wn + owe; wo = Wn + owo; GT_DMA(0u) }
;     const char* cur = smem + (kt & 1) * 32768;
; #pragma unroll
;     for (int ks = 0; ks < 2; ++ks) {
;       bf16x8 xf[MT], wf[4];
;       const int ch = ((ks * 4 + g) ^ rsw) << 4;
; #pragma unroll
;       for (int i = 0; i < MT; ++i) xf[i] = *(const bf16x8*)(cur + (wm * 16 * MT + i * 16 + lr) * 128 + ch);
; #pragma unroll
;       for (int i = 0; i < 4; ++i) wf[i] = *(const bf16x8*)(cur + 16384 + (wn * 64 + i * 16 + lr) * 128 + ch);
; #pragma unroll
;       for (int nt = 0; nt < 4; ++nt)
; #pragma unroll
;         for (int mt = 0; mt < MT; ++mt)
; DI void phase_even(const Params& p, int e, int sub, char* smem) {
;     ...
;         const int u = t - 1056, c = u >> 3, g = (u >> 1) & 3, tn = u & 1;
;         EpiSgu epi{p.b_spatial + (e * 4 + g) * 128, uvbuf, gbuf, g, c < 128 ? c * 128 : M_PROMPT + (c - 128) * 32, c < 128 ? 128 : 32};
;         gemm_tile<4>(W + WE_WS + (size_t)g * 16384, 128, vT + ((size_t)c * 1024 + g * 256 + tn * 128) * 128, 128, 128, smem, 0, tn * 128, epi);
.LBB0_299:
	s_cmpk_gt_i32 s4, 0x41f
	s_mov_b64 s[38:39], -1
	s_cbranch_scc0 .LBB0_309
	s_add_i32 s7, s4, 0xfffffbe0
	s_bfe_u32 s8, s4, 0x20001
	v_readlane_b32 s56, v252, 8
	s_lshr_b32 s34, s7, 3
	s_lshl_b32 s9, s8, 9
	v_readlane_b32 s66, v252, 18
	v_readlane_b32 s67, v252, 19
	s_add_u32 s38, s66, s9
	s_addc_u32 s39, s67, 0
	s_lshl_b32 s9, s34, 5
	s_lshl_b32 s10, s34, 7
	s_add_i32 s11, s9, 0x3000
	s_cmpk_lt_u32 s7, 0x400
	s_cselect_b32 s9, 0x80, 32
	s_cselect_b32 s7, s10, s11
	s_lshl_b32 s10, s8, 15
	v_readlane_b32 s12, v252, 41
	v_readlane_b32 s13, v252, 42
	s_add_u32 s12, s12, s10
	s_addc_u32 s13, s13, 0
	s_lshl_b64 s[14:15], s[34:35], 10
	s_lshl_b32 s8, s8, 8
	v_mov_b32_e32 v1, v185
	s_or_b32 s11, s14, s8
	s_and_b32 s10, s5, 0x80
	s_or_b32 s14, s11, s10
	v_ashrrev_i32_e32 v3, 6, v1
	v_bfe_u32 v4, v1, 3, 3
	v_readfirstlane_b32 s11, v3
	s_waitcnt vmcnt(3)
	v_bfe_u32 v111, v1, 4, 2
	v_bitop3_b32 v8, v111, v1, 7 bitop3:0x78
	v_lshl_or_b32 v4, s11, 5, v4
	v_ashrrev_i32_e32 v5, 31, v4
	s_lshl_b64 s[14:15], s[14:15], 8
	v_readlane_b32 s16, v252, 37
	v_lshlrev_b64 v[4:5], 8, v[4:5]
	v_lshlrev_b32_e32 v182, 4, v8
	v_readlane_b32 s17, v252, 38
	s_add_u32 s14, s16, s14
	v_mov_b32_e32 v2, v183
	v_lshl_add_u64 v[6:7], s[12:13], 0, v[4:5]
	v_xor_b32_e32 v10, 64, v182
	v_mov_b32_e32 v11, v183
	s_addc_u32 s15, s17, s15
	v_lshl_add_u64 v[8:9], v[6:7], 0, v[182:183]
	v_lshl_add_u64 v[6:7], v[6:7], 0, v[10:11]
	s_lshl_b32 s11, s11, 12
	s_barrier
	s_mov_b32 m0, s11
	s_nop 0
	global_load_lds_dwordx4 v[8:9], off
	s_mov_b64 s[18:19], 0x800
	v_lshl_add_u64 v[4:5], s[14:15], 0, v[4:5]
	v_lshl_add_u64 v[14:15], v[6:7], 0, s[18:19]
	s_or_b32 s12, s11, 0x400
	s_mov_b32 m0, s12
	s_nop 0
	global_load_lds_dwordx4 v[14:15], off
	s_mov_b64 s[14:15], 0x1000
	v_lshl_add_u64 v[14:15], v[8:9], 0, s[14:15]
	s_or_b32 s12, s11, 0x800
	s_mov_b32 m0, s12
	s_nop 0
	global_load_lds_dwordx4 v[14:15], off
	s_mov_b64 s[16:17], 0x1800
	v_lshl_add_u64 v[14:15], v[6:7], 0, s[16:17]
	s_or_b32 s12, s11, 0xc00
	s_mov_b32 m0, s12
	s_nop 0
	global_load_lds_dwordx4 v[14:15], off
	v_lshl_add_u64 v[12:13], v[4:5], 0, v[182:183]
	v_lshl_add_u64 v[4:5], v[4:5], 0, v[10:11]
	s_add_i32 s12, s11, 0x4000
	s_mov_b32 m0, s12
	s_nop 0
	global_load_lds_dwordx4 v[12:13], off
	v_lshl_add_u64 v[10:11], v[4:5], 0, s[18:19]
	s_add_i32 s12, s11, 0x4400
	s_mov_b32 m0, s12
	s_nop 0
	global_load_lds_dwordx4 v[10:11], off
	v_lshl_add_u64 v[10:11], v[12:13], 0, s[14:15]
	s_add_i32 s12, s11, 0x4800
	s_mov_b32 m0, s12
	s_nop 0
	global_load_lds_dwordx4 v[10:11], off
	v_lshl_add_u64 v[10:11], v[4:5], 0, s[16:17]
	s_add_i32 s12, s11, 0x4c00
	s_mov_b32 m0, s12
	s_nop 0
	global_load_lds_dwordx4 v[10:11], off
	s_waitcnt vmcnt(0)
	s_barrier
	s_add_i32 s13, s11, 0x8000
	v_lshl_add_u64 v[10:11], v[8:9], 0, s[28:29]
	s_mov_b32 m0, s13
	s_nop 0
	global_load_lds_dwordx4 v[10:11], off
	s_mov_b64 s[18:19], 0x880
	v_lshl_add_u64 v[10:11], v[6:7], 0, s[18:19]
	s_add_i32 s13, s11, 0x8400
	s_mov_b32 m0, s13
	s_nop 0
	global_load_lds_dwordx4 v[10:11], off
	s_mov_b64 s[20:21], 0x1080
	v_lshl_add_u64 v[8:9], v[8:9], 0, s[20:21]
	s_add_i32 s13, s11, 0x8800
	s_mov_b32 m0, s13
	s_nop 0
	global_load_lds_dwordx4 v[8:9], off
	s_mov_b64 s[16:17], 0x1880
	v_lshl_add_u64 v[6:7], v[6:7], 0, s[16:17]
	s_add_i32 s13, s11, 0x8c00
	s_mov_b32 m0, s13
	s_nop 0
	global_load_lds_dwordx4 v[6:7], off
	s_add_i32 s12, s11, 0xc000
	v_lshl_add_u64 v[14:15], v[12:13], 0, s[28:29]
	s_mov_b32 m0, s12
	s_nop 0
	global_load_lds_dwordx4 v[14:15], off
	v_lshl_add_u64 v[6:7], v[4:5], 0, s[18:19]
	s_add_i32 s12, s11, 0xc400
	s_mov_b32 m0, s12
	s_nop 0
	global_load_lds_dwordx4 v[6:7], off
	v_lshrrev_b32_e32 v16, 1, v1
	v_lshl_add_u64 v[6:7], v[12:13], 0, s[20:21]
	s_add_i32 s12, s11, 0xc800
	s_mov_b32 m0, s12
	s_nop 0
	global_load_lds_dwordx4 v[6:7], off
	v_lshl_add_u64 v[4:5], v[4:5], 0, s[16:17]
	v_and_b32_e32 v110, 15, v1
	v_ashrrev_i32_e32 v112, 7, v1
	s_add_i32 s11, s11, 0xcc00
	s_mov_b32 m0, s11
	s_nop 0
	global_load_lds_dwordx4 v[4:5], off
	v_bitop3_b32 v4, v111, v16, 7 bitop3:0x78
	v_lshlrev_b32_e32 v4, 4, v4
	v_lshlrev_b32_e32 v78, 7, v110
	v_lshlrev_b32_e32 v74, 13, v112
	s_waitcnt vmcnt(1)
	v_or3_b32 v102, v4, v74, v78
	ds_read_b128 v[6:9], v102 offset:16384
	ds_read_b128 v[38:41], v102 offset:18432
	ds_read_b128 v[54:57], v102 offset:20480
	ds_read_b128 v[70:73], v102 offset:22528
	v_bfe_u32 v1, v1, 1, 3
	v_and_b32_e32 v113, 1, v3
	v_bitop3_b32 v1, v111, v1, 4 bitop3:0x36
	v_lshlrev_b32_e32 v79, 13, v113
	v_lshlrev_b32_e32 v1, 4, v1
	v_or3_b32 v86, v4, v79, v78
	v_or_b32_e32 v74, v1, v74
	ds_read_b128 v[10:13], v86
	ds_read_b128 v[18:21], v86 offset:2048
	ds_read_b128 v[26:29], v86 offset:4096
	ds_read_b128 v[34:37], v86 offset:6144
	v_add_u32_e32 v114, v74, v78
	ds_read_b128 v[74:77], v114 offset:16384
	v_or_b32_e32 v1, v1, v79
	v_mov_b32_e32 v3, v2
	v_mov_b32_e32 v4, v2
	v_mov_b32_e32 v5, v2
	v_add_u32_e32 v1, v1, v78
	ds_read_b128 v[78:81], v1 offset:4096
	ds_read_b128 v[82:85], v1 offset:6144
	s_waitcnt lgkmcnt(6)
	v_mfma_f32_16x16x32_bf16 v[14:17], v[6:9], v[10:13], v[2:5]
	v_readlane_b32 s57, v252, 9
	v_readlane_b32 s58, v252, 10
	v_readlane_b32 s59, v252, 11
	s_waitcnt lgkmcnt(5)
	v_mfma_f32_16x16x32_bf16 v[22:25], v[6:9], v[18:21], v[2:5]
	v_readlane_b32 s60, v252, 12
	v_readlane_b32 s61, v252, 13
	v_readlane_b32 s62, v252, 14
	s_waitcnt lgkmcnt(4)
	v_mfma_f32_16x16x32_bf16 v[30:33], v[6:9], v[26:29], v[2:5]
	v_readlane_b32 s63, v252, 15
	v_readlane_b32 s64, v252, 16
	v_readlane_b32 s65, v252, 17
	s_waitcnt lgkmcnt(3)
; template <int MT, class Epi>
; DI void gemm_tile(const u16* __restrict__ X, long ldx, const u16* __restrict__ W, long ldw, int K, char* smem,
;                   int m0, int n0, const Epi& epi, bool pre = false, const u16* Xn = nullptr, const u16* Wn = nullptr) {
;     ...
; #pragma unroll
;     for (int ks = 0; ks < 2; ++ks) {
;       bf16x8 xf[MT], wf[4];
;       const int ch = ((ks * 4 + g) ^ rsw) << 4;
; #pragma unroll
;       for (int i = 0; i < MT; ++i) xf[i] = *(const bf16x8*)(cur + (wm * 16 * MT + i * 16 + lr) * 128 + ch);
; #pragma unroll
;       for (int i = 0; i < 4; ++i) wf[i] = *(const bf16x8*)(cur + 16384 + (wn * 64 + i * 16 + lr) * 128 + ch);
; #pragma unroll
;       for (int nt = 0; nt < 4; ++nt)
; #pragma unroll
;         for (int mt = 0; mt < MT; ++mt)
;           acc[nt][mt] = __builtin_amdgcn_mfma_f32_16x16x32_bf16(wf[nt], xf[mt], acc[nt][mt], 0, 0, 0);
;     }
;   } while (++kt < nk);
;     ...
;   epi.run(acc, m0 + wm * 16 * MT + lr, n0 + wn * 64 + 4 * g);
;   template <int NT, int MT> DI void run(f32x4 (&acc)[NT][MT], int mb, int nb) const {
; #pragma unroll
;     for (int mt = 0; mt < MT; ++mt) {
;       const int i = mb + mt * 16;
;       if (i < nvalid) {
	v_mfma_f32_16x16x32_bf16 v[6:9], v[6:9], v[34:37], v[2:5]
	v_readlane_b32 s68, v252, 20
	v_readlane_b32 s69, v252, 21
	v_readlane_b32 s70, v252, 22
	v_mfma_f32_16x16x32_bf16 v[42:45], v[38:41], v[10:13], v[2:5]
	v_readlane_b32 s71, v252, 23
	v_mfma_f32_16x16x32_bf16 v[46:49], v[38:41], v[18:21], v[2:5]
	v_mfma_f32_16x16x32_bf16 v[50:53], v[38:41], v[26:29], v[2:5]
	v_mfma_f32_16x16x32_bf16 v[38:41], v[38:41], v[34:37], v[2:5]
	v_mfma_f32_16x16x32_bf16 v[58:61], v[54:57], v[10:13], v[2:5]
	v_mfma_f32_16x16x32_bf16 v[62:65], v[54:57], v[18:21], v[2:5]
	v_mfma_f32_16x16x32_bf16 v[66:69], v[54:57], v[26:29], v[2:5]
	v_mfma_f32_16x16x32_bf16 v[54:57], v[54:57], v[34:37], v[2:5]
	v_mfma_f32_16x16x32_bf16 v[10:13], v[70:73], v[10:13], v[2:5]
	v_mfma_f32_16x16x32_bf16 v[18:21], v[70:73], v[18:21], v[2:5]
	v_mfma_f32_16x16x32_bf16 v[26:29], v[70:73], v[26:29], v[2:5]
	v_mfma_f32_16x16x32_bf16 v[2:5], v[70:73], v[34:37], v[2:5]
	ds_read_b128 v[34:37], v1
	ds_read_b128 v[70:73], v1 offset:2048
	s_waitcnt lgkmcnt(1)
	v_mfma_f32_16x16x32_bf16 v[14:17], v[74:77], v[34:37], v[14:17]
	s_waitcnt lgkmcnt(0)
	v_mfma_f32_16x16x32_bf16 v[22:25], v[74:77], v[70:73], v[22:25]
	v_mfma_f32_16x16x32_bf16 v[30:33], v[74:77], v[78:81], v[30:33]
	v_mfma_f32_16x16x32_bf16 v[6:9], v[74:77], v[82:85], v[6:9]
	ds_read_b128 v[74:77], v114 offset:18432
	s_waitcnt lgkmcnt(0)
	v_mfma_f32_16x16x32_bf16 v[42:45], v[74:77], v[34:37], v[42:45]
	v_mfma_f32_16x16x32_bf16 v[46:49], v[74:77], v[70:73], v[46:49]
	v_mfma_f32_16x16x32_bf16 v[50:53], v[74:77], v[78:81], v[50:53]
	v_mfma_f32_16x16x32_bf16 v[38:41], v[74:77], v[82:85], v[38:41]
	ds_read_b128 v[74:77], v114 offset:20480
	s_waitcnt lgkmcnt(0)
	v_mfma_f32_16x16x32_bf16 v[58:61], v[74:77], v[34:37], v[58:61]
	v_mfma_f32_16x16x32_bf16 v[62:65], v[74:77], v[70:73], v[62:65]
	v_mfma_f32_16x16x32_bf16 v[66:69], v[74:77], v[78:81], v[66:69]
	v_mfma_f32_16x16x32_bf16 v[54:57], v[74:77], v[82:85], v[54:57]
	ds_read_b128 v[74:77], v114 offset:22528
	s_waitcnt vmcnt(0)
	s_waitcnt lgkmcnt(0)
	v_mfma_f32_16x16x32_bf16 v[10:13], v[74:77], v[34:37], v[10:13]
	s_barrier
	ds_read_b128 v[34:37], v102 offset:49152
	v_mfma_f32_16x16x32_bf16 v[18:21], v[74:77], v[70:73], v[18:21]
	ds_read_b128 v[70:73], v86 offset:32768
	ds_read_b128 v[106:109], v1 offset:38912
	v_mfma_f32_16x16x32_bf16 v[26:29], v[74:77], v[78:81], v[26:29]
	ds_read_b128 v[78:81], v86 offset:36864
	v_mfma_f32_16x16x32_bf16 v[2:5], v[74:77], v[82:85], v[2:5]
	ds_read_b128 v[74:77], v86 offset:34816
	ds_read_b128 v[82:85], v86 offset:38912
	s_waitcnt lgkmcnt(4)
	v_mfma_f32_16x16x32_bf16 v[14:17], v[34:37], v[70:73], v[14:17]
	s_waitcnt lgkmcnt(1)
	v_mfma_f32_16x16x32_bf16 v[22:25], v[34:37], v[74:77], v[22:25]
	v_mfma_f32_16x16x32_bf16 v[30:33], v[34:37], v[78:81], v[30:33]
	s_waitcnt lgkmcnt(0)
	v_mfma_f32_16x16x32_bf16 v[6:9], v[34:37], v[82:85], v[6:9]
	ds_read_b128 v[34:37], v102 offset:51200
	s_waitcnt lgkmcnt(0)
	v_mfma_f32_16x16x32_bf16 v[42:45], v[34:37], v[70:73], v[42:45]
	v_mfma_f32_16x16x32_bf16 v[86:89], v[34:37], v[74:77], v[46:49]
	v_mfma_f32_16x16x32_bf16 v[50:53], v[34:37], v[78:81], v[50:53]
	v_mfma_f32_16x16x32_bf16 v[34:37], v[34:37], v[82:85], v[38:41]
	s_nop 2
	ds_read_b128 v[38:41], v102 offset:53248
	s_waitcnt lgkmcnt(0)
	v_mfma_f32_16x16x32_bf16 v[90:93], v[38:41], v[70:73], v[58:61]
	s_waitcnt vmcnt(0)
	v_mfma_f32_16x16x32_bf16 v[94:97], v[38:41], v[74:77], v[62:65]
	v_mfma_f32_16x16x32_bf16 v[66:69], v[38:41], v[78:81], v[66:69]
	v_mfma_f32_16x16x32_bf16 v[98:101], v[38:41], v[82:85], v[54:57]
	ds_read_b128 v[38:41], v102 offset:55296
	ds_read_b128 v[102:105], v1 offset:36864
	s_waitcnt lgkmcnt(1)
	v_mfma_f32_16x16x32_bf16 v[70:73], v[38:41], v[70:73], v[10:13]
	s_nop 2
	ds_read_b128 v[10:13], v114 offset:49152
	v_mfma_f32_16x16x32_bf16 v[18:21], v[38:41], v[74:77], v[18:21]
	v_mfma_f32_16x16x32_bf16 v[74:77], v[38:41], v[78:81], v[26:29]
	ds_read_b128 v[78:81], v1 offset:32768
	v_mfma_f32_16x16x32_bf16 v[2:5], v[38:41], v[82:85], v[2:5]
	ds_read_b128 v[82:85], v1 offset:34816
	v_lshl_add_u32 v1, v112, 6, s10
	v_lshl_or_b32 v1, v111, 2, v1
	s_waitcnt lgkmcnt(1)
	v_mfma_f32_16x16x32_bf16 v[62:65], v[10:13], v[78:81], v[14:17]
	v_mfma_f32_16x16x32_bf16 v[14:17], v[10:13], v[106:109], v[6:9]
	s_nop 2
	ds_read_b128 v[6:9], v114 offset:51200
	s_waitcnt lgkmcnt(1)
	v_mfma_f32_16x16x32_bf16 v[46:49], v[10:13], v[82:85], v[22:25]
	v_mfma_f32_16x16x32_bf16 v[30:33], v[10:13], v[102:105], v[30:33]
	s_waitcnt lgkmcnt(0)
	v_mfma_f32_16x16x32_bf16 v[58:61], v[6:9], v[78:81], v[42:45]
	v_mfma_f32_16x16x32_bf16 v[42:45], v[6:9], v[82:85], v[86:89]
	v_mfma_f32_16x16x32_bf16 v[26:29], v[6:9], v[102:105], v[50:53]
	s_nop 1
	ds_read_b128 v[86:89], v114 offset:55296
	v_mfma_f32_16x16x32_bf16 v[10:13], v[6:9], v[106:109], v[34:37]
	ds_read_b128 v[6:9], v114 offset:53248
	s_waitcnt lgkmcnt(0)
	v_mfma_f32_16x16x32_bf16 v[54:57], v[6:9], v[78:81], v[90:93]
	v_mfma_f32_16x16x32_bf16 v[38:41], v[6:9], v[82:85], v[94:97]
	v_mfma_f32_16x16x32_bf16 v[22:25], v[6:9], v[102:105], v[66:69]
	v_mfma_f32_16x16x32_bf16 v[6:9], v[6:9], v[106:109], v[98:101]
	s_nop 1
	v_lshl_or_b32 v67, v113, 6, v110
	v_cmp_gt_u32_e32 vcc, s9, v67
	v_mfma_f32_16x16x32_bf16 v[50:53], v[86:89], v[78:81], v[70:73]
	v_mfma_f32_16x16x32_bf16 v[34:37], v[86:89], v[82:85], v[18:21]
	v_mfma_f32_16x16x32_bf16 v[18:21], v[86:89], v[102:105], v[74:77]
	v_mfma_f32_16x16x32_bf16 v[2:5], v[86:89], v[106:109], v[2:5]
	s_and_saveexec_b64 s[40:41], vcc
	s_cbranch_execz .LBB0_302
; DI float bflo(unsigned u) { return __uint_as_float(u << 16); }
; DI float bfhi(unsigned u) { return __uint_as_float(u & 0xffff0000u); }
; DI void st_bf4(u16* p, float a, float b, float c, float d) { *(uint2*)p = make_uint2(pk2(a, b), pk2(c, d)); }
;   template <int NT, int MT> DI void run(f32x4 (&acc)[NT][MT], int mb, int nb) const {
; #pragma unroll
;     for (int mt = 0; mt < MT; ++mt) {
;       const int i = mb + mt * 16;
;       if (i < nvalid) {
;         const float bias = bs[i];
;         const size_t row = (size_t)(rowbase + i);
; #pragma unroll
;         for (int nt = 0; nt < NT; ++nt) {
;           const int ch = g * 256 + nb + nt * 16;
;           const uint2 uu = *(const uint2*)(uv + row * 2048 + ch);
;           u16* q = mix + row * 2048 + 1024 + ch;
;           const uint2 gt = *(const uint2*)q;
;           f32x4 v = acc[nt][mt];
;           st_bf4(q, (v[0] + bias) * bflo(uu.x) * bflo(gt.x), (v[1] + bias) * bfhi(uu.x) * bfhi(gt.x),
;                  (v[2] + bias) * bflo(uu.y) * bflo(gt.y), (v[3] + bias) * bfhi(uu.y) * bfhi(gt.y));
;         }
;       }
;     }
	v_mov_b32_e32 v135, v183
	v_add_u32_e32 v134, s7, v67
	v_readlane_b32 s10, v252, 33
	v_add_u32_e32 v136, s8, v1
	v_lshlrev_b64 v[138:139], 12, v[134:135]
	v_readlane_b32 s11, v252, 34
	v_ashrrev_i32_e32 v137, 31, v136
	v_lshlrev_b64 v[140:141], 1, v[136:137]
	v_lshl_add_u64 v[142:143], s[10:11], 0, v[138:139]
	v_readlane_b32 s10, v252, 35
	v_readlane_b32 s11, v252, 36
	v_lshlrev_b32_e32 v144, 2, v67
	v_lshl_add_u64 v[146:147], v[142:143], 0, v[140:141]
	v_lshl_add_u64 v[148:149], s[10:11], 0, v[138:139]
	global_load_dword v145, v144, s[38:39] offset:2048
	v_lshl_add_u64 v[150:151], v[148:149], 0, v[140:141]
	global_load_dwordx2 v[152:153], v[146:147], off
	global_load_dwordx2 v[154:155], v[150:151], off offset:2048
	v_add_u32_e32 v156, 16, v136
	v_ashrrev_i32_e32 v157, 31, v156
	v_lshlrev_b64 v[158:159], 1, v[156:157]
	v_lshl_add_u64 v[160:161], v[142:143], 0, v[158:159]
	global_load_dwordx2 v[162:163], v[160:161], off
	v_lshl_add_u64 v[164:165], v[148:149], 0, v[158:159]
	global_load_dwordx2 v[166:167], v[164:165], off offset:2048
	v_add_u32_e32 v168, 32, v136
	v_ashrrev_i32_e32 v169, 31, v168
	v_lshlrev_b64 v[170:171], 1, v[168:169]
	v_lshl_add_u64 v[172:173], v[142:143], 0, v[170:171]
	global_load_dwordx2 v[174:175], v[172:173], off
	v_lshl_add_u64 v[176:177], v[148:149], 0, v[170:171]
	global_load_dwordx2 v[178:179], v[176:177], off offset:2048
	v_add_u32_e32 v180, 48, v136
	v_ashrrev_i32_e32 v181, 31, v180
	v_lshlrev_b64 v[186:187], 1, v[180:181]
	v_lshl_add_u64 v[188:189], v[142:143], 0, v[186:187]
	global_load_dwordx2 v[190:191], v[188:189], off
	v_lshl_add_u64 v[192:193], v[148:149], 0, v[186:187]
	global_load_dwordx2 v[194:195], v[192:193], off offset:2048
	s_nop 0
	s_nop 0
	s_nop 0
	s_nop 0
	s_nop 0
	s_nop 0
	s_nop 0
	s_nop 0
	s_nop 0
	s_nop 0
	s_nop 0
	s_nop 0
	s_nop 0
	s_nop 0
	s_nop 0
	s_nop 0
	s_waitcnt vmcnt(8)
	v_mov_b32_e32 v196, v145
	v_mov_b32_e32 v197, v67
	v_pk_add_f32 v[62:63], v[62:63], v[196:197] op_sel_hi:[1,0]
	s_nop 0
	s_waitcnt vmcnt(7)
	v_lshlrev_b32_e32 v80, 16, v152
	v_and_b32_e32 v81, 0xffff0000, v152
	v_lshlrev_b32_e32 v76, 16, v153
	v_and_b32_e32 v77, 0xffff0000, v153
	v_mov_b32_e32 v224, v145
	v_mov_b32_e32 v225, v67
	v_pk_add_f32 v[64:65], v[64:65], v[224:225] op_sel_hi:[1,0]
	v_pk_mul_f32 v[62:63], v[62:63], v[80:81]
	v_pk_mul_f32 v[64:65], v[64:65], v[76:77]
	v_mov_b32_e32 v226, v145
	v_mov_b32_e32 v227, v67
	v_pk_add_f32 v[58:59], v[58:59], v[226:227] op_sel_hi:[1,0]
	v_mov_b32_e32 v228, v145
	v_mov_b32_e32 v229, v67
	v_pk_add_f32 v[60:61], v[60:61], v[228:229] op_sel_hi:[1,0]
	v_mov_b32_e32 v230, v145
	v_mov_b32_e32 v231, v67
	v_pk_add_f32 v[54:55], v[54:55], v[230:231] op_sel_hi:[1,0]
	v_mov_b32_e32 v232, v145
	v_mov_b32_e32 v233, v67
	v_pk_add_f32 v[56:57], v[56:57], v[232:233] op_sel_hi:[1,0]
	v_mov_b32_e32 v234, v145
	v_mov_b32_e32 v235, v67
	v_pk_add_f32 v[50:51], v[50:51], v[234:235] op_sel_hi:[1,0]
	v_mov_b32_e32 v236, v145
	v_mov_b32_e32 v237, v67
	v_pk_add_f32 v[52:53], v[52:53], v[236:237] op_sel_hi:[1,0]
	s_waitcnt vmcnt(6)
	v_lshlrev_b32_e32 v82, 16, v154
	v_and_b32_e32 v83, 0xffff0000, v154
	v_lshlrev_b32_e32 v78, 16, v155
	v_and_b32_e32 v79, 0xffff0000, v155
	v_pk_mul_f32 v[62:63], v[62:63], v[82:83]
	v_pk_mul_f32 v[64:65], v[64:65], v[78:79]
	v_cvt_pk_bf16_f32 v62, v62, v63
	v_cvt_pk_bf16_f32 v63, v64, v65
	global_store_dwordx2 v[150:151], v[62:63], off offset:2048
	s_nop 0
	s_nop 0
	s_nop 0
	s_nop 0
	s_nop 0
	s_nop 0
	s_nop 0
	s_waitcnt vmcnt(5)
	v_lshlrev_b32_e32 v76, 16, v162
	v_and_b32_e32 v77, 0xffff0000, v162
	v_lshlrev_b32_e32 v64, 16, v163
	v_and_b32_e32 v65, 0xffff0000, v163
	s_waitcnt vmcnt(4)
	v_lshlrev_b32_e32 v78, 16, v166
	v_and_b32_e32 v79, 0xffff0000, v166
	v_pk_mul_f32 v[58:59], v[58:59], v[76:77]
	v_lshlrev_b32_e32 v74, 16, v167
	v_and_b32_e32 v75, 0xffff0000, v167
	v_pk_mul_f32 v[60:61], v[60:61], v[64:65]
	v_pk_mul_f32 v[58:59], v[58:59], v[78:79]
	v_pk_mul_f32 v[60:61], v[60:61], v[74:75]
	v_cvt_pk_bf16_f32 v58, v58, v59
	v_cvt_pk_bf16_f32 v59, v60, v61
	global_store_dwordx2 v[164:165], v[58:59], off offset:2048
	s_nop 0
	s_nop 0
	s_nop 0
	s_nop 0
	s_nop 0
	s_nop 0
	s_nop 0
	s_waitcnt vmcnt(3)
	v_lshlrev_b32_e32 v64, 16, v174
	v_and_b32_e32 v65, 0xffff0000, v174
	v_lshlrev_b32_e32 v60, 16, v175
	v_and_b32_e32 v61, 0xffff0000, v175
	s_waitcnt vmcnt(2)
	v_lshlrev_b32_e32 v74, 16, v178
	v_and_b32_e32 v75, 0xffff0000, v178
	v_pk_mul_f32 v[54:55], v[54:55], v[64:65]
	v_lshlrev_b32_e32 v62, 16, v179
	v_and_b32_e32 v63, 0xffff0000, v179
	v_pk_mul_f32 v[56:57], v[56:57], v[60:61]
	v_pk_mul_f32 v[54:55], v[54:55], v[74:75]
	v_pk_mul_f32 v[56:57], v[56:57], v[62:63]
	v_cvt_pk_bf16_f32 v54, v54, v55
	v_cvt_pk_bf16_f32 v55, v56, v57
	global_store_dwordx2 v[176:177], v[54:55], off offset:2048
	s_nop 0
	s_nop 0
	s_nop 0
	s_nop 0
	s_nop 0
	s_nop 0
	s_nop 0
	s_waitcnt vmcnt(1)
	v_lshlrev_b32_e32 v60, 16, v190
	v_and_b32_e32 v61, 0xffff0000, v190
	v_lshlrev_b32_e32 v56, 16, v191
	v_and_b32_e32 v57, 0xffff0000, v191
	s_waitcnt vmcnt(0)
	v_lshlrev_b32_e32 v62, 16, v194
	v_and_b32_e32 v63, 0xffff0000, v194
	v_pk_mul_f32 v[50:51], v[50:51], v[60:61]
	v_lshlrev_b32_e32 v58, 16, v195
	v_and_b32_e32 v59, 0xffff0000, v195
	v_pk_mul_f32 v[52:53], v[52:53], v[56:57]
	v_pk_mul_f32 v[50:51], v[50:51], v[62:63]
	v_pk_mul_f32 v[52:53], v[52:53], v[58:59]
	v_cvt_pk_bf16_f32 v50, v50, v51
	v_cvt_pk_bf16_f32 v51, v52, v53
	global_store_dwordx2 v[192:193], v[50:51], off offset:2048
	v_mov_b32_e32 v54, v192
	v_mov_b32_e32 v55, v193
	v_mov_b32_e32 v66, v145
	v_mov_b32_e32 v68, v142
	v_mov_b32_e32 v69, v143
	v_mov_b32_e32 v70, v136
	v_mov_b32_e32 v71, v137
	v_mov_b32_e32 v72, v148
	v_mov_b32_e32 v73, v149
	v_mov_b32_e32 v182, v134

; template <int MT, class Epi>
; DI void gemm_tile(const u16* __restrict__ X, long ldx, const u16* __restrict__ W, long ldw, int K, char* smem,
;                   int m0, int n0, const Epi& epi, bool pre = false, const u16* Xn = nullptr, const u16* Wn = nullptr) {
;     ...
;   const int wu = __builtin_amdgcn_readfirstlane(wave);
;   const unsigned sbase = (unsigned)__builtin_amdgcn_readfirstlane((int)(unsigned)(size_t)smem);
;   const int r8 = lane >> 3, c0 = (lane & 7) ^ (r8 >> 1);
;   const long oxe = (long)(wu * MT * 8 + r8) * ldx + (c0 << 3), oxo = (long)(wu * MT * 8 + r8) * ldx + ((c0 ^ 4) << 3);
;   const long owe = (long)(wu * 32 + r8) * ldw + (c0 << 3), owo = (long)(wu * 32 + r8) * ldw + ((c0 ^ 4) << 3);
;   const u16 *xe = X + oxe, *xo = X + oxo, *we = W + owe, *wo = W + owo;
;   const long ldx8 = 8 * ldx, ldw8 = 8 * ldw;
;   const unsigned xdst = sbase + wu * MT * 1024, wdst = sbase + 16384 + wu * 4096;
;     ...
;   if (!pre) {
;     __syncthreads();
;     GT_DMA(0u)
;   } else {
;     xe += 64; xo += 64; we += 64; wo += 64;
;   }
;   const int nk = K >> 6;
;   int kt = 0;
;   do {
;     asm volatile("s_waitcnt vmcnt(0)" ::: "memory");
;     __syncthreads();
;     if (kt + 1 < nk) GT_DMA((unsigned)((kt + 1) & 1) * 32768u)
;     else if (Xn != nullptr) { xe = Xn + oxe; xo = Xn + oxo; we = Wn + owe; wo = Wn + owo; GT_DMA(0u) }
;     const char* cur = smem + (kt & 1) * 32768;
; #pragma unroll
;     for (int ks = 0; ks < 2; ++ks) {
;       bf16x8 xf[MT], wf[4];
;       const int ch = ((ks * 4 + g) ^ rsw) << 4;
; #pragma unroll
;       for (int i = 0; i < MT; ++i) xf[i] = *(const bf16x8*)(cur + (wm * 16 * MT + i * 16 + lr) * 128 + ch);
; #pragma unroll
;       for (int i = 0; i < 4; ++i) wf[i] = *(const bf16x8*)(cur + 16384 + (wn * 64 + i * 16 + lr) * 128 + ch);
; #pragma unroll
;       for (int nt = 0; nt < 4; ++nt)
; #pragma unroll
;         for (int mt = 0; mt < MT; ++mt)
; DI void phase_even(const Params& p, int e, int sub, char* smem) {
;     ...
;     for (int t = get_bid(); t < 1056 + 1152; t += gridDim.x) {
;       if (t < 1056) {
;         const int g = t / 264, r = t % 264, tm = r >> 1, tn = r & 1;
;         EpiPool epi{p.pool_scale + e * 1024, gbuf, g};
;         gemm_tile<4>(hbuf + (size_t)tm * 128 * 1024 + g * 256, 1024, W + WE_POOL + (size_t)g * 65536 + (size_t)tn * 128 * 256, 256, 256, smem,
;                      tm * 128, tn * 128, epi);
.LBB0_309:
	s_and_b64 vcc, exec, s[38:39]
	s_cbranch_vccz .LBB0_298
	s_mul_hi_i32 s7, s4, 0x3e0f83e1
	s_lshr_b32 s8, s7, 31
	s_ashr_i32 s7, s7, 6
	s_add_i32 s8, s7, s8
	s_mul_i32 s7, s8, 0xfffffef8
	s_add_i32 s7, s4, s7
	s_ashr_i32 s10, s7, 1
	s_ashr_i32 s11, s10, 31
	s_and_b32 s16, s7, 1
	s_lshl_b64 s[12:13], s[10:11], 18
	s_add_u32 s7, s0, s12
	s_addc_u32 s9, s1, s13
	s_lshl_b32 s38, s8, 8
	s_ashr_i32 s39, s38, 31
	s_lshl_b64 s[12:13], s[38:39], 1
	s_add_u32 s12, s7, s12
	s_addc_u32 s13, s9, s13
	s_ashr_i32 s9, s8, 31
	s_lshl_b64 s[8:9], s[8:9], 17
	v_readlane_b32 s7, v252, 43
	s_add_u32 s7, s7, s8
	v_readlane_b32 s8, v252, 44
	s_waitcnt vmcnt(7)
	v_mov_b32_e32 v18, v185
	s_addc_u32 s8, s8, s9
	s_lshl_b32 s9, s16, 16
	s_add_u32 s14, s7, s9
	v_ashrrev_i32_e32 v2, 6, v18
	v_and_b32_e32 v54, 1, v2
	v_readfirstlane_b32 s9, v2
	v_bfe_u32 v2, v18, 3, 3
	v_bfe_u32 v55, v18, 4, 2
	v_lshl_or_b32 v2, s9, 5, v2
	v_bitop3_b32 v6, v55, v18, 7 bitop3:0x78
	v_ashrrev_i32_e32 v3, 31, v2
	v_lshlrev_b64 v[4:5], 11, v[2:3]
	v_lshlrev_b32_e32 v182, 4, v6
	v_mov_b32_e32 v12, v183
	v_lshl_add_u64 v[4:5], s[12:13], 0, v[4:5]
	v_xor_b32_e32 v8, 64, v182
	v_mov_b32_e32 v9, v183
	s_addc_u32 s15, s8, 0
	s_lshl_b32 s7, s10, 7
	v_lshl_add_u64 v[6:7], v[4:5], 0, v[182:183]
	v_lshl_add_u64 v[4:5], v[4:5], 0, v[8:9]
	s_lshl_b32 s17, s9, 12
	s_barrier
	s_mov_b32 m0, s17
	s_nop 0
	global_load_lds_dwordx4 v[6:7], off
	s_mov_b64 s[10:11], 0x4000
	v_lshl_add_u64 v[16:17], v[4:5], 0, s[10:11]
	s_or_b32 s18, s17, 0x400
	s_mov_b32 m0, s18
	s_nop 0
	global_load_lds_dwordx4 v[16:17], off
	s_mov_b64 s[10:11], 0x8000
	v_lshlrev_b64 v[2:3], 9, v[2:3]
	v_lshl_add_u64 v[16:17], v[6:7], 0, s[10:11]
	s_or_b32 s19, s17, 0x800
	s_mov_b32 m0, s19
	s_nop 0
	global_load_lds_dwordx4 v[16:17], off
	s_mov_b64 s[10:11], 0xc000
	v_lshl_add_u64 v[10:11], s[14:15], 0, v[2:3]
	v_lshl_add_u64 v[16:17], v[4:5], 0, s[10:11]
	s_or_b32 s34, s17, 0xc00
	s_mov_b32 m0, s34
	s_nop 0
	global_load_lds_dwordx4 v[16:17], off
	v_lshl_add_u64 v[2:3], v[10:11], 0, v[182:183]
	v_lshl_add_u64 v[8:9], v[10:11], 0, v[8:9]
	s_add_i32 s39, s17, 0x4000
	s_mov_b32 m0, s39
	s_nop 0
	global_load_lds_dwordx4 v[2:3], off
	s_mov_b64 s[10:11], 0x1000
	v_lshl_add_u64 v[10:11], v[8:9], 0, s[10:11]
	s_add_i32 s40, s17, 0x4400
	s_mov_b32 m0, s40
	s_nop 0
	global_load_lds_dwordx4 v[10:11], off
	s_mov_b64 s[10:11], 0x2000
	v_lshl_add_u64 v[10:11], v[2:3], 0, s[10:11]
	s_add_i32 s41, s17, 0x4800
	s_mov_b32 m0, s41
	s_nop 0
	global_load_lds_dwordx4 v[10:11], off
	s_mov_b64 s[10:11], 0x3000
	v_lshl_add_u64 v[10:11], v[8:9], 0, s[10:11]
	s_add_i32 s42, s17, 0x4c00
	s_mov_b32 m0, s42
	s_nop 0
	global_load_lds_dwordx4 v[10:11], off
	s_waitcnt vmcnt(0)
	s_barrier
	v_lshl_add_u64 v[10:11], v[6:7], 0, s[28:29]
	s_add_i32 s12, s17, 0x8000
	s_mov_b32 m0, s12
	s_nop 0
	global_load_lds_dwordx4 v[10:11], off
	v_lshl_add_u64 v[10:11], v[4:5], 0, s[94:95]
	s_add_i32 s10, s17, 0x8400
	s_mov_b32 m0, s10
	s_nop 0
	global_load_lds_dwordx4 v[10:11], off
	v_lshl_add_u64 v[10:11], v[6:7], 0, s[78:79]
	s_add_i32 s9, s17, 0x8800
	s_mov_b32 m0, s9
	s_nop 0
	global_load_lds_dwordx4 v[10:11], off
	v_lshl_add_u64 v[10:11], v[4:5], 0, s[54:55]
	s_add_i32 s13, s17, 0x8c00
	s_mov_b32 m0, s13
	s_nop 0
	global_load_lds_dwordx4 v[10:11], off
	v_lshl_add_u64 v[16:17], v[2:3], 0, s[28:29]
	s_add_i32 s11, s17, 0xc000
	s_mov_b32 m0, s11
	s_nop 0
	global_load_lds_dwordx4 v[16:17], off
	s_mov_b64 s[14:15], 0x1080
	v_lshl_add_u64 v[10:11], v[8:9], 0, s[14:15]
	s_mov_b64 s[20:21], 0x2080
	s_add_i32 s15, s17, 0xc400
	s_mov_b32 m0, s15
	s_nop 0
	global_load_lds_dwordx4 v[10:11], off
	v_lshl_add_u64 v[10:11], v[2:3], 0, s[20:21]
	s_mov_b64 s[20:21], 0x3080
	s_lshl_b32 s8, s16, 7
	v_lshrrev_b32_e32 v19, 1, v18
	s_add_i32 s14, s17, 0xc800
	s_mov_b32 m0, s14
	s_nop 0
	global_load_lds_dwordx4 v[10:11], off
	v_lshl_add_u64 v[10:11], v[8:9], 0, s[20:21]
	v_and_b32_e32 v1, 15, v18
	v_ashrrev_i32_e32 v56, 7, v18
	s_add_i32 s16, s17, 0xcc00
	s_mov_b32 m0, s16
	s_nop 0
	global_load_lds_dwordx4 v[10:11], off
	v_bitop3_b32 v10, v55, v19, 7 bitop3:0x78
	v_lshlrev_b32_e32 v11, 4, v10
	v_lshlrev_b32_e32 v90, 13, v54
	s_waitcnt vmcnt(1)
	v_lshlrev_b32_e32 v102, 7, v1
	v_lshlrev_b32_e32 v103, 13, v56
	v_or3_b32 v10, v11, v90, v102
	v_or3_b32 v11, v11, v103, v102
	v_bfe_u32 v57, v18, 1, 3
	ds_read_b128 v[16:19], v10
	ds_read_b128 v[20:23], v10 offset:2048
	ds_read_b128 v[24:27], v10 offset:4096
	ds_read_b128 v[28:31], v10 offset:6144
	ds_read_b128 v[32:35], v11 offset:16384
	ds_read_b128 v[36:39], v11 offset:18432
	ds_read_b128 v[40:43], v11 offset:20480
	ds_read_b128 v[44:47], v11 offset:22528
	v_mov_b32_e32 v13, v12
	v_mov_b32_e32 v14, v12
	v_mov_b32_e32 v15, v12
	s_mov_b64 s[20:21], 0x100
	v_lshl_add_u64 v[52:53], v[6:7], 0, s[20:21]
	s_waitcnt lgkmcnt(3)
	v_mfma_f32_16x16x32_bf16 v[48:51], v[32:35], v[16:19], v[12:15]
	v_lshl_add_u64 v[118:119], v[2:3], 0, s[20:21]
	s_mov_b64 s[20:21], 0x4100
	v_lshlrev_b32_e32 v54, 6, v54
	v_mfma_f32_16x16x32_bf16 v[58:61], v[32:35], v[20:23], v[12:15]
	v_mfma_f32_16x16x32_bf16 v[62:65], v[32:35], v[24:27], v[12:15]
	v_mfma_f32_16x16x32_bf16 v[32:35], v[32:35], v[28:31], v[12:15]
	s_waitcnt lgkmcnt(2)
	v_mfma_f32_16x16x32_bf16 v[66:69], v[36:39], v[16:19], v[12:15]
	v_mfma_f32_16x16x32_bf16 v[70:73], v[36:39], v[20:23], v[12:15]
	v_mfma_f32_16x16x32_bf16 v[74:77], v[36:39], v[24:27], v[12:15]
	v_mfma_f32_16x16x32_bf16 v[36:39], v[36:39], v[28:31], v[12:15]
	s_waitcnt lgkmcnt(1)
	v_mfma_f32_16x16x32_bf16 v[78:81], v[40:43], v[16:19], v[12:15]
	v_mfma_f32_16x16x32_bf16 v[82:85], v[40:43], v[20:23], v[12:15]
	v_mfma_f32_16x16x32_bf16 v[86:89], v[40:43], v[24:27], v[12:15]
	v_mfma_f32_16x16x32_bf16 v[40:43], v[40:43], v[28:31], v[12:15]
	s_waitcnt lgkmcnt(0)
	v_mfma_f32_16x16x32_bf16 v[16:19], v[44:47], v[16:19], v[12:15]
	v_mfma_f32_16x16x32_bf16 v[20:23], v[44:47], v[20:23], v[12:15]
	v_mfma_f32_16x16x32_bf16 v[24:27], v[44:47], v[24:27], v[12:15]
	v_mfma_f32_16x16x32_bf16 v[28:31], v[44:47], v[28:31], v[12:15]
	s_nop 2
	v_bitop3_b32 v12, v55, v57, 4 bitop3:0x36
	v_lshlrev_b32_e32 v13, 4, v12
	v_or_b32_e32 v12, v13, v90
	v_or_b32_e32 v13, v13, v103
	v_add_u32_e32 v12, v12, v102
	v_add_u32_e32 v13, v13, v102
	ds_read_b128 v[44:47], v12
	ds_read_b128 v[90:93], v12 offset:2048
	s_waitcnt vmcnt(0)
	ds_read_b128 v[94:97], v12 offset:4096
	ds_read_b128 v[98:101], v12 offset:6144
	ds_read_b128 v[102:105], v13 offset:16384
	ds_read_b128 v[106:109], v13 offset:18432
	ds_read_b128 v[110:113], v13 offset:20480
	ds_read_b128 v[114:117], v13 offset:22528
	s_waitcnt vmcnt(0)
	s_waitcnt lgkmcnt(0)
	s_barrier
; template <int MT, class Epi>
; DI void gemm_tile(const u16* __restrict__ X, long ldx, const u16* __restrict__ W, long ldw, int K, char* smem,
;                   int m0, int n0, const Epi& epi, bool pre = false, const u16* Xn = nullptr, const u16* Wn = nullptr) {
;     ...
;   do {
;     asm volatile("s_waitcnt vmcnt(0)" ::: "memory");
;     __syncthreads();
;     if (kt + 1 < nk) GT_DMA((unsigned)((kt + 1) & 1) * 32768u)
;     else if (Xn != nullptr) { xe = Xn + oxe; xo = Xn + oxo; we = Wn + owe; wo = Wn + owo; GT_DMA(0u) }
;     const char* cur = smem + (kt & 1) * 32768;
; #pragma unroll
;     for (int ks = 0; ks < 2; ++ks) {
;       bf16x8 xf[MT], wf[4];
;       const int ch = ((ks * 4 + g) ^ rsw) << 4;
; #pragma unroll
;       for (int i = 0; i < MT; ++i) xf[i] = *(const bf16x8*)(cur + (wm * 16 * MT + i * 16 + lr) * 128 + ch);
; #pragma unroll
;       for (int i = 0; i < 4; ++i) wf[i] = *(const bf16x8*)(cur + 16384 + (wn * 64 + i * 16 + lr) * 128 + ch);
; #pragma unroll
;       for (int nt = 0; nt < 4; ++nt)
; #pragma unroll
;         for (int mt = 0; mt < MT; ++mt)
;           acc[nt][mt] = __builtin_amdgcn_mfma_f32_16x16x32_bf16(wf[nt], xf[mt], acc[nt][mt], 0, 0, 0);
	s_mov_b32 m0, s17
	s_nop 0
	global_load_lds_dwordx4 v[52:53], off
	v_mfma_f32_16x16x32_bf16 v[14:17], v[114:117], v[44:47], v[16:19]
	v_mfma_f32_16x16x32_bf16 v[18:21], v[114:117], v[90:93], v[20:23]
	v_mfma_f32_16x16x32_bf16 v[22:25], v[114:117], v[94:97], v[24:27]
	v_mfma_f32_16x16x32_bf16 v[26:29], v[114:117], v[98:101], v[28:31]
	s_nop 2
	v_lshl_add_u64 v[30:31], v[4:5], 0, s[20:21]
	s_mov_b32 m0, s18
	s_nop 0
	global_load_lds_dwordx4 v[30:31], off
	s_mov_b64 s[20:21], 0x8100
	v_lshl_add_u64 v[30:31], v[6:7], 0, s[20:21]
	s_mov_b32 m0, s19
	s_nop 0
	global_load_lds_dwordx4 v[30:31], off
	s_mov_b64 s[18:19], 0xc100
	v_lshl_add_u64 v[30:31], v[4:5], 0, s[18:19]
	s_mov_b32 m0, s34
	s_nop 0
	global_load_lds_dwordx4 v[30:31], off
	s_mov_b64 s[18:19], 0x1100
	s_mov_b32 m0, s39
	s_nop 0
	global_load_lds_dwordx4 v[118:119], off
	v_lshl_add_u64 v[30:31], v[8:9], 0, s[18:19]
	s_mov_b32 m0, s40
	s_nop 0
	global_load_lds_dwordx4 v[30:31], off
	s_mov_b64 s[18:19], 0x2100
	v_lshl_add_u64 v[30:31], v[2:3], 0, s[18:19]
	s_mov_b32 m0, s41
	s_nop 0
	global_load_lds_dwordx4 v[30:31], off
	s_mov_b64 s[18:19], 0x3100
	v_lshl_add_u64 v[30:31], v[8:9], 0, s[18:19]
	s_mov_b32 m0, s42
	s_nop 0
	global_load_lds_dwordx4 v[30:31], off
	v_mfma_f32_16x16x32_bf16 v[48:51], v[102:105], v[44:47], v[48:51]
	s_mov_b64 s[18:19], 0x180
	v_lshl_add_u64 v[118:119], v[6:7], 0, s[18:19]
	v_lshl_add_u64 v[120:121], v[2:3], 0, s[18:19]
	v_mfma_f32_16x16x32_bf16 v[58:61], v[102:105], v[90:93], v[58:61]
	s_mov_b64 s[18:19], 0x4180
	v_mfma_f32_16x16x32_bf16 v[62:65], v[102:105], v[94:97], v[62:65]
	v_mfma_f32_16x16x32_bf16 v[32:35], v[102:105], v[98:101], v[32:35]
	v_mfma_f32_16x16x32_bf16 v[66:69], v[106:109], v[44:47], v[66:69]
	v_mfma_f32_16x16x32_bf16 v[70:73], v[106:109], v[90:93], v[70:73]
	v_mfma_f32_16x16x32_bf16 v[74:77], v[106:109], v[94:97], v[74:77]
	v_mfma_f32_16x16x32_bf16 v[36:39], v[106:109], v[98:101], v[36:39]
	v_mfma_f32_16x16x32_bf16 v[78:81], v[110:113], v[44:47], v[78:81]
	v_mfma_f32_16x16x32_bf16 v[82:85], v[110:113], v[90:93], v[82:85]
	v_mfma_f32_16x16x32_bf16 v[86:89], v[110:113], v[94:97], v[86:89]
	v_mfma_f32_16x16x32_bf16 v[40:43], v[110:113], v[98:101], v[40:43]
	ds_read_b128 v[44:47], v10 offset:32768
	ds_read_b128 v[90:93], v10 offset:34816
	ds_read_b128 v[94:97], v10 offset:36864
	ds_read_b128 v[98:101], v10 offset:38912
	ds_read_b128 v[102:105], v11 offset:49152
	ds_read_b128 v[106:109], v11 offset:51200
	ds_read_b128 v[110:113], v11 offset:53248
	ds_read_b128 v[114:117], v11 offset:55296
	s_waitcnt lgkmcnt(3)
	v_mfma_f32_16x16x32_bf16 v[48:51], v[102:105], v[44:47], v[48:51]
	v_mfma_f32_16x16x32_bf16 v[58:61], v[102:105], v[90:93], v[58:61]
	v_mfma_f32_16x16x32_bf16 v[62:65], v[102:105], v[94:97], v[62:65]
	v_mfma_f32_16x16x32_bf16 v[30:33], v[102:105], v[98:101], v[32:35]
	s_waitcnt lgkmcnt(2)
	v_mfma_f32_16x16x32_bf16 v[66:69], v[106:109], v[44:47], v[66:69]
	v_mfma_f32_16x16x32_bf16 v[70:73], v[106:109], v[90:93], v[70:73]
	v_mfma_f32_16x16x32_bf16 v[74:77], v[106:109], v[94:97], v[74:77]
	v_mfma_f32_16x16x32_bf16 v[34:37], v[106:109], v[98:101], v[36:39]
	s_waitcnt lgkmcnt(1)
	v_mfma_f32_16x16x32_bf16 v[78:81], v[110:113], v[44:47], v[78:81]
	v_mfma_f32_16x16x32_bf16 v[82:85], v[110:113], v[90:93], v[82:85]
	v_mfma_f32_16x16x32_bf16 v[86:89], v[110:113], v[94:97], v[86:89]
	v_mfma_f32_16x16x32_bf16 v[38:41], v[110:113], v[98:101], v[40:43]
	s_waitcnt lgkmcnt(0)
	v_mfma_f32_16x16x32_bf16 v[14:17], v[114:117], v[44:47], v[14:17]
	v_mfma_f32_16x16x32_bf16 v[18:21], v[114:117], v[90:93], v[18:21]
	v_mfma_f32_16x16x32_bf16 v[22:25], v[114:117], v[94:97], v[22:25]
	v_mfma_f32_16x16x32_bf16 v[26:29], v[114:117], v[98:101], v[26:29]
	ds_read_b128 v[42:45], v12 offset:32768
	ds_read_b128 v[90:93], v12 offset:34816
	ds_read_b128 v[94:97], v12 offset:36864
	ds_read_b128 v[98:101], v12 offset:38912
	ds_read_b128 v[102:105], v13 offset:49152
	ds_read_b128 v[106:109], v13 offset:51200
	ds_read_b128 v[110:113], v13 offset:53248
	ds_read_b128 v[114:117], v13 offset:55296
	s_waitcnt vmcnt(0)
	s_waitcnt lgkmcnt(0)
	s_barrier
	s_mov_b32 m0, s12
	s_nop 0
	global_load_lds_dwordx4 v[118:119], off
	v_mfma_f32_16x16x32_bf16 v[46:49], v[102:105], v[42:45], v[48:51]
	v_mfma_f32_16x16x32_bf16 v[50:53], v[102:105], v[90:93], v[58:61]
	v_mfma_f32_16x16x32_bf16 v[58:61], v[102:105], v[94:97], v[62:65]
	v_mfma_f32_16x16x32_bf16 v[62:65], v[106:109], v[42:45], v[66:69]
	v_mfma_f32_16x16x32_bf16 v[66:69], v[106:109], v[90:93], v[70:73]
	v_mfma_f32_16x16x32_bf16 v[70:73], v[106:109], v[94:97], v[74:77]
	v_mfma_f32_16x16x32_bf16 v[74:77], v[110:113], v[42:45], v[78:81]
	v_mfma_f32_16x16x32_bf16 v[14:17], v[114:117], v[42:45], v[14:17]
	v_lshl_add_u64 v[42:43], v[4:5], 0, s[18:19]
	s_mov_b32 m0, s10
	s_nop 0
	global_load_lds_dwordx4 v[42:43], off
	s_mov_b64 s[18:19], 0x8180
	v_lshl_add_u64 v[6:7], v[6:7], 0, s[18:19]
	s_mov_b32 m0, s9
	s_nop 0
	global_load_lds_dwordx4 v[6:7], off
	s_mov_b64 s[18:19], 0xc180
	v_lshl_add_u64 v[4:5], v[4:5], 0, s[18:19]
	s_mov_b32 m0, s13
	s_nop 0
	global_load_lds_dwordx4 v[4:5], off
	v_mfma_f32_16x16x32_bf16 v[30:33], v[102:105], v[98:101], v[30:33]
	s_mov_b32 m0, s11
	s_nop 0
	global_load_lds_dwordx4 v[120:121], off
	s_mov_b64 s[10:11], 0x1180
	v_lshl_add_u64 v[4:5], v[8:9], 0, s[10:11]
	s_mov_b32 m0, s15
	s_nop 0
	global_load_lds_dwordx4 v[4:5], off
	s_mov_b64 s[10:11], 0x2180
	v_lshl_add_u64 v[2:3], v[2:3], 0, s[10:11]
	s_mov_b32 m0, s14
	s_nop 0
	global_load_lds_dwordx4 v[2:3], off
	s_mov_b64 s[10:11], 0x3180
	v_lshl_add_u64 v[2:3], v[8:9], 0, s[10:11]
	s_mov_b32 m0, s16
	s_nop 0
	global_load_lds_dwordx4 v[2:3], off
	v_mfma_f32_16x16x32_bf16 v[34:37], v[106:109], v[98:101], v[34:37]
	v_mfma_f32_16x16x32_bf16 v[78:81], v[110:113], v[90:93], v[82:85]
	v_mfma_f32_16x16x32_bf16 v[82:85], v[110:113], v[94:97], v[86:89]
	v_mfma_f32_16x16x32_bf16 v[38:41], v[110:113], v[98:101], v[38:41]
	v_mfma_f32_16x16x32_bf16 v[18:21], v[114:117], v[90:93], v[18:21]
	v_mfma_f32_16x16x32_bf16 v[22:25], v[114:117], v[94:97], v[22:25]
	v_mfma_f32_16x16x32_bf16 v[26:29], v[114:117], v[98:101], v[26:29]
	ds_read_b128 v[2:5], v10
	ds_read_b128 v[6:9], v10 offset:2048
	ds_read_b128 v[42:45], v10 offset:4096
	ds_read_b128 v[86:89], v10 offset:6144
	ds_read_b128 v[90:93], v11 offset:16384
	ds_read_b128 v[94:97], v11 offset:18432
	ds_read_b128 v[98:101], v11 offset:20480
	ds_read_b128 v[102:105], v11 offset:22528
	s_waitcnt lgkmcnt(3)
; DI float bflo(unsigned u) { return __uint_as_float(u << 16); }
; DI float bfhi(unsigned u) { return __uint_as_float(u & 0xffff0000u); }
; DI void st_bf4(u16* p, float a, float b, float c, float d) { *(uint2*)p = make_uint2(pk2(a, b), pk2(c, d)); }
;   template <int NT, int MT> DI void run(f32x4 (&acc)[NT][MT], int mb, int nb) const {
; #pragma unroll
;     for (int nt = 0; nt < NT; ++nt) {
;       const int ch = g * 256 + nb + nt * 16;
;       const float4 sc = *(const float4*)(scale + ch);
; #pragma unroll
;       for (int mt = 0; mt < MT; ++mt) {
;         const int m = mb + mt * 16;
;         u16* q = mix + (size_t)m * 2048 + ch;
;         const uint2 gt = *(const uint2*)q;
;         f32x4 v = acc[nt][mt];
;         st_bf4(q, v[0] * sc.x * bflo(gt.x), v[1] * sc.y * bfhi(gt.x), v[2] * sc.z * bflo(gt.y), v[3] * sc.w * bfhi(gt.y));
;       }
;     }
	v_mfma_f32_16x16x32_bf16 v[46:49], v[90:93], v[2:5], v[46:49]
	v_mfma_f32_16x16x32_bf16 v[50:53], v[90:93], v[6:9], v[50:53]
	v_mfma_f32_16x16x32_bf16 v[58:61], v[90:93], v[42:45], v[58:61]
	v_mfma_f32_16x16x32_bf16 v[30:33], v[90:93], v[86:89], v[30:33]
	s_waitcnt lgkmcnt(2)
	v_mfma_f32_16x16x32_bf16 v[62:65], v[94:97], v[2:5], v[62:65]
	v_mfma_f32_16x16x32_bf16 v[66:69], v[94:97], v[6:9], v[66:69]
	v_mfma_f32_16x16x32_bf16 v[70:73], v[94:97], v[42:45], v[70:73]
	v_mfma_f32_16x16x32_bf16 v[34:37], v[94:97], v[86:89], v[34:37]
	s_waitcnt lgkmcnt(1)
	v_mfma_f32_16x16x32_bf16 v[74:77], v[98:101], v[2:5], v[74:77]
	v_mfma_f32_16x16x32_bf16 v[78:81], v[98:101], v[6:9], v[78:81]
	v_mfma_f32_16x16x32_bf16 v[82:85], v[98:101], v[42:45], v[82:85]
	v_mfma_f32_16x16x32_bf16 v[38:41], v[98:101], v[86:89], v[38:41]
	s_waitcnt lgkmcnt(0)
	v_mfma_f32_16x16x32_bf16 v[2:5], v[102:105], v[2:5], v[14:17]
	v_mfma_f32_16x16x32_bf16 v[6:9], v[102:105], v[6:9], v[18:21]
	v_mfma_f32_16x16x32_bf16 v[14:17], v[102:105], v[42:45], v[22:25]
	v_mfma_f32_16x16x32_bf16 v[18:21], v[102:105], v[86:89], v[26:29]
	s_nop 1
	ds_read_b128 v[22:25], v12
	ds_read_b128 v[26:29], v12 offset:2048
	ds_read_b128 v[42:45], v12 offset:4096
	ds_read_b128 v[86:89], v12 offset:6144
	ds_read_b128 v[90:93], v13 offset:16384
	ds_read_b128 v[94:97], v13 offset:18432
	ds_read_b128 v[98:101], v13 offset:20480
	ds_read_b128 v[102:105], v13 offset:22528
	s_waitcnt vmcnt(0)
	s_waitcnt lgkmcnt(0)
	v_mfma_f32_16x16x32_bf16 v[70:73], v[94:97], v[42:45], v[70:73]
	s_barrier
	v_or3_b32 v134, v54, s7, v1
	v_lshl_add_u32 v135, v56, 6, s8
	v_lshl_or_b32 v136, v55, 2, v135
	v_ashrrev_i32_e32 v137, 31, v134
	v_readlane_b32 s8, v252, 35
	v_mov_b32_e32 v230, v134
	v_mov_b32_e32 v231, v137
	v_lshlrev_b64 v[138:139], 12, v[230:231]
	v_readlane_b32 s9, v252, 36
	v_add_u32_e32 v140, s38, v136
	v_ashrrev_i32_e32 v141, 31, v140
	v_lshl_add_u64 v[142:143], s[8:9], 0, v[138:139]
	v_lshl_add_u64 v[144:145], v[140:141], 2, s[46:47]
	global_load_dwordx4 v[146:149], v[144:145], off
	v_lshlrev_b64 v[150:151], 1, v[140:141]
	v_lshl_add_u64 v[152:153], v[142:143], 0, v[150:151]
	global_load_dwordx2 v[154:155], v[152:153], off
	v_or_b32_e32 v156, 16, v134
	v_ashrrev_i32_e32 v157, 31, v156
	v_lshlrev_b64 v[158:159], 12, v[156:157]
	v_lshl_add_u64 v[160:161], s[8:9], 0, v[158:159]
	v_lshl_add_u64 v[162:163], v[160:161], 0, v[150:151]
	global_load_dwordx2 v[164:165], v[162:163], off
	v_or_b32_e32 v166, 32, v134
	v_ashrrev_i32_e32 v167, 31, v166
	v_lshlrev_b64 v[168:169], 12, v[166:167]
	v_lshl_add_u64 v[170:171], s[8:9], 0, v[168:169]
	v_lshl_add_u64 v[172:173], v[170:171], 0, v[150:151]
	global_load_dwordx2 v[174:175], v[172:173], off
	v_or_b32_e32 v176, 48, v134
	v_ashrrev_i32_e32 v177, 31, v176
	v_lshlrev_b64 v[178:179], 12, v[176:177]
	v_lshl_add_u64 v[180:181], s[8:9], 0, v[178:179]
	v_lshl_add_u64 v[186:187], v[180:181], 0, v[150:151]
	global_load_dwordx2 v[188:189], v[186:187], off
	v_or_b32_e32 v190, 16, v140
	v_ashrrev_i32_e32 v191, 31, v190
	v_lshlrev_b64 v[192:193], 1, v[190:191]
	v_lshl_add_u64 v[194:195], v[190:191], 2, s[46:47]
	v_lshl_add_u64 v[196:197], v[142:143], 0, v[192:193]
	global_load_dwordx2 v[224:225], v[196:197], off
	global_load_dwordx4 v[226:229], v[194:195], off
	v_mfma_f32_16x16x32_bf16 v[46:49], v[90:93], v[22:25], v[46:49]
	v_mfma_f32_16x16x32_bf16 v[50:53], v[90:93], v[26:29], v[50:53]
	v_mfma_f32_16x16x32_bf16 v[58:61], v[90:93], v[42:45], v[58:61]
	v_mfma_f32_16x16x32_bf16 v[30:33], v[90:93], v[86:89], v[30:33]
	v_mfma_f32_16x16x32_bf16 v[62:65], v[94:97], v[22:25], v[62:65]
	v_mfma_f32_16x16x32_bf16 v[66:69], v[94:97], v[26:29], v[66:69]
	v_mfma_f32_16x16x32_bf16 v[34:37], v[94:97], v[86:89], v[34:37]
	v_mfma_f32_16x16x32_bf16 v[74:77], v[98:101], v[22:25], v[74:77]
	v_mfma_f32_16x16x32_bf16 v[78:81], v[98:101], v[26:29], v[78:81]
	v_mfma_f32_16x16x32_bf16 v[82:85], v[98:101], v[42:45], v[82:85]
	v_mfma_f32_16x16x32_bf16 v[38:41], v[98:101], v[86:89], v[38:41]
	v_mfma_f32_16x16x32_bf16 v[2:5], v[102:105], v[22:25], v[2:5]
	v_mfma_f32_16x16x32_bf16 v[6:9], v[102:105], v[26:29], v[6:9]
	v_mfma_f32_16x16x32_bf16 v[14:17], v[102:105], v[42:45], v[14:17]
	v_mfma_f32_16x16x32_bf16 v[18:21], v[102:105], v[86:89], v[18:21]
	ds_read_b128 v[86:89], v13 offset:55296
	ds_read_b128 v[90:93], v13 offset:53248
	ds_read_b128 v[22:25], v13 offset:51200
	ds_read_b128 v[26:29], v13 offset:49152
	ds_read_b128 v[94:97], v12 offset:38912
	ds_read_b128 v[98:101], v12 offset:36864
	ds_read_b128 v[102:105], v12 offset:34816
	ds_read_b128 v[106:109], v12 offset:32768
	ds_read_b128 v[42:45], v11 offset:55296
	ds_read_b128 v[110:113], v11 offset:53248
	ds_read_b128 v[114:117], v11 offset:51200
	ds_read_b128 v[118:121], v11 offset:49152
	ds_read_b128 v[122:125], v10 offset:38912
	ds_read_b128 v[126:129], v10 offset:36864
	ds_read_b128 v[130:133], v10 offset:34816
	ds_read_b128 v[10:13], v10 offset:32768
	s_waitcnt lgkmcnt(2)
	v_mfma_f32_16x16x32_bf16 v[70:73], v[114:117], v[126:129], v[70:73]
	s_waitcnt lgkmcnt(1)
	v_mfma_f32_16x16x32_bf16 v[66:69], v[114:117], v[130:133], v[66:69]
	v_mfma_f32_16x16x32_bf16 v[50:53], v[118:121], v[130:133], v[50:53]
	v_mfma_f32_16x16x32_bf16 v[30:33], v[118:121], v[122:125], v[30:33]
	s_waitcnt lgkmcnt(0)
; DI float bflo(unsigned u) { return __uint_as_float(u << 16); }
; DI float bfhi(unsigned u) { return __uint_as_float(u & 0xffff0000u); }
; DI void st_bf4(u16* p, float a, float b, float c, float d) { *(uint2*)p = make_uint2(pk2(a, b), pk2(c, d)); }
;   template <int NT, int MT> DI void run(f32x4 (&acc)[NT][MT], int mb, int nb) const {
; #pragma unroll
;     for (int nt = 0; nt < NT; ++nt) {
;       const int ch = g * 256 + nb + nt * 16;
;       const float4 sc = *(const float4*)(scale + ch);
; #pragma unroll
;       for (int mt = 0; mt < MT; ++mt) {
;         const int m = mb + mt * 16;
;         u16* q = mix + (size_t)m * 2048 + ch;
;         const uint2 gt = *(const uint2*)q;
;         f32x4 v = acc[nt][mt];
;         st_bf4(q, v[0] * sc.x * bflo(gt.x), v[1] * sc.y * bfhi(gt.x), v[2] * sc.z * bflo(gt.y), v[3] * sc.w * bfhi(gt.y));
;       }
;     }
	v_mfma_f32_16x16x32_bf16 v[74:77], v[110:113], v[10:13], v[74:77]
	v_mfma_f32_16x16x32_bf16 v[78:81], v[110:113], v[130:133], v[78:81]
	v_mfma_f32_16x16x32_bf16 v[82:85], v[110:113], v[126:129], v[82:85]
	v_mfma_f32_16x16x32_bf16 v[110:113], v[110:113], v[122:125], v[38:41]
	v_mfma_f32_16x16x32_bf16 v[38:41], v[22:25], v[98:101], v[70:73]
	s_nop 2
	s_nop 0
	s_nop 0
	s_nop 0
	v_mfma_f32_16x16x32_bf16 v[46:49], v[118:121], v[10:13], v[46:49]
	s_nop 0
	s_nop 0
	s_nop 0
	v_mfma_f32_16x16x32_bf16 v[58:61], v[118:121], v[126:129], v[58:61]
	s_nop 0
	v_mfma_f32_16x16x32_bf16 v[118:121], v[114:117], v[10:13], v[62:65]
	v_mfma_f32_16x16x32_bf16 v[34:37], v[114:117], v[122:125], v[34:37]
	v_mfma_f32_16x16x32_bf16 v[2:5], v[42:45], v[10:13], v[2:5]
	v_mfma_f32_16x16x32_bf16 v[6:9], v[42:45], v[130:133], v[6:9]
	v_mfma_f32_16x16x32_bf16 v[114:117], v[42:45], v[126:129], v[14:17]
	v_mfma_f32_16x16x32_bf16 v[122:125], v[42:45], v[122:125], v[18:21]
	v_mfma_f32_16x16x32_bf16 v[42:45], v[22:25], v[102:105], v[66:69]
	s_nop 2
	s_nop 0
	s_nop 0
	v_mfma_f32_16x16x32_bf16 v[62:65], v[26:29], v[102:105], v[50:53]
	s_nop 0
	s_nop 0
	s_nop 0
	v_mfma_f32_16x16x32_bf16 v[50:53], v[26:29], v[94:97], v[30:33]
	v_mfma_f32_16x16x32_bf16 v[30:33], v[90:93], v[106:109], v[74:77]
	s_waitcnt vmcnt(6)
	s_nop 1
	v_pk_mul_f32 v[62:63], v[62:63], v[146:147]
	s_nop 0
	s_nop 0
	s_nop 0
	v_mfma_f32_16x16x32_bf16 v[126:129], v[26:29], v[106:109], v[46:49]
	v_mul_f32_e64 v64, v64, v148
	v_mul_f32_e64 v65, v65, v149
	v_pk_mul_f32 v[50:51], v[50:51], v[146:147]
	v_pk_mul_f32 v[52:53], v[52:53], v[148:149]
	v_mfma_f32_16x16x32_bf16 v[58:61], v[26:29], v[98:101], v[58:61]
	v_mfma_f32_16x16x32_bf16 v[26:29], v[90:93], v[102:105], v[78:81]
	s_nop 2
	v_mul_f32_e64 v80, v126, v146
	v_mul_f32_e64 v81, v127, v147
	s_nop 1
	v_pk_mul_f32 v[58:59], v[58:59], v[146:147]
	v_pk_mul_f32 v[60:61], v[60:61], v[148:149]
	v_mfma_f32_16x16x32_bf16 v[46:49], v[22:25], v[106:109], v[118:121]
	s_waitcnt vmcnt(5)
	v_lshlrev_b32_e32 v78, 16, v154
	v_and_b32_e32 v79, 0xffff0000, v154
	v_pk_mul_f32 v[78:79], v[80:81], v[78:79]
	v_lshlrev_b32_e32 v76, 16, v155
	v_and_b32_e32 v77, 0xffff0000, v155
	v_pk_mul_f32 v[80:81], v[128:129], v[148:149]
	v_cvt_pk_bf16_f32 v78, v78, v79
	v_pk_mul_f32 v[76:77], v[80:81], v[76:77]
	v_mfma_f32_16x16x32_bf16 v[34:37], v[22:25], v[94:97], v[34:37]
	v_cvt_pk_bf16_f32 v79, v76, v77
	global_store_dwordx2 v[152:153], v[78:79], off
	s_nop 0
	s_nop 0
	s_nop 0
	s_nop 0
	s_nop 0
	s_nop 0
	v_mfma_f32_16x16x32_bf16 v[22:25], v[90:93], v[98:101], v[82:85]
	s_waitcnt vmcnt(4)
	v_lshlrev_b32_e32 v80, 16, v164
	v_and_b32_e32 v81, 0xffff0000, v164
	v_lshlrev_b32_e32 v78, 16, v165
	v_and_b32_e32 v79, 0xffff0000, v165
	v_pk_mul_f32 v[62:63], v[62:63], v[80:81]
	v_pk_mul_f32 v[64:65], v[64:65], v[78:79]
	v_cvt_pk_bf16_f32 v62, v62, v63
	v_cvt_pk_bf16_f32 v63, v64, v65
	global_store_dwordx2 v[162:163], v[62:63], off
	s_nop 0
	s_nop 0
	s_nop 0
	s_nop 0
	s_nop 0
	s_nop 0
	v_mfma_f32_16x16x32_bf16 v[18:21], v[90:93], v[94:97], v[110:113]
	s_waitcnt vmcnt(3)
	v_lshlrev_b32_e32 v78, 16, v174
	v_and_b32_e32 v79, 0xffff0000, v174
	v_lshlrev_b32_e32 v76, 16, v175
	v_and_b32_e32 v77, 0xffff0000, v175
	v_pk_mul_f32 v[58:59], v[58:59], v[78:79]
	v_pk_mul_f32 v[60:61], v[60:61], v[76:77]
	v_cvt_pk_bf16_f32 v58, v58, v59
	v_cvt_pk_bf16_f32 v59, v60, v61
	global_store_dwordx2 v[172:173], v[58:59], off
	s_nop 0
	s_nop 0
	s_nop 0
	s_nop 0
	s_nop 0
	s_nop 0
	v_mfma_f32_16x16x32_bf16 v[14:17], v[86:89], v[106:109], v[2:5]
	s_waitcnt vmcnt(2)
	v_lshlrev_b32_e32 v72, 16, v188
	v_and_b32_e32 v73, 0xffff0000, v188
	v_lshlrev_b32_e32 v54, 16, v189
	v_and_b32_e32 v55, 0xffff0000, v189
	v_pk_mul_f32 v[50:51], v[50:51], v[72:73]
	v_pk_mul_f32 v[52:53], v[52:53], v[54:55]
	v_cvt_pk_bf16_f32 v50, v50, v51
	v_cvt_pk_bf16_f32 v51, v52, v53
	global_store_dwordx2 v[186:187], v[50:51], off
	s_nop 0
	s_nop 0
	s_nop 0
	s_nop 0
	s_nop 0
	s_nop 0
	v_mfma_f32_16x16x32_bf16 v[10:13], v[86:89], v[102:105], v[6:9]
	s_nop 0
	s_waitcnt vmcnt(1)
	v_lshlrev_b32_e32 v64, 16, v224
	v_and_b32_e32 v65, 0xffff0000, v224
	s_waitcnt vmcnt(0)
	v_pk_mul_f32 v[46:47], v[46:47], v[226:227]
	v_lshlrev_b32_e32 v60, 16, v225
	v_and_b32_e32 v61, 0xffff0000, v225
	v_pk_mul_f32 v[48:49], v[48:49], v[228:229]
	v_pk_mul_f32 v[46:47], v[46:47], v[64:65]
	v_pk_mul_f32 v[48:49], v[48:49], v[60:61]
	v_cvt_pk_bf16_f32 v46, v46, v47
	v_cvt_pk_bf16_f32 v47, v48, v49
	global_store_dwordx2 v[196:197], v[46:47], off
	v_mov_b32_e32 v1, v136
	v_mov_b32_e32 v50, v226
	v_mov_b32_e32 v51, v227
	v_mov_b32_e32 v52, v228
	v_mov_b32_e32 v53, v229
	v_mov_b32_e32 v54, v192
	v_mov_b32_e32 v55, v193
	v_mov_b32_e32 v56, v196
	v_mov_b32_e32 v57, v197
	v_mov_b32_e32 v58, v180
	v_mov_b32_e32 v59, v181
	v_mov_b32_e32 v62, v170
	v_mov_b32_e32 v63, v171
	v_mov_b32_e32 v66, v140
	v_mov_b32_e32 v67, v141
	v_mov_b32_e32 v68, v142
	v_mov_b32_e32 v69, v143
	v_mov_b32_e32 v70, v160
	v_mov_b32_e32 v71, v161
	v_mov_b32_e32 v74, v150
	v_mov_b32_e32 v75, v151
	v_lshl_add_u64 v[134:135], v[70:71], 0, v[54:55]
	global_load_dwordx2 v[136:137], v[134:135], off
	v_lshl_add_u64 v[138:139], v[62:63], 0, v[54:55]
	global_load_dwordx2 v[140:141], v[138:139], off
	v_lshl_add_u64 v[142:143], v[58:59], 0, v[54:55]
	global_load_dwordx2 v[144:145], v[142:143], off
	v_or_b32_e32 v146, 32, v66
	v_ashrrev_i32_e32 v147, 31, v146
	v_lshl_add_u64 v[148:149], v[146:147], 2, s[46:47]
	v_lshlrev_b64 v[150:151], 1, v[146:147]
	v_lshl_add_u64 v[152:153], v[68:69], 0, v[150:151]
	global_load_dwordx4 v[154:157], v[148:149], off
	global_load_dwordx2 v[158:159], v[152:153], off
	v_lshl_add_u64 v[160:161], v[70:71], 0, v[150:151]
	global_load_dwordx2 v[162:163], v[160:161], off
	v_lshl_add_u64 v[164:165], v[62:63], 0, v[150:151]
	global_load_dwordx2 v[166:167], v[164:165], off
	v_lshl_add_u64 v[168:169], v[58:59], 0, v[150:151]
	global_load_dwordx2 v[170:171], v[168:169], off
	v_or_b32_e32 v172, 48, v66
	v_ashrrev_i32_e32 v173, 31, v172
	v_lshl_add_u64 v[174:175], v[172:173], 2, s[46:47]
	v_lshlrev_b64 v[176:177], 1, v[172:173]
	v_lshl_add_u64 v[178:179], v[68:69], 0, v[176:177]
	global_load_dwordx4 v[186:189], v[174:175], off
	global_load_dwordx2 v[180:181], v[178:179], off
	v_lshl_add_u64 v[190:191], v[70:71], 0, v[176:177]
	global_load_dwordx2 v[192:193], v[190:191], off
	v_lshl_add_u64 v[194:195], v[62:63], 0, v[176:177]
	global_load_dwordx2 v[196:197], v[194:195], off
	v_lshl_add_u64 v[224:225], v[58:59], 0, v[176:177]
	global_load_dwordx2 v[226:227], v[224:225], off
	s_nop 0
	s_nop 0
	v_pk_mul_f32 v[42:43], v[42:43], v[50:51]
	v_pk_mul_f32 v[44:45], v[44:45], v[52:53]
	v_pk_mul_f32 v[38:39], v[38:39], v[50:51]
	v_pk_mul_f32 v[40:41], v[40:41], v[52:53]
	v_pk_mul_f32 v[34:35], v[34:35], v[50:51]
	v_pk_mul_f32 v[36:37], v[36:37], v[52:53]
	v_mfma_f32_16x16x32_bf16 v[6:9], v[86:89], v[98:101], v[114:117]
	s_waitcnt vmcnt(12)
; DI float bflo(unsigned u) { return __uint_as_float(u << 16); }
; DI float bfhi(unsigned u) { return __uint_as_float(u & 0xffff0000u); }
; DI void st_bf4(u16* p, float a, float b, float c, float d) { *(uint2*)p = make_uint2(pk2(a, b), pk2(c, d)); }
;   template <int NT, int MT> DI void run(f32x4 (&acc)[NT][MT], int mb, int nb) const {
; #pragma unroll
;     for (int nt = 0; nt < NT; ++nt) {
;       const int ch = g * 256 + nb + nt * 16;
;       const float4 sc = *(const float4*)(scale + ch);
; #pragma unroll
;       for (int mt = 0; mt < MT; ++mt) {
;         const int m = mb + mt * 16;
;         u16* q = mix + (size_t)m * 2048 + ch;
;         const uint2 gt = *(const uint2*)q;
;         f32x4 v = acc[nt][mt];
;         st_bf4(q, v[0] * sc.x * bflo(gt.x), v[1] * sc.y * bfhi(gt.x), v[2] * sc.z * bflo(gt.y), v[3] * sc.w * bfhi(gt.y));
;       }
;     }
	v_lshlrev_b32_e32 v56, 16, v136
	v_and_b32_e32 v57, 0xffff0000, v136
	v_lshlrev_b32_e32 v48, 16, v137
	v_and_b32_e32 v49, 0xffff0000, v137
	v_pk_mul_f32 v[42:43], v[42:43], v[56:57]
	v_pk_mul_f32 v[44:45], v[44:45], v[48:49]
	v_cvt_pk_bf16_f32 v42, v42, v43
	v_cvt_pk_bf16_f32 v43, v44, v45
	global_store_dwordx2 v[134:135], v[42:43], off
	s_nop 0
	s_nop 0
	v_mfma_f32_16x16x32_bf16 v[2:5], v[86:89], v[94:97], v[122:125]
	s_waitcnt vmcnt(11)
	v_lshlrev_b32_e32 v46, 16, v140
	v_and_b32_e32 v47, 0xffff0000, v140
	v_lshlrev_b32_e32 v44, 16, v141
	v_and_b32_e32 v45, 0xffff0000, v141
	v_pk_mul_f32 v[38:39], v[38:39], v[46:47]
	v_pk_mul_f32 v[40:41], v[40:41], v[44:45]
	v_cvt_pk_bf16_f32 v38, v38, v39
	v_cvt_pk_bf16_f32 v39, v40, v41
	global_store_dwordx2 v[138:139], v[38:39], off
	s_nop 0
	s_nop 0
	s_waitcnt vmcnt(10)
	v_lshlrev_b32_e32 v42, 16, v144
	v_and_b32_e32 v43, 0xffff0000, v144
	v_lshlrev_b32_e32 v40, 16, v145
	v_and_b32_e32 v41, 0xffff0000, v145
	v_pk_mul_f32 v[34:35], v[34:35], v[42:43]
	v_pk_mul_f32 v[36:37], v[36:37], v[40:41]
	v_cvt_pk_bf16_f32 v34, v34, v35
	v_cvt_pk_bf16_f32 v35, v36, v37
	global_store_dwordx2 v[142:143], v[34:35], off
	s_nop 0
	s_nop 0
	s_nop 0
	s_nop 0
	s_nop 0
	s_nop 0
	s_waitcnt vmcnt(9)
	v_pk_mul_f32 v[30:31], v[30:31], v[154:155]
	s_nop 0
	v_pk_mul_f32 v[32:33], v[32:33], v[156:157]
	v_pk_mul_f32 v[26:27], v[26:27], v[154:155]
	v_pk_mul_f32 v[28:29], v[28:29], v[156:157]
	v_pk_mul_f32 v[22:23], v[22:23], v[154:155]
	v_pk_mul_f32 v[24:25], v[24:25], v[156:157]
	v_pk_mul_f32 v[18:19], v[18:19], v[154:155]
	v_pk_mul_f32 v[20:21], v[20:21], v[156:157]
	s_waitcnt vmcnt(8)
	v_lshlrev_b32_e32 v44, 16, v158
	v_and_b32_e32 v45, 0xffff0000, v158
	v_lshlrev_b32_e32 v42, 16, v159
	v_and_b32_e32 v43, 0xffff0000, v159
	v_pk_mul_f32 v[30:31], v[30:31], v[44:45]
	v_pk_mul_f32 v[32:33], v[32:33], v[42:43]
	v_cvt_pk_bf16_f32 v30, v30, v31
	v_cvt_pk_bf16_f32 v31, v32, v33
	global_store_dwordx2 v[152:153], v[30:31], off
	s_nop 0
	s_nop 0
	s_waitcnt vmcnt(7)
	v_lshlrev_b32_e32 v40, 16, v162
	v_and_b32_e32 v41, 0xffff0000, v162
	v_lshlrev_b32_e32 v32, 16, v163
	v_and_b32_e32 v33, 0xffff0000, v163
	v_pk_mul_f32 v[26:27], v[26:27], v[40:41]
	v_pk_mul_f32 v[28:29], v[28:29], v[32:33]
	v_cvt_pk_bf16_f32 v26, v26, v27
	v_cvt_pk_bf16_f32 v27, v28, v29
	global_store_dwordx2 v[160:161], v[26:27], off
	s_nop 0
	s_nop 0
	s_waitcnt vmcnt(6)
	v_lshlrev_b32_e32 v30, 16, v166
	v_and_b32_e32 v31, 0xffff0000, v166
	v_lshlrev_b32_e32 v28, 16, v167
	v_and_b32_e32 v29, 0xffff0000, v167
	v_pk_mul_f32 v[22:23], v[22:23], v[30:31]
	v_pk_mul_f32 v[24:25], v[24:25], v[28:29]
	v_cvt_pk_bf16_f32 v22, v22, v23
	v_cvt_pk_bf16_f32 v23, v24, v25
	global_store_dwordx2 v[164:165], v[22:23], off
	s_nop 0
	s_nop 0
	s_waitcnt vmcnt(5)
	v_lshlrev_b32_e32 v26, 16, v170
	v_and_b32_e32 v27, 0xffff0000, v170
	v_lshlrev_b32_e32 v24, 16, v171
	v_and_b32_e32 v25, 0xffff0000, v171
	v_pk_mul_f32 v[18:19], v[18:19], v[26:27]
	v_pk_mul_f32 v[20:21], v[20:21], v[24:25]
	v_cvt_pk_bf16_f32 v18, v18, v19
	v_cvt_pk_bf16_f32 v19, v20, v21
	global_store_dwordx2 v[168:169], v[18:19], off
	s_nop 0
	s_nop 0
	s_nop 0
	s_nop 0
	s_nop 0
	s_nop 0
	s_waitcnt vmcnt(4)
	v_pk_mul_f32 v[14:15], v[14:15], v[186:187]
	s_nop 0
	v_pk_mul_f32 v[16:17], v[16:17], v[188:189]
	v_pk_mul_f32 v[10:11], v[10:11], v[186:187]
	v_pk_mul_f32 v[12:13], v[12:13], v[188:189]
	v_pk_mul_f32 v[6:7], v[6:7], v[186:187]
	v_pk_mul_f32 v[8:9], v[8:9], v[188:189]
	v_pk_mul_f32 v[2:3], v[2:3], v[186:187]
	v_pk_mul_f32 v[4:5], v[4:5], v[188:189]
	s_waitcnt vmcnt(3)
	v_lshlrev_b32_e32 v28, 16, v180
	v_and_b32_e32 v29, 0xffff0000, v180
	v_lshlrev_b32_e32 v26, 16, v181
	v_and_b32_e32 v27, 0xffff0000, v181
	v_pk_mul_f32 v[14:15], v[14:15], v[28:29]
	v_pk_mul_f32 v[16:17], v[16:17], v[26:27]
	v_cvt_pk_bf16_f32 v14, v14, v15
	v_cvt_pk_bf16_f32 v15, v16, v17
	global_store_dwordx2 v[178:179], v[14:15], off
	s_nop 0
	s_nop 0
	s_waitcnt vmcnt(2)
	v_lshlrev_b32_e32 v24, 16, v192
	v_and_b32_e32 v25, 0xffff0000, v192
	v_lshlrev_b32_e32 v16, 16, v193
	v_and_b32_e32 v17, 0xffff0000, v193
	v_pk_mul_f32 v[10:11], v[10:11], v[24:25]
	v_pk_mul_f32 v[12:13], v[12:13], v[16:17]
	v_cvt_pk_bf16_f32 v10, v10, v11
	v_cvt_pk_bf16_f32 v11, v12, v13
	global_store_dwordx2 v[190:191], v[10:11], off
	s_nop 0
	s_nop 0
	s_waitcnt vmcnt(1)
	v_lshlrev_b32_e32 v14, 16, v196
	v_and_b32_e32 v15, 0xffff0000, v196
	v_lshlrev_b32_e32 v12, 16, v197
	v_and_b32_e32 v13, 0xffff0000, v197
	v_pk_mul_f32 v[6:7], v[6:7], v[14:15]
	v_pk_mul_f32 v[8:9], v[8:9], v[12:13]
	v_cvt_pk_bf16_f32 v6, v6, v7
	v_cvt_pk_bf16_f32 v7, v8, v9
	global_store_dwordx2 v[194:195], v[6:7], off
	s_nop 0
	s_nop 0
	s_waitcnt vmcnt(0)
	v_lshlrev_b32_e32 v10, 16, v226
	v_and_b32_e32 v11, 0xffff0000, v226
	v_lshlrev_b32_e32 v8, 16, v227
	v_and_b32_e32 v9, 0xffff0000, v227
	v_pk_mul_f32 v[2:3], v[2:3], v[10:11]
	v_pk_mul_f32 v[4:5], v[4:5], v[8:9]
	v_cvt_pk_bf16_f32 v2, v2, v3
	v_cvt_pk_bf16_f32 v3, v4, v5
	global_store_dwordx2 v[224:225], v[2:3], off
	v_mov_b32_e32 v6, v224
	v_mov_b32_e32 v7, v225
	v_mov_b32_e32 v18, v186
	v_mov_b32_e32 v19, v187
	v_mov_b32_e32 v20, v188
	v_mov_b32_e32 v21, v189
	v_mov_b32_e32 v22, v176
	v_mov_b32_e32 v23, v177
	v_mov_b32_e32 v34, v154
	v_mov_b32_e32 v35, v155
	v_mov_b32_e32 v36, v156
	v_mov_b32_e32 v37, v157
	v_mov_b32_e32 v38, v150
	v_mov_b32_e32 v39, v151
	s_branch .LBB0_298

; DI int get_bid() { int b = blockIdx.x; asm volatile("" : "+s"(b)); return b; }
; template <int MT, class Epi>
; DI void gemm_tile(const u16* __restrict__ X, long ldx, const u16* __restrict__ W, long ldw, int K, char* smem,
;                   int m0, int n0, const Epi& epi, bool pre = false, const u16* Xn = nullptr, const u16* Wn = nullptr) {
;     ...
;   const int wu = __builtin_amdgcn_readfirstlane(wave);
;   const unsigned sbase = (unsigned)__builtin_amdgcn_readfirstlane((int)(unsigned)(size_t)smem);
;   const int r8 = lane >> 3, c0 = (lane & 7) ^ (r8 >> 1);
;   const long oxe = (long)(wu * MT * 8 + r8) * ldx + (c0 << 3), oxo = (long)(wu * MT * 8 + r8) * ldx + ((c0 ^ 4) << 3);
;   const long owe = (long)(wu * 32 + r8) * ldw + (c0 << 3), owo = (long)(wu * 32 + r8) * ldw + ((c0 ^ 4) << 3);
;   const u16 *xe = X + oxe, *xo = X + oxo, *we = W + owe, *wo = W + owo;
;   const long ldx8 = 8 * ldx, ldw8 = 8 * ldw;
;   const unsigned xdst = sbase + wu * MT * 1024, wdst = sbase + 16384 + wu * 4096;
;     ...
;   if (!pre) {
;     __syncthreads();
;     GT_DMA(0u)
; DI void phase_even(const Params& p, int e, int sub, char* smem) {
;     ...
;     for (int t = get_bid(); t < 132 * 40; t += gridDim.x) {
;       const int tm = t / 40, tn = t % 40;
;       const int t2 = t + gridDim.x, tm2 = t2 / 40, tn2 = t2 % 40;
;       const bool nx = t2 < 132 * 40;
;       gemm_tile<4>(hbuf + (size_t)tm * 128 * 1024, 1024, W + WE_IN + (size_t)tn * 128 * 1024, 1024, 1024, smem, tm * 128, tn * 128, epi, pre,
;                    nx ? hbuf + (size_t)tm2 * 128 * 1024 : nullptr, W + WE_IN + (size_t)tn2 * 128 * 1024);
.LBB0_419:
	s_mul_hi_i32 s5, s4, 0x66666667
	s_lshr_b32 s6, s5, 31
	s_ashr_i32 s5, s5, 4
	s_add_i32 s42, s5, s6
	v_mov_b32_e32 v5, v185
	s_mul_i32 s5, s42, 40
	s_sub_i32 s38, s4, s5
	v_ashrrev_i32_e32 v1, 6, v5
	v_bfe_u32 v4, v5, 3, 3
	v_readfirstlane_b32 s5, v1
	s_lshl_b32 s7, s5, 5
	v_bfe_u32 v78, v5, 4, 2
	v_or_b32_e32 v6, s7, v4
	v_bitop3_b32 v3, v78, v5, 7 bitop3:0x78
	v_ashrrev_i32_e32 v7, 31, v6
	v_lshlrev_b64 v[8:9], 10, v[6:7]
	v_lshlrev_b32_e32 v6, 3, v3
	s_ashr_i32 s43, s42, 31
	s_ashr_i32 s39, s38, 31
	v_or_b32_e32 v10, v8, v6
	v_mov_b32_e32 v11, v9
	v_bitop3_b32 v8, v8, v6, 32 bitop3:0xf6
	s_lshl_b32 s5, s5, 12
	s_lshl_b64 s[40:41], s[42:43], 18
	s_lshl_b64 s[44:45], s[38:39], 18
	v_mov_b32_e32 v2, v183
	s_add_i32 s6, s5, 0x4000
	s_and_b64 vcc, exec, s[46:47]
	v_lshlrev_b64 v[68:69], 1, v[10:11]
	v_lshlrev_b64 v[66:67], 1, v[8:9]
	s_cbranch_vccnz .LBB0_421
	s_add_u32 s8, s0, s40
	v_readlane_b32 s12, v255, 5
	s_addc_u32 s9, s1, s41
	v_readlane_b32 s16, v255, 9
	v_readlane_b32 s17, v255, 10
	s_add_u32 s10, s16, s44
	s_addc_u32 s11, s17, s45
	v_readlane_b32 s13, v255, 6
	v_lshl_add_u64 v[8:9], s[8:9], 0, v[68:69]
	v_lshl_add_u64 v[10:11], s[8:9], 0, v[66:67]
	v_lshl_add_u64 v[12:13], s[10:11], 0, v[68:69]
	v_lshl_add_u64 v[14:15], s[10:11], 0, v[66:67]
	s_barrier
	s_mov_b32 m0, s5
	s_nop 0
	global_load_lds_dwordx4 v[8:9], off
	s_mov_b64 s[10:11], 0x4000
	v_readlane_b32 s14, v255, 7
	v_readlane_b32 s15, v255, 8
	v_lshl_add_u64 v[16:17], v[10:11], 0, s[10:11]
	s_add_i32 s8, s5, 0x400
	s_mov_b32 m0, s8
	s_nop 0
	global_load_lds_dwordx4 v[16:17], off
	s_mov_b64 s[12:13], 0x8000
	v_lshl_add_u64 v[8:9], v[8:9], 0, s[12:13]
	s_add_i32 s8, s5, 0x800
	s_mov_b32 m0, s8
	s_nop 0
	global_load_lds_dwordx4 v[8:9], off
	s_mov_b64 s[14:15], 0xc000
	v_lshl_add_u64 v[8:9], v[10:11], 0, s[14:15]
	s_add_i32 s8, s5, 0xc00
	s_mov_b32 m0, s8
	s_nop 0
	global_load_lds_dwordx4 v[8:9], off
	s_mov_b32 m0, s6
	s_nop 0
	global_load_lds_dwordx4 v[12:13], off
	v_lshl_add_u64 v[8:9], v[14:15], 0, s[10:11]
	s_add_i32 s8, s5, 0x4400
	s_mov_b32 m0, s8
	s_nop 0
	global_load_lds_dwordx4 v[8:9], off
	v_lshl_add_u64 v[8:9], v[12:13], 0, s[12:13]
	s_add_i32 s8, s5, 0x4800
	s_mov_b32 m0, s8
	s_nop 0
	global_load_lds_dwordx4 v[8:9], off
	v_lshl_add_u64 v[8:9], v[14:15], 0, s[14:15]
	s_add_i32 s8, s5, 0x4c00
	s_mov_b32 m0, s8
	s_nop 0
	global_load_lds_dwordx4 v[8:9], off
	v_readlane_b32 s18, v255, 11
	v_readlane_b32 s19, v255, 12

; DI int get_bid() { int b = blockIdx.x; asm volatile("" : "+s"(b)); return b; }
; template <int MT, class Epi>
; DI void gemm_tile(const u16* __restrict__ X, long ldx, const u16* __restrict__ W, long ldw, int K, char* smem,
;                   int m0, int n0, const Epi& epi, bool pre = false, const u16* Xn = nullptr, const u16* Wn = nullptr) {
;     ...
;   do {
;     asm volatile("s_waitcnt vmcnt(0)" ::: "memory");
;     __syncthreads();
;     if (kt + 1 < nk) GT_DMA((unsigned)((kt + 1) & 1) * 32768u)
;     else if (Xn != nullptr) { xe = Xn + oxe; xo = Xn + oxo; we = Wn + owe; wo = Wn + owo; GT_DMA(0u) }
;     const char* cur = smem + (kt & 1) * 32768;
; #pragma unroll
;     for (int ks = 0; ks < 2; ++ks) {
;       bf16x8 xf[MT], wf[4];
;       const int ch = ((ks * 4 + g) ^ rsw) << 4;
; #pragma unroll
;       for (int i = 0; i < MT; ++i) xf[i] = *(const bf16x8*)(cur + (wm * 16 * MT + i * 16 + lr) * 128 + ch);
; #pragma unroll
;       for (int i = 0; i < 4; ++i) wf[i] = *(const bf16x8*)(cur + 16384 + (wn * 64 + i * 16 + lr) * 128 + ch);
; #pragma unroll
;       for (int nt = 0; nt < 4; ++nt)
; #pragma unroll
;         for (int mt = 0; mt < MT; ++mt)
;           acc[nt][mt] = __builtin_amdgcn_mfma_f32_16x16x32_bf16(wf[nt], xf[mt], acc[nt][mt], 0, 0, 0);
;     }
;   } while (++kt < nk);
; DI void phase_even(const Params& p, int e, int sub, char* smem) {
;     ...
;     for (int t = get_bid(); t < 132 * 40; t += gridDim.x) {
;       const int tm = t / 40, tn = t % 40;
;       const int t2 = t + gridDim.x, tm2 = t2 / 40, tn2 = t2 % 40;
;       const bool nx = t2 < 132 * 40;
;       gemm_tile<4>(hbuf + (size_t)tm * 128 * 1024, 1024, W + WE_IN + (size_t)tn * 128 * 1024, 1024, 1024, smem, tm * 128, tn * 128, epi, pre,
;                    nx ? hbuf + (size_t)tm2 * 128 * 1024 : nullptr, W + WE_IN + (size_t)tn2 * 128 * 1024);
;       pre = nx;
.LBB0_422:
	s_add_i32 s7, s8, 0x8000
	v_lshl_add_u64 v[124:125], v[76:77], 0, s[40:41]
	s_and_b32 s9, s7, 0x8000
	v_lshl_add_u64 v[122:123], v[74:75], 0, s[40:41]
	v_lshl_add_u64 v[126:127], v[124:125], 0, s[74:75]
	s_waitcnt vmcnt(0)
	s_barrier
	s_and_b32 s8, s8, 0x8000
	v_or_b32_e32 v162, s8, v85
	v_add3_u32 v163, v162, v81, v82
	v_add3_u32 v164, v162, v84, v82
	v_or_b32_e32 v165, s8, v83
	v_add3_u32 v166, v165, v81, v82
	v_add3_u32 v167, v165, v84, v82
	ds_read_b128 v[86:89], v163
	ds_read_b128 v[90:93], v163 offset:2048
	ds_read_b128 v[94:97], v163 offset:4096
	ds_read_b128 v[98:101], v163 offset:6144
	ds_read_b128 v[102:105], v164 offset:16384
	ds_read_b128 v[106:109], v164 offset:18432
	ds_read_b128 v[110:113], v164 offset:20480
	ds_read_b128 v[114:117], v164 offset:22528
	ds_read_b128 v[130:133], v166
	ds_read_b128 v[134:137], v166 offset:2048
	ds_read_b128 v[138:141], v166 offset:4096
	ds_read_b128 v[142:145], v166 offset:6144
	ds_read_b128 v[146:149], v167 offset:16384
	ds_read_b128 v[150:153], v167 offset:18432
	ds_read_b128 v[154:157], v167 offset:20480
	ds_read_b128 v[158:161], v167 offset:22528
	s_add_i32 s10, s9, s5
	s_mov_b32 m0, s10
	s_nop 0
	global_load_lds_dwordx4 v[126:127], off
	v_lshl_add_u64 v[126:127], v[122:123], 0, s[94:95]
	s_add_i32 s11, s10, 0x400
	s_mov_b32 m0, s11
	s_nop 0
	global_load_lds_dwordx4 v[126:127], off
	v_lshl_add_u64 v[124:125], v[124:125], 0, s[76:77]
	s_add_i32 s11, s10, 0x800
	s_mov_b32 m0, s11
	s_nop 0
	global_load_lds_dwordx4 v[124:125], off
	v_lshl_add_u64 v[120:121], v[72:73], 0, s[40:41]
	v_lshl_add_u64 v[122:123], v[122:123], 0, s[54:55]
	s_addk_i32 s10, 0xc00
	s_mov_b32 m0, s10
	s_nop 0
	global_load_lds_dwordx4 v[122:123], off
	v_lshl_add_u64 v[118:119], v[70:71], 0, s[40:41]
	v_lshl_add_u64 v[128:129], v[120:121], 0, s[28:29]
	s_add_i32 s9, s9, s6
	s_mov_b32 m0, s9
	s_nop 0
	global_load_lds_dwordx4 v[128:129], off
	v_lshl_add_u64 v[122:123], v[118:119], 0, s[94:95]
	s_add_i32 s10, s9, 0x400
	s_mov_b32 m0, s10
	s_nop 0
	global_load_lds_dwordx4 v[122:123], off
	v_lshl_add_u64 v[120:121], v[120:121], 0, s[78:79]
	s_add_i32 s10, s9, 0x800
	s_mov_b32 m0, s10
	s_nop 0
	global_load_lds_dwordx4 v[120:121], off
	v_lshl_add_u64 v[118:119], v[118:119], 0, s[54:55]
	s_addk_i32 s9, 0xc00
	s_mov_b32 m0, s9
	s_nop 0
	global_load_lds_dwordx4 v[118:119], off
	s_mov_b32 s8, s7
	s_add_u32 s40, s40, 0x80
	s_addc_u32 s41, s41, 0
	s_cmpk_lg_i32 s40, 0x780
	s_waitcnt lgkmcnt(11)
	v_mfma_f32_16x16x32_bf16 v[62:65], v[102:105], v[86:89], v[62:65]
	v_mfma_f32_16x16x32_bf16 v[58:61], v[102:105], v[90:93], v[58:61]
	v_mfma_f32_16x16x32_bf16 v[54:57], v[102:105], v[94:97], v[54:57]
	v_mfma_f32_16x16x32_bf16 v[50:53], v[102:105], v[98:101], v[50:53]
	s_waitcnt lgkmcnt(10)
	v_mfma_f32_16x16x32_bf16 v[34:37], v[106:109], v[98:101], v[34:37]
	s_waitcnt lgkmcnt(9)
	v_mfma_f32_16x16x32_bf16 v[18:21], v[110:113], v[98:101], v[18:21]
	s_waitcnt lgkmcnt(8)
	v_mfma_f32_16x16x32_bf16 v[14:17], v[114:117], v[86:89], v[14:17]
	v_mfma_f32_16x16x32_bf16 v[10:13], v[114:117], v[90:93], v[10:13]
	v_mfma_f32_16x16x32_bf16 v[6:9], v[114:117], v[94:97], v[6:9]
	v_mfma_f32_16x16x32_bf16 v[2:5], v[114:117], v[98:101], v[2:5]
	v_mfma_f32_16x16x32_bf16 v[46:49], v[106:109], v[86:89], v[46:49]
	v_mfma_f32_16x16x32_bf16 v[42:45], v[106:109], v[90:93], v[42:45]
	v_mfma_f32_16x16x32_bf16 v[38:41], v[106:109], v[94:97], v[38:41]
	v_mfma_f32_16x16x32_bf16 v[30:33], v[110:113], v[86:89], v[30:33]
	v_mfma_f32_16x16x32_bf16 v[26:29], v[110:113], v[90:93], v[26:29]
	v_mfma_f32_16x16x32_bf16 v[22:25], v[110:113], v[94:97], v[22:25]
	s_waitcnt lgkmcnt(3)
	v_mfma_f32_16x16x32_bf16 v[62:65], v[146:149], v[130:133], v[62:65]
	v_mfma_f32_16x16x32_bf16 v[58:61], v[146:149], v[134:137], v[58:61]
	v_mfma_f32_16x16x32_bf16 v[54:57], v[146:149], v[138:141], v[54:57]
	v_mfma_f32_16x16x32_bf16 v[50:53], v[146:149], v[142:145], v[50:53]
	s_waitcnt lgkmcnt(2)
	v_mfma_f32_16x16x32_bf16 v[46:49], v[150:153], v[130:133], v[46:49]
	v_mfma_f32_16x16x32_bf16 v[42:45], v[150:153], v[134:137], v[42:45]
	v_mfma_f32_16x16x32_bf16 v[38:41], v[150:153], v[138:141], v[38:41]
	v_mfma_f32_16x16x32_bf16 v[34:37], v[150:153], v[142:145], v[34:37]
	s_waitcnt lgkmcnt(1)
	v_mfma_f32_16x16x32_bf16 v[30:33], v[154:157], v[130:133], v[30:33]
	v_mfma_f32_16x16x32_bf16 v[26:29], v[154:157], v[134:137], v[26:29]
	v_mfma_f32_16x16x32_bf16 v[22:25], v[154:157], v[138:141], v[22:25]
	v_mfma_f32_16x16x32_bf16 v[18:21], v[154:157], v[142:145], v[18:21]
	s_waitcnt lgkmcnt(0)
	v_mfma_f32_16x16x32_bf16 v[14:17], v[158:161], v[130:133], v[14:17]
	v_mfma_f32_16x16x32_bf16 v[10:13], v[158:161], v[134:137], v[10:13]
	v_mfma_f32_16x16x32_bf16 v[6:9], v[158:161], v[138:141], v[6:9]
	v_mfma_f32_16x16x32_bf16 v[2:5], v[158:161], v[142:145], v[2:5]
	s_cbranch_scc1 .LBB0_422
	v_readlane_b32 s8, v255, 5
	v_readlane_b32 s14, v255, 11
	s_add_i32 s4, s4, s14
	s_mul_hi_i32 s7, s4, 0x66666667
	s_lshr_b32 s8, s7, 31
	s_ashr_i32 s7, s7, 4
	s_add_i32 s46, s7, s8
	s_cmpk_gt_i32 s4, 0x149f
	v_readlane_b32 s9, v255, 6
	s_cselect_b64 s[44:45], -1, 0
	s_ashr_i32 s47, s46, 31
	s_lshl_b64 s[8:9], s[46:47], 18
	s_add_u32 s7, s0, s8
	s_addc_u32 s8, s1, s9
	s_cmpk_lt_i32 s4, 0x14a0
	s_waitcnt vmcnt(0)
	s_cselect_b32 s41, s8, 0
	s_cselect_b32 s40, s7, 0
	v_readlane_b32 s12, v255, 9
	v_readlane_b32 s13, v255, 10
	s_cmp_eq_u64 s[40:41], 0
	v_readlane_b32 s10, v255, 7
	v_readlane_b32 s11, v255, 8
	v_readlane_b32 s15, v255, 12
	s_barrier
	s_cbranch_scc1 .LBB0_425
	s_mul_i32 s7, s46, 40
	s_sub_i32 s8, s4, s7
	s_ashr_i32 s9, s8, 31
	s_lshl_b64 s[8:9], s[8:9], 18
	s_add_u32 s8, s12, s8
	s_addc_u32 s9, s13, s9
	v_lshl_add_u64 v[70:71], s[40:41], 0, v[68:69]
	v_lshl_add_u64 v[72:73], s[8:9], 0, v[66:67]
	v_lshl_add_u64 v[66:67], s[40:41], 0, v[66:67]
	s_mov_b32 m0, s5
	s_nop 0
	global_load_lds_dwordx4 v[70:71], off
	s_mov_b64 s[10:11], 0x4000
	v_lshl_add_u64 v[68:69], s[8:9], 0, v[68:69]
	v_lshl_add_u64 v[74:75], v[66:67], 0, s[10:11]
	s_add_i32 s7, s5, 0x400
	s_mov_b32 m0, s7
	s_nop 0
	global_load_lds_dwordx4 v[74:75], off
	s_mov_b64 s[12:13], 0x8000
	v_lshl_add_u64 v[70:71], v[70:71], 0, s[12:13]
	s_add_i32 s7, s5, 0x800
	s_mov_b32 m0, s7
	s_nop 0
	global_load_lds_dwordx4 v[70:71], off
	s_mov_b64 s[14:15], 0xc000
	v_lshl_add_u64 v[66:67], v[66:67], 0, s[14:15]
	s_add_i32 s7, s5, 0xc00
	s_mov_b32 m0, s7
	s_nop 0
	global_load_lds_dwordx4 v[66:67], off
	s_mov_b32 m0, s6
	s_nop 0
	global_load_lds_dwordx4 v[68:69], off
	v_lshl_add_u64 v[66:67], v[72:73], 0, s[10:11]
	s_add_i32 s6, s5, 0x4400
	s_mov_b32 m0, s6
	s_nop 0
	global_load_lds_dwordx4 v[66:67], off
	v_lshl_add_u64 v[66:67], v[68:69], 0, s[12:13]
	s_add_i32 s6, s5, 0x4800
	s_mov_b32 m0, s6
	s_nop 0
	global_load_lds_dwordx4 v[66:67], off
	v_lshl_add_u64 v[66:67], v[72:73], 0, s[14:15]
	s_addk_i32 s5, 0x4c00
	s_mov_b32 m0, s5
	s_nop 0
	global_load_lds_dwordx4 v[66:67], off

; DI int get_tid() { int t = threadIdx.x; asm volatile("" : "+v"(t)); return t; }
; DI float zero_f() { float z = 0.f; asm volatile("" : "+v"(z)); return z; }
; template <int MT, class Epi>
; DI void gemm_tile(const u16* __restrict__ X, long ldx, const u16* __restrict__ W, long ldw, int K, char* smem,
;                   int m0, int n0, const Epi& epi, bool pre = false, const u16* Xn = nullptr, const u16* Wn = nullptr) {
;   const int tid = get_tid(), lane = tid & 63, wave = tid >> 6;
;   const int wm = wave & 1, wn = wave >> 1;
;   const int lr = lane & 15, g = lane >> 4;
;   const int rsw = (lr >> 1) & 7;
;   f32x4 acc[4][MT];
;   { const float z = zero_f();
; #pragma unroll
;   for (int a = 0; a < 4; ++a)
; #pragma unroll
;     for (int b = 0; b < MT; ++b) acc[a][b] = (f32x4){z, z, z, z}; }
;   const int wu = __builtin_amdgcn_readfirstlane(wave);
;   const unsigned sbase = (unsigned)__builtin_amdgcn_readfirstlane((int)(unsigned)(size_t)smem);
;   const int r8 = lane >> 3, c0 = (lane & 7) ^ (r8 >> 1);
;   const long oxe = (long)(wu * MT * 8 + r8) * ldx + (c0 << 3), oxo = (long)(wu * MT * 8 + r8) * ldx + ((c0 ^ 4) << 3);
;   const long owe = (long)(wu * 32 + r8) * ldw + (c0 << 3), owo = (long)(wu * 32 + r8) * ldw + ((c0 ^ 4) << 3);
;   const u16 *xe = X + oxe, *xo = X + oxo, *we = W + owe, *wo = W + owo;
;   const long ldx8 = 8 * ldx, ldw8 = 8 * ldw;
;   const unsigned xdst = sbase + wu * MT * 1024, wdst = sbase + 16384 + wu * 4096;
;     ...
;   if (!pre) {
;     __syncthreads();
;     GT_DMA(0u)
; DI void phase_odd(const Params& p, int o, int sub, char* smem) {
;     ...
;       } else {
;         const int u = t - 512, tm = u >> 3, tn = u & 7, m0 = M_PROMPT + tm * 64;
;         gemm_tile<2>(ao + (size_t)m0 * 1024, 1024, W + WO_O + (size_t)tn * 128 * 1024, 1024, 1024, smem, m0, tn * 128, epi);
.LBB0_904:
	s_and_b32 s7, s4, 7
	s_lshl_b32 s34, s7, 18
	s_cmpk_gt_i32 s6, 0x1ff
	s_mov_b64 s[38:39], -1
	s_cbranch_scc0 .LBB0_908
	s_bfe_u32 s8, s5, 0x190006
	s_mov_b32 s9, s35
	s_lshl_b64 s[12:13], s[8:9], 17
	s_lshl_b32 s8, s6, 3
	s_and_b32 s8, s8, 0x7fffffc0
	s_add_i32 s38, s8, 0x3000
	s_mov_b32 s39, s35
	s_and_b32 s7, s6, 7
	s_lshl_b64 s[8:9], s[38:39], 11
	v_readlane_b32 s10, v252, 24
	v_mov_b32_e32 v1, v185
	v_readlane_b32 s11, v252, 25
	s_add_u32 s8, s10, s8
	s_addc_u32 s9, s11, s9
	v_ashrrev_i32_e32 v2, 6, v1
	v_bfe_u32 v4, v1, 3, 3
	v_readfirstlane_b32 s11, v2
	v_and_b32_e32 v40, 1, v2
	v_bfe_u32 v42, v1, 4, 2
	v_lshl_or_b32 v2, s11, 4, v4
	v_bitop3_b32 v8, v42, v1, 7 bitop3:0x78
	v_ashrrev_i32_e32 v3, 31, v2
	s_lshl_b32 s10, s7, 18
	v_readlane_b32 s16, v252, 26
	v_lshl_or_b32 v4, s11, 5, v4
	v_lshlrev_b64 v[2:3], 11, v[2:3]
	v_lshlrev_b32_e32 v182, 4, v8
	v_readlane_b32 s17, v252, 27
	s_add_u32 s14, s16, s10
	v_mov_b32_e32 v0, v183
	v_ashrrev_i32_e32 v5, 31, v4
	v_lshl_add_u64 v[6:7], s[8:9], 0, v[2:3]
	v_xor_b32_e32 v10, 64, v182
	v_mov_b32_e32 v11, v183
	s_addc_u32 s15, s17, 0
	v_lshl_add_u64 v[8:9], v[6:7], 0, v[182:183]
	v_lshl_add_u64 v[6:7], v[6:7], 0, v[10:11]
	v_lshlrev_b64 v[4:5], 11, v[4:5]
	s_lshl_b32 s8, s11, 11
	s_barrier
	s_mov_b32 m0, s8
	s_nop 0
	global_load_lds_dwordx4 v[8:9], off
	s_mov_b64 s[18:19], 0x4000
	v_lshl_add_u64 v[12:13], s[14:15], 0, v[4:5]
	s_lshl_b32 s11, s11, 12
	v_lshl_add_u64 v[6:7], v[6:7], 0, s[18:19]
	s_or_b32 s9, s8, 0x400
	s_mov_b32 m0, s9
	s_nop 0
	global_load_lds_dwordx4 v[6:7], off
	v_lshl_add_u64 v[14:15], v[12:13], 0, v[182:183]
	v_lshl_add_u64 v[6:7], v[12:13], 0, v[10:11]
	s_add_i32 s9, s11, 0x4000
	s_mov_b32 m0, s9
	s_nop 0
	global_load_lds_dwordx4 v[14:15], off
	v_lshl_add_u64 v[8:9], v[6:7], 0, s[18:19]
	s_add_i32 s14, s11, 0x4400
	s_mov_b32 m0, s14
	s_nop 0
	global_load_lds_dwordx4 v[8:9], off
	s_mov_b64 s[14:15], 0x8000
	v_lshl_add_u64 v[8:9], v[14:15], 0, s[14:15]
	s_add_i32 s14, s11, 0x4800
	s_mov_b32 m0, s14
	s_nop 0
	global_load_lds_dwordx4 v[8:9], off
	s_mov_b64 s[14:15], 0xc000
	v_lshrrev_b32_e32 v16, 1, v1
	v_lshl_add_u64 v[6:7], v[6:7], 0, s[14:15]
	s_addk_i32 s11, 0x4c00
	s_mov_b32 m0, s11
	s_nop 0
	global_load_lds_dwordx4 v[6:7], off
	v_bitop3_b32 v6, v42, v16, 7 bitop3:0x78
	v_lshl_add_u64 v[4:5], s[34:35], 0, v[4:5]
	v_lshlrev_b32_e32 v48, 4, v6
	v_lshl_add_u64 v[6:7], v[4:5], 0, v[10:11]
	v_lshl_add_u64 v[32:33], s[16:17], 0, v[6:7]
	v_readlane_b32 s16, v255, 5
	v_lshl_add_u64 v[4:5], v[4:5], 0, v[182:183]
	v_readlane_b32 s20, v255, 9
	v_readlane_b32 s21, v255, 10
	v_lshl_add_u64 v[2:3], s[12:13], 0, v[2:3]
	v_readlane_b32 s12, v254, 54
	v_lshl_add_u64 v[34:35], s[20:21], 0, v[4:5]
	v_bitop3_b32 v4, v2, v182, 64 bitop3:0xf6
	v_mov_b32_e32 v5, v3
	v_readlane_b32 s13, v254, 55
	v_and_b32_e32 v41, 15, v1
	v_ashrrev_i32_e32 v43, 7, v1
	v_bfe_u32 v1, v1, 1, 3
	v_lshl_add_u64 v[36:37], s[12:13], 0, v[4:5]
	v_readlane_b32 s12, v254, 57
	v_bitop3_b32 v1, v42, v1, 4 bitop3:0x36
	v_readlane_b32 s17, v255, 6
	v_or_b32_e32 v2, v2, v182
	v_readlane_b32 s13, v254, 58
	s_mov_b32 s10, 0
	v_lshlrev_b32_e32 v47, 12, v40
	v_lshlrev_b32_e32 v44, 7, v41
	v_lshlrev_b32_e32 v45, 13, v43
	v_lshlrev_b32_e32 v46, 4, v1
	v_lshl_add_u64 v[38:39], s[12:13], 0, v[2:3]
	s_mov_b64 s[40:41], 0
	v_mov_b32_e32 v1, v0
	v_mov_b32_e32 v2, v0
	v_mov_b32_e32 v3, v0
	v_mov_b32_e32 v4, v0
	v_mov_b32_e32 v5, v0
	v_mov_b32_e32 v6, v0
	v_mov_b32_e32 v7, v0
	v_mov_b32_e32 v8, v0
	v_mov_b32_e32 v9, v0
	v_mov_b32_e32 v10, v0
	v_mov_b32_e32 v11, v0
	v_mov_b32_e32 v12, v0
	v_mov_b32_e32 v13, v0
	v_mov_b32_e32 v14, v0
	v_mov_b32_e32 v15, v0
	v_mov_b32_e32 v16, v0
	v_mov_b32_e32 v17, v0
	v_mov_b32_e32 v18, v0
	v_mov_b32_e32 v19, v0
	v_mov_b32_e32 v20, v0
	v_mov_b32_e32 v21, v0
	v_mov_b32_e32 v22, v0
	v_mov_b32_e32 v23, v0
	v_mov_b32_e32 v24, v0
	v_mov_b32_e32 v25, v0
	v_mov_b32_e32 v26, v0
	v_mov_b32_e32 v27, v0
	v_mov_b32_e32 v28, v0
	v_mov_b32_e32 v29, v0
	v_mov_b32_e32 v30, v0
	v_mov_b32_e32 v31, v0
	s_mov_b64 s[16:17], 0x5a0080
	v_readlane_b32 s18, v255, 7
	v_readlane_b32 s19, v255, 8
	v_readlane_b32 s22, v255, 11
	v_readlane_b32 s23, v255, 12

; DI int get_tid() { int t = threadIdx.x; asm volatile("" : "+v"(t)); return t; }
; DI float zero_f() { float z = 0.f; asm volatile("" : "+v"(z)); return z; }
; template <int BM, class Epi>
; DI void gemm_dma(const u16* __restrict__ X, long ldx, const u16* __restrict__ W, long ldw, int K, char* smem,
;                  int m0, int n0, const Epi& epi) {
;     ...
;   const int tid = get_tid(), lane = tid & 63, wave = tid >> 6;
;   const int lr = lane & 15, g = lane >> 4;
;   const int rd = lr * 64 + ((g ^ ((4 - (lr >> 2)) & 3)) << 4);
;   const int xrow0 = BIG ? wave * 64 : (wave & 1) * (BM / 2);
;   const int wrow0 = BIG ? 0 : (wave >> 1) * 64;
;   f32x4 acc[NT][MT];
;   { const float z = zero_f();
; #pragma unroll
;   for (int a = 0; a < NT; ++a)
; #pragma unroll
;     for (int b = 0; b < MT; ++b) acc[a][b] = (f32x4){z, z, z, z}; }
;   const int wu = __builtin_amdgcn_readfirstlane(wave);
;   const unsigned sbase = (unsigned)__builtin_amdgcn_readfirstlane((int)(unsigned)(size_t)smem);
;   const int r16 = lane >> 2, chunk = (lane & 3) ^ ((4 - (r16 >> 2)) & 3);
;   const u16* xs = X + (long)(wu * XD * 16 + r16) * ldx + (chunk << 3);
;   const u16* ws = W + (long)(wu * 32 + r16) * ldw + (chunk << 3);
;   const long ldx16 = 16 * ldx, ldw16 = 16 * ldw;
;   const unsigned xdst = sbase + wu * XD * 1024, wdst = sbase + BM * 64 + wu * 2048;
;     ...
;   const int nk = K >> 5;
;   __syncthreads();
; #pragma unroll
;   for (int s = 0; s < D - 1; ++s) GD_ISSUE(s)
;   int cur = 0, nxt = D - 1, kt = 0;
; DI void phase_odd(const Params& p, int o, int sub, char* smem) {
;     ...
;       if (t < 512) {
;         const int tm = t >> 3, tn = t & 7;
;         gemm_dma<256>(ao + (size_t)tm * 256 * 1024, 1024, W + WO_O + (size_t)tn * 128 * 1024, 1024, 1024, smem, tm * 256, tn * 128, epi);
.LBB0_908:
	s_and_b64 vcc, exec, s[38:39]
	s_cbranch_vccz .LBB0_903
	s_ashr_i32 s38, s6, 3
	s_ashr_i32 s39, s38, 31
	v_mov_b32_e32 v1, v185
	s_and_b32 s7, s6, 7
	s_lshl_b64 s[40:41], s[38:39], 19
	v_readlane_b32 s8, v252, 24
	v_readlane_b32 s9, v252, 25
	v_lshrrev_b32_e32 v2, 2, v1
	s_add_u32 s8, s8, s40
	v_and_b32_e32 v133, 15, v1
	v_bfe_u32 v132, v1, 4, 2
	v_sub_u32_e32 v2, 0, v2
	s_addc_u32 s9, s9, s41
	s_lshl_b32 s10, s7, 18
	v_readlane_b32 s12, v252, 26
	v_lshlrev_b32_e32 v0, 6, v133
	v_bitop3_b32 v2, v132, v2, 3 bitop3:0x78
	v_readlane_b32 s13, v252, 27
	s_add_u32 s12, s12, s10
	v_lshl_or_b32 v134, v2, 4, v0
	v_readfirstlane_b32 s14, v1
	v_lshrrev_b32_e32 v2, 4, v1
	s_addc_u32 s13, s13, 0
	s_ashr_i32 s15, s14, 6
	v_bfe_u32 v6, v1, 2, 4
	v_sub_u32_e32 v14, 0, v2
	s_andn2_b32 s14, s14, 63
	v_xor_b32_e32 v7, v1, v14
	v_or_b32_e32 v2, s14, v6
	v_ashrrev_i32_e32 v3, 31, v2
	v_lshlrev_b32_e32 v7, 4, v7
	v_lshl_or_b32 v6, s15, 5, v6
	v_lshlrev_b64 v[2:3], 11, v[2:3]
	v_and_b32_e32 v182, 48, v7
	v_ashrrev_i32_e32 v7, 31, v6
	v_mov_b32_e32 v0, v183
	v_lshl_add_u64 v[4:5], s[8:9], 0, v[2:3]
	v_lshlrev_b64 v[6:7], 11, v[6:7]
	v_lshl_add_u64 v[4:5], v[4:5], 0, v[182:183]
	v_lshl_add_u64 v[8:9], s[12:13], 0, v[6:7]
	s_lshl_b32 s8, s15, 12
	s_barrier
	s_mov_b32 m0, s8
	s_nop 0
	global_load_lds_dwordx4 v[4:5], off
	s_mov_b64 s[16:17], 0x8000
	v_lshl_add_u64 v[10:11], v[4:5], 0, s[16:17]
	s_or_b32 s13, s8, 0x400
	s_mov_b32 m0, s13
	s_nop 0
	global_load_lds_dwordx4 v[10:11], off
	s_mov_b64 s[18:19], 0x10000
	v_lshl_add_u64 v[10:11], v[4:5], 0, s[18:19]
	s_or_b32 s13, s8, 0x800
	s_mov_b32 m0, s13
	s_nop 0
	global_load_lds_dwordx4 v[10:11], off
	s_mov_b64 s[20:21], 0x18000
	s_lshl_b32 s12, s15, 11
	v_lshl_add_u64 v[10:11], v[4:5], 0, s[20:21]
	s_or_b32 s13, s8, 0xc00
	s_mov_b32 m0, s13
	s_nop 0
	global_load_lds_dwordx4 v[10:11], off
	v_lshl_add_u64 v[8:9], v[8:9], 0, v[182:183]
	s_add_i32 s9, s12, 0x4000
	s_mov_b32 m0, s9
	s_nop 0
	global_load_lds_dwordx4 v[8:9], off
	v_lshl_add_u64 v[10:11], v[8:9], 0, s[16:17]
	s_add_i32 s13, s12, 0x4400
	s_mov_b32 m0, s13
	s_nop 0
	global_load_lds_dwordx4 v[10:11], off
	v_lshl_add_u64 v[10:11], v[4:5], 0, 64
	s_add_i32 s13, s8, 0x6000
	s_mov_b32 m0, s13
	s_nop 0
	global_load_lds_dwordx4 v[10:11], off
	s_mov_b64 s[22:23], 0x8040
	v_lshl_add_u64 v[10:11], v[4:5], 0, s[22:23]
	s_add_i32 s13, s8, 0x6400
	s_mov_b32 m0, s13
	s_nop 0
	global_load_lds_dwordx4 v[10:11], off
	s_mov_b64 s[14:15], 0x10040
	v_lshl_add_u64 v[10:11], v[4:5], 0, s[14:15]
	s_add_i32 s13, s8, 0x6800
	s_mov_b32 m0, s13
	s_nop 0
	global_load_lds_dwordx4 v[10:11], off
	s_mov_b64 s[14:15], 0x18040
	v_lshl_add_u64 v[4:5], v[4:5], 0, s[14:15]
	s_add_i32 s13, s8, 0x6c00
	s_mov_b32 m0, s13
	s_nop 0
	global_load_lds_dwordx4 v[4:5], off
	v_lshl_add_u64 v[12:13], v[8:9], 0, 64
	s_add_i32 s13, s12, 0xa000
	s_mov_b32 m0, s13
	s_nop 0
	global_load_lds_dwordx4 v[12:13], off
	v_lshl_add_u64 v[4:5], v[8:9], 0, s[22:23]
	s_add_i32 s12, s12, 0xa400
	s_mov_b32 m0, s12
	s_nop 0
	global_load_lds_dwordx4 v[4:5], off
	v_and_b32_e32 v135, 0xffffffc0, v1
	v_bitop3_b32 v1, v1, 3, v14 bitop3:0x48
	v_lshl_add_u64 v[4:5], s[34:35], 0, v[6:7]
	v_lshlrev_b32_e32 v182, 4, v1
	v_readlane_b32 s12, v254, 59
	v_lshl_add_u64 v[4:5], v[4:5], 0, v[182:183]
	v_readlane_b32 s13, v254, 60
	v_lshl_add_u64 v[2:3], s[40:41], 0, v[2:3]
	v_or_b32_e32 v2, v2, v182
	v_lshl_add_u64 v[128:129], s[12:13], 0, v[4:5]
	v_readlane_b32 s12, v254, 61
	v_readlane_b32 s13, v254, 62
	s_mov_b32 s10, 2
	s_mov_b32 s11, 0
	v_lshlrev_b32_e32 v136, 6, v135
	v_lshl_add_u64 v[130:131], s[12:13], 0, v[2:3]
	s_mov_b64 s[40:41], 0
	v_mov_b32_e32 v1, v0
	v_mov_b32_e32 v2, v0
	v_mov_b32_e32 v3, v0
	v_mov_b32_e32 v4, v0
	v_mov_b32_e32 v5, v0
	v_mov_b32_e32 v6, v0
	v_mov_b32_e32 v7, v0
	v_mov_b32_e32 v8, v0
	v_mov_b32_e32 v9, v0
	v_mov_b32_e32 v10, v0
	v_mov_b32_e32 v11, v0
	v_mov_b32_e32 v12, v0
	v_mov_b32_e32 v13, v0
	v_mov_b32_e32 v14, v0
	v_mov_b32_e32 v15, v0
	v_mov_b32_e32 v16, v0
	v_mov_b32_e32 v17, v0
	v_mov_b32_e32 v18, v0
	v_mov_b32_e32 v19, v0
	v_mov_b32_e32 v20, v0
	v_mov_b32_e32 v21, v0
	v_mov_b32_e32 v22, v0
	v_mov_b32_e32 v23, v0
	v_mov_b32_e32 v24, v0
	v_mov_b32_e32 v25, v0
	v_mov_b32_e32 v26, v0
	v_mov_b32_e32 v27, v0
	v_mov_b32_e32 v28, v0
	v_mov_b32_e32 v29, v0
	v_mov_b32_e32 v30, v0
	v_mov_b32_e32 v31, v0
	v_mov_b32_e32 v32, v0
	v_mov_b32_e32 v33, v0
	v_mov_b32_e32 v34, v0
	v_mov_b32_e32 v35, v0
	v_mov_b32_e32 v36, v0
	v_mov_b32_e32 v37, v0
	v_mov_b32_e32 v38, v0
	v_mov_b32_e32 v39, v0
	v_mov_b32_e32 v40, v0
	v_mov_b32_e32 v41, v0
	v_mov_b32_e32 v42, v0
	v_mov_b32_e32 v43, v0
	v_mov_b32_e32 v44, v0
	v_mov_b32_e32 v45, v0
	v_mov_b32_e32 v46, v0
	v_mov_b32_e32 v47, v0
	v_mov_b32_e32 v48, v0
	v_mov_b32_e32 v49, v0
	v_mov_b32_e32 v50, v0
	v_mov_b32_e32 v51, v0
	v_mov_b32_e32 v52, v0
	v_mov_b32_e32 v53, v0
	v_mov_b32_e32 v54, v0
	v_mov_b32_e32 v55, v0
	v_mov_b32_e32 v56, v0
	v_mov_b32_e32 v57, v0
	v_mov_b32_e32 v58, v0
	v_mov_b32_e32 v59, v0
	v_mov_b32_e32 v60, v0
	v_mov_b32_e32 v61, v0
	v_mov_b32_e32 v62, v0
	v_mov_b32_e32 v63, v0
	v_mov_b32_e32 v64, v0
	v_mov_b32_e32 v65, v0
	v_mov_b32_e32 v66, v0
	v_mov_b32_e32 v67, v0
	v_mov_b32_e32 v68, v0
	v_mov_b32_e32 v69, v0
	v_mov_b32_e32 v70, v0
	v_mov_b32_e32 v71, v0
	v_mov_b32_e32 v72, v0
	v_mov_b32_e32 v73, v0
	v_mov_b32_e32 v74, v0
	v_mov_b32_e32 v75, v0
	v_mov_b32_e32 v76, v0
	v_mov_b32_e32 v77, v0
	v_mov_b32_e32 v78, v0
	v_mov_b32_e32 v79, v0
	v_mov_b32_e32 v80, v0
	v_mov_b32_e32 v81, v0
	v_mov_b32_e32 v82, v0
	v_mov_b32_e32 v83, v0
	v_mov_b32_e32 v84, v0
	v_mov_b32_e32 v85, v0
	v_mov_b32_e32 v86, v0
	v_mov_b32_e32 v87, v0
	v_mov_b32_e32 v88, v0
	v_mov_b32_e32 v89, v0
	v_mov_b32_e32 v90, v0
	v_mov_b32_e32 v91, v0
	v_mov_b32_e32 v92, v0
	v_mov_b32_e32 v93, v0
	v_mov_b32_e32 v94, v0
	v_mov_b32_e32 v95, v0
	v_mov_b32_e32 v96, v0
	v_mov_b32_e32 v97, v0
	v_mov_b32_e32 v98, v0
	v_mov_b32_e32 v99, v0
	v_mov_b32_e32 v100, v0
	v_mov_b32_e32 v101, v0
	v_mov_b32_e32 v102, v0
	v_mov_b32_e32 v103, v0
	v_mov_b32_e32 v104, v0
	v_mov_b32_e32 v105, v0
	v_mov_b32_e32 v106, v0
	v_mov_b32_e32 v107, v0
	v_mov_b32_e32 v108, v0
	v_mov_b32_e32 v109, v0
	v_mov_b32_e32 v110, v0
	v_mov_b32_e32 v111, v0
	v_mov_b32_e32 v112, v0
	v_mov_b32_e32 v113, v0
	v_mov_b32_e32 v114, v0
	v_mov_b32_e32 v115, v0
	v_mov_b32_e32 v116, v0
	v_mov_b32_e32 v117, v0
	v_mov_b32_e32 v118, v0
	v_mov_b32_e32 v119, v0
	v_mov_b32_e32 v120, v0
	v_mov_b32_e32 v121, v0
	v_mov_b32_e32 v122, v0
	v_mov_b32_e32 v123, v0
	v_mov_b32_e32 v124, v0
	v_mov_b32_e32 v125, v0
	v_mov_b32_e32 v126, v0
	v_mov_b32_e32 v127, v0

; DI float zero_f() { float z = 0.f; asm volatile("" : "+v"(z)); return z; }
; DI void attn_item(const u16* __restrict__ qbuf, const u16* __restrict__ knope, const u16* __restrict__ krope, ...
;     ...
;   f32x16 oacc[4];
;   { const float z = zero_f();
; #pragma unroll
;   for (int i = 0; i < 4; ++i)
; #pragma unroll
;     for (int j = 0; j < 16; ++j) oacc[i][j] = z; }
;   float m_run = -INFINITY, l_run = 0.f;
;   const int wu = __builtin_amdgcn_readfirstlane(wave);
;   const unsigned sbase = (unsigned)__builtin_amdgcn_readfirstlane((int)(unsigned)(size_t)smem);
;   const int r8 = lane >> 3, c0 = (lane & 7) ^ (r8 >> 1);
;   const unsigned ce = (unsigned)(c0 << 3), co = (unsigned)((c0 ^ 4) << 3);
;   unsigned ko = (unsigned)((kvrow0 + (wu & 1) * 32 + r8) * 1024 + head * 128 + (wu >> 1) * 64);
;   unsigned ro = (unsigned)((kvrow0 + wu * 16 + r8) * 64);
;   unsigned vo = (unsigned)((head * 128 + wu * 32 + r8) * vt_ld);
;   const unsigned vld8 = (unsigned)vt_ld * 8u;
;   const unsigned kdst = sbase + (wu >> 1) * 8192 + (wu & 1) * 4096;
;   const unsigned rdst = sbase + 16384 + wu * 2048;
;   const unsigned vdst = sbase + 24576 + wu * 4096;
;     ...
;   __syncthreads();
;   ATT_DMA(0u)
;   for (int kt = 0; kt < ntiles; ++kt) {
;     asm volatile("s_waitcnt vmcnt(0)" ::: "memory");
;     __syncthreads();
;     if (kt + 1 < ntiles) ATT_DMA((unsigned)((kt + 1) & 1) * 40960u)
.LBB0_938:
	s_or_b64 exec, exec, s[40:41]
	v_and_b32_e32 v3, 63, v0
	v_readfirstlane_b32 s11, v2
	v_lshrrev_b32_e32 v4, 3, v3
	v_lshrrev_b32_e32 v3, 4, v3
	s_and_b32 s10, s11, 1
	s_ashr_i32 s12, s11, 1
	v_bitop3_b32 v3, v3, v0, 7 bitop3:0x78
	s_lshl_b32 s14, s12, 6
	v_or_b32_e32 v5, s8, v4
	s_lshl_b32 s15, s10, 15
	v_lshlrev_b32_e32 v145, 3, v3
	v_lshl_or_b32 v3, v5, 10, s9
	s_add_i32 s15, s15, s14
	v_add_u32_e32 v3, s15, v3
	v_lshlrev_b32_e32 v8, 6, v5
	v_xor_b32_e32 v5, 32, v145
	v_or_b32_e32 v182, v3, v145
	v_add_u32_e32 v9, v3, v5
	v_mov_b32_e32 v48, v183
	s_lshl_b32 s12, s12, 13
	s_lshl_b32 s10, s10, 12
	v_lshl_add_u64 v[6:7], v[182:183], 1, s[92:93]
	v_add_u32_e32 v182, 0x2000, v9
	s_movk_i32 s2, 0x4000
	s_or_b32 s10, s12, s10
	s_barrier
	s_mov_b32 m0, s10
	s_nop 0
	global_load_lds_dwordx4 v[6:7], off
	v_lshl_add_u64 v[6:7], v[182:183], 1, s[92:93]
	v_add3_u32 v182, v3, v145, s2
	s_or_b32 s15, s10, 0x400
	s_mov_b32 m0, s15
	s_nop 0
	global_load_lds_dwordx4 v[6:7], off
	v_lshl_add_u64 v[6:7], v[182:183], 1, s[92:93]
	v_add_u32_e32 v182, 0x6000, v9
	s_or_b32 s15, s10, 0x800
	s_mov_b32 m0, s15
	s_nop 0
	global_load_lds_dwordx4 v[6:7], off
	v_lshl_add_u64 v[6:7], v[182:183], 1, s[92:93]
	s_lshl_b32 s14, s11, 5
	s_or_b32 s15, s10, 0xc00
	s_mov_b32 m0, s15
	s_nop 0
	global_load_lds_dwordx4 v[6:7], off
	v_lshl_add_u32 v6, s11, 10, v8
	s_add_i32 s14, s14, s9
	v_or_b32_e32 v182, v6, v145
	v_or_b32_e32 v4, s14, v4
	s_lshl_b32 s12, s11, 11
	v_lshl_add_u64 v[8:9], v[182:183], 1, s[30:31]
	v_bitop3_b32 v182, v145, v6, 32 bitop3:0xde
	v_lshlrev_b32_e32 v4, 13, v4
	s_lshl_b32 s14, s11, 12
	s_add_i32 s11, s12, 0x4000
	s_mov_b32 m0, s11
	s_nop 0
	global_load_lds_dwordx4 v[8:9], off
	v_lshl_add_u64 v[8:9], v[182:183], 1, s[30:31]
	s_mov_b64 s[16:17], 0x400
	v_lshl_add_u64 v[8:9], v[8:9], 0, s[16:17]
	v_or_b32_e32 v182, v4, v145
	s_addk_i32 s12, 0x4400
	s_mov_b32 m0, s12
	s_nop 0
	global_load_lds_dwordx4 v[8:9], off
	v_lshl_add_u64 v[8:9], v[182:183], 1, s[90:91]
	v_bitop3_b32 v7, v4, v145, 32 bitop3:0xf6
	s_add_i32 s12, s14, 0x6000
	s_mov_b32 m0, s12
	s_nop 0
	global_load_lds_dwordx4 v[8:9], off
	v_or_b32_e32 v8, 0x10000, v7
	v_mov_b32_e32 v9, v183
	v_lshl_add_u64 v[8:9], v[8:9], 1, s[90:91]
	s_add_i32 s15, s14, 0x6400
	s_mov_b32 m0, s15
	s_nop 0
	global_load_lds_dwordx4 v[8:9], off
	v_or_b32_e32 v182, 0x20000, v182
	v_lshl_add_u64 v[8:9], v[182:183], 1, s[90:91]
	s_add_i32 s15, s14, 0x6800
	s_mov_b32 m0, s15
	s_nop 0
	global_load_lds_dwordx4 v[8:9], off
	v_or_b32_e32 v182, 0x30000, v7
	v_lshl_add_u64 v[8:9], v[182:183], 1, s[90:91]
	s_addk_i32 s14, 0x6c00
	s_mov_b32 m0, s14
	s_nop 0
	global_load_lds_dwordx4 v[8:9], off
	v_mov_b32_e32 v49, v48
	v_mov_b32_e32 v50, v48
	v_mov_b32_e32 v51, v48
	v_mov_b32_e32 v52, v48
	v_mov_b32_e32 v53, v48
	v_mov_b32_e32 v54, v48
	v_mov_b32_e32 v55, v48
	v_mov_b32_e32 v56, v48
	v_mov_b32_e32 v57, v48
	v_mov_b32_e32 v58, v48
	v_mov_b32_e32 v59, v48
	v_mov_b32_e32 v60, v48
	v_mov_b32_e32 v61, v48
	v_mov_b32_e32 v62, v48
	v_mov_b32_e32 v63, v48
	s_cmp_lt_i32 s13, 0
	s_cbranch_scc1 .LBB0_950
	v_cmp_gt_i32_e32 vcc, 2, v2
	v_lshrrev_b32_e32 v2, 1, v0
	s_lshl_b32 s14, s13, 1
	v_bfe_u32 v0, v0, 1, 3
	v_lshlrev_b32_e32 v1, 7, v1
	v_bitop3_b32 v2, v147, v2, 7 bitop3:0x78
	s_add_i32 s13, s14, 2
	s_or_b32 s15, s14, 1
	v_lshl_or_b32 v149, v2, 4, v1
	v_bitop3_b32 v2, v147, v0, 2 bitop3:0x36
	v_mov_b32_e32 v7, s13
	v_mov_b32_e32 v8, s15
	v_lshl_or_b32 v150, v2, 4, v1
	v_bitop3_b32 v2, v147, v0, 4 bitop3:0x36
	v_bitop3_b32 v0, v147, v0, 6 bitop3:0x36
	v_cndmask_b32_e32 v148, v7, v8, vcc
	v_lshl_or_b32 v151, v2, 4, v1
	v_lshl_or_b32 v152, v0, 4, v1
	v_or_b32_e32 v153, 64, v4
	v_add_u32_e32 v154, 0x1000, v6
	v_add_u32_e32 v155, 0x10000, v3
	v_or_b32_e32 v157, 0x2000, v5
	v_or_b32_e32 v159, 0x6000, v5
	v_or_b32_e32 v160, 0x200, v5
	v_or_b32_e32 v161, 0x10000, v5
	v_or_b32_e32 v163, 0x30000, v5
	v_mov_b64_e32 v[0:1], v[48:49]
	v_mov_b64_e32 v[16:17], v[48:49]
	v_mov_b64_e32 v[32:33], v[48:49]
	s_lshl_b32 s14, s13, 6
	v_lshlrev_b32_e32 v156, 2, v147
	v_or_b32_e32 v158, 0x4000, v145
	v_or_b32_e32 v162, 0x20000, v145
	v_mov_b32_e32 v146, 0xff800000
	v_mov_b32_e32 v164, 0
	s_mov_b32 s15, 0
	v_mov_b64_e32 v[2:3], v[50:51]
	v_mov_b64_e32 v[4:5], v[52:53]
	v_mov_b64_e32 v[6:7], v[54:55]
	v_mov_b64_e32 v[8:9], v[56:57]
	v_mov_b64_e32 v[10:11], v[58:59]
	v_mov_b64_e32 v[12:13], v[60:61]
	v_mov_b64_e32 v[14:15], v[62:63]
	v_mov_b64_e32 v[18:19], v[50:51]
	v_mov_b64_e32 v[20:21], v[52:53]
	v_mov_b64_e32 v[22:23], v[54:55]
	v_mov_b64_e32 v[24:25], v[56:57]
	v_mov_b64_e32 v[26:27], v[58:59]
	v_mov_b64_e32 v[28:29], v[60:61]
	v_mov_b64_e32 v[30:31], v[62:63]
	v_mov_b64_e32 v[34:35], v[50:51]
	v_mov_b64_e32 v[36:37], v[52:53]
	v_mov_b64_e32 v[38:39], v[54:55]
	v_mov_b64_e32 v[40:41], v[56:57]
	v_mov_b64_e32 v[42:43], v[58:59]
	v_mov_b64_e32 v[44:45], v[60:61]
	v_mov_b64_e32 v[46:47], v[62:63]
	s_mov_b32 s17, 0
.LBB0_940:
	s_waitcnt vmcnt(0)
	s_add_i32 s16, s17, 1
	s_cmp_ge_i32 s16, s13
	s_barrier
	s_cbranch_scc1 .LBB0_943
	s_bitcmp1_b32 s16, 0
	s_cselect_b32 s18, 0xa000, 0
	v_add_u32_e32 v182, v155, v145
	s_add_i32 s19, s18, s10
	v_lshl_add_u64 v[64:65], v[182:183], 1, s[92:93]
	s_mov_b32 m0, s19
	s_nop 0
	global_load_lds_dwordx4 v[64:65], off
	v_add_u32_e32 v182, v157, v155
	v_lshl_add_u64 v[64:65], v[182:183], 1, s[92:93]
	s_add_i32 s34, s19, 0x400
	s_mov_b32 m0, s34
	s_nop 0
	global_load_lds_dwordx4 v[64:65], off
	v_add_u32_e32 v182, v158, v155
	v_lshl_add_u64 v[64:65], v[182:183], 1, s[92:93]
	s_add_i32 s34, s19, 0x800
	s_mov_b32 m0, s34
	s_nop 0
	global_load_lds_dwordx4 v[64:65], off
	v_add_u32_e32 v182, v159, v155
	v_lshl_add_u64 v[64:65], v[182:183], 1, s[92:93]
	s_addk_i32 s19, 0xc00
	s_mov_b32 m0, s19
	s_nop 0
	global_load_lds_dwordx4 v[64:65], off
	v_add_u32_e32 v182, v154, v145
	s_add_i32 s19, s18, s11
	v_lshl_add_u64 v[64:65], v[182:183], 1, s[30:31]
	s_mov_b32 m0, s19
	s_nop 0
	global_load_lds_dwordx4 v[64:65], off
	v_add_u32_e32 v182, v160, v154
	v_lshl_add_u64 v[64:65], v[182:183], 1, s[30:31]
	s_addk_i32 s19, 0x400
	s_mov_b32 m0, s19
	s_nop 0
	global_load_lds_dwordx4 v[64:65], off
	v_add_u32_e32 v182, v153, v145
	s_add_i32 s18, s18, s12
	v_lshl_add_u64 v[64:65], v[182:183], 1, s[90:91]
	s_mov_b32 m0, s18
	s_nop 0
	global_load_lds_dwordx4 v[64:65], off
	v_add_u32_e32 v182, v161, v153
	v_lshl_add_u64 v[64:65], v[182:183], 1, s[90:91]
	s_add_i32 s19, s18, 0x400
	s_mov_b32 m0, s19
	s_nop 0
	global_load_lds_dwordx4 v[64:65], off
	v_add_u32_e32 v182, v162, v153
	v_lshl_add_u64 v[64:65], v[182:183], 1, s[90:91]
	s_add_i32 s19, s18, 0x800
	s_mov_b32 m0, s19
	s_nop 0
	global_load_lds_dwordx4 v[64:65], off
	v_add_u32_e32 v182, v163, v153
	v_lshl_add_u64 v[64:65], v[182:183], 1, s[90:91]
	s_addk_i32 s18, 0xc00
	s_mov_b32 m0, s18
	s_nop 0
	global_load_lds_dwordx4 v[64:65], off
	v_add_u32_e32 v155, 0x10000, v155
	v_add_u32_e32 v154, 0x1000, v154
	v_add_u32_e32 v153, 64, v153
	v_cmp_lt_i32_e32 vcc, s17, v148
	s_and_b64 s[18:19], s[38:39], vcc
	s_and_saveexec_b64 s[84:85], s[18:19]
	s_cbranch_execnz .LBB0_944

; template <int N> DI void wait_vm() { asm volatile("s_waitcnt vmcnt(%0)" ::"n"(N) : "memory"); }
; template <int BM, class Epi>
; DI void gemm_dma(const u16* __restrict__ X, long ldx, const u16* __restrict__ W, long ldw, int K, char* smem,
;                  int m0, int n0, const Epi& epi) {
;     ...
;   const int wu = __builtin_amdgcn_readfirstlane(wave);
;   const unsigned sbase = (unsigned)__builtin_amdgcn_readfirstlane((int)(unsigned)(size_t)smem);
;   const int r16 = lane >> 2, chunk = (lane & 3) ^ ((4 - (r16 >> 2)) & 3);
;   const u16* xs = X + (long)(wu * XD * 16 + r16) * ldx + (chunk << 3);
;   const u16* ws = W + (long)(wu * 32 + r16) * ldw + (chunk << 3);
;   const long ldx16 = 16 * ldx, ldw16 = 16 * ldw;
;   const unsigned xdst = sbase + wu * XD * 1024, wdst = sbase + BM * 64 + wu * 2048;
;     ...
;   const int nk = K >> 5;
;   __syncthreads();
; #pragma unroll
;   for (int s = 0; s < D - 1; ++s) GD_ISSUE(s)
;   int cur = 0, nxt = D - 1, kt = 0;
;   do {
;     if (kt + D - 2 < nk) wait_vm<PW * (D - 2)>(); else wait_vm<0>();
;     __syncthreads();
;     if (kt + D - 1 < nk) GD_ISSUE(nxt)
;     nxt = (nxt + 1 == D) ? 0 : nxt + 1;
;     const char* base = smem + cur * STG;
;     cur = (cur + 1 == D) ? 0 : cur + 1;
;     bf16x8 xf[MT];
; #pragma unroll
;     for (int i = 0; i < MT; ++i) xf[i] = *(const bf16x8*)(base + (xrow0 + i * 16) * 64 + rd);
; DI void phase_odd(const Params& p, int o, int sub, char* smem) {
;     ...
;         int b, tm, tn; long kv0, ld; u16* C;
;         if (t < 512) { b = t >> 8; const int r = t & 255; tm = r >> 6; tn = r & 63; kv0 = (long)b * 8192; ld = 8192; C = vtb + (size_t)b * 1024 * 8192; }
;         else { const int u = t - 512; b = u / 36; const int r = u % 36; tm = r / 9; tn = r % 9; kv0 = (long)M_PROMPT + (long)b * KSTR_S; ld = KSTR_S;
;                C = vtb + (size_t)2 * 1024 * 8192 + (size_t)b * 1024 * KSTR_S; }
;         EpiVT ev{C, ld};
;         gemm_dma<256>(W + WO_KV + (size_t)(1024 + tm * 256) * 256, 256, ckvb + (size_t)(kv0 + tn * 128) * 256, 256, 256, smem, tm * 256, tn * 128, ev);
.LBB0_964:
	v_readlane_b32 s8, v255, 5
	s_lshl_b32 s7, s6, 17
	v_readlane_b32 s12, v255, 9
	v_readlane_b32 s9, v255, 6
	v_readlane_b32 s13, v255, 10
	s_add_u32 s8, s12, s7
	v_readlane_b32 s10, v255, 7
	s_addc_u32 s9, s13, 0
	s_lshl_b32 s5, s5, 7
	v_readlane_b32 s11, v255, 8
	s_add_u32 s10, s42, s5
	s_addc_u32 s11, s43, 0
	s_lshl_b64 s[10:11], s[10:11], 9
	v_mov_b32_e32 v128, v185
	s_add_u32 s42, s0, s10
	s_addc_u32 s43, s1, s11
	v_readfirstlane_b32 s7, v128
	v_lshrrev_b32_e32 v4, 4, v128
	s_ashr_i32 s10, s7, 6
	v_bfe_u32 v6, v128, 2, 4
	v_sub_u32_e32 v4, 0, v4
	s_andn2_b32 s7, s7, 63
	v_xor_b32_e32 v7, v128, v4
	v_or_b32_e32 v4, s7, v6
	v_lshrrev_b32_e32 v2, 2, v128
	v_ashrrev_i32_e32 v5, 31, v4
	v_and_b32_e32 v129, 15, v128
	v_bfe_u32 v0, v128, 4, 2
	v_sub_u32_e32 v2, 0, v2
	v_lshlrev_b64 v[4:5], 9, v[4:5]
	v_lshlrev_b32_e32 v7, 4, v7
	v_lshlrev_b32_e32 v1, 6, v129
	v_bitop3_b32 v0, v0, v2, 3 bitop3:0x78
	v_lshl_add_u64 v[4:5], s[8:9], 0, v[4:5]
	v_and_b32_e32 v182, 48, v7
	v_readlane_b32 s14, v255, 11
	v_lshl_or_b32 v8, v0, 4, v1
	v_mov_b32_e32 v0, v183
	v_lshl_add_u64 v[4:5], v[4:5], 0, v[182:183]
	s_mov_b64 s[8:9], 0x520000
	v_lshl_add_u64 v[10:11], v[4:5], 0, s[8:9]
	v_lshl_or_b32 v6, s10, 5, v6
	s_lshl_b32 s14, s10, 12
	s_waitcnt lgkmcnt(0)
	s_barrier
	s_mov_b32 m0, s14
	s_nop 0
	global_load_lds_dwordx4 v[10:11], off
	s_mov_b64 s[8:9], 0x522000
	v_ashrrev_i32_e32 v7, 31, v6
	v_lshl_add_u64 v[10:11], v[4:5], 0, s[8:9]
	s_or_b32 s17, s14, 0x400
	s_mov_b32 m0, s17
	s_nop 0
	global_load_lds_dwordx4 v[10:11], off
	s_mov_b64 s[8:9], 0x524000
	v_lshlrev_b64 v[6:7], 9, v[6:7]
	v_lshl_add_u64 v[10:11], v[4:5], 0, s[8:9]
	s_or_b32 s18, s14, 0x800
	s_mov_b32 m0, s18
	s_nop 0
	global_load_lds_dwordx4 v[10:11], off
	s_mov_b64 s[8:9], 0x526000
	v_lshl_add_u64 v[6:7], s[42:43], 0, v[6:7]
	s_lshl_b32 s34, s10, 11
	v_lshl_add_u64 v[10:11], v[4:5], 0, s[8:9]
	s_or_b32 s16, s14, 0xc00
	s_mov_b32 m0, s16
	s_nop 0
	global_load_lds_dwordx4 v[10:11], off
	v_readlane_b32 s15, v255, 12
	v_lshl_add_u64 v[6:7], v[6:7], 0, v[182:183]
	s_add_i32 s13, s34, 0x4000
	s_mov_b32 m0, s13
	s_nop 0
	global_load_lds_dwordx4 v[6:7], off
	s_mov_b64 s[8:9], 0x2000
	v_lshl_add_u64 v[10:11], v[6:7], 0, s[8:9]
	s_add_i32 s15, s34, 0x4400
	s_mov_b32 m0, s15
	s_nop 0
	global_load_lds_dwordx4 v[10:11], off
	s_mov_b64 s[8:9], 0x520040
	v_lshl_add_u64 v[10:11], v[4:5], 0, s[8:9]
	s_add_i32 s10, s14, 0x6000
	s_mov_b32 m0, s10
	s_nop 0
	global_load_lds_dwordx4 v[10:11], off
	s_mov_b64 s[8:9], 0x522040
	v_lshl_add_u64 v[10:11], v[4:5], 0, s[8:9]
	s_add_i32 s9, s14, 0x6400
	s_mov_b32 m0, s9
	s_nop 0
	global_load_lds_dwordx4 v[10:11], off
	s_mov_b64 s[20:21], 0x524040
	v_lshl_add_u64 v[10:11], v[4:5], 0, s[20:21]
	s_add_i32 s12, s14, 0x6800
	s_mov_b32 m0, s12
	s_nop 0
	global_load_lds_dwordx4 v[10:11], off
	s_mov_b64 s[20:21], 0x526040
	v_lshl_add_u64 v[10:11], v[4:5], 0, s[20:21]
	s_add_i32 s11, s14, 0x6c00
	s_mov_b32 m0, s11
	s_nop 0
	global_load_lds_dwordx4 v[10:11], off
	v_lshl_add_u64 v[12:13], v[6:7], 0, 64
	s_add_i32 s7, s34, 0xa000
	s_mov_b32 m0, s7
	s_nop 0
	global_load_lds_dwordx4 v[12:13], off
	s_mov_b64 s[20:21], 0x2040
	v_lshl_add_u64 v[10:11], v[6:7], 0, s[20:21]
	s_add_i32 s8, s34, 0xa400
	s_mov_b32 m0, s8
	s_nop 0
	global_load_lds_dwordx4 v[10:11], off
	s_mov_b64 s[20:21], 0x520080
	v_lshl_add_u64 v[10:11], v[4:5], 0, s[20:21]
	s_waitcnt vmcnt(6)
	s_barrier
	s_add_i32 s42, s14, 0xc000
	s_mov_b32 m0, s42
	s_nop 0
	global_load_lds_dwordx4 v[10:11], off
	s_mov_b64 s[20:21], 0x522080
	v_lshl_add_u64 v[10:11], v[4:5], 0, s[20:21]
	s_add_i32 s41, s14, 0xc400
	s_mov_b32 m0, s41
	s_nop 0
	global_load_lds_dwordx4 v[10:11], off
	s_mov_b64 s[20:21], 0x524080
	v_lshl_add_u64 v[10:11], v[4:5], 0, s[20:21]
	s_add_i32 s44, s14, 0xc800
	s_mov_b32 m0, s44
	s_nop 0
	global_load_lds_dwordx4 v[10:11], off
	s_mov_b64 s[20:21], 0x526080
	v_lshl_add_u64 v[10:11], v[4:5], 0, s[20:21]
	s_add_i32 s43, s14, 0xcc00
	s_mov_b32 m0, s43
	s_nop 0
	global_load_lds_dwordx4 v[10:11], off
	v_lshl_add_u64 v[12:13], v[6:7], 0, s[28:29]
	v_and_b32_e32 v130, 0xffffffc0, v128
	s_add_i32 s19, s34, 0x10000
	s_mov_b32 m0, s19
	s_nop 0
	global_load_lds_dwordx4 v[12:13], off
	s_mov_b64 s[20:21], 0x2080
	v_lshl_add_u64 v[10:11], v[6:7], 0, s[20:21]
	s_add_i32 s34, s34, 0x10400
	s_mov_b32 m0, s34
	s_nop 0
	global_load_lds_dwordx4 v[10:11], off
	v_lshl_or_b32 v9, v130, 6, v8
	ds_read_b128 v[10:13], v9
	ds_read_b128 v[14:17], v9 offset:1024
	ds_read_b128 v[18:21], v9 offset:2048
	ds_read_b128 v[22:25], v9 offset:3072
	ds_read_b128 v[26:29], v8 offset:16384
	ds_read_b128 v[30:33], v8 offset:17408
	ds_read_b128 v[34:37], v8 offset:18432
	ds_read_b128 v[38:41], v8 offset:19456
	ds_read_b128 v[90:93], v8 offset:20480
	ds_read_b128 v[94:97], v8 offset:21504
	ds_read_b128 v[98:101], v8 offset:22528
	ds_read_b128 v[102:105], v8 offset:23552
	s_mov_b64 s[20:21], 0x5200c0
	v_lshl_add_u64 v[126:127], v[4:5], 0, s[20:21]
	s_mov_b64 s[20:21], 0xc0
	v_mov_b32_e32 v1, v0
	v_mov_b32_e32 v2, v0
	v_mov_b32_e32 v3, v0
	v_lshl_add_u64 v[148:149], v[6:7], 0, s[20:21]
	s_waitcnt vmcnt(6)
	s_waitcnt lgkmcnt(0)
	s_barrier
; template <int N> DI void wait_vm() { asm volatile("s_waitcnt vmcnt(%0)" ::"n"(N) : "memory"); }
; template <int BM, class Epi>
; DI void gemm_dma(const u16* __restrict__ X, long ldx, const u16* __restrict__ W, long ldw, int K, char* smem,
;                  int m0, int n0, const Epi& epi) {
;     ...
;   do {
;     if (kt + D - 2 < nk) wait_vm<PW * (D - 2)>(); else wait_vm<0>();
;     __syncthreads();
;     if (kt + D - 1 < nk) GD_ISSUE(nxt)
;     nxt = (nxt + 1 == D) ? 0 : nxt + 1;
;     const char* base = smem + cur * STG;
;     cur = (cur + 1 == D) ? 0 : cur + 1;
;     bf16x8 xf[MT];
; #pragma unroll
;     for (int i = 0; i < MT; ++i) xf[i] = *(const bf16x8*)(base + (xrow0 + i * 16) * 64 + rd);
; #pragma unroll
;     for (int nh = 0; nh < NT / 4; ++nh) {
;       bf16x8 wf[4];
; #pragma unroll
;       for (int i = 0; i < 4; ++i) wf[i] = *(const bf16x8*)(base + BM * 64 + (wrow0 + (nh * 4 + i) * 16) * 64 + rd);
; #pragma unroll
;       for (int i = 0; i < 4; ++i)
; #pragma unroll
;         for (int mt = 0; mt < MT; ++mt)
;           acc[nh * 4 + i][mt] = __builtin_amdgcn_mfma_f32_16x16x32_bf16(wf[i], xf[mt], acc[nh * 4 + i][mt], 0, 0, 0);
;     }
	s_mov_b32 m0, s14
	s_nop 0
	global_load_lds_dwordx4 v[126:127], off
	s_mov_b64 s[20:21], 0x5220c0
	v_mfma_f32_16x16x32_bf16 v[42:45], v[26:29], v[10:13], v[0:3]
	v_or_b32_e32 v131, 0x11000, v8
	v_or_b32_e32 v178, 0x11400, v8
	v_or_b32_e32 v179, 0x11800, v8
	v_mfma_f32_16x16x32_bf16 v[46:49], v[26:29], v[14:17], v[0:3]
	v_or_b32_e32 v180, 0x11c00, v8
	v_lshl_add_u32 v130, s6, 8, v130
	s_and_b32 s6, s5, 0x1f80
	v_mfma_f32_16x16x32_bf16 v[50:53], v[26:29], v[18:21], v[0:3]
	v_mfma_f32_16x16x32_bf16 v[26:29], v[26:29], v[22:25], v[0:3]
	v_mfma_f32_16x16x32_bf16 v[54:57], v[30:33], v[10:13], v[0:3]
	v_mfma_f32_16x16x32_bf16 v[58:61], v[30:33], v[14:17], v[0:3]
	v_mfma_f32_16x16x32_bf16 v[62:65], v[30:33], v[18:21], v[0:3]
	v_mfma_f32_16x16x32_bf16 v[30:33], v[30:33], v[22:25], v[0:3]
	v_mfma_f32_16x16x32_bf16 v[66:69], v[34:37], v[10:13], v[0:3]
	v_mfma_f32_16x16x32_bf16 v[70:73], v[34:37], v[14:17], v[0:3]
	v_mfma_f32_16x16x32_bf16 v[74:77], v[34:37], v[18:21], v[0:3]
	v_mfma_f32_16x16x32_bf16 v[34:37], v[34:37], v[22:25], v[0:3]
	v_mfma_f32_16x16x32_bf16 v[78:81], v[38:41], v[10:13], v[0:3]
	v_mfma_f32_16x16x32_bf16 v[82:85], v[38:41], v[14:17], v[0:3]
	v_mfma_f32_16x16x32_bf16 v[86:89], v[38:41], v[18:21], v[0:3]
	v_mfma_f32_16x16x32_bf16 v[38:41], v[38:41], v[22:25], v[0:3]
	v_mfma_f32_16x16x32_bf16 v[106:109], v[90:93], v[10:13], v[0:3]
	v_mfma_f32_16x16x32_bf16 v[110:113], v[90:93], v[14:17], v[0:3]
	v_mfma_f32_16x16x32_bf16 v[114:117], v[90:93], v[18:21], v[0:3]
	v_mfma_f32_16x16x32_bf16 v[90:93], v[90:93], v[22:25], v[0:3]
	v_mfma_f32_16x16x32_bf16 v[118:121], v[94:97], v[10:13], v[0:3]
	v_mfma_f32_16x16x32_bf16 v[122:125], v[94:97], v[14:17], v[0:3]
	v_mfma_f32_16x16x32_bf16 v[132:135], v[94:97], v[18:21], v[0:3]
	v_mfma_f32_16x16x32_bf16 v[94:97], v[94:97], v[22:25], v[0:3]
	v_mfma_f32_16x16x32_bf16 v[136:139], v[98:101], v[10:13], v[0:3]
	v_mfma_f32_16x16x32_bf16 v[140:143], v[98:101], v[14:17], v[0:3]
	v_mfma_f32_16x16x32_bf16 v[144:147], v[98:101], v[18:21], v[0:3]
	v_mfma_f32_16x16x32_bf16 v[98:101], v[98:101], v[22:25], v[0:3]
	v_mfma_f32_16x16x32_bf16 v[10:13], v[102:105], v[10:13], v[0:3]
	v_mfma_f32_16x16x32_bf16 v[14:17], v[102:105], v[14:17], v[0:3]
	v_mfma_f32_16x16x32_bf16 v[18:21], v[102:105], v[18:21], v[0:3]
	v_mfma_f32_16x16x32_bf16 v[0:3], v[102:105], v[22:25], v[0:3]
	v_lshl_add_u64 v[22:23], v[4:5], 0, s[20:21]
	s_mov_b32 m0, s17
	s_nop 0
	global_load_lds_dwordx4 v[22:23], off
	s_mov_b64 s[20:21], 0x5240c0
	v_lshl_add_u64 v[22:23], v[4:5], 0, s[20:21]
	s_mov_b32 m0, s18
	s_nop 0
	global_load_lds_dwordx4 v[22:23], off
	s_mov_b64 s[20:21], 0x5260c0
	v_lshl_add_u64 v[22:23], v[4:5], 0, s[20:21]
	s_mov_b32 m0, s16
	s_nop 0
	global_load_lds_dwordx4 v[22:23], off
	s_mov_b64 s[20:21], 0x20c0
	s_mov_b32 m0, s13
	s_nop 0
	global_load_lds_dwordx4 v[148:149], off
	v_lshl_add_u64 v[22:23], v[6:7], 0, s[20:21]
	s_mov_b32 m0, s15
	s_nop 0
	global_load_lds_dwordx4 v[22:23], off
	ds_read_b128 v[22:25], v9 offset:24576
	ds_read_b128 v[102:105], v9 offset:25600
	ds_read_b128 v[148:151], v9 offset:26624
	ds_read_b128 v[152:155], v9 offset:27648
	ds_read_b128 v[156:159], v8 offset:40960
	ds_read_b128 v[160:163], v8 offset:41984
	ds_read_b128 v[164:167], v8 offset:43008
	ds_read_b128 v[168:171], v8 offset:44032
	s_waitcnt lgkmcnt(3)
	v_mfma_f32_16x16x32_bf16 v[42:45], v[156:159], v[22:25], v[42:45]
	s_mov_b64 s[20:21], 0x520100
	v_lshl_add_u64 v[126:127], v[4:5], 0, s[20:21]
	s_mov_b64 s[20:21], 0x100
	v_mfma_f32_16x16x32_bf16 v[46:49], v[156:159], v[102:105], v[46:49]
	v_lshl_add_u64 v[172:173], v[6:7], 0, s[20:21]
	s_mov_b64 s[20:21], 0x522100
	v_mfma_f32_16x16x32_bf16 v[50:53], v[156:159], v[148:151], v[50:53]
	v_mfma_f32_16x16x32_bf16 v[26:29], v[156:159], v[152:155], v[26:29]
	s_waitcnt lgkmcnt(2)
	v_mfma_f32_16x16x32_bf16 v[54:57], v[160:163], v[22:25], v[54:57]
	v_mfma_f32_16x16x32_bf16 v[58:61], v[160:163], v[102:105], v[58:61]
	v_mfma_f32_16x16x32_bf16 v[62:65], v[160:163], v[148:151], v[62:65]
	v_mfma_f32_16x16x32_bf16 v[30:33], v[160:163], v[152:155], v[30:33]
	s_waitcnt lgkmcnt(1)
	v_mfma_f32_16x16x32_bf16 v[66:69], v[164:167], v[22:25], v[66:69]
	v_mfma_f32_16x16x32_bf16 v[70:73], v[164:167], v[102:105], v[70:73]
	v_mfma_f32_16x16x32_bf16 v[74:77], v[164:167], v[148:151], v[74:77]
	v_mfma_f32_16x16x32_bf16 v[34:37], v[164:167], v[152:155], v[34:37]
	s_waitcnt lgkmcnt(0)
	v_mfma_f32_16x16x32_bf16 v[78:81], v[168:171], v[22:25], v[78:81]
	v_mfma_f32_16x16x32_bf16 v[82:85], v[168:171], v[102:105], v[82:85]
	v_mfma_f32_16x16x32_bf16 v[86:89], v[168:171], v[148:151], v[86:89]
	v_mfma_f32_16x16x32_bf16 v[38:41], v[168:171], v[152:155], v[38:41]
	ds_read_b128 v[156:159], v8 offset:45056
	ds_read_b128 v[160:163], v8 offset:46080
	ds_read_b128 v[164:167], v8 offset:47104
	ds_read_b128 v[168:171], v8 offset:48128
	s_waitcnt vmcnt(6)
	s_waitcnt lgkmcnt(0)
	s_barrier
; template <int N> DI void wait_vm() { asm volatile("s_waitcnt vmcnt(%0)" ::"n"(N) : "memory"); }
; template <int BM, class Epi>
; DI void gemm_dma(const u16* __restrict__ X, long ldx, const u16* __restrict__ W, long ldw, int K, char* smem,
;                  int m0, int n0, const Epi& epi) {
;     ...
;   do {
;     if (kt + D - 2 < nk) wait_vm<PW * (D - 2)>(); else wait_vm<0>();
;     __syncthreads();
;     if (kt + D - 1 < nk) GD_ISSUE(nxt)
;     nxt = (nxt + 1 == D) ? 0 : nxt + 1;
;     const char* base = smem + cur * STG;
;     cur = (cur + 1 == D) ? 0 : cur + 1;
;     bf16x8 xf[MT];
; #pragma unroll
;     for (int i = 0; i < MT; ++i) xf[i] = *(const bf16x8*)(base + (xrow0 + i * 16) * 64 + rd);
; #pragma unroll
;     for (int nh = 0; nh < NT / 4; ++nh) {
;       bf16x8 wf[4];
; #pragma unroll
;       for (int i = 0; i < 4; ++i) wf[i] = *(const bf16x8*)(base + BM * 64 + (wrow0 + (nh * 4 + i) * 16) * 64 + rd);
; #pragma unroll
;       for (int i = 0; i < 4; ++i)
; #pragma unroll
;         for (int mt = 0; mt < MT; ++mt)
;           acc[nh * 4 + i][mt] = __builtin_amdgcn_mfma_f32_16x16x32_bf16(wf[i], xf[mt], acc[nh * 4 + i][mt], 0, 0, 0);
;     }
	s_mov_b32 m0, s10
	s_nop 0
	global_load_lds_dwordx4 v[126:127], off
	v_mfma_f32_16x16x32_bf16 v[106:109], v[156:159], v[22:25], v[106:109]
	v_mfma_f32_16x16x32_bf16 v[118:121], v[160:163], v[22:25], v[118:121]
	v_mfma_f32_16x16x32_bf16 v[136:139], v[164:167], v[22:25], v[136:139]
	v_mfma_f32_16x16x32_bf16 v[10:13], v[168:171], v[22:25], v[10:13]
	v_mfma_f32_16x16x32_bf16 v[22:25], v[168:171], v[152:155], v[0:3]
	s_nop 2
	v_lshl_add_u64 v[0:1], v[4:5], 0, s[20:21]
	s_mov_b32 m0, s9
	s_nop 0
	global_load_lds_dwordx4 v[0:1], off
	s_mov_b64 s[20:21], 0x524100
	v_lshl_add_u64 v[0:1], v[4:5], 0, s[20:21]
	s_mov_b32 m0, s12
	s_nop 0
	global_load_lds_dwordx4 v[0:1], off
	s_mov_b64 s[20:21], 0x526100
	v_lshl_add_u64 v[0:1], v[4:5], 0, s[20:21]
	s_mov_b32 m0, s11
	s_nop 0
	global_load_lds_dwordx4 v[0:1], off
	s_mov_b64 s[20:21], 0x2100
	s_mov_b32 m0, s7
	s_nop 0
	global_load_lds_dwordx4 v[172:173], off
	v_lshl_add_u64 v[0:1], v[6:7], 0, s[20:21]
	s_mov_b32 m0, s8
	s_nop 0
	global_load_lds_dwordx4 v[0:1], off
	v_or_b32_e32 v0, 0x10000, v8
	v_or_b32_e32 v1, 0x10400, v8
	v_or_b32_e32 v2, 0x10800, v8
	v_or_b32_e32 v3, 0x10c00, v8
	v_mfma_f32_16x16x32_bf16 v[110:113], v[156:159], v[102:105], v[110:113]
	s_mov_b64 s[20:21], 0x520140
	v_lshl_add_u64 v[126:127], v[4:5], 0, s[20:21]
	s_mov_b64 s[20:21], 0x140
	v_mfma_f32_16x16x32_bf16 v[114:117], v[156:159], v[148:151], v[114:117]
	v_lshl_add_u64 v[176:177], v[6:7], 0, s[20:21]
	s_mov_b64 s[20:21], 0x522140
	v_mfma_f32_16x16x32_bf16 v[90:93], v[156:159], v[152:155], v[90:93]
	v_mfma_f32_16x16x32_bf16 v[122:125], v[160:163], v[102:105], v[122:125]
	v_mfma_f32_16x16x32_bf16 v[132:135], v[160:163], v[148:151], v[132:135]
	v_mfma_f32_16x16x32_bf16 v[94:97], v[160:163], v[152:155], v[94:97]
	v_mfma_f32_16x16x32_bf16 v[140:143], v[164:167], v[102:105], v[140:143]
	v_mfma_f32_16x16x32_bf16 v[144:147], v[164:167], v[148:151], v[144:147]
	v_mfma_f32_16x16x32_bf16 v[98:101], v[164:167], v[152:155], v[98:101]
	v_mfma_f32_16x16x32_bf16 v[14:17], v[168:171], v[102:105], v[14:17]
	v_mfma_f32_16x16x32_bf16 v[18:21], v[168:171], v[148:151], v[18:21]
	ds_read_b128 v[102:105], v9 offset:49152
	ds_read_b128 v[148:151], v9 offset:50176
	ds_read_b128 v[152:155], v9 offset:51200
	ds_read_b128 v[156:159], v9 offset:52224
	ds_read_b128 v[160:163], v0
	ds_read_b128 v[164:167], v1
	ds_read_b128 v[168:171], v2
	ds_read_b128 v[172:175], v3
	s_waitcnt lgkmcnt(3)
	v_mfma_f32_16x16x32_bf16 v[42:45], v[160:163], v[102:105], v[42:45]
	v_mfma_f32_16x16x32_bf16 v[46:49], v[160:163], v[148:151], v[46:49]
	v_mfma_f32_16x16x32_bf16 v[50:53], v[160:163], v[152:155], v[50:53]
	v_mfma_f32_16x16x32_bf16 v[26:29], v[160:163], v[156:159], v[26:29]
	ds_read_b128 v[160:163], v131
	s_waitcnt lgkmcnt(3)
	v_mfma_f32_16x16x32_bf16 v[54:57], v[164:167], v[102:105], v[54:57]
	v_mfma_f32_16x16x32_bf16 v[58:61], v[164:167], v[148:151], v[58:61]
	v_mfma_f32_16x16x32_bf16 v[62:65], v[164:167], v[152:155], v[62:65]
	v_mfma_f32_16x16x32_bf16 v[30:33], v[164:167], v[156:159], v[30:33]
	ds_read_b128 v[164:167], v178
	s_waitcnt lgkmcnt(3)
	v_mfma_f32_16x16x32_bf16 v[66:69], v[168:171], v[102:105], v[66:69]
	v_mfma_f32_16x16x32_bf16 v[70:73], v[168:171], v[148:151], v[70:73]
	v_mfma_f32_16x16x32_bf16 v[74:77], v[168:171], v[152:155], v[74:77]
	v_mfma_f32_16x16x32_bf16 v[34:37], v[168:171], v[156:159], v[34:37]
	ds_read_b128 v[168:171], v179
	s_waitcnt lgkmcnt(3)
	v_mfma_f32_16x16x32_bf16 v[78:81], v[172:175], v[102:105], v[78:81]
	v_mfma_f32_16x16x32_bf16 v[82:85], v[172:175], v[148:151], v[82:85]
	v_mfma_f32_16x16x32_bf16 v[86:89], v[172:175], v[152:155], v[86:89]
	v_mfma_f32_16x16x32_bf16 v[38:41], v[172:175], v[156:159], v[38:41]
	ds_read_b128 v[172:175], v180
	s_waitcnt vmcnt(6)
	s_waitcnt lgkmcnt(0)
	s_barrier
	s_mov_b32 m0, s42
	s_nop 0
	global_load_lds_dwordx4 v[126:127], off
	v_mfma_f32_16x16x32_bf16 v[106:109], v[160:163], v[102:105], v[106:109]
	v_mfma_f32_16x16x32_bf16 v[118:121], v[164:167], v[102:105], v[118:121]
	v_mfma_f32_16x16x32_bf16 v[136:139], v[168:171], v[102:105], v[136:139]
	v_mfma_f32_16x16x32_bf16 v[10:13], v[172:175], v[102:105], v[10:13]
	v_lshl_add_u64 v[102:103], v[4:5], 0, s[20:21]
	s_mov_b32 m0, s41
	s_nop 0
	global_load_lds_dwordx4 v[102:103], off
	s_mov_b64 s[20:21], 0x524140
	v_lshl_add_u64 v[102:103], v[4:5], 0, s[20:21]
	s_mov_b32 m0, s44
	s_nop 0
	global_load_lds_dwordx4 v[102:103], off
	s_mov_b64 s[20:21], 0x526140
	v_lshl_add_u64 v[102:103], v[4:5], 0, s[20:21]
	s_mov_b32 m0, s43
	s_nop 0
	global_load_lds_dwordx4 v[102:103], off
	s_mov_b64 s[20:21], 0x2140
	s_mov_b32 m0, s19
	s_nop 0
	global_load_lds_dwordx4 v[176:177], off
	v_lshl_add_u64 v[102:103], v[6:7], 0, s[20:21]
	s_mov_b32 m0, s34
	s_nop 0
	global_load_lds_dwordx4 v[102:103], off
	v_mfma_f32_16x16x32_bf16 v[110:113], v[160:163], v[148:151], v[110:113]
	s_mov_b64 s[20:21], 0x520180
	v_lshl_add_u64 v[126:127], v[4:5], 0, s[20:21]
	s_mov_b64 s[20:21], 0x180
	v_mfma_f32_16x16x32_bf16 v[114:117], v[160:163], v[152:155], v[114:117]
	v_lshl_add_u64 v[176:177], v[6:7], 0, s[20:21]
	s_mov_b64 s[20:21], 0x522180
	v_mfma_f32_16x16x32_bf16 v[90:93], v[160:163], v[156:159], v[90:93]
	v_mfma_f32_16x16x32_bf16 v[122:125], v[164:167], v[148:151], v[122:125]
	v_mfma_f32_16x16x32_bf16 v[132:135], v[164:167], v[152:155], v[132:135]
	v_mfma_f32_16x16x32_bf16 v[94:97], v[164:167], v[156:159], v[94:97]
	v_mfma_f32_16x16x32_bf16 v[140:143], v[168:171], v[148:151], v[140:143]
	v_mfma_f32_16x16x32_bf16 v[144:147], v[168:171], v[152:155], v[144:147]
	v_mfma_f32_16x16x32_bf16 v[98:101], v[168:171], v[156:159], v[98:101]
	v_mfma_f32_16x16x32_bf16 v[14:17], v[172:175], v[148:151], v[14:17]
	v_mfma_f32_16x16x32_bf16 v[18:21], v[172:175], v[152:155], v[18:21]
	v_mfma_f32_16x16x32_bf16 v[22:25], v[172:175], v[156:159], v[22:25]
	ds_read_b128 v[102:105], v9
	ds_read_b128 v[148:151], v9 offset:1024
	ds_read_b128 v[152:155], v9 offset:2048
	ds_read_b128 v[156:159], v9 offset:3072
	ds_read_b128 v[160:163], v8 offset:16384
	ds_read_b128 v[164:167], v8 offset:17408
	ds_read_b128 v[168:171], v8 offset:18432
	ds_read_b128 v[172:175], v8 offset:19456
	s_waitcnt lgkmcnt(3)
; template <int N> DI void wait_vm() { asm volatile("s_waitcnt vmcnt(%0)" ::"n"(N) : "memory"); }
; template <int BM, class Epi>
; DI void gemm_dma(const u16* __restrict__ X, long ldx, const u16* __restrict__ W, long ldw, int K, char* smem,
;                  int m0, int n0, const Epi& epi) {
;     ...
;   do {
;     if (kt + D - 2 < nk) wait_vm<PW * (D - 2)>(); else wait_vm<0>();
;     __syncthreads();
;     if (kt + D - 1 < nk) GD_ISSUE(nxt)
;     nxt = (nxt + 1 == D) ? 0 : nxt + 1;
;     const char* base = smem + cur * STG;
;     cur = (cur + 1 == D) ? 0 : cur + 1;
;     bf16x8 xf[MT];
; #pragma unroll
;     for (int i = 0; i < MT; ++i) xf[i] = *(const bf16x8*)(base + (xrow0 + i * 16) * 64 + rd);
; #pragma unroll
;     for (int nh = 0; nh < NT / 4; ++nh) {
;       bf16x8 wf[4];
; #pragma unroll
;       for (int i = 0; i < 4; ++i) wf[i] = *(const bf16x8*)(base + BM * 64 + (wrow0 + (nh * 4 + i) * 16) * 64 + rd);
; #pragma unroll
;       for (int i = 0; i < 4; ++i)
; #pragma unroll
;         for (int mt = 0; mt < MT; ++mt)
;           acc[nh * 4 + i][mt] = __builtin_amdgcn_mfma_f32_16x16x32_bf16(wf[i], xf[mt], acc[nh * 4 + i][mt], 0, 0, 0);
;     }
	v_mfma_f32_16x16x32_bf16 v[42:45], v[160:163], v[102:105], v[42:45]
	v_mfma_f32_16x16x32_bf16 v[46:49], v[160:163], v[148:151], v[46:49]
	v_mfma_f32_16x16x32_bf16 v[50:53], v[160:163], v[152:155], v[50:53]
	v_mfma_f32_16x16x32_bf16 v[26:29], v[160:163], v[156:159], v[26:29]
	s_waitcnt lgkmcnt(2)
	v_mfma_f32_16x16x32_bf16 v[54:57], v[164:167], v[102:105], v[54:57]
	v_mfma_f32_16x16x32_bf16 v[58:61], v[164:167], v[148:151], v[58:61]
	v_mfma_f32_16x16x32_bf16 v[62:65], v[164:167], v[152:155], v[62:65]
	v_mfma_f32_16x16x32_bf16 v[30:33], v[164:167], v[156:159], v[30:33]
	s_waitcnt lgkmcnt(1)
	v_mfma_f32_16x16x32_bf16 v[66:69], v[168:171], v[102:105], v[66:69]
	v_mfma_f32_16x16x32_bf16 v[70:73], v[168:171], v[148:151], v[70:73]
	v_mfma_f32_16x16x32_bf16 v[74:77], v[168:171], v[152:155], v[74:77]
	v_mfma_f32_16x16x32_bf16 v[34:37], v[168:171], v[156:159], v[34:37]
	s_waitcnt lgkmcnt(0)
	v_mfma_f32_16x16x32_bf16 v[78:81], v[172:175], v[102:105], v[78:81]
	v_mfma_f32_16x16x32_bf16 v[82:85], v[172:175], v[148:151], v[82:85]
	v_mfma_f32_16x16x32_bf16 v[86:89], v[172:175], v[152:155], v[86:89]
	v_mfma_f32_16x16x32_bf16 v[38:41], v[172:175], v[156:159], v[38:41]
	ds_read_b128 v[160:163], v8 offset:20480
	ds_read_b128 v[164:167], v8 offset:21504
	ds_read_b128 v[168:171], v8 offset:22528
	ds_read_b128 v[172:175], v8 offset:23552
	s_waitcnt vmcnt(6)
	s_waitcnt lgkmcnt(0)
	s_barrier
	s_mov_b32 m0, s14
	s_nop 0
	global_load_lds_dwordx4 v[126:127], off
	v_mfma_f32_16x16x32_bf16 v[106:109], v[160:163], v[102:105], v[106:109]
	v_mfma_f32_16x16x32_bf16 v[118:121], v[164:167], v[102:105], v[118:121]
	v_mfma_f32_16x16x32_bf16 v[136:139], v[168:171], v[102:105], v[136:139]
	v_mfma_f32_16x16x32_bf16 v[10:13], v[172:175], v[102:105], v[10:13]
	v_lshl_add_u64 v[102:103], v[4:5], 0, s[20:21]
	s_mov_b32 m0, s17
	s_nop 0
	global_load_lds_dwordx4 v[102:103], off
	s_mov_b64 s[20:21], 0x524180
	v_lshl_add_u64 v[102:103], v[4:5], 0, s[20:21]
	s_mov_b32 m0, s18
	s_nop 0
	global_load_lds_dwordx4 v[102:103], off
	s_mov_b64 s[18:19], 0x526180
	v_lshl_add_u64 v[102:103], v[4:5], 0, s[18:19]
	s_mov_b32 m0, s16
	s_nop 0
	global_load_lds_dwordx4 v[102:103], off
	s_mov_b64 s[16:17], 0x2180
	s_mov_b32 m0, s13
	s_nop 0
	global_load_lds_dwordx4 v[176:177], off
	v_lshl_add_u64 v[102:103], v[6:7], 0, s[16:17]
	s_mov_b32 m0, s15
	s_nop 0
	global_load_lds_dwordx4 v[102:103], off
	v_mfma_f32_16x16x32_bf16 v[110:113], v[160:163], v[148:151], v[110:113]
	s_mov_b64 s[14:15], 0x5201c0
	v_lshl_add_u64 v[126:127], v[4:5], 0, s[14:15]
	s_mov_b64 s[14:15], 0x1c0
	v_mfma_f32_16x16x32_bf16 v[114:117], v[160:163], v[152:155], v[114:117]
	v_lshl_add_u64 v[176:177], v[6:7], 0, s[14:15]
	s_mov_b64 s[14:15], 0x5221c0
	v_mfma_f32_16x16x32_bf16 v[90:93], v[160:163], v[156:159], v[90:93]
	v_mfma_f32_16x16x32_bf16 v[122:125], v[164:167], v[148:151], v[122:125]
	v_mfma_f32_16x16x32_bf16 v[132:135], v[164:167], v[152:155], v[132:135]
	v_mfma_f32_16x16x32_bf16 v[94:97], v[164:167], v[156:159], v[94:97]
	v_mfma_f32_16x16x32_bf16 v[140:143], v[168:171], v[148:151], v[140:143]
	v_mfma_f32_16x16x32_bf16 v[144:147], v[168:171], v[152:155], v[144:147]
	v_mfma_f32_16x16x32_bf16 v[98:101], v[168:171], v[156:159], v[98:101]
	v_mfma_f32_16x16x32_bf16 v[14:17], v[172:175], v[148:151], v[14:17]
	v_mfma_f32_16x16x32_bf16 v[18:21], v[172:175], v[152:155], v[18:21]
	v_mfma_f32_16x16x32_bf16 v[22:25], v[172:175], v[156:159], v[22:25]
	ds_read_b128 v[102:105], v9 offset:24576
	ds_read_b128 v[148:151], v9 offset:25600
	ds_read_b128 v[152:155], v9 offset:26624
	ds_read_b128 v[156:159], v9 offset:27648
	ds_read_b128 v[160:163], v8 offset:40960
	ds_read_b128 v[164:167], v8 offset:41984
	ds_read_b128 v[168:171], v8 offset:43008
	ds_read_b128 v[172:175], v8 offset:44032
	s_waitcnt lgkmcnt(3)
	v_mfma_f32_16x16x32_bf16 v[42:45], v[160:163], v[102:105], v[42:45]
	v_mfma_f32_16x16x32_bf16 v[46:49], v[160:163], v[148:151], v[46:49]
	v_mfma_f32_16x16x32_bf16 v[50:53], v[160:163], v[152:155], v[50:53]
	v_mfma_f32_16x16x32_bf16 v[26:29], v[160:163], v[156:159], v[26:29]
	s_waitcnt lgkmcnt(2)
	v_mfma_f32_16x16x32_bf16 v[54:57], v[164:167], v[102:105], v[54:57]
	v_mfma_f32_16x16x32_bf16 v[58:61], v[164:167], v[148:151], v[58:61]
	v_mfma_f32_16x16x32_bf16 v[62:65], v[164:167], v[152:155], v[62:65]
	v_mfma_f32_16x16x32_bf16 v[30:33], v[164:167], v[156:159], v[30:33]
	s_waitcnt lgkmcnt(1)
	v_mfma_f32_16x16x32_bf16 v[66:69], v[168:171], v[102:105], v[66:69]
	v_mfma_f32_16x16x32_bf16 v[70:73], v[168:171], v[148:151], v[70:73]
	v_mfma_f32_16x16x32_bf16 v[74:77], v[168:171], v[152:155], v[74:77]
	v_mfma_f32_16x16x32_bf16 v[34:37], v[168:171], v[156:159], v[34:37]
	s_waitcnt lgkmcnt(0)
	v_mfma_f32_16x16x32_bf16 v[78:81], v[172:175], v[102:105], v[78:81]
	v_mfma_f32_16x16x32_bf16 v[82:85], v[172:175], v[148:151], v[82:85]
	v_mfma_f32_16x16x32_bf16 v[86:89], v[172:175], v[152:155], v[86:89]
	v_mfma_f32_16x16x32_bf16 v[38:41], v[172:175], v[156:159], v[38:41]
	ds_read_b128 v[160:163], v8 offset:45056
	ds_read_b128 v[164:167], v8 offset:46080
	ds_read_b128 v[168:171], v8 offset:47104
	ds_read_b128 v[172:175], v8 offset:48128
	s_waitcnt vmcnt(6)
	s_waitcnt lgkmcnt(0)
	s_barrier
; template <int N> DI void wait_vm() { asm volatile("s_waitcnt vmcnt(%0)" ::"n"(N) : "memory"); }
; template <int BM, class Epi>
; DI void gemm_dma(const u16* __restrict__ X, long ldx, const u16* __restrict__ W, long ldw, int K, char* smem,
;                  int m0, int n0, const Epi& epi) {
;     ...
;   do {
;     if (kt + D - 2 < nk) wait_vm<PW * (D - 2)>(); else wait_vm<0>();
;     __syncthreads();
;     if (kt + D - 1 < nk) GD_ISSUE(nxt)
;     nxt = (nxt + 1 == D) ? 0 : nxt + 1;
;     const char* base = smem + cur * STG;
;     cur = (cur + 1 == D) ? 0 : cur + 1;
;     bf16x8 xf[MT];
; #pragma unroll
;     for (int i = 0; i < MT; ++i) xf[i] = *(const bf16x8*)(base + (xrow0 + i * 16) * 64 + rd);
; #pragma unroll
;     for (int nh = 0; nh < NT / 4; ++nh) {
;       bf16x8 wf[4];
; #pragma unroll
;       for (int i = 0; i < 4; ++i) wf[i] = *(const bf16x8*)(base + BM * 64 + (wrow0 + (nh * 4 + i) * 16) * 64 + rd);
; #pragma unroll
;       for (int i = 0; i < 4; ++i)
; #pragma unroll
;         for (int mt = 0; mt < MT; ++mt)
;           acc[nh * 4 + i][mt] = __builtin_amdgcn_mfma_f32_16x16x32_bf16(wf[i], xf[mt], acc[nh * 4 + i][mt], 0, 0, 0);
;     }
	s_mov_b32 m0, s10
	s_nop 0
	global_load_lds_dwordx4 v[126:127], off
	v_mfma_f32_16x16x32_bf16 v[106:109], v[160:163], v[102:105], v[106:109]
	v_mfma_f32_16x16x32_bf16 v[118:121], v[164:167], v[102:105], v[118:121]
	v_mfma_f32_16x16x32_bf16 v[136:139], v[168:171], v[102:105], v[136:139]
	v_mfma_f32_16x16x32_bf16 v[10:13], v[172:175], v[102:105], v[10:13]
	v_lshl_add_u64 v[102:103], v[4:5], 0, s[14:15]
	s_mov_b32 m0, s9
	s_nop 0
	global_load_lds_dwordx4 v[102:103], off
	s_mov_b64 s[14:15], 0x5241c0
	v_lshl_add_u64 v[102:103], v[4:5], 0, s[14:15]
	s_mov_b32 m0, s12
	s_nop 0
	global_load_lds_dwordx4 v[102:103], off
	s_mov_b64 s[12:13], 0x5261c0
	v_lshl_add_u64 v[4:5], v[4:5], 0, s[12:13]
	s_mov_b32 m0, s11
	s_nop 0
	global_load_lds_dwordx4 v[4:5], off
	s_mov_b64 s[10:11], 0x21c0
	s_mov_b32 m0, s7
	s_nop 0
	global_load_lds_dwordx4 v[176:177], off
	v_lshl_add_u64 v[4:5], v[6:7], 0, s[10:11]
	s_mov_b32 m0, s8
	s_nop 0
	global_load_lds_dwordx4 v[4:5], off
	v_mfma_f32_16x16x32_bf16 v[110:113], v[160:163], v[148:151], v[110:113]
	v_mfma_f32_16x16x32_bf16 v[114:117], v[160:163], v[152:155], v[114:117]
	v_mfma_f32_16x16x32_bf16 v[90:93], v[160:163], v[156:159], v[90:93]
	v_mfma_f32_16x16x32_bf16 v[122:125], v[164:167], v[148:151], v[122:125]
	v_mfma_f32_16x16x32_bf16 v[132:135], v[164:167], v[152:155], v[132:135]
	v_mfma_f32_16x16x32_bf16 v[94:97], v[164:167], v[156:159], v[94:97]
	v_mfma_f32_16x16x32_bf16 v[140:143], v[168:171], v[148:151], v[140:143]
	v_mfma_f32_16x16x32_bf16 v[144:147], v[168:171], v[152:155], v[144:147]
	v_mfma_f32_16x16x32_bf16 v[98:101], v[168:171], v[156:159], v[98:101]
	v_mfma_f32_16x16x32_bf16 v[14:17], v[172:175], v[148:151], v[14:17]
	v_mfma_f32_16x16x32_bf16 v[18:21], v[172:175], v[152:155], v[18:21]
	v_mfma_f32_16x16x32_bf16 v[22:25], v[172:175], v[156:159], v[22:25]
	ds_read_b128 v[4:7], v9 offset:49152
	ds_read_b128 v[102:105], v9 offset:50176
	ds_read_b128 v[148:151], v9 offset:51200
	ds_read_b128 v[152:155], v9 offset:52224
	ds_read_b128 v[156:159], v0
	ds_read_b128 v[160:163], v1
	ds_read_b128 v[164:167], v2
	ds_read_b128 v[0:3], v3
	s_waitcnt lgkmcnt(3)
	v_mfma_f32_16x16x32_bf16 v[42:45], v[156:159], v[4:7], v[42:45]
	v_mfma_f32_16x16x32_bf16 v[46:49], v[156:159], v[102:105], v[46:49]
	v_mfma_f32_16x16x32_bf16 v[50:53], v[156:159], v[148:151], v[50:53]
	v_mfma_f32_16x16x32_bf16 v[26:29], v[156:159], v[152:155], v[26:29]
	s_waitcnt lgkmcnt(2)
	v_mfma_f32_16x16x32_bf16 v[54:57], v[160:163], v[4:7], v[54:57]
	v_mfma_f32_16x16x32_bf16 v[58:61], v[160:163], v[102:105], v[58:61]
	v_mfma_f32_16x16x32_bf16 v[62:65], v[160:163], v[148:151], v[62:65]
	v_mfma_f32_16x16x32_bf16 v[30:33], v[160:163], v[152:155], v[30:33]
	s_waitcnt lgkmcnt(1)
	v_mfma_f32_16x16x32_bf16 v[66:69], v[164:167], v[4:7], v[66:69]
	v_mfma_f32_16x16x32_bf16 v[70:73], v[164:167], v[102:105], v[70:73]
	v_mfma_f32_16x16x32_bf16 v[74:77], v[164:167], v[148:151], v[74:77]
	v_mfma_f32_16x16x32_bf16 v[34:37], v[164:167], v[152:155], v[34:37]
	s_waitcnt lgkmcnt(0)
	v_mfma_f32_16x16x32_bf16 v[78:81], v[0:3], v[4:7], v[78:81]
	v_mfma_f32_16x16x32_bf16 v[82:85], v[0:3], v[102:105], v[82:85]
	v_mfma_f32_16x16x32_bf16 v[86:89], v[0:3], v[148:151], v[86:89]
	v_mfma_f32_16x16x32_bf16 v[0:3], v[0:3], v[152:155], v[38:41]
	s_nop 2
	ds_read_b128 v[38:41], v131
	ds_read_b128 v[156:159], v178
	ds_read_b128 v[160:163], v179
	ds_read_b128 v[164:167], v180
	s_waitcnt vmcnt(6)
	s_waitcnt lgkmcnt(0)
	v_mfma_f32_16x16x32_bf16 v[106:109], v[38:41], v[4:7], v[106:109]
	s_barrier
	v_mfma_f32_16x16x32_bf16 v[110:113], v[38:41], v[102:105], v[110:113]
	v_mfma_f32_16x16x32_bf16 v[114:117], v[38:41], v[148:151], v[114:117]
	v_mfma_f32_16x16x32_bf16 v[38:41], v[38:41], v[152:155], v[90:93]
	v_mfma_f32_16x16x32_bf16 v[90:93], v[156:159], v[4:7], v[118:121]
	v_mfma_f32_16x16x32_bf16 v[118:121], v[156:159], v[102:105], v[122:125]
	v_mfma_f32_16x16x32_bf16 v[122:125], v[156:159], v[148:151], v[132:135]
	v_mfma_f32_16x16x32_bf16 v[94:97], v[156:159], v[152:155], v[94:97]
	v_mfma_f32_16x16x32_bf16 v[132:135], v[160:163], v[4:7], v[136:139]
	v_mfma_f32_16x16x32_bf16 v[136:139], v[160:163], v[102:105], v[140:143]
	v_mfma_f32_16x16x32_bf16 v[140:143], v[160:163], v[148:151], v[144:147]
	v_mfma_f32_16x16x32_bf16 v[98:101], v[160:163], v[152:155], v[98:101]
	v_mfma_f32_16x16x32_bf16 v[4:7], v[164:167], v[4:7], v[10:13]
	v_mfma_f32_16x16x32_bf16 v[10:13], v[164:167], v[102:105], v[14:17]
	v_mfma_f32_16x16x32_bf16 v[14:17], v[164:167], v[148:151], v[18:21]
	v_mfma_f32_16x16x32_bf16 v[18:21], v[164:167], v[152:155], v[22:25]
	s_nop 2
	ds_read_b128 v[22:25], v8 offset:23552
	ds_read_b128 v[102:105], v8 offset:22528
	ds_read_b128 v[144:147], v8 offset:21504
	ds_read_b128 v[148:151], v8 offset:20480
	ds_read_b128 v[152:155], v8 offset:19456
	ds_read_b128 v[156:159], v8 offset:18432
	ds_read_b128 v[160:163], v8 offset:17408
	ds_read_b128 v[164:167], v8 offset:16384
	ds_read_b128 v[168:171], v9 offset:3072
	ds_read_b128 v[172:175], v9 offset:2048
	ds_read_b128 v[176:179], v9 offset:1024
	ds_read_b128 v[186:189], v9
	s_waitcnt vmcnt(0)
	s_waitcnt lgkmcnt(0)
	v_mfma_f32_16x16x32_bf16 v[42:45], v[164:167], v[186:189], v[42:45]
	s_barrier
; template <int N> DI void wait_vm() { asm volatile("s_waitcnt vmcnt(%0)" ::"n"(N) : "memory"); }
; DI void st_bf4(u16* p, float a, float b, float c, float d) { *(uint2*)p = make_uint2(pk2(a, b), pk2(c, d)); }
; template <int BM, class Epi>
; DI void gemm_dma(const u16* __restrict__ X, long ldx, const u16* __restrict__ W, long ldw, int K, char* smem,
;                  int m0, int n0, const Epi& epi) {
;     ...
;   do {
;     if (kt + D - 2 < nk) wait_vm<PW * (D - 2)>(); else wait_vm<0>();
;     __syncthreads();
;     if (kt + D - 1 < nk) GD_ISSUE(nxt)
;     nxt = (nxt + 1 == D) ? 0 : nxt + 1;
;     const char* base = smem + cur * STG;
;     cur = (cur + 1 == D) ? 0 : cur + 1;
;     bf16x8 xf[MT];
; #pragma unroll
;     for (int i = 0; i < MT; ++i) xf[i] = *(const bf16x8*)(base + (xrow0 + i * 16) * 64 + rd);
; #pragma unroll
;     for (int nh = 0; nh < NT / 4; ++nh) {
;       bf16x8 wf[4];
; #pragma unroll
;       for (int i = 0; i < 4; ++i) wf[i] = *(const bf16x8*)(base + BM * 64 + (wrow0 + (nh * 4 + i) * 16) * 64 + rd);
; #pragma unroll
;       for (int i = 0; i < 4; ++i)
; #pragma unroll
;         for (int mt = 0; mt < MT; ++mt)
;           acc[nh * 4 + i][mt] = __builtin_amdgcn_mfma_f32_16x16x32_bf16(wf[i], xf[mt], acc[nh * 4 + i][mt], 0, 0, 0);
;     }
;   } while (++kt < nk);
;     ...
;   epi.run(acc, m0 + xrow0 + lr, n0 + wrow0 + 4 * g);
;   template <int NT, int MT> DI void run(f32x4 (&acc)[NT][MT], int mb, int nb) const {
; #pragma unroll
;     for (int nt = 0; nt < NT; ++nt) {
;       const int n = nb + nt * 16;
;       const int np = (n & ~12) | ((n & 4) << 1) | ((n & 8) >> 1);
; #pragma unroll
;       for (int mt = 0; mt < MT; ++mt) {
;         f32x4 v = acc[nt][mt];
;         st_bf4(C + (size_t)(mb + mt * 16) * ldc + np, v[0], v[1], v[2], v[3]);
;       }
;     }
;   }
	v_mfma_f32_16x16x32_bf16 v[46:49], v[164:167], v[176:179], v[46:49]
	v_mfma_f32_16x16x32_bf16 v[50:53], v[164:167], v[172:175], v[50:53]
	v_mfma_f32_16x16x32_bf16 v[26:29], v[164:167], v[168:171], v[26:29]
	v_mfma_f32_16x16x32_bf16 v[54:57], v[160:163], v[186:189], v[54:57]
	v_mfma_f32_16x16x32_bf16 v[58:61], v[160:163], v[176:179], v[58:61]
	v_mfma_f32_16x16x32_bf16 v[62:65], v[160:163], v[172:175], v[62:65]
	v_mfma_f32_16x16x32_bf16 v[30:33], v[160:163], v[168:171], v[30:33]
	v_mfma_f32_16x16x32_bf16 v[66:69], v[156:159], v[186:189], v[66:69]
	v_mfma_f32_16x16x32_bf16 v[70:73], v[156:159], v[176:179], v[70:73]
	v_mfma_f32_16x16x32_bf16 v[74:77], v[156:159], v[172:175], v[74:77]
	v_mfma_f32_16x16x32_bf16 v[34:37], v[156:159], v[168:171], v[34:37]
	v_mfma_f32_16x16x32_bf16 v[156:159], v[152:155], v[186:189], v[78:81]
	v_mfma_f32_16x16x32_bf16 v[160:163], v[152:155], v[176:179], v[82:85]
	v_mfma_f32_16x16x32_bf16 v[164:167], v[152:155], v[172:175], v[86:89]
	v_mfma_f32_16x16x32_bf16 v[0:3], v[152:155], v[168:171], v[0:3]
	v_mfma_f32_16x16x32_bf16 v[152:155], v[148:151], v[186:189], v[106:109]
	v_mfma_f32_16x16x32_bf16 v[190:193], v[148:151], v[176:179], v[110:113]
	v_mfma_f32_16x16x32_bf16 v[194:197], v[148:151], v[172:175], v[114:117]
	v_mfma_f32_16x16x32_bf16 v[38:41], v[148:151], v[168:171], v[38:41]
	v_mfma_f32_16x16x32_bf16 v[148:151], v[144:147], v[186:189], v[90:93]
	v_mfma_f32_16x16x32_bf16 v[224:227], v[144:147], v[176:179], v[118:121]
	v_mfma_f32_16x16x32_bf16 v[228:231], v[144:147], v[172:175], v[122:125]
	v_mfma_f32_16x16x32_bf16 v[144:147], v[144:147], v[168:171], v[94:97]
	v_mfma_f32_16x16x32_bf16 v[132:135], v[102:105], v[186:189], v[132:135]
	v_mfma_f32_16x16x32_bf16 v[136:139], v[102:105], v[176:179], v[136:139]
	v_mfma_f32_16x16x32_bf16 v[140:143], v[102:105], v[172:175], v[140:143]
	v_mfma_f32_16x16x32_bf16 v[232:235], v[102:105], v[168:171], v[98:101]
	v_mfma_f32_16x16x32_bf16 v[4:7], v[22:25], v[186:189], v[4:7]
	v_mfma_f32_16x16x32_bf16 v[176:179], v[22:25], v[176:179], v[10:13]
	v_mfma_f32_16x16x32_bf16 v[172:175], v[22:25], v[172:175], v[14:17]
	v_mfma_f32_16x16x32_bf16 v[168:171], v[22:25], v[168:171], v[18:21]
	ds_read_b128 v[186:189], v8 offset:48128
	ds_read_b128 v[10:13], v8 offset:47104
	ds_read_b128 v[14:17], v8 offset:46080
	ds_read_b128 v[18:21], v8 offset:45056
	ds_read_b128 v[22:25], v8 offset:44032
	ds_read_b128 v[78:81], v8 offset:43008
	ds_read_b128 v[82:85], v8 offset:41984
	ds_read_b128 v[86:89], v8 offset:40960
	ds_read_b128 v[236:239], v9 offset:27648
	ds_read_b128 v[240:243], v9 offset:26624
	ds_read_b128 v[244:247], v9 offset:25600
	ds_read_b128 v[248:251], v9 offset:24576
	s_waitcnt lgkmcnt(3)
	v_mfma_f32_16x16x32_bf16 v[112:115], v[86:89], v[236:239], v[26:29]
	v_mfma_f32_16x16x32_bf16 v[96:99], v[82:85], v[236:239], v[30:33]
	s_waitcnt lgkmcnt(0)
	v_mfma_f32_16x16x32_bf16 v[28:31], v[10:13], v[248:251], v[132:135]
	s_nop 4
	v_cvt_pk_bf16_f32 v112, v112, v113
	v_cvt_pk_bf16_f32 v113, v114, v115
	v_cvt_pk_bf16_f32 v96, v96, v97
	v_or_b32_e32 v132, v130, v129
	v_lshrrev_b32_e32 v129, 1, v128
	v_mfma_f32_16x16x32_bf16 v[124:127], v[86:89], v[248:251], v[42:45]
	v_and_b32_e32 v129, 8, v129
	v_lshrrev_b32_e32 v128, 3, v128
	v_and_or_b32 v133, v128, 4, v129
	v_or_b32_e32 v130, s6, v133
	v_mad_i64_i32 v[128:129], s[6:7], s40, v132, 0
	v_lshl_add_u64 v[128:129], v[128:129], 1, s[38:39]
	v_lshlrev_b32_e32 v182, 1, v130
	v_mfma_f32_16x16x32_bf16 v[120:123], v[86:89], v[244:247], v[46:49]
	v_lshl_add_u64 v[130:131], v[128:129], 0, v[182:183]
	v_cvt_pk_bf16_f32 v124, v124, v125
	v_cvt_pk_bf16_f32 v125, v126, v127
	global_store_dwordx2 v[130:131], v[124:125], off
	v_or_b32_e32 v124, 16, v132
	v_mad_i64_i32 v[124:125], s[6:7], s40, v124, 0
	v_lshl_add_u64 v[124:125], v[124:125], 1, s[38:39]
	v_mfma_f32_16x16x32_bf16 v[116:119], v[86:89], v[240:243], v[50:53]
	v_lshl_add_u64 v[126:127], v[124:125], 0, v[182:183]
	v_cvt_pk_bf16_f32 v120, v120, v121
	v_cvt_pk_bf16_f32 v121, v122, v123
	global_store_dwordx2 v[126:127], v[120:121], off
	v_or_b32_e32 v120, 32, v132
	v_mad_i64_i32 v[120:121], s[6:7], s40, v120, 0
	v_lshl_add_u64 v[120:121], v[120:121], 1, s[38:39]
	v_lshl_add_u64 v[122:123], v[120:121], 0, v[182:183]
	v_cvt_pk_bf16_f32 v116, v116, v117
	v_cvt_pk_bf16_f32 v117, v118, v119
	global_store_dwordx2 v[122:123], v[116:117], off
	v_or_b32_e32 v116, 48, v132
	v_mad_i64_i32 v[116:117], s[6:7], s40, v116, 0
	v_mfma_f32_16x16x32_bf16 v[108:111], v[82:85], v[248:251], v[54:57]
	v_lshl_add_u64 v[116:117], v[116:117], 1, s[38:39]
	v_lshl_add_u64 v[118:119], v[116:117], 0, v[182:183]
	global_store_dwordx2 v[118:119], v[112:113], off
	v_mfma_f32_16x16x32_bf16 v[104:107], v[82:85], v[244:247], v[58:61]
	v_or_b32_e32 v112, s5, v133
	v_lshlrev_b32_e32 v182, 1, v112
	v_lshl_add_u64 v[112:113], v[128:129], 0, v[182:183]
	v_mfma_f32_16x16x32_bf16 v[100:103], v[82:85], v[240:243], v[62:65]
	v_cvt_pk_bf16_f32 v108, v108, v109
	v_cvt_pk_bf16_f32 v109, v110, v111
	global_store_dwordx2 v[112:113], v[108:109], off offset:32
	v_mfma_f32_16x16x32_bf16 v[92:95], v[78:81], v[248:251], v[66:69]
	v_lshl_add_u64 v[108:109], v[124:125], 0, v[182:183]
; DI void st_bf4(u16* p, float a, float b, float c, float d) { *(uint2*)p = make_uint2(pk2(a, b), pk2(c, d)); }
;   template <int NT, int MT> DI void run(f32x4 (&acc)[NT][MT], int mb, int nb) const {
; #pragma unroll
;     for (int nt = 0; nt < NT; ++nt) {
;       const int n = nb + nt * 16;
;       const int np = (n & ~12) | ((n & 4) << 1) | ((n & 8) >> 1);
; #pragma unroll
;       for (int mt = 0; mt < MT; ++mt) {
;         f32x4 v = acc[nt][mt];
;         st_bf4(C + (size_t)(mb + mt * 16) * ldc + np, v[0], v[1], v[2], v[3]);
;       }
;     }
;   }
	v_cvt_pk_bf16_f32 v104, v104, v105
	v_cvt_pk_bf16_f32 v105, v106, v107
	v_mfma_f32_16x16x32_bf16 v[88:91], v[78:81], v[244:247], v[70:73]
	global_store_dwordx2 v[108:109], v[104:105], off offset:32
	v_lshl_add_u64 v[104:105], v[120:121], 0, v[182:183]
	v_cvt_pk_bf16_f32 v100, v100, v101
	v_mfma_f32_16x16x32_bf16 v[84:87], v[78:81], v[240:243], v[74:77]
	v_cvt_pk_bf16_f32 v101, v102, v103
	global_store_dwordx2 v[104:105], v[100:101], off offset:32
	v_lshl_add_u64 v[100:101], v[116:117], 0, v[182:183]
	v_mfma_f32_16x16x32_bf16 v[80:83], v[78:81], v[236:239], v[34:37]
	v_cvt_pk_bf16_f32 v97, v98, v99
	v_cvt_pk_bf16_f32 v92, v92, v93
	v_cvt_pk_bf16_f32 v93, v94, v95
	v_mfma_f32_16x16x32_bf16 v[76:79], v[22:25], v[248:251], v[156:159]
	v_cvt_pk_bf16_f32 v88, v88, v89
	v_cvt_pk_bf16_f32 v89, v90, v91
	v_cvt_pk_bf16_f32 v84, v84, v85
	v_mfma_f32_16x16x32_bf16 v[72:75], v[22:25], v[244:247], v[160:163]
	v_cvt_pk_bf16_f32 v85, v86, v87
	v_cvt_pk_bf16_f32 v80, v80, v81
	v_cvt_pk_bf16_f32 v81, v82, v83
	v_mfma_f32_16x16x32_bf16 v[68:71], v[22:25], v[240:243], v[164:167]
	v_cvt_pk_bf16_f32 v76, v76, v77
	v_cvt_pk_bf16_f32 v77, v78, v79
	s_nop 1
	v_cvt_pk_bf16_f32 v72, v72, v73
	v_mfma_f32_16x16x32_bf16 v[64:67], v[22:25], v[236:239], v[0:3]
	v_cvt_pk_bf16_f32 v73, v74, v75
	s_nop 0
	v_cvt_pk_bf16_f32 v68, v68, v69
	v_cvt_pk_bf16_f32 v69, v70, v71
	v_mfma_f32_16x16x32_bf16 v[60:63], v[18:21], v[248:251], v[152:155]
	v_cvt_pk_bf16_f32 v28, v28, v29
	s_nop 1
	v_cvt_pk_bf16_f32 v64, v64, v65
	v_cvt_pk_bf16_f32 v65, v66, v67
	v_mfma_f32_16x16x32_bf16 v[56:59], v[18:21], v[244:247], v[190:193]
	v_cvt_pk_bf16_f32 v29, v30, v31
	s_nop 0
	v_cvt_pk_bf16_f32 v60, v60, v61
	v_cvt_pk_bf16_f32 v61, v62, v63
	v_mfma_f32_16x16x32_bf16 v[52:55], v[18:21], v[240:243], v[194:197]
	global_store_dwordx2 v[100:101], v[96:97], off offset:32
	s_nop 1
	v_cvt_pk_bf16_f32 v56, v56, v57
	v_cvt_pk_bf16_f32 v57, v58, v59
	v_mfma_f32_16x16x32_bf16 v[48:51], v[18:21], v[236:239], v[38:41]
	global_store_dwordx2 v[112:113], v[92:93], off offset:64
	s_nop 0
	v_cvt_pk_bf16_f32 v52, v52, v53
	v_cvt_pk_bf16_f32 v53, v54, v55
	v_mfma_f32_16x16x32_bf16 v[44:47], v[14:17], v[248:251], v[148:151]
	global_store_dwordx2 v[108:109], v[88:89], off offset:64
	s_nop 1
	v_cvt_pk_bf16_f32 v48, v48, v49
	v_cvt_pk_bf16_f32 v49, v50, v51
	v_mfma_f32_16x16x32_bf16 v[40:43], v[14:17], v[244:247], v[224:227]
	global_store_dwordx2 v[104:105], v[84:85], off offset:64
	s_nop 0
	v_cvt_pk_bf16_f32 v44, v44, v45
	v_cvt_pk_bf16_f32 v45, v46, v47
	v_mfma_f32_16x16x32_bf16 v[36:39], v[14:17], v[240:243], v[228:231]
	global_store_dwordx2 v[100:101], v[80:81], off offset:64
	s_nop 1
	v_cvt_pk_bf16_f32 v40, v40, v41
	v_cvt_pk_bf16_f32 v41, v42, v43
	v_mfma_f32_16x16x32_bf16 v[32:35], v[14:17], v[236:239], v[144:147]
	global_store_dwordx2 v[112:113], v[76:77], off offset:96
	s_nop 0
	v_cvt_pk_bf16_f32 v36, v36, v37
	v_cvt_pk_bf16_f32 v37, v38, v39
	v_mfma_f32_16x16x32_bf16 v[24:27], v[10:13], v[244:247], v[136:139]
	global_store_dwordx2 v[108:109], v[72:73], off offset:96
	s_nop 1
	v_cvt_pk_bf16_f32 v32, v32, v33
	v_cvt_pk_bf16_f32 v33, v34, v35
	v_mfma_f32_16x16x32_bf16 v[20:23], v[10:13], v[240:243], v[140:143]
	global_store_dwordx2 v[104:105], v[68:69], off offset:96
	s_nop 0
	v_cvt_pk_bf16_f32 v24, v24, v25
	v_cvt_pk_bf16_f32 v25, v26, v27
	v_mfma_f32_16x16x32_bf16 v[16:19], v[10:13], v[236:239], v[232:235]
	global_store_dwordx2 v[100:101], v[64:65], off offset:96
	s_nop 1
	v_cvt_pk_bf16_f32 v20, v20, v21
	v_cvt_pk_bf16_f32 v21, v22, v23
	v_mfma_f32_16x16x32_bf16 v[12:15], v[186:189], v[248:251], v[4:7]
	global_store_dwordx2 v[112:113], v[60:61], off offset:128
	s_nop 0
	v_cvt_pk_bf16_f32 v16, v16, v17
	v_cvt_pk_bf16_f32 v17, v18, v19
	v_mfma_f32_16x16x32_bf16 v[8:11], v[186:189], v[244:247], v[176:179]
	global_store_dwordx2 v[108:109], v[56:57], off offset:128
	s_nop 1
	v_cvt_pk_bf16_f32 v12, v12, v13
	v_cvt_pk_bf16_f32 v13, v14, v15
	v_mfma_f32_16x16x32_bf16 v[4:7], v[186:189], v[240:243], v[172:175]
	global_store_dwordx2 v[104:105], v[52:53], off offset:128
	s_nop 0
	v_cvt_pk_bf16_f32 v8, v8, v9
	v_cvt_pk_bf16_f32 v9, v10, v11
	v_mfma_f32_16x16x32_bf16 v[0:3], v[186:189], v[236:239], v[168:171]
	global_store_dwordx2 v[100:101], v[48:49], off offset:128
	s_nop 1
	v_cvt_pk_bf16_f32 v4, v4, v5
	v_cvt_pk_bf16_f32 v5, v6, v7
	global_store_dwordx2 v[112:113], v[44:45], off offset:160
	global_store_dwordx2 v[108:109], v[40:41], off offset:160
	s_nop 0
	v_cvt_pk_bf16_f32 v0, v0, v1
	v_cvt_pk_bf16_f32 v1, v2, v3
	global_store_dwordx2 v[104:105], v[36:37], off offset:160
	global_store_dwordx2 v[100:101], v[32:33], off offset:160
	global_store_dwordx2 v[112:113], v[28:29], off offset:192
	global_store_dwordx2 v[108:109], v[24:25], off offset:192
	global_store_dwordx2 v[104:105], v[20:21], off offset:192
	global_store_dwordx2 v[100:101], v[16:17], off offset:192
	global_store_dwordx2 v[112:113], v[12:13], off offset:224
	global_store_dwordx2 v[108:109], v[8:9], off offset:224
	global_store_dwordx2 v[104:105], v[4:5], off offset:224
	global_store_dwordx2 v[100:101], v[0:1], off offset:224

; template <int N> DI void wait_vm() { asm volatile("s_waitcnt vmcnt(%0)" ::"n"(N) : "memory"); }
; template <int BM, class Epi>
; DI void gemm_dma(const u16* __restrict__ X, long ldx, const u16* __restrict__ W, long ldw, int K, char* smem,
;                  int m0, int n0, const Epi& epi) {
;     ...
;   const int wu = __builtin_amdgcn_readfirstlane(wave);
;   const unsigned sbase = (unsigned)__builtin_amdgcn_readfirstlane((int)(unsigned)(size_t)smem);
;   const int r16 = lane >> 2, chunk = (lane & 3) ^ ((4 - (r16 >> 2)) & 3);
;   const u16* xs = X + (long)(wu * XD * 16 + r16) * ldx + (chunk << 3);
;   const u16* ws = W + (long)(wu * 32 + r16) * ldw + (chunk << 3);
;   const long ldx16 = 16 * ldx, ldw16 = 16 * ldw;
;   const unsigned xdst = sbase + wu * XD * 1024, wdst = sbase + BM * 64 + wu * 2048;
;     ...
;   const int nk = K >> 5;
;   __syncthreads();
; #pragma unroll
;   for (int s = 0; s < D - 1; ++s) GD_ISSUE(s)
;   int cur = 0, nxt = D - 1, kt = 0;
;   do {
;     if (kt + D - 2 < nk) wait_vm<PW * (D - 2)>(); else wait_vm<0>();
;     __syncthreads();
;     if (kt + D - 1 < nk) GD_ISSUE(nxt)
;     nxt = (nxt + 1 == D) ? 0 : nxt + 1;
;     const char* base = smem + cur * STG;
;     cur = (cur + 1 == D) ? 0 : cur + 1;
;     bf16x8 xf[MT];
; #pragma unroll
;     for (int i = 0; i < MT; ++i) xf[i] = *(const bf16x8*)(base + (xrow0 + i * 16) * 64 + rd);
; DI void knope_tile(const Params& p, int u, char* smem) {
;   const u16* W = (const u16*)(p.ws + OFF_W);
;   const u16* ckvb = (const u16*)(p.ws + OFF_CKVB);
;   EpiBF16 ek{(u16*)(p.ws + OFF_KN), 1024};
;   const int tm = u >> 3, tn = u & 7;
;   gemm_dma<256>(ckvb + (size_t)tm * 256 * 256, 256, W + WO_KV + (size_t)tn * 128 * 256, 256, 256, smem, tm * 256, tn * 128, ek);
.LBB0_966:
	s_cmpk_gt_i32 s4, 0x77f
	s_cbranch_scc1 .LBB0_974
	s_cmpk_gt_i32 s4, 0x43f
	s_mov_b64 s[38:39], -1
	s_cbranch_scc0 .LBB0_969
	s_add_i32 s5, s4, 0xfffffcc0
	s_bfe_u32 s98, s5, 0x30003
	s_and_b32 s99, s5, 7
	s_lshl_b32 s99, s99, 3
	s_andn2_b32 s5, s5, 63
	s_or_b32 s5, s5, s99
	s_or_b32 s5, s5, s98
	s_lshr_b32 s6, s5, 3
	s_and_b32 s5, s5, 7
	s_lshl_b32 s7, s6, 17
	s_add_u32 s8, s0, s7
	s_addc_u32 s9, s1, 0
	s_lshl_b32 s7, s5, 16
	v_mov_b32_e32 v9, v185
	s_add_u32 s10, s87, s7
	s_addc_u32 s11, s90, 0
	v_readfirstlane_b32 s7, v9
	v_lshrrev_b32_e32 v4, 4, v9
	s_ashr_i32 s12, s7, 6
	v_bfe_u32 v6, v9, 2, 4
	v_sub_u32_e32 v4, 0, v4
	s_andn2_b32 s7, s7, 63
	v_lshrrev_b32_e32 v1, 2, v9
	v_xor_b32_e32 v7, v9, v4
	v_or_b32_e32 v4, s7, v6
	v_and_b32_e32 v89, 15, v9
	v_bfe_u32 v88, v9, 4, 2
	v_sub_u32_e32 v1, 0, v1
	v_ashrrev_i32_e32 v5, 31, v4
	v_lshlrev_b32_e32 v0, 6, v89
	v_bitop3_b32 v1, v88, v1, 3 bitop3:0x78
	v_lshlrev_b64 v[4:5], 9, v[4:5]
	v_lshlrev_b32_e32 v7, 4, v7
	v_lshl_or_b32 v6, s12, 5, v6
	v_lshl_or_b32 v8, v1, 4, v0
	v_mov_b32_e32 v0, v183
	v_lshl_add_u64 v[4:5], s[8:9], 0, v[4:5]
	v_and_b32_e32 v182, 48, v7
	v_ashrrev_i32_e32 v7, 31, v6
	v_lshl_add_u64 v[4:5], v[4:5], 0, v[182:183]
	v_lshlrev_b64 v[6:7], 9, v[6:7]
	s_lshl_b32 s14, s12, 12
	s_waitcnt lgkmcnt(0)
	s_barrier
	s_mov_b32 m0, s14
	s_nop 0
	global_load_lds_dwordx4 v[4:5], off
	s_mov_b64 s[8:9], 0x2000
	v_lshl_add_u64 v[6:7], s[10:11], 0, v[6:7]
	v_lshl_add_u64 v[10:11], v[4:5], 0, s[8:9]
	s_or_b32 s15, s14, 0x400
	s_mov_b32 m0, s15
	s_nop 0
	global_load_lds_dwordx4 v[10:11], off
	s_mov_b64 s[10:11], 0x4000
	v_lshl_add_u64 v[10:11], v[4:5], 0, s[10:11]
	s_or_b32 s16, s14, 0x800
	s_mov_b32 m0, s16
	s_nop 0
	global_load_lds_dwordx4 v[10:11], off
	s_mov_b64 s[10:11], 0x6000
	s_lshl_b32 s41, s12, 11
	v_lshl_add_u64 v[10:11], v[4:5], 0, s[10:11]
	s_or_b32 s17, s14, 0xc00
	s_mov_b32 m0, s17
	s_nop 0
	global_load_lds_dwordx4 v[10:11], off
	v_lshl_add_u64 v[6:7], v[6:7], 0, v[182:183]
	s_add_i32 s13, s41, 0x4000
	s_mov_b32 m0, s13
	s_nop 0
	global_load_lds_dwordx4 v[6:7], off
	v_lshl_add_u64 v[10:11], v[6:7], 0, s[8:9]
	s_add_i32 s18, s41, 0x4400
	s_mov_b32 m0, s18
	s_nop 0
	global_load_lds_dwordx4 v[10:11], off
	v_lshl_add_u64 v[10:11], v[4:5], 0, 64
	s_add_i32 s7, s14, 0x6000
	s_mov_b32 m0, s7
	s_nop 0
	global_load_lds_dwordx4 v[10:11], off
	s_mov_b64 s[20:21], 0x2040
	v_lshl_add_u64 v[10:11], v[4:5], 0, s[20:21]
	s_add_i32 s8, s14, 0x6400
	s_mov_b32 m0, s8
	s_nop 0
	global_load_lds_dwordx4 v[10:11], off
	s_mov_b64 s[10:11], 0x4040
	v_lshl_add_u64 v[10:11], v[4:5], 0, s[10:11]
	s_add_i32 s9, s14, 0x6800
	s_mov_b32 m0, s9
	s_nop 0
	global_load_lds_dwordx4 v[10:11], off
	s_mov_b64 s[10:11], 0x6040
	v_lshl_add_u64 v[10:11], v[4:5], 0, s[10:11]
	s_add_i32 s10, s14, 0x6c00
	s_mov_b32 m0, s10
	s_nop 0
	global_load_lds_dwordx4 v[10:11], off
	v_lshl_add_u64 v[12:13], v[6:7], 0, 64
	s_add_i32 s11, s41, 0xa000
	s_mov_b32 m0, s11
	s_nop 0
	global_load_lds_dwordx4 v[12:13], off
	v_lshl_add_u64 v[10:11], v[6:7], 0, s[20:21]
	s_add_i32 s12, s41, 0xa400
	s_mov_b32 m0, s12
	s_nop 0
	global_load_lds_dwordx4 v[10:11], off
	s_waitcnt vmcnt(6)
	s_barrier
	v_lshl_add_u64 v[12:13], v[4:5], 0, s[28:29]
	s_add_i32 s19, s14, 0xc000
	s_mov_b32 m0, s19
	s_nop 0
	global_load_lds_dwordx4 v[12:13], off
	s_mov_b64 s[20:21], 0x2080
	v_lshl_add_u64 v[12:13], v[4:5], 0, s[20:21]
	s_add_i32 s34, s14, 0xc400
	s_mov_b32 m0, s34
	s_nop 0
	global_load_lds_dwordx4 v[12:13], off
	v_lshl_add_u64 v[12:13], v[4:5], 0, s[94:95]
	s_add_i32 s38, s14, 0xc800
	s_mov_b32 m0, s38
	s_nop 0
	global_load_lds_dwordx4 v[12:13], off
	s_mov_b64 s[22:23], 0x6080
	v_lshl_add_u64 v[12:13], v[4:5], 0, s[22:23]
	s_add_i32 s39, s14, 0xcc00
	s_mov_b32 m0, s39
	s_nop 0
	global_load_lds_dwordx4 v[12:13], off
	v_and_b32_e32 v90, 0xffffffc0, v9
	v_lshl_add_u64 v[10:11], v[6:7], 0, s[28:29]
	s_add_i32 s40, s41, 0x10000
	s_mov_b32 m0, s40
	s_nop 0
	global_load_lds_dwordx4 v[10:11], off
	v_lshl_add_u64 v[10:11], v[6:7], 0, s[20:21]
	s_add_i32 s41, s41, 0x10400
	s_mov_b32 m0, s41
	s_nop 0
	global_load_lds_dwordx4 v[10:11], off
	v_lshl_or_b32 v9, v90, 6, v8
	ds_read_b128 v[10:13], v9
	ds_read_b128 v[14:17], v9 offset:1024
	ds_read_b128 v[18:21], v9 offset:2048
	ds_read_b128 v[22:25], v9 offset:3072
	ds_read_b128 v[26:29], v8 offset:16384
	ds_read_b128 v[30:33], v8 offset:17408
	ds_read_b128 v[34:37], v8 offset:18432
	ds_read_b128 v[38:41], v8 offset:19456
	ds_read_b128 v[96:99], v8 offset:20480
	ds_read_b128 v[100:103], v8 offset:21504
	ds_read_b128 v[104:107], v8 offset:22528
	ds_read_b128 v[108:111], v8 offset:23552
	s_mov_b64 s[20:21], 0xc0
	v_mov_b32_e32 v1, v0
	v_mov_b32_e32 v2, v0
	v_mov_b32_e32 v3, v0
	v_lshl_add_u64 v[86:87], v[4:5], 0, s[20:21]
	v_lshl_add_u64 v[148:149], v[6:7], 0, s[20:21]
	s_waitcnt vmcnt(6)
	s_waitcnt lgkmcnt(0)
	s_barrier
; template <int N> DI void wait_vm() { asm volatile("s_waitcnt vmcnt(%0)" ::"n"(N) : "memory"); }
; template <int BM, class Epi>
; DI void gemm_dma(const u16* __restrict__ X, long ldx, const u16* __restrict__ W, long ldw, int K, char* smem,
;                  int m0, int n0, const Epi& epi) {
;     ...
;   do {
;     if (kt + D - 2 < nk) wait_vm<PW * (D - 2)>(); else wait_vm<0>();
;     __syncthreads();
;     if (kt + D - 1 < nk) GD_ISSUE(nxt)
;     nxt = (nxt + 1 == D) ? 0 : nxt + 1;
;     const char* base = smem + cur * STG;
;     cur = (cur + 1 == D) ? 0 : cur + 1;
;     bf16x8 xf[MT];
; #pragma unroll
;     for (int i = 0; i < MT; ++i) xf[i] = *(const bf16x8*)(base + (xrow0 + i * 16) * 64 + rd);
; #pragma unroll
;     for (int nh = 0; nh < NT / 4; ++nh) {
;       bf16x8 wf[4];
; #pragma unroll
;       for (int i = 0; i < 4; ++i) wf[i] = *(const bf16x8*)(base + BM * 64 + (wrow0 + (nh * 4 + i) * 16) * 64 + rd);
; #pragma unroll
;       for (int i = 0; i < 4; ++i)
; #pragma unroll
;         for (int mt = 0; mt < MT; ++mt)
;           acc[nh * 4 + i][mt] = __builtin_amdgcn_mfma_f32_16x16x32_bf16(wf[i], xf[mt], acc[nh * 4 + i][mt], 0, 0, 0);
;     }
	s_mov_b32 m0, s14
	s_nop 0
	global_load_lds_dwordx4 v[86:87], off
	s_mov_b64 s[20:21], 0x20c0
	v_mfma_f32_16x16x32_bf16 v[42:45], v[26:29], v[10:13], v[0:3]
	s_mov_b64 s[22:23], 0x40c0
	v_or_b32_e32 v91, 0x10000, v8
	v_or_b32_e32 v174, 0x10400, v8
	v_mfma_f32_16x16x32_bf16 v[46:49], v[26:29], v[14:17], v[0:3]
	v_or_b32_e32 v175, 0x10800, v8
	v_or_b32_e32 v176, 0x10c00, v8
	v_or_b32_e32 v177, 0x11000, v8
	v_mfma_f32_16x16x32_bf16 v[50:53], v[26:29], v[18:21], v[0:3]
	v_or_b32_e32 v178, 0x11400, v8
	v_or_b32_e32 v179, 0x11800, v8
	v_or_b32_e32 v180, 0x11c00, v8
	v_mfma_f32_16x16x32_bf16 v[26:29], v[26:29], v[22:25], v[0:3]
	v_lshl_add_u32 v90, s6, 8, v90
	s_lshl_b32 s5, s5, 8
	v_lshl_or_b32 v182, v88, 3, s5
	v_mfma_f32_16x16x32_bf16 v[54:57], v[30:33], v[10:13], v[0:3]
	v_mfma_f32_16x16x32_bf16 v[58:61], v[30:33], v[14:17], v[0:3]
	v_mfma_f32_16x16x32_bf16 v[62:65], v[30:33], v[18:21], v[0:3]
	v_mfma_f32_16x16x32_bf16 v[30:33], v[30:33], v[22:25], v[0:3]
	v_mfma_f32_16x16x32_bf16 v[66:69], v[34:37], v[10:13], v[0:3]
	v_mfma_f32_16x16x32_bf16 v[70:73], v[34:37], v[14:17], v[0:3]
	v_mfma_f32_16x16x32_bf16 v[74:77], v[34:37], v[18:21], v[0:3]
	v_mfma_f32_16x16x32_bf16 v[34:37], v[34:37], v[22:25], v[0:3]
	v_mfma_f32_16x16x32_bf16 v[78:81], v[38:41], v[10:13], v[0:3]
	v_mfma_f32_16x16x32_bf16 v[82:85], v[38:41], v[14:17], v[0:3]
	v_mfma_f32_16x16x32_bf16 v[92:95], v[38:41], v[18:21], v[0:3]
	v_mfma_f32_16x16x32_bf16 v[38:41], v[38:41], v[22:25], v[0:3]
	v_mfma_f32_16x16x32_bf16 v[112:115], v[96:99], v[10:13], v[0:3]
	v_mfma_f32_16x16x32_bf16 v[116:119], v[96:99], v[14:17], v[0:3]
	v_mfma_f32_16x16x32_bf16 v[120:123], v[96:99], v[18:21], v[0:3]
	v_mfma_f32_16x16x32_bf16 v[96:99], v[96:99], v[22:25], v[0:3]
	v_mfma_f32_16x16x32_bf16 v[124:127], v[100:103], v[10:13], v[0:3]
	v_mfma_f32_16x16x32_bf16 v[128:131], v[100:103], v[14:17], v[0:3]
	v_mfma_f32_16x16x32_bf16 v[132:135], v[100:103], v[18:21], v[0:3]
	v_mfma_f32_16x16x32_bf16 v[100:103], v[100:103], v[22:25], v[0:3]
	v_mfma_f32_16x16x32_bf16 v[136:139], v[104:107], v[10:13], v[0:3]
	v_mfma_f32_16x16x32_bf16 v[140:143], v[104:107], v[14:17], v[0:3]
	v_mfma_f32_16x16x32_bf16 v[144:147], v[104:107], v[18:21], v[0:3]
	v_mfma_f32_16x16x32_bf16 v[104:107], v[104:107], v[22:25], v[0:3]
	v_mfma_f32_16x16x32_bf16 v[10:13], v[108:111], v[10:13], v[0:3]
	v_mfma_f32_16x16x32_bf16 v[14:17], v[108:111], v[14:17], v[0:3]
	v_mfma_f32_16x16x32_bf16 v[18:21], v[108:111], v[18:21], v[0:3]
	v_mfma_f32_16x16x32_bf16 v[0:3], v[108:111], v[22:25], v[0:3]
	v_lshl_add_u64 v[22:23], v[4:5], 0, s[20:21]
	s_mov_b32 m0, s15
	s_nop 0
	global_load_lds_dwordx4 v[22:23], off
	v_lshl_add_u64 v[22:23], v[4:5], 0, s[22:23]
	s_mov_b32 m0, s16
	s_nop 0
	global_load_lds_dwordx4 v[22:23], off
	s_mov_b64 s[22:23], 0x60c0
	v_lshl_add_u64 v[22:23], v[4:5], 0, s[22:23]
	s_mov_b32 m0, s17
	s_nop 0
	global_load_lds_dwordx4 v[22:23], off
	v_lshl_add_u64 v[22:23], v[6:7], 0, s[20:21]
	s_mov_b32 m0, s13
	s_nop 0
	global_load_lds_dwordx4 v[148:149], off
	s_mov_b64 s[20:21], 0x100
	s_mov_b32 m0, s18
	s_nop 0
	global_load_lds_dwordx4 v[22:23], off
	ds_read_b128 v[22:25], v9 offset:24576
	ds_read_b128 v[108:111], v9 offset:25600
	ds_read_b128 v[148:151], v9 offset:26624
	ds_read_b128 v[152:155], v9 offset:27648
	ds_read_b128 v[156:159], v8 offset:40960
	ds_read_b128 v[160:163], v8 offset:41984
	ds_read_b128 v[164:167], v8 offset:43008
	ds_read_b128 v[168:171], v8 offset:44032
	s_waitcnt lgkmcnt(3)
	v_mfma_f32_16x16x32_bf16 v[42:45], v[156:159], v[22:25], v[42:45]
	v_lshl_add_u64 v[86:87], v[4:5], 0, s[20:21]
	v_lshl_add_u64 v[172:173], v[6:7], 0, s[20:21]
	s_mov_b64 s[20:21], 0x2100
	v_mfma_f32_16x16x32_bf16 v[46:49], v[156:159], v[108:111], v[46:49]
	s_mov_b64 s[22:23], 0x4100
	v_mfma_f32_16x16x32_bf16 v[50:53], v[156:159], v[148:151], v[50:53]
	v_mfma_f32_16x16x32_bf16 v[26:29], v[156:159], v[152:155], v[26:29]
	s_waitcnt lgkmcnt(2)
	v_mfma_f32_16x16x32_bf16 v[54:57], v[160:163], v[22:25], v[54:57]
	v_mfma_f32_16x16x32_bf16 v[58:61], v[160:163], v[108:111], v[58:61]
	v_mfma_f32_16x16x32_bf16 v[62:65], v[160:163], v[148:151], v[62:65]
	v_mfma_f32_16x16x32_bf16 v[30:33], v[160:163], v[152:155], v[30:33]
	s_waitcnt lgkmcnt(1)
	v_mfma_f32_16x16x32_bf16 v[66:69], v[164:167], v[22:25], v[66:69]
	v_mfma_f32_16x16x32_bf16 v[70:73], v[164:167], v[108:111], v[70:73]
	v_mfma_f32_16x16x32_bf16 v[74:77], v[164:167], v[148:151], v[74:77]
	v_mfma_f32_16x16x32_bf16 v[34:37], v[164:167], v[152:155], v[34:37]
	s_waitcnt lgkmcnt(0)
	v_mfma_f32_16x16x32_bf16 v[78:81], v[168:171], v[22:25], v[78:81]
	v_mfma_f32_16x16x32_bf16 v[82:85], v[168:171], v[108:111], v[82:85]
	v_mfma_f32_16x16x32_bf16 v[92:95], v[168:171], v[148:151], v[92:95]
	v_mfma_f32_16x16x32_bf16 v[38:41], v[168:171], v[152:155], v[38:41]
	ds_read_b128 v[156:159], v8 offset:45056
	ds_read_b128 v[160:163], v8 offset:46080
	ds_read_b128 v[164:167], v8 offset:47104
	ds_read_b128 v[168:171], v8 offset:48128
	s_waitcnt vmcnt(6)
	s_waitcnt lgkmcnt(0)
	s_barrier
; template <int N> DI void wait_vm() { asm volatile("s_waitcnt vmcnt(%0)" ::"n"(N) : "memory"); }
; template <int BM, class Epi>
; DI void gemm_dma(const u16* __restrict__ X, long ldx, const u16* __restrict__ W, long ldw, int K, char* smem,
;                  int m0, int n0, const Epi& epi) {
;     ...
;   do {
;     if (kt + D - 2 < nk) wait_vm<PW * (D - 2)>(); else wait_vm<0>();
;     __syncthreads();
;     if (kt + D - 1 < nk) GD_ISSUE(nxt)
;     nxt = (nxt + 1 == D) ? 0 : nxt + 1;
;     const char* base = smem + cur * STG;
;     cur = (cur + 1 == D) ? 0 : cur + 1;
;     bf16x8 xf[MT];
; #pragma unroll
;     for (int i = 0; i < MT; ++i) xf[i] = *(const bf16x8*)(base + (xrow0 + i * 16) * 64 + rd);
; #pragma unroll
;     for (int nh = 0; nh < NT / 4; ++nh) {
;       bf16x8 wf[4];
; #pragma unroll
;       for (int i = 0; i < 4; ++i) wf[i] = *(const bf16x8*)(base + BM * 64 + (wrow0 + (nh * 4 + i) * 16) * 64 + rd);
; #pragma unroll
;       for (int i = 0; i < 4; ++i)
; #pragma unroll
;         for (int mt = 0; mt < MT; ++mt)
;           acc[nh * 4 + i][mt] = __builtin_amdgcn_mfma_f32_16x16x32_bf16(wf[i], xf[mt], acc[nh * 4 + i][mt], 0, 0, 0);
;     }
	s_mov_b32 m0, s7
	s_nop 0
	global_load_lds_dwordx4 v[86:87], off
	v_mfma_f32_16x16x32_bf16 v[112:115], v[156:159], v[22:25], v[112:115]
	v_mfma_f32_16x16x32_bf16 v[124:127], v[160:163], v[22:25], v[124:127]
	v_mfma_f32_16x16x32_bf16 v[136:139], v[164:167], v[22:25], v[136:139]
	v_mfma_f32_16x16x32_bf16 v[10:13], v[168:171], v[22:25], v[10:13]
	v_lshl_add_u64 v[22:23], v[4:5], 0, s[20:21]
	s_mov_b32 m0, s8
	s_nop 0
	global_load_lds_dwordx4 v[22:23], off
	v_lshl_add_u64 v[22:23], v[4:5], 0, s[22:23]
	s_mov_b32 m0, s9
	s_nop 0
	global_load_lds_dwordx4 v[22:23], off
	s_mov_b64 s[22:23], 0x6100
	v_lshl_add_u64 v[22:23], v[4:5], 0, s[22:23]
	s_mov_b32 m0, s10
	s_nop 0
	global_load_lds_dwordx4 v[22:23], off
	v_lshl_add_u64 v[22:23], v[6:7], 0, s[20:21]
	s_mov_b32 m0, s11
	s_nop 0
	global_load_lds_dwordx4 v[172:173], off
	v_mfma_f32_16x16x32_bf16 v[116:119], v[156:159], v[108:111], v[116:119]
	s_mov_b32 m0, s12
	s_nop 0
	global_load_lds_dwordx4 v[22:23], off
	s_mov_b64 s[20:21], 0x140
	v_lshl_add_u64 v[86:87], v[4:5], 0, s[20:21]
	v_mfma_f32_16x16x32_bf16 v[120:123], v[156:159], v[148:151], v[120:123]
	v_lshl_add_u64 v[172:173], v[6:7], 0, s[20:21]
	s_mov_b64 s[20:21], 0x2140
	s_mov_b64 s[22:23], 0x4140
	v_mfma_f32_16x16x32_bf16 v[96:99], v[156:159], v[152:155], v[96:99]
	v_mfma_f32_16x16x32_bf16 v[128:131], v[160:163], v[108:111], v[128:131]
	v_mfma_f32_16x16x32_bf16 v[132:135], v[160:163], v[148:151], v[132:135]
	v_mfma_f32_16x16x32_bf16 v[100:103], v[160:163], v[152:155], v[100:103]
	v_mfma_f32_16x16x32_bf16 v[140:143], v[164:167], v[108:111], v[140:143]
	v_mfma_f32_16x16x32_bf16 v[144:147], v[164:167], v[148:151], v[144:147]
	v_mfma_f32_16x16x32_bf16 v[104:107], v[164:167], v[152:155], v[104:107]
	v_mfma_f32_16x16x32_bf16 v[14:17], v[168:171], v[108:111], v[14:17]
	v_mfma_f32_16x16x32_bf16 v[18:21], v[168:171], v[148:151], v[18:21]
	v_mfma_f32_16x16x32_bf16 v[0:3], v[168:171], v[152:155], v[0:3]
	ds_read_b128 v[22:25], v9 offset:49152
	ds_read_b128 v[108:111], v9 offset:50176
	ds_read_b128 v[148:151], v9 offset:51200
	ds_read_b128 v[152:155], v9 offset:52224
	ds_read_b128 v[156:159], v91
	ds_read_b128 v[160:163], v174
	ds_read_b128 v[164:167], v175
	ds_read_b128 v[168:171], v176
	s_waitcnt lgkmcnt(3)
	v_mfma_f32_16x16x32_bf16 v[42:45], v[156:159], v[22:25], v[42:45]
	v_mfma_f32_16x16x32_bf16 v[46:49], v[156:159], v[108:111], v[46:49]
	v_mfma_f32_16x16x32_bf16 v[50:53], v[156:159], v[148:151], v[50:53]
	v_mfma_f32_16x16x32_bf16 v[26:29], v[156:159], v[152:155], v[26:29]
	ds_read_b128 v[156:159], v177
	s_waitcnt lgkmcnt(3)
	v_mfma_f32_16x16x32_bf16 v[54:57], v[160:163], v[22:25], v[54:57]
	v_mfma_f32_16x16x32_bf16 v[58:61], v[160:163], v[108:111], v[58:61]
	v_mfma_f32_16x16x32_bf16 v[62:65], v[160:163], v[148:151], v[62:65]
	v_mfma_f32_16x16x32_bf16 v[30:33], v[160:163], v[152:155], v[30:33]
	ds_read_b128 v[160:163], v178
	s_waitcnt lgkmcnt(3)
	v_mfma_f32_16x16x32_bf16 v[66:69], v[164:167], v[22:25], v[66:69]
	v_mfma_f32_16x16x32_bf16 v[70:73], v[164:167], v[108:111], v[70:73]
	v_mfma_f32_16x16x32_bf16 v[74:77], v[164:167], v[148:151], v[74:77]
	v_mfma_f32_16x16x32_bf16 v[34:37], v[164:167], v[152:155], v[34:37]
	ds_read_b128 v[164:167], v179
	s_waitcnt lgkmcnt(3)
	v_mfma_f32_16x16x32_bf16 v[78:81], v[168:171], v[22:25], v[78:81]
	v_mfma_f32_16x16x32_bf16 v[82:85], v[168:171], v[108:111], v[82:85]
	v_mfma_f32_16x16x32_bf16 v[92:95], v[168:171], v[148:151], v[92:95]
	v_mfma_f32_16x16x32_bf16 v[38:41], v[168:171], v[152:155], v[38:41]
	ds_read_b128 v[168:171], v180
	s_waitcnt vmcnt(6)
	s_waitcnt lgkmcnt(0)
	s_barrier
	s_mov_b32 m0, s19
	s_nop 0
	global_load_lds_dwordx4 v[86:87], off
	v_mfma_f32_16x16x32_bf16 v[112:115], v[156:159], v[22:25], v[112:115]
	v_mfma_f32_16x16x32_bf16 v[124:127], v[160:163], v[22:25], v[124:127]
	v_mfma_f32_16x16x32_bf16 v[136:139], v[164:167], v[22:25], v[136:139]
	v_mfma_f32_16x16x32_bf16 v[10:13], v[168:171], v[22:25], v[10:13]
	v_lshl_add_u64 v[22:23], v[4:5], 0, s[20:21]
	s_mov_b32 m0, s34
	s_nop 0
	global_load_lds_dwordx4 v[22:23], off
	v_lshl_add_u64 v[22:23], v[4:5], 0, s[22:23]
	s_mov_b32 m0, s38
	s_nop 0
	global_load_lds_dwordx4 v[22:23], off
	s_mov_b64 s[22:23], 0x6140
	v_lshl_add_u64 v[22:23], v[4:5], 0, s[22:23]
	s_mov_b32 m0, s39
	s_nop 0
	global_load_lds_dwordx4 v[22:23], off
	v_lshl_add_u64 v[22:23], v[6:7], 0, s[20:21]
	s_mov_b32 m0, s40
	s_nop 0
	global_load_lds_dwordx4 v[172:173], off
	v_mfma_f32_16x16x32_bf16 v[116:119], v[156:159], v[108:111], v[116:119]
	s_mov_b32 m0, s41
	s_nop 0
	global_load_lds_dwordx4 v[22:23], off
	s_mov_b64 s[20:21], 0x180
	v_lshl_add_u64 v[86:87], v[4:5], 0, s[20:21]
	v_mfma_f32_16x16x32_bf16 v[120:123], v[156:159], v[148:151], v[120:123]
	v_lshl_add_u64 v[172:173], v[6:7], 0, s[20:21]
	s_mov_b64 s[20:21], 0x2180
	s_mov_b64 s[38:39], 0
	v_mfma_f32_16x16x32_bf16 v[96:99], v[156:159], v[152:155], v[96:99]
	v_mfma_f32_16x16x32_bf16 v[128:131], v[160:163], v[108:111], v[128:131]
	v_mfma_f32_16x16x32_bf16 v[132:135], v[160:163], v[148:151], v[132:135]
	v_mfma_f32_16x16x32_bf16 v[100:103], v[160:163], v[152:155], v[100:103]
	v_mfma_f32_16x16x32_bf16 v[140:143], v[164:167], v[108:111], v[140:143]
	v_mfma_f32_16x16x32_bf16 v[144:147], v[164:167], v[148:151], v[144:147]
	v_mfma_f32_16x16x32_bf16 v[104:107], v[164:167], v[152:155], v[104:107]
	v_mfma_f32_16x16x32_bf16 v[14:17], v[168:171], v[108:111], v[14:17]
	v_mfma_f32_16x16x32_bf16 v[18:21], v[168:171], v[148:151], v[18:21]
	v_mfma_f32_16x16x32_bf16 v[0:3], v[168:171], v[152:155], v[0:3]
	ds_read_b128 v[22:25], v9
	ds_read_b128 v[108:111], v9 offset:1024
	ds_read_b128 v[148:151], v9 offset:2048
	ds_read_b128 v[152:155], v9 offset:3072
	ds_read_b128 v[156:159], v8 offset:16384
	ds_read_b128 v[160:163], v8 offset:17408
	ds_read_b128 v[164:167], v8 offset:18432
	ds_read_b128 v[168:171], v8 offset:19456
	s_waitcnt lgkmcnt(3)
; template <int N> DI void wait_vm() { asm volatile("s_waitcnt vmcnt(%0)" ::"n"(N) : "memory"); }
; template <int BM, class Epi>
; DI void gemm_dma(const u16* __restrict__ X, long ldx, const u16* __restrict__ W, long ldw, int K, char* smem,
;                  int m0, int n0, const Epi& epi) {
;     ...
;   do {
;     if (kt + D - 2 < nk) wait_vm<PW * (D - 2)>(); else wait_vm<0>();
;     __syncthreads();
;     if (kt + D - 1 < nk) GD_ISSUE(nxt)
;     nxt = (nxt + 1 == D) ? 0 : nxt + 1;
;     const char* base = smem + cur * STG;
;     cur = (cur + 1 == D) ? 0 : cur + 1;
;     bf16x8 xf[MT];
; #pragma unroll
;     for (int i = 0; i < MT; ++i) xf[i] = *(const bf16x8*)(base + (xrow0 + i * 16) * 64 + rd);
; #pragma unroll
;     for (int nh = 0; nh < NT / 4; ++nh) {
;       bf16x8 wf[4];
; #pragma unroll
;       for (int i = 0; i < 4; ++i) wf[i] = *(const bf16x8*)(base + BM * 64 + (wrow0 + (nh * 4 + i) * 16) * 64 + rd);
; #pragma unroll
;       for (int i = 0; i < 4; ++i)
; #pragma unroll
;         for (int mt = 0; mt < MT; ++mt)
;           acc[nh * 4 + i][mt] = __builtin_amdgcn_mfma_f32_16x16x32_bf16(wf[i], xf[mt], acc[nh * 4 + i][mt], 0, 0, 0);
;     }
	v_mfma_f32_16x16x32_bf16 v[42:45], v[156:159], v[22:25], v[42:45]
	v_mfma_f32_16x16x32_bf16 v[46:49], v[156:159], v[108:111], v[46:49]
	v_mfma_f32_16x16x32_bf16 v[50:53], v[156:159], v[148:151], v[50:53]
	v_mfma_f32_16x16x32_bf16 v[26:29], v[156:159], v[152:155], v[26:29]
	s_waitcnt lgkmcnt(2)
	v_mfma_f32_16x16x32_bf16 v[54:57], v[160:163], v[22:25], v[54:57]
	v_mfma_f32_16x16x32_bf16 v[58:61], v[160:163], v[108:111], v[58:61]
	v_mfma_f32_16x16x32_bf16 v[62:65], v[160:163], v[148:151], v[62:65]
	v_mfma_f32_16x16x32_bf16 v[30:33], v[160:163], v[152:155], v[30:33]
	s_waitcnt lgkmcnt(1)
	v_mfma_f32_16x16x32_bf16 v[66:69], v[164:167], v[22:25], v[66:69]
	v_mfma_f32_16x16x32_bf16 v[70:73], v[164:167], v[108:111], v[70:73]
	v_mfma_f32_16x16x32_bf16 v[74:77], v[164:167], v[148:151], v[74:77]
	v_mfma_f32_16x16x32_bf16 v[34:37], v[164:167], v[152:155], v[34:37]
	s_waitcnt lgkmcnt(0)
	v_mfma_f32_16x16x32_bf16 v[78:81], v[168:171], v[22:25], v[78:81]
	v_mfma_f32_16x16x32_bf16 v[82:85], v[168:171], v[108:111], v[82:85]
	v_mfma_f32_16x16x32_bf16 v[92:95], v[168:171], v[148:151], v[92:95]
	v_mfma_f32_16x16x32_bf16 v[38:41], v[168:171], v[152:155], v[38:41]
	ds_read_b128 v[156:159], v8 offset:20480
	ds_read_b128 v[160:163], v8 offset:21504
	ds_read_b128 v[164:167], v8 offset:22528
	ds_read_b128 v[168:171], v8 offset:23552
	s_waitcnt vmcnt(6)
	s_waitcnt lgkmcnt(0)
	s_barrier
	s_mov_b32 m0, s14
	s_nop 0
	global_load_lds_dwordx4 v[86:87], off
	v_mfma_f32_16x16x32_bf16 v[112:115], v[156:159], v[22:25], v[112:115]
	v_mfma_f32_16x16x32_bf16 v[124:127], v[160:163], v[22:25], v[124:127]
	v_mfma_f32_16x16x32_bf16 v[136:139], v[164:167], v[22:25], v[136:139]
	v_mfma_f32_16x16x32_bf16 v[10:13], v[168:171], v[22:25], v[10:13]
	v_lshl_add_u64 v[22:23], v[4:5], 0, s[20:21]
	s_mov_b32 m0, s15
	s_nop 0
	global_load_lds_dwordx4 v[22:23], off
	s_mov_b64 s[14:15], 0x4180
	v_lshl_add_u64 v[22:23], v[4:5], 0, s[14:15]
	s_mov_b32 m0, s16
	s_nop 0
	global_load_lds_dwordx4 v[22:23], off
	s_mov_b64 s[14:15], 0x6180
	v_lshl_add_u64 v[22:23], v[4:5], 0, s[14:15]
	s_mov_b32 m0, s17
	s_nop 0
	global_load_lds_dwordx4 v[22:23], off
	v_lshl_add_u64 v[22:23], v[6:7], 0, s[20:21]
	s_mov_b32 m0, s13
	s_nop 0
	global_load_lds_dwordx4 v[172:173], off
	s_mov_b32 m0, s18
	s_nop 0
	global_load_lds_dwordx4 v[22:23], off
	v_mfma_f32_16x16x32_bf16 v[116:119], v[156:159], v[108:111], v[116:119]
	s_mov_b64 s[14:15], 0x1c0
	v_lshl_add_u64 v[86:87], v[4:5], 0, s[14:15]
	v_lshl_add_u64 v[172:173], v[6:7], 0, s[14:15]
	v_mfma_f32_16x16x32_bf16 v[120:123], v[156:159], v[148:151], v[120:123]
	s_mov_b64 s[14:15], 0x21c0
	s_mov_b64 s[16:17], 0x41c0
	v_mfma_f32_16x16x32_bf16 v[96:99], v[156:159], v[152:155], v[96:99]
	v_mfma_f32_16x16x32_bf16 v[128:131], v[160:163], v[108:111], v[128:131]
	v_mfma_f32_16x16x32_bf16 v[132:135], v[160:163], v[148:151], v[132:135]
	v_mfma_f32_16x16x32_bf16 v[100:103], v[160:163], v[152:155], v[100:103]
	v_mfma_f32_16x16x32_bf16 v[140:143], v[164:167], v[108:111], v[140:143]
	v_mfma_f32_16x16x32_bf16 v[144:147], v[164:167], v[148:151], v[144:147]
	v_mfma_f32_16x16x32_bf16 v[104:107], v[164:167], v[152:155], v[104:107]
	v_mfma_f32_16x16x32_bf16 v[14:17], v[168:171], v[108:111], v[14:17]
	v_mfma_f32_16x16x32_bf16 v[18:21], v[168:171], v[148:151], v[18:21]
	v_mfma_f32_16x16x32_bf16 v[0:3], v[168:171], v[152:155], v[0:3]
	ds_read_b128 v[22:25], v9 offset:24576
	ds_read_b128 v[108:111], v9 offset:25600
	ds_read_b128 v[148:151], v9 offset:26624
	ds_read_b128 v[152:155], v9 offset:27648
	ds_read_b128 v[156:159], v8 offset:40960
	ds_read_b128 v[160:163], v8 offset:41984
	ds_read_b128 v[164:167], v8 offset:43008
	ds_read_b128 v[168:171], v8 offset:44032
	s_waitcnt lgkmcnt(3)
	v_mfma_f32_16x16x32_bf16 v[42:45], v[156:159], v[22:25], v[42:45]
	v_mfma_f32_16x16x32_bf16 v[46:49], v[156:159], v[108:111], v[46:49]
	v_mfma_f32_16x16x32_bf16 v[50:53], v[156:159], v[148:151], v[50:53]
	v_mfma_f32_16x16x32_bf16 v[26:29], v[156:159], v[152:155], v[26:29]
	s_waitcnt lgkmcnt(2)
	v_mfma_f32_16x16x32_bf16 v[54:57], v[160:163], v[22:25], v[54:57]
	v_mfma_f32_16x16x32_bf16 v[58:61], v[160:163], v[108:111], v[58:61]
	v_mfma_f32_16x16x32_bf16 v[62:65], v[160:163], v[148:151], v[62:65]
	v_mfma_f32_16x16x32_bf16 v[30:33], v[160:163], v[152:155], v[30:33]
	s_waitcnt lgkmcnt(1)
	v_mfma_f32_16x16x32_bf16 v[66:69], v[164:167], v[22:25], v[66:69]
	v_mfma_f32_16x16x32_bf16 v[70:73], v[164:167], v[108:111], v[70:73]
	v_mfma_f32_16x16x32_bf16 v[74:77], v[164:167], v[148:151], v[74:77]
	v_mfma_f32_16x16x32_bf16 v[34:37], v[164:167], v[152:155], v[34:37]
	s_waitcnt lgkmcnt(0)
	v_mfma_f32_16x16x32_bf16 v[78:81], v[168:171], v[22:25], v[78:81]
	v_mfma_f32_16x16x32_bf16 v[82:85], v[168:171], v[108:111], v[82:85]
	v_mfma_f32_16x16x32_bf16 v[92:95], v[168:171], v[148:151], v[92:95]
	v_mfma_f32_16x16x32_bf16 v[38:41], v[168:171], v[152:155], v[38:41]
	ds_read_b128 v[156:159], v8 offset:45056
	ds_read_b128 v[160:163], v8 offset:46080
	ds_read_b128 v[164:167], v8 offset:47104
	ds_read_b128 v[168:171], v8 offset:48128
	s_waitcnt vmcnt(6)
	s_waitcnt lgkmcnt(0)
	s_barrier
; template <int N> DI void wait_vm() { asm volatile("s_waitcnt vmcnt(%0)" ::"n"(N) : "memory"); }
; template <int BM, class Epi>
; DI void gemm_dma(const u16* __restrict__ X, long ldx, const u16* __restrict__ W, long ldw, int K, char* smem,
;                  int m0, int n0, const Epi& epi) {
;     ...
;   do {
;     if (kt + D - 2 < nk) wait_vm<PW * (D - 2)>(); else wait_vm<0>();
;     __syncthreads();
;     if (kt + D - 1 < nk) GD_ISSUE(nxt)
;     nxt = (nxt + 1 == D) ? 0 : nxt + 1;
;     const char* base = smem + cur * STG;
;     cur = (cur + 1 == D) ? 0 : cur + 1;
;     bf16x8 xf[MT];
; #pragma unroll
;     for (int i = 0; i < MT; ++i) xf[i] = *(const bf16x8*)(base + (xrow0 + i * 16) * 64 + rd);
; #pragma unroll
;     for (int nh = 0; nh < NT / 4; ++nh) {
;       bf16x8 wf[4];
; #pragma unroll
;       for (int i = 0; i < 4; ++i) wf[i] = *(const bf16x8*)(base + BM * 64 + (wrow0 + (nh * 4 + i) * 16) * 64 + rd);
; #pragma unroll
;       for (int i = 0; i < 4; ++i)
; #pragma unroll
;         for (int mt = 0; mt < MT; ++mt)
;           acc[nh * 4 + i][mt] = __builtin_amdgcn_mfma_f32_16x16x32_bf16(wf[i], xf[mt], acc[nh * 4 + i][mt], 0, 0, 0);
;     }
	s_mov_b32 m0, s7
	s_nop 0
	global_load_lds_dwordx4 v[86:87], off
	v_mfma_f32_16x16x32_bf16 v[112:115], v[156:159], v[22:25], v[112:115]
	v_mfma_f32_16x16x32_bf16 v[124:127], v[160:163], v[22:25], v[124:127]
	v_mfma_f32_16x16x32_bf16 v[136:139], v[164:167], v[22:25], v[136:139]
	v_mfma_f32_16x16x32_bf16 v[10:13], v[168:171], v[22:25], v[10:13]
	v_lshl_add_u64 v[22:23], v[4:5], 0, s[14:15]
	s_mov_b32 m0, s8
	s_nop 0
	global_load_lds_dwordx4 v[22:23], off
	v_lshl_add_u64 v[22:23], v[4:5], 0, s[16:17]
	s_mov_b32 m0, s9
	s_nop 0
	global_load_lds_dwordx4 v[22:23], off
	s_mov_b64 s[8:9], 0x61c0
	v_lshl_add_u64 v[4:5], v[4:5], 0, s[8:9]
	s_mov_b32 m0, s10
	s_nop 0
	global_load_lds_dwordx4 v[4:5], off
	v_lshl_add_u64 v[4:5], v[6:7], 0, s[14:15]
	s_mov_b32 m0, s11
	s_nop 0
	global_load_lds_dwordx4 v[172:173], off
	v_mfma_f32_16x16x32_bf16 v[116:119], v[156:159], v[108:111], v[116:119]
	s_mov_b32 m0, s12
	s_nop 0
	global_load_lds_dwordx4 v[4:5], off
	v_mfma_f32_16x16x32_bf16 v[120:123], v[156:159], v[148:151], v[120:123]
	v_mfma_f32_16x16x32_bf16 v[96:99], v[156:159], v[152:155], v[96:99]
	v_mfma_f32_16x16x32_bf16 v[128:131], v[160:163], v[108:111], v[128:131]
	v_mfma_f32_16x16x32_bf16 v[132:135], v[160:163], v[148:151], v[132:135]
	v_mfma_f32_16x16x32_bf16 v[100:103], v[160:163], v[152:155], v[100:103]
	v_mfma_f32_16x16x32_bf16 v[140:143], v[164:167], v[108:111], v[140:143]
	v_mfma_f32_16x16x32_bf16 v[144:147], v[164:167], v[148:151], v[144:147]
	v_mfma_f32_16x16x32_bf16 v[104:107], v[164:167], v[152:155], v[104:107]
	v_mfma_f32_16x16x32_bf16 v[14:17], v[168:171], v[108:111], v[14:17]
	v_mfma_f32_16x16x32_bf16 v[18:21], v[168:171], v[148:151], v[18:21]
	v_mfma_f32_16x16x32_bf16 v[0:3], v[168:171], v[152:155], v[0:3]
	ds_read_b128 v[4:7], v9 offset:49152
	ds_read_b128 v[22:25], v9 offset:50176
	ds_read_b128 v[108:111], v9 offset:51200
	ds_read_b128 v[148:151], v9 offset:52224
	ds_read_b128 v[152:155], v91
	ds_read_b128 v[156:159], v174
	ds_read_b128 v[160:163], v175
	ds_read_b128 v[164:167], v176
	s_waitcnt lgkmcnt(3)
	v_mfma_f32_16x16x32_bf16 v[42:45], v[152:155], v[4:7], v[42:45]
	v_mfma_f32_16x16x32_bf16 v[46:49], v[152:155], v[22:25], v[46:49]
	v_mfma_f32_16x16x32_bf16 v[50:53], v[152:155], v[108:111], v[50:53]
	v_mfma_f32_16x16x32_bf16 v[26:29], v[152:155], v[148:151], v[26:29]
	s_waitcnt lgkmcnt(2)
	v_mfma_f32_16x16x32_bf16 v[54:57], v[156:159], v[4:7], v[54:57]
	v_mfma_f32_16x16x32_bf16 v[58:61], v[156:159], v[22:25], v[58:61]
	v_mfma_f32_16x16x32_bf16 v[62:65], v[156:159], v[108:111], v[62:65]
	v_mfma_f32_16x16x32_bf16 v[30:33], v[156:159], v[148:151], v[30:33]
	s_waitcnt lgkmcnt(1)
	v_mfma_f32_16x16x32_bf16 v[66:69], v[160:163], v[4:7], v[66:69]
	v_mfma_f32_16x16x32_bf16 v[70:73], v[160:163], v[22:25], v[70:73]
	v_mfma_f32_16x16x32_bf16 v[74:77], v[160:163], v[108:111], v[74:77]
	v_mfma_f32_16x16x32_bf16 v[34:37], v[160:163], v[148:151], v[34:37]
	s_waitcnt lgkmcnt(0)
	v_mfma_f32_16x16x32_bf16 v[78:81], v[164:167], v[4:7], v[78:81]
	v_mfma_f32_16x16x32_bf16 v[82:85], v[164:167], v[22:25], v[82:85]
	v_mfma_f32_16x16x32_bf16 v[92:95], v[164:167], v[108:111], v[92:95]
	v_mfma_f32_16x16x32_bf16 v[38:41], v[164:167], v[148:151], v[38:41]
	ds_read_b128 v[152:155], v177
	ds_read_b128 v[156:159], v178
	ds_read_b128 v[160:163], v179
	ds_read_b128 v[164:167], v180
	s_waitcnt vmcnt(6)
	s_waitcnt lgkmcnt(0)
	v_mfma_f32_16x16x32_bf16 v[112:115], v[152:155], v[4:7], v[112:115]
	s_barrier
	v_mfma_f32_16x16x32_bf16 v[116:119], v[152:155], v[22:25], v[116:119]
	v_mfma_f32_16x16x32_bf16 v[120:123], v[152:155], v[108:111], v[120:123]
	v_mfma_f32_16x16x32_bf16 v[96:99], v[152:155], v[148:151], v[96:99]
	v_mfma_f32_16x16x32_bf16 v[124:127], v[156:159], v[4:7], v[124:127]
	v_mfma_f32_16x16x32_bf16 v[128:131], v[156:159], v[22:25], v[128:131]
	v_mfma_f32_16x16x32_bf16 v[132:135], v[156:159], v[108:111], v[132:135]
	v_mfma_f32_16x16x32_bf16 v[100:103], v[156:159], v[148:151], v[100:103]
	v_mfma_f32_16x16x32_bf16 v[136:139], v[160:163], v[4:7], v[136:139]
	v_mfma_f32_16x16x32_bf16 v[140:143], v[160:163], v[22:25], v[140:143]
	v_mfma_f32_16x16x32_bf16 v[144:147], v[160:163], v[108:111], v[144:147]
	v_mfma_f32_16x16x32_bf16 v[104:107], v[160:163], v[148:151], v[104:107]
	v_mfma_f32_16x16x32_bf16 v[4:7], v[164:167], v[4:7], v[10:13]
	v_mfma_f32_16x16x32_bf16 v[10:13], v[164:167], v[22:25], v[14:17]
	v_mfma_f32_16x16x32_bf16 v[14:17], v[164:167], v[108:111], v[18:21]
	v_mfma_f32_16x16x32_bf16 v[0:3], v[164:167], v[148:151], v[0:3]
	s_nop 1
	ds_read_b128 v[18:21], v8 offset:23552
	ds_read_b128 v[22:25], v8 offset:22528
	ds_read_b128 v[108:111], v8 offset:21504
	ds_read_b128 v[148:151], v8 offset:20480
	ds_read_b128 v[152:155], v8 offset:19456
	ds_read_b128 v[156:159], v8 offset:18432
	ds_read_b128 v[160:163], v8 offset:17408
	ds_read_b128 v[164:167], v8 offset:16384
	ds_read_b128 v[168:171], v9 offset:3072
	ds_read_b128 v[172:175], v9 offset:2048
	ds_read_b128 v[176:179], v9 offset:1024
	ds_read_b128 v[186:189], v9
	s_waitcnt vmcnt(0)
	s_waitcnt lgkmcnt(0)
	v_mfma_f32_16x16x32_bf16 v[42:45], v[164:167], v[186:189], v[42:45]
	s_barrier
; template <int N> DI void wait_vm() { asm volatile("s_waitcnt vmcnt(%0)" ::"n"(N) : "memory"); }
; DI void st_bf4(u16* p, float a, float b, float c, float d) { *(uint2*)p = make_uint2(pk2(a, b), pk2(c, d)); }
; template <int BM, class Epi>
; DI void gemm_dma(const u16* __restrict__ X, long ldx, const u16* __restrict__ W, long ldw, int K, char* smem,
;                  int m0, int n0, const Epi& epi) {
;     ...
;   do {
;     if (kt + D - 2 < nk) wait_vm<PW * (D - 2)>(); else wait_vm<0>();
;     __syncthreads();
;     if (kt + D - 1 < nk) GD_ISSUE(nxt)
;     nxt = (nxt + 1 == D) ? 0 : nxt + 1;
;     const char* base = smem + cur * STG;
;     cur = (cur + 1 == D) ? 0 : cur + 1;
;     bf16x8 xf[MT];
; #pragma unroll
;     for (int i = 0; i < MT; ++i) xf[i] = *(const bf16x8*)(base + (xrow0 + i * 16) * 64 + rd);
; #pragma unroll
;     for (int nh = 0; nh < NT / 4; ++nh) {
;       bf16x8 wf[4];
; #pragma unroll
;       for (int i = 0; i < 4; ++i) wf[i] = *(const bf16x8*)(base + BM * 64 + (wrow0 + (nh * 4 + i) * 16) * 64 + rd);
; #pragma unroll
;       for (int i = 0; i < 4; ++i)
; #pragma unroll
;         for (int mt = 0; mt < MT; ++mt)
;           acc[nh * 4 + i][mt] = __builtin_amdgcn_mfma_f32_16x16x32_bf16(wf[i], xf[mt], acc[nh * 4 + i][mt], 0, 0, 0);
;     }
;   } while (++kt < nk);
;     ...
;   epi.run(acc, m0 + xrow0 + lr, n0 + wrow0 + 4 * g);
;   template <int NT, int MT> DI void run(f32x4 (&acc)[NT][MT], int mb, int nb) const {
; #pragma unroll
;     for (int nt = 0; nt < NT; ++nt)
; #pragma unroll
;       for (int mt = 0; mt < MT; ++mt) {
;         f32x4 v = acc[nt][mt];
;         st_bf4(C + (size_t)(mb + mt * 16) * ldc + nb + nt * 16, v[0], v[1], v[2], v[3]);
;       }
;   }
	v_mfma_f32_16x16x32_bf16 v[46:49], v[164:167], v[176:179], v[46:49]
	v_mfma_f32_16x16x32_bf16 v[50:53], v[164:167], v[172:175], v[50:53]
	v_mfma_f32_16x16x32_bf16 v[26:29], v[164:167], v[168:171], v[26:29]
	v_mfma_f32_16x16x32_bf16 v[54:57], v[160:163], v[186:189], v[54:57]
	v_mfma_f32_16x16x32_bf16 v[58:61], v[160:163], v[176:179], v[58:61]
	v_mfma_f32_16x16x32_bf16 v[62:65], v[160:163], v[172:175], v[62:65]
	v_mfma_f32_16x16x32_bf16 v[30:33], v[160:163], v[168:171], v[30:33]
	v_mfma_f32_16x16x32_bf16 v[66:69], v[156:159], v[186:189], v[66:69]
	v_mfma_f32_16x16x32_bf16 v[70:73], v[156:159], v[176:179], v[70:73]
	v_mfma_f32_16x16x32_bf16 v[74:77], v[156:159], v[172:175], v[74:77]
	v_mfma_f32_16x16x32_bf16 v[34:37], v[156:159], v[168:171], v[34:37]
	v_mfma_f32_16x16x32_bf16 v[156:159], v[152:155], v[186:189], v[78:81]
	v_mfma_f32_16x16x32_bf16 v[84:87], v[152:155], v[176:179], v[82:85]
	v_mfma_f32_16x16x32_bf16 v[92:95], v[152:155], v[172:175], v[92:95]
	v_mfma_f32_16x16x32_bf16 v[152:155], v[152:155], v[168:171], v[38:41]
	v_mfma_f32_16x16x32_bf16 v[112:115], v[148:151], v[186:189], v[112:115]
	v_mfma_f32_16x16x32_bf16 v[116:119], v[148:151], v[176:179], v[116:119]
	v_mfma_f32_16x16x32_bf16 v[120:123], v[148:151], v[172:175], v[120:123]
	v_mfma_f32_16x16x32_bf16 v[96:99], v[148:151], v[168:171], v[96:99]
	v_mfma_f32_16x16x32_bf16 v[124:127], v[108:111], v[186:189], v[124:127]
	v_mfma_f32_16x16x32_bf16 v[128:131], v[108:111], v[176:179], v[128:131]
	v_mfma_f32_16x16x32_bf16 v[132:135], v[108:111], v[172:175], v[132:135]
	v_mfma_f32_16x16x32_bf16 v[100:103], v[108:111], v[168:171], v[100:103]
	v_mfma_f32_16x16x32_bf16 v[108:111], v[22:25], v[186:189], v[136:139]
	v_mfma_f32_16x16x32_bf16 v[136:139], v[22:25], v[176:179], v[140:143]
	v_mfma_f32_16x16x32_bf16 v[140:143], v[22:25], v[172:175], v[144:147]
	v_mfma_f32_16x16x32_bf16 v[104:107], v[22:25], v[168:171], v[104:107]
	v_mfma_f32_16x16x32_bf16 v[4:7], v[18:21], v[186:189], v[4:7]
	v_mfma_f32_16x16x32_bf16 v[144:147], v[18:21], v[176:179], v[10:13]
	v_mfma_f32_16x16x32_bf16 v[148:151], v[18:21], v[172:175], v[14:17]
	v_mfma_f32_16x16x32_bf16 v[0:3], v[18:21], v[168:171], v[0:3]
	s_nop 0
	ds_read_b128 v[10:13], v9 offset:24576
	ds_read_b128 v[160:163], v9 offset:25600
	ds_read_b128 v[164:167], v9 offset:26624
	ds_read_b128 v[168:171], v9 offset:27648
	ds_read_b128 v[14:17], v8 offset:40960
	ds_read_b128 v[18:21], v8 offset:41984
	ds_read_b128 v[22:25], v8 offset:43008
	ds_read_b128 v[172:175], v8 offset:44032
	s_waitcnt lgkmcnt(3)
	v_mfma_f32_16x16x32_bf16 v[176:179], v[14:17], v[10:13], v[42:45]
	v_mfma_f32_16x16x32_bf16 v[186:189], v[14:17], v[160:163], v[46:49]
	v_mfma_f32_16x16x32_bf16 v[190:193], v[14:17], v[164:167], v[50:53]
	v_mfma_f32_16x16x32_bf16 v[194:197], v[14:17], v[168:171], v[26:29]
	s_waitcnt lgkmcnt(2)
	v_mfma_f32_16x16x32_bf16 v[224:227], v[18:21], v[10:13], v[54:57]
	v_mfma_f32_16x16x32_bf16 v[228:231], v[18:21], v[160:163], v[58:61]
	v_mfma_f32_16x16x32_bf16 v[232:235], v[18:21], v[164:167], v[62:65]
	v_mfma_f32_16x16x32_bf16 v[236:239], v[18:21], v[168:171], v[30:33]
	s_waitcnt lgkmcnt(1)
	v_mfma_f32_16x16x32_bf16 v[240:243], v[22:25], v[10:13], v[66:69]
	v_mfma_f32_16x16x32_bf16 v[64:67], v[22:25], v[168:171], v[34:37]
	s_waitcnt lgkmcnt(0)
	v_mfma_f32_16x16x32_bf16 v[40:43], v[172:175], v[164:167], v[92:95]
	v_mfma_f32_16x16x32_bf16 v[32:35], v[172:175], v[168:171], v[152:155]
	ds_read_b128 v[14:17], v8 offset:45056
	ds_read_b128 v[18:21], v8 offset:46080
	ds_read_b128 v[92:95], v8 offset:47104
	ds_read_b128 v[152:155], v8 offset:48128
	s_nop 0
	v_cvt_pk_bf16_f32 v64, v64, v65
	v_cvt_pk_bf16_f32 v65, v66, v67
	v_mfma_f32_16x16x32_bf16 v[80:83], v[22:25], v[160:163], v[70:73]
	v_cvt_pk_bf16_f32 v32, v32, v33
	v_cvt_pk_bf16_f32 v33, v34, v35
	v_cvt_pk_bf16_f32 v40, v40, v41
	v_mfma_f32_16x16x32_bf16 v[72:75], v[22:25], v[164:167], v[74:77]
	v_cvt_pk_bf16_f32 v41, v42, v43
	s_nop 2
	v_cvt_pk_bf16_f32 v80, v80, v81
	v_cvt_pk_bf16_f32 v81, v82, v83
	v_mfma_f32_16x16x32_bf16 v[48:51], v[172:175], v[160:163], v[84:87]
	s_waitcnt lgkmcnt(3)
	v_mfma_f32_16x16x32_bf16 v[112:115], v[14:17], v[10:13], v[112:115]
	v_cvt_pk_bf16_f32 v72, v72, v73
	v_cvt_pk_bf16_f32 v73, v74, v75
	s_nop 3
	v_cvt_pk_bf16_f32 v48, v48, v49
	v_mfma_f32_16x16x32_bf16 v[84:87], v[14:17], v[160:163], v[116:119]
	v_cvt_pk_bf16_f32 v49, v50, v51
	v_mfma_f32_16x16x32_bf16 v[76:79], v[14:17], v[164:167], v[120:123]
	v_mfma_f32_16x16x32_bf16 v[68:71], v[14:17], v[168:171], v[96:99]
	s_waitcnt lgkmcnt(2)
	v_mfma_f32_16x16x32_bf16 v[60:63], v[18:21], v[10:13], v[124:127]
	s_nop 0
	v_cvt_pk_bf16_f32 v96, v190, v191
	v_cvt_pk_bf16_f32 v97, v192, v193
	v_mfma_f32_16x16x32_bf16 v[52:55], v[18:21], v[160:163], v[128:131]
	v_mfma_f32_16x16x32_bf16 v[44:47], v[18:21], v[164:167], v[132:135]
	v_mfma_f32_16x16x32_bf16 v[36:39], v[18:21], v[168:171], v[100:103]
	s_waitcnt lgkmcnt(1)
; DI void st_bf4(u16* p, float a, float b, float c, float d) { *(uint2*)p = make_uint2(pk2(a, b), pk2(c, d)); }
;   template <int NT, int MT> DI void run(f32x4 (&acc)[NT][MT], int mb, int nb) const {
; #pragma unroll
;     for (int nt = 0; nt < NT; ++nt)
; #pragma unroll
;       for (int mt = 0; mt < MT; ++mt) {
;         f32x4 v = acc[nt][mt];
;         st_bf4(C + (size_t)(mb + mt * 16) * ldc + nb + nt * 16, v[0], v[1], v[2], v[3]);
;       }
;   }
	v_mfma_f32_16x16x32_bf16 v[28:31], v[92:95], v[10:13], v[108:111]
	v_mfma_f32_16x16x32_bf16 v[24:27], v[92:95], v[160:163], v[136:139]
	v_mfma_f32_16x16x32_bf16 v[20:23], v[92:95], v[164:167], v[140:143]
	s_nop 5
	v_cvt_pk_bf16_f32 v28, v28, v29
	v_cvt_pk_bf16_f32 v29, v30, v31
	v_cvt_pk_bf16_f32 v24, v24, v25
	v_mfma_f32_16x16x32_bf16 v[16:19], v[92:95], v[168:171], v[104:107]
	v_or_b32_e32 v92, v90, v89
	v_ashrrev_i32_e32 v93, 31, v92
	v_lshlrev_b64 v[90:91], 11, v[92:93]
	v_lshl_add_u64 v[90:91], s[92:93], 0, v[90:91]
	v_lshl_add_u64 v[88:89], v[90:91], 0, v[182:183]
	v_cvt_pk_bf16_f32 v90, v176, v177
	v_cvt_pk_bf16_f32 v91, v178, v179
	global_store_dwordx2 v[88:89], v[90:91], off
	v_or_b32_e32 v90, 16, v92
	v_ashrrev_i32_e32 v91, 31, v90
	v_lshlrev_b64 v[90:91], 11, v[90:91]
	v_lshl_add_u64 v[90:91], s[92:93], 0, v[90:91]
	v_lshl_add_u64 v[90:91], v[90:91], 0, v[182:183]
	v_cvt_pk_bf16_f32 v94, v186, v187
	v_cvt_pk_bf16_f32 v95, v188, v189
	global_store_dwordx2 v[90:91], v[94:95], off
	v_or_b32_e32 v94, 32, v92
	v_or_b32_e32 v92, 48, v92
	v_ashrrev_i32_e32 v93, 31, v92
	v_lshlrev_b64 v[92:93], 11, v[92:93]
	v_ashrrev_i32_e32 v95, 31, v94
	v_lshl_add_u64 v[92:93], s[92:93], 0, v[92:93]
	v_lshlrev_b64 v[94:95], 11, v[94:95]
	v_lshl_add_u64 v[92:93], v[92:93], 0, v[182:183]
	v_lshl_add_u64 v[94:95], s[92:93], 0, v[94:95]
	global_store_dwordx2 v[92:93], v[32:33], off offset:96
	v_cvt_pk_bf16_f32 v32, v112, v113
	v_cvt_pk_bf16_f32 v33, v114, v115
	v_lshl_add_u64 v[94:95], v[94:95], 0, v[182:183]
	global_store_dwordx2 v[88:89], v[32:33], off offset:128
	v_cvt_pk_bf16_f32 v32, v84, v85
	v_cvt_pk_bf16_f32 v33, v86, v87
	global_store_dwordx2 v[94:95], v[96:97], off
	v_cvt_pk_bf16_f32 v96, v194, v195
	v_cvt_pk_bf16_f32 v97, v196, v197
	global_store_dwordx2 v[90:91], v[32:33], off offset:128
	v_cvt_pk_bf16_f32 v32, v76, v77
	v_cvt_pk_bf16_f32 v33, v78, v79
	v_mfma_f32_16x16x32_bf16 v[56:59], v[172:175], v[10:13], v[156:159]
	global_store_dwordx2 v[92:93], v[96:97], off
	v_cvt_pk_bf16_f32 v96, v224, v225
	v_cvt_pk_bf16_f32 v97, v226, v227
	s_waitcnt lgkmcnt(0)
	v_mfma_f32_16x16x32_bf16 v[12:15], v[152:155], v[10:13], v[4:7]
	global_store_dwordx2 v[94:95], v[32:33], off offset:128
	v_cvt_pk_bf16_f32 v32, v68, v69
	v_cvt_pk_bf16_f32 v33, v70, v71
	v_mfma_f32_16x16x32_bf16 v[8:11], v[152:155], v[160:163], v[144:147]
	global_store_dwordx2 v[88:89], v[96:97], off offset:32
	v_cvt_pk_bf16_f32 v96, v228, v229
	v_cvt_pk_bf16_f32 v97, v230, v231
	v_mfma_f32_16x16x32_bf16 v[4:7], v[152:155], v[164:167], v[148:151]
	global_store_dwordx2 v[92:93], v[32:33], off offset:128
	v_cvt_pk_bf16_f32 v32, v60, v61
	v_cvt_pk_bf16_f32 v33, v62, v63
	v_mfma_f32_16x16x32_bf16 v[0:3], v[152:155], v[168:171], v[0:3]
	global_store_dwordx2 v[90:91], v[96:97], off offset:32
	v_cvt_pk_bf16_f32 v96, v232, v233
	v_cvt_pk_bf16_f32 v97, v234, v235
	global_store_dwordx2 v[88:89], v[32:33], off offset:160
	v_cvt_pk_bf16_f32 v32, v52, v53
	v_cvt_pk_bf16_f32 v33, v54, v55
	global_store_dwordx2 v[94:95], v[96:97], off offset:32
	v_cvt_pk_bf16_f32 v96, v236, v237
	v_cvt_pk_bf16_f32 v97, v238, v239
	global_store_dwordx2 v[90:91], v[32:33], off offset:160
	v_cvt_pk_bf16_f32 v32, v44, v45
	v_cvt_pk_bf16_f32 v33, v46, v47
	global_store_dwordx2 v[92:93], v[96:97], off offset:32
	v_cvt_pk_bf16_f32 v96, v240, v241
	v_cvt_pk_bf16_f32 v97, v242, v243
	v_cvt_pk_bf16_f32 v56, v56, v57
	v_cvt_pk_bf16_f32 v57, v58, v59
	global_store_dwordx2 v[94:95], v[32:33], off offset:160
	v_cvt_pk_bf16_f32 v32, v36, v37
	v_cvt_pk_bf16_f32 v33, v38, v39
	v_cvt_pk_bf16_f32 v25, v26, v27
	v_cvt_pk_bf16_f32 v20, v20, v21
	v_cvt_pk_bf16_f32 v21, v22, v23
	v_cvt_pk_bf16_f32 v16, v16, v17
	v_cvt_pk_bf16_f32 v17, v18, v19
	v_cvt_pk_bf16_f32 v12, v12, v13
	v_cvt_pk_bf16_f32 v13, v14, v15
	v_cvt_pk_bf16_f32 v8, v8, v9
	v_cvt_pk_bf16_f32 v9, v10, v11
	v_cvt_pk_bf16_f32 v4, v4, v5
	v_cvt_pk_bf16_f32 v5, v6, v7
	v_cvt_pk_bf16_f32 v0, v0, v1
	v_cvt_pk_bf16_f32 v1, v2, v3
	global_store_dwordx2 v[88:89], v[96:97], off offset:64
	global_store_dwordx2 v[90:91], v[80:81], off offset:64
	global_store_dwordx2 v[94:95], v[72:73], off offset:64
	global_store_dwordx2 v[92:93], v[64:65], off offset:64
	global_store_dwordx2 v[88:89], v[56:57], off offset:96
	global_store_dwordx2 v[90:91], v[48:49], off offset:96
	global_store_dwordx2 v[94:95], v[40:41], off offset:96
	global_store_dwordx2 v[92:93], v[32:33], off offset:160
	global_store_dwordx2 v[88:89], v[28:29], off offset:192
	global_store_dwordx2 v[90:91], v[24:25], off offset:192
	global_store_dwordx2 v[94:95], v[20:21], off offset:192
	global_store_dwordx2 v[92:93], v[16:17], off offset:192
	global_store_dwordx2 v[88:89], v[12:13], off offset:224
	global_store_dwordx2 v[90:91], v[8:9], off offset:224
	global_store_dwordx2 v[94:95], v[4:5], off offset:224
	global_store_dwordx2 v[92:93], v[0:1], off offset:224

; template <int N> DI void wait_vm() { asm volatile("s_waitcnt vmcnt(%0)" ::"n"(N) : "memory"); }
; template <int BM, class Epi>
; DI void gemm_dma(const u16* __restrict__ X, long ldx, const u16* __restrict__ W, long ldw, int K, char* smem,
;                  int m0, int n0, const Epi& epi) {
;     ...
;   const int wu = __builtin_amdgcn_readfirstlane(wave);
;   const unsigned sbase = (unsigned)__builtin_amdgcn_readfirstlane((int)(unsigned)(size_t)smem);
;   const int r16 = lane >> 2, chunk = (lane & 3) ^ ((4 - (r16 >> 2)) & 3);
;   const u16* xs = X + (long)(wu * XD * 16 + r16) * ldx + (chunk << 3);
;   const u16* ws = W + (long)(wu * 32 + r16) * ldw + (chunk << 3);
;   const long ldx16 = 16 * ldx, ldw16 = 16 * ldw;
;   const unsigned xdst = sbase + wu * XD * 1024, wdst = sbase + BM * 64 + wu * 2048;
;     ...
;   const int nk = K >> 5;
;   __syncthreads();
; #pragma unroll
;   for (int s = 0; s < D - 1; ++s) GD_ISSUE(s)
;   int cur = 0, nxt = D - 1, kt = 0;
;   do {
;     if (kt + D - 2 < nk) wait_vm<PW * (D - 2)>(); else wait_vm<0>();
;     __syncthreads();
;     if (kt + D - 1 < nk) GD_ISSUE(nxt)
;     nxt = (nxt + 1 == D) ? 0 : nxt + 1;
;     const char* base = smem + cur * STG;
;     cur = (cur + 1 == D) ? 0 : cur + 1;
;     bf16x8 xf[MT];
; #pragma unroll
;     for (int i = 0; i < MT; ++i) xf[i] = *(const bf16x8*)(base + (xrow0 + i * 16) * 64 + rd);
; DI void phase_odd(const Params& p, int o, int sub, char* smem) {
;     ...
;       } else {
;         knope_tile(p, t - 1584, smem);
;       }
.LBB0_981:
	s_cmpk_gt_i32 s5, 0x62f
	s_mov_b64 s[38:39], -1
	s_cbranch_scc0 .LBB0_983
	s_add_i32 s4, s5, 0xfffff9d0
	s_bfe_u32 s98, s4, 0x30003
	s_and_b32 s99, s4, 7
	s_lshl_b32 s99, s99, 3
	s_andn2_b32 s4, s4, 63
	s_or_b32 s4, s4, s99
	s_or_b32 s4, s4, s98
	s_lshr_b32 s6, s4, 3
	s_and_b32 s4, s4, 7
	s_lshl_b32 s7, s6, 17
	s_add_u32 s8, s0, s7
	s_addc_u32 s9, s1, 0
	s_lshl_b32 s7, s4, 16
	v_mov_b32_e32 v9, v185
	s_add_u32 s10, s87, s7
	s_addc_u32 s11, s90, 0
	v_readfirstlane_b32 s7, v9
	v_lshrrev_b32_e32 v4, 4, v9
	s_ashr_i32 s12, s7, 6
	v_bfe_u32 v6, v9, 2, 4
	v_sub_u32_e32 v4, 0, v4
	s_andn2_b32 s7, s7, 63
	v_lshrrev_b32_e32 v1, 2, v9
	v_xor_b32_e32 v7, v9, v4
	v_or_b32_e32 v4, s7, v6
	v_and_b32_e32 v89, 15, v9
	v_bfe_u32 v88, v9, 4, 2
	v_sub_u32_e32 v1, 0, v1
	v_ashrrev_i32_e32 v5, 31, v4
	v_lshlrev_b32_e32 v0, 6, v89
	v_bitop3_b32 v1, v88, v1, 3 bitop3:0x78
	v_lshlrev_b64 v[4:5], 9, v[4:5]
	v_lshlrev_b32_e32 v7, 4, v7
	v_lshl_or_b32 v6, s12, 5, v6
	v_lshl_or_b32 v8, v1, 4, v0
	v_mov_b32_e32 v0, v183
	v_lshl_add_u64 v[4:5], s[8:9], 0, v[4:5]
	v_and_b32_e32 v182, 48, v7
	v_ashrrev_i32_e32 v7, 31, v6
	v_lshl_add_u64 v[4:5], v[4:5], 0, v[182:183]
	v_lshlrev_b64 v[6:7], 9, v[6:7]
	s_lshl_b32 s14, s12, 12
	s_waitcnt lgkmcnt(0)
	s_barrier
	s_mov_b32 m0, s14
	s_nop 0
	global_load_lds_dwordx4 v[4:5], off
	s_mov_b64 s[8:9], 0x2000
	v_lshl_add_u64 v[6:7], s[10:11], 0, v[6:7]
	v_lshl_add_u64 v[10:11], v[4:5], 0, s[8:9]
	s_or_b32 s15, s14, 0x400
	s_mov_b32 m0, s15
	s_nop 0
	global_load_lds_dwordx4 v[10:11], off
	s_mov_b64 s[10:11], 0x4000
	v_lshl_add_u64 v[10:11], v[4:5], 0, s[10:11]
	s_or_b32 s16, s14, 0x800
	s_mov_b32 m0, s16
	s_nop 0
	global_load_lds_dwordx4 v[10:11], off
	s_mov_b64 s[10:11], 0x6000
	s_lshl_b32 s42, s12, 11
	v_lshl_add_u64 v[10:11], v[4:5], 0, s[10:11]
	s_or_b32 s17, s14, 0xc00
	s_mov_b32 m0, s17
	s_nop 0
	global_load_lds_dwordx4 v[10:11], off
	v_lshl_add_u64 v[6:7], v[6:7], 0, v[182:183]
	s_add_i32 s13, s42, 0x4000
	s_mov_b32 m0, s13
	s_nop 0
	global_load_lds_dwordx4 v[6:7], off
	v_lshl_add_u64 v[10:11], v[6:7], 0, s[8:9]
	s_add_i32 s18, s42, 0x4400
	s_mov_b32 m0, s18
	s_nop 0
	global_load_lds_dwordx4 v[10:11], off
	v_lshl_add_u64 v[10:11], v[4:5], 0, 64
	s_add_i32 s7, s14, 0x6000
	s_mov_b32 m0, s7
	s_nop 0
	global_load_lds_dwordx4 v[10:11], off
	s_mov_b64 s[20:21], 0x2040
	v_lshl_add_u64 v[10:11], v[4:5], 0, s[20:21]
	s_add_i32 s8, s14, 0x6400
	s_mov_b32 m0, s8
	s_nop 0
	global_load_lds_dwordx4 v[10:11], off
	s_mov_b64 s[10:11], 0x4040
	v_lshl_add_u64 v[10:11], v[4:5], 0, s[10:11]
	s_add_i32 s9, s14, 0x6800
	s_mov_b32 m0, s9
	s_nop 0
	global_load_lds_dwordx4 v[10:11], off
	s_mov_b64 s[10:11], 0x6040
	v_lshl_add_u64 v[10:11], v[4:5], 0, s[10:11]
	s_add_i32 s10, s14, 0x6c00
	s_mov_b32 m0, s10
	s_nop 0
	global_load_lds_dwordx4 v[10:11], off
	v_lshl_add_u64 v[12:13], v[6:7], 0, 64
	s_add_i32 s11, s42, 0xa000
	s_mov_b32 m0, s11
	s_nop 0
	global_load_lds_dwordx4 v[12:13], off
	v_lshl_add_u64 v[10:11], v[6:7], 0, s[20:21]
	s_add_i32 s12, s42, 0xa400
	s_mov_b32 m0, s12
	s_nop 0
	global_load_lds_dwordx4 v[10:11], off
	s_waitcnt vmcnt(6)
	s_barrier
	v_lshl_add_u64 v[12:13], v[4:5], 0, s[28:29]
	s_add_i32 s19, s14, 0xc000
	s_mov_b32 m0, s19
	s_nop 0
	global_load_lds_dwordx4 v[12:13], off
	s_mov_b64 s[20:21], 0x2080
	v_lshl_add_u64 v[12:13], v[4:5], 0, s[20:21]
	s_add_i32 s34, s14, 0xc400
	s_mov_b32 m0, s34
	s_nop 0
	global_load_lds_dwordx4 v[12:13], off
	v_lshl_add_u64 v[12:13], v[4:5], 0, s[94:95]
	s_add_i32 s38, s14, 0xc800
	s_mov_b32 m0, s38
	s_nop 0
	global_load_lds_dwordx4 v[12:13], off
	s_mov_b64 s[22:23], 0x6080
	v_lshl_add_u64 v[12:13], v[4:5], 0, s[22:23]
	s_add_i32 s43, s14, 0xcc00
	s_mov_b32 m0, s43
	s_nop 0
	global_load_lds_dwordx4 v[12:13], off
	v_and_b32_e32 v90, 0xffffffc0, v9
	v_lshl_add_u64 v[10:11], v[6:7], 0, s[28:29]
	s_add_i32 s39, s42, 0x10000
	s_mov_b32 m0, s39
	s_nop 0
	global_load_lds_dwordx4 v[10:11], off
	v_lshl_add_u64 v[10:11], v[6:7], 0, s[20:21]
	s_add_i32 s42, s42, 0x10400
	s_mov_b32 m0, s42
	s_nop 0
	global_load_lds_dwordx4 v[10:11], off
	v_lshl_or_b32 v9, v90, 6, v8
	ds_read_b128 v[10:13], v9
	s_waitcnt vmcnt(7)
	ds_read_b128 v[14:17], v9 offset:1024
	s_waitcnt vmcnt(5)
	ds_read_b128 v[18:21], v9 offset:2048
	s_waitcnt vmcnt(5)
	ds_read_b128 v[22:25], v9 offset:3072
	s_waitcnt vmcnt(4)
	ds_read_b128 v[26:29], v8 offset:16384
	s_waitcnt vmcnt(4)
	ds_read_b128 v[30:33], v8 offset:17408
	ds_read_b128 v[34:37], v8 offset:18432
	ds_read_b128 v[38:41], v8 offset:19456
	s_waitcnt vmcnt(0)
	ds_read_b128 v[96:99], v8 offset:20480
	ds_read_b128 v[100:103], v8 offset:21504
	ds_read_b128 v[104:107], v8 offset:22528
	ds_read_b128 v[108:111], v8 offset:23552
	s_mov_b64 s[20:21], 0xc0
	v_mov_b32_e32 v1, v0
	v_mov_b32_e32 v2, v0
	v_mov_b32_e32 v3, v0
	v_lshl_add_u64 v[86:87], v[4:5], 0, s[20:21]
	v_lshl_add_u64 v[148:149], v[6:7], 0, s[20:21]
	s_waitcnt vmcnt(6)
	s_waitcnt lgkmcnt(0)
	s_barrier
; template <int N> DI void wait_vm() { asm volatile("s_waitcnt vmcnt(%0)" ::"n"(N) : "memory"); }
; template <int BM, class Epi>
; DI void gemm_dma(const u16* __restrict__ X, long ldx, const u16* __restrict__ W, long ldw, int K, char* smem,
;                  int m0, int n0, const Epi& epi) {
;     ...
;   do {
;     if (kt + D - 2 < nk) wait_vm<PW * (D - 2)>(); else wait_vm<0>();
;     __syncthreads();
;     if (kt + D - 1 < nk) GD_ISSUE(nxt)
;     nxt = (nxt + 1 == D) ? 0 : nxt + 1;
;     const char* base = smem + cur * STG;
;     cur = (cur + 1 == D) ? 0 : cur + 1;
;     bf16x8 xf[MT];
; #pragma unroll
;     for (int i = 0; i < MT; ++i) xf[i] = *(const bf16x8*)(base + (xrow0 + i * 16) * 64 + rd);
; #pragma unroll
;     for (int nh = 0; nh < NT / 4; ++nh) {
;       bf16x8 wf[4];
; #pragma unroll
;       for (int i = 0; i < 4; ++i) wf[i] = *(const bf16x8*)(base + BM * 64 + (wrow0 + (nh * 4 + i) * 16) * 64 + rd);
; #pragma unroll
;       for (int i = 0; i < 4; ++i)
; #pragma unroll
;         for (int mt = 0; mt < MT; ++mt)
;           acc[nh * 4 + i][mt] = __builtin_amdgcn_mfma_f32_16x16x32_bf16(wf[i], xf[mt], acc[nh * 4 + i][mt], 0, 0, 0);
;     }
	s_mov_b32 m0, s14
	s_nop 0
	global_load_lds_dwordx4 v[86:87], off
	s_mov_b64 s[20:21], 0x20c0
	v_mfma_f32_16x16x32_bf16 v[42:45], v[26:29], v[10:13], v[0:3]
	s_mov_b64 s[22:23], 0x40c0
	v_or_b32_e32 v91, 0x10000, v8
	v_or_b32_e32 v174, 0x10400, v8
	v_mfma_f32_16x16x32_bf16 v[46:49], v[26:29], v[14:17], v[0:3]
	v_or_b32_e32 v175, 0x10800, v8
	v_or_b32_e32 v176, 0x10c00, v8
	v_or_b32_e32 v177, 0x11000, v8
	v_mfma_f32_16x16x32_bf16 v[50:53], v[26:29], v[18:21], v[0:3]
	v_or_b32_e32 v178, 0x11400, v8
	v_or_b32_e32 v179, 0x11800, v8
	v_or_b32_e32 v180, 0x11c00, v8
	v_mfma_f32_16x16x32_bf16 v[26:29], v[26:29], v[22:25], v[0:3]
	v_lshl_add_u32 v90, s6, 8, v90
	s_lshl_b32 s4, s4, 8
	v_lshl_or_b32 v182, v88, 3, s4
	v_mfma_f32_16x16x32_bf16 v[54:57], v[30:33], v[10:13], v[0:3]
	v_mfma_f32_16x16x32_bf16 v[58:61], v[30:33], v[14:17], v[0:3]
	v_mfma_f32_16x16x32_bf16 v[62:65], v[30:33], v[18:21], v[0:3]
	v_mfma_f32_16x16x32_bf16 v[30:33], v[30:33], v[22:25], v[0:3]
	v_mfma_f32_16x16x32_bf16 v[66:69], v[34:37], v[10:13], v[0:3]
	v_mfma_f32_16x16x32_bf16 v[70:73], v[34:37], v[14:17], v[0:3]
	v_mfma_f32_16x16x32_bf16 v[74:77], v[34:37], v[18:21], v[0:3]
	v_mfma_f32_16x16x32_bf16 v[34:37], v[34:37], v[22:25], v[0:3]
	v_mfma_f32_16x16x32_bf16 v[78:81], v[38:41], v[10:13], v[0:3]
	v_mfma_f32_16x16x32_bf16 v[82:85], v[38:41], v[14:17], v[0:3]
	v_mfma_f32_16x16x32_bf16 v[92:95], v[38:41], v[18:21], v[0:3]
	v_mfma_f32_16x16x32_bf16 v[38:41], v[38:41], v[22:25], v[0:3]
	v_mfma_f32_16x16x32_bf16 v[112:115], v[96:99], v[10:13], v[0:3]
	v_mfma_f32_16x16x32_bf16 v[116:119], v[96:99], v[14:17], v[0:3]
	v_mfma_f32_16x16x32_bf16 v[120:123], v[96:99], v[18:21], v[0:3]
	v_mfma_f32_16x16x32_bf16 v[96:99], v[96:99], v[22:25], v[0:3]
	v_mfma_f32_16x16x32_bf16 v[124:127], v[100:103], v[10:13], v[0:3]
	v_mfma_f32_16x16x32_bf16 v[128:131], v[100:103], v[14:17], v[0:3]
	v_mfma_f32_16x16x32_bf16 v[132:135], v[100:103], v[18:21], v[0:3]
	v_mfma_f32_16x16x32_bf16 v[100:103], v[100:103], v[22:25], v[0:3]
	v_mfma_f32_16x16x32_bf16 v[136:139], v[104:107], v[10:13], v[0:3]
	v_mfma_f32_16x16x32_bf16 v[140:143], v[104:107], v[14:17], v[0:3]
	v_mfma_f32_16x16x32_bf16 v[144:147], v[104:107], v[18:21], v[0:3]
	v_mfma_f32_16x16x32_bf16 v[104:107], v[104:107], v[22:25], v[0:3]
	v_mfma_f32_16x16x32_bf16 v[10:13], v[108:111], v[10:13], v[0:3]
	v_mfma_f32_16x16x32_bf16 v[14:17], v[108:111], v[14:17], v[0:3]
	v_mfma_f32_16x16x32_bf16 v[18:21], v[108:111], v[18:21], v[0:3]
	v_mfma_f32_16x16x32_bf16 v[0:3], v[108:111], v[22:25], v[0:3]
	v_lshl_add_u64 v[22:23], v[4:5], 0, s[20:21]
	s_mov_b32 m0, s15
	s_nop 0
	global_load_lds_dwordx4 v[22:23], off
	v_lshl_add_u64 v[22:23], v[4:5], 0, s[22:23]
	s_mov_b32 m0, s16
	s_nop 0
	global_load_lds_dwordx4 v[22:23], off
	s_mov_b64 s[22:23], 0x60c0
	v_lshl_add_u64 v[22:23], v[4:5], 0, s[22:23]
	s_mov_b32 m0, s17
	s_nop 0
	global_load_lds_dwordx4 v[22:23], off
	v_lshl_add_u64 v[22:23], v[6:7], 0, s[20:21]
	s_mov_b32 m0, s13
	s_nop 0
	global_load_lds_dwordx4 v[148:149], off
	s_mov_b64 s[20:21], 0x100
	s_mov_b32 m0, s18
	s_nop 0
	global_load_lds_dwordx4 v[22:23], off
	ds_read_b128 v[22:25], v9 offset:24576
	ds_read_b128 v[108:111], v9 offset:25600
	ds_read_b128 v[148:151], v9 offset:26624
	ds_read_b128 v[152:155], v9 offset:27648
	ds_read_b128 v[156:159], v8 offset:40960
	ds_read_b128 v[160:163], v8 offset:41984
	ds_read_b128 v[164:167], v8 offset:43008
	ds_read_b128 v[168:171], v8 offset:44032
	s_waitcnt lgkmcnt(3)
	v_mfma_f32_16x16x32_bf16 v[42:45], v[156:159], v[22:25], v[42:45]
	v_lshl_add_u64 v[86:87], v[4:5], 0, s[20:21]
	v_lshl_add_u64 v[172:173], v[6:7], 0, s[20:21]
	s_mov_b64 s[20:21], 0x2100
	v_mfma_f32_16x16x32_bf16 v[46:49], v[156:159], v[108:111], v[46:49]
	s_mov_b64 s[22:23], 0x4100
	v_mfma_f32_16x16x32_bf16 v[50:53], v[156:159], v[148:151], v[50:53]
	v_mfma_f32_16x16x32_bf16 v[26:29], v[156:159], v[152:155], v[26:29]
	s_waitcnt lgkmcnt(2)
	v_mfma_f32_16x16x32_bf16 v[54:57], v[160:163], v[22:25], v[54:57]
	v_mfma_f32_16x16x32_bf16 v[58:61], v[160:163], v[108:111], v[58:61]
	v_mfma_f32_16x16x32_bf16 v[62:65], v[160:163], v[148:151], v[62:65]
	v_mfma_f32_16x16x32_bf16 v[30:33], v[160:163], v[152:155], v[30:33]
	s_waitcnt lgkmcnt(1)
	v_mfma_f32_16x16x32_bf16 v[66:69], v[164:167], v[22:25], v[66:69]
	v_mfma_f32_16x16x32_bf16 v[70:73], v[164:167], v[108:111], v[70:73]
	v_mfma_f32_16x16x32_bf16 v[74:77], v[164:167], v[148:151], v[74:77]
	v_mfma_f32_16x16x32_bf16 v[34:37], v[164:167], v[152:155], v[34:37]
	s_waitcnt lgkmcnt(0)
	v_mfma_f32_16x16x32_bf16 v[78:81], v[168:171], v[22:25], v[78:81]
	v_mfma_f32_16x16x32_bf16 v[82:85], v[168:171], v[108:111], v[82:85]
	v_mfma_f32_16x16x32_bf16 v[92:95], v[168:171], v[148:151], v[92:95]
	v_mfma_f32_16x16x32_bf16 v[38:41], v[168:171], v[152:155], v[38:41]
	ds_read_b128 v[156:159], v8 offset:45056
	ds_read_b128 v[160:163], v8 offset:46080
	ds_read_b128 v[164:167], v8 offset:47104
	ds_read_b128 v[168:171], v8 offset:48128
	s_waitcnt vmcnt(6)
	s_waitcnt lgkmcnt(0)
	s_barrier
; template <int N> DI void wait_vm() { asm volatile("s_waitcnt vmcnt(%0)" ::"n"(N) : "memory"); }
; template <int BM, class Epi>
; DI void gemm_dma(const u16* __restrict__ X, long ldx, const u16* __restrict__ W, long ldw, int K, char* smem,
;                  int m0, int n0, const Epi& epi) {
;     ...
;   do {
;     if (kt + D - 2 < nk) wait_vm<PW * (D - 2)>(); else wait_vm<0>();
;     __syncthreads();
;     if (kt + D - 1 < nk) GD_ISSUE(nxt)
;     nxt = (nxt + 1 == D) ? 0 : nxt + 1;
;     const char* base = smem + cur * STG;
;     cur = (cur + 1 == D) ? 0 : cur + 1;
;     bf16x8 xf[MT];
; #pragma unroll
;     for (int i = 0; i < MT; ++i) xf[i] = *(const bf16x8*)(base + (xrow0 + i * 16) * 64 + rd);
; #pragma unroll
;     for (int nh = 0; nh < NT / 4; ++nh) {
;       bf16x8 wf[4];
; #pragma unroll
;       for (int i = 0; i < 4; ++i) wf[i] = *(const bf16x8*)(base + BM * 64 + (wrow0 + (nh * 4 + i) * 16) * 64 + rd);
; #pragma unroll
;       for (int i = 0; i < 4; ++i)
; #pragma unroll
;         for (int mt = 0; mt < MT; ++mt)
;           acc[nh * 4 + i][mt] = __builtin_amdgcn_mfma_f32_16x16x32_bf16(wf[i], xf[mt], acc[nh * 4 + i][mt], 0, 0, 0);
;     }
	s_mov_b32 m0, s7
	s_nop 0
	global_load_lds_dwordx4 v[86:87], off
	v_mfma_f32_16x16x32_bf16 v[112:115], v[156:159], v[22:25], v[112:115]
	v_mfma_f32_16x16x32_bf16 v[124:127], v[160:163], v[22:25], v[124:127]
	v_mfma_f32_16x16x32_bf16 v[136:139], v[164:167], v[22:25], v[136:139]
	v_mfma_f32_16x16x32_bf16 v[10:13], v[168:171], v[22:25], v[10:13]
	v_lshl_add_u64 v[22:23], v[4:5], 0, s[20:21]
	s_mov_b32 m0, s8
	s_nop 0
	global_load_lds_dwordx4 v[22:23], off
	v_lshl_add_u64 v[22:23], v[4:5], 0, s[22:23]
	s_mov_b32 m0, s9
	s_nop 0
	global_load_lds_dwordx4 v[22:23], off
	s_mov_b64 s[22:23], 0x6100
	v_lshl_add_u64 v[22:23], v[4:5], 0, s[22:23]
	s_mov_b32 m0, s10
	s_nop 0
	global_load_lds_dwordx4 v[22:23], off
	v_lshl_add_u64 v[22:23], v[6:7], 0, s[20:21]
	s_mov_b32 m0, s11
	s_nop 0
	global_load_lds_dwordx4 v[172:173], off
	v_mfma_f32_16x16x32_bf16 v[116:119], v[156:159], v[108:111], v[116:119]
	s_mov_b32 m0, s12
	s_nop 0
	global_load_lds_dwordx4 v[22:23], off
	s_mov_b64 s[20:21], 0x140
	v_lshl_add_u64 v[86:87], v[4:5], 0, s[20:21]
	v_mfma_f32_16x16x32_bf16 v[120:123], v[156:159], v[148:151], v[120:123]
	v_lshl_add_u64 v[172:173], v[6:7], 0, s[20:21]
	s_mov_b64 s[20:21], 0x2140
	s_mov_b64 s[22:23], 0x4140
	v_mfma_f32_16x16x32_bf16 v[96:99], v[156:159], v[152:155], v[96:99]
	v_mfma_f32_16x16x32_bf16 v[128:131], v[160:163], v[108:111], v[128:131]
	v_mfma_f32_16x16x32_bf16 v[132:135], v[160:163], v[148:151], v[132:135]
	v_mfma_f32_16x16x32_bf16 v[100:103], v[160:163], v[152:155], v[100:103]
	v_mfma_f32_16x16x32_bf16 v[140:143], v[164:167], v[108:111], v[140:143]
	v_mfma_f32_16x16x32_bf16 v[144:147], v[164:167], v[148:151], v[144:147]
	v_mfma_f32_16x16x32_bf16 v[104:107], v[164:167], v[152:155], v[104:107]
	v_mfma_f32_16x16x32_bf16 v[14:17], v[168:171], v[108:111], v[14:17]
	v_mfma_f32_16x16x32_bf16 v[18:21], v[168:171], v[148:151], v[18:21]
	v_mfma_f32_16x16x32_bf16 v[0:3], v[168:171], v[152:155], v[0:3]
	ds_read_b128 v[22:25], v9 offset:49152
	ds_read_b128 v[108:111], v9 offset:50176
	ds_read_b128 v[148:151], v9 offset:51200
	ds_read_b128 v[152:155], v9 offset:52224
	ds_read_b128 v[156:159], v91
	ds_read_b128 v[160:163], v174
	ds_read_b128 v[164:167], v175
	ds_read_b128 v[168:171], v176
	s_waitcnt lgkmcnt(3)
	v_mfma_f32_16x16x32_bf16 v[42:45], v[156:159], v[22:25], v[42:45]
	v_mfma_f32_16x16x32_bf16 v[46:49], v[156:159], v[108:111], v[46:49]
	v_mfma_f32_16x16x32_bf16 v[50:53], v[156:159], v[148:151], v[50:53]
	v_mfma_f32_16x16x32_bf16 v[26:29], v[156:159], v[152:155], v[26:29]
	ds_read_b128 v[156:159], v177
	s_waitcnt lgkmcnt(3)
	v_mfma_f32_16x16x32_bf16 v[54:57], v[160:163], v[22:25], v[54:57]
	v_mfma_f32_16x16x32_bf16 v[58:61], v[160:163], v[108:111], v[58:61]
	v_mfma_f32_16x16x32_bf16 v[62:65], v[160:163], v[148:151], v[62:65]
	v_mfma_f32_16x16x32_bf16 v[30:33], v[160:163], v[152:155], v[30:33]
	ds_read_b128 v[160:163], v178
	s_waitcnt lgkmcnt(3)
	v_mfma_f32_16x16x32_bf16 v[66:69], v[164:167], v[22:25], v[66:69]
	v_mfma_f32_16x16x32_bf16 v[70:73], v[164:167], v[108:111], v[70:73]
	v_mfma_f32_16x16x32_bf16 v[74:77], v[164:167], v[148:151], v[74:77]
	v_mfma_f32_16x16x32_bf16 v[34:37], v[164:167], v[152:155], v[34:37]
	ds_read_b128 v[164:167], v179
	s_waitcnt lgkmcnt(3)
	v_mfma_f32_16x16x32_bf16 v[78:81], v[168:171], v[22:25], v[78:81]
	v_mfma_f32_16x16x32_bf16 v[82:85], v[168:171], v[108:111], v[82:85]
	v_mfma_f32_16x16x32_bf16 v[92:95], v[168:171], v[148:151], v[92:95]
	v_mfma_f32_16x16x32_bf16 v[38:41], v[168:171], v[152:155], v[38:41]
	ds_read_b128 v[168:171], v180
	s_waitcnt vmcnt(6)
	s_waitcnt lgkmcnt(0)
	s_barrier
	s_mov_b32 m0, s19
	s_nop 0
	global_load_lds_dwordx4 v[86:87], off
	v_mfma_f32_16x16x32_bf16 v[112:115], v[156:159], v[22:25], v[112:115]
	v_mfma_f32_16x16x32_bf16 v[124:127], v[160:163], v[22:25], v[124:127]
	v_mfma_f32_16x16x32_bf16 v[136:139], v[164:167], v[22:25], v[136:139]
	v_mfma_f32_16x16x32_bf16 v[10:13], v[168:171], v[22:25], v[10:13]
	v_lshl_add_u64 v[22:23], v[4:5], 0, s[20:21]
	s_mov_b32 m0, s34
	s_nop 0
	global_load_lds_dwordx4 v[22:23], off
	v_lshl_add_u64 v[22:23], v[4:5], 0, s[22:23]
	s_mov_b32 m0, s38
	s_nop 0
	global_load_lds_dwordx4 v[22:23], off
	s_mov_b64 s[22:23], 0x6140
	v_lshl_add_u64 v[22:23], v[4:5], 0, s[22:23]
	s_mov_b32 m0, s43
	s_nop 0
	global_load_lds_dwordx4 v[22:23], off
	v_lshl_add_u64 v[22:23], v[6:7], 0, s[20:21]
	s_mov_b32 m0, s39
	s_nop 0
	global_load_lds_dwordx4 v[172:173], off
	v_mfma_f32_16x16x32_bf16 v[116:119], v[156:159], v[108:111], v[116:119]
	s_mov_b32 m0, s42
	s_nop 0
	global_load_lds_dwordx4 v[22:23], off
	s_mov_b64 s[20:21], 0x180
	v_lshl_add_u64 v[86:87], v[4:5], 0, s[20:21]
	v_mfma_f32_16x16x32_bf16 v[120:123], v[156:159], v[148:151], v[120:123]
	v_lshl_add_u64 v[172:173], v[6:7], 0, s[20:21]
	s_mov_b64 s[20:21], 0x2180
	s_mov_b64 s[38:39], 0
	v_mfma_f32_16x16x32_bf16 v[96:99], v[156:159], v[152:155], v[96:99]
	v_mfma_f32_16x16x32_bf16 v[128:131], v[160:163], v[108:111], v[128:131]
	v_mfma_f32_16x16x32_bf16 v[132:135], v[160:163], v[148:151], v[132:135]
	v_mfma_f32_16x16x32_bf16 v[100:103], v[160:163], v[152:155], v[100:103]
	v_mfma_f32_16x16x32_bf16 v[140:143], v[164:167], v[108:111], v[140:143]
	v_mfma_f32_16x16x32_bf16 v[144:147], v[164:167], v[148:151], v[144:147]
	v_mfma_f32_16x16x32_bf16 v[104:107], v[164:167], v[152:155], v[104:107]
	v_mfma_f32_16x16x32_bf16 v[14:17], v[168:171], v[108:111], v[14:17]
	v_mfma_f32_16x16x32_bf16 v[18:21], v[168:171], v[148:151], v[18:21]
	v_mfma_f32_16x16x32_bf16 v[0:3], v[168:171], v[152:155], v[0:3]
	ds_read_b128 v[22:25], v9
	ds_read_b128 v[108:111], v9 offset:1024
	ds_read_b128 v[148:151], v9 offset:2048
	ds_read_b128 v[152:155], v9 offset:3072
	ds_read_b128 v[156:159], v8 offset:16384
	ds_read_b128 v[160:163], v8 offset:17408
	ds_read_b128 v[164:167], v8 offset:18432
	ds_read_b128 v[168:171], v8 offset:19456
	s_waitcnt lgkmcnt(3)
; template <int N> DI void wait_vm() { asm volatile("s_waitcnt vmcnt(%0)" ::"n"(N) : "memory"); }
; template <int BM, class Epi>
; DI void gemm_dma(const u16* __restrict__ X, long ldx, const u16* __restrict__ W, long ldw, int K, char* smem,
;                  int m0, int n0, const Epi& epi) {
;     ...
;   do {
;     if (kt + D - 2 < nk) wait_vm<PW * (D - 2)>(); else wait_vm<0>();
;     __syncthreads();
;     if (kt + D - 1 < nk) GD_ISSUE(nxt)
;     nxt = (nxt + 1 == D) ? 0 : nxt + 1;
;     const char* base = smem + cur * STG;
;     cur = (cur + 1 == D) ? 0 : cur + 1;
;     bf16x8 xf[MT];
; #pragma unroll
;     for (int i = 0; i < MT; ++i) xf[i] = *(const bf16x8*)(base + (xrow0 + i * 16) * 64 + rd);
; #pragma unroll
;     for (int nh = 0; nh < NT / 4; ++nh) {
;       bf16x8 wf[4];
; #pragma unroll
;       for (int i = 0; i < 4; ++i) wf[i] = *(const bf16x8*)(base + BM * 64 + (wrow0 + (nh * 4 + i) * 16) * 64 + rd);
; #pragma unroll
;       for (int i = 0; i < 4; ++i)
; #pragma unroll
;         for (int mt = 0; mt < MT; ++mt)
;           acc[nh * 4 + i][mt] = __builtin_amdgcn_mfma_f32_16x16x32_bf16(wf[i], xf[mt], acc[nh * 4 + i][mt], 0, 0, 0);
;     }
;   } while (++kt < nk);
	v_mfma_f32_16x16x32_bf16 v[42:45], v[156:159], v[22:25], v[42:45]
	v_mfma_f32_16x16x32_bf16 v[46:49], v[156:159], v[108:111], v[46:49]
	v_mfma_f32_16x16x32_bf16 v[50:53], v[156:159], v[148:151], v[50:53]
	v_mfma_f32_16x16x32_bf16 v[26:29], v[156:159], v[152:155], v[26:29]
	s_waitcnt lgkmcnt(2)
	v_mfma_f32_16x16x32_bf16 v[54:57], v[160:163], v[22:25], v[54:57]
	v_mfma_f32_16x16x32_bf16 v[58:61], v[160:163], v[108:111], v[58:61]
	v_mfma_f32_16x16x32_bf16 v[62:65], v[160:163], v[148:151], v[62:65]
	v_mfma_f32_16x16x32_bf16 v[30:33], v[160:163], v[152:155], v[30:33]
	s_waitcnt lgkmcnt(1)
	v_mfma_f32_16x16x32_bf16 v[66:69], v[164:167], v[22:25], v[66:69]
	v_mfma_f32_16x16x32_bf16 v[70:73], v[164:167], v[108:111], v[70:73]
	v_mfma_f32_16x16x32_bf16 v[74:77], v[164:167], v[148:151], v[74:77]
	v_mfma_f32_16x16x32_bf16 v[34:37], v[164:167], v[152:155], v[34:37]
	s_waitcnt lgkmcnt(0)
	v_mfma_f32_16x16x32_bf16 v[78:81], v[168:171], v[22:25], v[78:81]
	v_mfma_f32_16x16x32_bf16 v[82:85], v[168:171], v[108:111], v[82:85]
	v_mfma_f32_16x16x32_bf16 v[92:95], v[168:171], v[148:151], v[92:95]
	v_mfma_f32_16x16x32_bf16 v[38:41], v[168:171], v[152:155], v[38:41]
	ds_read_b128 v[156:159], v8 offset:20480
	ds_read_b128 v[160:163], v8 offset:21504
	ds_read_b128 v[164:167], v8 offset:22528
	ds_read_b128 v[168:171], v8 offset:23552
	s_waitcnt vmcnt(6)
	s_waitcnt lgkmcnt(0)
	s_barrier
	s_mov_b32 m0, s14
	s_nop 0
	global_load_lds_dwordx4 v[86:87], off
	v_mfma_f32_16x16x32_bf16 v[112:115], v[156:159], v[22:25], v[112:115]
	v_mfma_f32_16x16x32_bf16 v[124:127], v[160:163], v[22:25], v[124:127]
	v_mfma_f32_16x16x32_bf16 v[136:139], v[164:167], v[22:25], v[136:139]
	v_mfma_f32_16x16x32_bf16 v[10:13], v[168:171], v[22:25], v[10:13]
	v_lshl_add_u64 v[22:23], v[4:5], 0, s[20:21]
	s_mov_b32 m0, s15
	s_nop 0
	global_load_lds_dwordx4 v[22:23], off
	s_mov_b64 s[14:15], 0x4180
	v_lshl_add_u64 v[22:23], v[4:5], 0, s[14:15]
	s_mov_b32 m0, s16
	s_nop 0
	global_load_lds_dwordx4 v[22:23], off
	s_mov_b64 s[14:15], 0x6180
	v_lshl_add_u64 v[22:23], v[4:5], 0, s[14:15]
	s_mov_b32 m0, s17
	s_nop 0
	global_load_lds_dwordx4 v[22:23], off
	v_lshl_add_u64 v[22:23], v[6:7], 0, s[20:21]
	s_mov_b32 m0, s13
	s_nop 0
	global_load_lds_dwordx4 v[172:173], off
	s_mov_b32 m0, s18
	s_nop 0
	global_load_lds_dwordx4 v[22:23], off
	v_mfma_f32_16x16x32_bf16 v[116:119], v[156:159], v[108:111], v[116:119]
	s_mov_b64 s[14:15], 0x1c0
	v_lshl_add_u64 v[86:87], v[4:5], 0, s[14:15]
	v_lshl_add_u64 v[172:173], v[6:7], 0, s[14:15]
	v_mfma_f32_16x16x32_bf16 v[120:123], v[156:159], v[148:151], v[120:123]
	s_mov_b64 s[14:15], 0x21c0
	s_mov_b64 s[16:17], 0x41c0
	v_mfma_f32_16x16x32_bf16 v[96:99], v[156:159], v[152:155], v[96:99]
	v_mfma_f32_16x16x32_bf16 v[128:131], v[160:163], v[108:111], v[128:131]
	v_mfma_f32_16x16x32_bf16 v[132:135], v[160:163], v[148:151], v[132:135]
	v_mfma_f32_16x16x32_bf16 v[100:103], v[160:163], v[152:155], v[100:103]
	v_mfma_f32_16x16x32_bf16 v[140:143], v[164:167], v[108:111], v[140:143]
	v_mfma_f32_16x16x32_bf16 v[144:147], v[164:167], v[148:151], v[144:147]
	v_mfma_f32_16x16x32_bf16 v[104:107], v[164:167], v[152:155], v[104:107]
	v_mfma_f32_16x16x32_bf16 v[14:17], v[168:171], v[108:111], v[14:17]
	v_mfma_f32_16x16x32_bf16 v[18:21], v[168:171], v[148:151], v[18:21]
	v_mfma_f32_16x16x32_bf16 v[0:3], v[168:171], v[152:155], v[0:3]
	ds_read_b128 v[22:25], v9 offset:24576
	ds_read_b128 v[108:111], v9 offset:25600
	ds_read_b128 v[148:151], v9 offset:26624
	ds_read_b128 v[152:155], v9 offset:27648
	ds_read_b128 v[156:159], v8 offset:40960
	ds_read_b128 v[160:163], v8 offset:41984
	ds_read_b128 v[164:167], v8 offset:43008
	ds_read_b128 v[168:171], v8 offset:44032
	s_waitcnt lgkmcnt(3)
	v_mfma_f32_16x16x32_bf16 v[42:45], v[156:159], v[22:25], v[42:45]
	v_mfma_f32_16x16x32_bf16 v[46:49], v[156:159], v[108:111], v[46:49]
	v_mfma_f32_16x16x32_bf16 v[50:53], v[156:159], v[148:151], v[50:53]
	v_mfma_f32_16x16x32_bf16 v[26:29], v[156:159], v[152:155], v[26:29]
	s_waitcnt lgkmcnt(2)
	v_mfma_f32_16x16x32_bf16 v[54:57], v[160:163], v[22:25], v[54:57]
	v_mfma_f32_16x16x32_bf16 v[58:61], v[160:163], v[108:111], v[58:61]
	v_mfma_f32_16x16x32_bf16 v[62:65], v[160:163], v[148:151], v[62:65]
	v_mfma_f32_16x16x32_bf16 v[30:33], v[160:163], v[152:155], v[30:33]
	s_waitcnt lgkmcnt(1)
	v_mfma_f32_16x16x32_bf16 v[66:69], v[164:167], v[22:25], v[66:69]
	v_mfma_f32_16x16x32_bf16 v[70:73], v[164:167], v[108:111], v[70:73]
	v_mfma_f32_16x16x32_bf16 v[74:77], v[164:167], v[148:151], v[74:77]
	v_mfma_f32_16x16x32_bf16 v[34:37], v[164:167], v[152:155], v[34:37]
	s_waitcnt lgkmcnt(0)
	v_mfma_f32_16x16x32_bf16 v[78:81], v[168:171], v[22:25], v[78:81]
	v_mfma_f32_16x16x32_bf16 v[82:85], v[168:171], v[108:111], v[82:85]
	v_mfma_f32_16x16x32_bf16 v[92:95], v[168:171], v[148:151], v[92:95]
	v_mfma_f32_16x16x32_bf16 v[38:41], v[168:171], v[152:155], v[38:41]
	ds_read_b128 v[156:159], v8 offset:45056
	ds_read_b128 v[160:163], v8 offset:46080
	ds_read_b128 v[164:167], v8 offset:47104
	ds_read_b128 v[168:171], v8 offset:48128
	s_waitcnt vmcnt(6)
	s_waitcnt lgkmcnt(0)
	s_barrier
; template <int N> DI void wait_vm() { asm volatile("s_waitcnt vmcnt(%0)" ::"n"(N) : "memory"); }
; template <int BM, class Epi>
; DI void gemm_dma(const u16* __restrict__ X, long ldx, const u16* __restrict__ W, long ldw, int K, char* smem,
;                  int m0, int n0, const Epi& epi) {
;     ...
;   do {
;     if (kt + D - 2 < nk) wait_vm<PW * (D - 2)>(); else wait_vm<0>();
;     __syncthreads();
;     if (kt + D - 1 < nk) GD_ISSUE(nxt)
;     nxt = (nxt + 1 == D) ? 0 : nxt + 1;
;     const char* base = smem + cur * STG;
;     cur = (cur + 1 == D) ? 0 : cur + 1;
;     bf16x8 xf[MT];
; #pragma unroll
;     for (int i = 0; i < MT; ++i) xf[i] = *(const bf16x8*)(base + (xrow0 + i * 16) * 64 + rd);
; #pragma unroll
;     for (int nh = 0; nh < NT / 4; ++nh) {
;       bf16x8 wf[4];
; #pragma unroll
;       for (int i = 0; i < 4; ++i) wf[i] = *(const bf16x8*)(base + BM * 64 + (wrow0 + (nh * 4 + i) * 16) * 64 + rd);
; #pragma unroll
;       for (int i = 0; i < 4; ++i)
; #pragma unroll
;         for (int mt = 0; mt < MT; ++mt)
;           acc[nh * 4 + i][mt] = __builtin_amdgcn_mfma_f32_16x16x32_bf16(wf[i], xf[mt], acc[nh * 4 + i][mt], 0, 0, 0);
;     }
;   } while (++kt < nk);
	s_mov_b32 m0, s7
	s_nop 0
	global_load_lds_dwordx4 v[86:87], off
	v_mfma_f32_16x16x32_bf16 v[112:115], v[156:159], v[22:25], v[112:115]
	v_mfma_f32_16x16x32_bf16 v[124:127], v[160:163], v[22:25], v[124:127]
	v_mfma_f32_16x16x32_bf16 v[136:139], v[164:167], v[22:25], v[136:139]
	v_mfma_f32_16x16x32_bf16 v[10:13], v[168:171], v[22:25], v[10:13]
	v_lshl_add_u64 v[22:23], v[4:5], 0, s[14:15]
	s_mov_b32 m0, s8
	s_nop 0
	global_load_lds_dwordx4 v[22:23], off
	v_lshl_add_u64 v[22:23], v[4:5], 0, s[16:17]
	s_mov_b32 m0, s9
	s_nop 0
	global_load_lds_dwordx4 v[22:23], off
	s_mov_b64 s[8:9], 0x61c0
	v_lshl_add_u64 v[4:5], v[4:5], 0, s[8:9]
	s_mov_b32 m0, s10
	s_nop 0
	global_load_lds_dwordx4 v[4:5], off
	v_lshl_add_u64 v[4:5], v[6:7], 0, s[14:15]
	s_mov_b32 m0, s11
	s_nop 0
	global_load_lds_dwordx4 v[172:173], off
	v_mfma_f32_16x16x32_bf16 v[116:119], v[156:159], v[108:111], v[116:119]
	s_mov_b32 m0, s12
	s_nop 0
	global_load_lds_dwordx4 v[4:5], off
	v_readlane_b32 s8, v255, 5
	v_readlane_b32 s14, v255, 11
	v_mfma_f32_16x16x32_bf16 v[120:123], v[156:159], v[148:151], v[120:123]
	v_readlane_b32 s9, v255, 6
	v_readlane_b32 s10, v255, 7
	v_readlane_b32 s11, v255, 8
	v_mfma_f32_16x16x32_bf16 v[96:99], v[156:159], v[152:155], v[96:99]
	v_readlane_b32 s12, v255, 9
	v_readlane_b32 s13, v255, 10
	v_readlane_b32 s15, v255, 12
	v_mfma_f32_16x16x32_bf16 v[128:131], v[160:163], v[108:111], v[128:131]
	s_add_i32 s4, s5, s14
	v_mfma_f32_16x16x32_bf16 v[132:135], v[160:163], v[148:151], v[132:135]
	v_mfma_f32_16x16x32_bf16 v[100:103], v[160:163], v[152:155], v[100:103]
	v_mfma_f32_16x16x32_bf16 v[140:143], v[164:167], v[108:111], v[140:143]
	v_mfma_f32_16x16x32_bf16 v[144:147], v[164:167], v[148:151], v[144:147]
	v_mfma_f32_16x16x32_bf16 v[104:107], v[164:167], v[152:155], v[104:107]
	v_mfma_f32_16x16x32_bf16 v[14:17], v[168:171], v[108:111], v[14:17]
	v_mfma_f32_16x16x32_bf16 v[18:21], v[168:171], v[148:151], v[18:21]
	v_mfma_f32_16x16x32_bf16 v[0:3], v[168:171], v[152:155], v[0:3]
	ds_read_b128 v[4:7], v9 offset:49152
	ds_read_b128 v[22:25], v9 offset:50176
	ds_read_b128 v[108:111], v9 offset:51200
	ds_read_b128 v[148:151], v9 offset:52224
	ds_read_b128 v[152:155], v91
	ds_read_b128 v[156:159], v174
	ds_read_b128 v[160:163], v175
	ds_read_b128 v[164:167], v176
	s_waitcnt lgkmcnt(3)
	v_mfma_f32_16x16x32_bf16 v[42:45], v[152:155], v[4:7], v[42:45]
	v_mfma_f32_16x16x32_bf16 v[46:49], v[152:155], v[22:25], v[46:49]
	v_mfma_f32_16x16x32_bf16 v[50:53], v[152:155], v[108:111], v[50:53]
	v_mfma_f32_16x16x32_bf16 v[26:29], v[152:155], v[148:151], v[26:29]
	s_waitcnt lgkmcnt(2)
	v_mfma_f32_16x16x32_bf16 v[54:57], v[156:159], v[4:7], v[54:57]
	v_mfma_f32_16x16x32_bf16 v[58:61], v[156:159], v[22:25], v[58:61]
	v_mfma_f32_16x16x32_bf16 v[62:65], v[156:159], v[108:111], v[62:65]
	v_mfma_f32_16x16x32_bf16 v[30:33], v[156:159], v[148:151], v[30:33]
	s_waitcnt lgkmcnt(1)
	v_mfma_f32_16x16x32_bf16 v[66:69], v[160:163], v[4:7], v[66:69]
	v_mfma_f32_16x16x32_bf16 v[70:73], v[160:163], v[22:25], v[70:73]
	v_mfma_f32_16x16x32_bf16 v[74:77], v[160:163], v[108:111], v[74:77]
	v_mfma_f32_16x16x32_bf16 v[34:37], v[160:163], v[148:151], v[34:37]
	s_waitcnt lgkmcnt(0)
	v_mfma_f32_16x16x32_bf16 v[78:81], v[164:167], v[4:7], v[78:81]
	v_mfma_f32_16x16x32_bf16 v[82:85], v[164:167], v[22:25], v[82:85]
	v_mfma_f32_16x16x32_bf16 v[92:95], v[164:167], v[108:111], v[92:95]
	v_mfma_f32_16x16x32_bf16 v[38:41], v[164:167], v[148:151], v[38:41]
	ds_read_b128 v[152:155], v177
	ds_read_b128 v[156:159], v178
	ds_read_b128 v[160:163], v179
	ds_read_b128 v[164:167], v180
	s_waitcnt vmcnt(6)
	s_waitcnt lgkmcnt(0)
	v_mfma_f32_16x16x32_bf16 v[112:115], v[152:155], v[4:7], v[112:115]
	s_barrier
	v_mfma_f32_16x16x32_bf16 v[116:119], v[152:155], v[22:25], v[116:119]
	v_mfma_f32_16x16x32_bf16 v[120:123], v[152:155], v[108:111], v[120:123]
	v_mfma_f32_16x16x32_bf16 v[96:99], v[152:155], v[148:151], v[96:99]
	v_mfma_f32_16x16x32_bf16 v[124:127], v[156:159], v[4:7], v[124:127]
	v_mfma_f32_16x16x32_bf16 v[128:131], v[156:159], v[22:25], v[128:131]
	v_mfma_f32_16x16x32_bf16 v[132:135], v[156:159], v[108:111], v[132:135]
	v_mfma_f32_16x16x32_bf16 v[100:103], v[156:159], v[148:151], v[100:103]
	v_mfma_f32_16x16x32_bf16 v[136:139], v[160:163], v[4:7], v[136:139]
	v_mfma_f32_16x16x32_bf16 v[140:143], v[160:163], v[22:25], v[140:143]
	v_mfma_f32_16x16x32_bf16 v[144:147], v[160:163], v[108:111], v[144:147]
	v_mfma_f32_16x16x32_bf16 v[104:107], v[160:163], v[148:151], v[104:107]
	v_mfma_f32_16x16x32_bf16 v[4:7], v[164:167], v[4:7], v[10:13]
	v_mfma_f32_16x16x32_bf16 v[10:13], v[164:167], v[22:25], v[14:17]
	v_mfma_f32_16x16x32_bf16 v[14:17], v[164:167], v[108:111], v[18:21]
	v_mfma_f32_16x16x32_bf16 v[0:3], v[164:167], v[148:151], v[0:3]
	s_nop 1
	ds_read_b128 v[18:21], v8 offset:23552
	ds_read_b128 v[22:25], v8 offset:22528
	ds_read_b128 v[108:111], v8 offset:21504
	ds_read_b128 v[148:151], v8 offset:20480
	ds_read_b128 v[152:155], v8 offset:19456
	ds_read_b128 v[156:159], v8 offset:18432
	ds_read_b128 v[160:163], v8 offset:17408
	ds_read_b128 v[164:167], v8 offset:16384
	ds_read_b128 v[168:171], v9 offset:3072
	ds_read_b128 v[172:175], v9 offset:2048
	ds_read_b128 v[176:179], v9 offset:1024
	ds_read_b128 v[186:189], v9
	s_waitcnt vmcnt(0)
	s_waitcnt lgkmcnt(0)
	v_mfma_f32_16x16x32_bf16 v[42:45], v[164:167], v[186:189], v[42:45]
	s_barrier
; template <int N> DI void wait_vm() { asm volatile("s_waitcnt vmcnt(%0)" ::"n"(N) : "memory"); }
; template <int BM, class Epi>
; DI void gemm_dma(const u16* __restrict__ X, long ldx, const u16* __restrict__ W, long ldw, int K, char* smem,
;                  int m0, int n0, const Epi& epi) {
;     ...
;   do {
;     if (kt + D - 2 < nk) wait_vm<PW * (D - 2)>(); else wait_vm<0>();
;     __syncthreads();
;     if (kt + D - 1 < nk) GD_ISSUE(nxt)
;     nxt = (nxt + 1 == D) ? 0 : nxt + 1;
;     const char* base = smem + cur * STG;
;     cur = (cur + 1 == D) ? 0 : cur + 1;
;     bf16x8 xf[MT];
; #pragma unroll
;     for (int i = 0; i < MT; ++i) xf[i] = *(const bf16x8*)(base + (xrow0 + i * 16) * 64 + rd);
; #pragma unroll
;     for (int nh = 0; nh < NT / 4; ++nh) {
;       bf16x8 wf[4];
; #pragma unroll
;       for (int i = 0; i < 4; ++i) wf[i] = *(const bf16x8*)(base + BM * 64 + (wrow0 + (nh * 4 + i) * 16) * 64 + rd);
; #pragma unroll
;       for (int i = 0; i < 4; ++i)
; #pragma unroll
;         for (int mt = 0; mt < MT; ++mt)
;           acc[nh * 4 + i][mt] = __builtin_amdgcn_mfma_f32_16x16x32_bf16(wf[i], xf[mt], acc[nh * 4 + i][mt], 0, 0, 0);
;     }
;   } while (++kt < nk);
;     ...
;   epi.run(acc, m0 + xrow0 + lr, n0 + wrow0 + 4 * g);
	v_mfma_f32_16x16x32_bf16 v[46:49], v[164:167], v[176:179], v[46:49]
	v_mfma_f32_16x16x32_bf16 v[50:53], v[164:167], v[172:175], v[50:53]
	v_mfma_f32_16x16x32_bf16 v[26:29], v[164:167], v[168:171], v[26:29]
	v_mfma_f32_16x16x32_bf16 v[54:57], v[160:163], v[186:189], v[54:57]
	v_mfma_f32_16x16x32_bf16 v[58:61], v[160:163], v[176:179], v[58:61]
	v_mfma_f32_16x16x32_bf16 v[62:65], v[160:163], v[172:175], v[62:65]
	v_mfma_f32_16x16x32_bf16 v[30:33], v[160:163], v[168:171], v[30:33]
	v_mfma_f32_16x16x32_bf16 v[66:69], v[156:159], v[186:189], v[66:69]
	v_mfma_f32_16x16x32_bf16 v[70:73], v[156:159], v[176:179], v[70:73]
	v_mfma_f32_16x16x32_bf16 v[74:77], v[156:159], v[172:175], v[74:77]
	v_mfma_f32_16x16x32_bf16 v[34:37], v[156:159], v[168:171], v[34:37]
	v_mfma_f32_16x16x32_bf16 v[156:159], v[152:155], v[186:189], v[78:81]
	v_mfma_f32_16x16x32_bf16 v[84:87], v[152:155], v[176:179], v[82:85]
	v_mfma_f32_16x16x32_bf16 v[92:95], v[152:155], v[172:175], v[92:95]
	v_mfma_f32_16x16x32_bf16 v[152:155], v[152:155], v[168:171], v[38:41]
	v_mfma_f32_16x16x32_bf16 v[112:115], v[148:151], v[186:189], v[112:115]
	v_mfma_f32_16x16x32_bf16 v[116:119], v[148:151], v[176:179], v[116:119]
	v_mfma_f32_16x16x32_bf16 v[120:123], v[148:151], v[172:175], v[120:123]
	v_mfma_f32_16x16x32_bf16 v[96:99], v[148:151], v[168:171], v[96:99]
	v_mfma_f32_16x16x32_bf16 v[124:127], v[108:111], v[186:189], v[124:127]
	v_mfma_f32_16x16x32_bf16 v[128:131], v[108:111], v[176:179], v[128:131]
	v_mfma_f32_16x16x32_bf16 v[132:135], v[108:111], v[172:175], v[132:135]
	v_mfma_f32_16x16x32_bf16 v[100:103], v[108:111], v[168:171], v[100:103]
	v_mfma_f32_16x16x32_bf16 v[108:111], v[22:25], v[186:189], v[136:139]
	v_mfma_f32_16x16x32_bf16 v[136:139], v[22:25], v[176:179], v[140:143]
	v_mfma_f32_16x16x32_bf16 v[140:143], v[22:25], v[172:175], v[144:147]
	v_mfma_f32_16x16x32_bf16 v[104:107], v[22:25], v[168:171], v[104:107]
	v_mfma_f32_16x16x32_bf16 v[4:7], v[18:21], v[186:189], v[4:7]
	v_mfma_f32_16x16x32_bf16 v[144:147], v[18:21], v[176:179], v[10:13]
	v_mfma_f32_16x16x32_bf16 v[148:151], v[18:21], v[172:175], v[14:17]
	v_mfma_f32_16x16x32_bf16 v[0:3], v[18:21], v[168:171], v[0:3]
	s_nop 0
	ds_read_b128 v[10:13], v9 offset:24576
	ds_read_b128 v[160:163], v9 offset:25600
	ds_read_b128 v[164:167], v9 offset:26624
	ds_read_b128 v[168:171], v9 offset:27648
	ds_read_b128 v[14:17], v8 offset:40960
	ds_read_b128 v[18:21], v8 offset:41984
	ds_read_b128 v[22:25], v8 offset:43008
	ds_read_b128 v[172:175], v8 offset:44032
	s_waitcnt lgkmcnt(3)
	v_mfma_f32_16x16x32_bf16 v[176:179], v[14:17], v[10:13], v[42:45]
	v_mfma_f32_16x16x32_bf16 v[186:189], v[14:17], v[160:163], v[46:49]
	v_mfma_f32_16x16x32_bf16 v[190:193], v[14:17], v[164:167], v[50:53]
	v_mfma_f32_16x16x32_bf16 v[194:197], v[14:17], v[168:171], v[26:29]
	s_waitcnt lgkmcnt(2)
	v_mfma_f32_16x16x32_bf16 v[224:227], v[18:21], v[10:13], v[54:57]
	v_mfma_f32_16x16x32_bf16 v[228:231], v[18:21], v[160:163], v[58:61]
	v_mfma_f32_16x16x32_bf16 v[232:235], v[18:21], v[164:167], v[62:65]
	v_mfma_f32_16x16x32_bf16 v[236:239], v[18:21], v[168:171], v[30:33]
	s_waitcnt lgkmcnt(1)
	v_mfma_f32_16x16x32_bf16 v[240:243], v[22:25], v[10:13], v[66:69]
	v_mfma_f32_16x16x32_bf16 v[64:67], v[22:25], v[168:171], v[34:37]
	s_waitcnt lgkmcnt(0)
	v_mfma_f32_16x16x32_bf16 v[40:43], v[172:175], v[164:167], v[92:95]
	v_mfma_f32_16x16x32_bf16 v[32:35], v[172:175], v[168:171], v[152:155]
	ds_read_b128 v[14:17], v8 offset:45056
	ds_read_b128 v[18:21], v8 offset:46080
	ds_read_b128 v[92:95], v8 offset:47104
	ds_read_b128 v[152:155], v8 offset:48128
	s_nop 0
	v_cvt_pk_bf16_f32 v64, v64, v65
	v_cvt_pk_bf16_f32 v65, v66, v67
	v_mfma_f32_16x16x32_bf16 v[80:83], v[22:25], v[160:163], v[70:73]
	v_cvt_pk_bf16_f32 v32, v32, v33
	v_cvt_pk_bf16_f32 v33, v34, v35
	v_cvt_pk_bf16_f32 v40, v40, v41
	v_mfma_f32_16x16x32_bf16 v[72:75], v[22:25], v[164:167], v[74:77]
	v_cvt_pk_bf16_f32 v41, v42, v43
	s_nop 2
	v_cvt_pk_bf16_f32 v80, v80, v81
	v_cvt_pk_bf16_f32 v81, v82, v83
	v_mfma_f32_16x16x32_bf16 v[48:51], v[172:175], v[160:163], v[84:87]
	s_waitcnt lgkmcnt(3)
	v_mfma_f32_16x16x32_bf16 v[112:115], v[14:17], v[10:13], v[112:115]
	v_cvt_pk_bf16_f32 v72, v72, v73
	v_cvt_pk_bf16_f32 v73, v74, v75
	s_nop 3
	v_cvt_pk_bf16_f32 v48, v48, v49
	v_mfma_f32_16x16x32_bf16 v[84:87], v[14:17], v[160:163], v[116:119]
	v_cvt_pk_bf16_f32 v49, v50, v51
	v_mfma_f32_16x16x32_bf16 v[76:79], v[14:17], v[164:167], v[120:123]
	v_mfma_f32_16x16x32_bf16 v[68:71], v[14:17], v[168:171], v[96:99]
	s_waitcnt lgkmcnt(2)
	v_mfma_f32_16x16x32_bf16 v[60:63], v[18:21], v[10:13], v[124:127]
	s_nop 0
	v_cvt_pk_bf16_f32 v96, v190, v191
	v_cvt_pk_bf16_f32 v97, v192, v193
	v_mfma_f32_16x16x32_bf16 v[52:55], v[18:21], v[160:163], v[128:131]
	v_mfma_f32_16x16x32_bf16 v[44:47], v[18:21], v[164:167], v[132:135]
	v_mfma_f32_16x16x32_bf16 v[36:39], v[18:21], v[168:171], v[100:103]
	s_waitcnt lgkmcnt(1)
; DI void st_bf4(u16* p, float a, float b, float c, float d) { *(uint2*)p = make_uint2(pk2(a, b), pk2(c, d)); }
; template <int BM, class Epi>
; DI void gemm_dma(const u16* __restrict__ X, long ldx, const u16* __restrict__ W, long ldw, int K, char* smem,
;                  int m0, int n0, const Epi& epi) {
;     ...
;       for (int i = 0; i < 4; ++i)
; #pragma unroll
;         for (int mt = 0; mt < MT; ++mt)
;           acc[nh * 4 + i][mt] = __builtin_amdgcn_mfma_f32_16x16x32_bf16(wf[i], xf[mt], acc[nh * 4 + i][mt], 0, 0, 0);
;     }
;   } while (++kt < nk);
;     ...
;   epi.run(acc, m0 + xrow0 + lr, n0 + wrow0 + 4 * g);
;   template <int NT, int MT> DI void run(f32x4 (&acc)[NT][MT], int mb, int nb) const {
; #pragma unroll
;     for (int nt = 0; nt < NT; ++nt)
; #pragma unroll
;       for (int mt = 0; mt < MT; ++mt) {
;         f32x4 v = acc[nt][mt];
;         st_bf4(C + (size_t)(mb + mt * 16) * ldc + nb + nt * 16, v[0], v[1], v[2], v[3]);
;       }
;   }
	v_mfma_f32_16x16x32_bf16 v[28:31], v[92:95], v[10:13], v[108:111]
	v_mfma_f32_16x16x32_bf16 v[24:27], v[92:95], v[160:163], v[136:139]
	v_mfma_f32_16x16x32_bf16 v[20:23], v[92:95], v[164:167], v[140:143]
	s_nop 5
	v_cvt_pk_bf16_f32 v28, v28, v29
	v_cvt_pk_bf16_f32 v29, v30, v31
	v_cvt_pk_bf16_f32 v24, v24, v25
	v_mfma_f32_16x16x32_bf16 v[16:19], v[92:95], v[168:171], v[104:107]
	v_or_b32_e32 v92, v90, v89
	v_ashrrev_i32_e32 v93, 31, v92
	v_lshlrev_b64 v[90:91], 11, v[92:93]
	v_lshl_add_u64 v[90:91], s[92:93], 0, v[90:91]
	v_lshl_add_u64 v[88:89], v[90:91], 0, v[182:183]
	v_cvt_pk_bf16_f32 v90, v176, v177
	v_cvt_pk_bf16_f32 v91, v178, v179
	global_store_dwordx2 v[88:89], v[90:91], off
	v_or_b32_e32 v90, 16, v92
	v_ashrrev_i32_e32 v91, 31, v90
	v_lshlrev_b64 v[90:91], 11, v[90:91]
	v_lshl_add_u64 v[90:91], s[92:93], 0, v[90:91]
	v_lshl_add_u64 v[90:91], v[90:91], 0, v[182:183]
	v_cvt_pk_bf16_f32 v94, v186, v187
	v_cvt_pk_bf16_f32 v95, v188, v189
	global_store_dwordx2 v[90:91], v[94:95], off
	v_or_b32_e32 v94, 32, v92
	v_or_b32_e32 v92, 48, v92
	v_ashrrev_i32_e32 v93, 31, v92
	v_lshlrev_b64 v[92:93], 11, v[92:93]
	v_ashrrev_i32_e32 v95, 31, v94
	v_lshl_add_u64 v[92:93], s[92:93], 0, v[92:93]
	v_lshlrev_b64 v[94:95], 11, v[94:95]
	v_lshl_add_u64 v[92:93], v[92:93], 0, v[182:183]
	v_lshl_add_u64 v[94:95], s[92:93], 0, v[94:95]
	global_store_dwordx2 v[92:93], v[32:33], off offset:96
	v_cvt_pk_bf16_f32 v32, v112, v113
	v_cvt_pk_bf16_f32 v33, v114, v115
	v_lshl_add_u64 v[94:95], v[94:95], 0, v[182:183]
	global_store_dwordx2 v[88:89], v[32:33], off offset:128
	v_cvt_pk_bf16_f32 v32, v84, v85
	v_cvt_pk_bf16_f32 v33, v86, v87
	global_store_dwordx2 v[94:95], v[96:97], off
	v_cvt_pk_bf16_f32 v96, v194, v195
	v_cvt_pk_bf16_f32 v97, v196, v197
	global_store_dwordx2 v[90:91], v[32:33], off offset:128
	v_cvt_pk_bf16_f32 v32, v76, v77
	v_cvt_pk_bf16_f32 v33, v78, v79
	v_mfma_f32_16x16x32_bf16 v[56:59], v[172:175], v[10:13], v[156:159]
	global_store_dwordx2 v[92:93], v[96:97], off
	v_cvt_pk_bf16_f32 v96, v224, v225
	v_cvt_pk_bf16_f32 v97, v226, v227
	s_waitcnt lgkmcnt(0)
	v_mfma_f32_16x16x32_bf16 v[12:15], v[152:155], v[10:13], v[4:7]
	global_store_dwordx2 v[94:95], v[32:33], off offset:128
	v_cvt_pk_bf16_f32 v32, v68, v69
	v_cvt_pk_bf16_f32 v33, v70, v71
	v_mfma_f32_16x16x32_bf16 v[8:11], v[152:155], v[160:163], v[144:147]
	global_store_dwordx2 v[88:89], v[96:97], off offset:32
	v_cvt_pk_bf16_f32 v96, v228, v229
	v_cvt_pk_bf16_f32 v97, v230, v231
	v_mfma_f32_16x16x32_bf16 v[4:7], v[152:155], v[164:167], v[148:151]
	global_store_dwordx2 v[92:93], v[32:33], off offset:128
	v_cvt_pk_bf16_f32 v32, v60, v61
	v_cvt_pk_bf16_f32 v33, v62, v63
	v_mfma_f32_16x16x32_bf16 v[0:3], v[152:155], v[168:171], v[0:3]
	global_store_dwordx2 v[90:91], v[96:97], off offset:32
	v_cvt_pk_bf16_f32 v96, v232, v233
	v_cvt_pk_bf16_f32 v97, v234, v235
	global_store_dwordx2 v[88:89], v[32:33], off offset:160
	v_cvt_pk_bf16_f32 v32, v52, v53
	v_cvt_pk_bf16_f32 v33, v54, v55
	global_store_dwordx2 v[94:95], v[96:97], off offset:32
	v_cvt_pk_bf16_f32 v96, v236, v237
	v_cvt_pk_bf16_f32 v97, v238, v239
	global_store_dwordx2 v[90:91], v[32:33], off offset:160
	v_cvt_pk_bf16_f32 v32, v44, v45
	v_cvt_pk_bf16_f32 v33, v46, v47
	global_store_dwordx2 v[92:93], v[96:97], off offset:32
	v_cvt_pk_bf16_f32 v96, v240, v241
	v_cvt_pk_bf16_f32 v97, v242, v243
	v_cvt_pk_bf16_f32 v56, v56, v57
	v_cvt_pk_bf16_f32 v57, v58, v59
	global_store_dwordx2 v[94:95], v[32:33], off offset:160
	v_cvt_pk_bf16_f32 v32, v36, v37
	v_cvt_pk_bf16_f32 v33, v38, v39
	v_cvt_pk_bf16_f32 v25, v26, v27
	v_cvt_pk_bf16_f32 v20, v20, v21
	v_cvt_pk_bf16_f32 v21, v22, v23
	v_cvt_pk_bf16_f32 v16, v16, v17
	v_cvt_pk_bf16_f32 v17, v18, v19
	v_cvt_pk_bf16_f32 v12, v12, v13
	v_cvt_pk_bf16_f32 v13, v14, v15
	v_cvt_pk_bf16_f32 v8, v8, v9
	v_cvt_pk_bf16_f32 v9, v10, v11
	v_cvt_pk_bf16_f32 v4, v4, v5
	v_cvt_pk_bf16_f32 v5, v6, v7
	v_cvt_pk_bf16_f32 v0, v0, v1
	v_cvt_pk_bf16_f32 v1, v2, v3
	global_store_dwordx2 v[88:89], v[96:97], off offset:64
	global_store_dwordx2 v[90:91], v[80:81], off offset:64
	global_store_dwordx2 v[94:95], v[72:73], off offset:64
	global_store_dwordx2 v[92:93], v[64:65], off offset:64
	global_store_dwordx2 v[88:89], v[56:57], off offset:96
	global_store_dwordx2 v[90:91], v[48:49], off offset:96
	global_store_dwordx2 v[94:95], v[40:41], off offset:96
	global_store_dwordx2 v[92:93], v[32:33], off offset:160
	global_store_dwordx2 v[88:89], v[28:29], off offset:192
	global_store_dwordx2 v[90:91], v[24:25], off offset:192
	global_store_dwordx2 v[94:95], v[20:21], off offset:192
	global_store_dwordx2 v[92:93], v[16:17], off offset:192
	global_store_dwordx2 v[88:89], v[12:13], off offset:224
	global_store_dwordx2 v[90:91], v[8:9], off offset:224
	global_store_dwordx2 v[94:95], v[4:5], off offset:224
	global_store_dwordx2 v[92:93], v[0:1], off offset:224

; template <int MT, class Epi>
; DI void gemm_tile(const u16* __restrict__ X, long ldx, const u16* __restrict__ W, long ldw, int K, char* smem,
;                   int m0, int n0, const Epi& epi, bool pre = false, const u16* Xn = nullptr, const u16* Wn = nullptr) {
;     ...
;   const int wu = __builtin_amdgcn_readfirstlane(wave);
;   const unsigned sbase = (unsigned)__builtin_amdgcn_readfirstlane((int)(unsigned)(size_t)smem);
;   const int r8 = lane >> 3, c0 = (lane & 7) ^ (r8 >> 1);
;   const long oxe = (long)(wu * MT * 8 + r8) * ldx + (c0 << 3), oxo = (long)(wu * MT * 8 + r8) * ldx + ((c0 ^ 4) << 3);
;   const long owe = (long)(wu * 32 + r8) * ldw + (c0 << 3), owo = (long)(wu * 32 + r8) * ldw + ((c0 ^ 4) << 3);
;   const u16 *xe = X + oxe, *xo = X + oxo, *we = W + owe, *wo = W + owo;
;   const long ldx8 = 8 * ldx, ldw8 = 8 * ldw;
;   const unsigned xdst = sbase + wu * MT * 1024, wdst = sbase + 16384 + wu * 4096;
;     ...
;   if (!pre) {
;     __syncthreads();
;     GT_DMA(0u)
; DI void phase_odd(const Params& p, int o, int sub, char* smem) {
;     ...
;       if (t < 1584) {
;         const int tm = t / 12, tn = t % 12;
;         const int t2 = t + gridDim.x, tm2 = t2 / 12, tn2 = t2 % 12;
;         const bool nx = t2 < 1584;
;         gemm_tile<4>(qn + (size_t)tm * 128 * 384, 384, W + WO_Q + (size_t)tn * 128 * 384, 384, 384, smem, tm * 128, tn * 128, eq, pre,
;                      nx ? qn + (size_t)tm2 * 128 * 384 : nullptr, W + WO_Q + (size_t)tn2 * 128 * 384);
;         pre = nx;
.LBB0_986:
	s_mul_hi_i32 s6, s5, 0x2aaaaaab
	s_lshr_b32 s9, s6, 31
	s_ashr_i32 s6, s6, 1
	s_add_i32 s6, s6, s9
	s_mul_i32 s9, s6, 12
	s_xor_b64 s[12:13], s[40:41], -1
	s_sub_i32 s5, s5, s9
	s_mul_i32 s10, s6, 0x18000
	s_mul_hi_i32 s9, s6, 0x18000
	s_add_u32 s10, s88, s10
	s_mul_i32 s14, s5, 0xc000
	v_mov_b32_e32 v14, v185
	s_addc_u32 s11, s89, s9
	s_ashr_i32 s15, s14, 31
	s_lshl_b64 s[14:15], s[14:15], 1
	v_ashrrev_i32_e32 v1, 6, v14
	v_readlane_b32 s16, v252, 29
	v_bfe_u32 v68, v14, 4, 2
	v_readfirstlane_b32 s9, v1
	v_bfe_u32 v2, v14, 3, 3
	v_readlane_b32 s17, v252, 30
	s_add_u32 s14, s16, s14
	v_bitop3_b32 v4, v68, v14, 7 bitop3:0x78
	v_lshl_or_b32 v2, s9, 5, v2
	s_movk_i32 s16, 0x180
	s_addc_u32 s15, s17, s15
	v_mad_i64_i32 v[2:3], s[16:17], v2, s16, 0
	v_lshlrev_b32_e32 v6, 3, v4
	v_or_b32_e32 v4, v2, v6
	v_mov_b32_e32 v5, v3
	v_bitop3_b32 v2, v2, v6, 32 bitop3:0xf6
	v_lshlrev_b64 v[64:65], 1, v[4:5]
	v_lshlrev_b64 v[66:67], 1, v[2:3]
	v_lshl_add_u64 v[10:11], s[10:11], 0, v[64:65]
	v_lshl_add_u64 v[8:9], s[10:11], 0, v[66:67]
	s_lshl_b32 s10, s9, 12
	v_mov_b32_e32 v0, v183
	v_lshl_add_u64 v[6:7], s[14:15], 0, v[64:65]
	v_lshl_add_u64 v[4:5], s[14:15], 0, v[66:67]
	s_add_i32 s9, s10, 0x4000
	s_mov_b64 s[40:41], -1
	s_and_b64 vcc, exec, s[12:13]
	s_cbranch_vccz .LBB0_988
	s_barrier
	s_mov_b32 m0, s10
	s_nop 0
	global_load_lds_dwordx4 v[10:11], off
	s_mov_b64 s[18:19], 0x1800
	v_lshl_add_u64 v[2:3], v[8:9], 0, s[18:19]
	s_add_i32 s11, s10, 0x400
	s_mov_b32 m0, s11
	s_nop 0
	global_load_lds_dwordx4 v[2:3], off
	s_mov_b64 s[16:17], 0x3000
	v_lshl_add_u64 v[2:3], v[10:11], 0, s[16:17]
	s_add_i32 s12, s10, 0x800
	s_mov_b32 m0, s12
	s_nop 0
	global_load_lds_dwordx4 v[2:3], off
	s_mov_b64 s[20:21], 0x4800
	v_lshl_add_u64 v[2:3], v[8:9], 0, s[20:21]
	s_add_i32 s13, s10, 0xc00
	s_mov_b32 m0, s13
	s_nop 0
	global_load_lds_dwordx4 v[2:3], off
	v_lshl_add_u64 v[2:3], v[4:5], 0, s[18:19]
	s_mov_b32 m0, s9
	s_nop 0
	global_load_lds_dwordx4 v[6:7], off
	s_add_i32 s14, s10, 0x4400
	s_mov_b32 m0, s14
	s_nop 0
	global_load_lds_dwordx4 v[2:3], off
	v_lshl_add_u64 v[2:3], v[6:7], 0, s[16:17]
	s_add_i32 s15, s10, 0x4800
	s_mov_b32 m0, s15
	s_nop 0
	global_load_lds_dwordx4 v[2:3], off
	v_lshl_add_u64 v[2:3], v[4:5], 0, s[20:21]
	s_add_i32 s16, s10, 0x4c00
	s_mov_b32 m0, s16
	s_nop 0
	global_load_lds_dwordx4 v[2:3], off
	s_mov_b64 s[40:41], 0

; template <int MT, class Epi>
; DI void gemm_tile(const u16* __restrict__ X, long ldx, const u16* __restrict__ W, long ldw, int K, char* smem,
;                   int m0, int n0, const Epi& epi, bool pre = false, const u16* Xn = nullptr, const u16* Wn = nullptr) {
;     ...
;   do {
;     asm volatile("s_waitcnt vmcnt(0)" ::: "memory");
;     __syncthreads();
;     if (kt + 1 < nk) GT_DMA((unsigned)((kt + 1) & 1) * 32768u)
;     else if (Xn != nullptr) { xe = Xn + oxe; xo = Xn + oxo; we = Wn + owe; wo = Wn + owo; GT_DMA(0u) }
;     const char* cur = smem + (kt & 1) * 32768;
; #pragma unroll
;     for (int ks = 0; ks < 2; ++ks) {
;       bf16x8 xf[MT], wf[4];
;       const int ch = ((ks * 4 + g) ^ rsw) << 4;
; #pragma unroll
;       for (int i = 0; i < MT; ++i) xf[i] = *(const bf16x8*)(cur + (wm * 16 * MT + i * 16 + lr) * 128 + ch);
; #pragma unroll
;       for (int i = 0; i < 4; ++i) wf[i] = *(const bf16x8*)(cur + 16384 + (wn * 64 + i * 16 + lr) * 128 + ch);
; #pragma unroll
;       for (int nt = 0; nt < 4; ++nt)
; #pragma unroll
;         for (int mt = 0; mt < MT; ++mt)
;           acc[nt][mt] = __builtin_amdgcn_mfma_f32_16x16x32_bf16(wf[nt], xf[mt], acc[nt][mt], 0, 0, 0);
.LBB0_990:
	s_add_i32 s45, s10, 0x8000
	s_waitcnt vmcnt(0)
	s_barrier
	v_lshl_add_u64 v[12:13], v[10:11], 0, s[28:29]
	s_mov_b32 m0, s45
	s_nop 0
	global_load_lds_dwordx4 v[12:13], off
	s_mov_b64 s[20:21], 0x1880
	s_add_i32 s44, s10, 0x8400
	v_lshl_add_u64 v[12:13], v[8:9], 0, s[20:21]
	s_mov_b32 m0, s44
	s_nop 0
	global_load_lds_dwordx4 v[12:13], off
	s_mov_b64 s[22:23], 0x3080
	s_add_i32 s41, s10, 0x8800
	v_lshl_add_u64 v[12:13], v[10:11], 0, s[22:23]
	s_mov_b32 m0, s41
	s_nop 0
	global_load_lds_dwordx4 v[12:13], off
	s_mov_b64 s[48:49], 0x4880
	v_and_b32_e32 v70, 1, v1
	v_lshrrev_b32_e32 v1, 1, v14
	s_add_i32 s34, s10, 0x8c00
	v_lshl_add_u64 v[12:13], v[8:9], 0, s[48:49]
	s_mov_b32 m0, s34
	s_nop 0
	global_load_lds_dwordx4 v[12:13], off
	v_ashrrev_i32_e32 v71, 7, v14
	s_add_i32 s40, s10, 0xc000
	v_lshl_add_u64 v[2:3], v[6:7], 0, s[28:29]
	s_mov_b32 m0, s40
	s_nop 0
	global_load_lds_dwordx4 v[2:3], off
	v_bitop3_b32 v1, v68, v1, 7 bitop3:0x78
	v_and_b32_e32 v69, 15, v14
	s_add_i32 s19, s10, 0xc400
	v_lshl_add_u64 v[2:3], v[4:5], 0, s[20:21]
	s_mov_b32 m0, s19
	s_nop 0
	global_load_lds_dwordx4 v[2:3], off
	v_lshlrev_b32_e32 v1, 4, v1
	v_lshlrev_b32_e32 v15, 13, v71
	s_add_i32 s18, s10, 0xc800
	v_lshl_add_u64 v[2:3], v[6:7], 0, s[22:23]
	s_mov_b32 m0, s18
	s_nop 0
	global_load_lds_dwordx4 v[2:3], off
	v_lshlrev_b32_e32 v72, 7, v69
	v_or_b32_e32 v73, v1, v15
	s_add_i32 s17, s10, 0xcc00
	v_lshl_add_u64 v[2:3], v[4:5], 0, s[48:49]
	s_mov_b32 m0, s17
	s_nop 0
	global_load_lds_dwordx4 v[2:3], off
	v_or_b32_e32 v12, v73, v72
	s_waitcnt vmcnt(7)
	ds_read_b128 v[16:19], v12 offset:16384
	ds_read_b128 v[48:51], v12 offset:18432
	ds_read_b128 v[82:85], v12 offset:20480
	s_waitcnt vmcnt(0)
	ds_read_b128 v[98:101], v12 offset:22528
	v_lshlrev_b32_e32 v53, 13, v70
	v_bfe_u32 v14, v14, 1, 3
	v_or_b32_e32 v74, v1, v53
	v_bitop3_b32 v14, v68, v14, 4 bitop3:0x36
	v_or_b32_e32 v13, v74, v72
	v_lshlrev_b32_e32 v14, 4, v14
	ds_read_b128 v[20:23], v13
	ds_read_b128 v[28:31], v13 offset:2048
	ds_read_b128 v[36:39], v13 offset:4096
	ds_read_b128 v[44:47], v13 offset:6144
	v_or_b32_e32 v75, v14, v15
	v_or_b32_e32 v52, v75, v72
	ds_read_b128 v[102:105], v52 offset:16384
	v_mov_b32_e32 v1, v0
	v_mov_b32_e32 v2, v0
	v_mov_b32_e32 v3, v0
	v_or_b32_e32 v76, v14, v53
	s_mov_b64 s[20:21], 0x100
	s_waitcnt lgkmcnt(4)
	v_mfma_f32_16x16x32_bf16 v[24:27], v[16:19], v[20:23], v[0:3]
	s_mov_b64 s[22:23], 0x3100
	s_mov_b64 s[48:49], 0x4900
	s_cmp_eq_u64 s[42:43], 0
	s_waitcnt lgkmcnt(3)
	v_mfma_f32_16x16x32_bf16 v[32:35], v[16:19], v[28:31], v[0:3]
	s_waitcnt lgkmcnt(2)
	v_mfma_f32_16x16x32_bf16 v[40:43], v[16:19], v[36:39], v[0:3]
	s_waitcnt lgkmcnt(1)
	v_mfma_f32_16x16x32_bf16 v[16:19], v[16:19], v[44:47], v[0:3]
	v_mfma_f32_16x16x32_bf16 v[54:57], v[48:51], v[20:23], v[0:3]
	v_mfma_f32_16x16x32_bf16 v[58:61], v[48:51], v[28:31], v[0:3]
	v_mfma_f32_16x16x32_bf16 v[78:81], v[48:51], v[36:39], v[0:3]
	v_mfma_f32_16x16x32_bf16 v[48:51], v[48:51], v[44:47], v[0:3]
	v_mfma_f32_16x16x32_bf16 v[86:89], v[82:85], v[20:23], v[0:3]
	v_mfma_f32_16x16x32_bf16 v[90:93], v[82:85], v[28:31], v[0:3]
	v_mfma_f32_16x16x32_bf16 v[94:97], v[82:85], v[36:39], v[0:3]
	v_mfma_f32_16x16x32_bf16 v[82:85], v[82:85], v[44:47], v[0:3]
	v_mfma_f32_16x16x32_bf16 v[20:23], v[98:101], v[20:23], v[0:3]
	v_mfma_f32_16x16x32_bf16 v[28:31], v[98:101], v[28:31], v[0:3]
	v_mfma_f32_16x16x32_bf16 v[36:39], v[98:101], v[36:39], v[0:3]
	v_mfma_f32_16x16x32_bf16 v[44:47], v[98:101], v[44:47], v[0:3]
	s_nop 2
	v_or_b32_e32 v0, v76, v72
	ds_read_b128 v[98:101], v0
	ds_read_b128 v[106:109], v0 offset:2048
	ds_read_b128 v[110:113], v0 offset:4096
	ds_read_b128 v[114:117], v0 offset:6144
	s_waitcnt lgkmcnt(3)
	v_mfma_f32_16x16x32_bf16 v[24:27], v[102:105], v[98:101], v[24:27]
	v_lshl_add_u64 v[2:3], v[10:11], 0, s[20:21]
	s_waitcnt lgkmcnt(2)
	v_mfma_f32_16x16x32_bf16 v[32:35], v[102:105], v[106:109], v[32:35]
	s_waitcnt lgkmcnt(1)
	v_mfma_f32_16x16x32_bf16 v[40:43], v[102:105], v[110:113], v[40:43]
	s_waitcnt lgkmcnt(0)
	v_mfma_f32_16x16x32_bf16 v[14:17], v[102:105], v[114:117], v[16:19]
	ds_read_b128 v[102:105], v52 offset:18432
	s_waitcnt lgkmcnt(0)
	v_mfma_f32_16x16x32_bf16 v[54:57], v[102:105], v[98:101], v[54:57]
	v_mfma_f32_16x16x32_bf16 v[58:61], v[102:105], v[106:109], v[58:61]
	v_mfma_f32_16x16x32_bf16 v[78:81], v[102:105], v[110:113], v[78:81]
	v_mfma_f32_16x16x32_bf16 v[48:51], v[102:105], v[114:117], v[48:51]
	ds_read_b128 v[102:105], v52 offset:20480
	s_waitcnt lgkmcnt(0)
	v_mfma_f32_16x16x32_bf16 v[86:89], v[102:105], v[98:101], v[86:89]
	v_mfma_f32_16x16x32_bf16 v[90:93], v[102:105], v[106:109], v[90:93]
	v_mfma_f32_16x16x32_bf16 v[94:97], v[102:105], v[110:113], v[94:97]
	v_mfma_f32_16x16x32_bf16 v[82:85], v[102:105], v[114:117], v[82:85]
	ds_read_b128 v[102:105], v52 offset:22528
	s_waitcnt vmcnt(0)
	s_waitcnt lgkmcnt(0)
	v_mfma_f32_16x16x32_bf16 v[18:21], v[102:105], v[98:101], v[20:23]
	s_nop 2
	v_lshl_add_u64 v[22:23], v[6:7], 0, s[20:21]
	s_barrier
; template <int MT, class Epi>
; DI void gemm_tile(const u16* __restrict__ X, long ldx, const u16* __restrict__ W, long ldw, int K, char* smem,
;                   int m0, int n0, const Epi& epi, bool pre = false, const u16* Xn = nullptr, const u16* Wn = nullptr) {
;     ...
;   do {
;     asm volatile("s_waitcnt vmcnt(0)" ::: "memory");
;     __syncthreads();
;     if (kt + 1 < nk) GT_DMA((unsigned)((kt + 1) & 1) * 32768u)
;     else if (Xn != nullptr) { xe = Xn + oxe; xo = Xn + oxo; we = Wn + owe; wo = Wn + owo; GT_DMA(0u) }
;     const char* cur = smem + (kt & 1) * 32768;
; #pragma unroll
;     for (int ks = 0; ks < 2; ++ks) {
;       bf16x8 xf[MT], wf[4];
;       const int ch = ((ks * 4 + g) ^ rsw) << 4;
; #pragma unroll
;       for (int i = 0; i < MT; ++i) xf[i] = *(const bf16x8*)(cur + (wm * 16 * MT + i * 16 + lr) * 128 + ch);
; #pragma unroll
;       for (int i = 0; i < 4; ++i) wf[i] = *(const bf16x8*)(cur + 16384 + (wn * 64 + i * 16 + lr) * 128 + ch);
; #pragma unroll
;       for (int nt = 0; nt < 4; ++nt)
; #pragma unroll
;         for (int mt = 0; mt < MT; ++mt)
;           acc[nt][mt] = __builtin_amdgcn_mfma_f32_16x16x32_bf16(wf[nt], xf[mt], acc[nt][mt], 0, 0, 0);
	s_mov_b32 m0, s10
	s_nop 0
	global_load_lds_dwordx4 v[2:3], off
	s_mov_b64 s[20:21], 0x1900
	v_lshl_add_u64 v[2:3], v[8:9], 0, s[20:21]
	s_mov_b32 m0, s11
	s_nop 0
	global_load_lds_dwordx4 v[2:3], off
	v_lshl_add_u64 v[2:3], v[10:11], 0, s[22:23]
	s_mov_b32 m0, s12
	s_nop 0
	global_load_lds_dwordx4 v[2:3], off
	v_lshl_add_u64 v[2:3], v[8:9], 0, s[48:49]
	s_mov_b32 m0, s13
	s_nop 0
	global_load_lds_dwordx4 v[2:3], off
	v_lshl_add_u64 v[2:3], v[4:5], 0, s[20:21]
	s_mov_b32 m0, s9
	s_nop 0
	global_load_lds_dwordx4 v[22:23], off
	v_mfma_f32_16x16x32_bf16 v[28:31], v[102:105], v[106:109], v[28:31]
	s_mov_b32 m0, s14
	s_nop 0
	global_load_lds_dwordx4 v[2:3], off
	v_lshl_add_u64 v[2:3], v[6:7], 0, s[22:23]
	s_mov_b32 m0, s15
	s_nop 0
	global_load_lds_dwordx4 v[2:3], off
	v_lshl_add_u64 v[2:3], v[4:5], 0, s[48:49]
	s_mov_b32 m0, s16
	s_nop 0
	global_load_lds_dwordx4 v[2:3], off
	ds_read_b128 v[98:101], v12 offset:49152
	v_mfma_f32_16x16x32_bf16 v[36:39], v[102:105], v[110:113], v[36:39]
	ds_read_b128 v[106:109], v13 offset:34816
	ds_read_b128 v[110:113], v13 offset:36864
	s_mov_b64 s[20:21], 0x180
	v_mfma_f32_16x16x32_bf16 v[44:47], v[102:105], v[114:117], v[44:47]
	ds_read_b128 v[102:105], v13 offset:32768
	ds_read_b128 v[114:117], v13 offset:38912
	v_lshl_add_u64 v[2:3], v[10:11], 0, s[20:21]
	s_waitcnt lgkmcnt(1)
	v_mfma_f32_16x16x32_bf16 v[22:25], v[98:101], v[102:105], v[24:27]
	v_lshl_add_u64 v[62:63], v[6:7], 0, s[20:21]
	s_mov_b64 s[20:21], 0x1980
	s_mov_b64 s[22:23], 0x3180
	v_mfma_f32_16x16x32_bf16 v[32:35], v[98:101], v[106:109], v[32:35]
	s_mov_b64 s[48:49], 0x4980
	v_mfma_f32_16x16x32_bf16 v[40:43], v[98:101], v[110:113], v[40:43]
	s_waitcnt lgkmcnt(0)
	v_mfma_f32_16x16x32_bf16 v[14:17], v[98:101], v[114:117], v[14:17]
	ds_read_b128 v[98:101], v12 offset:51200
	s_waitcnt lgkmcnt(0)
	v_mfma_f32_16x16x32_bf16 v[54:57], v[98:101], v[102:105], v[54:57]
	v_mfma_f32_16x16x32_bf16 v[58:61], v[98:101], v[106:109], v[58:61]
	v_mfma_f32_16x16x32_bf16 v[78:81], v[98:101], v[110:113], v[78:81]
	v_mfma_f32_16x16x32_bf16 v[48:51], v[98:101], v[114:117], v[48:51]
	ds_read_b128 v[98:101], v12 offset:53248
	s_waitcnt lgkmcnt(0)
	v_mfma_f32_16x16x32_bf16 v[86:89], v[98:101], v[102:105], v[86:89]
	v_mfma_f32_16x16x32_bf16 v[90:93], v[98:101], v[106:109], v[90:93]
	v_mfma_f32_16x16x32_bf16 v[94:97], v[98:101], v[110:113], v[94:97]
	v_mfma_f32_16x16x32_bf16 v[82:85], v[98:101], v[114:117], v[82:85]
	ds_read_b128 v[98:101], v12 offset:55296
	s_waitcnt lgkmcnt(0)
	v_mfma_f32_16x16x32_bf16 v[18:21], v[98:101], v[102:105], v[18:21]
	ds_read_b128 v[102:105], v52 offset:49152
	v_mfma_f32_16x16x32_bf16 v[26:29], v[98:101], v[106:109], v[28:31]
	ds_read_b128 v[106:109], v0 offset:34816
	v_mfma_f32_16x16x32_bf16 v[36:39], v[98:101], v[110:113], v[36:39]
	ds_read_b128 v[110:113], v0 offset:36864
	v_mfma_f32_16x16x32_bf16 v[44:47], v[98:101], v[114:117], v[44:47]
	ds_read_b128 v[98:101], v0 offset:32768
	ds_read_b128 v[114:117], v0 offset:38912
	s_waitcnt lgkmcnt(1)
	v_mfma_f32_16x16x32_bf16 v[22:25], v[102:105], v[98:101], v[22:25]
	v_mfma_f32_16x16x32_bf16 v[30:33], v[102:105], v[106:109], v[32:35]
	v_mfma_f32_16x16x32_bf16 v[40:43], v[102:105], v[110:113], v[40:43]
	s_waitcnt lgkmcnt(0)
	v_mfma_f32_16x16x32_bf16 v[14:17], v[102:105], v[114:117], v[14:17]
	ds_read_b128 v[102:105], v52 offset:51200
	s_waitcnt lgkmcnt(0)
	v_mfma_f32_16x16x32_bf16 v[54:57], v[102:105], v[98:101], v[54:57]
	v_mfma_f32_16x16x32_bf16 v[58:61], v[102:105], v[106:109], v[58:61]
	v_mfma_f32_16x16x32_bf16 v[78:81], v[102:105], v[110:113], v[78:81]
	v_mfma_f32_16x16x32_bf16 v[48:51], v[102:105], v[114:117], v[48:51]
	ds_read_b128 v[102:105], v52 offset:53248
	s_waitcnt lgkmcnt(0)
	v_mfma_f32_16x16x32_bf16 v[86:89], v[102:105], v[98:101], v[86:89]
	v_mfma_f32_16x16x32_bf16 v[90:93], v[102:105], v[106:109], v[90:93]
	v_mfma_f32_16x16x32_bf16 v[94:97], v[102:105], v[110:113], v[94:97]
	v_mfma_f32_16x16x32_bf16 v[82:85], v[102:105], v[114:117], v[82:85]
	ds_read_b128 v[102:105], v52 offset:55296
	s_waitcnt vmcnt(0)
	s_waitcnt lgkmcnt(0)
	s_barrier
	s_mov_b32 m0, s45
	s_nop 0
	global_load_lds_dwordx4 v[2:3], off
	v_lshl_add_u64 v[2:3], v[8:9], 0, s[20:21]
	s_mov_b32 m0, s44
	s_nop 0
	global_load_lds_dwordx4 v[2:3], off
	v_lshl_add_u64 v[2:3], v[10:11], 0, s[22:23]
	s_mov_b32 m0, s41
	s_nop 0
	global_load_lds_dwordx4 v[2:3], off
	v_lshl_add_u64 v[2:3], v[8:9], 0, s[48:49]
	s_mov_b32 m0, s34
	s_nop 0
	global_load_lds_dwordx4 v[2:3], off
	v_lshl_add_u64 v[2:3], v[4:5], 0, s[20:21]
	s_mov_b32 m0, s40
	s_nop 0
	global_load_lds_dwordx4 v[62:63], off
	v_mfma_f32_16x16x32_bf16 v[18:21], v[102:105], v[98:101], v[18:21]
	s_mov_b32 m0, s19
	s_nop 0
	global_load_lds_dwordx4 v[2:3], off
	v_lshl_add_u64 v[2:3], v[6:7], 0, s[22:23]
	s_mov_b32 m0, s18
	s_nop 0
	global_load_lds_dwordx4 v[2:3], off
	v_lshl_add_u64 v[2:3], v[4:5], 0, s[48:49]
	s_mov_b32 m0, s17
	s_nop 0
	global_load_lds_dwordx4 v[2:3], off
	ds_read_b128 v[98:101], v12 offset:16384
	v_mfma_f32_16x16x32_bf16 v[26:29], v[102:105], v[106:109], v[26:29]
	ds_read_b128 v[106:109], v13 offset:2048
	s_mov_b64 s[20:21], 0x200
	v_lshl_add_u64 v[2:3], v[10:11], 0, s[20:21]
	v_mfma_f32_16x16x32_bf16 v[34:37], v[102:105], v[110:113], v[36:39]
	ds_read_b128 v[110:113], v13 offset:4096
	s_mov_b64 s[22:23], 0x3200
	s_mov_b64 s[48:49], 0x4a00
	v_mfma_f32_16x16x32_bf16 v[44:47], v[102:105], v[114:117], v[44:47]
	ds_read_b128 v[102:105], v13
	ds_read_b128 v[114:117], v13 offset:6144
	s_waitcnt lgkmcnt(1)
	v_mfma_f32_16x16x32_bf16 v[22:25], v[98:101], v[102:105], v[22:25]
	v_mfma_f32_16x16x32_bf16 v[30:33], v[98:101], v[106:109], v[30:33]
	v_mfma_f32_16x16x32_bf16 v[38:41], v[98:101], v[110:113], v[40:43]
	s_waitcnt lgkmcnt(0)
; template <int MT, class Epi>
; DI void gemm_tile(const u16* __restrict__ X, long ldx, const u16* __restrict__ W, long ldw, int K, char* smem,
;                   int m0, int n0, const Epi& epi, bool pre = false, const u16* Xn = nullptr, const u16* Wn = nullptr) {
;     ...
;   do {
;     asm volatile("s_waitcnt vmcnt(0)" ::: "memory");
;     __syncthreads();
;     if (kt + 1 < nk) GT_DMA((unsigned)((kt + 1) & 1) * 32768u)
;     else if (Xn != nullptr) { xe = Xn + oxe; xo = Xn + oxo; we = Wn + owe; wo = Wn + owo; GT_DMA(0u) }
;     const char* cur = smem + (kt & 1) * 32768;
; #pragma unroll
;     for (int ks = 0; ks < 2; ++ks) {
;       bf16x8 xf[MT], wf[4];
;       const int ch = ((ks * 4 + g) ^ rsw) << 4;
; #pragma unroll
;       for (int i = 0; i < MT; ++i) xf[i] = *(const bf16x8*)(cur + (wm * 16 * MT + i * 16 + lr) * 128 + ch);
; #pragma unroll
;       for (int i = 0; i < 4; ++i) wf[i] = *(const bf16x8*)(cur + 16384 + (wn * 64 + i * 16 + lr) * 128 + ch);
; #pragma unroll
;       for (int nt = 0; nt < 4; ++nt)
; #pragma unroll
;         for (int mt = 0; mt < MT; ++mt)
;           acc[nt][mt] = __builtin_amdgcn_mfma_f32_16x16x32_bf16(wf[nt], xf[mt], acc[nt][mt], 0, 0, 0);
	v_mfma_f32_16x16x32_bf16 v[14:17], v[98:101], v[114:117], v[14:17]
	ds_read_b128 v[98:101], v12 offset:18432
	s_waitcnt lgkmcnt(0)
	v_mfma_f32_16x16x32_bf16 v[54:57], v[98:101], v[102:105], v[54:57]
	v_mfma_f32_16x16x32_bf16 v[58:61], v[98:101], v[106:109], v[58:61]
	v_mfma_f32_16x16x32_bf16 v[78:81], v[98:101], v[110:113], v[78:81]
	v_mfma_f32_16x16x32_bf16 v[48:51], v[98:101], v[114:117], v[48:51]
	ds_read_b128 v[98:101], v12 offset:20480
	s_waitcnt lgkmcnt(0)
	v_mfma_f32_16x16x32_bf16 v[86:89], v[98:101], v[102:105], v[86:89]
	v_mfma_f32_16x16x32_bf16 v[90:93], v[98:101], v[106:109], v[90:93]
	v_mfma_f32_16x16x32_bf16 v[94:97], v[98:101], v[110:113], v[94:97]
	v_mfma_f32_16x16x32_bf16 v[82:85], v[98:101], v[114:117], v[82:85]
	ds_read_b128 v[98:101], v12 offset:22528
	s_waitcnt lgkmcnt(0)
	v_mfma_f32_16x16x32_bf16 v[18:21], v[98:101], v[102:105], v[18:21]
	ds_read_b128 v[102:105], v52 offset:16384
	v_mfma_f32_16x16x32_bf16 v[26:29], v[98:101], v[106:109], v[26:29]
	ds_read_b128 v[106:109], v0 offset:2048
	v_mfma_f32_16x16x32_bf16 v[34:37], v[98:101], v[110:113], v[34:37]
	ds_read_b128 v[110:113], v0 offset:4096
	v_mfma_f32_16x16x32_bf16 v[42:45], v[98:101], v[114:117], v[44:47]
	ds_read_b128 v[98:101], v0
	ds_read_b128 v[114:117], v0 offset:6144
	s_waitcnt lgkmcnt(1)
	v_mfma_f32_16x16x32_bf16 v[22:25], v[102:105], v[98:101], v[22:25]
	v_mfma_f32_16x16x32_bf16 v[30:33], v[102:105], v[106:109], v[30:33]
	v_mfma_f32_16x16x32_bf16 v[38:41], v[102:105], v[110:113], v[38:41]
	s_waitcnt lgkmcnt(0)
	v_mfma_f32_16x16x32_bf16 v[14:17], v[102:105], v[114:117], v[14:17]
	ds_read_b128 v[102:105], v52 offset:18432
	s_waitcnt lgkmcnt(0)
	v_mfma_f32_16x16x32_bf16 v[54:57], v[102:105], v[98:101], v[54:57]
	v_mfma_f32_16x16x32_bf16 v[58:61], v[102:105], v[106:109], v[58:61]
	v_mfma_f32_16x16x32_bf16 v[78:81], v[102:105], v[110:113], v[78:81]
	v_mfma_f32_16x16x32_bf16 v[46:49], v[102:105], v[114:117], v[48:51]
	ds_read_b128 v[102:105], v52 offset:20480
	s_waitcnt lgkmcnt(0)
	v_mfma_f32_16x16x32_bf16 v[86:89], v[102:105], v[98:101], v[86:89]
	v_lshl_add_u64 v[50:51], v[6:7], 0, s[20:21]
	s_mov_b64 s[20:21], 0x1a00
	v_mfma_f32_16x16x32_bf16 v[90:93], v[102:105], v[106:109], v[90:93]
	v_mfma_f32_16x16x32_bf16 v[94:97], v[102:105], v[110:113], v[94:97]
	v_mfma_f32_16x16x32_bf16 v[82:85], v[102:105], v[114:117], v[82:85]
	ds_read_b128 v[102:105], v52 offset:22528
	s_waitcnt vmcnt(0)
	s_waitcnt lgkmcnt(0)
	s_barrier
	s_mov_b32 m0, s10
	s_nop 0
	global_load_lds_dwordx4 v[2:3], off
	v_lshl_add_u64 v[2:3], v[8:9], 0, s[20:21]
	s_mov_b32 m0, s11
	s_nop 0
	global_load_lds_dwordx4 v[2:3], off
	v_lshl_add_u64 v[2:3], v[10:11], 0, s[22:23]
	s_mov_b32 m0, s12
	s_nop 0
	global_load_lds_dwordx4 v[2:3], off
	v_lshl_add_u64 v[2:3], v[8:9], 0, s[48:49]
	s_mov_b32 m0, s13
	s_nop 0
	global_load_lds_dwordx4 v[2:3], off
	v_lshl_add_u64 v[2:3], v[4:5], 0, s[20:21]
	s_mov_b32 m0, s9
	s_nop 0
	global_load_lds_dwordx4 v[50:51], off
	v_mfma_f32_16x16x32_bf16 v[18:21], v[102:105], v[98:101], v[18:21]
	s_mov_b32 m0, s14
	s_nop 0
	global_load_lds_dwordx4 v[2:3], off
	v_lshl_add_u64 v[2:3], v[6:7], 0, s[22:23]
	s_mov_b32 m0, s15
	s_nop 0
	global_load_lds_dwordx4 v[2:3], off
	v_lshl_add_u64 v[2:3], v[4:5], 0, s[48:49]
	s_mov_b32 m0, s16
	s_nop 0
	global_load_lds_dwordx4 v[2:3], off
	ds_read_b128 v[98:101], v12 offset:49152
	v_mfma_f32_16x16x32_bf16 v[26:29], v[102:105], v[106:109], v[26:29]
	ds_read_b128 v[106:109], v13 offset:34816
	s_mov_b64 s[20:21], 0x280
	v_lshl_add_u64 v[2:3], v[10:11], 0, s[20:21]
	v_mfma_f32_16x16x32_bf16 v[34:37], v[102:105], v[110:113], v[34:37]
	ds_read_b128 v[110:113], v13 offset:36864
	v_lshl_add_u64 v[50:51], v[6:7], 0, s[20:21]
	s_mov_b64 s[20:21], 0x1a80
	v_mfma_f32_16x16x32_bf16 v[42:45], v[102:105], v[114:117], v[42:45]
	ds_read_b128 v[102:105], v13 offset:32768
	ds_read_b128 v[114:117], v13 offset:38912
	s_mov_b64 s[22:23], 0x3280
	s_waitcnt lgkmcnt(1)
	v_mfma_f32_16x16x32_bf16 v[22:25], v[98:101], v[102:105], v[22:25]
	v_mfma_f32_16x16x32_bf16 v[30:33], v[98:101], v[106:109], v[30:33]
	v_mfma_f32_16x16x32_bf16 v[38:41], v[98:101], v[110:113], v[38:41]
	s_waitcnt lgkmcnt(0)
	v_mfma_f32_16x16x32_bf16 v[14:17], v[98:101], v[114:117], v[14:17]
	ds_read_b128 v[98:101], v12 offset:51200
	s_waitcnt lgkmcnt(0)
	v_mfma_f32_16x16x32_bf16 v[54:57], v[98:101], v[102:105], v[54:57]
	v_mfma_f32_16x16x32_bf16 v[58:61], v[98:101], v[106:109], v[58:61]
	v_mfma_f32_16x16x32_bf16 v[78:81], v[98:101], v[110:113], v[78:81]
	v_mfma_f32_16x16x32_bf16 v[46:49], v[98:101], v[114:117], v[46:49]
	ds_read_b128 v[98:101], v12 offset:53248
	s_waitcnt lgkmcnt(0)
	v_mfma_f32_16x16x32_bf16 v[86:89], v[98:101], v[102:105], v[86:89]
	v_mfma_f32_16x16x32_bf16 v[90:93], v[98:101], v[106:109], v[90:93]
	v_mfma_f32_16x16x32_bf16 v[94:97], v[98:101], v[110:113], v[94:97]
	v_mfma_f32_16x16x32_bf16 v[82:85], v[98:101], v[114:117], v[82:85]
	ds_read_b128 v[98:101], v12 offset:55296
	s_waitcnt lgkmcnt(0)
	v_mfma_f32_16x16x32_bf16 v[18:21], v[98:101], v[102:105], v[18:21]
	ds_read_b128 v[102:105], v52 offset:49152
	v_mfma_f32_16x16x32_bf16 v[26:29], v[98:101], v[106:109], v[26:29]
	ds_read_b128 v[106:109], v0 offset:34816
	v_mfma_f32_16x16x32_bf16 v[34:37], v[98:101], v[110:113], v[34:37]
	ds_read_b128 v[110:113], v0 offset:36864
	v_mfma_f32_16x16x32_bf16 v[42:45], v[98:101], v[114:117], v[42:45]
	ds_read_b128 v[98:101], v0 offset:32768
	ds_read_b128 v[114:117], v0 offset:38912
	s_waitcnt lgkmcnt(1)
	v_mfma_f32_16x16x32_bf16 v[22:25], v[102:105], v[98:101], v[22:25]
	v_mfma_f32_16x16x32_bf16 v[30:33], v[102:105], v[106:109], v[30:33]
	v_mfma_f32_16x16x32_bf16 v[38:41], v[102:105], v[110:113], v[38:41]
	s_waitcnt lgkmcnt(0)
	v_mfma_f32_16x16x32_bf16 v[14:17], v[102:105], v[114:117], v[14:17]
	ds_read_b128 v[102:105], v52 offset:51200
	s_waitcnt lgkmcnt(0)
	v_mfma_f32_16x16x32_bf16 v[54:57], v[102:105], v[98:101], v[54:57]
	v_mfma_f32_16x16x32_bf16 v[58:61], v[102:105], v[106:109], v[58:61]
	v_mfma_f32_16x16x32_bf16 v[78:81], v[102:105], v[110:113], v[78:81]
	v_mfma_f32_16x16x32_bf16 v[46:49], v[102:105], v[114:117], v[46:49]
	ds_read_b128 v[102:105], v52 offset:53248
	s_waitcnt lgkmcnt(0)
	v_mfma_f32_16x16x32_bf16 v[86:89], v[102:105], v[98:101], v[86:89]
	v_mfma_f32_16x16x32_bf16 v[90:93], v[102:105], v[106:109], v[90:93]
	v_mfma_f32_16x16x32_bf16 v[94:97], v[102:105], v[110:113], v[94:97]
	v_mfma_f32_16x16x32_bf16 v[82:85], v[102:105], v[114:117], v[82:85]
	ds_read_b128 v[102:105], v52 offset:55296
	s_waitcnt vmcnt(0)
	s_waitcnt lgkmcnt(0)
	s_barrier
; template <int MT, class Epi>
; DI void gemm_tile(const u16* __restrict__ X, long ldx, const u16* __restrict__ W, long ldw, int K, char* smem,
;                   int m0, int n0, const Epi& epi, bool pre = false, const u16* Xn = nullptr, const u16* Wn = nullptr) {
;     ...
;   do {
;     asm volatile("s_waitcnt vmcnt(0)" ::: "memory");
;     __syncthreads();
;     if (kt + 1 < nk) GT_DMA((unsigned)((kt + 1) & 1) * 32768u)
;     else if (Xn != nullptr) { xe = Xn + oxe; xo = Xn + oxo; we = Wn + owe; wo = Wn + owo; GT_DMA(0u) }
;     const char* cur = smem + (kt & 1) * 32768;
; #pragma unroll
;     for (int ks = 0; ks < 2; ++ks) {
;       bf16x8 xf[MT], wf[4];
;       const int ch = ((ks * 4 + g) ^ rsw) << 4;
; #pragma unroll
;       for (int i = 0; i < MT; ++i) xf[i] = *(const bf16x8*)(cur + (wm * 16 * MT + i * 16 + lr) * 128 + ch);
; #pragma unroll
;       for (int i = 0; i < 4; ++i) wf[i] = *(const bf16x8*)(cur + 16384 + (wn * 64 + i * 16 + lr) * 128 + ch);
; #pragma unroll
;       for (int nt = 0; nt < 4; ++nt)
; #pragma unroll
;         for (int mt = 0; mt < MT; ++mt)
;           acc[nt][mt] = __builtin_amdgcn_mfma_f32_16x16x32_bf16(wf[nt], xf[mt], acc[nt][mt], 0, 0, 0);
;     }
;   } while (++kt < nk);
	s_mov_b32 m0, s45
	s_nop 0
	global_load_lds_dwordx4 v[2:3], off
	v_lshl_add_u64 v[2:3], v[8:9], 0, s[20:21]
	s_mov_b32 m0, s44
	s_nop 0
	global_load_lds_dwordx4 v[2:3], off
	v_lshl_add_u64 v[2:3], v[10:11], 0, s[22:23]
	s_mov_b32 m0, s41
	s_nop 0
	global_load_lds_dwordx4 v[2:3], off
	s_mov_b64 s[44:45], 0x4a80
	v_lshl_add_u64 v[2:3], v[8:9], 0, s[44:45]
	s_mov_b32 m0, s34
	s_nop 0
	global_load_lds_dwordx4 v[2:3], off
	s_mov_b32 m0, s40
	s_nop 0
	global_load_lds_dwordx4 v[50:51], off
	v_lshl_add_u64 v[2:3], v[4:5], 0, s[20:21]
	s_mov_b32 m0, s19
	s_nop 0
	global_load_lds_dwordx4 v[2:3], off
	v_lshl_add_u64 v[2:3], v[6:7], 0, s[22:23]
	s_mov_b32 m0, s18
	s_nop 0
	global_load_lds_dwordx4 v[2:3], off
	v_lshl_add_u64 v[2:3], v[4:5], 0, s[44:45]
	s_mov_b32 m0, s17
	s_nop 0
	global_load_lds_dwordx4 v[2:3], off
	ds_read_b128 v[2:5], v12 offset:16384
	ds_read_b128 v[126:129], v0 offset:4096
	v_mfma_f32_16x16x32_bf16 v[18:21], v[102:105], v[98:101], v[18:21]
	ds_read_b128 v[98:101], v13 offset:2048
	ds_read_b128 v[118:121], v0
	ds_read_b128 v[122:125], v0 offset:2048
	v_mfma_f32_16x16x32_bf16 v[26:29], v[102:105], v[106:109], v[26:29]
	ds_read_b128 v[106:109], v13 offset:6144
	v_mfma_f32_16x16x32_bf16 v[34:37], v[102:105], v[110:113], v[34:37]
	v_mfma_f32_16x16x32_bf16 v[6:9], v[102:105], v[114:117], v[42:45]
	ds_read_b128 v[102:105], v13 offset:4096
	s_nop 1
	ds_read_b128 v[42:45], v13
	s_waitcnt lgkmcnt(0)
	v_mfma_f32_16x16x32_bf16 v[22:25], v[2:5], v[42:45], v[22:25]
	v_mfma_f32_16x16x32_bf16 v[30:33], v[2:5], v[98:101], v[30:33]
	v_mfma_f32_16x16x32_bf16 v[38:41], v[2:5], v[102:105], v[38:41]
	v_mfma_f32_16x16x32_bf16 v[110:113], v[2:5], v[106:109], v[14:17]
	ds_read_b128 v[2:5], v12 offset:18432
	s_waitcnt lgkmcnt(0)
	v_mfma_f32_16x16x32_bf16 v[54:57], v[2:5], v[42:45], v[54:57]
	v_mfma_f32_16x16x32_bf16 v[58:61], v[2:5], v[98:101], v[58:61]
	v_mfma_f32_16x16x32_bf16 v[78:81], v[2:5], v[102:105], v[78:81]
	v_mfma_f32_16x16x32_bf16 v[46:49], v[2:5], v[106:109], v[46:49]
	ds_read_b128 v[2:5], v12 offset:20480
	s_waitcnt lgkmcnt(0)
	v_mfma_f32_16x16x32_bf16 v[86:89], v[2:5], v[42:45], v[86:89]
	v_mfma_f32_16x16x32_bf16 v[90:93], v[2:5], v[98:101], v[90:93]
	v_mfma_f32_16x16x32_bf16 v[94:97], v[2:5], v[102:105], v[94:97]
	v_mfma_f32_16x16x32_bf16 v[82:85], v[2:5], v[106:109], v[82:85]
	ds_read_b128 v[2:5], v12 offset:22528
	s_waitcnt lgkmcnt(0)
	v_mfma_f32_16x16x32_bf16 v[114:117], v[2:5], v[42:45], v[18:21]
	s_nop 2
	ds_read_b128 v[16:19], v52 offset:16384
	v_mfma_f32_16x16x32_bf16 v[98:101], v[2:5], v[98:101], v[26:29]
	v_mfma_f32_16x16x32_bf16 v[102:105], v[2:5], v[102:105], v[34:37]
	v_mfma_f32_16x16x32_bf16 v[106:109], v[2:5], v[106:109], v[6:9]
	ds_read_b128 v[0:3], v0 offset:6144
	s_waitcnt lgkmcnt(1)
	v_mfma_f32_16x16x32_bf16 v[8:11], v[16:19], v[122:125], v[30:33]
	s_nop 2
	ds_read_b128 v[32:35], v52 offset:18432
	v_mfma_f32_16x16x32_bf16 v[4:7], v[16:19], v[118:121], v[22:25]
	s_waitcnt lgkmcnt(0)
	v_mfma_f32_16x16x32_bf16 v[20:23], v[32:35], v[118:121], v[54:57]
	v_mfma_f32_16x16x32_bf16 v[24:27], v[32:35], v[122:125], v[58:61]
	v_mfma_f32_16x16x32_bf16 v[28:31], v[32:35], v[126:129], v[78:81]
	v_mfma_f32_16x16x32_bf16 v[32:35], v[32:35], v[0:3], v[46:49]
	s_nop 1
	ds_read_b128 v[78:81], v52 offset:22528
	ds_read_b128 v[48:51], v52 offset:20480
	v_mfma_f32_16x16x32_bf16 v[12:15], v[16:19], v[126:129], v[38:41]
	s_waitcnt vmcnt(0)
	s_waitcnt lgkmcnt(0)
	s_barrier
	v_mfma_f32_16x16x32_bf16 v[16:19], v[16:19], v[0:3], v[110:113]
	v_mfma_f32_16x16x32_bf16 v[36:39], v[48:51], v[118:121], v[86:89]
	v_mfma_f32_16x16x32_bf16 v[40:43], v[48:51], v[122:125], v[90:93]
	v_mfma_f32_16x16x32_bf16 v[44:47], v[48:51], v[126:129], v[94:97]
	v_mfma_f32_16x16x32_bf16 v[48:51], v[48:51], v[0:3], v[82:85]
	v_mfma_f32_16x16x32_bf16 v[52:55], v[78:81], v[118:121], v[114:117]
	v_mfma_f32_16x16x32_bf16 v[56:59], v[78:81], v[122:125], v[98:101]
	v_mfma_f32_16x16x32_bf16 v[60:63], v[78:81], v[126:129], v[102:105]
	v_mfma_f32_16x16x32_bf16 v[0:3], v[78:81], v[0:3], v[106:109]
	s_cbranch_scc1 .LBB0_992
	s_mul_i32 s8, s8, 12
	s_sub_i32 s7, s7, s8
	s_mul_i32 s18, s7, 0xc000
	s_ashr_i32 s19, s18, 31
	s_lshl_b64 s[18:19], s[18:19], 1
	v_readlane_b32 s20, v252, 29
	v_readlane_b32 s21, v252, 30
	s_add_u32 s18, s20, s18
	s_addc_u32 s19, s21, s19
	v_lshl_add_u64 v[78:79], s[18:19], 0, v[66:67]
	v_lshl_add_u64 v[80:81], s[18:19], 0, v[64:65]
	v_lshl_add_u64 v[66:67], s[42:43], 0, v[66:67]
	v_lshl_add_u64 v[64:65], s[42:43], 0, v[64:65]
	s_mov_b32 m0, s10
	s_nop 0
	global_load_lds_dwordx4 v[64:65], off
	s_mov_b64 s[18:19], 0x1800
	v_lshl_add_u64 v[82:83], v[66:67], 0, s[18:19]
	s_mov_b32 m0, s11
	s_nop 0
	global_load_lds_dwordx4 v[82:83], off
	s_mov_b64 s[10:11], 0x3000
	v_lshl_add_u64 v[64:65], v[64:65], 0, s[10:11]
	s_mov_b32 m0, s12
	s_nop 0
	global_load_lds_dwordx4 v[64:65], off
	s_mov_b64 s[20:21], 0x4800
	v_lshl_add_u64 v[64:65], v[66:67], 0, s[20:21]
	s_mov_b32 m0, s13
	s_nop 0
	global_load_lds_dwordx4 v[64:65], off
	v_lshl_add_u64 v[64:65], v[78:79], 0, s[18:19]
	s_mov_b32 m0, s9
	s_nop 0
	global_load_lds_dwordx4 v[80:81], off
	s_nop 0
	s_mov_b32 m0, s14
	s_nop 0
	global_load_lds_dwordx4 v[64:65], off
	v_lshl_add_u64 v[64:65], v[80:81], 0, s[10:11]
	s_mov_b32 m0, s15
	s_nop 0
	global_load_lds_dwordx4 v[64:65], off
	v_lshl_add_u64 v[64:65], v[78:79], 0, s[20:21]
	s_mov_b32 m0, s16
	s_nop 0
	global_load_lds_dwordx4 v[64:65], off

; DI int get_bid() { int b = blockIdx.x; asm volatile("" : "+s"(b)); return b; }
; template <int MT, class Epi>
; DI void gemm_tile(const u16* __restrict__ X, long ldx, const u16* __restrict__ W, long ldw, int K, char* smem,
;                   int m0, int n0, const Epi& epi, bool pre = false, const u16* Xn = nullptr, const u16* Wn = nullptr) {
;     ...
;   const int wu = __builtin_amdgcn_readfirstlane(wave);
;   const unsigned sbase = (unsigned)__builtin_amdgcn_readfirstlane((int)(unsigned)(size_t)smem);
;   const int r8 = lane >> 3, c0 = (lane & 7) ^ (r8 >> 1);
;   const long oxe = (long)(wu * MT * 8 + r8) * ldx + (c0 << 3), oxo = (long)(wu * MT * 8 + r8) * ldx + ((c0 ^ 4) << 3);
;   const long owe = (long)(wu * 32 + r8) * ldw + (c0 << 3), owo = (long)(wu * 32 + r8) * ldw + ((c0 ^ 4) << 3);
;   const u16 *xe = X + oxe, *xo = X + oxo, *we = W + owe, *wo = W + owo;
;   const long ldx8 = 8 * ldx, ldw8 = 8 * ldw;
;   const unsigned xdst = sbase + wu * MT * 1024, wdst = sbase + 16384 + wu * 4096;
;     ...
;   if (!pre) {
;     __syncthreads();
;     GT_DMA(0u)
; DI void phase_odd(const Params& p, int o, int sub, char* smem) {
;     ...
;     for (int t = get_bid(); t < 132 * 14; t += gridDim.x) {
;       const int tm = t / 14, tn = t % 14;
;       const int t2 = t + gridDim.x, tm2 = t2 / 14, tn2 = t2 % 14;
;       const bool nx = t2 < 132 * 14;
;       gemm_tile<4>(hbuf + (size_t)tm * 128 * 1024, 1024, W + WO_IN + (size_t)tn * 128 * 1024, 1024, 1024, smem, tm * 128, tn * 128, epi, pre,
;                    nx ? hbuf + (size_t)tm2 * 128 * 1024 : nullptr, W + WO_IN + (size_t)tn2 * 128 * 1024);
.LBB0_1023:
	s_mul_hi_i32 s5, s4, 0x92492493
	s_add_i32 s5, s5, s4
	s_lshr_b32 s6, s5, 31
	s_ashr_i32 s5, s5, 3
	s_add_i32 s38, s5, s6
	v_mov_b32_e32 v3, v185
	s_mul_i32 s5, s38, 14
	s_sub_i32 s42, s4, s5
	v_ashrrev_i32_e32 v4, 6, v3
	v_bfe_u32 v2, v3, 3, 3
	v_readfirstlane_b32 s5, v4
	s_lshl_b32 s7, s5, 5
	v_bfe_u32 v76, v3, 4, 2
	v_or_b32_e32 v6, s7, v2
	v_bitop3_b32 v1, v76, v3, 7 bitop3:0x78
	v_ashrrev_i32_e32 v7, 31, v6
	v_lshlrev_b64 v[6:7], 10, v[6:7]
	v_lshlrev_b32_e32 v5, 3, v1
	s_ashr_i32 s39, s38, 31
	s_ashr_i32 s43, s42, 31
	v_or_b32_e32 v8, v6, v5
	v_mov_b32_e32 v9, v7
	v_bitop3_b32 v6, v6, v5, 32 bitop3:0xf6
	s_lshl_b32 s5, s5, 12
	s_lshl_b64 s[40:41], s[38:39], 18
	s_lshl_b64 s[44:45], s[42:43], 18
	v_mov_b32_e32 v0, v183
	s_add_i32 s6, s5, 0x4000
	s_and_b64 vcc, exec, s[46:47]
	v_lshlrev_b64 v[66:67], 1, v[8:9]
	v_lshlrev_b64 v[64:65], 1, v[6:7]
	s_cbranch_vccnz .LBB0_1025
	s_add_u32 s8, s0, s40
	v_readlane_b32 s12, v255, 5
	s_addc_u32 s9, s1, s41
	v_readlane_b32 s16, v255, 9
	v_readlane_b32 s17, v255, 10
	s_add_u32 s10, s16, s44
	s_addc_u32 s11, s17, s45
	v_readlane_b32 s13, v255, 6
	v_lshl_add_u64 v[6:7], s[8:9], 0, v[66:67]
	v_lshl_add_u64 v[8:9], s[8:9], 0, v[64:65]
	v_lshl_add_u64 v[10:11], s[10:11], 0, v[66:67]
	v_lshl_add_u64 v[12:13], s[10:11], 0, v[64:65]
	s_waitcnt lgkmcnt(0)
	s_barrier
	s_mov_b32 m0, s5
	s_nop 0
	global_load_lds_dwordx4 v[6:7], off
	s_mov_b64 s[10:11], 0x4000
	v_readlane_b32 s14, v255, 7
	v_readlane_b32 s15, v255, 8
	v_lshl_add_u64 v[14:15], v[8:9], 0, s[10:11]
	s_add_i32 s8, s5, 0x400
	s_mov_b32 m0, s8
	s_nop 0
	global_load_lds_dwordx4 v[14:15], off
	s_mov_b64 s[12:13], 0x8000
	v_lshl_add_u64 v[6:7], v[6:7], 0, s[12:13]
	s_add_i32 s8, s5, 0x800
	s_mov_b32 m0, s8
	s_nop 0
	global_load_lds_dwordx4 v[6:7], off
	s_mov_b64 s[14:15], 0xc000
	v_lshl_add_u64 v[6:7], v[8:9], 0, s[14:15]
	s_add_i32 s8, s5, 0xc00
	s_mov_b32 m0, s8
	s_nop 0
	global_load_lds_dwordx4 v[6:7], off
	s_mov_b32 m0, s6
	s_nop 0
	global_load_lds_dwordx4 v[10:11], off
	v_lshl_add_u64 v[6:7], v[12:13], 0, s[10:11]
	s_add_i32 s8, s5, 0x4400
	s_mov_b32 m0, s8
	s_nop 0
	global_load_lds_dwordx4 v[6:7], off
	v_lshl_add_u64 v[6:7], v[10:11], 0, s[12:13]
	s_add_i32 s8, s5, 0x4800
	s_mov_b32 m0, s8
	s_nop 0
	global_load_lds_dwordx4 v[6:7], off
	v_lshl_add_u64 v[6:7], v[12:13], 0, s[14:15]
	s_add_i32 s8, s5, 0x4c00
	s_mov_b32 m0, s8
	s_nop 0
	global_load_lds_dwordx4 v[6:7], off
	v_readlane_b32 s18, v255, 11
	v_readlane_b32 s19, v255, 12

; template <int MT, class Epi>
; DI void gemm_tile(const u16* __restrict__ X, long ldx, const u16* __restrict__ W, long ldw, int K, char* smem,
;                   int m0, int n0, const Epi& epi, bool pre = false, const u16* Xn = nullptr, const u16* Wn = nullptr) {
;     ...
;   do {
;     asm volatile("s_waitcnt vmcnt(0)" ::: "memory");
;     __syncthreads();
;     if (kt + 1 < nk) GT_DMA((unsigned)((kt + 1) & 1) * 32768u)
;     else if (Xn != nullptr) { xe = Xn + oxe; xo = Xn + oxo; we = Wn + owe; wo = Wn + owo; GT_DMA(0u) }
;     const char* cur = smem + (kt & 1) * 32768;
; #pragma unroll
;     for (int ks = 0; ks < 2; ++ks) {
;       bf16x8 xf[MT], wf[4];
;       const int ch = ((ks * 4 + g) ^ rsw) << 4;
; #pragma unroll
;       for (int i = 0; i < MT; ++i) xf[i] = *(const bf16x8*)(cur + (wm * 16 * MT + i * 16 + lr) * 128 + ch);
; #pragma unroll
;       for (int i = 0; i < 4; ++i) wf[i] = *(const bf16x8*)(cur + 16384 + (wn * 64 + i * 16 + lr) * 128 + ch);
; #pragma unroll
;       for (int nt = 0; nt < 4; ++nt)
; #pragma unroll
;         for (int mt = 0; mt < MT; ++mt)
;           acc[nt][mt] = __builtin_amdgcn_mfma_f32_16x16x32_bf16(wf[nt], xf[mt], acc[nt][mt], 0, 0, 0);
;     }
;   } while (++kt < nk);
; DI void phase_odd(const Params& p, int o, int sub, char* smem) {
;     ...
;       const int t2 = t + gridDim.x, tm2 = t2 / 14, tn2 = t2 % 14;
;       const bool nx = t2 < 132 * 14;
;       gemm_tile<4>(hbuf + (size_t)tm * 128 * 1024, 1024, W + WO_IN + (size_t)tn * 128 * 1024, 1024, 1024, smem, tm * 128, tn * 128, epi, pre,
;                    nx ? hbuf + (size_t)tm2 * 128 * 1024 : nullptr, W + WO_IN + (size_t)tn2 * 128 * 1024);
.LBB0_1026:
	s_add_i32 s7, s8, 0x8000
	v_lshl_add_u64 v[124:125], v[74:75], 0, s[40:41]
	s_and_b32 s9, s7, 0x8000
	v_lshl_add_u64 v[122:123], v[72:73], 0, s[40:41]
	v_lshl_add_u64 v[126:127], v[124:125], 0, s[74:75]
	s_waitcnt vmcnt(0)
	s_waitcnt lgkmcnt(0)
	s_barrier
	s_and_b32 s8, s8, 0x8000
	v_or_b32_e32 v162, s8, v84
	v_add3_u32 v163, v162, v80, v81
	v_add3_u32 v164, v162, v83, v81
	v_or_b32_e32 v165, s8, v82
	v_add3_u32 v166, v165, v80, v81
	v_add3_u32 v167, v165, v83, v81
	ds_read_b128 v[86:89], v163
	ds_read_b128 v[90:93], v163 offset:2048
	ds_read_b128 v[94:97], v163 offset:4096
	ds_read_b128 v[98:101], v163 offset:6144
	ds_read_b128 v[102:105], v164 offset:16384
	ds_read_b128 v[106:109], v164 offset:18432
	ds_read_b128 v[110:113], v164 offset:20480
	ds_read_b128 v[114:117], v164 offset:22528
	ds_read_b128 v[130:133], v166
	ds_read_b128 v[134:137], v166 offset:2048
	ds_read_b128 v[138:141], v166 offset:4096
	ds_read_b128 v[142:145], v166 offset:6144
	ds_read_b128 v[146:149], v167 offset:16384
	ds_read_b128 v[150:153], v167 offset:18432
	ds_read_b128 v[154:157], v167 offset:20480
	ds_read_b128 v[158:161], v167 offset:22528
	s_add_i32 s10, s9, s5
	s_mov_b32 m0, s10
	s_nop 0
	global_load_lds_dwordx4 v[126:127], off
	v_lshl_add_u64 v[126:127], v[122:123], 0, s[94:95]
	s_add_i32 s11, s10, 0x400
	s_mov_b32 m0, s11
	s_nop 0
	global_load_lds_dwordx4 v[126:127], off
	v_lshl_add_u64 v[124:125], v[124:125], 0, s[76:77]
	s_add_i32 s11, s10, 0x800
	s_mov_b32 m0, s11
	s_nop 0
	global_load_lds_dwordx4 v[124:125], off
	v_lshl_add_u64 v[120:121], v[70:71], 0, s[40:41]
	v_lshl_add_u64 v[122:123], v[122:123], 0, s[54:55]
	s_addk_i32 s10, 0xc00
	s_mov_b32 m0, s10
	s_nop 0
	global_load_lds_dwordx4 v[122:123], off
	v_lshl_add_u64 v[118:119], v[68:69], 0, s[40:41]
	v_lshl_add_u64 v[128:129], v[120:121], 0, s[28:29]
	s_add_i32 s9, s9, s6
	s_mov_b32 m0, s9
	s_nop 0
	global_load_lds_dwordx4 v[128:129], off
	v_lshl_add_u64 v[122:123], v[118:119], 0, s[94:95]
	s_add_i32 s10, s9, 0x400
	s_mov_b32 m0, s10
	s_nop 0
	global_load_lds_dwordx4 v[122:123], off
	v_lshl_add_u64 v[120:121], v[120:121], 0, s[78:79]
	s_add_i32 s10, s9, 0x800
	s_mov_b32 m0, s10
	s_nop 0
	global_load_lds_dwordx4 v[120:121], off
	v_lshl_add_u64 v[118:119], v[118:119], 0, s[54:55]
	s_addk_i32 s9, 0xc00
	s_mov_b32 m0, s9
	s_nop 0
	global_load_lds_dwordx4 v[118:119], off
	s_mov_b32 s8, s7
	s_add_u32 s40, s40, 0x80
	s_addc_u32 s41, s41, 0
	s_cmpk_lg_i32 s40, 0x780
	s_waitcnt lgkmcnt(11)
	v_mfma_f32_16x16x32_bf16 v[48:51], v[102:105], v[98:101], v[48:51]
	s_waitcnt lgkmcnt(10)
	v_mfma_f32_16x16x32_bf16 v[32:35], v[106:109], v[98:101], v[32:35]
	s_waitcnt lgkmcnt(9)
	v_mfma_f32_16x16x32_bf16 v[16:19], v[110:113], v[98:101], v[16:19]
	s_waitcnt lgkmcnt(8)
	v_mfma_f32_16x16x32_bf16 v[0:3], v[114:117], v[98:101], v[0:3]
	v_mfma_f32_16x16x32_bf16 v[60:63], v[102:105], v[86:89], v[60:63]
	v_mfma_f32_16x16x32_bf16 v[56:59], v[102:105], v[90:93], v[56:59]
	v_mfma_f32_16x16x32_bf16 v[52:55], v[102:105], v[94:97], v[52:55]
	v_mfma_f32_16x16x32_bf16 v[44:47], v[106:109], v[86:89], v[44:47]
	v_mfma_f32_16x16x32_bf16 v[40:43], v[106:109], v[90:93], v[40:43]
	v_mfma_f32_16x16x32_bf16 v[36:39], v[106:109], v[94:97], v[36:39]
	v_mfma_f32_16x16x32_bf16 v[28:31], v[110:113], v[86:89], v[28:31]
	v_mfma_f32_16x16x32_bf16 v[24:27], v[110:113], v[90:93], v[24:27]
	v_mfma_f32_16x16x32_bf16 v[20:23], v[110:113], v[94:97], v[20:23]
	v_mfma_f32_16x16x32_bf16 v[12:15], v[114:117], v[86:89], v[12:15]
	v_mfma_f32_16x16x32_bf16 v[8:11], v[114:117], v[90:93], v[8:11]
	v_mfma_f32_16x16x32_bf16 v[4:7], v[114:117], v[94:97], v[4:7]
	s_waitcnt lgkmcnt(3)
	v_mfma_f32_16x16x32_bf16 v[60:63], v[146:149], v[130:133], v[60:63]
	v_mfma_f32_16x16x32_bf16 v[56:59], v[146:149], v[134:137], v[56:59]
	v_mfma_f32_16x16x32_bf16 v[52:55], v[146:149], v[138:141], v[52:55]
	v_mfma_f32_16x16x32_bf16 v[48:51], v[146:149], v[142:145], v[48:51]
	s_waitcnt lgkmcnt(2)
	v_mfma_f32_16x16x32_bf16 v[44:47], v[150:153], v[130:133], v[44:47]
	v_mfma_f32_16x16x32_bf16 v[40:43], v[150:153], v[134:137], v[40:43]
	v_mfma_f32_16x16x32_bf16 v[36:39], v[150:153], v[138:141], v[36:39]
	v_mfma_f32_16x16x32_bf16 v[32:35], v[150:153], v[142:145], v[32:35]
	s_waitcnt lgkmcnt(1)
	v_mfma_f32_16x16x32_bf16 v[28:31], v[154:157], v[130:133], v[28:31]
	v_mfma_f32_16x16x32_bf16 v[24:27], v[154:157], v[134:137], v[24:27]
	v_mfma_f32_16x16x32_bf16 v[20:23], v[154:157], v[138:141], v[20:23]
	v_mfma_f32_16x16x32_bf16 v[16:19], v[154:157], v[142:145], v[16:19]
	s_waitcnt lgkmcnt(0)
	v_mfma_f32_16x16x32_bf16 v[12:15], v[158:161], v[130:133], v[12:15]
	v_mfma_f32_16x16x32_bf16 v[8:11], v[158:161], v[134:137], v[8:11]
	v_mfma_f32_16x16x32_bf16 v[4:7], v[158:161], v[138:141], v[4:7]
	v_mfma_f32_16x16x32_bf16 v[0:3], v[158:161], v[142:145], v[0:3]
	s_cbranch_scc1 .LBB0_1026
	v_readlane_b32 s8, v255, 5
	v_readlane_b32 s14, v255, 11
	s_add_i32 s4, s4, s14
	s_mul_hi_i32 s7, s4, 0x92492493
	s_add_i32 s7, s7, s4
	s_lshr_b32 s8, s7, 31
	s_ashr_i32 s7, s7, 3
	s_add_i32 s46, s7, s8
	s_cmpk_gt_i32 s4, 0x737
	v_readlane_b32 s9, v255, 6
	s_cselect_b64 s[40:41], -1, 0
	s_ashr_i32 s47, s46, 31
	s_lshl_b64 s[8:9], s[46:47], 18
	s_add_u32 s7, s0, s8
	s_addc_u32 s8, s1, s9
	s_cmpk_lt_i32 s4, 0x738
	s_waitcnt vmcnt(0)
	s_cselect_b32 s45, s8, 0
	s_cselect_b32 s44, s7, 0
	v_readlane_b32 s12, v255, 9
	v_readlane_b32 s13, v255, 10
	s_cmp_eq_u64 s[44:45], 0
	v_readlane_b32 s10, v255, 7
	v_readlane_b32 s11, v255, 8
	v_readlane_b32 s15, v255, 12
	s_barrier
	s_cbranch_scc1 .LBB0_1029
	s_mul_i32 s7, s46, 14
	s_sub_i32 s8, s4, s7
	s_ashr_i32 s9, s8, 31
	s_lshl_b64 s[8:9], s[8:9], 18
	s_add_u32 s8, s12, s8
	s_addc_u32 s9, s13, s9
	v_lshl_add_u64 v[68:69], s[44:45], 0, v[66:67]
	v_lshl_add_u64 v[70:71], s[8:9], 0, v[64:65]
	v_lshl_add_u64 v[64:65], s[44:45], 0, v[64:65]
	s_mov_b32 m0, s5
	s_nop 0
	global_load_lds_dwordx4 v[68:69], off
	s_mov_b64 s[10:11], 0x4000
	v_lshl_add_u64 v[66:67], s[8:9], 0, v[66:67]
	v_lshl_add_u64 v[72:73], v[64:65], 0, s[10:11]
	s_add_i32 s7, s5, 0x400
	s_mov_b32 m0, s7
	s_nop 0
	global_load_lds_dwordx4 v[72:73], off
	s_mov_b64 s[12:13], 0x8000
	v_lshl_add_u64 v[68:69], v[68:69], 0, s[12:13]
	s_add_i32 s7, s5, 0x800
	s_mov_b32 m0, s7
	s_nop 0
	global_load_lds_dwordx4 v[68:69], off
	s_mov_b64 s[14:15], 0xc000
	v_lshl_add_u64 v[64:65], v[64:65], 0, s[14:15]
	s_add_i32 s7, s5, 0xc00
	s_mov_b32 m0, s7
	s_nop 0
	global_load_lds_dwordx4 v[64:65], off
	s_mov_b32 m0, s6
	s_nop 0
	global_load_lds_dwordx4 v[66:67], off
	v_lshl_add_u64 v[64:65], v[70:71], 0, s[10:11]
	s_add_i32 s6, s5, 0x4400
	s_mov_b32 m0, s6
	s_nop 0
	global_load_lds_dwordx4 v[64:65], off
	v_lshl_add_u64 v[64:65], v[66:67], 0, s[12:13]
	s_add_i32 s6, s5, 0x4800
	s_mov_b32 m0, s6
	s_nop 0
	global_load_lds_dwordx4 v[64:65], off
	v_lshl_add_u64 v[64:65], v[70:71], 0, s[14:15]
	s_addk_i32 s5, 0x4c00
	s_mov_b32 m0, s5
	s_nop 0
	global_load_lds_dwordx4 v[64:65], off

; template <int MT, class Epi>
; DI void gemm_tile(const u16* __restrict__ X, long ldx, const u16* __restrict__ W, long ldw, int K, char* smem,
;                   int m0, int n0, const Epi& epi, bool pre = false, const u16* Xn = nullptr, const u16* Wn = nullptr) {
;     ...
;   const int wu = __builtin_amdgcn_readfirstlane(wave);
;   const unsigned sbase = (unsigned)__builtin_amdgcn_readfirstlane((int)(unsigned)(size_t)smem);
;   const int r8 = lane >> 3, c0 = (lane & 7) ^ (r8 >> 1);
;   const long oxe = (long)(wu * MT * 8 + r8) * ldx + (c0 << 3), oxo = (long)(wu * MT * 8 + r8) * ldx + ((c0 ^ 4) << 3);
;   const long owe = (long)(wu * 32 + r8) * ldw + (c0 << 3), owo = (long)(wu * 32 + r8) * ldw + ((c0 ^ 4) << 3);
;   const u16 *xe = X + oxe, *xo = X + oxo, *we = W + owe, *wo = W + owo;
;   const long ldx8 = 8 * ldx, ldw8 = 8 * ldw;
;   const unsigned xdst = sbase + wu * MT * 1024, wdst = sbase + 16384 + wu * 4096;
;     ...
;   if (!pre) {
;     __syncthreads();
;     GT_DMA(0u)
;   } else {
;     xe += 64; xo += 64; we += 64; wo += 64;
;   }
;   const int nk = K >> 6;
;   int kt = 0;
;   do {
;     asm volatile("s_waitcnt vmcnt(0)" ::: "memory");
;     __syncthreads();
;     if (kt + 1 < nk) GT_DMA((unsigned)((kt + 1) & 1) * 32768u)
;     else if (Xn != nullptr) { xe = Xn + oxe; xo = Xn + oxo; we = Wn + owe; wo = Wn + owo; GT_DMA(0u) }
;     const char* cur = smem + (kt & 1) * 32768;
; #pragma unroll
;     for (int ks = 0; ks < 2; ++ks) {
;       bf16x8 xf[MT], wf[4];
;       const int ch = ((ks * 4 + g) ^ rsw) << 4;
; #pragma unroll
;       for (int i = 0; i < MT; ++i) xf[i] = *(const bf16x8*)(cur + (wm * 16 * MT + i * 16 + lr) * 128 + ch);
; #pragma unroll
;       for (int i = 0; i < 4; ++i) wf[i] = *(const bf16x8*)(cur + 16384 + (wn * 64 + i * 16 + lr) * 128 + ch);
; #pragma unroll
;       for (int nt = 0; nt < 4; ++nt)
; #pragma unroll
;         for (int mt = 0; mt < MT; ++mt)
;           acc[nt][mt] = __builtin_amdgcn_mfma_f32_16x16x32_bf16(wf[nt], xf[mt], acc[nt][mt], 0, 0, 0);
;     }
;   } while (++kt < nk);
; DI void phase_even(const Params& p, int e, int sub, char* smem) {
;     ...
;         const int u = t - 512, tm = u >> 3, tn = u & 7, m0 = M_PROMPT + tm * 64;
;         gemm_tile<2>(gbuf + (size_t)m0 * 2048, 2048, W + WE_OUT + (size_t)tn * 128 * 2048, 2048, 2048, smem, m0, tn * 128, epi);
.LBB0_1133:
	s_and_b32 s7, s4, 7
	s_lshl_b32 s34, s7, 19
	s_cmpk_gt_i32 s6, 0x1ff
	s_mov_b64 s[40:41], -1
	s_cbranch_scc0 .LBB0_1137
	s_bfe_u32 s8, s5, 0x190006
	s_mov_b32 s9, s35
	s_lshl_b64 s[12:13], s[8:9], 18
	s_lshl_b32 s8, s6, 3
	s_and_b32 s8, s8, 0x7fffffc0
	s_add_i32 s40, s8, 0x3000
	s_mov_b32 s41, s35
	s_and_b32 s7, s6, 7
	s_lshl_b64 s[8:9], s[40:41], 12
	v_readlane_b32 s10, v252, 35
	v_mov_b32_e32 v1, v185
	v_readlane_b32 s11, v252, 36
	s_add_u32 s8, s10, s8
	s_addc_u32 s9, s11, s9
	v_ashrrev_i32_e32 v2, 6, v1
	v_bfe_u32 v4, v1, 3, 3
	v_readfirstlane_b32 s11, v2
	v_and_b32_e32 v40, 1, v2
	v_bfe_u32 v42, v1, 4, 2
	v_lshl_or_b32 v2, s11, 4, v4
	v_bitop3_b32 v8, v42, v1, 7 bitop3:0x78
	v_ashrrev_i32_e32 v3, 31, v2
	s_lshl_b32 s10, s7, 19
	v_readlane_b32 s16, v252, 39
	v_lshl_or_b32 v4, s11, 5, v4
	v_lshlrev_b64 v[2:3], 12, v[2:3]
	v_lshlrev_b32_e32 v182, 4, v8
	v_readlane_b32 s17, v252, 40
	s_add_u32 s14, s16, s10
	v_mov_b32_e32 v0, v183
	v_ashrrev_i32_e32 v5, 31, v4
	v_lshl_add_u64 v[6:7], s[8:9], 0, v[2:3]
	v_xor_b32_e32 v10, 64, v182
	v_mov_b32_e32 v11, v183
	s_addc_u32 s15, s17, 0
	v_lshl_add_u64 v[8:9], v[6:7], 0, v[182:183]
	v_lshl_add_u64 v[6:7], v[6:7], 0, v[10:11]
	v_lshlrev_b64 v[4:5], 12, v[4:5]
	s_lshl_b32 s8, s11, 11
	s_waitcnt lgkmcnt(0)
	s_barrier
	s_mov_b32 m0, s8
	s_nop 0
	global_load_lds_dwordx4 v[8:9], off
	v_lshl_add_u64 v[12:13], s[14:15], 0, v[4:5]
	s_lshl_b32 s11, s11, 12
	v_lshl_add_u64 v[6:7], v[6:7], 0, s[56:57]
	s_or_b32 s9, s8, 0x400
	s_mov_b32 m0, s9
	s_nop 0
	global_load_lds_dwordx4 v[6:7], off
	v_lshl_add_u64 v[14:15], v[12:13], 0, v[182:183]
	v_lshl_add_u64 v[6:7], v[12:13], 0, v[10:11]
	s_add_i32 s9, s11, 0x4000
	s_mov_b32 m0, s9
	s_nop 0
	global_load_lds_dwordx4 v[14:15], off
	v_lshl_add_u64 v[8:9], v[6:7], 0, s[56:57]
	s_add_i32 s14, s11, 0x4400
	s_mov_b32 m0, s14
	s_nop 0
	global_load_lds_dwordx4 v[8:9], off
	v_lshrrev_b32_e32 v16, 1, v1
	v_lshl_add_u64 v[8:9], v[14:15], 0, s[58:59]
	s_add_i32 s14, s11, 0x4800
	s_mov_b32 m0, s14
	s_nop 0
	global_load_lds_dwordx4 v[8:9], off
	v_lshl_add_u64 v[6:7], v[6:7], 0, s[60:61]
	s_addk_i32 s11, 0x4c00
	s_mov_b32 m0, s11
	s_nop 0
	global_load_lds_dwordx4 v[6:7], off
	v_bitop3_b32 v6, v42, v16, 7 bitop3:0x78
	v_lshl_add_u64 v[4:5], s[34:35], 0, v[4:5]
	v_lshlrev_b32_e32 v48, 4, v6
	v_lshl_add_u64 v[6:7], v[4:5], 0, v[10:11]
	v_lshl_add_u64 v[32:33], s[16:17], 0, v[6:7]
	v_readlane_b32 s16, v255, 5
	v_and_b32_e32 v41, 15, v1
	v_ashrrev_i32_e32 v43, 7, v1
	v_bfe_u32 v1, v1, 1, 3
	v_lshl_add_u64 v[4:5], v[4:5], 0, v[182:183]
	v_readlane_b32 s20, v255, 9
	v_readlane_b32 s21, v255, 10
	v_lshl_add_u64 v[2:3], s[12:13], 0, v[2:3]
	v_bitop3_b32 v1, v42, v1, 4 bitop3:0x36
	v_readlane_b32 s17, v255, 6
	v_readlane_b32 s18, v255, 7
	v_readlane_b32 s19, v255, 8
	v_lshl_add_u64 v[34:35], s[20:21], 0, v[4:5]
	v_bitop3_b32 v4, v2, v182, 64 bitop3:0xf6
	v_mov_b32_e32 v5, v3
	v_or_b32_e32 v2, v2, v182
	s_mov_b32 s10, 0
	v_lshlrev_b32_e32 v47, 12, v40
	v_lshlrev_b32_e32 v44, 7, v41
	v_lshlrev_b32_e32 v45, 13, v43
	v_lshlrev_b32_e32 v46, 4, v1
	v_lshl_add_u64 v[36:37], s[46:47], 0, v[4:5]
	v_lshl_add_u64 v[38:39], s[48:49], 0, v[2:3]
	s_mov_b64 s[42:43], 0
	v_mov_b32_e32 v1, v0
	v_mov_b32_e32 v2, v0
	v_mov_b32_e32 v3, v0
	v_mov_b32_e32 v4, v0
	v_mov_b32_e32 v5, v0
	v_mov_b32_e32 v6, v0
	v_mov_b32_e32 v7, v0
	v_mov_b32_e32 v8, v0
	v_mov_b32_e32 v9, v0
	v_mov_b32_e32 v10, v0
	v_mov_b32_e32 v11, v0
	v_mov_b32_e32 v12, v0
	v_mov_b32_e32 v13, v0
	v_mov_b32_e32 v14, v0
	v_mov_b32_e32 v15, v0
	v_mov_b32_e32 v16, v0
	v_mov_b32_e32 v17, v0
	v_mov_b32_e32 v18, v0
	v_mov_b32_e32 v19, v0
	v_mov_b32_e32 v20, v0
	v_mov_b32_e32 v21, v0
	v_mov_b32_e32 v22, v0
	v_mov_b32_e32 v23, v0
	v_mov_b32_e32 v24, v0
	v_mov_b32_e32 v25, v0
	v_mov_b32_e32 v26, v0
	v_mov_b32_e32 v27, v0
	v_mov_b32_e32 v28, v0
	v_mov_b32_e32 v29, v0
	v_mov_b32_e32 v30, v0
	v_mov_b32_e32 v31, v0
	s_mov_b64 s[16:17], 0xa00080
	s_mov_b64 s[18:19], 0x18080
	v_readlane_b32 s22, v255, 11
	v_readlane_b32 s23, v255, 12
.LBB0_1135:
	s_add_i32 s11, s10, 0x8000
	s_and_b32 s12, s11, 0x8000
	v_lshl_add_u64 v[54:55], v[36:37], 0, s[42:43]
	v_lshl_add_u64 v[56:57], v[38:39], 0, s[42:43]
	s_waitcnt vmcnt(0)
	s_barrier
	s_add_i32 s13, s12, s8
	s_mov_b32 m0, s13
	s_nop 0
	global_load_lds_dwordx4 v[56:57], off
	v_lshl_add_u64 v[52:53], v[34:35], 0, s[42:43]
	v_lshl_add_u64 v[54:55], v[54:55], 0, s[78:79]
	s_addk_i32 s13, 0x400
	s_mov_b32 m0, s13
	s_nop 0
	global_load_lds_dwordx4 v[54:55], off
	v_lshl_add_u64 v[50:51], v[32:33], 0, s[42:43]
	v_lshl_add_u64 v[58:59], v[52:53], 0, s[16:17]
	s_add_i32 s12, s12, s9
	s_mov_b32 m0, s12
	s_nop 0
	global_load_lds_dwordx4 v[58:59], off
	v_lshl_add_u64 v[54:55], v[50:51], 0, s[78:79]
	s_add_i32 s13, s12, 0x400
	s_mov_b32 m0, s13
	s_nop 0
	global_load_lds_dwordx4 v[54:55], off
	s_and_b32 s10, s10, 0x8000
	v_lshl_add_u64 v[52:53], v[52:53], 0, s[82:83]
	s_add_i32 s13, s12, 0x800
	s_mov_b32 m0, s13
	s_nop 0
	global_load_lds_dwordx4 v[52:53], off
	v_or_b32_e32 v49, s10, v48
	v_lshl_add_u64 v[50:51], v[50:51], 0, s[18:19]
	s_addk_i32 s12, 0xc00
	s_mov_b32 m0, s12
	s_nop 0
	global_load_lds_dwordx4 v[50:51], off
	v_add3_u32 v54, v49, v47, v44
	v_add3_u32 v49, v49, v45, v44
	ds_read_b128 v[50:53], v54
	ds_read_b128 v[54:57], v54 offset:2048
	ds_read_b128 v[58:61], v49 offset:16384
	ds_read_b128 v[62:65], v49 offset:18432
	ds_read_b128 v[66:69], v49 offset:20480
	ds_read_b128 v[70:73], v49 offset:22528
	v_or_b32_e32 v49, s10, v46
	s_waitcnt lgkmcnt(3)
	v_mfma_f32_16x16x32_bf16 v[24:27], v[58:61], v[54:57], v[24:27]
	s_add_u32 s42, s42, 0x80
	s_addc_u32 s43, s43, 0
	s_cmpk_lg_i32 s42, 0xf80
	s_waitcnt lgkmcnt(2)
; DI void st_bf4(u16* p, float a, float b, float c, float d) { *(uint2*)p = make_uint2(pk2(a, b), pk2(c, d)); }
; template <int MT, class Epi>
; DI void gemm_tile(const u16* __restrict__ X, long ldx, const u16* __restrict__ W, long ldw, int K, char* smem,
;                   int m0, int n0, const Epi& epi, bool pre = false, const u16* Xn = nullptr, const u16* Wn = nullptr) {
;     ...
;     for (int ks = 0; ks < 2; ++ks) {
;       bf16x8 xf[MT], wf[4];
;       const int ch = ((ks * 4 + g) ^ rsw) << 4;
; #pragma unroll
;       for (int i = 0; i < MT; ++i) xf[i] = *(const bf16x8*)(cur + (wm * 16 * MT + i * 16 + lr) * 128 + ch);
; #pragma unroll
;       for (int i = 0; i < 4; ++i) wf[i] = *(const bf16x8*)(cur + 16384 + (wn * 64 + i * 16 + lr) * 128 + ch);
; #pragma unroll
;       for (int nt = 0; nt < 4; ++nt)
; #pragma unroll
;         for (int mt = 0; mt < MT; ++mt)
;           acc[nt][mt] = __builtin_amdgcn_mfma_f32_16x16x32_bf16(wf[nt], xf[mt], acc[nt][mt], 0, 0, 0);
;     }
;   } while (++kt < nk);
;     ...
;   epi.run(acc, m0 + wm * 16 * MT + lr, n0 + wn * 64 + 4 * g);
;   template <int NT, int MT> DI void run(f32x4 (&acc)[NT][MT], int mb, int nb) const {
; #pragma unroll
;     for (int nt = 0; nt < NT; ++nt)
; #pragma unroll
;       for (int mt = 0; mt < MT; ++mt) {
;         f32x4 v = acc[nt][mt];
;         st_bf4(C + (size_t)(mb + mt * 16) * ldc + nb + nt * 16, v[0], v[1], v[2], v[3]);
;       }
;   }
	v_mfma_f32_16x16x32_bf16 v[16:19], v[62:65], v[54:57], v[16:19]
	s_mov_b32 s10, s11
	s_waitcnt lgkmcnt(1)
	v_mfma_f32_16x16x32_bf16 v[8:11], v[66:69], v[54:57], v[8:11]
	s_waitcnt lgkmcnt(0)
	v_mfma_f32_16x16x32_bf16 v[0:3], v[70:73], v[54:57], v[0:3]
	v_add3_u32 v54, v49, v47, v44
	v_add3_u32 v49, v49, v45, v44
	v_mfma_f32_16x16x32_bf16 v[28:31], v[58:61], v[50:53], v[28:31]
	v_mfma_f32_16x16x32_bf16 v[20:23], v[62:65], v[50:53], v[20:23]
	v_mfma_f32_16x16x32_bf16 v[12:15], v[66:69], v[50:53], v[12:15]
	v_mfma_f32_16x16x32_bf16 v[4:7], v[70:73], v[50:53], v[4:7]
	ds_read_b128 v[50:53], v54
	ds_read_b128 v[54:57], v54 offset:2048
	ds_read_b128 v[58:61], v49 offset:16384
	ds_read_b128 v[62:65], v49 offset:18432
	ds_read_b128 v[66:69], v49 offset:20480
	ds_read_b128 v[70:73], v49 offset:22528
	s_waitcnt lgkmcnt(3)
	v_mfma_f32_16x16x32_bf16 v[28:31], v[58:61], v[50:53], v[28:31]
	v_mfma_f32_16x16x32_bf16 v[24:27], v[58:61], v[54:57], v[24:27]
	s_waitcnt lgkmcnt(2)
	v_mfma_f32_16x16x32_bf16 v[20:23], v[62:65], v[50:53], v[20:23]
	v_mfma_f32_16x16x32_bf16 v[16:19], v[62:65], v[54:57], v[16:19]
	s_waitcnt lgkmcnt(1)
	v_mfma_f32_16x16x32_bf16 v[12:15], v[66:69], v[50:53], v[12:15]
	v_mfma_f32_16x16x32_bf16 v[8:11], v[66:69], v[54:57], v[8:11]
	s_waitcnt lgkmcnt(0)
	v_mfma_f32_16x16x32_bf16 v[4:7], v[70:73], v[50:53], v[4:7]
	v_mfma_f32_16x16x32_bf16 v[0:3], v[70:73], v[54:57], v[0:3]
	s_cbranch_scc1 .LBB0_1135
	v_add3_u32 v36, v48, v47, v44
	v_add3_u32 v60, v48, v45, v44
	s_waitcnt vmcnt(0)
	s_barrier
	ds_read_b128 v[32:35], v36 offset:32768
	ds_read_b128 v[36:39], v36 offset:34816
	ds_read_b128 v[48:51], v60 offset:49152
	ds_read_b128 v[52:55], v60 offset:51200
	ds_read_b128 v[56:59], v60 offset:53248
	ds_read_b128 v[60:63], v60 offset:55296
	s_waitcnt lgkmcnt(3)
	v_mfma_f32_16x16x32_bf16 v[24:27], v[48:51], v[36:39], v[24:27]
	s_lshl_b32 s7, s7, 7
	v_readlane_b32 s8, v252, 33
	v_readlane_b32 s9, v252, 34
	s_waitcnt lgkmcnt(2)
	v_mfma_f32_16x16x32_bf16 v[16:19], v[52:55], v[36:39], v[16:19]
	s_waitcnt lgkmcnt(1)
	v_mfma_f32_16x16x32_bf16 v[12:15], v[56:59], v[32:35], v[12:15]
	v_mfma_f32_16x16x32_bf16 v[8:11], v[56:59], v[36:39], v[8:11]
	v_add3_u32 v56, v46, v45, v44
	s_waitcnt lgkmcnt(0)
	v_mfma_f32_16x16x32_bf16 v[0:3], v[60:63], v[36:39], v[0:3]
	v_add3_u32 v36, v46, v47, v44
	v_mfma_f32_16x16x32_bf16 v[28:31], v[48:51], v[32:35], v[28:31]
	v_mfma_f32_16x16x32_bf16 v[20:23], v[52:55], v[32:35], v[20:23]
	v_mfma_f32_16x16x32_bf16 v[4:7], v[60:63], v[32:35], v[4:7]
	ds_read_b128 v[32:35], v36 offset:32768
	ds_read_b128 v[36:39], v36 offset:34816
	ds_read_b128 v[44:47], v56 offset:49152
	ds_read_b128 v[48:51], v56 offset:51200
	ds_read_b128 v[52:55], v56 offset:53248
	ds_read_b128 v[56:59], v56 offset:55296
	s_waitcnt lgkmcnt(3)
	v_mfma_f32_16x16x32_bf16 v[28:31], v[44:47], v[32:35], v[28:31]
	s_waitcnt lgkmcnt(2)
	v_mfma_f32_16x16x32_bf16 v[20:23], v[48:51], v[32:35], v[20:23]
	s_nop 5
	v_cvt_pk_bf16_f32 v28, v28, v29
	v_cvt_pk_bf16_f32 v29, v30, v31
	s_waitcnt lgkmcnt(1)
	v_mfma_f32_16x16x32_bf16 v[12:15], v[52:55], v[32:35], v[12:15]
	s_waitcnt lgkmcnt(0)
	v_mfma_f32_16x16x32_bf16 v[4:7], v[56:59], v[32:35], v[4:7]
	v_lshlrev_b32_e32 v32, 5, v40
	v_or3_b32 v182, v32, s40, v41
	v_lshl_add_u32 v32, v43, 6, s7
	v_lshl_or_b32 v32, v42, 2, v32
	v_ashrrev_i32_e32 v33, 31, v32
	v_lshlrev_b64 v[34:35], 11, v[182:183]
	v_mfma_f32_16x16x32_bf16 v[24:27], v[44:47], v[36:39], v[24:27]
	v_lshl_add_u64 v[34:35], s[8:9], 0, v[34:35]
	v_lshlrev_b64 v[32:33], 1, v[32:33]
	v_lshl_add_u64 v[34:35], v[34:35], 0, v[32:33]
	v_mfma_f32_16x16x32_bf16 v[16:19], v[48:51], v[36:39], v[16:19]
	v_or_b32_e32 v182, 16, v182
	global_store_dwordx2 v[34:35], v[28:29], off
	v_lshlrev_b64 v[28:29], 11, v[182:183]
	v_mfma_f32_16x16x32_bf16 v[8:11], v[52:55], v[36:39], v[8:11]
	v_lshl_add_u64 v[28:29], s[8:9], 0, v[28:29]
	v_lshl_add_u64 v[28:29], v[28:29], 0, v[32:33]
	v_cvt_pk_bf16_f32 v24, v24, v25
	v_mfma_f32_16x16x32_bf16 v[0:3], v[56:59], v[36:39], v[0:3]
	v_cvt_pk_bf16_f32 v25, v26, v27
	v_cvt_pk_bf16_f32 v20, v20, v21
	v_cvt_pk_bf16_f32 v21, v22, v23
	v_cvt_pk_bf16_f32 v16, v16, v17
	v_cvt_pk_bf16_f32 v17, v18, v19
	v_cvt_pk_bf16_f32 v12, v12, v13
	v_cvt_pk_bf16_f32 v13, v14, v15
	v_cvt_pk_bf16_f32 v8, v8, v9
	v_cvt_pk_bf16_f32 v9, v10, v11
	v_cvt_pk_bf16_f32 v4, v4, v5
	v_cvt_pk_bf16_f32 v5, v6, v7
	v_cvt_pk_bf16_f32 v0, v0, v1
	v_cvt_pk_bf16_f32 v1, v2, v3
	s_mov_b64 s[40:41], 0
	global_store_dwordx2 v[28:29], v[24:25], off
	global_store_dwordx2 v[34:35], v[20:21], off offset:32
	global_store_dwordx2 v[28:29], v[16:17], off offset:32
	global_store_dwordx2 v[34:35], v[12:13], off offset:64
	global_store_dwordx2 v[28:29], v[8:9], off offset:64
	global_store_dwordx2 v[34:35], v[4:5], off offset:96
	global_store_dwordx2 v[28:29], v[0:1], off offset:96
; DI int get_tid() { int t = threadIdx.x; asm volatile("" : "+v"(t)); return t; }
; DI float zero_f() { float z = 0.f; asm volatile("" : "+v"(z)); return z; }
; template <int BM, class Epi>
; DI void gemm_dma(const u16* __restrict__ X, long ldx, const u16* __restrict__ W, long ldw, int K, char* smem,
;                  int m0, int n0, const Epi& epi) {
;     ...
;   const int tid = get_tid(), lane = tid & 63, wave = tid >> 6;
;   const int lr = lane & 15, g = lane >> 4;
;   const int rd = lr * 64 + ((g ^ ((4 - (lr >> 2)) & 3)) << 4);
;   const int xrow0 = BIG ? wave * 64 : (wave & 1) * (BM / 2);
;   const int wrow0 = BIG ? 0 : (wave >> 1) * 64;
;   f32x4 acc[NT][MT];
;   { const float z = zero_f();
; #pragma unroll
;   for (int a = 0; a < NT; ++a)
; #pragma unroll
;     for (int b = 0; b < MT; ++b) acc[a][b] = (f32x4){z, z, z, z}; }
;   const int wu = __builtin_amdgcn_readfirstlane(wave);
;   const unsigned sbase = (unsigned)__builtin_amdgcn_readfirstlane((int)(unsigned)(size_t)smem);
;   const int r16 = lane >> 2, chunk = (lane & 3) ^ ((4 - (r16 >> 2)) & 3);
;   const u16* xs = X + (long)(wu * XD * 16 + r16) * ldx + (chunk << 3);
;   const u16* ws = W + (long)(wu * 32 + r16) * ldw + (chunk << 3);
;   const long ldx16 = 16 * ldx, ldw16 = 16 * ldw;
;   const unsigned xdst = sbase + wu * XD * 1024, wdst = sbase + BM * 64 + wu * 2048;
;     ...
;   const int nk = K >> 5;
;   __syncthreads();
; #pragma unroll
;   for (int s = 0; s < D - 1; ++s) GD_ISSUE(s)
;   int cur = 0, nxt = D - 1, kt = 0;
; DI void phase_even(const Params& p, int e, int sub, char* smem) {
;     ...
;         const int tm = t >> 3, tn = t & 7;
;         gemm_dma<256>(gbuf + (size_t)tm * 256 * 2048, 2048, W + WE_OUT + (size_t)tn * 128 * 2048, 2048, 2048, smem, tm * 256, tn * 128, epi);
.LBB0_1137:
	s_and_b64 vcc, exec, s[40:41]
	s_cbranch_vccz .LBB0_1132
	s_ashr_i32 s40, s6, 3
	s_ashr_i32 s41, s40, 31
	v_mov_b32_e32 v1, v185
	s_and_b32 s7, s6, 7
	s_lshl_b64 s[42:43], s[40:41], 20
	v_readlane_b32 s8, v252, 35
	v_readlane_b32 s9, v252, 36
	v_lshrrev_b32_e32 v2, 2, v1
	s_add_u32 s8, s8, s42
	v_and_b32_e32 v133, 15, v1
	v_bfe_u32 v132, v1, 4, 2
	v_sub_u32_e32 v2, 0, v2
	s_addc_u32 s9, s9, s43
	s_lshl_b32 s10, s7, 19
	v_readlane_b32 s12, v252, 39
	v_lshlrev_b32_e32 v0, 6, v133
	v_bitop3_b32 v2, v132, v2, 3 bitop3:0x78
	v_readlane_b32 s13, v252, 40
	s_add_u32 s12, s12, s10
	v_lshl_or_b32 v134, v2, 4, v0
	v_readfirstlane_b32 s14, v1
	v_lshrrev_b32_e32 v2, 4, v1
	s_addc_u32 s13, s13, 0
	s_ashr_i32 s15, s14, 6
	v_bfe_u32 v6, v1, 2, 4
	v_sub_u32_e32 v14, 0, v2
	s_andn2_b32 s14, s14, 63
	v_xor_b32_e32 v7, v1, v14
	v_or_b32_e32 v2, s14, v6
	v_ashrrev_i32_e32 v3, 31, v2
	v_lshlrev_b32_e32 v7, 4, v7
	v_lshl_or_b32 v6, s15, 5, v6
	v_lshlrev_b64 v[2:3], 12, v[2:3]
	v_and_b32_e32 v182, 48, v7
	v_ashrrev_i32_e32 v7, 31, v6
	v_mov_b32_e32 v0, v183
	v_lshl_add_u64 v[4:5], s[8:9], 0, v[2:3]
	v_lshlrev_b64 v[6:7], 12, v[6:7]
	v_lshl_add_u64 v[4:5], v[4:5], 0, v[182:183]
	v_lshl_add_u64 v[8:9], s[12:13], 0, v[6:7]
	s_lshl_b32 s8, s15, 12
	s_waitcnt lgkmcnt(0)
	s_barrier
	s_mov_b32 m0, s8
	s_nop 0
	global_load_lds_dwordx4 v[4:5], off
	v_lshl_add_u64 v[10:11], v[4:5], 0, s[58:59]
	s_or_b32 s13, s8, 0x400
	s_mov_b32 m0, s13
	s_nop 0
	global_load_lds_dwordx4 v[10:11], off
	s_mov_b64 s[16:17], 0x20000
	v_lshl_add_u64 v[10:11], v[4:5], 0, s[16:17]
	s_or_b32 s13, s8, 0x800
	s_mov_b32 m0, s13
	s_nop 0
	global_load_lds_dwordx4 v[10:11], off
	s_mov_b64 s[18:19], 0x30000
	s_lshl_b32 s12, s15, 11
	v_lshl_add_u64 v[10:11], v[4:5], 0, s[18:19]
	s_or_b32 s13, s8, 0xc00
	s_mov_b32 m0, s13
	s_nop 0
	global_load_lds_dwordx4 v[10:11], off
	v_lshl_add_u64 v[8:9], v[8:9], 0, v[182:183]
	s_add_i32 s9, s12, 0x4000
	s_mov_b32 m0, s9
	s_nop 0
	global_load_lds_dwordx4 v[8:9], off
	v_lshl_add_u64 v[10:11], v[8:9], 0, s[58:59]
	s_add_i32 s13, s12, 0x4400
	s_mov_b32 m0, s13
	s_nop 0
	global_load_lds_dwordx4 v[10:11], off
	v_lshl_add_u64 v[10:11], v[4:5], 0, 64
	s_add_i32 s13, s8, 0x6000
	s_mov_b32 m0, s13
	s_nop 0
	global_load_lds_dwordx4 v[10:11], off
	v_lshl_add_u64 v[10:11], v[4:5], 0, s[62:63]
	s_add_i32 s13, s8, 0x6400
	s_mov_b32 m0, s13
	s_nop 0
	global_load_lds_dwordx4 v[10:11], off
	s_mov_b64 s[14:15], 0x20040
	v_lshl_add_u64 v[10:11], v[4:5], 0, s[14:15]
	s_add_i32 s13, s8, 0x6800
	s_mov_b32 m0, s13
	s_nop 0
	global_load_lds_dwordx4 v[10:11], off
	s_mov_b64 s[14:15], 0x30040
	v_lshl_add_u64 v[4:5], v[4:5], 0, s[14:15]
	s_add_i32 s13, s8, 0x6c00
	s_mov_b32 m0, s13
	s_nop 0
	global_load_lds_dwordx4 v[4:5], off
	v_lshl_add_u64 v[12:13], v[8:9], 0, 64
	s_add_i32 s13, s12, 0xa000
	s_mov_b32 m0, s13
	s_nop 0
	global_load_lds_dwordx4 v[12:13], off
	v_lshl_add_u64 v[4:5], v[8:9], 0, s[62:63]
	v_and_b32_e32 v135, 0xffffffc0, v1
	v_bitop3_b32 v1, v1, 3, v14 bitop3:0x48
	s_add_i32 s12, s12, 0xa400
	s_mov_b32 m0, s12
	s_nop 0
	global_load_lds_dwordx4 v[4:5], off
	v_lshl_add_u64 v[4:5], s[34:35], 0, v[6:7]
	v_lshlrev_b32_e32 v182, 4, v1
	v_lshl_add_u64 v[2:3], s[42:43], 0, v[2:3]
	v_lshl_add_u64 v[4:5], v[4:5], 0, v[182:183]
	v_or_b32_e32 v2, v2, v182
	s_mov_b32 s10, 2
	s_mov_b32 s11, 0
	v_lshlrev_b32_e32 v136, 6, v135
	v_lshl_add_u64 v[128:129], s[50:51], 0, v[4:5]
	v_lshl_add_u64 v[130:131], s[52:53], 0, v[2:3]
	s_mov_b64 s[42:43], 0
	v_mov_b32_e32 v1, v0
	v_mov_b32_e32 v2, v0
	v_mov_b32_e32 v3, v0
	v_mov_b32_e32 v4, v0
	v_mov_b32_e32 v5, v0
	v_mov_b32_e32 v6, v0
	v_mov_b32_e32 v7, v0
	v_mov_b32_e32 v8, v0
	v_mov_b32_e32 v9, v0
	v_mov_b32_e32 v10, v0
	v_mov_b32_e32 v11, v0
	v_mov_b32_e32 v12, v0
	v_mov_b32_e32 v13, v0
	v_mov_b32_e32 v14, v0
	v_mov_b32_e32 v15, v0
	v_mov_b32_e32 v16, v0
	v_mov_b32_e32 v17, v0
	v_mov_b32_e32 v18, v0
	v_mov_b32_e32 v19, v0
	v_mov_b32_e32 v20, v0
	v_mov_b32_e32 v21, v0
	v_mov_b32_e32 v22, v0
	v_mov_b32_e32 v23, v0
	v_mov_b32_e32 v24, v0
	v_mov_b32_e32 v25, v0
	v_mov_b32_e32 v26, v0
	v_mov_b32_e32 v27, v0
	v_mov_b32_e32 v28, v0
	v_mov_b32_e32 v29, v0
	v_mov_b32_e32 v30, v0
	v_mov_b32_e32 v31, v0
	v_mov_b32_e32 v32, v0
	v_mov_b32_e32 v33, v0
	v_mov_b32_e32 v34, v0
	v_mov_b32_e32 v35, v0
	v_mov_b32_e32 v36, v0
	v_mov_b32_e32 v37, v0
	v_mov_b32_e32 v38, v0
	v_mov_b32_e32 v39, v0
	v_mov_b32_e32 v40, v0
	v_mov_b32_e32 v41, v0
	v_mov_b32_e32 v42, v0
	v_mov_b32_e32 v43, v0
	v_mov_b32_e32 v44, v0
	v_mov_b32_e32 v45, v0
	v_mov_b32_e32 v46, v0
	v_mov_b32_e32 v47, v0
	v_mov_b32_e32 v48, v0
	v_mov_b32_e32 v49, v0
	v_mov_b32_e32 v50, v0
	v_mov_b32_e32 v51, v0
	v_mov_b32_e32 v52, v0
	v_mov_b32_e32 v53, v0
	v_mov_b32_e32 v54, v0
	v_mov_b32_e32 v55, v0
	v_mov_b32_e32 v56, v0
	v_mov_b32_e32 v57, v0
	v_mov_b32_e32 v58, v0
	v_mov_b32_e32 v59, v0
	v_mov_b32_e32 v60, v0
	v_mov_b32_e32 v61, v0
	v_mov_b32_e32 v62, v0
	v_mov_b32_e32 v63, v0
	v_mov_b32_e32 v64, v0
	v_mov_b32_e32 v65, v0
	v_mov_b32_e32 v66, v0
	v_mov_b32_e32 v67, v0
	v_mov_b32_e32 v68, v0
	v_mov_b32_e32 v69, v0
	v_mov_b32_e32 v70, v0
	v_mov_b32_e32 v71, v0
	v_mov_b32_e32 v72, v0
	v_mov_b32_e32 v73, v0
	v_mov_b32_e32 v74, v0
	v_mov_b32_e32 v75, v0
	v_mov_b32_e32 v76, v0
	v_mov_b32_e32 v77, v0
	v_mov_b32_e32 v78, v0
	v_mov_b32_e32 v79, v0
	v_mov_b32_e32 v80, v0
	v_mov_b32_e32 v81, v0
	v_mov_b32_e32 v82, v0
	v_mov_b32_e32 v83, v0
	v_mov_b32_e32 v84, v0
	v_mov_b32_e32 v85, v0
	v_mov_b32_e32 v86, v0
	v_mov_b32_e32 v87, v0
	v_mov_b32_e32 v88, v0
	v_mov_b32_e32 v89, v0
	v_mov_b32_e32 v90, v0
	v_mov_b32_e32 v91, v0
	v_mov_b32_e32 v92, v0
	v_mov_b32_e32 v93, v0
	v_mov_b32_e32 v94, v0
	v_mov_b32_e32 v95, v0
	v_mov_b32_e32 v96, v0
	v_mov_b32_e32 v97, v0
	v_mov_b32_e32 v98, v0
	v_mov_b32_e32 v99, v0
	v_mov_b32_e32 v100, v0
	v_mov_b32_e32 v101, v0
	v_mov_b32_e32 v102, v0
	v_mov_b32_e32 v103, v0
	v_mov_b32_e32 v104, v0
	v_mov_b32_e32 v105, v0
	v_mov_b32_e32 v106, v0
	v_mov_b32_e32 v107, v0
	v_mov_b32_e32 v108, v0
	v_mov_b32_e32 v109, v0
	v_mov_b32_e32 v110, v0
	v_mov_b32_e32 v111, v0
	v_mov_b32_e32 v112, v0
	v_mov_b32_e32 v113, v0
	v_mov_b32_e32 v114, v0
	v_mov_b32_e32 v115, v0
	v_mov_b32_e32 v116, v0
	v_mov_b32_e32 v117, v0
	v_mov_b32_e32 v118, v0
	v_mov_b32_e32 v119, v0
	v_mov_b32_e32 v120, v0
	v_mov_b32_e32 v121, v0
	v_mov_b32_e32 v122, v0
	v_mov_b32_e32 v123, v0
	v_mov_b32_e32 v124, v0
	v_mov_b32_e32 v125, v0
	v_mov_b32_e32 v126, v0
	v_mov_b32_e32 v127, v0
; template <int N> DI void wait_vm() { asm volatile("s_waitcnt vmcnt(%0)" ::"n"(N) : "memory"); }
; template <int BM, class Epi>
; DI void gemm_dma(const u16* __restrict__ X, long ldx, const u16* __restrict__ W, long ldw, int K, char* smem,
;                  int m0, int n0, const Epi& epi) {
;     ...
;   do {
;     if (kt + D - 2 < nk) wait_vm<PW * (D - 2)>(); else wait_vm<0>();
;     __syncthreads();
;     if (kt + D - 1 < nk) GD_ISSUE(nxt)
;     nxt = (nxt + 1 == D) ? 0 : nxt + 1;
;     const char* base = smem + cur * STG;
;     cur = (cur + 1 == D) ? 0 : cur + 1;
;     bf16x8 xf[MT];
; #pragma unroll
;     for (int i = 0; i < MT; ++i) xf[i] = *(const bf16x8*)(base + (xrow0 + i * 16) * 64 + rd);
; #pragma unroll
;     for (int nh = 0; nh < NT / 4; ++nh) {
;       bf16x8 wf[4];
; #pragma unroll
;       for (int i = 0; i < 4; ++i) wf[i] = *(const bf16x8*)(base + BM * 64 + (wrow0 + (nh * 4 + i) * 16) * 64 + rd);
; #pragma unroll
;       for (int i = 0; i < 4; ++i)
; #pragma unroll
;         for (int mt = 0; mt < MT; ++mt)
;           acc[nh * 4 + i][mt] = __builtin_amdgcn_mfma_f32_16x16x32_bf16(wf[i], xf[mt], acc[nh * 4 + i][mt], 0, 0, 0);
;     }
;   } while (++kt < nk);
.LBB0_1139:
	s_mul_i32 s12, s10, 0x6000
	v_lshl_add_u64 v[196:197], v[130:131], 0, s[42:43]
	s_waitcnt vmcnt(6)
	s_barrier
	s_mul_i32 s98, s11, 0x6000
	v_or_b32_e32 v137, s98, v134
	v_add_u32_e32 v150, v137, v136
	ds_read_b128 v[138:141], v150
	ds_read_b128 v[142:145], v150 offset:1024
	ds_read_b128 v[146:149], v150 offset:2048
	ds_read_b128 v[150:153], v150 offset:3072
	ds_read_b128 v[154:157], v137 offset:16384
	ds_read_b128 v[158:161], v137 offset:17408
	ds_read_b128 v[162:165], v137 offset:18432
	ds_read_b128 v[166:169], v137 offset:19456
	ds_read_b128 v[226:229], v137 offset:20480
	ds_read_b128 v[230:233], v137 offset:21504
	ds_read_b128 v[234:237], v137 offset:22528
	ds_read_b128 v[238:241], v137 offset:23552
	s_add_i32 s13, s12, s8
	s_mov_b32 m0, s13
	s_nop 0
	global_load_lds_dwordx4 v[196:197], off
	v_lshl_add_u64 v[224:225], v[196:197], 0, s[58:59]
	s_add_i32 s14, s13, 0x400
	s_mov_b32 m0, s14
	s_nop 0
	global_load_lds_dwordx4 v[224:225], off
	v_lshl_add_u64 v[224:225], v[196:197], 0, s[16:17]
	s_add_i32 s14, s13, 0x800
	s_mov_b32 m0, s14
	s_nop 0
	global_load_lds_dwordx4 v[224:225], off
	v_lshl_add_u64 v[196:197], v[196:197], 0, s[18:19]
	s_addk_i32 s13, 0xc00
	s_mov_b32 m0, s13
	s_nop 0
	global_load_lds_dwordx4 v[196:197], off
	s_add_i32 s12, s12, s9
	v_lshl_add_u64 v[194:195], v[128:129], 0, s[42:43]
	s_mov_b32 m0, s12
	s_nop 0
	global_load_lds_dwordx4 v[194:195], off
	s_addk_i32 s12, 0x400
	v_lshl_add_u64 v[194:195], v[194:195], 0, s[58:59]
	s_mov_b32 m0, s12
	s_nop 0
	global_load_lds_dwordx4 v[194:195], off
	s_waitcnt lgkmcnt(7)
	v_mfma_f32_16x16x32_bf16 v[124:127], v[154:157], v[138:141], v[124:127]
	s_add_i32 s10, s10, 1
	s_add_i32 s11, s11, 1
	s_cmp_lg_u32 s10, 3
	v_mfma_f32_16x16x32_bf16 v[120:123], v[154:157], v[142:145], v[120:123]
	s_cselect_b32 s10, s10, 0
	s_cmp_lg_u32 s11, 3
	s_cselect_b32 s11, s11, 0
	v_mfma_f32_16x16x32_bf16 v[116:119], v[154:157], v[146:149], v[116:119]
	s_add_u32 s42, s42, 64
	s_addc_u32 s43, s43, 0
	s_cmpk_lg_i32 s42, 0xf80
	v_mfma_f32_16x16x32_bf16 v[112:115], v[154:157], v[150:153], v[112:115]
	s_waitcnt lgkmcnt(6)
	v_mfma_f32_16x16x32_bf16 v[108:111], v[158:161], v[138:141], v[108:111]
	v_mfma_f32_16x16x32_bf16 v[104:107], v[158:161], v[142:145], v[104:107]
	v_mfma_f32_16x16x32_bf16 v[100:103], v[158:161], v[146:149], v[100:103]
	v_mfma_f32_16x16x32_bf16 v[96:99], v[158:161], v[150:153], v[96:99]
	s_waitcnt lgkmcnt(5)
	v_mfma_f32_16x16x32_bf16 v[92:95], v[162:165], v[138:141], v[92:95]
	v_mfma_f32_16x16x32_bf16 v[88:91], v[162:165], v[142:145], v[88:91]
	v_mfma_f32_16x16x32_bf16 v[84:87], v[162:165], v[146:149], v[84:87]
	v_mfma_f32_16x16x32_bf16 v[80:83], v[162:165], v[150:153], v[80:83]
	s_waitcnt lgkmcnt(4)
	v_mfma_f32_16x16x32_bf16 v[76:79], v[166:169], v[138:141], v[76:79]
	v_mfma_f32_16x16x32_bf16 v[72:75], v[166:169], v[142:145], v[72:75]
	v_mfma_f32_16x16x32_bf16 v[68:71], v[166:169], v[146:149], v[68:71]
	v_mfma_f32_16x16x32_bf16 v[64:67], v[166:169], v[150:153], v[64:67]
	s_waitcnt lgkmcnt(3)
	v_mfma_f32_16x16x32_bf16 v[60:63], v[226:229], v[138:141], v[60:63]
	v_mfma_f32_16x16x32_bf16 v[56:59], v[226:229], v[142:145], v[56:59]
	v_mfma_f32_16x16x32_bf16 v[52:55], v[226:229], v[146:149], v[52:55]
	v_mfma_f32_16x16x32_bf16 v[48:51], v[226:229], v[150:153], v[48:51]
	s_waitcnt lgkmcnt(2)
	v_mfma_f32_16x16x32_bf16 v[44:47], v[230:233], v[138:141], v[44:47]
	v_mfma_f32_16x16x32_bf16 v[40:43], v[230:233], v[142:145], v[40:43]
	v_mfma_f32_16x16x32_bf16 v[36:39], v[230:233], v[146:149], v[36:39]
	v_mfma_f32_16x16x32_bf16 v[32:35], v[230:233], v[150:153], v[32:35]
	s_waitcnt lgkmcnt(1)
	v_mfma_f32_16x16x32_bf16 v[28:31], v[234:237], v[138:141], v[28:31]
	v_mfma_f32_16x16x32_bf16 v[24:27], v[234:237], v[142:145], v[24:27]
	v_mfma_f32_16x16x32_bf16 v[20:23], v[234:237], v[146:149], v[20:23]
	v_mfma_f32_16x16x32_bf16 v[16:19], v[234:237], v[150:153], v[16:19]
	s_waitcnt lgkmcnt(0)
	v_mfma_f32_16x16x32_bf16 v[12:15], v[238:241], v[138:141], v[12:15]
	v_mfma_f32_16x16x32_bf16 v[8:11], v[238:241], v[142:145], v[8:11]
	v_mfma_f32_16x16x32_bf16 v[4:7], v[238:241], v[146:149], v[4:7]
	v_mfma_f32_16x16x32_bf16 v[0:3], v[238:241], v[150:153], v[0:3]
	s_cbranch_scc1 .LBB0_1139
	v_add_u32_e32 v180, v134, v136
	v_or_b32_e32 v148, 0x10000, v134
	v_or_b32_e32 v152, 0x10400, v134
	v_or_b32_e32 v156, 0x10800, v134
	v_or_b32_e32 v160, 0x10c00, v134
	s_waitcnt vmcnt(6)
	s_barrier
	ds_read_b128 v[128:131], v180 offset:49152
	ds_read_b128 v[136:139], v180 offset:50176
	ds_read_b128 v[140:143], v180 offset:51200
	ds_read_b128 v[144:147], v180 offset:52224
	ds_read_b128 v[148:151], v148
	ds_read_b128 v[152:155], v152
	ds_read_b128 v[156:159], v156
	ds_read_b128 v[160:163], v160
	s_waitcnt lgkmcnt(3)
	v_mfma_f32_16x16x32_bf16 v[124:127], v[148:151], v[128:131], v[124:127]
	v_readlane_b32 s8, v252, 33
	v_readlane_b32 s9, v252, 34
	s_lshl_b32 s7, s7, 8
	v_mfma_f32_16x16x32_bf16 v[120:123], v[148:151], v[136:139], v[120:123]
	v_lshl_or_b32 v182, v132, 3, s7
	v_mfma_f32_16x16x32_bf16 v[116:119], v[148:151], v[140:143], v[116:119]
	v_mfma_f32_16x16x32_bf16 v[112:115], v[148:151], v[144:147], v[112:115]
	s_waitcnt lgkmcnt(2)
	v_mfma_f32_16x16x32_bf16 v[108:111], v[152:155], v[128:131], v[108:111]
	v_mfma_f32_16x16x32_bf16 v[104:107], v[152:155], v[136:139], v[104:107]
	v_mfma_f32_16x16x32_bf16 v[100:103], v[152:155], v[140:143], v[100:103]
	v_mfma_f32_16x16x32_bf16 v[96:99], v[152:155], v[144:147], v[96:99]
	s_waitcnt lgkmcnt(1)
	v_mfma_f32_16x16x32_bf16 v[92:95], v[156:159], v[128:131], v[92:95]
	v_mfma_f32_16x16x32_bf16 v[148:151], v[156:159], v[136:139], v[88:91]
	v_mfma_f32_16x16x32_bf16 v[84:87], v[156:159], v[140:143], v[84:87]
	s_nop 1
	v_or_b32_e32 v88, 0x11c00, v134
	ds_read_b128 v[88:91], v88
	v_mfma_f32_16x16x32_bf16 v[152:155], v[156:159], v[144:147], v[80:83]
	s_waitcnt lgkmcnt(1)
	v_mfma_f32_16x16x32_bf16 v[76:79], v[160:163], v[128:131], v[76:79]
	s_nop 0
	v_or_b32_e32 v80, 0x11800, v134
	ds_read_b128 v[80:83], v80
	v_mfma_f32_16x16x32_bf16 v[156:159], v[160:163], v[136:139], v[72:75]
	v_mfma_f32_16x16x32_bf16 v[68:71], v[160:163], v[140:143], v[68:71]
	s_nop 1
	v_or_b32_e32 v72, 0x11400, v134
	ds_read_b128 v[72:75], v72
	v_mfma_f32_16x16x32_bf16 v[160:163], v[160:163], v[144:147], v[64:67]
	s_nop 2
	v_or_b32_e32 v64, 0x11000, v134
	ds_read_b128 v[64:67], v64
	s_waitcnt lgkmcnt(1)
	v_mfma_f32_16x16x32_bf16 v[44:47], v[72:75], v[128:131], v[44:47]
	s_waitcnt vmcnt(0)
	s_waitcnt lgkmcnt(0)
	s_barrier
; template <int BM, class Epi>
; DI void gemm_dma(const u16* __restrict__ X, long ldx, const u16* __restrict__ W, long ldw, int K, char* smem,
;                  int m0, int n0, const Epi& epi) {
;     ...
;     bf16x8 xf[MT];
; #pragma unroll
;     for (int i = 0; i < MT; ++i) xf[i] = *(const bf16x8*)(base + (xrow0 + i * 16) * 64 + rd);
; #pragma unroll
;     for (int nh = 0; nh < NT / 4; ++nh) {
;       bf16x8 wf[4];
; #pragma unroll
;       for (int i = 0; i < 4; ++i) wf[i] = *(const bf16x8*)(base + BM * 64 + (wrow0 + (nh * 4 + i) * 16) * 64 + rd);
; #pragma unroll
;       for (int i = 0; i < 4; ++i)
; #pragma unroll
;         for (int mt = 0; mt < MT; ++mt)
;           acc[nh * 4 + i][mt] = __builtin_amdgcn_mfma_f32_16x16x32_bf16(wf[i], xf[mt], acc[nh * 4 + i][mt], 0, 0, 0);
;     }
;   } while (++kt < nk);
	v_mfma_f32_16x16x32_bf16 v[60:63], v[64:67], v[128:131], v[60:63]
	v_mfma_f32_16x16x32_bf16 v[164:167], v[64:67], v[136:139], v[56:59]
	v_mfma_f32_16x16x32_bf16 v[52:55], v[64:67], v[140:143], v[52:55]
	v_mfma_f32_16x16x32_bf16 v[168:171], v[64:67], v[144:147], v[48:51]
	v_mfma_f32_16x16x32_bf16 v[172:175], v[72:75], v[136:139], v[40:43]
	v_mfma_f32_16x16x32_bf16 v[36:39], v[72:75], v[140:143], v[36:39]
	v_mfma_f32_16x16x32_bf16 v[176:179], v[72:75], v[144:147], v[32:35]
	v_mfma_f32_16x16x32_bf16 v[28:31], v[80:83], v[128:131], v[28:31]
	v_mfma_f32_16x16x32_bf16 v[24:27], v[80:83], v[136:139], v[24:27]
	v_mfma_f32_16x16x32_bf16 v[20:23], v[80:83], v[140:143], v[20:23]
	v_mfma_f32_16x16x32_bf16 v[16:19], v[80:83], v[144:147], v[16:19]
	v_mfma_f32_16x16x32_bf16 v[12:15], v[88:91], v[128:131], v[12:15]
	v_mfma_f32_16x16x32_bf16 v[8:11], v[88:91], v[136:139], v[8:11]
	v_mfma_f32_16x16x32_bf16 v[4:7], v[88:91], v[140:143], v[4:7]
	v_mfma_f32_16x16x32_bf16 v[0:3], v[88:91], v[144:147], v[0:3]
	ds_read_b128 v[128:131], v180
	ds_read_b128 v[136:139], v180 offset:1024
	ds_read_b128 v[140:143], v180 offset:2048
	ds_read_b128 v[144:147], v180 offset:3072
	ds_read_b128 v[32:35], v134 offset:16384
	ds_read_b128 v[40:43], v134 offset:17408
	ds_read_b128 v[48:51], v134 offset:18432
	ds_read_b128 v[186:189], v134 offset:19456
	s_waitcnt lgkmcnt(2)
	v_mfma_f32_16x16x32_bf16 v[108:111], v[40:43], v[128:131], v[108:111]
	v_mfma_f32_16x16x32_bf16 v[104:107], v[40:43], v[136:139], v[104:107]
	v_mfma_f32_16x16x32_bf16 v[100:103], v[40:43], v[140:143], v[100:103]
	s_nop 5
	v_cvt_pk_bf16_f32 v108, v108, v109
	v_cvt_pk_bf16_f32 v109, v110, v111
	v_cvt_pk_bf16_f32 v104, v104, v105
	v_mfma_f32_16x16x32_bf16 v[190:193], v[40:43], v[144:147], v[96:99]
	v_cvt_pk_bf16_f32 v105, v106, v107
	v_cvt_pk_bf16_f32 v100, v100, v101
	v_cvt_pk_bf16_f32 v101, v102, v103
	s_waitcnt lgkmcnt(1)
	v_mfma_f32_16x16x32_bf16 v[80:83], v[48:51], v[136:139], v[148:151]
	v_mfma_f32_16x16x32_bf16 v[64:67], v[48:51], v[144:147], v[152:155]
	s_waitcnt lgkmcnt(0)
	v_mfma_f32_16x16x32_bf16 v[40:43], v[186:189], v[140:143], v[68:71]
	s_nop 2
	ds_read_b128 v[68:71], v134 offset:20480
	ds_read_b128 v[96:99], v134 offset:21504
	ds_read_b128 v[148:151], v134 offset:22528
	ds_read_b128 v[152:155], v134 offset:23552
	v_cvt_pk_bf16_f32 v80, v80, v81
	v_cvt_pk_bf16_f32 v81, v82, v83
	v_mfma_f32_16x16x32_bf16 v[88:91], v[48:51], v[128:131], v[92:95]
	v_cvt_pk_bf16_f32 v64, v64, v65
	v_cvt_pk_bf16_f32 v65, v66, v67
	v_cvt_pk_bf16_f32 v40, v40, v41
	v_mfma_f32_16x16x32_bf16 v[56:59], v[186:189], v[128:131], v[76:79]
	v_cvt_pk_bf16_f32 v41, v42, v43
	s_nop 2
	v_cvt_pk_bf16_f32 v88, v88, v89
	v_cvt_pk_bf16_f32 v89, v90, v91
	s_waitcnt lgkmcnt(3)
	v_mfma_f32_16x16x32_bf16 v[92:95], v[68:71], v[128:131], v[60:63]
	v_mfma_f32_16x16x32_bf16 v[76:79], v[68:71], v[140:143], v[52:55]
	v_cvt_pk_bf16_f32 v56, v56, v57
	v_cvt_pk_bf16_f32 v57, v58, v59
	s_waitcnt lgkmcnt(2)
	v_mfma_f32_16x16x32_bf16 v[60:63], v[96:99], v[128:131], v[44:47]
	v_mfma_f32_16x16x32_bf16 v[52:55], v[96:99], v[136:139], v[172:175]
	v_mfma_f32_16x16x32_bf16 v[44:47], v[96:99], v[140:143], v[36:39]
	v_mfma_f32_16x16x32_bf16 v[36:39], v[96:99], v[144:147], v[176:179]
	v_lshl_add_u32 v96, s40, 8, v135
	v_mfma_f32_16x16x32_bf16 v[124:127], v[32:35], v[128:131], v[124:127]
	s_waitcnt lgkmcnt(1)
	v_mfma_f32_16x16x32_bf16 v[28:31], v[148:151], v[128:131], v[28:31]
	s_waitcnt lgkmcnt(0)
; DI void st_bf4(u16* p, float a, float b, float c, float d) { *(uint2*)p = make_uint2(pk2(a, b), pk2(c, d)); }
; template <int BM, class Epi>
; DI void gemm_dma(const u16* __restrict__ X, long ldx, const u16* __restrict__ W, long ldw, int K, char* smem,
;                  int m0, int n0, const Epi& epi) {
;     ...
;       for (int i = 0; i < 4; ++i)
; #pragma unroll
;         for (int mt = 0; mt < MT; ++mt)
;           acc[nh * 4 + i][mt] = __builtin_amdgcn_mfma_f32_16x16x32_bf16(wf[i], xf[mt], acc[nh * 4 + i][mt], 0, 0, 0);
;     }
;   } while (++kt < nk);
;     ...
;   epi.run(acc, m0 + xrow0 + lr, n0 + wrow0 + 4 * g);
;   template <int NT, int MT> DI void run(f32x4 (&acc)[NT][MT], int mb, int nb) const {
; #pragma unroll
;     for (int nt = 0; nt < NT; ++nt)
; #pragma unroll
;       for (int mt = 0; mt < MT; ++mt) {
;         f32x4 v = acc[nt][mt];
;         st_bf4(C + (size_t)(mb + mt * 16) * ldc + nb + nt * 16, v[0], v[1], v[2], v[3]);
;       }
;   }
	v_mfma_f32_16x16x32_bf16 v[12:15], v[152:155], v[128:131], v[12:15]
	v_or_b32_e32 v128, v96, v133
	v_ashrrev_i32_e32 v129, 31, v128
	v_lshlrev_b64 v[96:97], 11, v[128:129]
	v_lshl_add_u64 v[96:97], s[8:9], 0, v[96:97]
	v_lshl_add_u64 v[96:97], v[96:97], 0, v[182:183]
	v_cvt_pk_bf16_f32 v98, v124, v125
	v_cvt_pk_bf16_f32 v99, v126, v127
	v_mfma_f32_16x16x32_bf16 v[120:123], v[32:35], v[136:139], v[120:123]
	global_store_dwordx2 v[96:97], v[98:99], off
	v_or_b32_e32 v98, 16, v128
	v_ashrrev_i32_e32 v99, 31, v98
	v_lshlrev_b64 v[98:99], 11, v[98:99]
	v_lshl_add_u64 v[98:99], s[8:9], 0, v[98:99]
	v_lshl_add_u64 v[98:99], v[98:99], 0, v[182:183]
	s_nop 1
	v_cvt_pk_bf16_f32 v120, v120, v121
	v_cvt_pk_bf16_f32 v121, v122, v123
	v_mfma_f32_16x16x32_bf16 v[116:119], v[32:35], v[140:143], v[116:119]
	global_store_dwordx2 v[98:99], v[120:121], off
	v_or_b32_e32 v120, 32, v128
	v_ashrrev_i32_e32 v121, 31, v120
	v_lshlrev_b64 v[120:121], 11, v[120:121]
	v_lshl_add_u64 v[120:121], s[8:9], 0, v[120:121]
	v_lshl_add_u64 v[120:121], v[120:121], 0, v[182:183]
	s_nop 1
	v_cvt_pk_bf16_f32 v116, v116, v117
	v_cvt_pk_bf16_f32 v117, v118, v119
	v_mfma_f32_16x16x32_bf16 v[112:115], v[32:35], v[144:147], v[112:115]
	global_store_dwordx2 v[120:121], v[116:117], off
	v_or_b32_e32 v116, 48, v128
	v_ashrrev_i32_e32 v117, 31, v116
	v_mfma_f32_16x16x32_bf16 v[32:35], v[186:189], v[144:147], v[160:163]
	v_lshlrev_b64 v[116:117], 11, v[116:117]
	v_lshl_add_u64 v[116:117], s[8:9], 0, v[116:117]
	v_lshl_add_u64 v[116:117], v[116:117], 0, v[182:183]
	v_mfma_f32_16x16x32_bf16 v[72:75], v[48:51], v[140:143], v[84:87]
	v_cvt_pk_bf16_f32 v112, v112, v113
	s_nop 2
	v_cvt_pk_bf16_f32 v32, v32, v33
	v_cvt_pk_bf16_f32 v33, v34, v35
	v_mfma_f32_16x16x32_bf16 v[84:87], v[68:71], v[136:139], v[164:167]
	global_store_dwordx2 v[116:117], v[32:33], off offset:96
	v_cvt_pk_bf16_f32 v32, v92, v93
	v_cvt_pk_bf16_f32 v33, v94, v95
	v_mfma_f32_16x16x32_bf16 v[68:71], v[68:71], v[144:147], v[168:171]
	global_store_dwordx2 v[96:97], v[32:33], off offset:128
	s_nop 2
	v_cvt_pk_bf16_f32 v32, v84, v85
	v_cvt_pk_bf16_f32 v33, v86, v87
	global_store_dwordx2 v[98:99], v[32:33], off offset:128
	v_cvt_pk_bf16_f32 v32, v76, v77
	v_cvt_pk_bf16_f32 v33, v78, v79
	v_mfma_f32_16x16x32_bf16 v[48:51], v[186:189], v[136:139], v[156:159]
	global_store_dwordx2 v[120:121], v[32:33], off offset:128
	v_cvt_pk_bf16_f32 v32, v68, v69
	v_cvt_pk_bf16_f32 v33, v70, v71
	v_mfma_f32_16x16x32_bf16 v[24:27], v[148:151], v[136:139], v[24:27]
	global_store_dwordx2 v[116:117], v[32:33], off offset:128
	v_cvt_pk_bf16_f32 v32, v60, v61
	v_cvt_pk_bf16_f32 v33, v62, v63
	v_mfma_f32_16x16x32_bf16 v[20:23], v[148:151], v[140:143], v[20:23]
	global_store_dwordx2 v[96:97], v[32:33], off offset:160
	v_cvt_pk_bf16_f32 v32, v52, v53
	v_cvt_pk_bf16_f32 v33, v54, v55
	v_mfma_f32_16x16x32_bf16 v[16:19], v[148:151], v[144:147], v[16:19]
	global_store_dwordx2 v[98:99], v[32:33], off offset:160
	v_cvt_pk_bf16_f32 v32, v44, v45
	v_cvt_pk_bf16_f32 v33, v46, v47
	v_mfma_f32_16x16x32_bf16 v[8:11], v[152:155], v[136:139], v[8:11]
	v_cvt_pk_bf16_f32 v113, v114, v115
	global_store_dwordx2 v[120:121], v[100:101], off offset:32
	v_cvt_pk_bf16_f32 v100, v190, v191
	v_mfma_f32_16x16x32_bf16 v[4:7], v[152:155], v[140:143], v[4:7]
	v_cvt_pk_bf16_f32 v101, v192, v193
	v_cvt_pk_bf16_f32 v72, v72, v73
	v_cvt_pk_bf16_f32 v73, v74, v75
	v_mfma_f32_16x16x32_bf16 v[0:3], v[152:155], v[144:147], v[0:3]
	v_cvt_pk_bf16_f32 v48, v48, v49
	v_cvt_pk_bf16_f32 v49, v50, v51
	global_store_dwordx2 v[120:121], v[32:33], off offset:160
	v_cvt_pk_bf16_f32 v32, v36, v37
	v_cvt_pk_bf16_f32 v33, v38, v39
	v_cvt_pk_bf16_f32 v28, v28, v29
	v_cvt_pk_bf16_f32 v29, v30, v31
	v_cvt_pk_bf16_f32 v24, v24, v25
	v_cvt_pk_bf16_f32 v25, v26, v27
	v_cvt_pk_bf16_f32 v20, v20, v21
	v_cvt_pk_bf16_f32 v21, v22, v23
	v_cvt_pk_bf16_f32 v16, v16, v17
	v_cvt_pk_bf16_f32 v17, v18, v19
	v_cvt_pk_bf16_f32 v12, v12, v13
	v_cvt_pk_bf16_f32 v13, v14, v15
	v_cvt_pk_bf16_f32 v8, v8, v9
	v_cvt_pk_bf16_f32 v9, v10, v11
	v_cvt_pk_bf16_f32 v4, v4, v5
	v_cvt_pk_bf16_f32 v5, v6, v7
	v_cvt_pk_bf16_f32 v0, v0, v1
	v_cvt_pk_bf16_f32 v1, v2, v3
	global_store_dwordx2 v[116:117], v[112:113], off
	global_store_dwordx2 v[96:97], v[108:109], off offset:32
	global_store_dwordx2 v[98:99], v[104:105], off offset:32
	global_store_dwordx2 v[116:117], v[100:101], off offset:32
	global_store_dwordx2 v[96:97], v[88:89], off offset:64
	global_store_dwordx2 v[98:99], v[80:81], off offset:64
	global_store_dwordx2 v[120:121], v[72:73], off offset:64
	global_store_dwordx2 v[116:117], v[64:65], off offset:64
	global_store_dwordx2 v[96:97], v[56:57], off offset:96
	global_store_dwordx2 v[98:99], v[48:49], off offset:96
	global_store_dwordx2 v[120:121], v[40:41], off offset:96
	global_store_dwordx2 v[116:117], v[32:33], off offset:160
	global_store_dwordx2 v[96:97], v[28:29], off offset:192
	global_store_dwordx2 v[98:99], v[24:25], off offset:192
	global_store_dwordx2 v[120:121], v[20:21], off offset:192
	global_store_dwordx2 v[116:117], v[16:17], off offset:192
	global_store_dwordx2 v[96:97], v[12:13], off offset:224
	global_store_dwordx2 v[98:99], v[8:9], off offset:224
	global_store_dwordx2 v[120:121], v[4:5], off offset:224
	global_store_dwordx2 v[116:117], v[0:1], off offset:224
	s_branch .LBB0_1132

; template <int MT, class Epi>
; DI void gemm_tile(const u16* __restrict__ X, long ldx, const u16* __restrict__ W, long ldw, int K, char* smem,
;                   int m0, int n0, const Epi& epi, bool pre = false, const u16* Xn = nullptr, const u16* Wn = nullptr) {
;     ...
;   const int wu = __builtin_amdgcn_readfirstlane(wave);
;   const unsigned sbase = (unsigned)__builtin_amdgcn_readfirstlane((int)(unsigned)(size_t)smem);
;   const int r8 = lane >> 3, c0 = (lane & 7) ^ (r8 >> 1);
;   const long oxe = (long)(wu * MT * 8 + r8) * ldx + (c0 << 3), oxo = (long)(wu * MT * 8 + r8) * ldx + ((c0 ^ 4) << 3);
;   const long owe = (long)(wu * 32 + r8) * ldw + (c0 << 3), owo = (long)(wu * 32 + r8) * ldw + ((c0 ^ 4) << 3);
;   const u16 *xe = X + oxe, *xo = X + oxo, *we = W + owe, *wo = W + owo;
;   const long ldx8 = 8 * ldx, ldw8 = 8 * ldw;
;   const unsigned xdst = sbase + wu * MT * 1024, wdst = sbase + 16384 + wu * 4096;
;     ...
;   if (!pre) {
;     __syncthreads();
;     GT_DMA(0u)
;   } else {
;     xe += 64; xo += 64; we += 64; wo += 64;
;   }
;   const int nk = K >> 6;
;   int kt = 0;
;   do {
;     asm volatile("s_waitcnt vmcnt(0)" ::: "memory");
;     __syncthreads();
;     if (kt + 1 < nk) GT_DMA((unsigned)((kt + 1) & 1) * 32768u)
;     else if (Xn != nullptr) { xe = Xn + oxe; xo = Xn + oxo; we = Wn + owe; wo = Wn + owo; GT_DMA(0u) }
;     const char* cur = smem + (kt & 1) * 32768;
; #pragma unroll
;     for (int ks = 0; ks < 2; ++ks) {
;       bf16x8 xf[MT], wf[4];
;       const int ch = ((ks * 4 + g) ^ rsw) << 4;
; #pragma unroll
;       for (int i = 0; i < MT; ++i) xf[i] = *(const bf16x8*)(cur + (wm * 16 * MT + i * 16 + lr) * 128 + ch);
; #pragma unroll
;       for (int i = 0; i < 4; ++i) wf[i] = *(const bf16x8*)(cur + 16384 + (wn * 64 + i * 16 + lr) * 128 + ch);
; #pragma unroll
;       for (int nt = 0; nt < 4; ++nt)
; #pragma unroll
;         for (int mt = 0; mt < MT; ++mt)
; DI void phase_even(const Params& p, int e, int sub, char* smem) {
;     ...
;         const int u = t - 1056, c = u >> 3, g = (u >> 1) & 3, tn = u & 1;
;         EpiSgu epi{p.b_spatial + (e * 4 + g) * 128, uvbuf, gbuf, g, c < 128 ? c * 128 : M_PROMPT + (c - 128) * 32, c < 128 ? 128 : 32};
;         gemm_tile<4>(W + WE_WS + (size_t)g * 16384, 128, vT + ((size_t)c * 1024 + g * 256 + tn * 128) * 128, 128, 128, smem, 0, tn * 128, epi);
.LBB0_1147:
	s_cmpk_gt_i32 s4, 0x41f
	s_mov_b64 s[40:41], -1
	s_cbranch_scc0 .LBB0_1157
	s_add_i32 s7, s4, 0xfffffbe0
	s_bfe_u32 s9, s4, 0x20001
	v_readlane_b32 s56, v252, 8
	s_lshr_b32 s34, s7, 3
	s_lshl_b32 s8, s9, 9
	v_readlane_b32 s66, v252, 18
	v_readlane_b32 s67, v252, 19
	s_add_u32 s40, s66, s8
	s_addc_u32 s41, s67, 0
	s_lshl_b32 s8, s34, 5
	s_lshl_b32 s10, s34, 7
	s_add_i32 s11, s8, 0x3000
	s_cmpk_lt_u32 s7, 0x400
	s_cselect_b32 s8, 0x80, 32
	s_cselect_b32 s7, s10, s11
	s_lshl_b32 s10, s9, 15
	v_readlane_b32 s12, v252, 41
	v_readlane_b32 s13, v252, 42
	s_add_u32 s12, s12, s10
	s_addc_u32 s13, s13, 0
	s_lshl_b64 s[14:15], s[34:35], 10
	s_lshl_b32 s9, s9, 8
	v_mov_b32_e32 v72, v185
	s_or_b32 s11, s14, s9
	s_and_b32 s10, s5, 0x80
	s_or_b32 s14, s11, s10
	v_ashrrev_i32_e32 v1, 6, v72
	v_bfe_u32 v2, v72, 3, 3
	v_readfirstlane_b32 s11, v1
	s_waitcnt vmcnt(4)
	v_bfe_u32 v113, v72, 4, 2
	v_bitop3_b32 v6, v113, v72, 7 bitop3:0x78
	v_lshl_or_b32 v2, s11, 5, v2
	v_ashrrev_i32_e32 v3, 31, v2
	s_lshl_b64 s[14:15], s[14:15], 8
	v_readlane_b32 s16, v252, 37
	v_lshlrev_b64 v[2:3], 8, v[2:3]
	v_lshlrev_b32_e32 v182, 4, v6
	v_readlane_b32 s17, v252, 38
	s_add_u32 s14, s16, s14
	v_mov_b32_e32 v0, v183
	v_lshl_add_u64 v[4:5], s[12:13], 0, v[2:3]
	v_xor_b32_e32 v8, 64, v182
	v_mov_b32_e32 v9, v183
	s_addc_u32 s15, s17, s15
	v_lshl_add_u64 v[6:7], v[4:5], 0, v[182:183]
	v_lshl_add_u64 v[4:5], v[4:5], 0, v[8:9]
	s_lshl_b32 s11, s11, 12
	s_waitcnt lgkmcnt(0)
	s_barrier
	s_mov_b32 m0, s11
	s_nop 0
	global_load_lds_dwordx4 v[6:7], off
	s_mov_b64 s[18:19], 0x800
	v_lshl_add_u64 v[2:3], s[14:15], 0, v[2:3]
	v_lshl_add_u64 v[12:13], v[4:5], 0, s[18:19]
	s_or_b32 s12, s11, 0x400
	s_mov_b32 m0, s12
	s_nop 0
	global_load_lds_dwordx4 v[12:13], off
	s_mov_b64 s[14:15], 0x1000
	v_lshl_add_u64 v[12:13], v[6:7], 0, s[14:15]
	s_or_b32 s12, s11, 0x800
	s_mov_b32 m0, s12
	s_nop 0
	global_load_lds_dwordx4 v[12:13], off
	s_mov_b64 s[16:17], 0x1800
	v_lshl_add_u64 v[12:13], v[4:5], 0, s[16:17]
	s_or_b32 s12, s11, 0xc00
	s_mov_b32 m0, s12
	s_nop 0
	global_load_lds_dwordx4 v[12:13], off
	v_lshl_add_u64 v[10:11], v[2:3], 0, v[182:183]
	v_lshl_add_u64 v[2:3], v[2:3], 0, v[8:9]
	s_add_i32 s12, s11, 0x4000
	s_mov_b32 m0, s12
	s_nop 0
	global_load_lds_dwordx4 v[10:11], off
	v_lshl_add_u64 v[8:9], v[2:3], 0, s[18:19]
	s_add_i32 s12, s11, 0x4400
	s_mov_b32 m0, s12
	s_nop 0
	global_load_lds_dwordx4 v[8:9], off
	v_lshl_add_u64 v[8:9], v[10:11], 0, s[14:15]
	s_add_i32 s12, s11, 0x4800
	s_mov_b32 m0, s12
	s_nop 0
	global_load_lds_dwordx4 v[8:9], off
	v_lshl_add_u64 v[8:9], v[2:3], 0, s[16:17]
	s_add_i32 s12, s11, 0x4c00
	s_mov_b32 m0, s12
	s_nop 0
	global_load_lds_dwordx4 v[8:9], off
	s_waitcnt vmcnt(0)
	s_barrier
	s_add_i32 s13, s11, 0x8000
	v_lshl_add_u64 v[8:9], v[6:7], 0, s[28:29]
	s_mov_b32 m0, s13
	s_nop 0
	global_load_lds_dwordx4 v[8:9], off
	s_mov_b64 s[18:19], 0x880
	v_lshl_add_u64 v[8:9], v[4:5], 0, s[18:19]
	s_add_i32 s13, s11, 0x8400
	s_mov_b32 m0, s13
	s_nop 0
	global_load_lds_dwordx4 v[8:9], off
	s_mov_b64 s[20:21], 0x1080
	v_lshl_add_u64 v[6:7], v[6:7], 0, s[20:21]
	s_add_i32 s13, s11, 0x8800
	s_mov_b32 m0, s13
	s_nop 0
	global_load_lds_dwordx4 v[6:7], off
	s_mov_b64 s[16:17], 0x1880
	v_lshl_add_u64 v[4:5], v[4:5], 0, s[16:17]
	s_add_i32 s13, s11, 0x8c00
	s_mov_b32 m0, s13
	s_nop 0
	global_load_lds_dwordx4 v[4:5], off
	s_add_i32 s12, s11, 0xc000
	v_lshl_add_u64 v[12:13], v[10:11], 0, s[28:29]
	s_mov_b32 m0, s12
	s_nop 0
	global_load_lds_dwordx4 v[12:13], off
	v_lshl_add_u64 v[4:5], v[2:3], 0, s[18:19]
	s_add_i32 s12, s11, 0xc400
	s_mov_b32 m0, s12
	s_nop 0
	global_load_lds_dwordx4 v[4:5], off
	v_lshrrev_b32_e32 v14, 1, v72
	v_lshl_add_u64 v[4:5], v[10:11], 0, s[20:21]
	s_add_i32 s12, s11, 0xc800
	s_mov_b32 m0, s12
	s_nop 0
	global_load_lds_dwordx4 v[4:5], off
	v_lshl_add_u64 v[2:3], v[2:3], 0, s[16:17]
	v_and_b32_e32 v112, 15, v72
	v_ashrrev_i32_e32 v114, 7, v72
	s_add_i32 s11, s11, 0xcc00
	s_mov_b32 m0, s11
	s_nop 0
	global_load_lds_dwordx4 v[2:3], off
	v_bitop3_b32 v2, v113, v14, 7 bitop3:0x78
	v_lshlrev_b32_e32 v2, 4, v2
	v_lshlrev_b32_e32 v76, 7, v112
	v_lshlrev_b32_e32 v73, 13, v114
	s_waitcnt vmcnt(1)
	v_or3_b32 v100, v2, v73, v76
	ds_read_b128 v[4:7], v100 offset:16384
	ds_read_b128 v[36:39], v100 offset:18432
	ds_read_b128 v[52:55], v100 offset:20480
	ds_read_b128 v[68:71], v100 offset:22528
	v_and_b32_e32 v115, 1, v1
	v_lshlrev_b32_e32 v77, 13, v115
	v_bfe_u32 v72, v72, 1, 3
	v_or3_b32 v84, v2, v77, v76
	v_bitop3_b32 v72, v113, v72, 4 bitop3:0x36
	ds_read_b128 v[8:11], v84
	ds_read_b128 v[16:19], v84 offset:2048
	ds_read_b128 v[24:27], v84 offset:4096
	ds_read_b128 v[32:35], v84 offset:6144
	v_lshlrev_b32_e32 v78, 4, v72
	v_or_b32_e32 v72, v78, v73
	v_add_u32_e32 v116, v72, v76
	ds_read_b128 v[72:75], v116 offset:16384
	v_mov_b32_e32 v1, v0
	v_mov_b32_e32 v2, v0
	v_mov_b32_e32 v3, v0
	v_readlane_b32 s57, v252, 9
	v_readlane_b32 s58, v252, 10
	s_waitcnt lgkmcnt(4)
	v_mfma_f32_16x16x32_bf16 v[12:15], v[4:7], v[8:11], v[0:3]
	v_readlane_b32 s59, v252, 11
	v_readlane_b32 s60, v252, 12
	v_readlane_b32 s61, v252, 13
	s_waitcnt lgkmcnt(3)
	v_mfma_f32_16x16x32_bf16 v[20:23], v[4:7], v[16:19], v[0:3]
	v_readlane_b32 s62, v252, 14
	v_readlane_b32 s63, v252, 15
	v_readlane_b32 s64, v252, 16
	s_waitcnt lgkmcnt(2)
	v_mfma_f32_16x16x32_bf16 v[28:31], v[4:7], v[24:27], v[0:3]
	v_readlane_b32 s65, v252, 17
	v_readlane_b32 s68, v252, 20
	v_readlane_b32 s69, v252, 21
	s_waitcnt lgkmcnt(1)
; template <int MT, class Epi>
; DI void gemm_tile(const u16* __restrict__ X, long ldx, const u16* __restrict__ W, long ldw, int K, char* smem,
;                   int m0, int n0, const Epi& epi, bool pre = false, const u16* Xn = nullptr, const u16* Wn = nullptr) {
;     ...
; #pragma unroll
;     for (int ks = 0; ks < 2; ++ks) {
;       bf16x8 xf[MT], wf[4];
;       const int ch = ((ks * 4 + g) ^ rsw) << 4;
; #pragma unroll
;       for (int i = 0; i < MT; ++i) xf[i] = *(const bf16x8*)(cur + (wm * 16 * MT + i * 16 + lr) * 128 + ch);
; #pragma unroll
;       for (int i = 0; i < 4; ++i) wf[i] = *(const bf16x8*)(cur + 16384 + (wn * 64 + i * 16 + lr) * 128 + ch);
; #pragma unroll
;       for (int nt = 0; nt < 4; ++nt)
; #pragma unroll
;         for (int mt = 0; mt < MT; ++mt)
;           acc[nt][mt] = __builtin_amdgcn_mfma_f32_16x16x32_bf16(wf[nt], xf[mt], acc[nt][mt], 0, 0, 0);
;     }
;   } while (++kt < nk);
;     ...
;   epi.run(acc, m0 + wm * 16 * MT + lr, n0 + wn * 64 + 4 * g);
;   template <int NT, int MT> DI void run(f32x4 (&acc)[NT][MT], int mb, int nb) const {
; #pragma unroll
;     for (int mt = 0; mt < MT; ++mt) {
;       const int i = mb + mt * 16;
;       if (i < nvalid) {
	v_mfma_f32_16x16x32_bf16 v[4:7], v[4:7], v[32:35], v[0:3]
	v_readlane_b32 s70, v252, 22
	v_readlane_b32 s71, v252, 23
	v_mfma_f32_16x16x32_bf16 v[40:43], v[36:39], v[8:11], v[0:3]
	v_mfma_f32_16x16x32_bf16 v[44:47], v[36:39], v[16:19], v[0:3]
	v_mfma_f32_16x16x32_bf16 v[48:51], v[36:39], v[24:27], v[0:3]
	v_mfma_f32_16x16x32_bf16 v[36:39], v[36:39], v[32:35], v[0:3]
	v_mfma_f32_16x16x32_bf16 v[56:59], v[52:55], v[8:11], v[0:3]
	v_mfma_f32_16x16x32_bf16 v[60:63], v[52:55], v[16:19], v[0:3]
	v_mfma_f32_16x16x32_bf16 v[64:67], v[52:55], v[24:27], v[0:3]
	v_mfma_f32_16x16x32_bf16 v[52:55], v[52:55], v[32:35], v[0:3]
	v_mfma_f32_16x16x32_bf16 v[8:11], v[68:71], v[8:11], v[0:3]
	v_mfma_f32_16x16x32_bf16 v[16:19], v[68:71], v[16:19], v[0:3]
	v_mfma_f32_16x16x32_bf16 v[24:27], v[68:71], v[24:27], v[0:3]
	v_mfma_f32_16x16x32_bf16 v[0:3], v[68:71], v[32:35], v[0:3]
	v_or_b32_e32 v32, v78, v77
	v_add_u32_e32 v108, v32, v76
	ds_read_b128 v[32:35], v108
	ds_read_b128 v[68:71], v108 offset:2048
	ds_read_b128 v[76:79], v108 offset:4096
	ds_read_b128 v[80:83], v108 offset:6144
	s_waitcnt lgkmcnt(3)
	v_mfma_f32_16x16x32_bf16 v[12:15], v[72:75], v[32:35], v[12:15]
	s_waitcnt lgkmcnt(2)
	v_mfma_f32_16x16x32_bf16 v[20:23], v[72:75], v[68:71], v[20:23]
	s_waitcnt lgkmcnt(1)
	v_mfma_f32_16x16x32_bf16 v[28:31], v[72:75], v[76:79], v[28:31]
	s_waitcnt lgkmcnt(0)
	v_mfma_f32_16x16x32_bf16 v[4:7], v[72:75], v[80:83], v[4:7]
	ds_read_b128 v[72:75], v116 offset:18432
	s_waitcnt lgkmcnt(0)
	v_mfma_f32_16x16x32_bf16 v[40:43], v[72:75], v[32:35], v[40:43]
	v_mfma_f32_16x16x32_bf16 v[44:47], v[72:75], v[68:71], v[44:47]
	v_mfma_f32_16x16x32_bf16 v[48:51], v[72:75], v[76:79], v[48:51]
	v_mfma_f32_16x16x32_bf16 v[36:39], v[72:75], v[80:83], v[36:39]
	ds_read_b128 v[72:75], v116 offset:20480
	s_waitcnt lgkmcnt(0)
	v_mfma_f32_16x16x32_bf16 v[56:59], v[72:75], v[32:35], v[56:59]
	v_mfma_f32_16x16x32_bf16 v[60:63], v[72:75], v[68:71], v[60:63]
	v_mfma_f32_16x16x32_bf16 v[64:67], v[72:75], v[76:79], v[64:67]
	v_mfma_f32_16x16x32_bf16 v[52:55], v[72:75], v[80:83], v[52:55]
	ds_read_b128 v[72:75], v116 offset:22528
	s_waitcnt vmcnt(0)
	s_waitcnt lgkmcnt(0)
	v_mfma_f32_16x16x32_bf16 v[8:11], v[72:75], v[32:35], v[8:11]
	s_barrier
	ds_read_b128 v[32:35], v100 offset:49152
	ds_read_b128 v[104:107], v108 offset:36864
	v_mfma_f32_16x16x32_bf16 v[16:19], v[72:75], v[68:71], v[16:19]
	ds_read_b128 v[68:71], v84 offset:32768
	v_mfma_f32_16x16x32_bf16 v[24:27], v[72:75], v[76:79], v[24:27]
	ds_read_b128 v[76:79], v84 offset:36864
	v_mfma_f32_16x16x32_bf16 v[0:3], v[72:75], v[80:83], v[0:3]
	ds_read_b128 v[72:75], v84 offset:34816
	ds_read_b128 v[80:83], v84 offset:38912
	s_waitcnt lgkmcnt(3)
	v_mfma_f32_16x16x32_bf16 v[12:15], v[32:35], v[68:71], v[12:15]
	s_waitcnt lgkmcnt(1)
	v_mfma_f32_16x16x32_bf16 v[20:23], v[32:35], v[72:75], v[20:23]
	v_mfma_f32_16x16x32_bf16 v[28:31], v[32:35], v[76:79], v[28:31]
	s_waitcnt lgkmcnt(0)
	v_mfma_f32_16x16x32_bf16 v[4:7], v[32:35], v[80:83], v[4:7]
	ds_read_b128 v[32:35], v100 offset:51200
	s_waitcnt lgkmcnt(0)
	v_mfma_f32_16x16x32_bf16 v[40:43], v[32:35], v[68:71], v[40:43]
	v_mfma_f32_16x16x32_bf16 v[84:87], v[32:35], v[72:75], v[44:47]
	v_mfma_f32_16x16x32_bf16 v[48:51], v[32:35], v[76:79], v[48:51]
	v_mfma_f32_16x16x32_bf16 v[32:35], v[32:35], v[80:83], v[36:39]
	s_nop 2
	ds_read_b128 v[36:39], v100 offset:53248
	s_waitcnt lgkmcnt(0)
	v_mfma_f32_16x16x32_bf16 v[88:91], v[36:39], v[68:71], v[56:59]
	v_mfma_f32_16x16x32_bf16 v[92:95], v[36:39], v[72:75], v[60:63]
	v_mfma_f32_16x16x32_bf16 v[64:67], v[36:39], v[76:79], v[64:67]
	s_waitcnt vmcnt(0)
	v_mfma_f32_16x16x32_bf16 v[96:99], v[36:39], v[80:83], v[52:55]
	ds_read_b128 v[36:39], v100 offset:55296
	ds_read_b128 v[100:103], v108 offset:34816
	s_waitcnt lgkmcnt(1)
	v_mfma_f32_16x16x32_bf16 v[68:71], v[36:39], v[68:71], v[8:11]
	s_nop 2
	ds_read_b128 v[8:11], v116 offset:49152
	v_mfma_f32_16x16x32_bf16 v[16:19], v[36:39], v[72:75], v[16:19]
	v_mfma_f32_16x16x32_bf16 v[74:77], v[36:39], v[76:79], v[24:27]
	v_mfma_f32_16x16x32_bf16 v[0:3], v[36:39], v[80:83], v[0:3]
	ds_read_b128 v[78:81], v108 offset:32768
	ds_read_b128 v[108:111], v108 offset:38912
	s_waitcnt lgkmcnt(1)
	v_mfma_f32_16x16x32_bf16 v[60:63], v[8:11], v[78:81], v[12:15]
	s_waitcnt lgkmcnt(0)
	v_mfma_f32_16x16x32_bf16 v[12:15], v[8:11], v[108:111], v[4:7]
	s_nop 2
	ds_read_b128 v[4:7], v116 offset:51200
	v_mfma_f32_16x16x32_bf16 v[44:47], v[8:11], v[100:103], v[20:23]
	v_mfma_f32_16x16x32_bf16 v[28:31], v[8:11], v[104:107], v[28:31]
	s_waitcnt lgkmcnt(0)
	v_mfma_f32_16x16x32_bf16 v[56:59], v[4:7], v[78:81], v[40:43]
	v_mfma_f32_16x16x32_bf16 v[40:43], v[4:7], v[100:103], v[84:87]
	v_mfma_f32_16x16x32_bf16 v[24:27], v[4:7], v[104:107], v[48:51]
	s_nop 1
	ds_read_b128 v[82:85], v116 offset:55296
	v_mfma_f32_16x16x32_bf16 v[8:11], v[4:7], v[108:111], v[32:35]
	ds_read_b128 v[4:7], v116 offset:53248
	s_nop 1
	v_lshl_add_u32 v32, v114, 6, s10
	s_waitcnt lgkmcnt(0)
	v_mfma_f32_16x16x32_bf16 v[52:55], v[4:7], v[78:81], v[88:91]
	v_mfma_f32_16x16x32_bf16 v[36:39], v[4:7], v[100:103], v[92:95]
	v_mfma_f32_16x16x32_bf16 v[20:23], v[4:7], v[104:107], v[64:67]
	v_mfma_f32_16x16x32_bf16 v[4:7], v[4:7], v[108:111], v[96:99]
	s_nop 1
	v_lshl_or_b32 v64, v113, 2, v32
	v_mfma_f32_16x16x32_bf16 v[48:51], v[82:85], v[78:81], v[68:71]
	v_lshl_or_b32 v78, v115, 6, v112
	v_cmp_gt_u32_e32 vcc, s8, v78
	v_lshlrev_b32_e32 v73, 2, v78
	v_mfma_f32_16x16x32_bf16 v[32:35], v[82:85], v[100:103], v[16:19]
	v_add_u32_e32 v70, s9, v64
	v_ashrrev_i32_e32 v71, 31, v70
	v_add_u32_e32 v68, 16, v70
	v_mfma_f32_16x16x32_bf16 v[16:19], v[82:85], v[104:107], v[74:77]
	v_add_u32_e32 v66, 32, v70
	v_add_u32_e32 v64, 48, v70
	v_mfma_f32_16x16x32_bf16 v[0:3], v[82:85], v[108:111], v[0:3]
	s_and_saveexec_b64 s[42:43], vcc
	s_cbranch_execz .LBB0_1150
; DI float bflo(unsigned u) { return __uint_as_float(u << 16); }
; DI float bfhi(unsigned u) { return __uint_as_float(u & 0xffff0000u); }
; DI void st_bf4(u16* p, float a, float b, float c, float d) { *(uint2*)p = make_uint2(pk2(a, b), pk2(c, d)); }
;   template <int NT, int MT> DI void run(f32x4 (&acc)[NT][MT], int mb, int nb) const {
; #pragma unroll
;     for (int mt = 0; mt < MT; ++mt) {
;       const int i = mb + mt * 16;
;       if (i < nvalid) {
;         const float bias = bs[i];
;         const size_t row = (size_t)(rowbase + i);
; #pragma unroll
;         for (int nt = 0; nt < NT; ++nt) {
;           const int ch = g * 256 + nb + nt * 16;
;           const uint2 uu = *(const uint2*)(uv + row * 2048 + ch);
;           u16* q = mix + row * 2048 + 1024 + ch;
;           const uint2 gt = *(const uint2*)q;
;           f32x4 v = acc[nt][mt];
;           st_bf4(q, (v[0] + bias) * bflo(uu.x) * bflo(gt.x), (v[1] + bias) * bfhi(uu.x) * bfhi(gt.x),
;                  (v[2] + bias) * bflo(uu.y) * bflo(gt.y), (v[3] + bias) * bfhi(uu.y) * bfhi(gt.y));
;         }
;       }
;     }
;   }
	v_mov_b32_e32 v135, v183
	v_add_u32_e32 v134, s7, v78
	v_readlane_b32 s10, v252, 33
	v_lshlrev_b64 v[136:137], 12, v[134:135]
	v_readlane_b32 s11, v252, 34
	v_lshlrev_b64 v[138:139], 1, v[70:71]
	global_load_dword v140, v73, s[40:41]
	v_lshl_add_u64 v[142:143], s[10:11], 0, v[136:137]
	v_readlane_b32 s10, v252, 35
	v_readlane_b32 s11, v252, 36
	v_lshl_add_u64 v[144:145], v[142:143], 0, v[138:139]
	global_load_dwordx2 v[146:147], v[144:145], off
	v_lshl_add_u64 v[148:149], s[10:11], 0, v[136:137]
	v_lshl_add_u64 v[150:151], v[148:149], 0, v[138:139]
	global_load_dwordx2 v[152:153], v[150:151], off offset:2048
	v_ashrrev_i32_e32 v141, 31, v68
	v_ashrrev_i32_e32 v154, 31, v66
	v_ashrrev_i32_e32 v155, 31, v64
	v_mov_b32_e32 v190, v68
	v_mov_b32_e32 v191, v141
	v_lshlrev_b64 v[156:157], 1, v[190:191]
	v_lshl_add_u64 v[158:159], v[142:143], 0, v[156:157]
	global_load_dwordx2 v[160:161], v[158:159], off
	v_lshl_add_u64 v[162:163], v[148:149], 0, v[156:157]
	global_load_dwordx2 v[164:165], v[162:163], off offset:2048
	v_mov_b32_e32 v192, v66
	v_mov_b32_e32 v193, v154
	v_lshlrev_b64 v[166:167], 1, v[192:193]
	v_lshl_add_u64 v[168:169], v[142:143], 0, v[166:167]
	global_load_dwordx2 v[170:171], v[168:169], off
	v_lshl_add_u64 v[172:173], v[148:149], 0, v[166:167]
	global_load_dwordx2 v[174:175], v[172:173], off offset:2048
	v_mov_b32_e32 v194, v64
	v_mov_b32_e32 v195, v155
	v_lshlrev_b64 v[176:177], 1, v[194:195]
	v_lshl_add_u64 v[178:179], v[142:143], 0, v[176:177]
	global_load_dwordx2 v[180:181], v[178:179], off
	v_lshl_add_u64 v[186:187], v[148:149], 0, v[176:177]
	global_load_dwordx2 v[188:189], v[186:187], off offset:2048
	s_nop 0
	s_nop 0
	s_nop 0
	s_nop 0
	s_nop 0
	s_nop 0
	s_nop 0
	s_nop 0
	s_nop 0
	s_nop 0
	s_nop 0
	s_nop 0
	s_nop 0
	s_nop 0
	s_nop 0
	s_nop 0
	s_nop 0
	s_waitcnt vmcnt(8)
	v_mov_b32_e32 v196, v140
	v_mov_b32_e32 v197, v73
	v_pk_add_f32 v[60:61], v[60:61], v[196:197] op_sel_hi:[1,0]
	v_mov_b32_e32 v224, v140
	v_mov_b32_e32 v225, v73
	v_pk_add_f32 v[62:63], v[62:63], v[224:225] op_sel_hi:[1,0]
	v_mov_b32_e32 v226, v140
	v_mov_b32_e32 v227, v73
	v_pk_add_f32 v[56:57], v[56:57], v[226:227] op_sel_hi:[1,0]
	v_mov_b32_e32 v228, v140
	v_mov_b32_e32 v229, v73
	v_pk_add_f32 v[58:59], v[58:59], v[228:229] op_sel_hi:[1,0]
	v_mov_b32_e32 v230, v140
	v_mov_b32_e32 v231, v73
	v_pk_add_f32 v[52:53], v[52:53], v[230:231] op_sel_hi:[1,0]
	s_waitcnt vmcnt(7)
	v_lshlrev_b32_e32 v86, 16, v146
	v_and_b32_e32 v87, 0xffff0000, v146
	v_lshlrev_b32_e32 v82, 16, v147
	v_and_b32_e32 v83, 0xffff0000, v147
	s_waitcnt vmcnt(6)
	v_lshlrev_b32_e32 v88, 16, v152
	v_and_b32_e32 v89, 0xffff0000, v152
	v_pk_mul_f32 v[60:61], v[60:61], v[86:87]
	v_lshlrev_b32_e32 v84, 16, v153
	v_and_b32_e32 v85, 0xffff0000, v153
	v_pk_mul_f32 v[62:63], v[62:63], v[82:83]
	v_pk_mul_f32 v[60:61], v[60:61], v[88:89]
	v_pk_mul_f32 v[62:63], v[62:63], v[84:85]
	v_cvt_pk_bf16_f32 v60, v60, v61
	v_cvt_pk_bf16_f32 v61, v62, v63
	global_store_dwordx2 v[150:151], v[60:61], off offset:2048
	s_nop 0
	s_nop 0
	s_nop 0
	s_nop 0
	s_nop 0
	v_mov_b32_e32 v232, v140
	v_mov_b32_e32 v233, v73
	v_pk_add_f32 v[54:55], v[54:55], v[232:233] op_sel_hi:[1,0]
	v_mov_b32_e32 v234, v140
	v_mov_b32_e32 v235, v73
	v_pk_add_f32 v[48:49], v[48:49], v[234:235] op_sel_hi:[1,0]
	v_mov_b32_e32 v236, v140
	v_mov_b32_e32 v237, v73
	v_pk_add_f32 v[50:51], v[50:51], v[236:237] op_sel_hi:[1,0]
	s_waitcnt vmcnt(5)
	v_lshlrev_b32_e32 v82, 16, v160
	v_and_b32_e32 v83, 0xffff0000, v160
	v_lshlrev_b32_e32 v62, 16, v161
	v_and_b32_e32 v63, 0xffff0000, v161
	s_waitcnt vmcnt(4)
	v_lshlrev_b32_e32 v84, 16, v164
	v_and_b32_e32 v85, 0xffff0000, v164
	v_pk_mul_f32 v[56:57], v[56:57], v[82:83]
	v_lshlrev_b32_e32 v80, 16, v165
	v_and_b32_e32 v81, 0xffff0000, v165
	v_pk_mul_f32 v[58:59], v[58:59], v[62:63]
	v_pk_mul_f32 v[56:57], v[56:57], v[84:85]
	v_pk_mul_f32 v[58:59], v[58:59], v[80:81]
	v_cvt_pk_bf16_f32 v56, v56, v57
	v_cvt_pk_bf16_f32 v57, v58, v59
	global_store_dwordx2 v[162:163], v[56:57], off offset:2048
	s_nop 0
	s_nop 0
	s_nop 0
	s_nop 0
	s_nop 0
	s_waitcnt vmcnt(3)
	v_lshlrev_b32_e32 v62, 16, v170
	v_and_b32_e32 v63, 0xffff0000, v170
	v_lshlrev_b32_e32 v58, 16, v171
	v_and_b32_e32 v59, 0xffff0000, v171
	s_waitcnt vmcnt(2)
	v_lshlrev_b32_e32 v80, 16, v174
	v_and_b32_e32 v81, 0xffff0000, v174
	v_pk_mul_f32 v[52:53], v[52:53], v[62:63]
	v_lshlrev_b32_e32 v60, 16, v175
	v_and_b32_e32 v61, 0xffff0000, v175
	v_pk_mul_f32 v[54:55], v[54:55], v[58:59]
	v_pk_mul_f32 v[52:53], v[52:53], v[80:81]
	v_pk_mul_f32 v[54:55], v[54:55], v[60:61]
	v_cvt_pk_bf16_f32 v52, v52, v53
	v_cvt_pk_bf16_f32 v53, v54, v55
	global_store_dwordx2 v[172:173], v[52:53], off offset:2048
	s_nop 0
	s_nop 0
	s_nop 0
	s_nop 0
	s_nop 0
	s_waitcnt vmcnt(1)
	v_lshlrev_b32_e32 v58, 16, v180
	v_and_b32_e32 v59, 0xffff0000, v180
	v_lshlrev_b32_e32 v54, 16, v181
	v_and_b32_e32 v55, 0xffff0000, v181
	s_waitcnt vmcnt(0)
	v_lshlrev_b32_e32 v60, 16, v188
	v_and_b32_e32 v61, 0xffff0000, v188
	v_pk_mul_f32 v[48:49], v[48:49], v[58:59]
	v_lshlrev_b32_e32 v56, 16, v189
	v_and_b32_e32 v57, 0xffff0000, v189
	v_pk_mul_f32 v[50:51], v[50:51], v[54:55]
	v_pk_mul_f32 v[48:49], v[48:49], v[60:61]
	v_pk_mul_f32 v[50:51], v[50:51], v[56:57]
	v_cvt_pk_bf16_f32 v48, v48, v49
	v_cvt_pk_bf16_f32 v49, v50, v51
	global_store_dwordx2 v[186:187], v[48:49], off offset:2048
	v_mov_b32_e32 v52, v186
	v_mov_b32_e32 v53, v187
	v_mov_b32_e32 v65, v155
	v_mov_b32_e32 v67, v154
	v_mov_b32_e32 v69, v141
	v_mov_b32_e32 v72, v140
	v_mov_b32_e32 v74, v142
	v_mov_b32_e32 v75, v143
	v_mov_b32_e32 v76, v148
	v_mov_b32_e32 v77, v149
	v_mov_b32_e32 v182, v134

; template <int MT, class Epi>
; DI void gemm_tile(const u16* __restrict__ X, long ldx, const u16* __restrict__ W, long ldw, int K, char* smem,
;                   int m0, int n0, const Epi& epi, bool pre = false, const u16* Xn = nullptr, const u16* Wn = nullptr) {
;     ...
;   const int wu = __builtin_amdgcn_readfirstlane(wave);
;   const unsigned sbase = (unsigned)__builtin_amdgcn_readfirstlane((int)(unsigned)(size_t)smem);
;   const int r8 = lane >> 3, c0 = (lane & 7) ^ (r8 >> 1);
;   const long oxe = (long)(wu * MT * 8 + r8) * ldx + (c0 << 3), oxo = (long)(wu * MT * 8 + r8) * ldx + ((c0 ^ 4) << 3);
;   const long owe = (long)(wu * 32 + r8) * ldw + (c0 << 3), owo = (long)(wu * 32 + r8) * ldw + ((c0 ^ 4) << 3);
;   const u16 *xe = X + oxe, *xo = X + oxo, *we = W + owe, *wo = W + owo;
;   const long ldx8 = 8 * ldx, ldw8 = 8 * ldw;
;   const unsigned xdst = sbase + wu * MT * 1024, wdst = sbase + 16384 + wu * 4096;
;     ...
;   if (!pre) {
;     __syncthreads();
;     GT_DMA(0u)
;   } else {
;     xe += 64; xo += 64; we += 64; wo += 64;
;   }
;   const int nk = K >> 6;
;   int kt = 0;
;   do {
;     asm volatile("s_waitcnt vmcnt(0)" ::: "memory");
;     __syncthreads();
;     if (kt + 1 < nk) GT_DMA((unsigned)((kt + 1) & 1) * 32768u)
; DI void phase_even(const Params& p, int e, int sub, char* smem) {
;     ...
;         const int g = t / 264, r = t % 264, tm = r >> 1, tn = r & 1;
;         EpiPool epi{p.pool_scale + e * 1024, gbuf, g};
;         gemm_tile<4>(hbuf + (size_t)tm * 128 * 1024 + g * 256, 1024, W + WE_POOL + (size_t)g * 65536 + (size_t)tn * 128 * 256, 256, 256, smem,
;                      tm * 128, tn * 128, epi);
.LBB0_1157:
	s_and_b64 vcc, exec, s[40:41]
	s_cbranch_vccz .LBB0_1146
	s_mul_hi_i32 s7, s4, 0x3e0f83e1
	s_lshr_b32 s8, s7, 31
	s_ashr_i32 s7, s7, 6
	s_add_i32 s8, s7, s8
	s_mul_i32 s7, s8, 0xfffffef8
	s_add_i32 s7, s4, s7
	s_ashr_i32 s10, s7, 1
	s_ashr_i32 s11, s10, 31
	s_and_b32 s16, s7, 1
	s_lshl_b64 s[12:13], s[10:11], 18
	s_add_u32 s7, s0, s12
	s_addc_u32 s9, s1, s13
	s_lshl_b32 s40, s8, 8
	s_ashr_i32 s41, s40, 31
	s_lshl_b64 s[12:13], s[40:41], 1
	s_add_u32 s12, s7, s12
	s_addc_u32 s13, s9, s13
	s_ashr_i32 s9, s8, 31
	s_lshl_b64 s[8:9], s[8:9], 17
	v_readlane_b32 s7, v252, 43
	s_add_u32 s7, s7, s8
	v_readlane_b32 s8, v252, 44
	s_waitcnt vmcnt(7)
	v_mov_b32_e32 v16, v185
	s_addc_u32 s8, s8, s9
	s_lshl_b32 s9, s16, 16
	s_add_u32 s14, s7, s9
	v_ashrrev_i32_e32 v0, 6, v16
	v_and_b32_e32 v53, 1, v0
	v_readfirstlane_b32 s9, v0
	v_bfe_u32 v0, v16, 3, 3
	v_bfe_u32 v54, v16, 4, 2
	v_lshl_or_b32 v0, s9, 5, v0
	v_bitop3_b32 v4, v54, v16, 7 bitop3:0x78
	v_ashrrev_i32_e32 v1, 31, v0
	v_lshlrev_b64 v[2:3], 11, v[0:1]
	v_lshlrev_b32_e32 v182, 4, v4
	v_mov_b32_e32 v10, v183
	v_lshl_add_u64 v[2:3], s[12:13], 0, v[2:3]
	v_xor_b32_e32 v6, 64, v182
	v_mov_b32_e32 v7, v183
	s_addc_u32 s15, s8, 0
	s_lshl_b32 s7, s10, 7
	v_lshl_add_u64 v[4:5], v[2:3], 0, v[182:183]
	v_lshl_add_u64 v[2:3], v[2:3], 0, v[6:7]
	s_lshl_b32 s41, s9, 12
	s_waitcnt lgkmcnt(0)
	s_barrier
	s_mov_b32 m0, s41
	s_nop 0
	global_load_lds_dwordx4 v[4:5], off
	s_mov_b64 s[10:11], 0x4000
	v_lshl_add_u64 v[14:15], v[2:3], 0, s[10:11]
	s_or_b32 s44, s41, 0x400
	s_mov_b32 m0, s44
	s_nop 0
	global_load_lds_dwordx4 v[14:15], off
	s_mov_b64 s[10:11], 0x8000
	v_lshlrev_b64 v[0:1], 9, v[0:1]
	v_lshl_add_u64 v[14:15], v[4:5], 0, s[10:11]
	s_or_b32 s42, s41, 0x800
	s_mov_b32 m0, s42
	s_nop 0
	global_load_lds_dwordx4 v[14:15], off
	s_mov_b64 s[10:11], 0xc000
	v_lshl_add_u64 v[8:9], s[14:15], 0, v[0:1]
	v_lshl_add_u64 v[14:15], v[2:3], 0, s[10:11]
	s_or_b32 s17, s41, 0xc00
	s_mov_b32 m0, s17
	s_nop 0
	global_load_lds_dwordx4 v[14:15], off
	v_lshl_add_u64 v[0:1], v[8:9], 0, v[182:183]
	v_lshl_add_u64 v[6:7], v[8:9], 0, v[6:7]
	s_add_i32 s18, s41, 0x4000
	s_mov_b32 m0, s18
	s_nop 0
	global_load_lds_dwordx4 v[0:1], off
	s_mov_b64 s[10:11], 0x1000
	v_lshl_add_u64 v[8:9], v[6:7], 0, s[10:11]
	s_add_i32 s19, s41, 0x4400
	s_mov_b32 m0, s19
	s_nop 0
	global_load_lds_dwordx4 v[8:9], off
	s_mov_b64 s[10:11], 0x2000
	v_lshl_add_u64 v[8:9], v[0:1], 0, s[10:11]
	s_add_i32 s34, s41, 0x4800
	s_mov_b32 m0, s34
	s_nop 0
	global_load_lds_dwordx4 v[8:9], off
	s_mov_b64 s[10:11], 0x3000
	v_lshl_add_u64 v[8:9], v[6:7], 0, s[10:11]
	s_add_i32 s43, s41, 0x4c00
	s_mov_b32 m0, s43
	s_nop 0
	global_load_lds_dwordx4 v[8:9], off
	s_waitcnt vmcnt(0)
	s_barrier
	v_lshl_add_u64 v[8:9], v[4:5], 0, s[28:29]
	s_add_i32 s14, s41, 0x8000
	s_mov_b32 m0, s14
	s_nop 0
	global_load_lds_dwordx4 v[8:9], off
	v_lshl_add_u64 v[8:9], v[2:3], 0, s[94:95]
	s_add_i32 s11, s41, 0x8400
	s_mov_b32 m0, s11
	s_nop 0
	global_load_lds_dwordx4 v[8:9], off
	v_lshl_add_u64 v[8:9], v[4:5], 0, s[78:79]
	s_add_i32 s9, s41, 0x8800
	s_mov_b32 m0, s9
	s_nop 0
	global_load_lds_dwordx4 v[8:9], off
	v_lshl_add_u64 v[8:9], v[2:3], 0, s[54:55]
	s_add_i32 s12, s41, 0x8c00
	s_mov_b32 m0, s12
	s_nop 0
	global_load_lds_dwordx4 v[8:9], off
	s_mov_b64 s[20:21], 0x1080
	v_lshl_add_u64 v[14:15], v[0:1], 0, s[28:29]
	s_add_i32 s10, s41, 0xc000
	s_mov_b32 m0, s10
	s_nop 0
	global_load_lds_dwordx4 v[14:15], off
	v_lshl_add_u64 v[8:9], v[6:7], 0, s[20:21]
	s_mov_b64 s[20:21], 0x2080
	s_add_i32 s15, s41, 0xc400
	s_mov_b32 m0, s15
	s_nop 0
	global_load_lds_dwordx4 v[8:9], off
	v_lshl_add_u64 v[8:9], v[0:1], 0, s[20:21]
	s_mov_b64 s[20:21], 0x3080
	s_lshl_b32 s8, s16, 7
	v_lshrrev_b32_e32 v17, 1, v16
	s_add_i32 s13, s41, 0xc800
	s_mov_b32 m0, s13
	s_nop 0
	global_load_lds_dwordx4 v[8:9], off
	v_lshl_add_u64 v[8:9], v[6:7], 0, s[20:21]
	v_and_b32_e32 v52, 15, v16
	v_ashrrev_i32_e32 v55, 7, v16
	s_add_i32 s16, s41, 0xcc00
	s_mov_b32 m0, s16
	s_nop 0
	global_load_lds_dwordx4 v[8:9], off
	v_bitop3_b32 v8, v54, v17, 7 bitop3:0x78
	v_lshlrev_b32_e32 v9, 4, v8
	v_lshlrev_b32_e32 v89, 13, v53
	s_waitcnt vmcnt(1)
	v_lshlrev_b32_e32 v100, 7, v52
	v_lshlrev_b32_e32 v101, 13, v55
	v_or3_b32 v8, v9, v89, v100
	v_or3_b32 v9, v9, v101, v100
	v_bfe_u32 v88, v16, 1, 3
	ds_read_b128 v[14:17], v8
	ds_read_b128 v[18:21], v8 offset:2048
	ds_read_b128 v[22:25], v8 offset:4096
	ds_read_b128 v[26:29], v8 offset:6144
	ds_read_b128 v[30:33], v9 offset:16384
	ds_read_b128 v[34:37], v9 offset:18432
	ds_read_b128 v[38:41], v9 offset:20480
	ds_read_b128 v[42:45], v9 offset:22528
	v_mov_b32_e32 v11, v10
	v_mov_b32_e32 v12, v10
	v_mov_b32_e32 v13, v10
	s_mov_b64 s[20:21], 0x100
	v_lshl_add_u64 v[50:51], v[4:5], 0, s[20:21]
	s_waitcnt lgkmcnt(3)
	v_mfma_f32_16x16x32_bf16 v[46:49], v[30:33], v[14:17], v[10:13]
	v_lshl_add_u64 v[116:117], v[0:1], 0, s[20:21]
	s_mov_b64 s[20:21], 0x4100
	v_lshlrev_b32_e32 v53, 6, v53
	v_mfma_f32_16x16x32_bf16 v[56:59], v[30:33], v[18:21], v[10:13]
	v_readlane_b32 s56, v252, 8
	v_readlane_b32 s58, v252, 10
	v_readlane_b32 s59, v252, 11
	v_mfma_f32_16x16x32_bf16 v[60:63], v[30:33], v[22:25], v[10:13]
	v_readlane_b32 s64, v252, 16
	v_readlane_b32 s65, v252, 17
	v_readlane_b32 s66, v252, 18
	v_mfma_f32_16x16x32_bf16 v[30:33], v[30:33], v[26:29], v[10:13]
	v_readlane_b32 s67, v252, 19
	v_readlane_b32 s68, v252, 20
	v_readlane_b32 s69, v252, 21
	s_waitcnt lgkmcnt(2)
; template <int MT, class Epi>
; DI void gemm_tile(const u16* __restrict__ X, long ldx, const u16* __restrict__ W, long ldw, int K, char* smem,
;                   int m0, int n0, const Epi& epi, bool pre = false, const u16* Xn = nullptr, const u16* Wn = nullptr) {
;     ...
;   do {
;     asm volatile("s_waitcnt vmcnt(0)" ::: "memory");
;     __syncthreads();
;     if (kt + 1 < nk) GT_DMA((unsigned)((kt + 1) & 1) * 32768u)
;     else if (Xn != nullptr) { xe = Xn + oxe; xo = Xn + oxo; we = Wn + owe; wo = Wn + owo; GT_DMA(0u) }
;     const char* cur = smem + (kt & 1) * 32768;
; #pragma unroll
;     for (int ks = 0; ks < 2; ++ks) {
;       bf16x8 xf[MT], wf[4];
;       const int ch = ((ks * 4 + g) ^ rsw) << 4;
; #pragma unroll
;       for (int i = 0; i < MT; ++i) xf[i] = *(const bf16x8*)(cur + (wm * 16 * MT + i * 16 + lr) * 128 + ch);
; #pragma unroll
;       for (int i = 0; i < 4; ++i) wf[i] = *(const bf16x8*)(cur + 16384 + (wn * 64 + i * 16 + lr) * 128 + ch);
; #pragma unroll
;       for (int nt = 0; nt < 4; ++nt)
; #pragma unroll
;         for (int mt = 0; mt < MT; ++mt)
;           acc[nt][mt] = __builtin_amdgcn_mfma_f32_16x16x32_bf16(wf[nt], xf[mt], acc[nt][mt], 0, 0, 0);
	v_mfma_f32_16x16x32_bf16 v[64:67], v[34:37], v[14:17], v[10:13]
	v_readlane_b32 s70, v252, 22
	v_readlane_b32 s71, v252, 23
	s_mov_b32 s65, 0x2aaaaaab
	v_mfma_f32_16x16x32_bf16 v[68:71], v[34:37], v[18:21], v[10:13]
	s_mov_b64 s[66:67], 0x5a8080
	s_movk_i32 s64, 0x41ff
	s_mov_b64 s[70:71], s[26:27]
	v_mfma_f32_16x16x32_bf16 v[72:75], v[34:37], v[22:25], v[10:13]
	s_mov_b64 s[68:69], s[24:25]
	v_readlane_b32 s57, v252, 9
	v_readlane_b32 s60, v252, 12
	v_mfma_f32_16x16x32_bf16 v[34:37], v[34:37], v[26:29], v[10:13]
	v_readlane_b32 s61, v252, 13
	v_readlane_b32 s62, v252, 14
	v_readlane_b32 s63, v252, 15
	s_waitcnt lgkmcnt(1)
	v_mfma_f32_16x16x32_bf16 v[76:79], v[38:41], v[14:17], v[10:13]
	v_mfma_f32_16x16x32_bf16 v[80:83], v[38:41], v[18:21], v[10:13]
	v_mfma_f32_16x16x32_bf16 v[84:87], v[38:41], v[22:25], v[10:13]
	v_mfma_f32_16x16x32_bf16 v[38:41], v[38:41], v[26:29], v[10:13]
	s_waitcnt lgkmcnt(0)
	v_mfma_f32_16x16x32_bf16 v[14:17], v[42:45], v[14:17], v[10:13]
	v_mfma_f32_16x16x32_bf16 v[18:21], v[42:45], v[18:21], v[10:13]
	v_mfma_f32_16x16x32_bf16 v[22:25], v[42:45], v[22:25], v[10:13]
	v_mfma_f32_16x16x32_bf16 v[26:29], v[42:45], v[26:29], v[10:13]
	s_nop 2
	v_bitop3_b32 v10, v54, v88, 4 bitop3:0x36
	v_lshlrev_b32_e32 v11, 4, v10
	v_or_b32_e32 v10, v11, v89
	v_or_b32_e32 v11, v11, v101
	v_add_u32_e32 v10, v10, v100
	v_add_u32_e32 v11, v11, v100
	ds_read_b128 v[42:45], v10
	ds_read_b128 v[88:91], v10 offset:2048
	ds_read_b128 v[92:95], v10 offset:4096
	s_waitcnt vmcnt(0)
	ds_read_b128 v[96:99], v10 offset:6144
	ds_read_b128 v[100:103], v11 offset:16384
	ds_read_b128 v[104:107], v11 offset:18432
	ds_read_b128 v[108:111], v11 offset:20480
	ds_read_b128 v[112:115], v11 offset:22528
	s_waitcnt vmcnt(0)
	s_waitcnt lgkmcnt(0)
	s_barrier
	s_mov_b32 m0, s41
	s_nop 0
	global_load_lds_dwordx4 v[50:51], off
	v_mfma_f32_16x16x32_bf16 v[12:15], v[112:115], v[42:45], v[14:17]
	v_mfma_f32_16x16x32_bf16 v[16:19], v[112:115], v[88:91], v[18:21]
	v_mfma_f32_16x16x32_bf16 v[20:23], v[112:115], v[92:95], v[22:25]
	v_mfma_f32_16x16x32_bf16 v[24:27], v[112:115], v[96:99], v[26:29]
	s_nop 2
	v_lshl_add_u64 v[28:29], v[2:3], 0, s[20:21]
	s_mov_b32 m0, s44
	s_nop 0
	global_load_lds_dwordx4 v[28:29], off
	s_mov_b64 s[20:21], 0x8100
	v_lshl_add_u64 v[28:29], v[4:5], 0, s[20:21]
	s_mov_b32 m0, s42
	s_nop 0
	global_load_lds_dwordx4 v[28:29], off
	s_mov_b64 s[20:21], 0xc100
	v_lshl_add_u64 v[28:29], v[2:3], 0, s[20:21]
	s_mov_b32 m0, s17
	s_nop 0
	global_load_lds_dwordx4 v[28:29], off
	s_mov_b32 m0, s18
	s_nop 0
	global_load_lds_dwordx4 v[116:117], off
	s_mov_b64 s[20:21], 0x1100
	v_lshl_add_u64 v[28:29], v[6:7], 0, s[20:21]
	s_mov_b32 m0, s19
	s_nop 0
	global_load_lds_dwordx4 v[28:29], off
	s_mov_b64 s[18:19], 0x2100
	v_lshl_add_u64 v[28:29], v[0:1], 0, s[18:19]
	s_mov_b32 m0, s34
	s_nop 0
	global_load_lds_dwordx4 v[28:29], off
	s_mov_b64 s[18:19], 0x3100
	v_lshl_add_u64 v[28:29], v[6:7], 0, s[18:19]
	s_mov_b32 m0, s43
	s_nop 0
	global_load_lds_dwordx4 v[28:29], off
	v_mfma_f32_16x16x32_bf16 v[46:49], v[100:103], v[42:45], v[46:49]
	s_mov_b64 s[18:19], 0x180
	v_lshl_add_u64 v[116:117], v[4:5], 0, s[18:19]
	v_lshl_add_u64 v[118:119], v[0:1], 0, s[18:19]
	v_mfma_f32_16x16x32_bf16 v[56:59], v[100:103], v[88:91], v[56:59]
	s_mov_b64 s[18:19], 0x4180
	v_mfma_f32_16x16x32_bf16 v[60:63], v[100:103], v[92:95], v[60:63]
	v_mfma_f32_16x16x32_bf16 v[30:33], v[100:103], v[96:99], v[30:33]
	v_mfma_f32_16x16x32_bf16 v[64:67], v[104:107], v[42:45], v[64:67]
	v_mfma_f32_16x16x32_bf16 v[68:71], v[104:107], v[88:91], v[68:71]
	v_mfma_f32_16x16x32_bf16 v[72:75], v[104:107], v[92:95], v[72:75]
	v_mfma_f32_16x16x32_bf16 v[34:37], v[104:107], v[96:99], v[34:37]
	v_mfma_f32_16x16x32_bf16 v[76:79], v[108:111], v[42:45], v[76:79]
	v_mfma_f32_16x16x32_bf16 v[80:83], v[108:111], v[88:91], v[80:83]
	v_mfma_f32_16x16x32_bf16 v[84:87], v[108:111], v[92:95], v[84:87]
	v_mfma_f32_16x16x32_bf16 v[38:41], v[108:111], v[96:99], v[38:41]
	ds_read_b128 v[42:45], v8 offset:32768
	ds_read_b128 v[88:91], v8 offset:34816
	ds_read_b128 v[92:95], v8 offset:36864
	ds_read_b128 v[96:99], v8 offset:38912
	ds_read_b128 v[100:103], v9 offset:49152
	ds_read_b128 v[104:107], v9 offset:51200
	ds_read_b128 v[108:111], v9 offset:53248
	ds_read_b128 v[112:115], v9 offset:55296
	s_waitcnt lgkmcnt(3)
	v_mfma_f32_16x16x32_bf16 v[46:49], v[100:103], v[42:45], v[46:49]
	v_mfma_f32_16x16x32_bf16 v[56:59], v[100:103], v[88:91], v[56:59]
	v_mfma_f32_16x16x32_bf16 v[60:63], v[100:103], v[92:95], v[60:63]
	v_mfma_f32_16x16x32_bf16 v[28:31], v[100:103], v[96:99], v[30:33]
	s_waitcnt lgkmcnt(2)
	v_mfma_f32_16x16x32_bf16 v[64:67], v[104:107], v[42:45], v[64:67]
	v_mfma_f32_16x16x32_bf16 v[68:71], v[104:107], v[88:91], v[68:71]
	v_mfma_f32_16x16x32_bf16 v[72:75], v[104:107], v[92:95], v[72:75]
	v_mfma_f32_16x16x32_bf16 v[32:35], v[104:107], v[96:99], v[34:37]
	s_waitcnt lgkmcnt(1)
	v_mfma_f32_16x16x32_bf16 v[76:79], v[108:111], v[42:45], v[76:79]
	v_mfma_f32_16x16x32_bf16 v[80:83], v[108:111], v[88:91], v[80:83]
	v_mfma_f32_16x16x32_bf16 v[84:87], v[108:111], v[92:95], v[84:87]
	v_mfma_f32_16x16x32_bf16 v[36:39], v[108:111], v[96:99], v[38:41]
	s_waitcnt lgkmcnt(0)
	v_mfma_f32_16x16x32_bf16 v[12:15], v[112:115], v[42:45], v[12:15]
	v_mfma_f32_16x16x32_bf16 v[16:19], v[112:115], v[88:91], v[16:19]
	v_mfma_f32_16x16x32_bf16 v[20:23], v[112:115], v[92:95], v[20:23]
	v_mfma_f32_16x16x32_bf16 v[24:27], v[112:115], v[96:99], v[24:27]
	ds_read_b128 v[40:43], v10 offset:32768
	ds_read_b128 v[88:91], v10 offset:34816
	ds_read_b128 v[92:95], v10 offset:36864
	ds_read_b128 v[96:99], v10 offset:38912
	ds_read_b128 v[100:103], v11 offset:49152
	ds_read_b128 v[104:107], v11 offset:51200
	ds_read_b128 v[108:111], v11 offset:53248
	ds_read_b128 v[112:115], v11 offset:55296
	s_waitcnt vmcnt(0)
	s_waitcnt lgkmcnt(0)
	s_barrier
; DI float bflo(unsigned u) { return __uint_as_float(u << 16); }
; DI float bfhi(unsigned u) { return __uint_as_float(u & 0xffff0000u); }
; DI void st_bf4(u16* p, float a, float b, float c, float d) { *(uint2*)p = make_uint2(pk2(a, b), pk2(c, d)); }
; template <int MT, class Epi>
; DI void gemm_tile(const u16* __restrict__ X, long ldx, const u16* __restrict__ W, long ldw, int K, char* smem,
;                   int m0, int n0, const Epi& epi, bool pre = false, const u16* Xn = nullptr, const u16* Wn = nullptr) {
;     ...
;   do {
;     asm volatile("s_waitcnt vmcnt(0)" ::: "memory");
;     __syncthreads();
;     if (kt + 1 < nk) GT_DMA((unsigned)((kt + 1) & 1) * 32768u)
;     else if (Xn != nullptr) { xe = Xn + oxe; xo = Xn + oxo; we = Wn + owe; wo = Wn + owo; GT_DMA(0u) }
;     const char* cur = smem + (kt & 1) * 32768;
; #pragma unroll
;     for (int ks = 0; ks < 2; ++ks) {
;       bf16x8 xf[MT], wf[4];
;       const int ch = ((ks * 4 + g) ^ rsw) << 4;
; #pragma unroll
;       for (int i = 0; i < MT; ++i) xf[i] = *(const bf16x8*)(cur + (wm * 16 * MT + i * 16 + lr) * 128 + ch);
; #pragma unroll
;       for (int i = 0; i < 4; ++i) wf[i] = *(const bf16x8*)(cur + 16384 + (wn * 64 + i * 16 + lr) * 128 + ch);
; #pragma unroll
;       for (int nt = 0; nt < 4; ++nt)
; #pragma unroll
;         for (int mt = 0; mt < MT; ++mt)
;           acc[nt][mt] = __builtin_amdgcn_mfma_f32_16x16x32_bf16(wf[nt], xf[mt], acc[nt][mt], 0, 0, 0);
;   template <int NT, int MT> DI void run(f32x4 (&acc)[NT][MT], int mb, int nb) const {
; #pragma unroll
;     for (int nt = 0; nt < NT; ++nt) {
;       const int ch = g * 256 + nb + nt * 16;
;       const float4 sc = *(const float4*)(scale + ch);
; #pragma unroll
;       for (int mt = 0; mt < MT; ++mt) {
;         const int m = mb + mt * 16;
;         u16* q = mix + (size_t)m * 2048 + ch;
;         const uint2 gt = *(const uint2*)q;
;         f32x4 v = acc[nt][mt];
;         st_bf4(q, v[0] * sc.x * bflo(gt.x), v[1] * sc.y * bfhi(gt.x), v[2] * sc.z * bflo(gt.y), v[3] * sc.w * bfhi(gt.y));
;       }
	s_mov_b32 m0, s14
	s_nop 0
	global_load_lds_dwordx4 v[116:117], off
	v_mfma_f32_16x16x32_bf16 v[44:47], v[100:103], v[40:43], v[46:49]
	v_mfma_f32_16x16x32_bf16 v[48:51], v[100:103], v[88:91], v[56:59]
	v_mfma_f32_16x16x32_bf16 v[56:59], v[100:103], v[92:95], v[60:63]
	v_mfma_f32_16x16x32_bf16 v[60:63], v[104:107], v[40:43], v[64:67]
	v_mfma_f32_16x16x32_bf16 v[64:67], v[104:107], v[88:91], v[68:71]
	v_mfma_f32_16x16x32_bf16 v[68:71], v[104:107], v[92:95], v[72:75]
	v_mfma_f32_16x16x32_bf16 v[72:75], v[108:111], v[40:43], v[76:79]
	v_mfma_f32_16x16x32_bf16 v[12:15], v[112:115], v[40:43], v[12:15]
	v_lshl_add_u64 v[40:41], v[2:3], 0, s[18:19]
	s_mov_b32 m0, s11
	s_nop 0
	global_load_lds_dwordx4 v[40:41], off
	s_mov_b64 s[18:19], 0x8180
	v_lshl_add_u64 v[4:5], v[4:5], 0, s[18:19]
	s_mov_b32 m0, s9
	s_nop 0
	global_load_lds_dwordx4 v[4:5], off
	s_mov_b64 s[18:19], 0xc180
	v_lshl_add_u64 v[2:3], v[2:3], 0, s[18:19]
	s_mov_b32 m0, s12
	s_nop 0
	global_load_lds_dwordx4 v[2:3], off
	v_mfma_f32_16x16x32_bf16 v[28:31], v[100:103], v[96:99], v[28:31]
	s_mov_b32 m0, s10
	s_nop 0
	global_load_lds_dwordx4 v[118:119], off
	s_mov_b64 s[10:11], 0x1180
	v_lshl_add_u64 v[2:3], v[6:7], 0, s[10:11]
	s_mov_b32 m0, s15
	s_nop 0
	global_load_lds_dwordx4 v[2:3], off
	s_mov_b64 s[10:11], 0x2180
	v_lshl_add_u64 v[0:1], v[0:1], 0, s[10:11]
	s_mov_b32 m0, s13
	s_nop 0
	global_load_lds_dwordx4 v[0:1], off
	s_mov_b64 s[10:11], 0x3180
	v_lshl_add_u64 v[0:1], v[6:7], 0, s[10:11]
	s_mov_b32 m0, s16
	s_nop 0
	global_load_lds_dwordx4 v[0:1], off
	v_mfma_f32_16x16x32_bf16 v[32:35], v[104:107], v[96:99], v[32:35]
	v_mfma_f32_16x16x32_bf16 v[76:79], v[108:111], v[88:91], v[80:83]
	v_mfma_f32_16x16x32_bf16 v[80:83], v[108:111], v[92:95], v[84:87]
	v_mfma_f32_16x16x32_bf16 v[36:39], v[108:111], v[96:99], v[36:39]
	v_mfma_f32_16x16x32_bf16 v[16:19], v[112:115], v[88:91], v[16:19]
	v_mfma_f32_16x16x32_bf16 v[20:23], v[112:115], v[92:95], v[20:23]
	v_mfma_f32_16x16x32_bf16 v[24:27], v[112:115], v[96:99], v[24:27]
	ds_read_b128 v[0:3], v8
	ds_read_b128 v[4:7], v8 offset:2048
	ds_read_b128 v[40:43], v8 offset:4096
	ds_read_b128 v[84:87], v8 offset:6144
	ds_read_b128 v[88:91], v9 offset:16384
	ds_read_b128 v[92:95], v9 offset:18432
	ds_read_b128 v[96:99], v9 offset:20480
	ds_read_b128 v[100:103], v9 offset:22528
	s_waitcnt lgkmcnt(3)
	v_mfma_f32_16x16x32_bf16 v[44:47], v[88:91], v[0:3], v[44:47]
	v_mfma_f32_16x16x32_bf16 v[48:51], v[88:91], v[4:7], v[48:51]
	v_mfma_f32_16x16x32_bf16 v[56:59], v[88:91], v[40:43], v[56:59]
	v_mfma_f32_16x16x32_bf16 v[28:31], v[88:91], v[84:87], v[28:31]
	s_waitcnt lgkmcnt(2)
	v_mfma_f32_16x16x32_bf16 v[60:63], v[92:95], v[0:3], v[60:63]
	v_mfma_f32_16x16x32_bf16 v[64:67], v[92:95], v[4:7], v[64:67]
	v_mfma_f32_16x16x32_bf16 v[68:71], v[92:95], v[40:43], v[68:71]
	v_mfma_f32_16x16x32_bf16 v[32:35], v[92:95], v[84:87], v[32:35]
	s_waitcnt lgkmcnt(1)
	v_mfma_f32_16x16x32_bf16 v[72:75], v[96:99], v[0:3], v[72:75]
	v_mfma_f32_16x16x32_bf16 v[76:79], v[96:99], v[4:7], v[76:79]
	v_mfma_f32_16x16x32_bf16 v[80:83], v[96:99], v[40:43], v[80:83]
	v_mfma_f32_16x16x32_bf16 v[36:39], v[96:99], v[84:87], v[36:39]
	s_waitcnt lgkmcnt(0)
	v_mfma_f32_16x16x32_bf16 v[0:3], v[100:103], v[0:3], v[12:15]
	v_mfma_f32_16x16x32_bf16 v[4:7], v[100:103], v[4:7], v[16:19]
	v_mfma_f32_16x16x32_bf16 v[12:15], v[100:103], v[40:43], v[20:23]
	v_mfma_f32_16x16x32_bf16 v[16:19], v[100:103], v[84:87], v[24:27]
	s_nop 1
	ds_read_b128 v[20:23], v10
	ds_read_b128 v[24:27], v10 offset:2048
	ds_read_b128 v[40:43], v10 offset:4096
	ds_read_b128 v[84:87], v10 offset:6144
	ds_read_b128 v[88:91], v11 offset:16384
	ds_read_b128 v[92:95], v11 offset:18432
	ds_read_b128 v[96:99], v11 offset:20480
	ds_read_b128 v[100:103], v11 offset:22528
	s_waitcnt vmcnt(0)
	s_waitcnt lgkmcnt(0)
	v_mfma_f32_16x16x32_bf16 v[68:71], v[92:95], v[40:43], v[68:71]
	s_barrier
	v_or3_b32 v134, v53, s7, v52
	v_lshl_add_u32 v135, v55, 6, s8
	v_lshl_or_b32 v136, v54, 2, v135
	v_ashrrev_i32_e32 v137, 31, v134
	v_readlane_b32 s8, v252, 35
	v_mov_b32_e32 v230, v134
	v_mov_b32_e32 v231, v137
	v_lshlrev_b64 v[138:139], 12, v[230:231]
	v_readlane_b32 s9, v252, 36
	v_add_u32_e32 v140, s40, v136
	v_ashrrev_i32_e32 v141, 31, v140
	v_lshl_add_u64 v[142:143], s[8:9], 0, v[138:139]
	v_lshl_add_u64 v[144:145], v[140:141], 2, s[58:59]
	global_load_dwordx4 v[146:149], v[144:145], off
	v_lshlrev_b64 v[150:151], 1, v[140:141]
	v_lshl_add_u64 v[152:153], v[142:143], 0, v[150:151]
	global_load_dwordx2 v[154:155], v[152:153], off
	v_or_b32_e32 v156, 16, v134
	v_ashrrev_i32_e32 v157, 31, v156
	v_lshlrev_b64 v[158:159], 12, v[156:157]
	v_lshl_add_u64 v[160:161], s[8:9], 0, v[158:159]
	v_lshl_add_u64 v[162:163], v[160:161], 0, v[150:151]
	global_load_dwordx2 v[164:165], v[162:163], off
	v_or_b32_e32 v166, 32, v134
	v_ashrrev_i32_e32 v167, 31, v166
	v_lshlrev_b64 v[168:169], 12, v[166:167]
	v_lshl_add_u64 v[170:171], s[8:9], 0, v[168:169]
	v_lshl_add_u64 v[172:173], v[170:171], 0, v[150:151]
	global_load_dwordx2 v[174:175], v[172:173], off
	v_or_b32_e32 v176, 48, v134
	v_ashrrev_i32_e32 v177, 31, v176
	v_lshlrev_b64 v[178:179], 12, v[176:177]
	v_lshl_add_u64 v[180:181], s[8:9], 0, v[178:179]
	v_lshl_add_u64 v[186:187], v[180:181], 0, v[150:151]
	global_load_dwordx2 v[188:189], v[186:187], off
	v_or_b32_e32 v190, 16, v140
	v_ashrrev_i32_e32 v191, 31, v190
	v_lshlrev_b64 v[192:193], 1, v[190:191]
	v_lshl_add_u64 v[194:195], v[190:191], 2, s[58:59]
	v_lshl_add_u64 v[196:197], v[142:143], 0, v[192:193]
	global_load_dwordx2 v[224:225], v[196:197], off
	global_load_dwordx4 v[226:229], v[194:195], off
	v_mfma_f32_16x16x32_bf16 v[44:47], v[88:91], v[20:23], v[44:47]
; DI float bflo(unsigned u) { return __uint_as_float(u << 16); }
; DI float bfhi(unsigned u) { return __uint_as_float(u & 0xffff0000u); }
; DI void st_bf4(u16* p, float a, float b, float c, float d) { *(uint2*)p = make_uint2(pk2(a, b), pk2(c, d)); }
; template <int MT, class Epi>
; DI void gemm_tile(const u16* __restrict__ X, long ldx, const u16* __restrict__ W, long ldw, int K, char* smem,
;                   int m0, int n0, const Epi& epi, bool pre = false, const u16* Xn = nullptr, const u16* Wn = nullptr) {
;     ...
;       for (int i = 0; i < MT; ++i) xf[i] = *(const bf16x8*)(cur + (wm * 16 * MT + i * 16 + lr) * 128 + ch);
; #pragma unroll
;       for (int i = 0; i < 4; ++i) wf[i] = *(const bf16x8*)(cur + 16384 + (wn * 64 + i * 16 + lr) * 128 + ch);
; #pragma unroll
;       for (int nt = 0; nt < 4; ++nt)
; #pragma unroll
;         for (int mt = 0; mt < MT; ++mt)
;           acc[nt][mt] = __builtin_amdgcn_mfma_f32_16x16x32_bf16(wf[nt], xf[mt], acc[nt][mt], 0, 0, 0);
;   template <int NT, int MT> DI void run(f32x4 (&acc)[NT][MT], int mb, int nb) const {
; #pragma unroll
;     for (int nt = 0; nt < NT; ++nt) {
;       const int ch = g * 256 + nb + nt * 16;
;       const float4 sc = *(const float4*)(scale + ch);
; #pragma unroll
;       for (int mt = 0; mt < MT; ++mt) {
;         const int m = mb + mt * 16;
;         u16* q = mix + (size_t)m * 2048 + ch;
;         const uint2 gt = *(const uint2*)q;
;         f32x4 v = acc[nt][mt];
;         st_bf4(q, v[0] * sc.x * bflo(gt.x), v[1] * sc.y * bfhi(gt.x), v[2] * sc.z * bflo(gt.y), v[3] * sc.w * bfhi(gt.y));
;       }
	v_mfma_f32_16x16x32_bf16 v[48:51], v[88:91], v[24:27], v[48:51]
	v_mfma_f32_16x16x32_bf16 v[56:59], v[88:91], v[40:43], v[56:59]
	v_mfma_f32_16x16x32_bf16 v[28:31], v[88:91], v[84:87], v[28:31]
	v_mfma_f32_16x16x32_bf16 v[60:63], v[92:95], v[20:23], v[60:63]
	v_mfma_f32_16x16x32_bf16 v[64:67], v[92:95], v[24:27], v[64:67]
	v_mfma_f32_16x16x32_bf16 v[32:35], v[92:95], v[84:87], v[32:35]
	v_mfma_f32_16x16x32_bf16 v[72:75], v[96:99], v[20:23], v[72:75]
	v_mfma_f32_16x16x32_bf16 v[76:79], v[96:99], v[24:27], v[76:79]
	v_mfma_f32_16x16x32_bf16 v[80:83], v[96:99], v[40:43], v[80:83]
	v_mfma_f32_16x16x32_bf16 v[36:39], v[96:99], v[84:87], v[36:39]
	v_mfma_f32_16x16x32_bf16 v[0:3], v[100:103], v[20:23], v[0:3]
	v_mfma_f32_16x16x32_bf16 v[4:7], v[100:103], v[24:27], v[4:7]
	v_mfma_f32_16x16x32_bf16 v[12:15], v[100:103], v[40:43], v[12:15]
	v_mfma_f32_16x16x32_bf16 v[16:19], v[100:103], v[84:87], v[16:19]
	ds_read_b128 v[84:87], v11 offset:55296
	ds_read_b128 v[88:91], v11 offset:53248
	ds_read_b128 v[20:23], v11 offset:51200
	ds_read_b128 v[24:27], v11 offset:49152
	ds_read_b128 v[92:95], v10 offset:38912
	ds_read_b128 v[96:99], v10 offset:36864
	ds_read_b128 v[100:103], v10 offset:34816
	ds_read_b128 v[104:107], v10 offset:32768
	ds_read_b128 v[40:43], v9 offset:55296
	ds_read_b128 v[108:111], v9 offset:53248
	ds_read_b128 v[112:115], v9 offset:51200
	ds_read_b128 v[116:119], v9 offset:49152
	ds_read_b128 v[120:123], v8 offset:38912
	ds_read_b128 v[124:127], v8 offset:36864
	ds_read_b128 v[128:131], v8 offset:34816
	ds_read_b128 v[8:11], v8 offset:32768
	s_waitcnt lgkmcnt(2)
	v_mfma_f32_16x16x32_bf16 v[68:71], v[112:115], v[124:127], v[68:71]
	s_waitcnt lgkmcnt(1)
	v_mfma_f32_16x16x32_bf16 v[64:67], v[112:115], v[128:131], v[64:67]
	v_mfma_f32_16x16x32_bf16 v[48:51], v[116:119], v[128:131], v[48:51]
	v_mfma_f32_16x16x32_bf16 v[28:31], v[116:119], v[120:123], v[28:31]
	s_waitcnt lgkmcnt(0)
	v_mfma_f32_16x16x32_bf16 v[72:75], v[108:111], v[8:11], v[72:75]
	v_mfma_f32_16x16x32_bf16 v[76:79], v[108:111], v[128:131], v[76:79]
	v_mfma_f32_16x16x32_bf16 v[80:83], v[108:111], v[124:127], v[80:83]
	v_mfma_f32_16x16x32_bf16 v[108:111], v[108:111], v[120:123], v[36:39]
	v_mfma_f32_16x16x32_bf16 v[36:39], v[20:23], v[96:99], v[68:71]
	s_nop 2
	s_nop 0
	s_nop 0
	s_nop 0
	v_mfma_f32_16x16x32_bf16 v[44:47], v[116:119], v[8:11], v[44:47]
	s_nop 0
	s_nop 0
	s_nop 0
	v_mfma_f32_16x16x32_bf16 v[56:59], v[116:119], v[124:127], v[56:59]
	s_nop 0
	v_mfma_f32_16x16x32_bf16 v[116:119], v[112:115], v[8:11], v[60:63]
	v_mfma_f32_16x16x32_bf16 v[32:35], v[112:115], v[120:123], v[32:35]
	v_mfma_f32_16x16x32_bf16 v[0:3], v[40:43], v[8:11], v[0:3]
	v_mfma_f32_16x16x32_bf16 v[4:7], v[40:43], v[128:131], v[4:7]
	v_mfma_f32_16x16x32_bf16 v[112:115], v[40:43], v[124:127], v[12:15]
	v_mfma_f32_16x16x32_bf16 v[120:123], v[40:43], v[120:123], v[16:19]
	v_mfma_f32_16x16x32_bf16 v[40:43], v[20:23], v[100:103], v[64:67]
	s_nop 2
	s_nop 0
	s_nop 0
	v_mfma_f32_16x16x32_bf16 v[60:63], v[24:27], v[100:103], v[48:51]
	s_nop 0
	s_nop 0
	s_nop 0
	v_mfma_f32_16x16x32_bf16 v[48:51], v[24:27], v[92:95], v[28:31]
	v_mfma_f32_16x16x32_bf16 v[28:31], v[88:91], v[104:107], v[72:75]
	s_waitcnt vmcnt(6)
	s_nop 1
	v_pk_mul_f32 v[60:61], v[60:61], v[146:147]
	s_nop 0
	s_nop 0
	s_nop 0
	v_mfma_f32_16x16x32_bf16 v[124:127], v[24:27], v[104:107], v[44:47]
	v_mul_f32_e64 v62, v62, v148
	v_mul_f32_e64 v63, v63, v149
	v_pk_mul_f32 v[48:49], v[48:49], v[146:147]
	v_pk_mul_f32 v[50:51], v[50:51], v[148:149]
	v_mfma_f32_16x16x32_bf16 v[56:59], v[24:27], v[96:99], v[56:59]
	v_mfma_f32_16x16x32_bf16 v[24:27], v[88:91], v[100:103], v[76:79]
	s_nop 2
	v_mul_f32_e64 v78, v124, v146
	v_mul_f32_e64 v79, v125, v147
	s_nop 1
	v_pk_mul_f32 v[56:57], v[56:57], v[146:147]
	v_pk_mul_f32 v[58:59], v[58:59], v[148:149]
	v_mfma_f32_16x16x32_bf16 v[44:47], v[20:23], v[104:107], v[116:119]
	s_waitcnt vmcnt(5)
	v_lshlrev_b32_e32 v76, 16, v154
	v_and_b32_e32 v77, 0xffff0000, v154
	v_pk_mul_f32 v[76:77], v[78:79], v[76:77]
	v_lshlrev_b32_e32 v74, 16, v155
	v_and_b32_e32 v75, 0xffff0000, v155
	v_pk_mul_f32 v[78:79], v[126:127], v[148:149]
	v_cvt_pk_bf16_f32 v76, v76, v77
	v_pk_mul_f32 v[74:75], v[78:79], v[74:75]
	v_mfma_f32_16x16x32_bf16 v[32:35], v[20:23], v[92:95], v[32:35]
	v_cvt_pk_bf16_f32 v77, v74, v75
	global_store_dwordx2 v[152:153], v[76:77], off
	s_nop 0
	s_nop 0
	s_nop 0
	s_nop 0
	s_nop 0
	s_nop 0
	v_mfma_f32_16x16x32_bf16 v[20:23], v[88:91], v[96:99], v[80:83]
	s_waitcnt vmcnt(4)
	v_lshlrev_b32_e32 v78, 16, v164
	v_and_b32_e32 v79, 0xffff0000, v164
	v_lshlrev_b32_e32 v76, 16, v165
	v_and_b32_e32 v77, 0xffff0000, v165
	v_pk_mul_f32 v[60:61], v[60:61], v[78:79]
	v_pk_mul_f32 v[62:63], v[62:63], v[76:77]
	v_cvt_pk_bf16_f32 v60, v60, v61
	v_cvt_pk_bf16_f32 v61, v62, v63
	global_store_dwordx2 v[162:163], v[60:61], off
	s_nop 0
	s_nop 0
	s_nop 0
	s_nop 0
	s_nop 0
	s_nop 0
	v_mfma_f32_16x16x32_bf16 v[16:19], v[88:91], v[92:95], v[108:111]
	s_waitcnt vmcnt(3)
	v_lshlrev_b32_e32 v76, 16, v174
	v_and_b32_e32 v77, 0xffff0000, v174
	v_lshlrev_b32_e32 v74, 16, v175
	v_and_b32_e32 v75, 0xffff0000, v175
	v_pk_mul_f32 v[56:57], v[56:57], v[76:77]
	v_pk_mul_f32 v[58:59], v[58:59], v[74:75]
	v_cvt_pk_bf16_f32 v56, v56, v57
	v_cvt_pk_bf16_f32 v57, v58, v59
	global_store_dwordx2 v[172:173], v[56:57], off
	s_nop 0
	s_nop 0
	s_nop 0
	s_nop 0
	s_nop 0
	s_nop 0
	v_mfma_f32_16x16x32_bf16 v[12:15], v[84:87], v[104:107], v[0:3]
	s_waitcnt vmcnt(2)
; DI float bflo(unsigned u) { return __uint_as_float(u << 16); }
; DI float bfhi(unsigned u) { return __uint_as_float(u & 0xffff0000u); }
; DI void st_bf4(u16* p, float a, float b, float c, float d) { *(uint2*)p = make_uint2(pk2(a, b), pk2(c, d)); }
;   template <int NT, int MT> DI void run(f32x4 (&acc)[NT][MT], int mb, int nb) const {
; #pragma unroll
;     for (int nt = 0; nt < NT; ++nt) {
;       const int ch = g * 256 + nb + nt * 16;
;       const float4 sc = *(const float4*)(scale + ch);
; #pragma unroll
;       for (int mt = 0; mt < MT; ++mt) {
;         const int m = mb + mt * 16;
;         u16* q = mix + (size_t)m * 2048 + ch;
;         const uint2 gt = *(const uint2*)q;
;         f32x4 v = acc[nt][mt];
;         st_bf4(q, v[0] * sc.x * bflo(gt.x), v[1] * sc.y * bfhi(gt.x), v[2] * sc.z * bflo(gt.y), v[3] * sc.w * bfhi(gt.y));
;       }
	v_lshlrev_b32_e32 v70, 16, v188
	v_and_b32_e32 v71, 0xffff0000, v188
	v_lshlrev_b32_e32 v52, 16, v189
	v_and_b32_e32 v53, 0xffff0000, v189
	v_pk_mul_f32 v[48:49], v[48:49], v[70:71]
	v_pk_mul_f32 v[50:51], v[50:51], v[52:53]
	v_cvt_pk_bf16_f32 v48, v48, v49
	v_cvt_pk_bf16_f32 v49, v50, v51
	global_store_dwordx2 v[186:187], v[48:49], off
	s_nop 0
	s_nop 0
	s_nop 0
	s_nop 0
	s_nop 0
	s_nop 0
	v_mfma_f32_16x16x32_bf16 v[8:11], v[84:87], v[100:103], v[4:7]
	s_nop 0
	s_waitcnt vmcnt(1)
	v_lshlrev_b32_e32 v62, 16, v224
	v_and_b32_e32 v63, 0xffff0000, v224
	s_waitcnt vmcnt(0)
	v_pk_mul_f32 v[44:45], v[44:45], v[226:227]
	v_lshlrev_b32_e32 v58, 16, v225
	v_and_b32_e32 v59, 0xffff0000, v225
	v_pk_mul_f32 v[46:47], v[46:47], v[228:229]
	v_pk_mul_f32 v[44:45], v[44:45], v[62:63]
	v_pk_mul_f32 v[46:47], v[46:47], v[58:59]
	v_cvt_pk_bf16_f32 v44, v44, v45
	v_cvt_pk_bf16_f32 v45, v46, v47
	global_store_dwordx2 v[196:197], v[44:45], off
	v_mov_b32_e32 v48, v226
	v_mov_b32_e32 v49, v227
	v_mov_b32_e32 v50, v228
	v_mov_b32_e32 v51, v229
	v_mov_b32_e32 v52, v192
	v_mov_b32_e32 v53, v193
	v_mov_b32_e32 v54, v196
	v_mov_b32_e32 v55, v197
	v_mov_b32_e32 v56, v180
	v_mov_b32_e32 v57, v181
	v_mov_b32_e32 v60, v170
	v_mov_b32_e32 v61, v171
	v_mov_b32_e32 v64, v140
	v_mov_b32_e32 v65, v141
	v_mov_b32_e32 v66, v142
	v_mov_b32_e32 v67, v143
	v_mov_b32_e32 v68, v160
	v_mov_b32_e32 v69, v161
	v_mov_b32_e32 v72, v150
	v_mov_b32_e32 v73, v151
	v_lshl_add_u64 v[134:135], v[68:69], 0, v[52:53]
	global_load_dwordx2 v[136:137], v[134:135], off
	v_lshl_add_u64 v[138:139], v[60:61], 0, v[52:53]
	global_load_dwordx2 v[140:141], v[138:139], off
	v_lshl_add_u64 v[142:143], v[56:57], 0, v[52:53]
	global_load_dwordx2 v[144:145], v[142:143], off
	v_or_b32_e32 v146, 32, v64
	v_ashrrev_i32_e32 v147, 31, v146
	v_lshl_add_u64 v[148:149], v[146:147], 2, s[58:59]
	v_lshlrev_b64 v[150:151], 1, v[146:147]
	v_lshl_add_u64 v[152:153], v[66:67], 0, v[150:151]
	global_load_dwordx4 v[154:157], v[148:149], off
	global_load_dwordx2 v[158:159], v[152:153], off
	v_lshl_add_u64 v[160:161], v[68:69], 0, v[150:151]
	global_load_dwordx2 v[162:163], v[160:161], off
	v_lshl_add_u64 v[164:165], v[60:61], 0, v[150:151]
	global_load_dwordx2 v[166:167], v[164:165], off
	v_lshl_add_u64 v[168:169], v[56:57], 0, v[150:151]
	global_load_dwordx2 v[170:171], v[168:169], off
	v_or_b32_e32 v172, 48, v64
	v_ashrrev_i32_e32 v173, 31, v172
	v_lshl_add_u64 v[174:175], v[172:173], 2, s[58:59]
	v_lshlrev_b64 v[176:177], 1, v[172:173]
	v_lshl_add_u64 v[178:179], v[66:67], 0, v[176:177]
	global_load_dwordx4 v[186:189], v[174:175], off
	global_load_dwordx2 v[180:181], v[178:179], off
	v_lshl_add_u64 v[190:191], v[68:69], 0, v[176:177]
	global_load_dwordx2 v[192:193], v[190:191], off
	v_lshl_add_u64 v[194:195], v[60:61], 0, v[176:177]
	global_load_dwordx2 v[196:197], v[194:195], off
	v_lshl_add_u64 v[224:225], v[56:57], 0, v[176:177]
	global_load_dwordx2 v[226:227], v[224:225], off
	s_nop 0
	s_nop 0
	v_pk_mul_f32 v[40:41], v[40:41], v[48:49]
	v_pk_mul_f32 v[42:43], v[42:43], v[50:51]
	v_pk_mul_f32 v[36:37], v[36:37], v[48:49]
	v_pk_mul_f32 v[38:39], v[38:39], v[50:51]
	v_pk_mul_f32 v[32:33], v[32:33], v[48:49]
	v_pk_mul_f32 v[34:35], v[34:35], v[50:51]
	v_mfma_f32_16x16x32_bf16 v[4:7], v[84:87], v[96:99], v[112:115]
	s_waitcnt vmcnt(12)
	v_lshlrev_b32_e32 v54, 16, v136
	v_and_b32_e32 v55, 0xffff0000, v136
	v_lshlrev_b32_e32 v46, 16, v137
	v_and_b32_e32 v47, 0xffff0000, v137
	v_pk_mul_f32 v[40:41], v[40:41], v[54:55]
	v_pk_mul_f32 v[42:43], v[42:43], v[46:47]
	v_cvt_pk_bf16_f32 v40, v40, v41
	v_cvt_pk_bf16_f32 v41, v42, v43
	global_store_dwordx2 v[134:135], v[40:41], off
	s_nop 0
	s_nop 0
	v_mfma_f32_16x16x32_bf16 v[0:3], v[84:87], v[92:95], v[120:123]
	s_waitcnt vmcnt(11)
	v_lshlrev_b32_e32 v44, 16, v140
	v_and_b32_e32 v45, 0xffff0000, v140
	v_lshlrev_b32_e32 v42, 16, v141
	v_and_b32_e32 v43, 0xffff0000, v141
	v_pk_mul_f32 v[36:37], v[36:37], v[44:45]
	v_pk_mul_f32 v[38:39], v[38:39], v[42:43]
	v_cvt_pk_bf16_f32 v36, v36, v37
	v_cvt_pk_bf16_f32 v37, v38, v39
	global_store_dwordx2 v[138:139], v[36:37], off
	s_nop 0
	s_nop 0
	s_waitcnt vmcnt(10)
; DI float bflo(unsigned u) { return __uint_as_float(u << 16); }
; DI float bfhi(unsigned u) { return __uint_as_float(u & 0xffff0000u); }
; DI void st_bf4(u16* p, float a, float b, float c, float d) { *(uint2*)p = make_uint2(pk2(a, b), pk2(c, d)); }
;   template <int NT, int MT> DI void run(f32x4 (&acc)[NT][MT], int mb, int nb) const {
; #pragma unroll
;     for (int nt = 0; nt < NT; ++nt) {
;       const int ch = g * 256 + nb + nt * 16;
;       const float4 sc = *(const float4*)(scale + ch);
; #pragma unroll
;       for (int mt = 0; mt < MT; ++mt) {
;         const int m = mb + mt * 16;
;         u16* q = mix + (size_t)m * 2048 + ch;
;         const uint2 gt = *(const uint2*)q;
;         f32x4 v = acc[nt][mt];
;         st_bf4(q, v[0] * sc.x * bflo(gt.x), v[1] * sc.y * bfhi(gt.x), v[2] * sc.z * bflo(gt.y), v[3] * sc.w * bfhi(gt.y));
;       }
	v_lshlrev_b32_e32 v40, 16, v144
	v_and_b32_e32 v41, 0xffff0000, v144
	v_lshlrev_b32_e32 v38, 16, v145
	v_and_b32_e32 v39, 0xffff0000, v145
	v_pk_mul_f32 v[32:33], v[32:33], v[40:41]
	v_pk_mul_f32 v[34:35], v[34:35], v[38:39]
	v_cvt_pk_bf16_f32 v32, v32, v33
	v_cvt_pk_bf16_f32 v33, v34, v35
	global_store_dwordx2 v[142:143], v[32:33], off
	s_nop 0
	s_nop 0
	s_nop 0
	s_nop 0
	s_nop 0
	s_nop 0
	s_waitcnt vmcnt(9)
	v_pk_mul_f32 v[28:29], v[28:29], v[154:155]
	s_nop 0
	v_pk_mul_f32 v[30:31], v[30:31], v[156:157]
	v_pk_mul_f32 v[24:25], v[24:25], v[154:155]
	v_pk_mul_f32 v[26:27], v[26:27], v[156:157]
	v_pk_mul_f32 v[20:21], v[20:21], v[154:155]
	v_pk_mul_f32 v[22:23], v[22:23], v[156:157]
	v_pk_mul_f32 v[16:17], v[16:17], v[154:155]
	v_pk_mul_f32 v[18:19], v[18:19], v[156:157]
	s_waitcnt vmcnt(8)
	v_lshlrev_b32_e32 v42, 16, v158
	v_and_b32_e32 v43, 0xffff0000, v158
	v_lshlrev_b32_e32 v40, 16, v159
	v_and_b32_e32 v41, 0xffff0000, v159
	v_pk_mul_f32 v[28:29], v[28:29], v[42:43]
	v_pk_mul_f32 v[30:31], v[30:31], v[40:41]
	v_cvt_pk_bf16_f32 v28, v28, v29
	v_cvt_pk_bf16_f32 v29, v30, v31
	global_store_dwordx2 v[152:153], v[28:29], off
	s_nop 0
	s_nop 0
	s_waitcnt vmcnt(7)
	v_lshlrev_b32_e32 v38, 16, v162
	v_and_b32_e32 v39, 0xffff0000, v162
	v_lshlrev_b32_e32 v30, 16, v163
	v_and_b32_e32 v31, 0xffff0000, v163
	v_pk_mul_f32 v[24:25], v[24:25], v[38:39]
	v_pk_mul_f32 v[26:27], v[26:27], v[30:31]
	v_cvt_pk_bf16_f32 v24, v24, v25
	v_cvt_pk_bf16_f32 v25, v26, v27
	global_store_dwordx2 v[160:161], v[24:25], off
	s_nop 0
	s_nop 0
	s_waitcnt vmcnt(6)
	v_lshlrev_b32_e32 v28, 16, v166
	v_and_b32_e32 v29, 0xffff0000, v166
	v_lshlrev_b32_e32 v26, 16, v167
	v_and_b32_e32 v27, 0xffff0000, v167
	v_pk_mul_f32 v[20:21], v[20:21], v[28:29]
	v_pk_mul_f32 v[22:23], v[22:23], v[26:27]
	v_cvt_pk_bf16_f32 v20, v20, v21
	v_cvt_pk_bf16_f32 v21, v22, v23
	global_store_dwordx2 v[164:165], v[20:21], off
	s_nop 0
	s_nop 0
	s_waitcnt vmcnt(5)
	v_lshlrev_b32_e32 v24, 16, v170
	v_and_b32_e32 v25, 0xffff0000, v170
	v_lshlrev_b32_e32 v22, 16, v171
	v_and_b32_e32 v23, 0xffff0000, v171
	v_pk_mul_f32 v[16:17], v[16:17], v[24:25]
	v_pk_mul_f32 v[18:19], v[18:19], v[22:23]
	v_cvt_pk_bf16_f32 v16, v16, v17
	v_cvt_pk_bf16_f32 v17, v18, v19
	global_store_dwordx2 v[168:169], v[16:17], off
	s_nop 0
	s_nop 0
	s_nop 0
	s_nop 0
	s_nop 0
	s_nop 0
	s_waitcnt vmcnt(4)
	v_pk_mul_f32 v[12:13], v[12:13], v[186:187]
	s_nop 0
	v_pk_mul_f32 v[14:15], v[14:15], v[188:189]
	v_pk_mul_f32 v[8:9], v[8:9], v[186:187]
	v_pk_mul_f32 v[10:11], v[10:11], v[188:189]
	v_pk_mul_f32 v[4:5], v[4:5], v[186:187]
	v_pk_mul_f32 v[6:7], v[6:7], v[188:189]
	v_pk_mul_f32 v[0:1], v[0:1], v[186:187]
	v_pk_mul_f32 v[2:3], v[2:3], v[188:189]
	s_waitcnt vmcnt(3)
	v_lshlrev_b32_e32 v26, 16, v180
	v_and_b32_e32 v27, 0xffff0000, v180
	v_lshlrev_b32_e32 v24, 16, v181
	v_and_b32_e32 v25, 0xffff0000, v181
	v_pk_mul_f32 v[12:13], v[12:13], v[26:27]
	v_pk_mul_f32 v[14:15], v[14:15], v[24:25]
	v_cvt_pk_bf16_f32 v12, v12, v13
	v_cvt_pk_bf16_f32 v13, v14, v15
	global_store_dwordx2 v[178:179], v[12:13], off
	s_nop 0
	s_nop 0
	s_waitcnt vmcnt(2)
	v_lshlrev_b32_e32 v22, 16, v192
	v_and_b32_e32 v23, 0xffff0000, v192
	v_lshlrev_b32_e32 v14, 16, v193
	v_and_b32_e32 v15, 0xffff0000, v193
	v_pk_mul_f32 v[8:9], v[8:9], v[22:23]
	v_pk_mul_f32 v[10:11], v[10:11], v[14:15]
	v_cvt_pk_bf16_f32 v8, v8, v9
	v_cvt_pk_bf16_f32 v9, v10, v11
	global_store_dwordx2 v[190:191], v[8:9], off
	s_nop 0
	s_nop 0
	s_waitcnt vmcnt(1)
	v_lshlrev_b32_e32 v12, 16, v196
	v_and_b32_e32 v13, 0xffff0000, v196
	v_lshlrev_b32_e32 v10, 16, v197
	v_and_b32_e32 v11, 0xffff0000, v197
	v_pk_mul_f32 v[4:5], v[4:5], v[12:13]
	v_pk_mul_f32 v[6:7], v[6:7], v[10:11]
	v_cvt_pk_bf16_f32 v4, v4, v5
	v_cvt_pk_bf16_f32 v5, v6, v7
	global_store_dwordx2 v[194:195], v[4:5], off
	s_nop 0
	s_nop 0
	s_waitcnt vmcnt(0)
	v_lshlrev_b32_e32 v8, 16, v226
	v_and_b32_e32 v9, 0xffff0000, v226
	v_lshlrev_b32_e32 v6, 16, v227
	v_and_b32_e32 v7, 0xffff0000, v227
	v_pk_mul_f32 v[0:1], v[0:1], v[8:9]
	v_pk_mul_f32 v[2:3], v[2:3], v[6:7]
	v_cvt_pk_bf16_f32 v0, v0, v1
	v_cvt_pk_bf16_f32 v1, v2, v3
	global_store_dwordx2 v[224:225], v[0:1], off
	v_mov_b32_e32 v4, v224
	v_mov_b32_e32 v5, v225
	v_mov_b32_e32 v16, v186
	v_mov_b32_e32 v17, v187
	v_mov_b32_e32 v18, v188
	v_mov_b32_e32 v19, v189
	v_mov_b32_e32 v20, v176
	v_mov_b32_e32 v21, v177
	v_mov_b32_e32 v32, v154
	v_mov_b32_e32 v33, v155
	v_mov_b32_e32 v34, v156
	v_mov_b32_e32 v35, v157
	v_mov_b32_e32 v36, v150
	v_mov_b32_e32 v37, v151
	s_branch .LBB0_1146

; DI int get_bid() { int b = blockIdx.x; asm volatile("" : "+s"(b)); return b; }
; template <int MT, class Epi>
; DI void gemm_tile(const u16* __restrict__ X, long ldx, const u16* __restrict__ W, long ldw, int K, char* smem,
;                   int m0, int n0, const Epi& epi, bool pre = false, const u16* Xn = nullptr, const u16* Wn = nullptr) {
;     ...
;   const int wu = __builtin_amdgcn_readfirstlane(wave);
;   const unsigned sbase = (unsigned)__builtin_amdgcn_readfirstlane((int)(unsigned)(size_t)smem);
;   const int r8 = lane >> 3, c0 = (lane & 7) ^ (r8 >> 1);
;   const long oxe = (long)(wu * MT * 8 + r8) * ldx + (c0 << 3), oxo = (long)(wu * MT * 8 + r8) * ldx + ((c0 ^ 4) << 3);
;   const long owe = (long)(wu * 32 + r8) * ldw + (c0 << 3), owo = (long)(wu * 32 + r8) * ldw + ((c0 ^ 4) << 3);
;   const u16 *xe = X + oxe, *xo = X + oxo, *we = W + owe, *wo = W + owo;
;   const long ldx8 = 8 * ldx, ldw8 = 8 * ldw;
;   const unsigned xdst = sbase + wu * MT * 1024, wdst = sbase + 16384 + wu * 4096;
;     ...
;   if (!pre) {
;     __syncthreads();
;     GT_DMA(0u)
; DI void phase_even(const Params& p, int e, int sub, char* smem) {
;     ...
;     for (int t = get_bid(); t < 132 * 40; t += gridDim.x) {
;       const int tm = t / 40, tn = t % 40;
;       const int t2 = t + gridDim.x, tm2 = t2 / 40, tn2 = t2 % 40;
;       const bool nx = t2 < 132 * 40;
;       gemm_tile<4>(hbuf + (size_t)tm * 128 * 1024, 1024, W + WE_IN + (size_t)tn * 128 * 1024, 1024, 1024, smem, tm * 128, tn * 128, epi, pre,
;                    nx ? hbuf + (size_t)tm2 * 128 * 1024 : nullptr, W + WE_IN + (size_t)tn2 * 128 * 1024);
.LBB0_1309:
	s_mul_hi_i32 s5, s4, 0x66666667
	s_lshr_b32 s6, s5, 31
	s_ashr_i32 s5, s5, 4
	s_add_i32 s42, s5, s6
	v_mov_b32_e32 v3, v185
	s_mul_i32 s5, s42, 40
	s_sub_i32 s38, s4, s5
	v_ashrrev_i32_e32 v4, 6, v3
	v_bfe_u32 v2, v3, 3, 3
	v_readfirstlane_b32 s5, v4
	s_lshl_b32 s7, s5, 5
	v_bfe_u32 v76, v3, 4, 2
	v_or_b32_e32 v6, s7, v2
	v_bitop3_b32 v1, v76, v3, 7 bitop3:0x78
	v_ashrrev_i32_e32 v7, 31, v6
	v_lshlrev_b64 v[6:7], 10, v[6:7]
	v_lshlrev_b32_e32 v5, 3, v1
	s_ashr_i32 s43, s42, 31
	s_ashr_i32 s39, s38, 31
	v_or_b32_e32 v8, v6, v5
	v_mov_b32_e32 v9, v7
	v_bitop3_b32 v6, v6, v5, 32 bitop3:0xf6
	s_lshl_b32 s5, s5, 12
	s_lshl_b64 s[40:41], s[42:43], 18
	s_lshl_b64 s[44:45], s[38:39], 18
	v_mov_b32_e32 v0, v183
	s_add_i32 s6, s5, 0x4000
	s_and_b64 vcc, exec, s[46:47]
	v_lshlrev_b64 v[66:67], 1, v[8:9]
	v_lshlrev_b64 v[64:65], 1, v[6:7]
	s_cbranch_vccnz .LBB0_1311
	s_add_u32 s8, s0, s40
	v_readlane_b32 s12, v255, 5
	s_addc_u32 s9, s1, s41
	v_readlane_b32 s16, v255, 9
	v_readlane_b32 s17, v255, 10
	s_add_u32 s10, s16, s44
	s_addc_u32 s11, s17, s45
	v_readlane_b32 s13, v255, 6
	v_lshl_add_u64 v[6:7], s[8:9], 0, v[66:67]
	v_lshl_add_u64 v[8:9], s[8:9], 0, v[64:65]
	v_lshl_add_u64 v[10:11], s[10:11], 0, v[66:67]
	v_lshl_add_u64 v[12:13], s[10:11], 0, v[64:65]
	s_waitcnt lgkmcnt(0)
	s_barrier
	s_mov_b32 m0, s5
	s_nop 0
	global_load_lds_dwordx4 v[6:7], off
	s_mov_b64 s[10:11], 0x4000
	v_readlane_b32 s14, v255, 7
	v_readlane_b32 s15, v255, 8
	v_lshl_add_u64 v[14:15], v[8:9], 0, s[10:11]
	s_add_i32 s8, s5, 0x400
	s_mov_b32 m0, s8
	s_nop 0
	global_load_lds_dwordx4 v[14:15], off
	s_mov_b64 s[12:13], 0x8000
	v_lshl_add_u64 v[6:7], v[6:7], 0, s[12:13]
	s_add_i32 s8, s5, 0x800
	s_mov_b32 m0, s8
	s_nop 0
	global_load_lds_dwordx4 v[6:7], off
	s_mov_b64 s[14:15], 0xc000
	v_lshl_add_u64 v[6:7], v[8:9], 0, s[14:15]
	s_add_i32 s8, s5, 0xc00
	s_mov_b32 m0, s8
	s_nop 0
	global_load_lds_dwordx4 v[6:7], off
	s_mov_b32 m0, s6
	s_nop 0
	global_load_lds_dwordx4 v[10:11], off
	v_lshl_add_u64 v[6:7], v[12:13], 0, s[10:11]
	s_add_i32 s8, s5, 0x4400
	s_mov_b32 m0, s8
	s_nop 0
	global_load_lds_dwordx4 v[6:7], off
	v_lshl_add_u64 v[6:7], v[10:11], 0, s[12:13]
	s_add_i32 s8, s5, 0x4800
	s_mov_b32 m0, s8
	s_nop 0
	global_load_lds_dwordx4 v[6:7], off
	v_lshl_add_u64 v[6:7], v[12:13], 0, s[14:15]
	s_add_i32 s8, s5, 0x4c00
	s_mov_b32 m0, s8
	s_nop 0
	global_load_lds_dwordx4 v[6:7], off
	v_readlane_b32 s18, v255, 11
	v_readlane_b32 s19, v255, 12

; DI int get_bid() { int b = blockIdx.x; asm volatile("" : "+s"(b)); return b; }
; template <int MT, class Epi>
; DI void gemm_tile(const u16* __restrict__ X, long ldx, const u16* __restrict__ W, long ldw, int K, char* smem,
;                   int m0, int n0, const Epi& epi, bool pre = false, const u16* Xn = nullptr, const u16* Wn = nullptr) {
;     ...
;   do {
;     asm volatile("s_waitcnt vmcnt(0)" ::: "memory");
;     __syncthreads();
;     if (kt + 1 < nk) GT_DMA((unsigned)((kt + 1) & 1) * 32768u)
;     else if (Xn != nullptr) { xe = Xn + oxe; xo = Xn + oxo; we = Wn + owe; wo = Wn + owo; GT_DMA(0u) }
;     const char* cur = smem + (kt & 1) * 32768;
; #pragma unroll
;     for (int ks = 0; ks < 2; ++ks) {
;       bf16x8 xf[MT], wf[4];
;       const int ch = ((ks * 4 + g) ^ rsw) << 4;
; #pragma unroll
;       for (int i = 0; i < MT; ++i) xf[i] = *(const bf16x8*)(cur + (wm * 16 * MT + i * 16 + lr) * 128 + ch);
; #pragma unroll
;       for (int i = 0; i < 4; ++i) wf[i] = *(const bf16x8*)(cur + 16384 + (wn * 64 + i * 16 + lr) * 128 + ch);
; #pragma unroll
;       for (int nt = 0; nt < 4; ++nt)
; #pragma unroll
;         for (int mt = 0; mt < MT; ++mt)
;           acc[nt][mt] = __builtin_amdgcn_mfma_f32_16x16x32_bf16(wf[nt], xf[mt], acc[nt][mt], 0, 0, 0);
;     }
;   } while (++kt < nk);
; DI void phase_even(const Params& p, int e, int sub, char* smem) {
;     ...
;     for (int t = get_bid(); t < 132 * 40; t += gridDim.x) {
;       const int tm = t / 40, tn = t % 40;
;       const int t2 = t + gridDim.x, tm2 = t2 / 40, tn2 = t2 % 40;
;       const bool nx = t2 < 132 * 40;
;       gemm_tile<4>(hbuf + (size_t)tm * 128 * 1024, 1024, W + WE_IN + (size_t)tn * 128 * 1024, 1024, 1024, smem, tm * 128, tn * 128, epi, pre,
;                    nx ? hbuf + (size_t)tm2 * 128 * 1024 : nullptr, W + WE_IN + (size_t)tn2 * 128 * 1024);
.LBB0_1312:
	s_add_i32 s7, s8, 0x8000
	v_lshl_add_u64 v[124:125], v[74:75], 0, s[40:41]
	s_and_b32 s9, s7, 0x8000
	v_lshl_add_u64 v[122:123], v[72:73], 0, s[40:41]
	v_lshl_add_u64 v[126:127], v[124:125], 0, s[74:75]
	s_waitcnt vmcnt(0)
	s_waitcnt lgkmcnt(0)
	s_barrier
	s_and_b32 s8, s8, 0x8000
	v_or_b32_e32 v162, s8, v84
	v_add3_u32 v163, v162, v80, v81
	v_add3_u32 v164, v162, v83, v81
	v_or_b32_e32 v165, s8, v82
	v_add3_u32 v166, v165, v80, v81
	v_add3_u32 v167, v165, v83, v81
	ds_read_b128 v[86:89], v163
	ds_read_b128 v[90:93], v163 offset:2048
	ds_read_b128 v[94:97], v163 offset:4096
	ds_read_b128 v[98:101], v163 offset:6144
	ds_read_b128 v[102:105], v164 offset:16384
	ds_read_b128 v[106:109], v164 offset:18432
	ds_read_b128 v[110:113], v164 offset:20480
	ds_read_b128 v[114:117], v164 offset:22528
	ds_read_b128 v[130:133], v166
	ds_read_b128 v[134:137], v166 offset:2048
	ds_read_b128 v[138:141], v166 offset:4096
	ds_read_b128 v[142:145], v166 offset:6144
	ds_read_b128 v[146:149], v167 offset:16384
	ds_read_b128 v[150:153], v167 offset:18432
	ds_read_b128 v[154:157], v167 offset:20480
	ds_read_b128 v[158:161], v167 offset:22528
	s_add_i32 s10, s9, s5
	s_mov_b32 m0, s10
	s_nop 0
	global_load_lds_dwordx4 v[126:127], off
	v_lshl_add_u64 v[126:127], v[122:123], 0, s[94:95]
	s_add_i32 s11, s10, 0x400
	s_mov_b32 m0, s11
	s_nop 0
	global_load_lds_dwordx4 v[126:127], off
	v_lshl_add_u64 v[124:125], v[124:125], 0, s[76:77]
	s_add_i32 s11, s10, 0x800
	s_mov_b32 m0, s11
	s_nop 0
	global_load_lds_dwordx4 v[124:125], off
	v_lshl_add_u64 v[120:121], v[70:71], 0, s[40:41]
	v_lshl_add_u64 v[122:123], v[122:123], 0, s[54:55]
	s_addk_i32 s10, 0xc00
	s_mov_b32 m0, s10
	s_nop 0
	global_load_lds_dwordx4 v[122:123], off
	v_lshl_add_u64 v[118:119], v[68:69], 0, s[40:41]
	v_lshl_add_u64 v[128:129], v[120:121], 0, s[28:29]
	s_add_i32 s9, s9, s6
	s_mov_b32 m0, s9
	s_nop 0
	global_load_lds_dwordx4 v[128:129], off
	v_lshl_add_u64 v[122:123], v[118:119], 0, s[94:95]
	s_add_i32 s10, s9, 0x400
	s_mov_b32 m0, s10
	s_nop 0
	global_load_lds_dwordx4 v[122:123], off
	v_lshl_add_u64 v[120:121], v[120:121], 0, s[78:79]
	s_add_i32 s10, s9, 0x800
	s_mov_b32 m0, s10
	s_nop 0
	global_load_lds_dwordx4 v[120:121], off
	v_lshl_add_u64 v[118:119], v[118:119], 0, s[54:55]
	s_addk_i32 s9, 0xc00
	s_mov_b32 m0, s9
	s_nop 0
	global_load_lds_dwordx4 v[118:119], off
	s_mov_b32 s8, s7
	s_add_u32 s40, s40, 0x80
	s_addc_u32 s41, s41, 0
	s_cmpk_lg_i32 s40, 0x780
	s_waitcnt lgkmcnt(11)
	v_mfma_f32_16x16x32_bf16 v[48:51], v[102:105], v[98:101], v[48:51]
	s_waitcnt lgkmcnt(10)
	v_mfma_f32_16x16x32_bf16 v[32:35], v[106:109], v[98:101], v[32:35]
	s_waitcnt lgkmcnt(9)
	v_mfma_f32_16x16x32_bf16 v[16:19], v[110:113], v[98:101], v[16:19]
	s_waitcnt lgkmcnt(8)
	v_mfma_f32_16x16x32_bf16 v[0:3], v[114:117], v[98:101], v[0:3]
	v_mfma_f32_16x16x32_bf16 v[60:63], v[102:105], v[86:89], v[60:63]
	v_mfma_f32_16x16x32_bf16 v[56:59], v[102:105], v[90:93], v[56:59]
	v_mfma_f32_16x16x32_bf16 v[52:55], v[102:105], v[94:97], v[52:55]
	v_mfma_f32_16x16x32_bf16 v[44:47], v[106:109], v[86:89], v[44:47]
	v_mfma_f32_16x16x32_bf16 v[40:43], v[106:109], v[90:93], v[40:43]
	v_mfma_f32_16x16x32_bf16 v[36:39], v[106:109], v[94:97], v[36:39]
	v_mfma_f32_16x16x32_bf16 v[28:31], v[110:113], v[86:89], v[28:31]
	v_mfma_f32_16x16x32_bf16 v[24:27], v[110:113], v[90:93], v[24:27]
	v_mfma_f32_16x16x32_bf16 v[20:23], v[110:113], v[94:97], v[20:23]
	v_mfma_f32_16x16x32_bf16 v[12:15], v[114:117], v[86:89], v[12:15]
	v_mfma_f32_16x16x32_bf16 v[8:11], v[114:117], v[90:93], v[8:11]
	v_mfma_f32_16x16x32_bf16 v[4:7], v[114:117], v[94:97], v[4:7]
	s_waitcnt lgkmcnt(3)
	v_mfma_f32_16x16x32_bf16 v[60:63], v[146:149], v[130:133], v[60:63]
	v_mfma_f32_16x16x32_bf16 v[56:59], v[146:149], v[134:137], v[56:59]
	v_mfma_f32_16x16x32_bf16 v[52:55], v[146:149], v[138:141], v[52:55]
	v_mfma_f32_16x16x32_bf16 v[48:51], v[146:149], v[142:145], v[48:51]
	s_waitcnt lgkmcnt(2)
	v_mfma_f32_16x16x32_bf16 v[44:47], v[150:153], v[130:133], v[44:47]
	v_mfma_f32_16x16x32_bf16 v[40:43], v[150:153], v[134:137], v[40:43]
	v_mfma_f32_16x16x32_bf16 v[36:39], v[150:153], v[138:141], v[36:39]
	v_mfma_f32_16x16x32_bf16 v[32:35], v[150:153], v[142:145], v[32:35]
	s_waitcnt lgkmcnt(1)
	v_mfma_f32_16x16x32_bf16 v[28:31], v[154:157], v[130:133], v[28:31]
	v_mfma_f32_16x16x32_bf16 v[24:27], v[154:157], v[134:137], v[24:27]
	v_mfma_f32_16x16x32_bf16 v[20:23], v[154:157], v[138:141], v[20:23]
	v_mfma_f32_16x16x32_bf16 v[16:19], v[154:157], v[142:145], v[16:19]
	s_waitcnt lgkmcnt(0)
	v_mfma_f32_16x16x32_bf16 v[12:15], v[158:161], v[130:133], v[12:15]
	v_mfma_f32_16x16x32_bf16 v[8:11], v[158:161], v[134:137], v[8:11]
	v_mfma_f32_16x16x32_bf16 v[4:7], v[158:161], v[138:141], v[4:7]
	v_mfma_f32_16x16x32_bf16 v[0:3], v[158:161], v[142:145], v[0:3]
	s_cbranch_scc1 .LBB0_1312
	v_readlane_b32 s8, v255, 5
	v_readlane_b32 s14, v255, 11
	s_add_i32 s4, s4, s14
	s_mul_hi_i32 s7, s4, 0x66666667
	s_lshr_b32 s8, s7, 31
	s_ashr_i32 s7, s7, 4
	s_add_i32 s46, s7, s8
	s_cmpk_gt_i32 s4, 0x149f
	v_readlane_b32 s9, v255, 6
	s_cselect_b64 s[44:45], -1, 0
	s_ashr_i32 s47, s46, 31
	s_lshl_b64 s[8:9], s[46:47], 18
	s_add_u32 s7, s0, s8
	s_addc_u32 s8, s1, s9
	s_cmpk_lt_i32 s4, 0x14a0
	s_waitcnt vmcnt(0)
	s_cselect_b32 s41, s8, 0
	s_cselect_b32 s40, s7, 0
	v_readlane_b32 s12, v255, 9
	v_readlane_b32 s13, v255, 10
	s_cmp_eq_u64 s[40:41], 0
	v_readlane_b32 s10, v255, 7
	v_readlane_b32 s11, v255, 8
	v_readlane_b32 s15, v255, 12
	s_barrier
	s_cbranch_scc1 .LBB0_1315
	s_mul_i32 s7, s46, 40
	s_sub_i32 s8, s4, s7
	s_ashr_i32 s9, s8, 31
	s_lshl_b64 s[8:9], s[8:9], 18
	s_add_u32 s8, s12, s8
	s_addc_u32 s9, s13, s9
	v_lshl_add_u64 v[68:69], s[40:41], 0, v[66:67]
	v_lshl_add_u64 v[70:71], s[8:9], 0, v[64:65]
	v_lshl_add_u64 v[64:65], s[40:41], 0, v[64:65]
	s_mov_b32 m0, s5
	s_nop 0
	global_load_lds_dwordx4 v[68:69], off
	s_mov_b64 s[10:11], 0x4000
	v_lshl_add_u64 v[66:67], s[8:9], 0, v[66:67]
	v_lshl_add_u64 v[72:73], v[64:65], 0, s[10:11]
	s_add_i32 s7, s5, 0x400
	s_mov_b32 m0, s7
	s_nop 0
	global_load_lds_dwordx4 v[72:73], off
	s_mov_b64 s[12:13], 0x8000
	v_lshl_add_u64 v[68:69], v[68:69], 0, s[12:13]
	s_add_i32 s7, s5, 0x800
	s_mov_b32 m0, s7
	s_nop 0
	global_load_lds_dwordx4 v[68:69], off
	s_mov_b64 s[14:15], 0xc000
	v_lshl_add_u64 v[64:65], v[64:65], 0, s[14:15]
	s_add_i32 s7, s5, 0xc00
	s_mov_b32 m0, s7
	s_nop 0
	global_load_lds_dwordx4 v[64:65], off
	s_mov_b32 m0, s6
	s_nop 0
	global_load_lds_dwordx4 v[66:67], off
	v_lshl_add_u64 v[64:65], v[70:71], 0, s[10:11]
	s_add_i32 s6, s5, 0x4400
	s_mov_b32 m0, s6
	s_nop 0
	global_load_lds_dwordx4 v[64:65], off
	v_lshl_add_u64 v[64:65], v[66:67], 0, s[12:13]
	s_add_i32 s6, s5, 0x4800
	s_mov_b32 m0, s6
	s_nop 0
	global_load_lds_dwordx4 v[64:65], off
	v_lshl_add_u64 v[64:65], v[70:71], 0, s[14:15]
	s_addk_i32 s5, 0x4c00
	s_mov_b32 m0, s5
	s_nop 0
	global_load_lds_dwordx4 v[64:65], off
